# UV sweep: per-token loop copies switched at run boundaries (no per-batch dispatch), row offsets and coefficients read as LDS broadcasts into VGPRs (no readlane/SALU address math)
# speedup vs baseline: 1.0877x; 1.0239x over previous
; __device__ __forceinline__ unsigned f2key(float f) { const unsigned u = __float_as_uint(f); return (u & 0x80000000u) ? ~u : (u | 0x80000000u); }
; __device__ __forceinline__ void peer_tile(const Args& A, LAS unsigned char* lds, int tile) {
;     ...
;         const int tg = w & 3, hg = w >> 2, tl = 16 * tg + l15;
;         const size_t m = (size_t)tile * 64 + tl;
;         unsigned LA[4][2][16];
; #pragma unroll
;         for (int hh = 0; hh < 4; ++hh) {
;             const int h = 4 * hg + hh;
; #pragma unroll
;             for (int p = 0; p < 2; ++p) {
;                 const int hp = 2 * h + p;
;                 unsigned k0[16], k1[16];
;                 { const bf16_t* sp = QRY + m * 2048 + hp * 128 + 32 * g;
;                   const u32x4 s0 = *(const u32x4*)sp, s1 = *(const u32x4*)(sp + 8), s2 = *(const u32x4*)(sp + 16), s3 = *(const u32x4*)(sp + 24);
;                   const unsigned sw[16] = {s0.x, s0.y, s0.z, s0.w, s1.x, s1.y, s1.z, s1.w, s2.x, s2.y, s2.z, s2.w, s3.x, s3.y, s3.z, s3.w};
; #pragma unroll
;                   for (int i = 0; i < 16; ++i) {
;                       const float lo = (float)__builtin_bit_cast(_Float16, (unsigned short)(sw[i] & 0xffffu)), hi = (float)__builtin_bit_cast(_Float16, (unsigned short)(sw[i] >> 16));
;                       const unsigned klo = (f2key(lo) & ~127u) | (unsigned)(127 - (32 * g + 2 * i)), khi = (f2key(hi) & ~127u) | (unsigned)(127 - (32 * g + 2 * i + 1));
;                       if (i < 8) { k0[2 * i] = klo; k0[2 * i + 1] = khi; } else { k1[2 * (i - 8)] = klo; k1[2 * (i - 8) + 1] = khi; } } }
.LBB0_699:
	v_mov_b32_e32 v19, v214
	s_ashr_i32 s3, s2, 31
	v_ashrrev_i32_e32 v7, 6, v19
	v_and_b32_e32 v0, 15, v19
	v_lshlrev_b32_e32 v1, 4, v7
	v_and_or_b32 v13, v1, 48, v0
	s_lshl_b64 s[28:29], s[2:3], 6
	v_or_b32_e32 v0, s28, v13
	v_mov_b32_e32 v1, s29
	v_bfe_u32 v221, v19, 4, 2
	v_ashrrev_i32_e32 v11, 8, v19
	v_lshlrev_b64 v[0:1], 12, v[0:1]
	v_lshlrev_b32_e32 v2, 10, v11
	v_lshl_add_u64 v[0:1], s[54:55], 0, v[0:1]
	v_lshlrev_b32_e32 v112, 6, v221
	v_lshl_add_u64 v[0:1], v[0:1], 0, v[112:113]
	v_ashrrev_i32_e32 v3, 31, v2
	v_lshl_add_u64 v[4:5], v[2:3], 1, v[0:1]
	global_load_dwordx4 v[20:23], v[4:5], off
	global_load_dwordx4 v[24:27], v[4:5], off offset:16
	global_load_dwordx4 v[0:3], v[4:5], off offset:48
	global_load_dwordx4 v[28:31], v[4:5], off offset:32
	v_lshlrev_b32_e32 v15, 5, v221
	v_or_b32_e32 v8, 8, v15
	v_or_b32_e32 v14, 2, v15
	v_or_b32_e32 v12, 4, v15
	v_or_b32_e32 v10, 6, v15
	v_and_b32_e32 v9, 63, v19
	v_cmp_gt_u32_e64 s[0:1], 16, v9
	v_cmp_gt_u32_e64 s[4:5], 32, v9
	v_mul_lo_u32 v6, v19, s17
	s_mov_b32 s3, 8
	s_waitcnt vmcnt(3)
	v_cvt_f32_f16_sdwa v17, v20 dst_sel:DWORD dst_unused:UNUSED_PAD src0_sel:WORD_1
	v_cvt_f32_f16_e32 v16, v20
	v_cvt_f32_f16_sdwa v20, v21 dst_sel:DWORD dst_unused:UNUSED_PAD src0_sel:WORD_1
	v_cvt_f32_f16_e32 v18, v21
	v_cvt_f32_f16_e32 v21, v22
	v_cvt_f32_f16_sdwa v22, v22 dst_sel:DWORD dst_unused:UNUSED_PAD src0_sel:WORD_1
	v_not_b32_e32 v34, v17
	v_or_b32_e32 v35, 0x80000000, v17
	v_cmp_gt_i32_e32 vcc, 0, v17
	v_not_b32_e32 v36, v16
	v_or_b32_e32 v37, 0x80000000, v16
	v_cndmask_b32_e32 v17, v35, v34, vcc
	v_cmp_gt_i32_e32 vcc, 0, v16
	v_cvt_f32_f16_e32 v32, v23
	v_cvt_f32_f16_sdwa v23, v23 dst_sel:DWORD dst_unused:UNUSED_PAD src0_sel:WORD_1
	v_not_b32_e32 v38, v20
	v_or_b32_e32 v39, 0x80000000, v20
	v_cndmask_b32_e32 v16, v37, v36, vcc
	v_cmp_gt_i32_e32 vcc, 0, v20
	v_not_b32_e32 v40, v18
	v_or_b32_e32 v41, 0x80000000, v18
	v_cndmask_b32_e32 v20, v39, v38, vcc
	v_cmp_gt_i32_e32 vcc, 0, v18
	s_waitcnt vmcnt(2)
	v_cvt_f32_f16_e32 v33, v24
	v_cvt_f32_f16_sdwa v24, v24 dst_sel:DWORD dst_unused:UNUSED_PAD src0_sel:WORD_1
	v_not_b32_e32 v42, v22
	v_or_b32_e32 v43, 0x80000000, v22
	v_cndmask_b32_e32 v18, v41, v40, vcc
	v_cmp_gt_i32_e32 vcc, 0, v22
	v_not_b32_e32 v44, v21
	v_or_b32_e32 v45, 0x80000000, v21
	v_cndmask_b32_e32 v22, v43, v42, vcc
	v_cmp_gt_i32_e32 vcc, 0, v21
	v_not_b32_e32 v46, v23
	v_or_b32_e32 v47, 0x80000000, v23
	v_cndmask_b32_e32 v21, v45, v44, vcc
	v_cmp_gt_i32_e32 vcc, 0, v23
	v_not_b32_e32 v48, v32
	v_or_b32_e32 v49, 0x80000000, v32
	v_cndmask_b32_e32 v23, v47, v46, vcc
	v_cmp_gt_i32_e32 vcc, 0, v32
	v_and_b32_e32 v16, 0xffffff80, v16
	v_not_b32_e32 v50, v24
	v_or_b32_e32 v51, 0x80000000, v24
	v_cndmask_b32_e32 v32, v49, v48, vcc
	v_sub_u32_e32 v16, v16, v15
	v_cmp_gt_i32_e32 vcc, 0, v24
	v_add_u32_e32 v35, 0x7f, v16
	v_and_b32_e32 v17, 0xffffff80, v17
	v_cndmask_b32_e32 v16, v51, v50, vcc
	v_and_b32_e32 v16, 0xffffff80, v16
	v_sub_u32_e32 v17, v17, v15
	v_sub_u32_e32 v16, v16, v8
	v_add_u32_e32 v34, 0x7e, v17
	v_add_u32_e32 v41, 0x7e, v16
	v_not_b32_e32 v16, v33
	v_or_b32_e32 v17, 0x80000000, v33
	v_cmp_gt_i32_e32 vcc, 0, v33
	v_and_b32_e32 v20, 0xffffff80, v20
	v_and_b32_e32 v18, 0xffffff80, v18
	v_cndmask_b32_e32 v16, v17, v16, vcc
	v_cvt_f32_f16_sdwa v17, v25 dst_sel:DWORD dst_unused:UNUSED_PAD src0_sel:WORD_1
	v_and_b32_e32 v21, 0xffffff80, v21
	v_sub_u32_e32 v20, v20, v14
	v_sub_u32_e32 v18, v18, v14
	v_sub_u32_e32 v21, v21, v12
	v_add_u32_e32 v36, 0x7e, v20
	v_add_u32_e32 v37, 0x7f, v18
	v_add_u32_e32 v39, 0x7f, v21
	v_and_b32_e32 v16, 0xffffff80, v16
	v_cvt_f32_f16_e32 v18, v25
	v_not_b32_e32 v20, v17
	v_or_b32_e32 v21, 0x80000000, v17
	v_cmp_gt_i32_e32 vcc, 0, v17
	v_sub_u32_e32 v16, v16, v8
	v_add_u32_e32 v33, 0x7f, v16
	v_cndmask_b32_e32 v17, v21, v20, vcc
	v_or_b32_e32 v16, 10, v15
	v_and_b32_e32 v17, 0xffffff80, v17
	v_sub_u32_e32 v17, v17, v16
	v_add_u32_e32 v42, 0x7e, v17
	v_not_b32_e32 v17, v18
	v_or_b32_e32 v20, 0x80000000, v18
	v_cmp_gt_i32_e32 vcc, 0, v18
	v_cvt_f32_f16_sdwa v18, v26 dst_sel:DWORD dst_unused:UNUSED_PAD src0_sel:WORD_1
	v_and_b32_e32 v22, 0xffffff80, v22
	v_sub_u32_e32 v22, v22, v12
	v_cndmask_b32_e32 v17, v20, v17, vcc
	v_add_u32_e32 v38, 0x7e, v22
	v_and_b32_e32 v17, 0xffffff80, v17
	v_cvt_f32_f16_e32 v20, v26
	v_not_b32_e32 v21, v18
	v_or_b32_e32 v22, 0x80000000, v18
	v_cmp_gt_i32_e32 vcc, 0, v18
	v_sub_u32_e32 v17, v17, v16
	v_add_u32_e32 v43, 0x7f, v17
	v_cndmask_b32_e32 v18, v22, v21, vcc
	v_or_b32_e32 v17, 12, v15
	v_and_b32_e32 v18, 0xffffff80, v18
	v_sub_u32_e32 v18, v18, v17
	v_add_u32_e32 v44, 0x7e, v18
	v_not_b32_e32 v18, v20
	v_or_b32_e32 v21, 0x80000000, v20
	v_cmp_gt_i32_e32 vcc, 0, v20
	v_cvt_f32_f16_sdwa v20, v27 dst_sel:DWORD dst_unused:UNUSED_PAD src0_sel:WORD_1
	v_and_b32_e32 v23, 0xffffff80, v23
	v_sub_u32_e32 v23, v23, v10
	v_cndmask_b32_e32 v18, v21, v18, vcc
	v_add_u32_e32 v40, 0x7e, v23
	v_and_b32_e32 v18, 0xffffff80, v18
	v_cvt_f32_f16_e32 v21, v27
	v_not_b32_e32 v22, v20
	v_or_b32_e32 v23, 0x80000000, v20
	v_cmp_gt_i32_e32 vcc, 0, v20
	v_sub_u32_e32 v18, v18, v17
	v_add_u32_e32 v45, 0x7f, v18
	v_cndmask_b32_e32 v20, v23, v22, vcc
	v_or_b32_e32 v18, 14, v15
	v_and_b32_e32 v20, 0xffffff80, v20
	v_sub_u32_e32 v20, v20, v18
	v_add_u32_e32 v27, 0x7e, v20
	v_not_b32_e32 v20, v21
	v_or_b32_e32 v22, 0x80000000, v21
	v_cmp_gt_i32_e32 vcc, 0, v21
	s_waitcnt vmcnt(0)
; __device__ __forceinline__ unsigned f2key(float f) { const unsigned u = __float_as_uint(f); return (u & 0x80000000u) ? ~u : (u | 0x80000000u); }
; #define CE_DESC(a, b) do { const unsigned _mx = (a) > (b) ? (a) : (b), _mn = (a) > (b) ? (b) : (a); (a) = _mx; (b) = _mn; } while (0)
; __device__ __forceinline__ void sort16_desc(unsigned (&k)[16]) {
; #pragma unroll
;     for (int size = 2; size <= 16; size <<= 1)
; #pragma unroll
;         for (int stride = size >> 1; stride > 0; stride >>= 1)
; #pragma unroll
;             for (int i = 0; i < 16; ++i) { const int j = i ^ stride;
;                 if (j > i) { if ((i & size) == 0) CE_DESC(k[i], k[j]); else CE_DESC(k[j], k[i]); } }
; }
; __device__ __forceinline__ void peer_tile(const Args& A, LAS unsigned char* lds, int tile) {
;     ...
;                 { const bf16_t* sp = QRY + m * 2048 + hp * 128 + 32 * g;
;                   const u32x4 s0 = *(const u32x4*)sp, s1 = *(const u32x4*)(sp + 8), s2 = *(const u32x4*)(sp + 16), s3 = *(const u32x4*)(sp + 24);
;                   const unsigned sw[16] = {s0.x, s0.y, s0.z, s0.w, s1.x, s1.y, s1.z, s1.w, s2.x, s2.y, s2.z, s2.w, s3.x, s3.y, s3.z, s3.w};
; #pragma unroll
;                   for (int i = 0; i < 16; ++i) {
;                       const float lo = (float)__builtin_bit_cast(_Float16, (unsigned short)(sw[i] & 0xffffu)), hi = (float)__builtin_bit_cast(_Float16, (unsigned short)(sw[i] >> 16));
;                       const unsigned klo = (f2key(lo) & ~127u) | (unsigned)(127 - (32 * g + 2 * i)), khi = (f2key(hi) & ~127u) | (unsigned)(127 - (32 * g + 2 * i + 1));
;                       if (i < 8) { k0[2 * i] = klo; k0[2 * i + 1] = khi; } else { k1[2 * (i - 8)] = klo; k1[2 * (i - 8) + 1] = khi; } } }
;                 sort16_desc(k0); sort16_desc(k1); merge16(k0, k1);
	v_cvt_f32_f16_sdwa v21, v28 dst_sel:DWORD dst_unused:UNUSED_PAD src0_sel:WORD_1
	v_and_b32_e32 v32, 0xffffff80, v32
	v_cndmask_b32_e32 v20, v22, v20, vcc
	v_and_b32_e32 v20, 0xffffff80, v20
	v_cvt_f32_f16_e32 v22, v28
	v_not_b32_e32 v23, v21
	v_or_b32_e32 v24, 0x80000000, v21
	v_cmp_gt_i32_e32 vcc, 0, v21
	v_sub_u32_e32 v20, v20, v18
	v_add_u32_e32 v46, 0x7f, v20
	v_cndmask_b32_e32 v21, v24, v23, vcc
	v_or_b32_e32 v20, 16, v15
	v_and_b32_e32 v21, 0xffffff80, v21
	v_sub_u32_e32 v21, v21, v20
	v_add_u32_e32 v47, 0x7e, v21
	v_not_b32_e32 v21, v22
	v_or_b32_e32 v23, 0x80000000, v22
	v_cmp_gt_i32_e32 vcc, 0, v22
	v_cvt_f32_f16_sdwa v22, v29 dst_sel:DWORD dst_unused:UNUSED_PAD src0_sel:WORD_1
	v_sub_u32_e32 v32, v32, v10
	v_cndmask_b32_e32 v21, v23, v21, vcc
	v_and_b32_e32 v21, 0xffffff80, v21
	v_cvt_f32_f16_e32 v23, v29
	v_not_b32_e32 v24, v22
	v_or_b32_e32 v25, 0x80000000, v22
	v_cmp_gt_i32_e32 vcc, 0, v22
	v_sub_u32_e32 v21, v21, v20
	v_add_u32_e32 v48, 0x7f, v21
	v_cndmask_b32_e32 v22, v25, v24, vcc
	v_or_b32_e32 v21, 18, v15
	v_and_b32_e32 v22, 0xffffff80, v22
	v_sub_u32_e32 v22, v22, v21
	v_add_u32_e32 v29, 0x7e, v22
	v_not_b32_e32 v22, v23
	v_or_b32_e32 v24, 0x80000000, v23
	v_cmp_gt_i32_e32 vcc, 0, v23
	v_cvt_f32_f16_sdwa v23, v30 dst_sel:DWORD dst_unused:UNUSED_PAD src0_sel:WORD_1
	v_add_u32_e32 v32, 0x7f, v32
	v_cndmask_b32_e32 v22, v24, v22, vcc
	v_and_b32_e32 v22, 0xffffff80, v22
	v_cvt_f32_f16_e32 v24, v30
	v_not_b32_e32 v25, v23
	v_or_b32_e32 v26, 0x80000000, v23
	v_cmp_gt_i32_e32 vcc, 0, v23
	v_sub_u32_e32 v22, v22, v21
	v_add_u32_e32 v49, 0x7f, v22
	v_cndmask_b32_e32 v23, v26, v25, vcc
	v_or_b32_e32 v22, 20, v15
	v_and_b32_e32 v23, 0xffffff80, v23
	v_sub_u32_e32 v23, v23, v22
	v_add_u32_e32 v30, 0x7e, v23
	v_not_b32_e32 v23, v24
	v_or_b32_e32 v25, 0x80000000, v24
	v_cmp_gt_i32_e32 vcc, 0, v24
	v_cvt_f32_f16_sdwa v24, v31 dst_sel:DWORD dst_unused:UNUSED_PAD src0_sel:WORD_1
	v_max_u32_e32 v64, v48, v47
	v_cndmask_b32_e32 v23, v25, v23, vcc
	v_and_b32_e32 v23, 0xffffff80, v23
	v_cvt_f32_f16_e32 v25, v31
	v_not_b32_e32 v26, v24
	v_or_b32_e32 v28, 0x80000000, v24
	v_cmp_gt_i32_e32 vcc, 0, v24
	v_sub_u32_e32 v23, v23, v22
	v_add_u32_e32 v50, 0x7f, v23
	v_cndmask_b32_e32 v24, v28, v26, vcc
	v_or_b32_e32 v23, 22, v15
	v_and_b32_e32 v24, 0xffffff80, v24
	v_sub_u32_e32 v24, v24, v23
	v_add_u32_e32 v31, 0x7e, v24
	v_not_b32_e32 v24, v25
	v_or_b32_e32 v26, 0x80000000, v25
	v_cmp_gt_i32_e32 vcc, 0, v25
	v_cvt_f32_f16_sdwa v25, v0 dst_sel:DWORD dst_unused:UNUSED_PAD src0_sel:WORD_1
	v_cvt_f32_f16_e32 v0, v0
	v_cndmask_b32_e32 v24, v26, v24, vcc
	v_and_b32_e32 v24, 0xffffff80, v24
	v_not_b32_e32 v26, v25
	v_or_b32_e32 v28, 0x80000000, v25
	v_cmp_gt_i32_e32 vcc, 0, v25
	v_sub_u32_e32 v24, v24, v23
	v_add_u32_e32 v51, 0x7f, v24
	v_cndmask_b32_e32 v25, v28, v26, vcc
	v_or_b32_e32 v24, 24, v15
	v_and_b32_e32 v25, 0xffffff80, v25
	v_sub_u32_e32 v25, v25, v24
	v_add_u32_e32 v52, 0x7e, v25
	v_not_b32_e32 v25, v0
	v_or_b32_e32 v26, 0x80000000, v0
	v_cmp_gt_i32_e32 vcc, 0, v0
	v_min_u32_e32 v47, v48, v47
	v_max_u32_e32 v48, v29, v49
	v_cndmask_b32_e32 v0, v26, v25, vcc
	v_cvt_f32_f16_sdwa v26, v1 dst_sel:DWORD dst_unused:UNUSED_PAD src0_sel:WORD_1
	v_cvt_f32_f16_e32 v1, v1
	v_or_b32_e32 v25, 26, v15
	v_and_b32_e32 v0, 0xffffff80, v0
	v_not_b32_e32 v28, v26
	v_or_b32_e32 v53, 0x80000000, v26
	v_cmp_gt_i32_e32 vcc, 0, v26
	v_sub_u32_e32 v0, v0, v24
	v_add_u32_e32 v0, 0x7f, v0
	v_cndmask_b32_e32 v26, v53, v28, vcc
	v_and_b32_e32 v26, 0xffffff80, v26
	v_sub_u32_e32 v26, v26, v25
	v_add_u32_e32 v53, 0x7e, v26
	v_not_b32_e32 v26, v1
	v_or_b32_e32 v28, 0x80000000, v1
	v_cmp_gt_i32_e32 vcc, 0, v1
	v_min_u32_e32 v29, v29, v49
	v_max_u32_e32 v49, v50, v30
	v_cndmask_b32_e32 v1, v28, v26, vcc
	v_cvt_f32_f16_sdwa v28, v2 dst_sel:DWORD dst_unused:UNUSED_PAD src0_sel:WORD_1
	v_cvt_f32_f16_e32 v2, v2
	v_or_b32_e32 v26, 28, v15
	v_and_b32_e32 v1, 0xffffff80, v1
	v_not_b32_e32 v54, v28
	v_or_b32_e32 v55, 0x80000000, v28
	v_cmp_gt_i32_e32 vcc, 0, v28
	v_sub_u32_e32 v1, v1, v25
	v_add_u32_e32 v1, 0x7f, v1
	v_cndmask_b32_e32 v28, v55, v54, vcc
	v_and_b32_e32 v28, 0xffffff80, v28
	v_sub_u32_e32 v28, v28, v26
	v_add_u32_e32 v54, 0x7e, v28
	v_not_b32_e32 v28, v2
	v_or_b32_e32 v55, 0x80000000, v2
	v_cmp_gt_i32_e32 vcc, 0, v2
	v_min_u32_e32 v30, v50, v30
	v_max_u32_e32 v50, v31, v51
	v_cndmask_b32_e32 v2, v55, v28, vcc
	v_cvt_f32_f16_e32 v55, v3
	v_cvt_f32_f16_sdwa v3, v3 dst_sel:DWORD dst_unused:UNUSED_PAD src0_sel:WORD_1
	v_and_b32_e32 v2, 0xffffff80, v2
	v_or_b32_e32 v28, 30, v15
	v_not_b32_e32 v56, v55
	v_or_b32_e32 v57, 0x80000000, v55
	v_cmp_gt_i32_e32 vcc, 0, v55
	v_sub_u32_e32 v2, v2, v26
	v_add_u32_e32 v2, 0x7f, v2
	v_cndmask_b32_e32 v55, v57, v56, vcc
	v_not_b32_e32 v56, v3
	v_or_b32_e32 v57, 0x80000000, v3
	v_cmp_gt_i32_e32 vcc, 0, v3
	v_and_b32_e32 v55, 0xffffff80, v55
	v_sub_u32_e32 v55, v55, v28
	v_cndmask_b32_e32 v3, v57, v56, vcc
	v_and_b32_e32 v3, 0xffffff80, v3
	v_sub_u32_e32 v3, v3, v28
	v_add_u32_e32 v55, 0x7f, v55
	v_add_u32_e32 v3, 0x7e, v3
	v_max_u32_e32 v56, v35, v34
	v_min_u32_e32 v34, v35, v34
	v_max_u32_e32 v35, v36, v37
	v_min_u32_e32 v36, v36, v37
	v_max_u32_e32 v37, v39, v38
	v_min_u32_e32 v38, v39, v38
	v_max_u32_e32 v39, v40, v32
	v_min_u32_e32 v32, v40, v32
	v_max_u32_e32 v40, v33, v41
	v_min_u32_e32 v33, v33, v41
	v_max_u32_e32 v41, v42, v43
	v_min_u32_e32 v42, v42, v43
	v_max_u32_e32 v43, v45, v44
	v_min_u32_e32 v44, v45, v44
	v_max_u32_e32 v45, v27, v46
	v_min_u32_e32 v27, v27, v46
	v_min_u32_e32 v31, v31, v51
	v_max_u32_e32 v51, v0, v52
	v_min_u32_e32 v0, v0, v52
	v_max_u32_e32 v52, v53, v1
	v_min_u32_e32 v1, v53, v1
	v_max_u32_e32 v53, v2, v54
; #define CE_DESC(a, b) do { const unsigned _mx = (a) > (b) ? (a) : (b), _mn = (a) > (b) ? (b) : (a); (a) = _mx; (b) = _mn; } while (0)
; __device__ __forceinline__ void sort16_desc(unsigned (&k)[16]) {
; #pragma unroll
;     for (int size = 2; size <= 16; size <<= 1)
; #pragma unroll
;         for (int stride = size >> 1; stride > 0; stride >>= 1)
; #pragma unroll
;             for (int i = 0; i < 16; ++i) { const int j = i ^ stride;
;                 if (j > i) { if ((i & size) == 0) CE_DESC(k[i], k[j]); else CE_DESC(k[j], k[i]); } }
; }
	v_min_u32_e32 v2, v2, v54
	v_max_u32_e32 v54, v3, v55
	v_min_u32_e32 v3, v3, v55
	v_max_u32_e32 v46, v56, v36
	v_min_u32_e32 v36, v56, v36
	v_max_u32_e32 v56, v34, v35
	v_min_u32_e32 v34, v34, v35
	v_max_u32_e32 v35, v32, v37
	v_min_u32_e32 v32, v32, v37
	v_max_u32_e32 v37, v39, v38
	v_min_u32_e32 v38, v39, v38
	v_max_u32_e32 v39, v40, v42
	v_min_u32_e32 v40, v40, v42
	v_max_u32_e32 v42, v33, v41
	v_min_u32_e32 v33, v33, v41
	v_max_u32_e32 v41, v27, v43
	v_min_u32_e32 v27, v27, v43
	v_max_u32_e32 v43, v45, v44
	v_min_u32_e32 v44, v45, v44
	v_max_u32_e32 v55, v64, v29
	v_min_u32_e32 v29, v64, v29
	v_max_u32_e32 v64, v47, v48
	v_min_u32_e32 v47, v47, v48
	v_max_u32_e32 v48, v31, v49
	v_min_u32_e32 v31, v31, v49
	v_max_u32_e32 v49, v50, v30
	v_min_u32_e32 v30, v50, v30
	v_max_u32_e32 v50, v51, v1
	v_min_u32_e32 v1, v51, v1
	v_max_u32_e32 v51, v0, v52
	v_min_u32_e32 v0, v0, v52
	v_max_u32_e32 v52, v3, v53
	v_min_u32_e32 v3, v3, v53
	v_max_u32_e32 v53, v54, v2
	v_min_u32_e32 v2, v54, v2
	v_max_u32_e32 v45, v46, v56
	v_min_u32_e32 v46, v46, v56
	v_max_u32_e32 v56, v36, v34
	v_min_u32_e32 v34, v36, v34
	v_max_u32_e32 v36, v38, v32
	v_min_u32_e32 v32, v38, v32
	v_max_u32_e32 v38, v37, v35
	v_min_u32_e32 v35, v37, v35
	v_max_u32_e32 v37, v39, v42
	v_min_u32_e32 v39, v39, v42
	v_max_u32_e32 v42, v40, v33
	v_min_u32_e32 v33, v40, v33
	v_max_u32_e32 v40, v44, v27
	v_min_u32_e32 v27, v44, v27
	v_max_u32_e32 v44, v43, v41
	v_min_u32_e32 v41, v43, v41
	v_max_u32_e32 v54, v55, v64
	v_min_u32_e32 v55, v55, v64
	v_max_u32_e32 v64, v29, v47
	v_min_u32_e32 v29, v29, v47
	v_max_u32_e32 v47, v30, v31
	v_min_u32_e32 v30, v30, v31
	v_max_u32_e32 v31, v49, v48
	v_min_u32_e32 v48, v49, v48
	v_max_u32_e32 v49, v50, v51
	v_min_u32_e32 v50, v50, v51
	v_max_u32_e32 v51, v1, v0
	v_min_u32_e32 v0, v1, v0
	v_max_u32_e32 v1, v2, v3
	v_min_u32_e32 v2, v2, v3
	v_max_u32_e32 v3, v53, v52
	v_min_u32_e32 v52, v53, v52
	v_max_u32_e32 v43, v45, v32
	v_min_u32_e32 v32, v45, v32
	v_max_u32_e32 v45, v46, v36
	v_min_u32_e32 v36, v46, v36
	v_max_u32_e32 v46, v56, v35
	v_min_u32_e32 v35, v56, v35
	v_max_u32_e32 v56, v34, v38
	v_min_u32_e32 v34, v34, v38
	v_max_u32_e32 v38, v27, v37
	v_min_u32_e32 v27, v27, v37
	v_max_u32_e32 v37, v40, v39
	v_min_u32_e32 v39, v40, v39
	v_max_u32_e32 v40, v41, v42
	v_min_u32_e32 v41, v41, v42
	v_max_u32_e32 v42, v44, v33
	v_min_u32_e32 v33, v44, v33
	v_max_u32_e32 v53, v54, v30
	v_min_u32_e32 v30, v54, v30
	v_max_u32_e32 v54, v55, v47
	v_min_u32_e32 v47, v55, v47
	v_max_u32_e32 v55, v64, v48
	v_min_u32_e32 v48, v64, v48
	v_max_u32_e32 v64, v29, v31
	v_min_u32_e32 v29, v29, v31
	v_max_u32_e32 v31, v2, v49
	v_min_u32_e32 v2, v2, v49
	v_max_u32_e32 v49, v1, v50
	v_min_u32_e32 v1, v1, v50
	v_max_u32_e32 v50, v52, v51
	v_min_u32_e32 v51, v52, v51
	v_max_u32_e32 v52, v3, v0
	v_min_u32_e32 v0, v3, v0
	v_max_u32_e32 v44, v43, v46
	v_min_u32_e32 v43, v43, v46
	v_max_u32_e32 v46, v45, v56
	v_min_u32_e32 v45, v45, v56
	v_max_u32_e32 v56, v32, v35
	v_min_u32_e32 v32, v32, v35
	v_max_u32_e32 v35, v36, v34
	v_min_u32_e32 v34, v36, v34
	v_max_u32_e32 v36, v41, v27
	v_min_u32_e32 v27, v41, v27
	v_max_u32_e32 v41, v33, v39
	v_min_u32_e32 v33, v33, v39
	v_max_u32_e32 v39, v40, v38
	v_min_u32_e32 v38, v40, v38
	v_max_u32_e32 v40, v42, v37
	v_min_u32_e32 v37, v42, v37
	v_max_u32_e32 v3, v53, v55
	v_min_u32_e32 v53, v53, v55
	v_max_u32_e32 v55, v54, v64
	v_min_u32_e32 v54, v54, v64
	v_max_u32_e32 v64, v30, v48
	v_min_u32_e32 v30, v30, v48
	v_max_u32_e32 v48, v47, v29
	v_min_u32_e32 v29, v47, v29
	v_max_u32_e32 v47, v51, v2
	v_min_u32_e32 v2, v51, v2
	v_max_u32_e32 v51, v0, v1
	v_min_u32_e32 v0, v0, v1
	v_max_u32_e32 v1, v50, v31
	v_min_u32_e32 v31, v50, v31
	v_max_u32_e32 v50, v52, v49
	v_min_u32_e32 v49, v52, v49
	v_max_u32_e32 v42, v44, v46
	v_min_u32_e32 v44, v44, v46
	v_max_u32_e32 v46, v43, v45
	v_min_u32_e32 v43, v43, v45
	v_max_u32_e32 v45, v56, v35
	v_min_u32_e32 v35, v56, v35
	v_max_u32_e32 v56, v32, v34
	v_min_u32_e32 v32, v32, v34
	v_max_u32_e32 v34, v33, v27
	v_min_u32_e32 v27, v33, v27
	v_max_u32_e32 v33, v41, v36
	v_min_u32_e32 v36, v41, v36
	v_max_u32_e32 v41, v37, v38
	v_min_u32_e32 v37, v37, v38
	v_max_u32_e32 v38, v40, v39
	v_min_u32_e32 v39, v40, v39
	v_max_u32_e32 v52, v3, v55
	v_min_u32_e32 v3, v3, v55
	v_max_u32_e32 v55, v53, v54
	v_min_u32_e32 v53, v53, v54
	v_max_u32_e32 v54, v64, v48
	v_min_u32_e32 v48, v64, v48
	v_max_u32_e32 v64, v30, v29
	v_min_u32_e32 v29, v30, v29
	v_max_u32_e32 v30, v0, v2
	v_min_u32_e32 v0, v0, v2
	v_max_u32_e32 v2, v51, v47
	v_min_u32_e32 v47, v51, v47
	v_max_u32_e32 v51, v49, v31
	v_min_u32_e32 v31, v49, v31
	v_max_u32_e32 v49, v50, v1
	v_min_u32_e32 v1, v50, v1
	v_max_u32_e32 v40, v42, v27
	v_min_u32_e32 v27, v42, v27
	v_max_u32_e32 v42, v44, v34
	v_min_u32_e32 v34, v44, v34
	v_max_u32_e32 v44, v46, v36
	v_min_u32_e32 v36, v46, v36
	v_max_u32_e32 v46, v43, v33
	v_min_u32_e32 v33, v43, v33
	v_max_u32_e32 v43, v45, v37
	v_min_u32_e32 v37, v45, v37
	v_max_u32_e32 v45, v35, v41
	v_min_u32_e32 v35, v35, v41
	v_max_u32_e32 v41, v56, v39
	v_min_u32_e32 v39, v56, v39
	v_max_u32_e32 v56, v32, v38
	v_min_u32_e32 v32, v32, v38
	v_max_u32_e32 v50, v52, v0
	v_min_u32_e32 v0, v52, v0
	v_max_u32_e32 v52, v3, v30
	v_min_u32_e32 v3, v3, v30
	v_max_u32_e32 v30, v55, v47
	v_min_u32_e32 v47, v55, v47
	v_max_u32_e32 v55, v53, v2
	v_min_u32_e32 v2, v53, v2
	v_max_u32_e32 v53, v54, v31
	v_min_u32_e32 v31, v54, v31
	v_max_u32_e32 v54, v48, v51
	v_min_u32_e32 v48, v48, v51
	v_max_u32_e32 v51, v64, v1
	v_min_u32_e32 v1, v64, v1
	v_max_u32_e32 v64, v29, v49
	v_min_u32_e32 v29, v29, v49
	v_max_u32_e32 v38, v40, v43
	v_min_u32_e32 v40, v40, v43
; #define CE_DESC(a, b) do { const unsigned _mx = (a) > (b) ? (a) : (b), _mn = (a) > (b) ? (b) : (a); (a) = _mx; (b) = _mn; } while (0)
; __device__ __forceinline__ void merge16(unsigned (&a)[16], const unsigned (&b)[16]) {
; #pragma unroll
;     for (int i = 0; i < 16; ++i) a[i] = a[i] > b[15 - i] ? a[i] : b[15 - i];
; #pragma unroll
;     for (int stride = 8; stride > 0; stride >>= 1)
; #pragma unroll
;         for (int i = 0; i < 16; ++i) { const int j = i ^ stride; if (j > i) CE_DESC(a[i], a[j]); }
; }
; __device__ __forceinline__ void peer_tile(const Args& A, LAS unsigned char* lds, int tile) {
;     ...
;                 sort16_desc(k0); sort16_desc(k1); merge16(k0, k1);
; #pragma unroll
;                 for (int msk = 16; msk <= 32; msk <<= 1) {
; #pragma unroll
;                     for (int i = 0; i < 16; ++i) k1[i] = (unsigned)__shfl_xor((int)k0[i], msk);
;                     merge16(k0, k1); }
	v_max_u32_e32 v43, v42, v45
	v_min_u32_e32 v42, v42, v45
	v_max_u32_e32 v45, v44, v41
	v_min_u32_e32 v41, v44, v41
	v_max_u32_e32 v44, v46, v56
	v_min_u32_e32 v46, v46, v56
	v_max_u32_e32 v56, v27, v37
	v_min_u32_e32 v27, v27, v37
	v_max_u32_e32 v37, v34, v35
	v_min_u32_e32 v34, v34, v35
	v_max_u32_e32 v35, v36, v39
	v_min_u32_e32 v36, v36, v39
	v_max_u32_e32 v39, v33, v32
	v_min_u32_e32 v32, v33, v32
	v_max_u32_e32 v49, v50, v53
	v_min_u32_e32 v50, v50, v53
	v_max_u32_e32 v53, v52, v54
	v_min_u32_e32 v52, v52, v54
	v_max_u32_e32 v54, v30, v51
	v_min_u32_e32 v30, v30, v51
	v_max_u32_e32 v51, v55, v64
	v_min_u32_e32 v55, v55, v64
	v_max_u32_e32 v64, v0, v31
	v_min_u32_e32 v0, v0, v31
	v_max_u32_e32 v31, v3, v48
	v_min_u32_e32 v3, v3, v48
	v_max_u32_e32 v48, v47, v1
	v_min_u32_e32 v1, v47, v1
	v_max_u32_e32 v47, v2, v29
	v_min_u32_e32 v2, v2, v29
	v_max_u32_e32 v33, v38, v45
	v_min_u32_e32 v38, v38, v45
	v_max_u32_e32 v45, v43, v44
	v_min_u32_e32 v43, v43, v44
	v_max_u32_e32 v44, v40, v41
	v_min_u32_e32 v40, v40, v41
	v_max_u32_e32 v41, v42, v46
	v_min_u32_e32 v42, v42, v46
	v_max_u32_e32 v46, v56, v35
	v_min_u32_e32 v35, v56, v35
	v_max_u32_e32 v56, v37, v39
	v_min_u32_e32 v37, v37, v39
	v_max_u32_e32 v39, v27, v36
	v_min_u32_e32 v27, v27, v36
	v_max_u32_e32 v36, v34, v32
	v_min_u32_e32 v32, v34, v32
	v_max_u32_e32 v29, v49, v54
	v_min_u32_e32 v49, v49, v54
	v_max_u32_e32 v54, v53, v51
	v_min_u32_e32 v51, v53, v51
	v_max_u32_e32 v53, v50, v30
	v_min_u32_e32 v30, v50, v30
	v_max_u32_e32 v50, v52, v55
	v_min_u32_e32 v52, v52, v55
	v_max_u32_e32 v55, v64, v48
	v_min_u32_e32 v48, v64, v48
	v_max_u32_e32 v64, v31, v47
	v_min_u32_e32 v31, v31, v47
	v_max_u32_e32 v47, v0, v1
	v_min_u32_e32 v0, v0, v1
	v_max_u32_e32 v1, v3, v2
	v_min_u32_e32 v2, v3, v2
	v_min_u32_e32 v34, v33, v45
	v_min_u32_e32 v57, v38, v43
	v_min_u32_e32 v58, v44, v41
	v_min_u32_e32 v59, v40, v42
	v_min_u32_e32 v60, v46, v56
	v_min_u32_e32 v61, v35, v37
	v_min_u32_e32 v62, v39, v36
	v_min_u32_e32 v63, v27, v32
	v_min_u32_e32 v3, v29, v54
	v_min_u32_e32 v65, v49, v51
	v_min_u32_e32 v66, v53, v50
	v_min_u32_e32 v67, v30, v52
	v_min_u32_e32 v68, v55, v64
	v_min_u32_e32 v69, v48, v31
	v_min_u32_e32 v70, v47, v1
	v_min_u32_e32 v71, v0, v2
	v_max3_u32 v33, v33, v45, v71
	v_max3_u32 v0, v34, v0, v2
	v_max3_u32 v2, v38, v43, v70
	v_max3_u32 v1, v57, v47, v1
	v_max3_u32 v34, v44, v41, v69
	v_max3_u32 v31, v58, v48, v31
	v_max3_u32 v38, v40, v42, v68
	v_max3_u32 v40, v59, v55, v64
	v_max3_u32 v41, v46, v56, v67
	v_max3_u32 v30, v60, v30, v52
	v_max3_u32 v35, v35, v37, v66
	v_max3_u32 v37, v61, v53, v50
	v_max3_u32 v36, v39, v36, v65
	v_max3_u32 v39, v62, v49, v51
	v_max3_u32 v3, v27, v32, v3
	v_max3_u32 v27, v63, v29, v54
	v_max_u32_e32 v29, v33, v41
	v_min_u32_e32 v32, v33, v41
	v_max_u32_e32 v33, v0, v30
	v_min_u32_e32 v0, v0, v30
	v_max_u32_e32 v30, v2, v35
	v_min_u32_e32 v2, v2, v35
	v_max_u32_e32 v35, v1, v37
	v_min_u32_e32 v1, v1, v37
	v_max_u32_e32 v37, v34, v36
	v_min_u32_e32 v34, v34, v36
	v_max_u32_e32 v36, v31, v39
	v_min_u32_e32 v31, v31, v39
	v_max_u32_e32 v39, v38, v3
	v_min_u32_e32 v3, v38, v3
	v_max_u32_e32 v38, v40, v27
	v_min_u32_e32 v27, v40, v27
	v_max_u32_e32 v40, v29, v37
	v_min_u32_e32 v29, v29, v37
	v_max_u32_e32 v37, v33, v36
	v_min_u32_e32 v33, v33, v36
	v_max_u32_e32 v36, v30, v39
	v_min_u32_e32 v30, v30, v39
	v_max_u32_e32 v39, v35, v38
	v_min_u32_e32 v35, v35, v38
	v_max_u32_e32 v38, v32, v34
	v_min_u32_e32 v32, v32, v34
	v_max_u32_e32 v34, v0, v31
	v_min_u32_e32 v0, v0, v31
	v_max_u32_e32 v31, v2, v3
	v_min_u32_e32 v2, v2, v3
	v_max_u32_e32 v3, v1, v27
	v_min_u32_e32 v1, v1, v27
	v_max_u32_e32 v27, v40, v36
	v_min_u32_e32 v36, v40, v36
	v_max_u32_e32 v40, v37, v39
	v_min_u32_e32 v37, v37, v39
	v_max_u32_e32 v39, v29, v30
	v_min_u32_e32 v29, v29, v30
	v_max_u32_e32 v30, v33, v35
	v_min_u32_e32 v33, v33, v35
	v_max_u32_e32 v35, v38, v31
	v_min_u32_e32 v31, v38, v31
	v_max_u32_e32 v38, v34, v3
	v_min_u32_e32 v3, v34, v3
	v_max_u32_e32 v34, v32, v2
	v_min_u32_e32 v2, v32, v2
	v_max_u32_e32 v32, v0, v1
	v_min_u32_e32 v0, v0, v1
	v_cmp_lt_i32_e32 vcc, v217, v216
	v_max_u32_e32 v41, v36, v37
	v_min_u32_e32 v36, v36, v37
	v_max_u32_e32 v37, v39, v30
	v_min_u32_e32 v30, v39, v30
	v_max_u32_e32 v39, v29, v33
	v_min_u32_e32 v29, v29, v33
	v_max_u32_e32 v33, v35, v38
	v_min_u32_e32 v35, v35, v38
	v_max_u32_e32 v38, v31, v3
	v_min_u32_e32 v3, v31, v3
	v_max_u32_e32 v31, v34, v32
	v_min_u32_e32 v32, v34, v32
	v_max_u32_e32 v34, v2, v0
	v_min_u32_e32 v0, v2, v0
	v_cndmask_b32_e32 v2, v215, v217, vcc
	v_max_u32_e32 v1, v27, v40
	v_min_u32_e32 v40, v27, v40
	v_lshlrev_b32_e32 v27, 2, v2
	ds_bpermute_b32 v2, v27, v1
	ds_bpermute_b32 v42, v27, v40
	ds_bpermute_b32 v43, v27, v41
	ds_bpermute_b32 v44, v27, v36
	ds_bpermute_b32 v45, v27, v37
	ds_bpermute_b32 v46, v27, v30
	ds_bpermute_b32 v47, v27, v39
	ds_bpermute_b32 v48, v27, v29
	ds_bpermute_b32 v49, v27, v33
	ds_bpermute_b32 v50, v27, v35
	ds_bpermute_b32 v51, v27, v38
	ds_bpermute_b32 v52, v27, v0
	ds_bpermute_b32 v53, v27, v34
	ds_bpermute_b32 v54, v27, v32
	ds_bpermute_b32 v55, v27, v31
	ds_bpermute_b32 v56, v27, v3
	s_waitcnt lgkmcnt(4)
	v_max_u32_e32 v1, v1, v52
	s_waitcnt lgkmcnt(3)
	v_max_u32_e32 v40, v40, v53
	s_waitcnt lgkmcnt(2)
	v_max_u32_e32 v41, v41, v54
	s_waitcnt lgkmcnt(1)
	v_max_u32_e32 v36, v36, v55
	s_waitcnt lgkmcnt(0)
; __device__ __forceinline__ unsigned f2key(float f) { const unsigned u = __float_as_uint(f); return (u & 0x80000000u) ? ~u : (u | 0x80000000u); }
; __device__ __forceinline__ void peer_tile(const Args& A, LAS unsigned char* lds, int tile) {
;     ...
;                 const int hp = 2 * h + p;
;                 unsigned k0[16], k1[16];
;                 { const bf16_t* sp = QRY + m * 2048 + hp * 128 + 32 * g;
;                   const u32x4 s0 = *(const u32x4*)sp, s1 = *(const u32x4*)(sp + 8), s2 = *(const u32x4*)(sp + 16), s3 = *(const u32x4*)(sp + 24);
;                   const unsigned sw[16] = {s0.x, s0.y, s0.z, s0.w, s1.x, s1.y, s1.z, s1.w, s2.x, s2.y, s2.z, s2.w, s3.x, s3.y, s3.z, s3.w};
; #pragma unroll
;                   for (int i = 0; i < 16; ++i) {
;                       const float lo = (float)__builtin_bit_cast(_Float16, (unsigned short)(sw[i] & 0xffffu)), hi = (float)__builtin_bit_cast(_Float16, (unsigned short)(sw[i] >> 16));
;                       const unsigned klo = (f2key(lo) & ~127u) | (unsigned)(127 - (32 * g + 2 * i)), khi = (f2key(hi) & ~127u) | (unsigned)(127 - (32 * g + 2 * i + 1));
;                       if (i < 8) { k0[2 * i] = klo; k0[2 * i + 1] = khi; } else { k1[2 * (i - 8)] = klo; k1[2 * (i - 8) + 1] = khi; } } }
;                 sort16_desc(k0); sort16_desc(k1); merge16(k0, k1);
; #pragma unroll
;                 for (int msk = 16; msk <= 32; msk <<= 1) {
; #pragma unroll
;                     for (int i = 0; i < 16; ++i) k1[i] = (unsigned)__shfl_xor((int)k0[i], msk);
;                     merge16(k0, k1); }
	v_max_u32_e32 v37, v37, v56
	v_max_u32_e32 v30, v30, v51
	v_max_u32_e32 v39, v39, v50
	v_max_u32_e32 v29, v29, v49
	v_max_u32_e32 v33, v33, v48
	v_max_u32_e32 v35, v35, v47
	v_max_u32_e32 v38, v38, v46
	v_max_u32_e32 v3, v3, v45
	v_max_u32_e32 v31, v31, v44
	v_max_u32_e32 v32, v32, v43
	v_max_u32_e32 v34, v34, v42
	v_max_u32_e32 v0, v0, v2
	v_max_u32_e32 v2, v1, v33
	v_min_u32_e32 v1, v1, v33
	v_max_u32_e32 v33, v40, v35
	v_min_u32_e32 v35, v40, v35
	v_max_u32_e32 v40, v41, v38
	v_min_u32_e32 v38, v41, v38
	v_max_u32_e32 v41, v36, v3
	v_min_u32_e32 v3, v36, v3
	v_max_u32_e32 v36, v37, v31
	v_min_u32_e32 v31, v37, v31
	v_max_u32_e32 v37, v30, v32
	v_min_u32_e32 v30, v30, v32
	v_max_u32_e32 v32, v39, v34
	v_min_u32_e32 v34, v39, v34
	v_max_u32_e32 v39, v29, v0
	v_min_u32_e32 v0, v29, v0
	v_max_u32_e32 v29, v2, v36
	v_min_u32_e32 v2, v2, v36
	v_max_u32_e32 v36, v33, v37
	v_min_u32_e32 v33, v33, v37
	v_max_u32_e32 v37, v40, v32
	v_min_u32_e32 v32, v40, v32
	v_max_u32_e32 v40, v41, v39
	v_min_u32_e32 v39, v41, v39
	v_max_u32_e32 v41, v1, v31
	v_min_u32_e32 v1, v1, v31
	v_max_u32_e32 v31, v35, v30
	v_min_u32_e32 v30, v35, v30
	v_max_u32_e32 v35, v38, v34
	v_min_u32_e32 v34, v38, v34
	v_max_u32_e32 v38, v3, v0
	v_min_u32_e32 v0, v3, v0
	v_max_u32_e32 v3, v29, v37
	v_min_u32_e32 v29, v29, v37
	v_max_u32_e32 v37, v36, v40
	v_min_u32_e32 v36, v36, v40
	v_max_u32_e32 v40, v2, v32
	v_min_u32_e32 v2, v2, v32
	v_max_u32_e32 v32, v33, v39
	v_min_u32_e32 v33, v33, v39
	v_max_u32_e32 v39, v41, v35
	v_min_u32_e32 v35, v41, v35
	v_max_u32_e32 v41, v31, v38
	v_min_u32_e32 v31, v31, v38
	v_max_u32_e32 v38, v1, v34
	v_min_u32_e32 v1, v1, v34
	v_max_u32_e32 v34, v30, v0
	v_min_u32_e32 v0, v30, v0
	v_cmp_lt_i32_e32 vcc, v218, v216
	v_max_u32_e32 v42, v40, v32
	v_min_u32_e32 v32, v40, v32
	v_max_u32_e32 v40, v2, v33
	v_min_u32_e32 v2, v2, v33
	v_max_u32_e32 v33, v39, v41
	v_min_u32_e32 v39, v39, v41
	v_max_u32_e32 v41, v35, v31
	v_min_u32_e32 v31, v35, v31
	v_max_u32_e32 v35, v38, v34
	v_min_u32_e32 v34, v38, v34
	v_max_u32_e32 v38, v1, v0
	v_min_u32_e32 v0, v1, v0
	v_cndmask_b32_e32 v1, v215, v218, vcc
	v_max_u32_e32 v30, v3, v37
	v_min_u32_e32 v3, v3, v37
	v_max_u32_e32 v37, v29, v36
	v_min_u32_e32 v36, v29, v36
	v_lshlrev_b32_e32 v29, 2, v1
	ds_bpermute_b32 v46, v29, v0
	ds_bpermute_b32 v1, v29, v30
	ds_bpermute_b32 v43, v29, v3
	ds_bpermute_b32 v44, v29, v37
	ds_bpermute_b32 v45, v29, v36
	s_waitcnt lgkmcnt(4)
	v_max_u32_e32 v30, v30, v46
	global_load_dwordx4 v[46:49], v[4:5], off offset:272
	global_load_dwordx4 v[50:53], v[4:5], off offset:256
	ds_bpermute_b32 v54, v29, v42
	ds_bpermute_b32 v55, v29, v32
	ds_bpermute_b32 v56, v29, v40
	ds_bpermute_b32 v57, v29, v2
	ds_bpermute_b32 v58, v29, v33
	ds_bpermute_b32 v59, v29, v39
	ds_bpermute_b32 v60, v29, v41
	ds_bpermute_b32 v61, v29, v31
	ds_bpermute_b32 v62, v29, v35
	ds_bpermute_b32 v63, v29, v38
	ds_bpermute_b32 v64, v29, v34
	s_waitcnt lgkmcnt(4)
	v_max_u32_e32 v32, v32, v60
	s_waitcnt lgkmcnt(3)
	v_max_u32_e32 v42, v42, v61
	s_waitcnt lgkmcnt(2)
	v_max_u32_e32 v36, v36, v62
	s_waitcnt lgkmcnt(1)
	v_max_u32_e32 v3, v3, v63
	s_waitcnt lgkmcnt(0)
	v_max_u32_e32 v37, v37, v64
	v_max_u32_e32 v40, v40, v59
	v_max_u32_e32 v2, v2, v58
	v_max_u32_e32 v33, v33, v57
	v_max_u32_e32 v39, v39, v56
	v_max_u32_e32 v41, v41, v55
	v_max_u32_e32 v31, v31, v54
	v_max_u32_e32 v35, v35, v45
	v_max_u32_e32 v34, v34, v44
	v_max_u32_e32 v38, v38, v43
	v_max_u32_e32 v0, v0, v1
	v_max_u32_e32 v1, v30, v33
	v_min_u32_e32 v30, v30, v33
	v_max_u32_e32 v33, v3, v39
	v_min_u32_e32 v3, v3, v39
	v_max_u32_e32 v39, v37, v41
	v_min_u32_e32 v37, v37, v41
	v_max_u32_e32 v41, v36, v31
	v_min_u32_e32 v31, v36, v31
	v_max_u32_e32 v36, v42, v35
	v_min_u32_e32 v35, v42, v35
	v_max_u32_e32 v42, v32, v34
	v_min_u32_e32 v32, v32, v34
	v_max_u32_e32 v34, v40, v38
	v_min_u32_e32 v38, v40, v38
	v_max_u32_e32 v40, v2, v0
	v_min_u32_e32 v0, v2, v0
	v_max_u32_e32 v2, v1, v36
	v_min_u32_e32 v1, v1, v36
	v_max_u32_e32 v36, v33, v42
	v_min_u32_e32 v33, v33, v42
	v_max_u32_e32 v42, v39, v34
	v_min_u32_e32 v34, v39, v34
	v_max_u32_e32 v39, v41, v40
	v_min_u32_e32 v40, v41, v40
	v_max_u32_e32 v41, v30, v35
	v_min_u32_e32 v30, v30, v35
	v_max_u32_e32 v35, v3, v32
	v_min_u32_e32 v3, v3, v32
	v_max_u32_e32 v32, v37, v38
	v_min_u32_e32 v37, v37, v38
	v_max_u32_e32 v38, v31, v0
	v_min_u32_e32 v0, v31, v0
	v_max_u32_e32 v31, v2, v42
	v_min_u32_e32 v2, v2, v42
	v_max_u32_e32 v42, v36, v39
	v_min_u32_e32 v36, v36, v39
	v_max_u32_e32 v39, v1, v34
	v_min_u32_e32 v1, v1, v34
	v_max_u32_e32 v34, v33, v40
	v_min_u32_e32 v33, v33, v40
	v_max_u32_e32 v54, v41, v32
	v_min_u32_e32 v32, v41, v32
	v_max_u32_e32 v55, v35, v38
	v_min_u32_e32 v56, v35, v38
	v_max_u32_e32 v57, v30, v37
	v_min_u32_e32 v30, v30, v37
	v_max_u32_e32 v58, v3, v0
	v_min_u32_e32 v0, v3, v0
	v_max_u32_e32 v45, v31, v42
	v_min_u32_e32 v44, v31, v42
	v_max_u32_e32 v43, v2, v36
	v_min_u32_e32 v42, v2, v36
	v_max_u32_e32 v41, v39, v34
	v_min_u32_e32 v40, v39, v34
	v_max_u32_e32 v39, v1, v33
	v_min_u32_e32 v38, v1, v33
	v_max_u32_e32 v37, v54, v55
	v_min_u32_e32 v36, v54, v55
	v_max_u32_e32 v35, v32, v56
	v_min_u32_e32 v34, v32, v56
	v_max_u32_e32 v33, v57, v58
	v_min_u32_e32 v32, v57, v58
	v_max_u32_e32 v31, v30, v0
	v_min_u32_e32 v30, v30, v0
	global_load_dwordx4 v[0:3], v[4:5], off offset:304
	global_load_dwordx4 v[54:57], v[4:5], off offset:288
	s_waitcnt vmcnt(2)
; __device__ __forceinline__ unsigned f2key(float f) { const unsigned u = __float_as_uint(f); return (u & 0x80000000u) ? ~u : (u | 0x80000000u); }
; __device__ __forceinline__ void peer_tile(const Args& A, LAS unsigned char* lds, int tile) {
;     ...
;                 { const bf16_t* sp = QRY + m * 2048 + hp * 128 + 32 * g;
;                   const u32x4 s0 = *(const u32x4*)sp, s1 = *(const u32x4*)(sp + 8), s2 = *(const u32x4*)(sp + 16), s3 = *(const u32x4*)(sp + 24);
;                   const unsigned sw[16] = {s0.x, s0.y, s0.z, s0.w, s1.x, s1.y, s1.z, s1.w, s2.x, s2.y, s2.z, s2.w, s3.x, s3.y, s3.z, s3.w};
; #pragma unroll
;                   for (int i = 0; i < 16; ++i) {
;                       const float lo = (float)__builtin_bit_cast(_Float16, (unsigned short)(sw[i] & 0xffffu)), hi = (float)__builtin_bit_cast(_Float16, (unsigned short)(sw[i] >> 16));
;                       const unsigned klo = (f2key(lo) & ~127u) | (unsigned)(127 - (32 * g + 2 * i)), khi = (f2key(hi) & ~127u) | (unsigned)(127 - (32 * g + 2 * i + 1));
;                       if (i < 8) { k0[2 * i] = klo; k0[2 * i + 1] = khi; } else { k1[2 * (i - 8)] = klo; k1[2 * (i - 8) + 1] = khi; } } }
	v_cvt_f32_f16_sdwa v58, v50 dst_sel:DWORD dst_unused:UNUSED_PAD src0_sel:WORD_1
	v_cvt_f32_f16_e32 v50, v50
	v_not_b32_e32 v59, v58
	v_or_b32_e32 v60, 0x80000000, v58
	v_cmp_gt_i32_e32 vcc, 0, v58
	s_nop 1
	v_cndmask_b32_e32 v58, v60, v59, vcc
	v_not_b32_e32 v59, v50
	v_or_b32_e32 v60, 0x80000000, v50
	v_cmp_gt_i32_e32 vcc, 0, v50
	v_and_b32_e32 v58, 0xffffff80, v58
	v_sub_u32_e32 v58, v58, v15
	v_cndmask_b32_e32 v50, v60, v59, vcc
	v_cvt_f32_f16_sdwa v59, v51 dst_sel:DWORD dst_unused:UNUSED_PAD src0_sel:WORD_1
	v_cvt_f32_f16_e32 v51, v51
	v_and_b32_e32 v50, 0xffffff80, v50
	v_sub_u32_e32 v50, v50, v15
	v_not_b32_e32 v60, v59
	v_or_b32_e32 v61, 0x80000000, v59
	v_cmp_gt_i32_e32 vcc, 0, v59
	v_add_u32_e32 v58, 0x7e, v58
	v_add_u32_e32 v50, 0x7f, v50
	v_cndmask_b32_e32 v59, v61, v60, vcc
	v_not_b32_e32 v60, v51
	v_or_b32_e32 v61, 0x80000000, v51
	v_cmp_gt_i32_e32 vcc, 0, v51
	v_and_b32_e32 v59, 0xffffff80, v59
	v_sub_u32_e32 v59, v59, v14
	v_cndmask_b32_e32 v51, v61, v60, vcc
	v_cvt_f32_f16_sdwa v60, v52 dst_sel:DWORD dst_unused:UNUSED_PAD src0_sel:WORD_1
	v_cvt_f32_f16_e32 v52, v52
	v_and_b32_e32 v51, 0xffffff80, v51
	v_sub_u32_e32 v51, v51, v14
	v_not_b32_e32 v61, v60
	v_or_b32_e32 v62, 0x80000000, v60
	v_cmp_gt_i32_e32 vcc, 0, v60
	v_add_u32_e32 v59, 0x7e, v59
	v_add_u32_e32 v51, 0x7f, v51
	v_cndmask_b32_e32 v60, v62, v61, vcc
	v_not_b32_e32 v61, v52
	v_or_b32_e32 v62, 0x80000000, v52
	v_cmp_gt_i32_e32 vcc, 0, v52
	v_and_b32_e32 v60, 0xffffff80, v60
	v_sub_u32_e32 v60, v60, v12
	v_cndmask_b32_e32 v52, v62, v61, vcc
	v_cvt_f32_f16_sdwa v61, v53 dst_sel:DWORD dst_unused:UNUSED_PAD src0_sel:WORD_1
	v_cvt_f32_f16_e32 v53, v53
	v_and_b32_e32 v52, 0xffffff80, v52
	v_sub_u32_e32 v52, v52, v12
	v_not_b32_e32 v62, v61
	v_or_b32_e32 v63, 0x80000000, v61
	v_cmp_gt_i32_e32 vcc, 0, v61
	v_add_u32_e32 v60, 0x7e, v60
	v_add_u32_e32 v52, 0x7f, v52
	v_cndmask_b32_e32 v61, v63, v62, vcc
	v_not_b32_e32 v62, v53
	v_or_b32_e32 v63, 0x80000000, v53
	v_cmp_gt_i32_e32 vcc, 0, v53
	v_and_b32_e32 v61, 0xffffff80, v61
	v_sub_u32_e32 v61, v61, v10
	v_cndmask_b32_e32 v53, v63, v62, vcc
	v_cvt_f32_f16_sdwa v62, v46 dst_sel:DWORD dst_unused:UNUSED_PAD src0_sel:WORD_1
	v_cvt_f32_f16_e32 v46, v46
	v_and_b32_e32 v53, 0xffffff80, v53
	v_sub_u32_e32 v53, v53, v10
	v_not_b32_e32 v63, v62
	v_or_b32_e32 v64, 0x80000000, v62
	v_cmp_gt_i32_e32 vcc, 0, v62
	v_add_u32_e32 v61, 0x7e, v61
	v_add_u32_e32 v53, 0x7f, v53
	v_cndmask_b32_e32 v62, v64, v63, vcc
	v_not_b32_e32 v63, v46
	v_or_b32_e32 v64, 0x80000000, v46
	v_cmp_gt_i32_e32 vcc, 0, v46
	v_and_b32_e32 v62, 0xffffff80, v62
	v_sub_u32_e32 v62, v62, v8
	v_cndmask_b32_e32 v46, v64, v63, vcc
	v_cvt_f32_f16_sdwa v63, v47 dst_sel:DWORD dst_unused:UNUSED_PAD src0_sel:WORD_1
	v_cvt_f32_f16_e32 v47, v47
	v_and_b32_e32 v46, 0xffffff80, v46
	v_sub_u32_e32 v46, v46, v8
	v_not_b32_e32 v64, v63
	v_or_b32_e32 v65, 0x80000000, v63
	v_cmp_gt_i32_e32 vcc, 0, v63
	v_add_u32_e32 v62, 0x7e, v62
	v_add_u32_e32 v46, 0x7f, v46
	v_cndmask_b32_e32 v63, v65, v64, vcc
	v_not_b32_e32 v64, v47
	v_or_b32_e32 v65, 0x80000000, v47
	v_cmp_gt_i32_e32 vcc, 0, v47
	v_and_b32_e32 v63, 0xffffff80, v63
	v_sub_u32_e32 v63, v63, v16
	v_cndmask_b32_e32 v47, v65, v64, vcc
	v_cvt_f32_f16_sdwa v64, v48 dst_sel:DWORD dst_unused:UNUSED_PAD src0_sel:WORD_1
	v_cvt_f32_f16_e32 v48, v48
	v_and_b32_e32 v47, 0xffffff80, v47
	v_sub_u32_e32 v47, v47, v16
	v_not_b32_e32 v65, v64
	v_or_b32_e32 v66, 0x80000000, v64
	v_cmp_gt_i32_e32 vcc, 0, v64
	v_add_u32_e32 v63, 0x7e, v63
	v_add_u32_e32 v47, 0x7f, v47
	v_cndmask_b32_e32 v64, v66, v65, vcc
	v_not_b32_e32 v65, v48
	v_or_b32_e32 v66, 0x80000000, v48
	v_cmp_gt_i32_e32 vcc, 0, v48
	v_and_b32_e32 v64, 0xffffff80, v64
	v_sub_u32_e32 v64, v64, v17
	v_cndmask_b32_e32 v48, v66, v65, vcc
	v_cvt_f32_f16_sdwa v65, v49 dst_sel:DWORD dst_unused:UNUSED_PAD src0_sel:WORD_1
	v_cvt_f32_f16_e32 v49, v49
	v_and_b32_e32 v48, 0xffffff80, v48
	v_sub_u32_e32 v48, v48, v17
	v_not_b32_e32 v66, v65
	v_or_b32_e32 v67, 0x80000000, v65
	v_cmp_gt_i32_e32 vcc, 0, v65
	v_add_u32_e32 v64, 0x7e, v64
	v_add_u32_e32 v48, 0x7f, v48
	v_cndmask_b32_e32 v65, v67, v66, vcc
	v_not_b32_e32 v66, v49
	v_or_b32_e32 v67, 0x80000000, v49
	v_cmp_gt_i32_e32 vcc, 0, v49
	v_and_b32_e32 v65, 0xffffff80, v65
	v_sub_u32_e32 v65, v65, v18
	v_cndmask_b32_e32 v49, v67, v66, vcc
	s_waitcnt vmcnt(0)
; __device__ __forceinline__ unsigned f2key(float f) { const unsigned u = __float_as_uint(f); return (u & 0x80000000u) ? ~u : (u | 0x80000000u); }
; #define CE_DESC(a, b) do { const unsigned _mx = (a) > (b) ? (a) : (b), _mn = (a) > (b) ? (b) : (a); (a) = _mx; (b) = _mn; } while (0)
; __device__ __forceinline__ void sort16_desc(unsigned (&k)[16]) {
; #pragma unroll
;     for (int size = 2; size <= 16; size <<= 1)
; #pragma unroll
;         for (int stride = size >> 1; stride > 0; stride >>= 1)
; #pragma unroll
;             for (int i = 0; i < 16; ++i) { const int j = i ^ stride;
;                 if (j > i) { if ((i & size) == 0) CE_DESC(k[i], k[j]); else CE_DESC(k[j], k[i]); } }
; }
; __device__ __forceinline__ void peer_tile(const Args& A, LAS unsigned char* lds, int tile) {
;     ...
;                 { const bf16_t* sp = QRY + m * 2048 + hp * 128 + 32 * g;
;                   const u32x4 s0 = *(const u32x4*)sp, s1 = *(const u32x4*)(sp + 8), s2 = *(const u32x4*)(sp + 16), s3 = *(const u32x4*)(sp + 24);
;                   const unsigned sw[16] = {s0.x, s0.y, s0.z, s0.w, s1.x, s1.y, s1.z, s1.w, s2.x, s2.y, s2.z, s2.w, s3.x, s3.y, s3.z, s3.w};
; #pragma unroll
;                   for (int i = 0; i < 16; ++i) {
;                       const float lo = (float)__builtin_bit_cast(_Float16, (unsigned short)(sw[i] & 0xffffu)), hi = (float)__builtin_bit_cast(_Float16, (unsigned short)(sw[i] >> 16));
;                       const unsigned klo = (f2key(lo) & ~127u) | (unsigned)(127 - (32 * g + 2 * i)), khi = (f2key(hi) & ~127u) | (unsigned)(127 - (32 * g + 2 * i + 1));
;                       if (i < 8) { k0[2 * i] = klo; k0[2 * i + 1] = khi; } else { k1[2 * (i - 8)] = klo; k1[2 * (i - 8) + 1] = khi; } } }
;                 sort16_desc(k0); sort16_desc(k1); merge16(k0, k1);
	v_cvt_f32_f16_sdwa v66, v54 dst_sel:DWORD dst_unused:UNUSED_PAD src0_sel:WORD_1
	v_cvt_f32_f16_e32 v54, v54
	v_and_b32_e32 v49, 0xffffff80, v49
	v_sub_u32_e32 v49, v49, v18
	v_not_b32_e32 v67, v66
	v_or_b32_e32 v68, 0x80000000, v66
	v_cmp_gt_i32_e32 vcc, 0, v66
	v_add_u32_e32 v65, 0x7e, v65
	v_add_u32_e32 v49, 0x7f, v49
	v_cndmask_b32_e32 v66, v68, v67, vcc
	v_not_b32_e32 v67, v54
	v_or_b32_e32 v68, 0x80000000, v54
	v_cmp_gt_i32_e32 vcc, 0, v54
	v_and_b32_e32 v66, 0xffffff80, v66
	v_sub_u32_e32 v66, v66, v20
	v_cndmask_b32_e32 v54, v68, v67, vcc
	v_cvt_f32_f16_sdwa v67, v55 dst_sel:DWORD dst_unused:UNUSED_PAD src0_sel:WORD_1
	v_cvt_f32_f16_e32 v55, v55
	v_and_b32_e32 v54, 0xffffff80, v54
	v_sub_u32_e32 v54, v54, v20
	v_not_b32_e32 v68, v67
	v_or_b32_e32 v69, 0x80000000, v67
	v_cmp_gt_i32_e32 vcc, 0, v67
	v_add_u32_e32 v66, 0x7e, v66
	v_add_u32_e32 v54, 0x7f, v54
	v_cndmask_b32_e32 v67, v69, v68, vcc
	v_not_b32_e32 v68, v55
	v_or_b32_e32 v69, 0x80000000, v55
	v_cmp_gt_i32_e32 vcc, 0, v55
	v_and_b32_e32 v67, 0xffffff80, v67
	v_sub_u32_e32 v67, v67, v21
	v_cndmask_b32_e32 v55, v69, v68, vcc
	v_cvt_f32_f16_sdwa v68, v56 dst_sel:DWORD dst_unused:UNUSED_PAD src0_sel:WORD_1
	v_cvt_f32_f16_e32 v56, v56
	v_and_b32_e32 v55, 0xffffff80, v55
	v_sub_u32_e32 v55, v55, v21
	v_not_b32_e32 v69, v68
	v_or_b32_e32 v70, 0x80000000, v68
	v_cmp_gt_i32_e32 vcc, 0, v68
	v_add_u32_e32 v67, 0x7e, v67
	v_add_u32_e32 v55, 0x7f, v55
	v_cndmask_b32_e32 v68, v70, v69, vcc
	v_not_b32_e32 v69, v56
	v_or_b32_e32 v70, 0x80000000, v56
	v_cmp_gt_i32_e32 vcc, 0, v56
	v_and_b32_e32 v68, 0xffffff80, v68
	v_sub_u32_e32 v68, v68, v22
	v_cndmask_b32_e32 v56, v70, v69, vcc
	v_cvt_f32_f16_sdwa v69, v57 dst_sel:DWORD dst_unused:UNUSED_PAD src0_sel:WORD_1
	v_cvt_f32_f16_e32 v57, v57
	v_and_b32_e32 v56, 0xffffff80, v56
	v_sub_u32_e32 v56, v56, v22
	v_not_b32_e32 v70, v69
	v_or_b32_e32 v71, 0x80000000, v69
	v_cmp_gt_i32_e32 vcc, 0, v69
	v_add_u32_e32 v68, 0x7e, v68
	v_add_u32_e32 v56, 0x7f, v56
	v_cndmask_b32_e32 v69, v71, v70, vcc
	v_not_b32_e32 v70, v57
	v_or_b32_e32 v71, 0x80000000, v57
	v_cmp_gt_i32_e32 vcc, 0, v57
	v_and_b32_e32 v69, 0xffffff80, v69
	v_sub_u32_e32 v69, v69, v23
	v_cndmask_b32_e32 v57, v71, v70, vcc
	v_cvt_f32_f16_sdwa v70, v0 dst_sel:DWORD dst_unused:UNUSED_PAD src0_sel:WORD_1
	v_cvt_f32_f16_e32 v0, v0
	v_and_b32_e32 v57, 0xffffff80, v57
	v_sub_u32_e32 v57, v57, v23
	v_not_b32_e32 v71, v70
	v_or_b32_e32 v72, 0x80000000, v70
	v_cmp_gt_i32_e32 vcc, 0, v70
	v_add_u32_e32 v69, 0x7e, v69
	v_add_u32_e32 v57, 0x7f, v57
	v_cndmask_b32_e32 v70, v72, v71, vcc
	v_not_b32_e32 v71, v0
	v_or_b32_e32 v72, 0x80000000, v0
	v_cmp_gt_i32_e32 vcc, 0, v0
	v_and_b32_e32 v70, 0xffffff80, v70
	v_sub_u32_e32 v70, v70, v24
	v_cndmask_b32_e32 v0, v72, v71, vcc
	v_cvt_f32_f16_sdwa v71, v1 dst_sel:DWORD dst_unused:UNUSED_PAD src0_sel:WORD_1
	v_cvt_f32_f16_e32 v1, v1
	v_and_b32_e32 v0, 0xffffff80, v0
	v_sub_u32_e32 v0, v0, v24
	v_not_b32_e32 v72, v71
	v_or_b32_e32 v73, 0x80000000, v71
	v_cmp_gt_i32_e32 vcc, 0, v71
	v_add_u32_e32 v70, 0x7e, v70
	v_add_u32_e32 v0, 0x7f, v0
	v_cndmask_b32_e32 v71, v73, v72, vcc
	v_not_b32_e32 v72, v1
	v_or_b32_e32 v73, 0x80000000, v1
	v_cmp_gt_i32_e32 vcc, 0, v1
	v_and_b32_e32 v71, 0xffffff80, v71
	v_sub_u32_e32 v71, v71, v25
	v_cndmask_b32_e32 v1, v73, v72, vcc
	v_cvt_f32_f16_sdwa v72, v2 dst_sel:DWORD dst_unused:UNUSED_PAD src0_sel:WORD_1
	v_cvt_f32_f16_e32 v2, v2
	v_and_b32_e32 v1, 0xffffff80, v1
	v_sub_u32_e32 v1, v1, v25
	v_not_b32_e32 v73, v72
	v_or_b32_e32 v74, 0x80000000, v72
	v_cmp_gt_i32_e32 vcc, 0, v72
	v_add_u32_e32 v71, 0x7e, v71
	v_add_u32_e32 v1, 0x7f, v1
	v_cndmask_b32_e32 v72, v74, v73, vcc
	v_not_b32_e32 v73, v2
	v_or_b32_e32 v74, 0x80000000, v2
	v_cmp_gt_i32_e32 vcc, 0, v2
	v_and_b32_e32 v72, 0xffffff80, v72
	v_sub_u32_e32 v72, v72, v26
	v_cndmask_b32_e32 v2, v74, v73, vcc
	v_cvt_f32_f16_sdwa v73, v3 dst_sel:DWORD dst_unused:UNUSED_PAD src0_sel:WORD_1
	v_cvt_f32_f16_e32 v3, v3
	v_and_b32_e32 v2, 0xffffff80, v2
	v_sub_u32_e32 v2, v2, v26
	v_not_b32_e32 v74, v73
	v_or_b32_e32 v75, 0x80000000, v73
	v_cmp_gt_i32_e32 vcc, 0, v73
	v_add_u32_e32 v72, 0x7e, v72
	v_add_u32_e32 v2, 0x7f, v2
	v_cndmask_b32_e32 v73, v75, v74, vcc
	v_not_b32_e32 v74, v3
	v_or_b32_e32 v75, 0x80000000, v3
	v_cmp_gt_i32_e32 vcc, 0, v3
	v_and_b32_e32 v73, 0xffffff80, v73
	v_sub_u32_e32 v73, v73, v28
	v_cndmask_b32_e32 v3, v75, v74, vcc
	v_and_b32_e32 v3, 0xffffff80, v3
	v_sub_u32_e32 v3, v3, v28
	v_add_u32_e32 v73, 0x7e, v73
	v_add_u32_e32 v3, 0x7f, v3
	v_max_u32_e32 v74, v50, v58
	v_min_u32_e32 v50, v50, v58
	v_max_u32_e32 v58, v59, v51
	v_min_u32_e32 v51, v59, v51
	v_max_u32_e32 v59, v52, v60
	v_min_u32_e32 v52, v52, v60
	v_max_u32_e32 v60, v61, v53
	v_min_u32_e32 v53, v61, v53
	v_max_u32_e32 v61, v46, v62
	v_min_u32_e32 v46, v46, v62
	v_max_u32_e32 v62, v63, v47
	v_min_u32_e32 v47, v63, v47
	v_max_u32_e32 v63, v48, v64
	v_min_u32_e32 v48, v48, v64
	v_max_u32_e32 v64, v65, v49
	v_min_u32_e32 v49, v65, v49
	v_max_u32_e32 v82, v54, v66
	v_min_u32_e32 v54, v54, v66
	v_max_u32_e32 v66, v67, v55
	v_min_u32_e32 v55, v67, v55
	v_max_u32_e32 v67, v56, v68
	v_min_u32_e32 v56, v56, v68
	v_max_u32_e32 v68, v69, v57
	v_min_u32_e32 v57, v69, v57
	v_max_u32_e32 v69, v0, v70
	v_min_u32_e32 v0, v0, v70
	v_max_u32_e32 v70, v71, v1
	v_min_u32_e32 v1, v71, v1
	v_max_u32_e32 v71, v2, v72
	v_min_u32_e32 v2, v2, v72
	v_max_u32_e32 v72, v73, v3
	v_min_u32_e32 v3, v73, v3
	v_max_u32_e32 v65, v74, v51
	v_min_u32_e32 v51, v74, v51
	v_max_u32_e32 v74, v50, v58
	v_min_u32_e32 v50, v50, v58
	v_max_u32_e32 v58, v53, v59
	v_min_u32_e32 v53, v53, v59
	v_max_u32_e32 v59, v60, v52
	v_min_u32_e32 v52, v60, v52
; #define CE_DESC(a, b) do { const unsigned _mx = (a) > (b) ? (a) : (b), _mn = (a) > (b) ? (b) : (a); (a) = _mx; (b) = _mn; } while (0)
; __device__ __forceinline__ void sort16_desc(unsigned (&k)[16]) {
; #pragma unroll
;     for (int size = 2; size <= 16; size <<= 1)
; #pragma unroll
;         for (int stride = size >> 1; stride > 0; stride >>= 1)
; #pragma unroll
;             for (int i = 0; i < 16; ++i) { const int j = i ^ stride;
;                 if (j > i) { if ((i & size) == 0) CE_DESC(k[i], k[j]); else CE_DESC(k[j], k[i]); } }
; }
	v_max_u32_e32 v60, v61, v47
	v_min_u32_e32 v47, v61, v47
	v_max_u32_e32 v61, v46, v62
	v_min_u32_e32 v46, v46, v62
	v_max_u32_e32 v62, v49, v63
	v_min_u32_e32 v49, v49, v63
	v_max_u32_e32 v63, v64, v48
	v_min_u32_e32 v48, v64, v48
	v_max_u32_e32 v73, v82, v55
	v_min_u32_e32 v55, v82, v55
	v_max_u32_e32 v82, v54, v66
	v_min_u32_e32 v54, v54, v66
	v_max_u32_e32 v66, v57, v67
	v_min_u32_e32 v57, v57, v67
	v_max_u32_e32 v67, v68, v56
	v_min_u32_e32 v56, v68, v56
	v_max_u32_e32 v68, v69, v1
	v_min_u32_e32 v1, v69, v1
	v_max_u32_e32 v69, v0, v70
	v_min_u32_e32 v0, v0, v70
	v_max_u32_e32 v70, v3, v71
	v_min_u32_e32 v3, v3, v71
	v_max_u32_e32 v71, v72, v2
	v_min_u32_e32 v2, v72, v2
	v_max_u32_e32 v64, v65, v74
	v_min_u32_e32 v65, v65, v74
	v_max_u32_e32 v74, v51, v50
	v_min_u32_e32 v50, v51, v50
	v_max_u32_e32 v51, v52, v53
	v_min_u32_e32 v52, v52, v53
	v_max_u32_e32 v53, v59, v58
	v_min_u32_e32 v58, v59, v58
	v_max_u32_e32 v59, v60, v61
	v_min_u32_e32 v60, v60, v61
	v_max_u32_e32 v61, v47, v46
	v_min_u32_e32 v46, v47, v46
	v_max_u32_e32 v47, v48, v49
	v_min_u32_e32 v48, v48, v49
	v_max_u32_e32 v49, v63, v62
	v_min_u32_e32 v62, v63, v62
	v_max_u32_e32 v72, v73, v82
	v_min_u32_e32 v73, v73, v82
	v_max_u32_e32 v82, v55, v54
	v_min_u32_e32 v54, v55, v54
	v_max_u32_e32 v55, v56, v57
	v_min_u32_e32 v56, v56, v57
	v_max_u32_e32 v57, v67, v66
	v_min_u32_e32 v66, v67, v66
	v_max_u32_e32 v67, v68, v69
	v_min_u32_e32 v68, v68, v69
	v_max_u32_e32 v69, v1, v0
	v_min_u32_e32 v0, v1, v0
	v_max_u32_e32 v1, v2, v3
	v_min_u32_e32 v2, v2, v3
	v_max_u32_e32 v3, v71, v70
	v_min_u32_e32 v70, v71, v70
	v_max_u32_e32 v63, v64, v52
	v_min_u32_e32 v52, v64, v52
	v_max_u32_e32 v64, v65, v51
	v_min_u32_e32 v51, v65, v51
	v_max_u32_e32 v65, v74, v58
	v_min_u32_e32 v58, v74, v58
	v_max_u32_e32 v74, v50, v53
	v_min_u32_e32 v50, v50, v53
	v_max_u32_e32 v53, v48, v59
	v_min_u32_e32 v48, v48, v59
	v_max_u32_e32 v59, v47, v60
	v_min_u32_e32 v47, v47, v60
	v_max_u32_e32 v60, v62, v61
	v_min_u32_e32 v61, v62, v61
	v_max_u32_e32 v62, v49, v46
	v_min_u32_e32 v46, v49, v46
	v_max_u32_e32 v71, v72, v56
	v_min_u32_e32 v56, v72, v56
	v_max_u32_e32 v72, v73, v55
	v_min_u32_e32 v55, v73, v55
	v_max_u32_e32 v73, v82, v66
	v_min_u32_e32 v66, v82, v66
	v_max_u32_e32 v82, v54, v57
	v_min_u32_e32 v54, v54, v57
	v_max_u32_e32 v57, v2, v67
	v_min_u32_e32 v2, v2, v67
	v_max_u32_e32 v67, v1, v68
	v_min_u32_e32 v1, v1, v68
	v_max_u32_e32 v68, v70, v69
	v_min_u32_e32 v69, v70, v69
	v_max_u32_e32 v70, v3, v0
	v_min_u32_e32 v0, v3, v0
	v_max_u32_e32 v49, v63, v65
	v_min_u32_e32 v63, v63, v65
	v_max_u32_e32 v65, v64, v74
	v_min_u32_e32 v64, v64, v74
	v_max_u32_e32 v74, v52, v58
	v_min_u32_e32 v52, v52, v58
	v_max_u32_e32 v58, v51, v50
	v_min_u32_e32 v50, v51, v50
	v_max_u32_e32 v51, v61, v48
	v_min_u32_e32 v48, v61, v48
	v_max_u32_e32 v61, v46, v47
	v_min_u32_e32 v46, v46, v47
	v_max_u32_e32 v47, v60, v53
	v_min_u32_e32 v53, v60, v53
	v_max_u32_e32 v60, v62, v59
	v_min_u32_e32 v59, v62, v59
	v_max_u32_e32 v3, v71, v73
	v_min_u32_e32 v71, v71, v73
	v_max_u32_e32 v73, v72, v82
	v_min_u32_e32 v72, v72, v82
	v_max_u32_e32 v82, v56, v66
	v_min_u32_e32 v56, v56, v66
	v_max_u32_e32 v66, v55, v54
	v_min_u32_e32 v54, v55, v54
	v_max_u32_e32 v55, v69, v2
	v_min_u32_e32 v2, v69, v2
	v_max_u32_e32 v69, v0, v1
	v_min_u32_e32 v0, v0, v1
	v_max_u32_e32 v1, v68, v57
	v_min_u32_e32 v57, v68, v57
	v_max_u32_e32 v68, v70, v67
	v_min_u32_e32 v67, v70, v67
	v_max_u32_e32 v62, v49, v65
	v_min_u32_e32 v49, v49, v65
	v_max_u32_e32 v65, v63, v64
	v_min_u32_e32 v63, v63, v64
	v_max_u32_e32 v64, v74, v58
	v_min_u32_e32 v58, v74, v58
	v_max_u32_e32 v74, v52, v50
	v_min_u32_e32 v50, v52, v50
	v_max_u32_e32 v52, v46, v48
	v_min_u32_e32 v46, v46, v48
	v_max_u32_e32 v48, v61, v51
	v_min_u32_e32 v51, v61, v51
	v_max_u32_e32 v61, v59, v53
	v_min_u32_e32 v53, v59, v53
	v_max_u32_e32 v59, v60, v47
	v_min_u32_e32 v47, v60, v47
	v_max_u32_e32 v70, v3, v73
	v_min_u32_e32 v3, v3, v73
	v_max_u32_e32 v73, v71, v72
	v_min_u32_e32 v71, v71, v72
	v_max_u32_e32 v72, v82, v66
	v_min_u32_e32 v66, v82, v66
	v_max_u32_e32 v82, v56, v54
	v_min_u32_e32 v54, v56, v54
	v_max_u32_e32 v56, v0, v2
	v_min_u32_e32 v0, v0, v2
	v_max_u32_e32 v2, v69, v55
	v_min_u32_e32 v55, v69, v55
	v_max_u32_e32 v69, v67, v57
	v_min_u32_e32 v57, v67, v57
	v_max_u32_e32 v67, v68, v1
	v_min_u32_e32 v1, v68, v1
	v_max_u32_e32 v60, v62, v46
	v_min_u32_e32 v46, v62, v46
	v_max_u32_e32 v62, v49, v52
	v_min_u32_e32 v49, v49, v52
	v_max_u32_e32 v52, v65, v51
	v_min_u32_e32 v51, v65, v51
	v_max_u32_e32 v65, v63, v48
	v_min_u32_e32 v48, v63, v48
	v_max_u32_e32 v63, v64, v53
	v_min_u32_e32 v53, v64, v53
	v_max_u32_e32 v64, v58, v61
	v_min_u32_e32 v58, v58, v61
	v_max_u32_e32 v61, v74, v47
	v_min_u32_e32 v47, v74, v47
	v_max_u32_e32 v74, v50, v59
	v_min_u32_e32 v50, v50, v59
	v_max_u32_e32 v68, v70, v0
	v_min_u32_e32 v0, v70, v0
	v_max_u32_e32 v70, v3, v56
	v_min_u32_e32 v3, v3, v56
	v_max_u32_e32 v56, v73, v55
	v_min_u32_e32 v55, v73, v55
	v_max_u32_e32 v73, v71, v2
	v_min_u32_e32 v2, v71, v2
	v_max_u32_e32 v71, v72, v57
	v_min_u32_e32 v57, v72, v57
	v_max_u32_e32 v72, v66, v69
	v_min_u32_e32 v66, v66, v69
	v_max_u32_e32 v69, v82, v1
	v_min_u32_e32 v1, v82, v1
	v_max_u32_e32 v82, v54, v67
	v_min_u32_e32 v54, v54, v67
	v_max_u32_e32 v59, v60, v63
	v_min_u32_e32 v60, v60, v63
	v_max_u32_e32 v63, v62, v64
	v_min_u32_e32 v62, v62, v64
	v_max_u32_e32 v64, v52, v61
	v_min_u32_e32 v52, v52, v61
	v_max_u32_e32 v61, v65, v74
	v_min_u32_e32 v65, v65, v74
	v_max_u32_e32 v74, v46, v53
	v_min_u32_e32 v46, v46, v53
	v_max_u32_e32 v53, v49, v58
	v_min_u32_e32 v49, v49, v58
	v_max_u32_e32 v58, v51, v47
; #define CE_DESC(a, b) do { const unsigned _mx = (a) > (b) ? (a) : (b), _mn = (a) > (b) ? (b) : (a); (a) = _mx; (b) = _mn; } while (0)
; __device__ __forceinline__ void sort16_desc(unsigned (&k)[16]) {
; #pragma unroll
;     for (int size = 2; size <= 16; size <<= 1)
; #pragma unroll
;         for (int stride = size >> 1; stride > 0; stride >>= 1)
; #pragma unroll
;             for (int i = 0; i < 16; ++i) { const int j = i ^ stride;
;                 if (j > i) { if ((i & size) == 0) CE_DESC(k[i], k[j]); else CE_DESC(k[j], k[i]); } }
; }
; __device__ __forceinline__ void merge16(unsigned (&a)[16], const unsigned (&b)[16]) {
; #pragma unroll
;     for (int i = 0; i < 16; ++i) a[i] = a[i] > b[15 - i] ? a[i] : b[15 - i];
; #pragma unroll
;     for (int stride = 8; stride > 0; stride >>= 1)
; #pragma unroll
;         for (int i = 0; i < 16; ++i) { const int j = i ^ stride; if (j > i) CE_DESC(a[i], a[j]); }
; }
; __device__ __forceinline__ void peer_tile(const Args& A, LAS unsigned char* lds, int tile) {
;     ...
;                 sort16_desc(k0); sort16_desc(k1); merge16(k0, k1);
; #pragma unroll
;                 for (int msk = 16; msk <= 32; msk <<= 1) {
; #pragma unroll
;                     for (int i = 0; i < 16; ++i) k1[i] = (unsigned)__shfl_xor((int)k0[i], msk);
;                     merge16(k0, k1); }
	v_min_u32_e32 v47, v51, v47
	v_max_u32_e32 v51, v48, v50
	v_min_u32_e32 v48, v48, v50
	v_max_u32_e32 v67, v68, v71
	v_min_u32_e32 v68, v68, v71
	v_max_u32_e32 v71, v70, v72
	v_min_u32_e32 v70, v70, v72
	v_max_u32_e32 v72, v56, v69
	v_min_u32_e32 v56, v56, v69
	v_max_u32_e32 v69, v73, v82
	v_min_u32_e32 v73, v73, v82
	v_max_u32_e32 v82, v0, v57
	v_min_u32_e32 v0, v0, v57
	v_max_u32_e32 v57, v3, v66
	v_min_u32_e32 v3, v3, v66
	v_max_u32_e32 v66, v55, v1
	v_min_u32_e32 v1, v55, v1
	v_max_u32_e32 v55, v2, v54
	v_min_u32_e32 v2, v2, v54
	v_max_u32_e32 v50, v59, v64
	v_min_u32_e32 v59, v59, v64
	v_max_u32_e32 v64, v63, v61
	v_min_u32_e32 v61, v63, v61
	v_max_u32_e32 v63, v60, v52
	v_min_u32_e32 v52, v60, v52
	v_max_u32_e32 v60, v62, v65
	v_min_u32_e32 v62, v62, v65
	v_max_u32_e32 v65, v74, v58
	v_min_u32_e32 v58, v74, v58
	v_max_u32_e32 v74, v53, v51
	v_min_u32_e32 v51, v53, v51
	v_max_u32_e32 v53, v46, v47
	v_min_u32_e32 v46, v46, v47
	v_max_u32_e32 v47, v49, v48
	v_min_u32_e32 v48, v49, v48
	v_max_u32_e32 v54, v67, v72
	v_min_u32_e32 v67, v67, v72
	v_max_u32_e32 v72, v71, v69
	v_min_u32_e32 v69, v71, v69
	v_max_u32_e32 v71, v68, v56
	v_min_u32_e32 v56, v68, v56
	v_max_u32_e32 v68, v70, v73
	v_min_u32_e32 v70, v70, v73
	v_max_u32_e32 v73, v82, v66
	v_min_u32_e32 v66, v82, v66
	v_max_u32_e32 v82, v57, v55
	v_min_u32_e32 v55, v57, v55
	v_max_u32_e32 v57, v0, v1
	v_min_u32_e32 v0, v0, v1
	v_max_u32_e32 v1, v3, v2
	v_min_u32_e32 v2, v3, v2
	v_min_u32_e32 v49, v50, v64
	v_min_u32_e32 v75, v59, v61
	v_min_u32_e32 v76, v63, v60
	v_min_u32_e32 v77, v52, v62
	v_min_u32_e32 v78, v65, v74
	v_min_u32_e32 v79, v58, v51
	v_min_u32_e32 v80, v53, v47
	v_min_u32_e32 v81, v46, v48
	v_min_u32_e32 v3, v54, v72
	v_min_u32_e32 v83, v67, v69
	v_min_u32_e32 v84, v71, v68
	v_min_u32_e32 v85, v56, v70
	v_min_u32_e32 v86, v73, v82
	v_min_u32_e32 v87, v66, v55
	v_min_u32_e32 v88, v57, v1
	v_min_u32_e32 v89, v0, v2
	v_max3_u32 v50, v50, v64, v89
	v_max3_u32 v0, v49, v0, v2
	v_max3_u32 v2, v59, v61, v88
	v_max3_u32 v1, v75, v57, v1
	v_max3_u32 v49, v63, v60, v87
	v_max3_u32 v55, v76, v66, v55
	v_max3_u32 v52, v52, v62, v86
	v_max3_u32 v57, v77, v73, v82
	v_max3_u32 v59, v65, v74, v85
	v_max3_u32 v56, v78, v56, v70
	v_max3_u32 v51, v58, v51, v84
	v_max3_u32 v58, v79, v71, v68
	v_max3_u32 v47, v53, v47, v83
	v_max3_u32 v53, v80, v67, v69
	v_max3_u32 v3, v46, v48, v3
	v_max3_u32 v46, v81, v54, v72
	v_max_u32_e32 v48, v50, v59
	v_min_u32_e32 v50, v50, v59
	v_max_u32_e32 v54, v0, v56
	v_min_u32_e32 v0, v0, v56
	v_max_u32_e32 v56, v2, v51
	v_min_u32_e32 v2, v2, v51
	v_max_u32_e32 v51, v1, v58
	v_min_u32_e32 v1, v1, v58
	v_max_u32_e32 v58, v49, v47
	v_min_u32_e32 v47, v49, v47
	v_max_u32_e32 v49, v55, v53
	v_min_u32_e32 v53, v55, v53
	v_max_u32_e32 v55, v52, v3
	v_min_u32_e32 v3, v52, v3
	v_max_u32_e32 v52, v57, v46
	v_min_u32_e32 v46, v57, v46
	v_max_u32_e32 v57, v48, v58
	v_min_u32_e32 v48, v48, v58
	v_max_u32_e32 v58, v54, v49
	v_min_u32_e32 v49, v54, v49
	v_max_u32_e32 v54, v56, v55
	v_min_u32_e32 v55, v56, v55
	v_max_u32_e32 v56, v51, v52
	v_min_u32_e32 v51, v51, v52
	v_max_u32_e32 v52, v50, v47
	v_min_u32_e32 v47, v50, v47
	v_max_u32_e32 v50, v0, v53
	v_min_u32_e32 v0, v0, v53
	v_max_u32_e32 v53, v2, v3
	v_min_u32_e32 v2, v2, v3
	v_max_u32_e32 v3, v1, v46
	v_min_u32_e32 v1, v1, v46
	v_max_u32_e32 v46, v57, v54
	v_min_u32_e32 v54, v57, v54
	v_max_u32_e32 v57, v58, v56
	v_min_u32_e32 v56, v58, v56
	v_max_u32_e32 v58, v48, v55
	v_min_u32_e32 v48, v48, v55
	v_max_u32_e32 v55, v49, v51
	v_min_u32_e32 v49, v49, v51
	v_max_u32_e32 v51, v52, v53
	v_min_u32_e32 v52, v52, v53
	v_max_u32_e32 v53, v50, v3
	v_min_u32_e32 v3, v50, v3
	v_max_u32_e32 v50, v47, v2
	v_min_u32_e32 v2, v47, v2
	v_max_u32_e32 v47, v0, v1
	v_min_u32_e32 v0, v0, v1
	v_max_u32_e32 v1, v46, v57
	v_min_u32_e32 v46, v46, v57
	v_max_u32_e32 v57, v54, v56
	v_min_u32_e32 v54, v54, v56
	v_max_u32_e32 v56, v58, v55
	v_min_u32_e32 v55, v58, v55
	v_max_u32_e32 v58, v48, v49
	v_min_u32_e32 v48, v48, v49
	v_max_u32_e32 v49, v51, v53
	v_min_u32_e32 v51, v51, v53
	v_max_u32_e32 v53, v52, v3
	v_min_u32_e32 v3, v52, v3
	v_max_u32_e32 v52, v50, v47
	v_min_u32_e32 v47, v50, v47
	v_max_u32_e32 v50, v2, v0
	v_min_u32_e32 v0, v2, v0
	ds_bpermute_b32 v2, v27, v1
	ds_bpermute_b32 v59, v27, v46
	ds_bpermute_b32 v60, v27, v57
	ds_bpermute_b32 v61, v27, v54
	ds_bpermute_b32 v62, v27, v56
	ds_bpermute_b32 v63, v27, v55
	ds_bpermute_b32 v64, v27, v58
	ds_bpermute_b32 v65, v27, v48
	ds_bpermute_b32 v66, v27, v49
	ds_bpermute_b32 v67, v27, v51
	ds_bpermute_b32 v68, v27, v53
	ds_bpermute_b32 v69, v27, v0
	ds_bpermute_b32 v70, v27, v50
	ds_bpermute_b32 v71, v27, v47
	ds_bpermute_b32 v72, v27, v52
	ds_bpermute_b32 v73, v27, v3
	s_waitcnt lgkmcnt(4)
	v_max_u32_e32 v1, v1, v69
	s_waitcnt lgkmcnt(3)
	v_max_u32_e32 v46, v46, v70
	s_waitcnt lgkmcnt(2)
	v_max_u32_e32 v57, v57, v71
	s_waitcnt lgkmcnt(1)
	v_max_u32_e32 v54, v54, v72
	s_waitcnt lgkmcnt(0)
; __device__ __forceinline__ void peer_tile(const Args& A, LAS unsigned char* lds, int tile) {
;     ...
;                 { const bf16_t* sp = QRY + m * 2048 + hp * 128 + 32 * g;
;                   const u32x4 s0 = *(const u32x4*)sp, s1 = *(const u32x4*)(sp + 8), s2 = *(const u32x4*)(sp + 16), s3 = *(const u32x4*)(sp + 24);
;     ...
;                 sort16_desc(k0); sort16_desc(k1); merge16(k0, k1);
; #pragma unroll
;                 for (int msk = 16; msk <= 32; msk <<= 1) {
; #pragma unroll
;                     for (int i = 0; i < 16; ++i) k1[i] = (unsigned)__shfl_xor((int)k0[i], msk);
;                     merge16(k0, k1); }
	v_max_u32_e32 v56, v56, v73
	v_max_u32_e32 v55, v55, v68
	v_max_u32_e32 v58, v58, v67
	v_max_u32_e32 v48, v48, v66
	v_max_u32_e32 v49, v49, v65
	v_max_u32_e32 v51, v51, v64
	v_max_u32_e32 v53, v53, v63
	v_max_u32_e32 v3, v3, v62
	v_max_u32_e32 v52, v52, v61
	v_max_u32_e32 v47, v47, v60
	v_max_u32_e32 v50, v50, v59
	v_max_u32_e32 v0, v0, v2
	v_max_u32_e32 v2, v1, v49
	v_min_u32_e32 v1, v1, v49
	v_max_u32_e32 v49, v46, v51
	v_min_u32_e32 v46, v46, v51
	v_max_u32_e32 v51, v57, v53
	v_min_u32_e32 v53, v57, v53
	v_max_u32_e32 v57, v54, v3
	v_min_u32_e32 v3, v54, v3
	v_max_u32_e32 v54, v56, v52
	v_min_u32_e32 v52, v56, v52
	v_max_u32_e32 v56, v55, v47
	v_min_u32_e32 v47, v55, v47
	v_max_u32_e32 v55, v58, v50
	v_min_u32_e32 v50, v58, v50
	v_max_u32_e32 v58, v48, v0
	v_min_u32_e32 v0, v48, v0
	v_max_u32_e32 v48, v2, v54
	v_min_u32_e32 v2, v2, v54
	v_max_u32_e32 v54, v49, v56
	v_min_u32_e32 v49, v49, v56
	v_max_u32_e32 v56, v51, v55
	v_min_u32_e32 v51, v51, v55
	v_max_u32_e32 v55, v57, v58
	v_min_u32_e32 v57, v57, v58
	v_max_u32_e32 v58, v1, v52
	v_min_u32_e32 v1, v1, v52
	v_max_u32_e32 v52, v46, v47
	v_min_u32_e32 v46, v46, v47
	v_max_u32_e32 v47, v53, v50
	v_min_u32_e32 v50, v53, v50
	v_max_u32_e32 v53, v3, v0
	v_min_u32_e32 v0, v3, v0
	v_max_u32_e32 v3, v48, v56
	v_min_u32_e32 v48, v48, v56
	v_max_u32_e32 v56, v54, v55
	v_min_u32_e32 v54, v54, v55
	v_max_u32_e32 v55, v2, v51
	v_min_u32_e32 v2, v2, v51
	v_max_u32_e32 v51, v49, v57
	v_min_u32_e32 v49, v49, v57
	v_max_u32_e32 v57, v58, v47
	v_min_u32_e32 v47, v58, v47
	v_max_u32_e32 v58, v52, v53
	v_min_u32_e32 v52, v52, v53
	v_max_u32_e32 v53, v1, v50
	v_min_u32_e32 v1, v1, v50
	v_max_u32_e32 v50, v46, v0
	v_min_u32_e32 v0, v46, v0
	v_max_u32_e32 v46, v3, v56
	v_min_u32_e32 v3, v3, v56
	v_max_u32_e32 v56, v48, v54
	v_min_u32_e32 v48, v48, v54
	v_max_u32_e32 v54, v55, v51
	v_min_u32_e32 v51, v55, v51
	v_max_u32_e32 v55, v2, v49
	v_min_u32_e32 v2, v2, v49
	v_max_u32_e32 v49, v57, v58
	v_min_u32_e32 v57, v57, v58
	v_max_u32_e32 v58, v47, v52
	v_min_u32_e32 v47, v47, v52
	v_max_u32_e32 v52, v53, v50
	v_min_u32_e32 v50, v53, v50
	v_max_u32_e32 v53, v1, v0
	v_min_u32_e32 v0, v1, v0
	ds_bpermute_b32 v62, v29, v0
	ds_bpermute_b32 v1, v29, v46
	ds_bpermute_b32 v59, v29, v3
	ds_bpermute_b32 v60, v29, v56
	ds_bpermute_b32 v61, v29, v48
	s_waitcnt lgkmcnt(4)
	v_max_u32_e32 v46, v46, v62
	global_load_dwordx4 v[62:65], v[4:5], off offset:528
	global_load_dwordx4 v[66:69], v[4:5], off offset:512
	ds_bpermute_b32 v70, v29, v54
	ds_bpermute_b32 v71, v29, v51
	ds_bpermute_b32 v72, v29, v55
	ds_bpermute_b32 v73, v29, v2
	ds_bpermute_b32 v74, v29, v49
	ds_bpermute_b32 v75, v29, v57
	ds_bpermute_b32 v76, v29, v58
	ds_bpermute_b32 v77, v29, v47
	ds_bpermute_b32 v78, v29, v52
	ds_bpermute_b32 v79, v29, v53
	ds_bpermute_b32 v80, v29, v50
	s_waitcnt lgkmcnt(4)
	v_max_u32_e32 v51, v51, v76
	s_waitcnt lgkmcnt(3)
	v_max_u32_e32 v54, v54, v77
	s_waitcnt lgkmcnt(2)
	v_max_u32_e32 v48, v48, v78
	s_waitcnt lgkmcnt(1)
	v_max_u32_e32 v3, v3, v79
	s_waitcnt lgkmcnt(0)
	v_max_u32_e32 v56, v56, v80
	v_max_u32_e32 v55, v55, v75
	v_max_u32_e32 v2, v2, v74
	v_max_u32_e32 v49, v49, v73
	v_max_u32_e32 v57, v57, v72
	v_max_u32_e32 v58, v58, v71
	v_max_u32_e32 v47, v47, v70
	v_max_u32_e32 v52, v52, v61
	v_max_u32_e32 v50, v50, v60
	v_max_u32_e32 v53, v53, v59
	v_max_u32_e32 v0, v0, v1
	v_max_u32_e32 v1, v46, v49
	v_min_u32_e32 v46, v46, v49
	v_max_u32_e32 v49, v3, v57
	v_min_u32_e32 v3, v3, v57
	v_max_u32_e32 v57, v56, v58
	v_min_u32_e32 v56, v56, v58
	v_max_u32_e32 v58, v48, v47
	v_min_u32_e32 v47, v48, v47
	v_max_u32_e32 v48, v54, v52
	v_min_u32_e32 v52, v54, v52
	v_max_u32_e32 v54, v51, v50
	v_min_u32_e32 v50, v51, v50
	v_max_u32_e32 v51, v55, v53
	v_min_u32_e32 v53, v55, v53
	v_max_u32_e32 v55, v2, v0
	v_min_u32_e32 v0, v2, v0
	v_max_u32_e32 v2, v1, v48
	v_min_u32_e32 v1, v1, v48
	v_max_u32_e32 v48, v49, v54
	v_min_u32_e32 v49, v49, v54
	v_max_u32_e32 v54, v57, v51
	v_min_u32_e32 v51, v57, v51
	v_max_u32_e32 v57, v58, v55
	v_min_u32_e32 v55, v58, v55
	v_max_u32_e32 v58, v46, v52
	v_min_u32_e32 v46, v46, v52
	v_max_u32_e32 v52, v3, v50
	v_min_u32_e32 v3, v3, v50
	v_max_u32_e32 v50, v56, v53
	v_min_u32_e32 v53, v56, v53
	v_max_u32_e32 v56, v47, v0
	v_min_u32_e32 v0, v47, v0
	v_max_u32_e32 v47, v2, v54
	v_min_u32_e32 v2, v2, v54
	v_max_u32_e32 v54, v48, v57
	v_min_u32_e32 v48, v48, v57
	v_max_u32_e32 v70, v1, v51
	v_min_u32_e32 v1, v1, v51
	v_max_u32_e32 v51, v49, v55
	v_min_u32_e32 v49, v49, v55
	v_max_u32_e32 v71, v58, v50
	v_min_u32_e32 v50, v58, v50
	v_max_u32_e32 v72, v52, v56
	v_min_u32_e32 v73, v52, v56
	v_max_u32_e32 v74, v46, v53
	v_min_u32_e32 v46, v46, v53
	v_max_u32_e32 v75, v3, v0
	v_min_u32_e32 v0, v3, v0
	v_max_u32_e32 v61, v47, v54
	v_min_u32_e32 v60, v47, v54
	v_max_u32_e32 v59, v2, v48
	v_min_u32_e32 v58, v2, v48
	v_max_u32_e32 v57, v70, v51
	v_min_u32_e32 v56, v70, v51
	v_max_u32_e32 v55, v1, v49
	v_min_u32_e32 v54, v1, v49
	v_max_u32_e32 v53, v71, v72
	v_min_u32_e32 v52, v71, v72
	v_max_u32_e32 v51, v50, v73
	v_min_u32_e32 v50, v50, v73
	v_max_u32_e32 v47, v46, v0
	v_min_u32_e32 v46, v46, v0
	global_load_dwordx4 v[0:3], v[4:5], off offset:560
	global_load_dwordx4 v[70:73], v[4:5], off offset:544
	v_max_u32_e32 v49, v74, v75
	v_min_u32_e32 v48, v74, v75
	s_waitcnt vmcnt(2)
; __device__ __forceinline__ unsigned f2key(float f) { const unsigned u = __float_as_uint(f); return (u & 0x80000000u) ? ~u : (u | 0x80000000u); }
; __device__ __forceinline__ void peer_tile(const Args& A, LAS unsigned char* lds, int tile) {
;     ...
;                   for (int i = 0; i < 16; ++i) {
;                       const float lo = (float)__builtin_bit_cast(_Float16, (unsigned short)(sw[i] & 0xffffu)), hi = (float)__builtin_bit_cast(_Float16, (unsigned short)(sw[i] >> 16));
;                       const unsigned klo = (f2key(lo) & ~127u) | (unsigned)(127 - (32 * g + 2 * i)), khi = (f2key(hi) & ~127u) | (unsigned)(127 - (32 * g + 2 * i + 1));
;                       if (i < 8) { k0[2 * i] = klo; k0[2 * i + 1] = khi; } else { k1[2 * (i - 8)] = klo; k1[2 * (i - 8) + 1] = khi; } } }
	v_cvt_f32_f16_sdwa v74, v66 dst_sel:DWORD dst_unused:UNUSED_PAD src0_sel:WORD_1
	v_cvt_f32_f16_e32 v66, v66
	v_not_b32_e32 v75, v74
	v_or_b32_e32 v76, 0x80000000, v74
	v_cmp_gt_i32_e32 vcc, 0, v74
	s_nop 1
	v_cndmask_b32_e32 v74, v76, v75, vcc
	v_not_b32_e32 v75, v66
	v_or_b32_e32 v76, 0x80000000, v66
	v_cmp_gt_i32_e32 vcc, 0, v66
	v_and_b32_e32 v74, 0xffffff80, v74
	v_sub_u32_e32 v74, v74, v15
	v_cndmask_b32_e32 v66, v76, v75, vcc
	v_cvt_f32_f16_sdwa v75, v67 dst_sel:DWORD dst_unused:UNUSED_PAD src0_sel:WORD_1
	v_cvt_f32_f16_e32 v67, v67
	v_and_b32_e32 v66, 0xffffff80, v66
	v_sub_u32_e32 v66, v66, v15
	v_not_b32_e32 v76, v75
	v_or_b32_e32 v77, 0x80000000, v75
	v_cmp_gt_i32_e32 vcc, 0, v75
	v_add_u32_e32 v74, 0x7e, v74
	v_add_u32_e32 v66, 0x7f, v66
	v_cndmask_b32_e32 v75, v77, v76, vcc
	v_not_b32_e32 v76, v67
	v_or_b32_e32 v77, 0x80000000, v67
	v_cmp_gt_i32_e32 vcc, 0, v67
	v_and_b32_e32 v75, 0xffffff80, v75
	v_sub_u32_e32 v75, v75, v14
	v_cndmask_b32_e32 v67, v77, v76, vcc
	v_cvt_f32_f16_sdwa v76, v68 dst_sel:DWORD dst_unused:UNUSED_PAD src0_sel:WORD_1
	v_cvt_f32_f16_e32 v68, v68
	v_and_b32_e32 v67, 0xffffff80, v67
	v_sub_u32_e32 v67, v67, v14
	v_not_b32_e32 v77, v76
	v_or_b32_e32 v78, 0x80000000, v76
	v_cmp_gt_i32_e32 vcc, 0, v76
	v_add_u32_e32 v75, 0x7e, v75
	v_add_u32_e32 v67, 0x7f, v67
	v_cndmask_b32_e32 v76, v78, v77, vcc
	v_not_b32_e32 v77, v68
	v_or_b32_e32 v78, 0x80000000, v68
	v_cmp_gt_i32_e32 vcc, 0, v68
	v_and_b32_e32 v76, 0xffffff80, v76
	v_sub_u32_e32 v76, v76, v12
	v_cndmask_b32_e32 v68, v78, v77, vcc
	v_cvt_f32_f16_sdwa v77, v69 dst_sel:DWORD dst_unused:UNUSED_PAD src0_sel:WORD_1
	v_cvt_f32_f16_e32 v69, v69
	v_and_b32_e32 v68, 0xffffff80, v68
	v_sub_u32_e32 v68, v68, v12
	v_not_b32_e32 v78, v77
	v_or_b32_e32 v79, 0x80000000, v77
	v_cmp_gt_i32_e32 vcc, 0, v77
	v_add_u32_e32 v76, 0x7e, v76
	v_add_u32_e32 v68, 0x7f, v68
	v_cndmask_b32_e32 v77, v79, v78, vcc
	v_not_b32_e32 v78, v69
	v_or_b32_e32 v79, 0x80000000, v69
	v_cmp_gt_i32_e32 vcc, 0, v69
	v_and_b32_e32 v77, 0xffffff80, v77
	v_sub_u32_e32 v77, v77, v10
	v_cndmask_b32_e32 v69, v79, v78, vcc
	v_cvt_f32_f16_sdwa v78, v62 dst_sel:DWORD dst_unused:UNUSED_PAD src0_sel:WORD_1
	v_cvt_f32_f16_e32 v62, v62
	v_and_b32_e32 v69, 0xffffff80, v69
	v_sub_u32_e32 v69, v69, v10
	v_not_b32_e32 v79, v78
	v_or_b32_e32 v80, 0x80000000, v78
	v_cmp_gt_i32_e32 vcc, 0, v78
	v_add_u32_e32 v77, 0x7e, v77
	v_add_u32_e32 v69, 0x7f, v69
	v_cndmask_b32_e32 v78, v80, v79, vcc
	v_not_b32_e32 v79, v62
	v_or_b32_e32 v80, 0x80000000, v62
	v_cmp_gt_i32_e32 vcc, 0, v62
	v_and_b32_e32 v78, 0xffffff80, v78
	v_sub_u32_e32 v78, v78, v8
	v_cndmask_b32_e32 v62, v80, v79, vcc
	v_cvt_f32_f16_sdwa v79, v63 dst_sel:DWORD dst_unused:UNUSED_PAD src0_sel:WORD_1
	v_cvt_f32_f16_e32 v63, v63
	v_and_b32_e32 v62, 0xffffff80, v62
	v_sub_u32_e32 v62, v62, v8
	v_not_b32_e32 v80, v79
	v_or_b32_e32 v81, 0x80000000, v79
	v_cmp_gt_i32_e32 vcc, 0, v79
	v_add_u32_e32 v78, 0x7e, v78
	v_add_u32_e32 v62, 0x7f, v62
	v_cndmask_b32_e32 v79, v81, v80, vcc
	v_not_b32_e32 v80, v63
	v_or_b32_e32 v81, 0x80000000, v63
	v_cmp_gt_i32_e32 vcc, 0, v63
	v_and_b32_e32 v79, 0xffffff80, v79
	v_sub_u32_e32 v79, v79, v16
	v_cndmask_b32_e32 v63, v81, v80, vcc
	v_cvt_f32_f16_sdwa v80, v64 dst_sel:DWORD dst_unused:UNUSED_PAD src0_sel:WORD_1
	v_cvt_f32_f16_e32 v64, v64
	v_and_b32_e32 v63, 0xffffff80, v63
	v_sub_u32_e32 v63, v63, v16
	v_not_b32_e32 v81, v80
	v_or_b32_e32 v82, 0x80000000, v80
	v_cmp_gt_i32_e32 vcc, 0, v80
	v_add_u32_e32 v79, 0x7e, v79
	v_add_u32_e32 v63, 0x7f, v63
	v_cndmask_b32_e32 v80, v82, v81, vcc
	v_not_b32_e32 v81, v64
	v_or_b32_e32 v82, 0x80000000, v64
	v_cmp_gt_i32_e32 vcc, 0, v64
	v_and_b32_e32 v80, 0xffffff80, v80
	v_sub_u32_e32 v80, v80, v17
	v_cndmask_b32_e32 v64, v82, v81, vcc
	v_cvt_f32_f16_sdwa v81, v65 dst_sel:DWORD dst_unused:UNUSED_PAD src0_sel:WORD_1
	v_cvt_f32_f16_e32 v65, v65
	v_and_b32_e32 v64, 0xffffff80, v64
	v_sub_u32_e32 v64, v64, v17
	v_not_b32_e32 v82, v81
	v_or_b32_e32 v83, 0x80000000, v81
	v_cmp_gt_i32_e32 vcc, 0, v81
	v_add_u32_e32 v80, 0x7e, v80
	v_add_u32_e32 v64, 0x7f, v64
	v_cndmask_b32_e32 v81, v83, v82, vcc
	v_not_b32_e32 v82, v65
	v_or_b32_e32 v83, 0x80000000, v65
	v_cmp_gt_i32_e32 vcc, 0, v65
	v_and_b32_e32 v81, 0xffffff80, v81
	v_sub_u32_e32 v81, v81, v18
	v_cndmask_b32_e32 v65, v83, v82, vcc
	s_waitcnt vmcnt(0)
; __device__ __forceinline__ unsigned f2key(float f) { const unsigned u = __float_as_uint(f); return (u & 0x80000000u) ? ~u : (u | 0x80000000u); }
; #define CE_DESC(a, b) do { const unsigned _mx = (a) > (b) ? (a) : (b), _mn = (a) > (b) ? (b) : (a); (a) = _mx; (b) = _mn; } while (0)
; __device__ __forceinline__ void sort16_desc(unsigned (&k)[16]) {
; #pragma unroll
;     for (int size = 2; size <= 16; size <<= 1)
; #pragma unroll
;         for (int stride = size >> 1; stride > 0; stride >>= 1)
; #pragma unroll
;             for (int i = 0; i < 16; ++i) { const int j = i ^ stride;
;                 if (j > i) { if ((i & size) == 0) CE_DESC(k[i], k[j]); else CE_DESC(k[j], k[i]); } }
; }
; __device__ __forceinline__ void peer_tile(const Args& A, LAS unsigned char* lds, int tile) {
;     ...
;                   for (int i = 0; i < 16; ++i) {
;                       const float lo = (float)__builtin_bit_cast(_Float16, (unsigned short)(sw[i] & 0xffffu)), hi = (float)__builtin_bit_cast(_Float16, (unsigned short)(sw[i] >> 16));
;                       const unsigned klo = (f2key(lo) & ~127u) | (unsigned)(127 - (32 * g + 2 * i)), khi = (f2key(hi) & ~127u) | (unsigned)(127 - (32 * g + 2 * i + 1));
;                       if (i < 8) { k0[2 * i] = klo; k0[2 * i + 1] = khi; } else { k1[2 * (i - 8)] = klo; k1[2 * (i - 8) + 1] = khi; } } }
	v_cvt_f32_f16_sdwa v82, v70 dst_sel:DWORD dst_unused:UNUSED_PAD src0_sel:WORD_1
	v_cvt_f32_f16_e32 v70, v70
	v_and_b32_e32 v65, 0xffffff80, v65
	v_sub_u32_e32 v65, v65, v18
	v_not_b32_e32 v83, v82
	v_or_b32_e32 v84, 0x80000000, v82
	v_cmp_gt_i32_e32 vcc, 0, v82
	v_add_u32_e32 v81, 0x7e, v81
	v_add_u32_e32 v65, 0x7f, v65
	v_cndmask_b32_e32 v82, v84, v83, vcc
	v_not_b32_e32 v83, v70
	v_or_b32_e32 v84, 0x80000000, v70
	v_cmp_gt_i32_e32 vcc, 0, v70
	v_and_b32_e32 v82, 0xffffff80, v82
	v_sub_u32_e32 v82, v82, v20
	v_cndmask_b32_e32 v70, v84, v83, vcc
	v_cvt_f32_f16_sdwa v83, v71 dst_sel:DWORD dst_unused:UNUSED_PAD src0_sel:WORD_1
	v_cvt_f32_f16_e32 v71, v71
	v_and_b32_e32 v70, 0xffffff80, v70
	v_sub_u32_e32 v70, v70, v20
	v_not_b32_e32 v84, v83
	v_or_b32_e32 v85, 0x80000000, v83
	v_cmp_gt_i32_e32 vcc, 0, v83
	v_add_u32_e32 v82, 0x7e, v82
	v_add_u32_e32 v70, 0x7f, v70
	v_cndmask_b32_e32 v83, v85, v84, vcc
	v_not_b32_e32 v84, v71
	v_or_b32_e32 v85, 0x80000000, v71
	v_cmp_gt_i32_e32 vcc, 0, v71
	v_and_b32_e32 v83, 0xffffff80, v83
	v_sub_u32_e32 v83, v83, v21
	v_cndmask_b32_e32 v71, v85, v84, vcc
	v_cvt_f32_f16_sdwa v84, v72 dst_sel:DWORD dst_unused:UNUSED_PAD src0_sel:WORD_1
	v_cvt_f32_f16_e32 v72, v72
	v_and_b32_e32 v71, 0xffffff80, v71
	v_sub_u32_e32 v71, v71, v21
	v_not_b32_e32 v85, v84
	v_or_b32_e32 v86, 0x80000000, v84
	v_cmp_gt_i32_e32 vcc, 0, v84
	v_add_u32_e32 v83, 0x7e, v83
	v_add_u32_e32 v71, 0x7f, v71
	v_cndmask_b32_e32 v84, v86, v85, vcc
	v_not_b32_e32 v85, v72
	v_or_b32_e32 v86, 0x80000000, v72
	v_cmp_gt_i32_e32 vcc, 0, v72
	v_and_b32_e32 v84, 0xffffff80, v84
	v_sub_u32_e32 v84, v84, v22
	v_cndmask_b32_e32 v72, v86, v85, vcc
	v_cvt_f32_f16_sdwa v85, v73 dst_sel:DWORD dst_unused:UNUSED_PAD src0_sel:WORD_1
	v_cvt_f32_f16_e32 v73, v73
	v_and_b32_e32 v72, 0xffffff80, v72
	v_sub_u32_e32 v72, v72, v22
	v_not_b32_e32 v86, v85
	v_or_b32_e32 v87, 0x80000000, v85
	v_cmp_gt_i32_e32 vcc, 0, v85
	v_add_u32_e32 v84, 0x7e, v84
	v_add_u32_e32 v72, 0x7f, v72
	v_cndmask_b32_e32 v85, v87, v86, vcc
	v_not_b32_e32 v86, v73
	v_or_b32_e32 v87, 0x80000000, v73
	v_cmp_gt_i32_e32 vcc, 0, v73
	v_and_b32_e32 v85, 0xffffff80, v85
	v_sub_u32_e32 v85, v85, v23
	v_cndmask_b32_e32 v73, v87, v86, vcc
	v_cvt_f32_f16_sdwa v86, v0 dst_sel:DWORD dst_unused:UNUSED_PAD src0_sel:WORD_1
	v_cvt_f32_f16_e32 v0, v0
	v_and_b32_e32 v73, 0xffffff80, v73
	v_sub_u32_e32 v73, v73, v23
	v_not_b32_e32 v87, v86
	v_or_b32_e32 v88, 0x80000000, v86
	v_cmp_gt_i32_e32 vcc, 0, v86
	v_add_u32_e32 v85, 0x7e, v85
	v_add_u32_e32 v73, 0x7f, v73
	v_cndmask_b32_e32 v86, v88, v87, vcc
	v_not_b32_e32 v87, v0
	v_or_b32_e32 v88, 0x80000000, v0
	v_cmp_gt_i32_e32 vcc, 0, v0
	v_and_b32_e32 v86, 0xffffff80, v86
	v_sub_u32_e32 v86, v86, v24
	v_cndmask_b32_e32 v0, v88, v87, vcc
	v_cvt_f32_f16_sdwa v87, v1 dst_sel:DWORD dst_unused:UNUSED_PAD src0_sel:WORD_1
	v_cvt_f32_f16_e32 v1, v1
	v_and_b32_e32 v0, 0xffffff80, v0
	v_sub_u32_e32 v0, v0, v24
	v_not_b32_e32 v88, v87
	v_or_b32_e32 v89, 0x80000000, v87
	v_cmp_gt_i32_e32 vcc, 0, v87
	v_add_u32_e32 v86, 0x7e, v86
	v_add_u32_e32 v0, 0x7f, v0
	v_cndmask_b32_e32 v87, v89, v88, vcc
	v_not_b32_e32 v88, v1
	v_or_b32_e32 v89, 0x80000000, v1
	v_cmp_gt_i32_e32 vcc, 0, v1
	v_and_b32_e32 v87, 0xffffff80, v87
	v_sub_u32_e32 v87, v87, v25
	v_cndmask_b32_e32 v1, v89, v88, vcc
	v_cvt_f32_f16_sdwa v88, v2 dst_sel:DWORD dst_unused:UNUSED_PAD src0_sel:WORD_1
	v_cvt_f32_f16_e32 v2, v2
	v_and_b32_e32 v1, 0xffffff80, v1
	v_sub_u32_e32 v1, v1, v25
	v_not_b32_e32 v89, v88
	v_or_b32_e32 v90, 0x80000000, v88
	v_cmp_gt_i32_e32 vcc, 0, v88
	v_add_u32_e32 v87, 0x7e, v87
	v_add_u32_e32 v1, 0x7f, v1
	v_cndmask_b32_e32 v88, v90, v89, vcc
	v_not_b32_e32 v89, v2
	v_or_b32_e32 v90, 0x80000000, v2
	v_cmp_gt_i32_e32 vcc, 0, v2
	v_and_b32_e32 v88, 0xffffff80, v88
	v_sub_u32_e32 v88, v88, v26
	v_cndmask_b32_e32 v2, v90, v89, vcc
	v_cvt_f32_f16_sdwa v89, v3 dst_sel:DWORD dst_unused:UNUSED_PAD src0_sel:WORD_1
	v_cvt_f32_f16_e32 v3, v3
	v_and_b32_e32 v2, 0xffffff80, v2
	v_sub_u32_e32 v2, v2, v26
	v_not_b32_e32 v90, v89
	v_or_b32_e32 v91, 0x80000000, v89
	v_cmp_gt_i32_e32 vcc, 0, v89
	v_add_u32_e32 v88, 0x7e, v88
	v_add_u32_e32 v2, 0x7f, v2
	v_cndmask_b32_e32 v89, v91, v90, vcc
	v_not_b32_e32 v90, v3
	v_or_b32_e32 v91, 0x80000000, v3
	v_cmp_gt_i32_e32 vcc, 0, v3
	v_and_b32_e32 v89, 0xffffff80, v89
	v_sub_u32_e32 v89, v89, v28
	v_cndmask_b32_e32 v3, v91, v90, vcc
	v_and_b32_e32 v3, 0xffffff80, v3
	v_sub_u32_e32 v3, v3, v28
	v_add_u32_e32 v89, 0x7e, v89
	v_add_u32_e32 v3, 0x7f, v3
	v_max_u32_e32 v90, v66, v74
	v_min_u32_e32 v66, v66, v74
	v_max_u32_e32 v74, v75, v67
	v_min_u32_e32 v67, v75, v67
	v_max_u32_e32 v75, v68, v76
	v_min_u32_e32 v68, v68, v76
	v_max_u32_e32 v76, v77, v69
	v_min_u32_e32 v69, v77, v69
	v_max_u32_e32 v77, v62, v78
	v_min_u32_e32 v62, v62, v78
	v_max_u32_e32 v78, v79, v63
	v_min_u32_e32 v63, v79, v63
	v_max_u32_e32 v79, v64, v80
	v_min_u32_e32 v64, v64, v80
	v_max_u32_e32 v80, v81, v65
	v_min_u32_e32 v65, v81, v65
	v_max_u32_e32 v98, v70, v82
	v_min_u32_e32 v70, v70, v82
	v_max_u32_e32 v82, v83, v71
	v_min_u32_e32 v71, v83, v71
	v_max_u32_e32 v83, v72, v84
	v_min_u32_e32 v72, v72, v84
	v_max_u32_e32 v84, v85, v73
	v_min_u32_e32 v73, v85, v73
	v_max_u32_e32 v85, v0, v86
	v_min_u32_e32 v0, v0, v86
	v_max_u32_e32 v86, v87, v1
	v_min_u32_e32 v1, v87, v1
	v_max_u32_e32 v87, v2, v88
	v_min_u32_e32 v2, v2, v88
	v_max_u32_e32 v88, v89, v3
	v_min_u32_e32 v3, v89, v3
	v_max_u32_e32 v81, v90, v67
	v_min_u32_e32 v67, v90, v67
	v_max_u32_e32 v90, v66, v74
	v_min_u32_e32 v66, v66, v74
	v_max_u32_e32 v74, v69, v75
	v_min_u32_e32 v69, v69, v75
	v_max_u32_e32 v75, v76, v68
	v_min_u32_e32 v68, v76, v68
; #define CE_DESC(a, b) do { const unsigned _mx = (a) > (b) ? (a) : (b), _mn = (a) > (b) ? (b) : (a); (a) = _mx; (b) = _mn; } while (0)
; __device__ __forceinline__ void sort16_desc(unsigned (&k)[16]) {
; #pragma unroll
;     for (int size = 2; size <= 16; size <<= 1)
; #pragma unroll
;         for (int stride = size >> 1; stride > 0; stride >>= 1)
; #pragma unroll
;             for (int i = 0; i < 16; ++i) { const int j = i ^ stride;
;                 if (j > i) { if ((i & size) == 0) CE_DESC(k[i], k[j]); else CE_DESC(k[j], k[i]); } }
; }
	v_max_u32_e32 v76, v77, v63
	v_min_u32_e32 v63, v77, v63
	v_max_u32_e32 v77, v62, v78
	v_min_u32_e32 v62, v62, v78
	v_max_u32_e32 v78, v65, v79
	v_min_u32_e32 v65, v65, v79
	v_max_u32_e32 v79, v80, v64
	v_min_u32_e32 v64, v80, v64
	v_max_u32_e32 v89, v98, v71
	v_min_u32_e32 v71, v98, v71
	v_max_u32_e32 v98, v70, v82
	v_min_u32_e32 v70, v70, v82
	v_max_u32_e32 v82, v73, v83
	v_min_u32_e32 v73, v73, v83
	v_max_u32_e32 v83, v84, v72
	v_min_u32_e32 v72, v84, v72
	v_max_u32_e32 v84, v85, v1
	v_min_u32_e32 v1, v85, v1
	v_max_u32_e32 v85, v0, v86
	v_min_u32_e32 v0, v0, v86
	v_max_u32_e32 v86, v3, v87
	v_min_u32_e32 v3, v3, v87
	v_max_u32_e32 v87, v88, v2
	v_min_u32_e32 v2, v88, v2
	v_max_u32_e32 v80, v81, v90
	v_min_u32_e32 v81, v81, v90
	v_max_u32_e32 v90, v67, v66
	v_min_u32_e32 v66, v67, v66
	v_max_u32_e32 v67, v68, v69
	v_min_u32_e32 v68, v68, v69
	v_max_u32_e32 v69, v75, v74
	v_min_u32_e32 v74, v75, v74
	v_max_u32_e32 v75, v76, v77
	v_min_u32_e32 v76, v76, v77
	v_max_u32_e32 v77, v63, v62
	v_min_u32_e32 v62, v63, v62
	v_max_u32_e32 v63, v64, v65
	v_min_u32_e32 v64, v64, v65
	v_max_u32_e32 v65, v79, v78
	v_min_u32_e32 v78, v79, v78
	v_max_u32_e32 v88, v89, v98
	v_min_u32_e32 v89, v89, v98
	v_max_u32_e32 v98, v71, v70
	v_min_u32_e32 v70, v71, v70
	v_max_u32_e32 v71, v72, v73
	v_min_u32_e32 v72, v72, v73
	v_max_u32_e32 v73, v83, v82
	v_min_u32_e32 v82, v83, v82
	v_max_u32_e32 v83, v84, v85
	v_min_u32_e32 v84, v84, v85
	v_max_u32_e32 v85, v1, v0
	v_min_u32_e32 v0, v1, v0
	v_max_u32_e32 v1, v2, v3
	v_min_u32_e32 v2, v2, v3
	v_max_u32_e32 v3, v87, v86
	v_min_u32_e32 v86, v87, v86
	v_max_u32_e32 v79, v80, v68
	v_min_u32_e32 v68, v80, v68
	v_max_u32_e32 v80, v81, v67
	v_min_u32_e32 v67, v81, v67
	v_max_u32_e32 v81, v90, v74
	v_min_u32_e32 v74, v90, v74
	v_max_u32_e32 v90, v66, v69
	v_min_u32_e32 v66, v66, v69
	v_max_u32_e32 v69, v64, v75
	v_min_u32_e32 v64, v64, v75
	v_max_u32_e32 v75, v63, v76
	v_min_u32_e32 v63, v63, v76
	v_max_u32_e32 v76, v78, v77
	v_min_u32_e32 v77, v78, v77
	v_max_u32_e32 v78, v65, v62
	v_min_u32_e32 v62, v65, v62
	v_max_u32_e32 v87, v88, v72
	v_min_u32_e32 v72, v88, v72
	v_max_u32_e32 v88, v89, v71
	v_min_u32_e32 v71, v89, v71
	v_max_u32_e32 v89, v98, v82
	v_min_u32_e32 v82, v98, v82
	v_max_u32_e32 v98, v70, v73
	v_min_u32_e32 v70, v70, v73
	v_max_u32_e32 v73, v2, v83
	v_min_u32_e32 v2, v2, v83
	v_max_u32_e32 v83, v1, v84
	v_min_u32_e32 v1, v1, v84
	v_max_u32_e32 v84, v86, v85
	v_min_u32_e32 v85, v86, v85
	v_max_u32_e32 v86, v3, v0
	v_min_u32_e32 v0, v3, v0
	v_max_u32_e32 v65, v79, v81
	v_min_u32_e32 v79, v79, v81
	v_max_u32_e32 v81, v80, v90
	v_min_u32_e32 v80, v80, v90
	v_max_u32_e32 v90, v68, v74
	v_min_u32_e32 v68, v68, v74
	v_max_u32_e32 v74, v67, v66
	v_min_u32_e32 v66, v67, v66
	v_max_u32_e32 v67, v77, v64
	v_min_u32_e32 v64, v77, v64
	v_max_u32_e32 v77, v62, v63
	v_min_u32_e32 v62, v62, v63
	v_max_u32_e32 v63, v76, v69
	v_min_u32_e32 v69, v76, v69
	v_max_u32_e32 v76, v78, v75
	v_min_u32_e32 v75, v78, v75
	v_max_u32_e32 v3, v87, v89
	v_min_u32_e32 v87, v87, v89
	v_max_u32_e32 v89, v88, v98
	v_min_u32_e32 v88, v88, v98
	v_max_u32_e32 v98, v72, v82
	v_min_u32_e32 v72, v72, v82
	v_max_u32_e32 v82, v71, v70
	v_min_u32_e32 v70, v71, v70
	v_max_u32_e32 v71, v85, v2
	v_min_u32_e32 v2, v85, v2
	v_max_u32_e32 v85, v0, v1
	v_min_u32_e32 v0, v0, v1
	v_max_u32_e32 v1, v84, v73
	v_min_u32_e32 v73, v84, v73
	v_max_u32_e32 v84, v86, v83
	v_min_u32_e32 v83, v86, v83
	v_max_u32_e32 v78, v65, v81
	v_min_u32_e32 v65, v65, v81
	v_max_u32_e32 v81, v79, v80
	v_min_u32_e32 v79, v79, v80
	v_max_u32_e32 v80, v90, v74
	v_min_u32_e32 v74, v90, v74
	v_max_u32_e32 v90, v68, v66
	v_min_u32_e32 v66, v68, v66
	v_max_u32_e32 v68, v62, v64
	v_min_u32_e32 v62, v62, v64
	v_max_u32_e32 v64, v77, v67
	v_min_u32_e32 v67, v77, v67
	v_max_u32_e32 v77, v75, v69
	v_min_u32_e32 v69, v75, v69
	v_max_u32_e32 v75, v76, v63
	v_min_u32_e32 v63, v76, v63
	v_max_u32_e32 v86, v3, v89
	v_min_u32_e32 v3, v3, v89
	v_max_u32_e32 v89, v87, v88
	v_min_u32_e32 v87, v87, v88
	v_max_u32_e32 v88, v98, v82
	v_min_u32_e32 v82, v98, v82
	v_max_u32_e32 v98, v72, v70
	v_min_u32_e32 v70, v72, v70
	v_max_u32_e32 v72, v0, v2
	v_min_u32_e32 v0, v0, v2
	v_max_u32_e32 v2, v85, v71
	v_min_u32_e32 v71, v85, v71
	v_max_u32_e32 v85, v83, v73
	v_min_u32_e32 v73, v83, v73
	v_max_u32_e32 v83, v84, v1
	v_min_u32_e32 v1, v84, v1
	v_max_u32_e32 v76, v78, v62
	v_min_u32_e32 v62, v78, v62
	v_max_u32_e32 v78, v65, v68
	v_min_u32_e32 v65, v65, v68
	v_max_u32_e32 v68, v81, v67
	v_min_u32_e32 v67, v81, v67
	v_max_u32_e32 v81, v79, v64
	v_min_u32_e32 v64, v79, v64
	v_max_u32_e32 v79, v80, v69
	v_min_u32_e32 v69, v80, v69
	v_max_u32_e32 v80, v74, v77
	v_min_u32_e32 v74, v74, v77
	v_max_u32_e32 v77, v90, v63
	v_min_u32_e32 v63, v90, v63
	v_max_u32_e32 v90, v66, v75
	v_min_u32_e32 v66, v66, v75
	v_max_u32_e32 v84, v86, v0
	v_min_u32_e32 v0, v86, v0
	v_max_u32_e32 v86, v3, v72
	v_min_u32_e32 v3, v3, v72
	v_max_u32_e32 v72, v89, v71
	v_min_u32_e32 v71, v89, v71
	v_max_u32_e32 v89, v87, v2
	v_min_u32_e32 v2, v87, v2
	v_max_u32_e32 v87, v88, v73
	v_min_u32_e32 v73, v88, v73
	v_max_u32_e32 v88, v82, v85
	v_min_u32_e32 v82, v82, v85
	v_max_u32_e32 v85, v98, v1
	v_min_u32_e32 v1, v98, v1
	v_max_u32_e32 v98, v70, v83
	v_min_u32_e32 v70, v70, v83
	v_max_u32_e32 v75, v76, v79
	v_min_u32_e32 v76, v76, v79
	v_max_u32_e32 v79, v78, v80
	v_min_u32_e32 v78, v78, v80
	v_max_u32_e32 v80, v68, v77
	v_min_u32_e32 v68, v68, v77
	v_max_u32_e32 v77, v81, v90
	v_min_u32_e32 v81, v81, v90
	v_max_u32_e32 v90, v62, v69
	v_min_u32_e32 v62, v62, v69
	v_max_u32_e32 v69, v65, v74
	v_min_u32_e32 v65, v65, v74
	v_max_u32_e32 v74, v67, v63
; #define CE_DESC(a, b) do { const unsigned _mx = (a) > (b) ? (a) : (b), _mn = (a) > (b) ? (b) : (a); (a) = _mx; (b) = _mn; } while (0)
; __device__ __forceinline__ void sort16_desc(unsigned (&k)[16]) {
; #pragma unroll
;     for (int size = 2; size <= 16; size <<= 1)
; #pragma unroll
;         for (int stride = size >> 1; stride > 0; stride >>= 1)
; #pragma unroll
;             for (int i = 0; i < 16; ++i) { const int j = i ^ stride;
;                 if (j > i) { if ((i & size) == 0) CE_DESC(k[i], k[j]); else CE_DESC(k[j], k[i]); } }
; }
; __device__ __forceinline__ void merge16(unsigned (&a)[16], const unsigned (&b)[16]) {
; #pragma unroll
;     for (int i = 0; i < 16; ++i) a[i] = a[i] > b[15 - i] ? a[i] : b[15 - i];
; #pragma unroll
;     for (int stride = 8; stride > 0; stride >>= 1)
; #pragma unroll
;         for (int i = 0; i < 16; ++i) { const int j = i ^ stride; if (j > i) CE_DESC(a[i], a[j]); }
; }
; __device__ __forceinline__ void peer_tile(const Args& A, LAS unsigned char* lds, int tile) {
;     ...
;                 for (int msk = 16; msk <= 32; msk <<= 1) {
; #pragma unroll
;                     for (int i = 0; i < 16; ++i) k1[i] = (unsigned)__shfl_xor((int)k0[i], msk);
;                     merge16(k0, k1); }
	v_min_u32_e32 v63, v67, v63
	v_max_u32_e32 v67, v64, v66
	v_min_u32_e32 v64, v64, v66
	v_max_u32_e32 v83, v84, v87
	v_min_u32_e32 v84, v84, v87
	v_max_u32_e32 v87, v86, v88
	v_min_u32_e32 v86, v86, v88
	v_max_u32_e32 v88, v72, v85
	v_min_u32_e32 v72, v72, v85
	v_max_u32_e32 v85, v89, v98
	v_min_u32_e32 v89, v89, v98
	v_max_u32_e32 v98, v0, v73
	v_min_u32_e32 v0, v0, v73
	v_max_u32_e32 v73, v3, v82
	v_min_u32_e32 v3, v3, v82
	v_max_u32_e32 v82, v71, v1
	v_min_u32_e32 v1, v71, v1
	v_max_u32_e32 v71, v2, v70
	v_min_u32_e32 v2, v2, v70
	v_max_u32_e32 v66, v75, v80
	v_min_u32_e32 v75, v75, v80
	v_max_u32_e32 v80, v79, v77
	v_min_u32_e32 v77, v79, v77
	v_max_u32_e32 v79, v76, v68
	v_min_u32_e32 v68, v76, v68
	v_max_u32_e32 v76, v78, v81
	v_min_u32_e32 v78, v78, v81
	v_max_u32_e32 v81, v90, v74
	v_min_u32_e32 v74, v90, v74
	v_max_u32_e32 v90, v69, v67
	v_min_u32_e32 v67, v69, v67
	v_max_u32_e32 v69, v62, v63
	v_min_u32_e32 v62, v62, v63
	v_max_u32_e32 v63, v65, v64
	v_min_u32_e32 v64, v65, v64
	v_max_u32_e32 v70, v83, v88
	v_min_u32_e32 v83, v83, v88
	v_max_u32_e32 v88, v87, v85
	v_min_u32_e32 v85, v87, v85
	v_max_u32_e32 v87, v84, v72
	v_min_u32_e32 v72, v84, v72
	v_max_u32_e32 v84, v86, v89
	v_min_u32_e32 v86, v86, v89
	v_max_u32_e32 v89, v98, v82
	v_min_u32_e32 v82, v98, v82
	v_max_u32_e32 v98, v73, v71
	v_min_u32_e32 v71, v73, v71
	v_max_u32_e32 v73, v0, v1
	v_min_u32_e32 v0, v0, v1
	v_max_u32_e32 v1, v3, v2
	v_min_u32_e32 v2, v3, v2
	v_min_u32_e32 v65, v66, v80
	v_min_u32_e32 v91, v75, v77
	v_min_u32_e32 v92, v79, v76
	v_min_u32_e32 v93, v68, v78
	v_min_u32_e32 v94, v81, v90
	v_min_u32_e32 v95, v74, v67
	v_min_u32_e32 v96, v69, v63
	v_min_u32_e32 v97, v62, v64
	v_min_u32_e32 v3, v70, v88
	v_min_u32_e32 v99, v83, v85
	v_min_u32_e32 v100, v87, v84
	v_min_u32_e32 v101, v72, v86
	v_min_u32_e32 v102, v89, v98
	v_min_u32_e32 v103, v82, v71
	v_min_u32_e32 v104, v73, v1
	v_min_u32_e32 v105, v0, v2
	v_max3_u32 v66, v66, v80, v105
	v_max3_u32 v0, v65, v0, v2
	v_max3_u32 v2, v75, v77, v104
	v_max3_u32 v1, v91, v73, v1
	v_max3_u32 v65, v79, v76, v103
	v_max3_u32 v71, v92, v82, v71
	v_max3_u32 v68, v68, v78, v102
	v_max3_u32 v73, v93, v89, v98
	v_max3_u32 v75, v81, v90, v101
	v_max3_u32 v72, v94, v72, v86
	v_max3_u32 v67, v74, v67, v100
	v_max3_u32 v74, v95, v87, v84
	v_max3_u32 v63, v69, v63, v99
	v_max3_u32 v69, v96, v83, v85
	v_max3_u32 v3, v62, v64, v3
	v_max3_u32 v62, v97, v70, v88
	v_max_u32_e32 v64, v66, v75
	v_min_u32_e32 v66, v66, v75
	v_max_u32_e32 v70, v0, v72
	v_min_u32_e32 v0, v0, v72
	v_max_u32_e32 v72, v2, v67
	v_min_u32_e32 v2, v2, v67
	v_max_u32_e32 v67, v1, v74
	v_min_u32_e32 v1, v1, v74
	v_max_u32_e32 v74, v65, v63
	v_min_u32_e32 v63, v65, v63
	v_max_u32_e32 v65, v71, v69
	v_min_u32_e32 v69, v71, v69
	v_max_u32_e32 v71, v68, v3
	v_min_u32_e32 v3, v68, v3
	v_max_u32_e32 v68, v73, v62
	v_min_u32_e32 v62, v73, v62
	v_max_u32_e32 v73, v64, v74
	v_min_u32_e32 v64, v64, v74
	v_max_u32_e32 v74, v70, v65
	v_min_u32_e32 v65, v70, v65
	v_max_u32_e32 v70, v72, v71
	v_min_u32_e32 v71, v72, v71
	v_max_u32_e32 v72, v67, v68
	v_min_u32_e32 v67, v67, v68
	v_max_u32_e32 v68, v66, v63
	v_min_u32_e32 v63, v66, v63
	v_max_u32_e32 v66, v0, v69
	v_min_u32_e32 v0, v0, v69
	v_max_u32_e32 v69, v2, v3
	v_min_u32_e32 v2, v2, v3
	v_max_u32_e32 v3, v1, v62
	v_min_u32_e32 v1, v1, v62
	v_max_u32_e32 v62, v73, v70
	v_min_u32_e32 v70, v73, v70
	v_max_u32_e32 v73, v74, v72
	v_min_u32_e32 v72, v74, v72
	v_max_u32_e32 v74, v64, v71
	v_min_u32_e32 v64, v64, v71
	v_max_u32_e32 v71, v65, v67
	v_min_u32_e32 v65, v65, v67
	v_max_u32_e32 v67, v68, v69
	v_min_u32_e32 v68, v68, v69
	v_max_u32_e32 v69, v66, v3
	v_min_u32_e32 v3, v66, v3
	v_max_u32_e32 v66, v63, v2
	v_min_u32_e32 v2, v63, v2
	v_max_u32_e32 v63, v0, v1
	v_min_u32_e32 v0, v0, v1
	v_max_u32_e32 v1, v62, v73
	v_min_u32_e32 v62, v62, v73
	v_max_u32_e32 v73, v70, v72
	v_min_u32_e32 v70, v70, v72
	v_max_u32_e32 v72, v74, v71
	v_min_u32_e32 v71, v74, v71
	v_max_u32_e32 v74, v64, v65
	v_min_u32_e32 v64, v64, v65
	v_max_u32_e32 v65, v67, v69
	v_min_u32_e32 v67, v67, v69
	v_max_u32_e32 v69, v68, v3
	v_min_u32_e32 v3, v68, v3
	v_max_u32_e32 v68, v66, v63
	v_min_u32_e32 v63, v66, v63
	v_max_u32_e32 v66, v2, v0
	v_min_u32_e32 v0, v2, v0
	ds_bpermute_b32 v2, v27, v1
	ds_bpermute_b32 v75, v27, v62
	ds_bpermute_b32 v76, v27, v73
	ds_bpermute_b32 v77, v27, v70
	ds_bpermute_b32 v78, v27, v72
	ds_bpermute_b32 v79, v27, v71
	ds_bpermute_b32 v80, v27, v74
	ds_bpermute_b32 v81, v27, v64
	ds_bpermute_b32 v82, v27, v65
	ds_bpermute_b32 v83, v27, v67
	ds_bpermute_b32 v84, v27, v69
	ds_bpermute_b32 v85, v27, v0
	ds_bpermute_b32 v86, v27, v66
	ds_bpermute_b32 v87, v27, v63
	ds_bpermute_b32 v88, v27, v68
	ds_bpermute_b32 v89, v27, v3
	s_waitcnt lgkmcnt(4)
	v_max_u32_e32 v1, v1, v85
	s_waitcnt lgkmcnt(3)
	v_max_u32_e32 v62, v62, v86
	s_waitcnt lgkmcnt(2)
	v_max_u32_e32 v73, v73, v87
	s_waitcnt lgkmcnt(1)
	v_max_u32_e32 v70, v70, v88
	s_waitcnt lgkmcnt(0)
; __device__ __forceinline__ void peer_tile(const Args& A, LAS unsigned char* lds, int tile) {
;     ...
;                 { const bf16_t* sp = QRY + m * 2048 + hp * 128 + 32 * g;
;                   const u32x4 s0 = *(const u32x4*)sp, s1 = *(const u32x4*)(sp + 8), s2 = *(const u32x4*)(sp + 16), s3 = *(const u32x4*)(sp + 24);
;     ...
;                 sort16_desc(k0); sort16_desc(k1); merge16(k0, k1);
; #pragma unroll
;                 for (int msk = 16; msk <= 32; msk <<= 1) {
; #pragma unroll
;                     for (int i = 0; i < 16; ++i) k1[i] = (unsigned)__shfl_xor((int)k0[i], msk);
;                     merge16(k0, k1); }
	v_max_u32_e32 v72, v72, v89
	v_max_u32_e32 v71, v71, v84
	v_max_u32_e32 v74, v74, v83
	v_max_u32_e32 v64, v64, v82
	v_max_u32_e32 v65, v65, v81
	v_max_u32_e32 v67, v67, v80
	v_max_u32_e32 v69, v69, v79
	v_max_u32_e32 v3, v3, v78
	v_max_u32_e32 v68, v68, v77
	v_max_u32_e32 v63, v63, v76
	v_max_u32_e32 v66, v66, v75
	v_max_u32_e32 v0, v0, v2
	v_max_u32_e32 v2, v1, v65
	v_min_u32_e32 v1, v1, v65
	v_max_u32_e32 v65, v62, v67
	v_min_u32_e32 v62, v62, v67
	v_max_u32_e32 v67, v73, v69
	v_min_u32_e32 v69, v73, v69
	v_max_u32_e32 v73, v70, v3
	v_min_u32_e32 v3, v70, v3
	v_max_u32_e32 v70, v72, v68
	v_min_u32_e32 v68, v72, v68
	v_max_u32_e32 v72, v71, v63
	v_min_u32_e32 v63, v71, v63
	v_max_u32_e32 v71, v74, v66
	v_min_u32_e32 v66, v74, v66
	v_max_u32_e32 v74, v64, v0
	v_min_u32_e32 v0, v64, v0
	v_max_u32_e32 v64, v2, v70
	v_min_u32_e32 v2, v2, v70
	v_max_u32_e32 v70, v65, v72
	v_min_u32_e32 v65, v65, v72
	v_max_u32_e32 v72, v67, v71
	v_min_u32_e32 v67, v67, v71
	v_max_u32_e32 v71, v73, v74
	v_min_u32_e32 v73, v73, v74
	v_max_u32_e32 v74, v1, v68
	v_min_u32_e32 v1, v1, v68
	v_max_u32_e32 v68, v62, v63
	v_min_u32_e32 v62, v62, v63
	v_max_u32_e32 v63, v69, v66
	v_min_u32_e32 v66, v69, v66
	v_max_u32_e32 v69, v3, v0
	v_min_u32_e32 v0, v3, v0
	v_max_u32_e32 v3, v64, v72
	v_min_u32_e32 v64, v64, v72
	v_max_u32_e32 v72, v70, v71
	v_min_u32_e32 v70, v70, v71
	v_max_u32_e32 v71, v2, v67
	v_min_u32_e32 v2, v2, v67
	v_max_u32_e32 v67, v65, v73
	v_min_u32_e32 v65, v65, v73
	v_max_u32_e32 v73, v74, v63
	v_min_u32_e32 v63, v74, v63
	v_max_u32_e32 v74, v68, v69
	v_min_u32_e32 v68, v68, v69
	v_max_u32_e32 v69, v1, v66
	v_min_u32_e32 v1, v1, v66
	v_max_u32_e32 v66, v62, v0
	v_min_u32_e32 v0, v62, v0
	v_max_u32_e32 v62, v3, v72
	v_min_u32_e32 v3, v3, v72
	v_max_u32_e32 v72, v64, v70
	v_min_u32_e32 v64, v64, v70
	v_max_u32_e32 v70, v71, v67
	v_min_u32_e32 v67, v71, v67
	v_max_u32_e32 v71, v2, v65
	v_min_u32_e32 v2, v2, v65
	v_max_u32_e32 v65, v73, v74
	v_min_u32_e32 v73, v73, v74
	v_max_u32_e32 v74, v63, v68
	v_min_u32_e32 v63, v63, v68
	v_max_u32_e32 v68, v69, v66
	v_min_u32_e32 v66, v69, v66
	v_max_u32_e32 v69, v1, v0
	v_min_u32_e32 v0, v1, v0
	ds_bpermute_b32 v78, v29, v0
	ds_bpermute_b32 v1, v29, v62
	ds_bpermute_b32 v75, v29, v3
	ds_bpermute_b32 v76, v29, v72
	ds_bpermute_b32 v77, v29, v64
	s_waitcnt lgkmcnt(4)
	v_max_u32_e32 v62, v62, v78
	global_load_dwordx4 v[78:81], v[4:5], off offset:784
	global_load_dwordx4 v[82:85], v[4:5], off offset:768
	ds_bpermute_b32 v86, v29, v70
	ds_bpermute_b32 v87, v29, v67
	ds_bpermute_b32 v88, v29, v71
	ds_bpermute_b32 v89, v29, v2
	ds_bpermute_b32 v90, v29, v65
	ds_bpermute_b32 v91, v29, v73
	ds_bpermute_b32 v92, v29, v74
	ds_bpermute_b32 v93, v29, v63
	ds_bpermute_b32 v94, v29, v68
	ds_bpermute_b32 v95, v29, v69
	ds_bpermute_b32 v96, v29, v66
	s_waitcnt lgkmcnt(4)
	v_max_u32_e32 v67, v67, v92
	s_waitcnt lgkmcnt(3)
	v_max_u32_e32 v70, v70, v93
	s_waitcnt lgkmcnt(2)
	v_max_u32_e32 v64, v64, v94
	s_waitcnt lgkmcnt(1)
	v_max_u32_e32 v3, v3, v95
	s_waitcnt lgkmcnt(0)
	v_max_u32_e32 v72, v72, v96
	v_max_u32_e32 v71, v71, v91
	v_max_u32_e32 v2, v2, v90
	v_max_u32_e32 v65, v65, v89
	v_max_u32_e32 v73, v73, v88
	v_max_u32_e32 v74, v74, v87
	v_max_u32_e32 v63, v63, v86
	v_max_u32_e32 v68, v68, v77
	v_max_u32_e32 v66, v66, v76
	v_max_u32_e32 v69, v69, v75
	v_max_u32_e32 v0, v0, v1
	v_max_u32_e32 v1, v62, v65
	v_min_u32_e32 v62, v62, v65
	v_max_u32_e32 v65, v3, v73
	v_min_u32_e32 v3, v3, v73
	v_max_u32_e32 v73, v72, v74
	v_min_u32_e32 v72, v72, v74
	v_max_u32_e32 v74, v64, v63
	v_min_u32_e32 v63, v64, v63
	v_max_u32_e32 v64, v70, v68
	v_min_u32_e32 v68, v70, v68
	v_max_u32_e32 v70, v67, v66
	v_min_u32_e32 v66, v67, v66
	v_max_u32_e32 v67, v71, v69
	v_min_u32_e32 v69, v71, v69
	v_max_u32_e32 v71, v2, v0
	v_min_u32_e32 v0, v2, v0
	v_max_u32_e32 v2, v1, v64
	v_min_u32_e32 v1, v1, v64
	v_max_u32_e32 v64, v65, v70
	v_min_u32_e32 v65, v65, v70
	v_max_u32_e32 v70, v73, v67
	v_min_u32_e32 v67, v73, v67
	v_max_u32_e32 v73, v74, v71
	v_min_u32_e32 v71, v74, v71
	v_max_u32_e32 v74, v62, v68
	v_min_u32_e32 v62, v62, v68
	v_max_u32_e32 v68, v3, v66
	v_min_u32_e32 v3, v3, v66
	v_max_u32_e32 v66, v72, v69
	v_min_u32_e32 v69, v72, v69
	v_max_u32_e32 v72, v63, v0
	v_min_u32_e32 v0, v63, v0
	v_max_u32_e32 v63, v2, v70
	v_min_u32_e32 v2, v2, v70
	v_max_u32_e32 v70, v64, v73
	v_min_u32_e32 v64, v64, v73
	v_max_u32_e32 v86, v1, v67
	v_min_u32_e32 v1, v1, v67
	v_max_u32_e32 v67, v65, v71
	v_min_u32_e32 v65, v65, v71
	v_max_u32_e32 v87, v74, v66
	v_min_u32_e32 v66, v74, v66
	v_max_u32_e32 v88, v68, v72
	v_min_u32_e32 v89, v68, v72
	v_max_u32_e32 v90, v62, v69
	v_min_u32_e32 v62, v62, v69
	v_max_u32_e32 v91, v3, v0
	v_min_u32_e32 v0, v3, v0
	v_max_u32_e32 v77, v63, v70
	v_min_u32_e32 v76, v63, v70
	v_max_u32_e32 v75, v2, v64
	v_min_u32_e32 v74, v2, v64
	v_max_u32_e32 v73, v86, v67
	v_min_u32_e32 v72, v86, v67
	v_max_u32_e32 v71, v1, v65
	v_min_u32_e32 v70, v1, v65
	v_max_u32_e32 v69, v87, v88
	v_min_u32_e32 v68, v87, v88
	v_max_u32_e32 v67, v66, v89
	v_min_u32_e32 v66, v66, v89
	v_max_u32_e32 v63, v62, v0
	v_min_u32_e32 v62, v62, v0
	global_load_dwordx4 v[0:3], v[4:5], off offset:816
	global_load_dwordx4 v[86:89], v[4:5], off offset:800
	v_max_u32_e32 v65, v90, v91
	v_min_u32_e32 v64, v90, v91
	s_waitcnt vmcnt(2)
; __device__ __forceinline__ unsigned f2key(float f) { const unsigned u = __float_as_uint(f); return (u & 0x80000000u) ? ~u : (u | 0x80000000u); }
; __device__ __forceinline__ void peer_tile(const Args& A, LAS unsigned char* lds, int tile) {
;     ...
;                   for (int i = 0; i < 16; ++i) {
;                       const float lo = (float)__builtin_bit_cast(_Float16, (unsigned short)(sw[i] & 0xffffu)), hi = (float)__builtin_bit_cast(_Float16, (unsigned short)(sw[i] >> 16));
;                       const unsigned klo = (f2key(lo) & ~127u) | (unsigned)(127 - (32 * g + 2 * i)), khi = (f2key(hi) & ~127u) | (unsigned)(127 - (32 * g + 2 * i + 1));
;                       if (i < 8) { k0[2 * i] = klo; k0[2 * i + 1] = khi; } else { k1[2 * (i - 8)] = klo; k1[2 * (i - 8) + 1] = khi; } } }
;     ...
;             for (int p = 0; p < 2; ++p)
; #pragma unroll
;                 for (int i = 0; i < 16; ++i) L2[p][i] = (g & 2) ? ((g & 1) ? LA[3][p][i] : LA[2][p][i]) : ((g & 1) ? LA[1][p][i] : LA[0][p][i]);
	v_cvt_f32_f16_sdwa v90, v82 dst_sel:DWORD dst_unused:UNUSED_PAD src0_sel:WORD_1
	v_cvt_f32_f16_e32 v82, v82
	v_cndmask_b32_e64 v38, v70, v38, s[0:1]
	v_cndmask_b32_e64 v37, v69, v37, s[0:1]
	v_not_b32_e32 v91, v90
	v_or_b32_e32 v92, 0x80000000, v90
	v_cmp_gt_i32_e32 vcc, 0, v90
	v_cndmask_b32_e64 v36, v68, v36, s[0:1]
	v_cndmask_b32_e64 v35, v67, v35, s[0:1]
	v_cndmask_b32_e32 v90, v92, v91, vcc
	v_not_b32_e32 v91, v82
	v_or_b32_e32 v92, 0x80000000, v82
	v_cmp_gt_i32_e32 vcc, 0, v82
	v_and_b32_e32 v90, 0xffffff80, v90
	v_sub_u32_e32 v90, v90, v15
	v_cndmask_b32_e32 v82, v92, v91, vcc
	v_cvt_f32_f16_sdwa v91, v83 dst_sel:DWORD dst_unused:UNUSED_PAD src0_sel:WORD_1
	v_cvt_f32_f16_e32 v83, v83
	v_and_b32_e32 v82, 0xffffff80, v82
	v_sub_u32_e32 v82, v82, v15
	v_not_b32_e32 v92, v91
	v_or_b32_e32 v93, 0x80000000, v91
	v_cmp_gt_i32_e32 vcc, 0, v91
	v_add_u32_e32 v90, 0x7e, v90
	v_add_u32_e32 v82, 0x7f, v82
	v_cndmask_b32_e32 v91, v93, v92, vcc
	v_not_b32_e32 v92, v83
	v_or_b32_e32 v93, 0x80000000, v83
	v_cmp_gt_i32_e32 vcc, 0, v83
	v_and_b32_e32 v91, 0xffffff80, v91
	v_sub_u32_e32 v91, v91, v14
	v_cndmask_b32_e32 v83, v93, v92, vcc
	v_cvt_f32_f16_sdwa v92, v84 dst_sel:DWORD dst_unused:UNUSED_PAD src0_sel:WORD_1
	v_cvt_f32_f16_e32 v84, v84
	v_and_b32_e32 v83, 0xffffff80, v83
	v_sub_u32_e32 v83, v83, v14
	v_not_b32_e32 v93, v92
	v_or_b32_e32 v94, 0x80000000, v92
	v_cmp_gt_i32_e32 vcc, 0, v92
	v_add_u32_e32 v91, 0x7e, v91
	v_add_u32_e32 v83, 0x7f, v83
	v_cndmask_b32_e32 v92, v94, v93, vcc
	v_not_b32_e32 v93, v84
	v_or_b32_e32 v94, 0x80000000, v84
	v_cmp_gt_i32_e32 vcc, 0, v84
	v_and_b32_e32 v92, 0xffffff80, v92
	v_sub_u32_e32 v92, v92, v12
	v_cndmask_b32_e32 v84, v94, v93, vcc
	v_cvt_f32_f16_sdwa v93, v85 dst_sel:DWORD dst_unused:UNUSED_PAD src0_sel:WORD_1
	v_cvt_f32_f16_e32 v85, v85
	v_and_b32_e32 v84, 0xffffff80, v84
	v_sub_u32_e32 v84, v84, v12
	v_not_b32_e32 v94, v93
	v_or_b32_e32 v95, 0x80000000, v93
	v_cmp_gt_i32_e32 vcc, 0, v93
	v_add_u32_e32 v92, 0x7e, v92
	v_add_u32_e32 v84, 0x7f, v84
	v_cndmask_b32_e32 v93, v95, v94, vcc
	v_not_b32_e32 v94, v85
	v_or_b32_e32 v95, 0x80000000, v85
	v_cmp_gt_i32_e32 vcc, 0, v85
	v_and_b32_e32 v93, 0xffffff80, v93
	v_sub_u32_e32 v93, v93, v10
	v_cndmask_b32_e32 v85, v95, v94, vcc
	v_cvt_f32_f16_sdwa v94, v78 dst_sel:DWORD dst_unused:UNUSED_PAD src0_sel:WORD_1
	v_cvt_f32_f16_e32 v78, v78
	v_and_b32_e32 v85, 0xffffff80, v85
	v_sub_u32_e32 v85, v85, v10
	v_not_b32_e32 v95, v94
	v_or_b32_e32 v96, 0x80000000, v94
	v_cmp_gt_i32_e32 vcc, 0, v94
	v_add_u32_e32 v93, 0x7e, v93
	v_add_u32_e32 v85, 0x7f, v85
	v_cndmask_b32_e32 v94, v96, v95, vcc
	v_not_b32_e32 v95, v78
	v_or_b32_e32 v96, 0x80000000, v78
	v_cmp_gt_i32_e32 vcc, 0, v78
	v_and_b32_e32 v94, 0xffffff80, v94
	v_sub_u32_e32 v94, v94, v8
	v_cndmask_b32_e32 v78, v96, v95, vcc
	v_cvt_f32_f16_sdwa v95, v79 dst_sel:DWORD dst_unused:UNUSED_PAD src0_sel:WORD_1
	v_cvt_f32_f16_e32 v79, v79
	v_and_b32_e32 v78, 0xffffff80, v78
	v_sub_u32_e32 v78, v78, v8
	v_not_b32_e32 v96, v95
	v_or_b32_e32 v97, 0x80000000, v95
	v_cmp_gt_i32_e32 vcc, 0, v95
	v_add_u32_e32 v94, 0x7e, v94
	v_add_u32_e32 v78, 0x7f, v78
	v_cndmask_b32_e32 v95, v97, v96, vcc
	v_not_b32_e32 v96, v79
	v_or_b32_e32 v97, 0x80000000, v79
	v_cmp_gt_i32_e32 vcc, 0, v79
	v_and_b32_e32 v95, 0xffffff80, v95
	v_sub_u32_e32 v95, v95, v16
	v_cndmask_b32_e32 v79, v97, v96, vcc
	v_cvt_f32_f16_sdwa v96, v80 dst_sel:DWORD dst_unused:UNUSED_PAD src0_sel:WORD_1
	v_cvt_f32_f16_e32 v80, v80
	v_and_b32_e32 v79, 0xffffff80, v79
	v_sub_u32_e32 v79, v79, v16
	v_not_b32_e32 v97, v96
	v_or_b32_e32 v98, 0x80000000, v96
	v_cmp_gt_i32_e32 vcc, 0, v96
	v_add_u32_e32 v95, 0x7e, v95
	v_add_u32_e32 v79, 0x7f, v79
	v_cndmask_b32_e32 v96, v98, v97, vcc
	v_not_b32_e32 v97, v80
	v_or_b32_e32 v98, 0x80000000, v80
	v_cmp_gt_i32_e32 vcc, 0, v80
	v_and_b32_e32 v96, 0xffffff80, v96
	v_sub_u32_e32 v96, v96, v17
	v_cndmask_b32_e32 v80, v98, v97, vcc
	v_cvt_f32_f16_sdwa v97, v81 dst_sel:DWORD dst_unused:UNUSED_PAD src0_sel:WORD_1
	v_cvt_f32_f16_e32 v81, v81
	v_and_b32_e32 v80, 0xffffff80, v80
	v_sub_u32_e32 v80, v80, v17
	v_not_b32_e32 v98, v97
	v_or_b32_e32 v99, 0x80000000, v97
	v_cmp_gt_i32_e32 vcc, 0, v97
	v_add_u32_e32 v96, 0x7e, v96
	v_add_u32_e32 v80, 0x7f, v80
	v_cndmask_b32_e32 v97, v99, v98, vcc
	v_not_b32_e32 v98, v81
	v_or_b32_e32 v99, 0x80000000, v81
	v_cmp_gt_i32_e32 vcc, 0, v81
	v_and_b32_e32 v97, 0xffffff80, v97
	v_sub_u32_e32 v97, v97, v18
	v_cndmask_b32_e32 v81, v99, v98, vcc
	s_waitcnt vmcnt(0)
; __device__ __forceinline__ unsigned f2key(float f) { const unsigned u = __float_as_uint(f); return (u & 0x80000000u) ? ~u : (u | 0x80000000u); }
; #define CE_DESC(a, b) do { const unsigned _mx = (a) > (b) ? (a) : (b), _mn = (a) > (b) ? (b) : (a); (a) = _mx; (b) = _mn; } while (0)
; __device__ __forceinline__ void sort16_desc(unsigned (&k)[16]) {
; #pragma unroll
;     for (int size = 2; size <= 16; size <<= 1)
; #pragma unroll
;         for (int stride = size >> 1; stride > 0; stride >>= 1)
; #pragma unroll
;             for (int i = 0; i < 16; ++i) { const int j = i ^ stride;
;                 if (j > i) { if ((i & size) == 0) CE_DESC(k[i], k[j]); else CE_DESC(k[j], k[i]); } }
; }
; __device__ __forceinline__ void peer_tile(const Args& A, LAS unsigned char* lds, int tile) {
;     ...
;                   for (int i = 0; i < 16; ++i) {
;                       const float lo = (float)__builtin_bit_cast(_Float16, (unsigned short)(sw[i] & 0xffffu)), hi = (float)__builtin_bit_cast(_Float16, (unsigned short)(sw[i] >> 16));
;                       const unsigned klo = (f2key(lo) & ~127u) | (unsigned)(127 - (32 * g + 2 * i)), khi = (f2key(hi) & ~127u) | (unsigned)(127 - (32 * g + 2 * i + 1));
;                       if (i < 8) { k0[2 * i] = klo; k0[2 * i + 1] = khi; } else { k1[2 * (i - 8)] = klo; k1[2 * (i - 8) + 1] = khi; } } }
	v_cvt_f32_f16_sdwa v98, v86 dst_sel:DWORD dst_unused:UNUSED_PAD src0_sel:WORD_1
	v_cvt_f32_f16_e32 v86, v86
	v_and_b32_e32 v81, 0xffffff80, v81
	v_sub_u32_e32 v81, v81, v18
	v_not_b32_e32 v99, v98
	v_or_b32_e32 v100, 0x80000000, v98
	v_cmp_gt_i32_e32 vcc, 0, v98
	v_add_u32_e32 v97, 0x7e, v97
	v_add_u32_e32 v81, 0x7f, v81
	v_cndmask_b32_e32 v98, v100, v99, vcc
	v_not_b32_e32 v99, v86
	v_or_b32_e32 v100, 0x80000000, v86
	v_cmp_gt_i32_e32 vcc, 0, v86
	v_and_b32_e32 v98, 0xffffff80, v98
	v_sub_u32_e32 v98, v98, v20
	v_cndmask_b32_e32 v86, v100, v99, vcc
	v_cvt_f32_f16_sdwa v99, v87 dst_sel:DWORD dst_unused:UNUSED_PAD src0_sel:WORD_1
	v_cvt_f32_f16_e32 v87, v87
	v_and_b32_e32 v86, 0xffffff80, v86
	v_sub_u32_e32 v86, v86, v20
	v_not_b32_e32 v100, v99
	v_or_b32_e32 v101, 0x80000000, v99
	v_cmp_gt_i32_e32 vcc, 0, v99
	v_add_u32_e32 v98, 0x7e, v98
	v_add_u32_e32 v86, 0x7f, v86
	v_cndmask_b32_e32 v99, v101, v100, vcc
	v_not_b32_e32 v100, v87
	v_or_b32_e32 v101, 0x80000000, v87
	v_cmp_gt_i32_e32 vcc, 0, v87
	v_and_b32_e32 v99, 0xffffff80, v99
	v_sub_u32_e32 v99, v99, v21
	v_cndmask_b32_e32 v87, v101, v100, vcc
	v_cvt_f32_f16_sdwa v100, v88 dst_sel:DWORD dst_unused:UNUSED_PAD src0_sel:WORD_1
	v_cvt_f32_f16_e32 v88, v88
	v_and_b32_e32 v87, 0xffffff80, v87
	v_sub_u32_e32 v87, v87, v21
	v_not_b32_e32 v101, v100
	v_or_b32_e32 v102, 0x80000000, v100
	v_cmp_gt_i32_e32 vcc, 0, v100
	v_add_u32_e32 v99, 0x7e, v99
	v_add_u32_e32 v87, 0x7f, v87
	v_cndmask_b32_e32 v100, v102, v101, vcc
	v_not_b32_e32 v101, v88
	v_or_b32_e32 v102, 0x80000000, v88
	v_cmp_gt_i32_e32 vcc, 0, v88
	v_and_b32_e32 v100, 0xffffff80, v100
	v_sub_u32_e32 v100, v100, v22
	v_cndmask_b32_e32 v88, v102, v101, vcc
	v_cvt_f32_f16_sdwa v101, v89 dst_sel:DWORD dst_unused:UNUSED_PAD src0_sel:WORD_1
	v_cvt_f32_f16_e32 v89, v89
	v_and_b32_e32 v88, 0xffffff80, v88
	v_sub_u32_e32 v88, v88, v22
	v_not_b32_e32 v102, v101
	v_or_b32_e32 v103, 0x80000000, v101
	v_cmp_gt_i32_e32 vcc, 0, v101
	v_add_u32_e32 v100, 0x7e, v100
	v_add_u32_e32 v88, 0x7f, v88
	v_cndmask_b32_e32 v101, v103, v102, vcc
	v_not_b32_e32 v102, v89
	v_or_b32_e32 v103, 0x80000000, v89
	v_cmp_gt_i32_e32 vcc, 0, v89
	v_and_b32_e32 v101, 0xffffff80, v101
	v_sub_u32_e32 v101, v101, v23
	v_cndmask_b32_e32 v89, v103, v102, vcc
	v_cvt_f32_f16_sdwa v102, v0 dst_sel:DWORD dst_unused:UNUSED_PAD src0_sel:WORD_1
	v_cvt_f32_f16_e32 v0, v0
	v_and_b32_e32 v89, 0xffffff80, v89
	v_sub_u32_e32 v89, v89, v23
	v_not_b32_e32 v103, v102
	v_or_b32_e32 v104, 0x80000000, v102
	v_cmp_gt_i32_e32 vcc, 0, v102
	v_add_u32_e32 v101, 0x7e, v101
	v_add_u32_e32 v89, 0x7f, v89
	v_cndmask_b32_e32 v102, v104, v103, vcc
	v_not_b32_e32 v103, v0
	v_or_b32_e32 v104, 0x80000000, v0
	v_cmp_gt_i32_e32 vcc, 0, v0
	v_and_b32_e32 v102, 0xffffff80, v102
	v_sub_u32_e32 v102, v102, v24
	v_cndmask_b32_e32 v0, v104, v103, vcc
	v_cvt_f32_f16_sdwa v103, v1 dst_sel:DWORD dst_unused:UNUSED_PAD src0_sel:WORD_1
	v_cvt_f32_f16_e32 v1, v1
	v_and_b32_e32 v0, 0xffffff80, v0
	v_sub_u32_e32 v0, v0, v24
	v_not_b32_e32 v104, v103
	v_or_b32_e32 v105, 0x80000000, v103
	v_cmp_gt_i32_e32 vcc, 0, v103
	v_add_u32_e32 v102, 0x7e, v102
	v_add_u32_e32 v0, 0x7f, v0
	v_cndmask_b32_e32 v103, v105, v104, vcc
	v_not_b32_e32 v104, v1
	v_or_b32_e32 v105, 0x80000000, v1
	v_cmp_gt_i32_e32 vcc, 0, v1
	v_and_b32_e32 v103, 0xffffff80, v103
	v_sub_u32_e32 v103, v103, v25
	v_cndmask_b32_e32 v1, v105, v104, vcc
	v_cvt_f32_f16_sdwa v104, v2 dst_sel:DWORD dst_unused:UNUSED_PAD src0_sel:WORD_1
	v_cvt_f32_f16_e32 v2, v2
	v_and_b32_e32 v1, 0xffffff80, v1
	v_sub_u32_e32 v1, v1, v25
	v_not_b32_e32 v105, v104
	v_or_b32_e32 v106, 0x80000000, v104
	v_cmp_gt_i32_e32 vcc, 0, v104
	v_add_u32_e32 v103, 0x7e, v103
	v_add_u32_e32 v1, 0x7f, v1
	v_cndmask_b32_e32 v104, v106, v105, vcc
	v_not_b32_e32 v105, v2
	v_or_b32_e32 v106, 0x80000000, v2
	v_cmp_gt_i32_e32 vcc, 0, v2
	v_and_b32_e32 v104, 0xffffff80, v104
	v_sub_u32_e32 v104, v104, v26
	v_cndmask_b32_e32 v2, v106, v105, vcc
	v_cvt_f32_f16_sdwa v105, v3 dst_sel:DWORD dst_unused:UNUSED_PAD src0_sel:WORD_1
	v_cvt_f32_f16_e32 v3, v3
	v_and_b32_e32 v2, 0xffffff80, v2
	v_sub_u32_e32 v2, v2, v26
	v_not_b32_e32 v106, v105
	v_or_b32_e32 v107, 0x80000000, v105
	v_cmp_gt_i32_e32 vcc, 0, v105
	v_add_u32_e32 v104, 0x7e, v104
	v_add_u32_e32 v2, 0x7f, v2
	v_cndmask_b32_e32 v105, v107, v106, vcc
	v_not_b32_e32 v106, v3
	v_or_b32_e32 v107, 0x80000000, v3
	v_cmp_gt_i32_e32 vcc, 0, v3
	v_and_b32_e32 v105, 0xffffff80, v105
	v_sub_u32_e32 v105, v105, v28
	v_cndmask_b32_e32 v3, v107, v106, vcc
	v_and_b32_e32 v3, 0xffffff80, v3
	v_sub_u32_e32 v3, v3, v28
	v_add_u32_e32 v105, 0x7e, v105
	v_add_u32_e32 v3, 0x7f, v3
	v_max_u32_e32 v106, v82, v90
	v_min_u32_e32 v82, v82, v90
	v_max_u32_e32 v90, v91, v83
	v_min_u32_e32 v83, v91, v83
	v_max_u32_e32 v91, v84, v92
	v_min_u32_e32 v84, v84, v92
	v_max_u32_e32 v92, v93, v85
	v_min_u32_e32 v85, v93, v85
	v_max_u32_e32 v93, v78, v94
	v_min_u32_e32 v78, v78, v94
	v_max_u32_e32 v94, v95, v79
	v_min_u32_e32 v79, v95, v79
	v_max_u32_e32 v95, v80, v96
	v_min_u32_e32 v80, v80, v96
	v_max_u32_e32 v96, v97, v81
	v_min_u32_e32 v81, v97, v81
	v_max_u32_e32 v115, v86, v98
	v_min_u32_e32 v86, v86, v98
	v_max_u32_e32 v98, v99, v87
	v_min_u32_e32 v87, v99, v87
	v_max_u32_e32 v99, v88, v100
	v_min_u32_e32 v88, v88, v100
	v_max_u32_e32 v100, v101, v89
	v_min_u32_e32 v89, v101, v89
	v_max_u32_e32 v101, v0, v102
	v_min_u32_e32 v0, v0, v102
	v_max_u32_e32 v102, v103, v1
	v_min_u32_e32 v1, v103, v1
	v_max_u32_e32 v103, v2, v104
	v_min_u32_e32 v2, v2, v104
	v_max_u32_e32 v104, v105, v3
	v_min_u32_e32 v3, v105, v3
	v_max_u32_e32 v97, v106, v83
	v_min_u32_e32 v83, v106, v83
	v_max_u32_e32 v106, v82, v90
; #define CE_DESC(a, b) do { const unsigned _mx = (a) > (b) ? (a) : (b), _mn = (a) > (b) ? (b) : (a); (a) = _mx; (b) = _mn; } while (0)
; __device__ __forceinline__ void sort16_desc(unsigned (&k)[16]) {
; #pragma unroll
;     for (int size = 2; size <= 16; size <<= 1)
; #pragma unroll
;         for (int stride = size >> 1; stride > 0; stride >>= 1)
; #pragma unroll
;             for (int i = 0; i < 16; ++i) { const int j = i ^ stride;
;                 if (j > i) { if ((i & size) == 0) CE_DESC(k[i], k[j]); else CE_DESC(k[j], k[i]); } }
; }
	v_min_u32_e32 v82, v82, v90
	v_max_u32_e32 v90, v85, v91
	v_min_u32_e32 v85, v85, v91
	v_max_u32_e32 v91, v92, v84
	v_min_u32_e32 v84, v92, v84
	v_max_u32_e32 v92, v93, v79
	v_min_u32_e32 v79, v93, v79
	v_max_u32_e32 v93, v78, v94
	v_min_u32_e32 v78, v78, v94
	v_max_u32_e32 v94, v81, v95
	v_min_u32_e32 v81, v81, v95
	v_max_u32_e32 v95, v96, v80
	v_min_u32_e32 v80, v96, v80
	v_max_u32_e32 v105, v115, v87
	v_min_u32_e32 v87, v115, v87
	v_max_u32_e32 v115, v86, v98
	v_min_u32_e32 v86, v86, v98
	v_max_u32_e32 v98, v89, v99
	v_min_u32_e32 v89, v89, v99
	v_max_u32_e32 v99, v100, v88
	v_min_u32_e32 v88, v100, v88
	v_max_u32_e32 v100, v101, v1
	v_min_u32_e32 v1, v101, v1
	v_max_u32_e32 v101, v0, v102
	v_min_u32_e32 v0, v0, v102
	v_max_u32_e32 v102, v3, v103
	v_min_u32_e32 v3, v3, v103
	v_max_u32_e32 v103, v104, v2
	v_min_u32_e32 v2, v104, v2
	v_max_u32_e32 v96, v97, v106
	v_min_u32_e32 v97, v97, v106
	v_max_u32_e32 v106, v83, v82
	v_min_u32_e32 v82, v83, v82
	v_max_u32_e32 v83, v84, v85
	v_min_u32_e32 v84, v84, v85
	v_max_u32_e32 v85, v91, v90
	v_min_u32_e32 v90, v91, v90
	v_max_u32_e32 v91, v92, v93
	v_min_u32_e32 v92, v92, v93
	v_max_u32_e32 v93, v79, v78
	v_min_u32_e32 v78, v79, v78
	v_max_u32_e32 v79, v80, v81
	v_min_u32_e32 v80, v80, v81
	v_max_u32_e32 v81, v95, v94
	v_min_u32_e32 v94, v95, v94
	v_max_u32_e32 v104, v105, v115
	v_min_u32_e32 v105, v105, v115
	v_max_u32_e32 v115, v87, v86
	v_min_u32_e32 v86, v87, v86
	v_max_u32_e32 v87, v88, v89
	v_min_u32_e32 v88, v88, v89
	v_max_u32_e32 v89, v99, v98
	v_min_u32_e32 v98, v99, v98
	v_max_u32_e32 v99, v100, v101
	v_min_u32_e32 v100, v100, v101
	v_max_u32_e32 v101, v1, v0
	v_min_u32_e32 v0, v1, v0
	v_max_u32_e32 v1, v2, v3
	v_min_u32_e32 v2, v2, v3
	v_max_u32_e32 v3, v103, v102
	v_min_u32_e32 v102, v103, v102
	v_max_u32_e32 v95, v96, v84
	v_min_u32_e32 v84, v96, v84
	v_max_u32_e32 v96, v97, v83
	v_min_u32_e32 v83, v97, v83
	v_max_u32_e32 v97, v106, v90
	v_min_u32_e32 v90, v106, v90
	v_max_u32_e32 v106, v82, v85
	v_min_u32_e32 v82, v82, v85
	v_max_u32_e32 v85, v80, v91
	v_min_u32_e32 v80, v80, v91
	v_max_u32_e32 v91, v79, v92
	v_min_u32_e32 v79, v79, v92
	v_max_u32_e32 v92, v94, v93
	v_min_u32_e32 v93, v94, v93
	v_max_u32_e32 v94, v81, v78
	v_min_u32_e32 v78, v81, v78
	v_max_u32_e32 v103, v104, v88
	v_min_u32_e32 v88, v104, v88
	v_max_u32_e32 v104, v105, v87
	v_min_u32_e32 v87, v105, v87
	v_max_u32_e32 v105, v115, v98
	v_min_u32_e32 v98, v115, v98
	v_max_u32_e32 v115, v86, v89
	v_min_u32_e32 v86, v86, v89
	v_max_u32_e32 v89, v2, v99
	v_min_u32_e32 v2, v2, v99
	v_max_u32_e32 v99, v1, v100
	v_min_u32_e32 v1, v1, v100
	v_max_u32_e32 v100, v102, v101
	v_min_u32_e32 v101, v102, v101
	v_max_u32_e32 v102, v3, v0
	v_min_u32_e32 v0, v3, v0
	v_max_u32_e32 v81, v95, v97
	v_min_u32_e32 v95, v95, v97
	v_max_u32_e32 v97, v96, v106
	v_min_u32_e32 v96, v96, v106
	v_max_u32_e32 v106, v84, v90
	v_min_u32_e32 v84, v84, v90
	v_max_u32_e32 v90, v83, v82
	v_min_u32_e32 v82, v83, v82
	v_max_u32_e32 v83, v93, v80
	v_min_u32_e32 v80, v93, v80
	v_max_u32_e32 v93, v78, v79
	v_min_u32_e32 v78, v78, v79
	v_max_u32_e32 v79, v92, v85
	v_min_u32_e32 v85, v92, v85
	v_max_u32_e32 v92, v94, v91
	v_min_u32_e32 v91, v94, v91
	v_max_u32_e32 v3, v103, v105
	v_min_u32_e32 v103, v103, v105
	v_max_u32_e32 v105, v104, v115
	v_min_u32_e32 v104, v104, v115
	v_max_u32_e32 v115, v88, v98
	v_min_u32_e32 v88, v88, v98
	v_max_u32_e32 v98, v87, v86
	v_min_u32_e32 v86, v87, v86
	v_max_u32_e32 v87, v101, v2
	v_min_u32_e32 v2, v101, v2
	v_max_u32_e32 v101, v0, v1
	v_min_u32_e32 v0, v0, v1
	v_max_u32_e32 v1, v100, v89
	v_min_u32_e32 v89, v100, v89
	v_max_u32_e32 v100, v102, v99
	v_min_u32_e32 v99, v102, v99
	v_max_u32_e32 v94, v81, v97
	v_min_u32_e32 v81, v81, v97
	v_max_u32_e32 v97, v95, v96
	v_min_u32_e32 v95, v95, v96
	v_max_u32_e32 v96, v106, v90
	v_min_u32_e32 v90, v106, v90
	v_max_u32_e32 v106, v84, v82
	v_min_u32_e32 v82, v84, v82
	v_max_u32_e32 v84, v78, v80
	v_min_u32_e32 v78, v78, v80
	v_max_u32_e32 v80, v93, v83
	v_min_u32_e32 v83, v93, v83
	v_max_u32_e32 v93, v91, v85
	v_min_u32_e32 v85, v91, v85
	v_max_u32_e32 v91, v92, v79
	v_min_u32_e32 v79, v92, v79
	v_max_u32_e32 v102, v3, v105
	v_min_u32_e32 v3, v3, v105
	v_max_u32_e32 v105, v103, v104
	v_min_u32_e32 v103, v103, v104
	v_max_u32_e32 v104, v115, v98
	v_min_u32_e32 v98, v115, v98
	v_max_u32_e32 v115, v88, v86
	v_min_u32_e32 v86, v88, v86
	v_max_u32_e32 v88, v0, v2
	v_min_u32_e32 v0, v0, v2
	v_max_u32_e32 v2, v101, v87
	v_min_u32_e32 v87, v101, v87
	v_max_u32_e32 v101, v99, v89
	v_min_u32_e32 v89, v99, v89
	v_max_u32_e32 v99, v100, v1
	v_min_u32_e32 v1, v100, v1
	v_max_u32_e32 v92, v94, v78
	v_min_u32_e32 v78, v94, v78
	v_max_u32_e32 v94, v81, v84
	v_min_u32_e32 v81, v81, v84
	v_max_u32_e32 v84, v97, v83
	v_min_u32_e32 v83, v97, v83
	v_max_u32_e32 v97, v95, v80
	v_min_u32_e32 v80, v95, v80
	v_max_u32_e32 v95, v96, v85
	v_min_u32_e32 v85, v96, v85
	v_max_u32_e32 v96, v90, v93
	v_min_u32_e32 v90, v90, v93
	v_max_u32_e32 v93, v106, v79
	v_min_u32_e32 v79, v106, v79
	v_max_u32_e32 v106, v82, v91
	v_min_u32_e32 v82, v82, v91
	v_max_u32_e32 v100, v102, v0
	v_min_u32_e32 v0, v102, v0
	v_max_u32_e32 v102, v3, v88
	v_min_u32_e32 v3, v3, v88
	v_max_u32_e32 v88, v105, v87
	v_min_u32_e32 v87, v105, v87
	v_max_u32_e32 v105, v103, v2
	v_min_u32_e32 v2, v103, v2
	v_max_u32_e32 v103, v104, v89
	v_min_u32_e32 v89, v104, v89
	v_max_u32_e32 v104, v98, v101
	v_min_u32_e32 v98, v98, v101
	v_max_u32_e32 v101, v115, v1
	v_min_u32_e32 v1, v115, v1
	v_max_u32_e32 v115, v86, v99
	v_min_u32_e32 v86, v86, v99
	v_max_u32_e32 v91, v92, v95
	v_min_u32_e32 v92, v92, v95
	v_max_u32_e32 v95, v94, v96
; #define CE_DESC(a, b) do { const unsigned _mx = (a) > (b) ? (a) : (b), _mn = (a) > (b) ? (b) : (a); (a) = _mx; (b) = _mn; } while (0)
; __device__ __forceinline__ void sort16_desc(unsigned (&k)[16]) {
; #pragma unroll
;     for (int size = 2; size <= 16; size <<= 1)
; #pragma unroll
;         for (int stride = size >> 1; stride > 0; stride >>= 1)
; #pragma unroll
;             for (int i = 0; i < 16; ++i) { const int j = i ^ stride;
;                 if (j > i) { if ((i & size) == 0) CE_DESC(k[i], k[j]); else CE_DESC(k[j], k[i]); } }
; }
; __device__ __forceinline__ void merge16(unsigned (&a)[16], const unsigned (&b)[16]) {
; #pragma unroll
;     for (int i = 0; i < 16; ++i) a[i] = a[i] > b[15 - i] ? a[i] : b[15 - i];
; #pragma unroll
;     for (int stride = 8; stride > 0; stride >>= 1)
; #pragma unroll
;         for (int i = 0; i < 16; ++i) { const int j = i ^ stride; if (j > i) CE_DESC(a[i], a[j]); }
; }
; __device__ __forceinline__ void peer_tile(const Args& A, LAS unsigned char* lds, int tile) {
;     ...
;                 for (int msk = 16; msk <= 32; msk <<= 1) {
; #pragma unroll
;                     for (int i = 0; i < 16; ++i) k1[i] = (unsigned)__shfl_xor((int)k0[i], msk);
;                     merge16(k0, k1); }
	v_min_u32_e32 v94, v94, v96
	v_max_u32_e32 v96, v84, v93
	v_min_u32_e32 v84, v84, v93
	v_max_u32_e32 v93, v97, v106
	v_min_u32_e32 v97, v97, v106
	v_max_u32_e32 v106, v78, v85
	v_min_u32_e32 v78, v78, v85
	v_max_u32_e32 v85, v81, v90
	v_min_u32_e32 v81, v81, v90
	v_max_u32_e32 v90, v83, v79
	v_min_u32_e32 v79, v83, v79
	v_max_u32_e32 v83, v80, v82
	v_min_u32_e32 v80, v80, v82
	v_max_u32_e32 v99, v100, v103
	v_min_u32_e32 v100, v100, v103
	v_max_u32_e32 v103, v102, v104
	v_min_u32_e32 v102, v102, v104
	v_max_u32_e32 v104, v88, v101
	v_min_u32_e32 v88, v88, v101
	v_max_u32_e32 v101, v105, v115
	v_min_u32_e32 v105, v105, v115
	v_max_u32_e32 v115, v0, v89
	v_min_u32_e32 v0, v0, v89
	v_max_u32_e32 v89, v3, v98
	v_min_u32_e32 v3, v3, v98
	v_max_u32_e32 v98, v87, v1
	v_min_u32_e32 v1, v87, v1
	v_max_u32_e32 v87, v2, v86
	v_min_u32_e32 v2, v2, v86
	v_max_u32_e32 v82, v91, v96
	v_min_u32_e32 v91, v91, v96
	v_max_u32_e32 v96, v95, v93
	v_min_u32_e32 v93, v95, v93
	v_max_u32_e32 v95, v92, v84
	v_min_u32_e32 v84, v92, v84
	v_max_u32_e32 v92, v94, v97
	v_min_u32_e32 v94, v94, v97
	v_max_u32_e32 v97, v106, v90
	v_min_u32_e32 v90, v106, v90
	v_max_u32_e32 v106, v85, v83
	v_min_u32_e32 v83, v85, v83
	v_max_u32_e32 v85, v78, v79
	v_min_u32_e32 v78, v78, v79
	v_max_u32_e32 v79, v81, v80
	v_min_u32_e32 v80, v81, v80
	v_max_u32_e32 v86, v99, v104
	v_min_u32_e32 v99, v99, v104
	v_max_u32_e32 v104, v103, v101
	v_min_u32_e32 v101, v103, v101
	v_max_u32_e32 v103, v100, v88
	v_min_u32_e32 v88, v100, v88
	v_max_u32_e32 v100, v102, v105
	v_min_u32_e32 v102, v102, v105
	v_max_u32_e32 v105, v115, v98
	v_min_u32_e32 v98, v115, v98
	v_max_u32_e32 v115, v89, v87
	v_min_u32_e32 v87, v89, v87
	v_max_u32_e32 v89, v0, v1
	v_min_u32_e32 v0, v0, v1
	v_max_u32_e32 v1, v3, v2
	v_min_u32_e32 v2, v3, v2
	v_min_u32_e32 v81, v82, v96
	v_min_u32_e32 v107, v91, v93
	v_min_u32_e32 v108, v95, v92
	v_min_u32_e32 v109, v84, v94
	v_min_u32_e32 v110, v97, v106
	v_min_u32_e32 v111, v90, v83
	v_min_u32_e32 v112, v85, v79
	v_min_u32_e32 v114, v78, v80
	v_min_u32_e32 v3, v86, v104
	v_min_u32_e32 v116, v99, v101
	v_min_u32_e32 v117, v103, v100
	v_min_u32_e32 v118, v88, v102
	v_min_u32_e32 v119, v105, v115
	v_min_u32_e32 v120, v98, v87
	v_min_u32_e32 v121, v89, v1
	v_min_u32_e32 v122, v0, v2
	v_max3_u32 v82, v82, v96, v122
	v_max3_u32 v0, v81, v0, v2
	v_max3_u32 v2, v91, v93, v121
	v_max3_u32 v1, v107, v89, v1
	v_max3_u32 v81, v95, v92, v120
	v_max3_u32 v87, v108, v98, v87
	v_max3_u32 v84, v84, v94, v119
	v_max3_u32 v89, v109, v105, v115
	v_max3_u32 v91, v97, v106, v118
	v_max3_u32 v88, v110, v88, v102
	v_max3_u32 v83, v90, v83, v117
	v_max3_u32 v90, v111, v103, v100
	v_max3_u32 v79, v85, v79, v116
	v_max3_u32 v85, v112, v99, v101
	v_max3_u32 v3, v78, v80, v3
	v_max3_u32 v78, v114, v86, v104
	v_max_u32_e32 v80, v82, v91
	v_min_u32_e32 v82, v82, v91
	v_max_u32_e32 v86, v0, v88
	v_min_u32_e32 v0, v0, v88
	v_max_u32_e32 v88, v2, v83
	v_min_u32_e32 v2, v2, v83
	v_max_u32_e32 v83, v1, v90
	v_min_u32_e32 v1, v1, v90
	v_max_u32_e32 v90, v81, v79
	v_min_u32_e32 v79, v81, v79
	v_max_u32_e32 v81, v87, v85
	v_min_u32_e32 v85, v87, v85
	v_max_u32_e32 v87, v84, v3
	v_min_u32_e32 v3, v84, v3
	v_max_u32_e32 v84, v89, v78
	v_min_u32_e32 v78, v89, v78
	v_max_u32_e32 v89, v80, v90
	v_min_u32_e32 v80, v80, v90
	v_max_u32_e32 v90, v86, v81
	v_min_u32_e32 v81, v86, v81
	v_max_u32_e32 v86, v88, v87
	v_min_u32_e32 v87, v88, v87
	v_max_u32_e32 v88, v83, v84
	v_min_u32_e32 v83, v83, v84
	v_max_u32_e32 v84, v82, v79
	v_min_u32_e32 v79, v82, v79
	v_max_u32_e32 v82, v0, v85
	v_min_u32_e32 v0, v0, v85
	v_max_u32_e32 v85, v2, v3
	v_min_u32_e32 v2, v2, v3
	v_max_u32_e32 v3, v1, v78
	v_min_u32_e32 v1, v1, v78
	v_max_u32_e32 v78, v89, v86
	v_min_u32_e32 v86, v89, v86
	v_max_u32_e32 v89, v90, v88
	v_min_u32_e32 v88, v90, v88
	v_max_u32_e32 v90, v80, v87
	v_min_u32_e32 v80, v80, v87
	v_max_u32_e32 v87, v81, v83
	v_min_u32_e32 v81, v81, v83
	v_max_u32_e32 v83, v84, v85
	v_min_u32_e32 v84, v84, v85
	v_max_u32_e32 v85, v82, v3
	v_min_u32_e32 v3, v82, v3
	v_max_u32_e32 v82, v79, v2
	v_min_u32_e32 v2, v79, v2
	v_max_u32_e32 v79, v0, v1
	v_min_u32_e32 v0, v0, v1
	v_max_u32_e32 v1, v78, v89
	v_min_u32_e32 v78, v78, v89
	v_max_u32_e32 v89, v86, v88
	v_min_u32_e32 v86, v86, v88
	v_max_u32_e32 v88, v90, v87
	v_min_u32_e32 v87, v90, v87
	v_max_u32_e32 v90, v80, v81
	v_min_u32_e32 v80, v80, v81
	v_max_u32_e32 v81, v83, v85
	v_min_u32_e32 v83, v83, v85
	v_max_u32_e32 v85, v84, v3
	v_min_u32_e32 v3, v84, v3
	v_max_u32_e32 v84, v82, v79
	v_min_u32_e32 v79, v82, v79
	v_max_u32_e32 v82, v2, v0
	v_min_u32_e32 v0, v2, v0
	ds_bpermute_b32 v2, v27, v1
	ds_bpermute_b32 v91, v27, v78
	ds_bpermute_b32 v92, v27, v89
	ds_bpermute_b32 v93, v27, v86
	ds_bpermute_b32 v94, v27, v88
	ds_bpermute_b32 v95, v27, v87
	ds_bpermute_b32 v96, v27, v90
	ds_bpermute_b32 v97, v27, v80
	ds_bpermute_b32 v98, v27, v81
	ds_bpermute_b32 v99, v27, v83
	ds_bpermute_b32 v100, v27, v85
	ds_bpermute_b32 v101, v27, v0
	ds_bpermute_b32 v102, v27, v82
	ds_bpermute_b32 v103, v27, v79
	ds_bpermute_b32 v104, v27, v84
	ds_bpermute_b32 v105, v27, v3
	s_waitcnt lgkmcnt(4)
	v_max_u32_e32 v1, v1, v101
	s_waitcnt lgkmcnt(3)
	v_max_u32_e32 v78, v78, v102
	s_waitcnt lgkmcnt(2)
	v_max_u32_e32 v89, v89, v103
	s_waitcnt lgkmcnt(1)
	v_max_u32_e32 v86, v86, v104
	s_waitcnt lgkmcnt(0)
; __device__ __forceinline__ void peer_tile(const Args& A, LAS unsigned char* lds, int tile) {
;     ...
;                 { const bf16_t* sp = QRY + m * 2048 + hp * 128 + 32 * g;
;                   const u32x4 s0 = *(const u32x4*)sp, s1 = *(const u32x4*)(sp + 8), s2 = *(const u32x4*)(sp + 16), s3 = *(const u32x4*)(sp + 24);
;     ...
;                 sort16_desc(k0); sort16_desc(k1); merge16(k0, k1);
; #pragma unroll
;                 for (int msk = 16; msk <= 32; msk <<= 1) {
; #pragma unroll
;                     for (int i = 0; i < 16; ++i) k1[i] = (unsigned)__shfl_xor((int)k0[i], msk);
;                     merge16(k0, k1); }
	v_max_u32_e32 v88, v88, v105
	v_max_u32_e32 v87, v87, v100
	v_max_u32_e32 v90, v90, v99
	v_max_u32_e32 v80, v80, v98
	v_max_u32_e32 v81, v81, v97
	v_max_u32_e32 v83, v83, v96
	v_max_u32_e32 v85, v85, v95
	v_max_u32_e32 v3, v3, v94
	v_max_u32_e32 v84, v84, v93
	v_max_u32_e32 v79, v79, v92
	v_max_u32_e32 v82, v82, v91
	v_max_u32_e32 v0, v0, v2
	v_max_u32_e32 v2, v1, v81
	v_min_u32_e32 v1, v1, v81
	v_max_u32_e32 v81, v78, v83
	v_min_u32_e32 v78, v78, v83
	v_max_u32_e32 v83, v89, v85
	v_min_u32_e32 v85, v89, v85
	v_max_u32_e32 v89, v86, v3
	v_min_u32_e32 v3, v86, v3
	v_max_u32_e32 v86, v88, v84
	v_min_u32_e32 v84, v88, v84
	v_max_u32_e32 v88, v87, v79
	v_min_u32_e32 v79, v87, v79
	v_max_u32_e32 v87, v90, v82
	v_min_u32_e32 v82, v90, v82
	v_max_u32_e32 v90, v80, v0
	v_min_u32_e32 v0, v80, v0
	v_max_u32_e32 v80, v2, v86
	v_min_u32_e32 v2, v2, v86
	v_max_u32_e32 v86, v81, v88
	v_min_u32_e32 v81, v81, v88
	v_max_u32_e32 v88, v83, v87
	v_min_u32_e32 v83, v83, v87
	v_max_u32_e32 v87, v89, v90
	v_min_u32_e32 v89, v89, v90
	v_max_u32_e32 v90, v1, v84
	v_min_u32_e32 v1, v1, v84
	v_max_u32_e32 v84, v78, v79
	v_min_u32_e32 v78, v78, v79
	v_max_u32_e32 v79, v85, v82
	v_min_u32_e32 v82, v85, v82
	v_max_u32_e32 v85, v3, v0
	v_min_u32_e32 v0, v3, v0
	v_max_u32_e32 v3, v80, v88
	v_min_u32_e32 v80, v80, v88
	v_max_u32_e32 v88, v86, v87
	v_min_u32_e32 v86, v86, v87
	v_max_u32_e32 v87, v2, v83
	v_min_u32_e32 v2, v2, v83
	v_max_u32_e32 v83, v81, v89
	v_min_u32_e32 v81, v81, v89
	v_max_u32_e32 v89, v90, v79
	v_min_u32_e32 v79, v90, v79
	v_max_u32_e32 v90, v84, v85
	v_min_u32_e32 v84, v84, v85
	v_max_u32_e32 v85, v1, v82
	v_min_u32_e32 v1, v1, v82
	v_max_u32_e32 v82, v78, v0
	v_min_u32_e32 v0, v78, v0
	v_max_u32_e32 v78, v3, v88
	v_min_u32_e32 v3, v3, v88
	v_max_u32_e32 v88, v80, v86
	v_min_u32_e32 v80, v80, v86
	v_max_u32_e32 v86, v87, v83
	v_min_u32_e32 v83, v87, v83
	v_max_u32_e32 v87, v2, v81
	v_min_u32_e32 v2, v2, v81
	v_max_u32_e32 v81, v89, v90
	v_min_u32_e32 v89, v89, v90
	v_max_u32_e32 v90, v79, v84
	v_min_u32_e32 v79, v79, v84
	v_max_u32_e32 v84, v85, v82
	v_min_u32_e32 v82, v85, v82
	v_max_u32_e32 v85, v1, v0
	v_min_u32_e32 v0, v1, v0
	ds_bpermute_b32 v94, v29, v0
	ds_bpermute_b32 v1, v29, v78
	ds_bpermute_b32 v91, v29, v3
	ds_bpermute_b32 v92, v29, v88
	ds_bpermute_b32 v93, v29, v80
	s_waitcnt lgkmcnt(4)
	v_max_u32_e32 v78, v78, v94
	global_load_dwordx4 v[94:97], v[4:5], off offset:1040
	global_load_dwordx4 v[98:101], v[4:5], off offset:1024
	ds_bpermute_b32 v102, v29, v86
	ds_bpermute_b32 v103, v29, v83
	ds_bpermute_b32 v104, v29, v87
	ds_bpermute_b32 v105, v29, v2
	ds_bpermute_b32 v106, v29, v81
	ds_bpermute_b32 v107, v29, v89
	ds_bpermute_b32 v108, v29, v90
	ds_bpermute_b32 v109, v29, v79
	ds_bpermute_b32 v110, v29, v84
	ds_bpermute_b32 v111, v29, v85
	ds_bpermute_b32 v112, v29, v82
	s_waitcnt lgkmcnt(4)
	v_max_u32_e32 v83, v83, v108
	s_waitcnt lgkmcnt(3)
	v_max_u32_e32 v86, v86, v109
	s_waitcnt lgkmcnt(2)
	v_max_u32_e32 v80, v80, v110
	s_waitcnt lgkmcnt(1)
	v_max_u32_e32 v3, v3, v111
	s_waitcnt lgkmcnt(0)
	v_max_u32_e32 v88, v88, v112
	v_max_u32_e32 v87, v87, v107
	v_max_u32_e32 v2, v2, v106
	v_max_u32_e32 v81, v81, v105
	v_max_u32_e32 v89, v89, v104
	v_max_u32_e32 v90, v90, v103
	v_max_u32_e32 v79, v79, v102
	v_max_u32_e32 v84, v84, v93
	v_max_u32_e32 v82, v82, v92
	v_max_u32_e32 v85, v85, v91
	v_max_u32_e32 v0, v0, v1
	v_max_u32_e32 v1, v78, v81
	v_min_u32_e32 v78, v78, v81
	v_max_u32_e32 v81, v3, v89
	v_min_u32_e32 v3, v3, v89
	v_max_u32_e32 v89, v88, v90
	v_min_u32_e32 v88, v88, v90
	v_max_u32_e32 v90, v80, v79
	v_min_u32_e32 v79, v80, v79
	v_max_u32_e32 v80, v86, v84
	v_min_u32_e32 v84, v86, v84
	v_max_u32_e32 v86, v83, v82
	v_min_u32_e32 v82, v83, v82
	v_max_u32_e32 v83, v87, v85
	v_min_u32_e32 v85, v87, v85
	v_max_u32_e32 v87, v2, v0
	v_min_u32_e32 v0, v2, v0
	v_max_u32_e32 v2, v1, v80
	v_min_u32_e32 v1, v1, v80
	v_max_u32_e32 v80, v81, v86
	v_min_u32_e32 v81, v81, v86
	v_max_u32_e32 v86, v89, v83
	v_min_u32_e32 v83, v89, v83
	v_max_u32_e32 v89, v90, v87
	v_min_u32_e32 v87, v90, v87
	v_max_u32_e32 v90, v78, v84
	v_min_u32_e32 v78, v78, v84
	v_max_u32_e32 v84, v3, v82
	v_min_u32_e32 v3, v3, v82
	v_max_u32_e32 v82, v88, v85
	v_min_u32_e32 v85, v88, v85
	v_max_u32_e32 v88, v79, v0
	v_min_u32_e32 v0, v79, v0
	v_max_u32_e32 v79, v2, v86
	v_min_u32_e32 v2, v2, v86
	v_max_u32_e32 v86, v80, v89
	v_min_u32_e32 v80, v80, v89
	v_max_u32_e32 v102, v1, v83
	v_min_u32_e32 v1, v1, v83
	v_max_u32_e32 v83, v81, v87
	v_min_u32_e32 v81, v81, v87
	v_max_u32_e32 v103, v90, v82
	v_min_u32_e32 v82, v90, v82
	v_max_u32_e32 v104, v84, v88
	v_min_u32_e32 v105, v84, v88
	v_max_u32_e32 v106, v78, v85
	v_min_u32_e32 v78, v78, v85
	v_max_u32_e32 v107, v3, v0
	v_min_u32_e32 v0, v3, v0
	v_max_u32_e32 v93, v79, v86
	v_min_u32_e32 v92, v79, v86
	v_max_u32_e32 v91, v2, v80
	v_min_u32_e32 v90, v2, v80
	v_max_u32_e32 v89, v102, v83
	v_min_u32_e32 v88, v102, v83
	v_max_u32_e32 v87, v1, v81
	v_min_u32_e32 v86, v1, v81
	v_max_u32_e32 v85, v103, v104
	v_min_u32_e32 v84, v103, v104
	v_max_u32_e32 v83, v82, v105
	v_min_u32_e32 v82, v82, v105
	v_max_u32_e32 v79, v78, v0
	v_min_u32_e32 v78, v78, v0
	global_load_dwordx4 v[0:3], v[4:5], off offset:1072
	global_load_dwordx4 v[102:105], v[4:5], off offset:1056
	v_max_u32_e32 v81, v106, v107
	v_min_u32_e32 v80, v106, v107
	s_waitcnt vmcnt(2)
; __device__ __forceinline__ unsigned f2key(float f) { const unsigned u = __float_as_uint(f); return (u & 0x80000000u) ? ~u : (u | 0x80000000u); }
; __device__ __forceinline__ void peer_tile(const Args& A, LAS unsigned char* lds, int tile) {
;     ...
;                   for (int i = 0; i < 16; ++i) {
;                       const float lo = (float)__builtin_bit_cast(_Float16, (unsigned short)(sw[i] & 0xffffu)), hi = (float)__builtin_bit_cast(_Float16, (unsigned short)(sw[i] >> 16));
;                       const unsigned klo = (f2key(lo) & ~127u) | (unsigned)(127 - (32 * g + 2 * i)), khi = (f2key(hi) & ~127u) | (unsigned)(127 - (32 * g + 2 * i + 1));
;                       if (i < 8) { k0[2 * i] = klo; k0[2 * i + 1] = khi; } else { k1[2 * (i - 8)] = klo; k1[2 * (i - 8) + 1] = khi; } } }
;     ...
;             for (int p = 0; p < 2; ++p)
; #pragma unroll
;                 for (int i = 0; i < 16; ++i) L2[p][i] = (g & 2) ? ((g & 1) ? LA[3][p][i] : LA[2][p][i]) : ((g & 1) ? LA[1][p][i] : LA[0][p][i]);
	v_cvt_f32_f16_sdwa v106, v98 dst_sel:DWORD dst_unused:UNUSED_PAD src0_sel:WORD_1
	v_cvt_f32_f16_e32 v98, v98
	v_cndmask_b32_e64 v34, v66, v34, s[0:1]
	v_cndmask_b32_e64 v33, v65, v33, s[0:1]
	v_not_b32_e32 v107, v106
	v_or_b32_e32 v108, 0x80000000, v106
	v_cmp_gt_i32_e32 vcc, 0, v106
	v_cndmask_b32_e64 v32, v64, v32, s[0:1]
	v_cndmask_b32_e64 v31, v63, v31, s[0:1]
	v_cndmask_b32_e32 v106, v108, v107, vcc
	v_not_b32_e32 v107, v98
	v_or_b32_e32 v108, 0x80000000, v98
	v_cmp_gt_i32_e32 vcc, 0, v98
	v_and_b32_e32 v106, 0xffffff80, v106
	v_sub_u32_e32 v106, v106, v15
	v_cndmask_b32_e32 v98, v108, v107, vcc
	v_cvt_f32_f16_sdwa v107, v99 dst_sel:DWORD dst_unused:UNUSED_PAD src0_sel:WORD_1
	v_cvt_f32_f16_e32 v99, v99
	v_and_b32_e32 v98, 0xffffff80, v98
	v_sub_u32_e32 v98, v98, v15
	v_not_b32_e32 v108, v107
	v_or_b32_e32 v109, 0x80000000, v107
	v_cmp_gt_i32_e32 vcc, 0, v107
	v_add_u32_e32 v106, 0x7e, v106
	v_add_u32_e32 v98, 0x7f, v98
	v_cndmask_b32_e32 v107, v109, v108, vcc
	v_not_b32_e32 v108, v99
	v_or_b32_e32 v109, 0x80000000, v99
	v_cmp_gt_i32_e32 vcc, 0, v99
	v_and_b32_e32 v107, 0xffffff80, v107
	v_sub_u32_e32 v107, v107, v14
	v_cndmask_b32_e32 v99, v109, v108, vcc
	v_cvt_f32_f16_sdwa v108, v100 dst_sel:DWORD dst_unused:UNUSED_PAD src0_sel:WORD_1
	v_cvt_f32_f16_e32 v100, v100
	v_and_b32_e32 v99, 0xffffff80, v99
	v_sub_u32_e32 v99, v99, v14
	v_not_b32_e32 v109, v108
	v_or_b32_e32 v110, 0x80000000, v108
	v_cmp_gt_i32_e32 vcc, 0, v108
	v_add_u32_e32 v107, 0x7e, v107
	v_add_u32_e32 v99, 0x7f, v99
	v_cndmask_b32_e32 v108, v110, v109, vcc
	v_not_b32_e32 v109, v100
	v_or_b32_e32 v110, 0x80000000, v100
	v_cmp_gt_i32_e32 vcc, 0, v100
	v_and_b32_e32 v108, 0xffffff80, v108
	v_sub_u32_e32 v108, v108, v12
	v_cndmask_b32_e32 v100, v110, v109, vcc
	v_cvt_f32_f16_sdwa v109, v101 dst_sel:DWORD dst_unused:UNUSED_PAD src0_sel:WORD_1
	v_cvt_f32_f16_e32 v101, v101
	v_and_b32_e32 v100, 0xffffff80, v100
	v_sub_u32_e32 v100, v100, v12
	v_not_b32_e32 v110, v109
	v_or_b32_e32 v111, 0x80000000, v109
	v_cmp_gt_i32_e32 vcc, 0, v109
	v_add_u32_e32 v108, 0x7e, v108
	v_add_u32_e32 v100, 0x7f, v100
	v_cndmask_b32_e32 v109, v111, v110, vcc
	v_not_b32_e32 v110, v101
	v_or_b32_e32 v111, 0x80000000, v101
	v_cmp_gt_i32_e32 vcc, 0, v101
	v_and_b32_e32 v109, 0xffffff80, v109
	v_sub_u32_e32 v109, v109, v10
	v_cndmask_b32_e32 v101, v111, v110, vcc
	v_cvt_f32_f16_sdwa v110, v94 dst_sel:DWORD dst_unused:UNUSED_PAD src0_sel:WORD_1
	v_cvt_f32_f16_e32 v94, v94
	v_and_b32_e32 v101, 0xffffff80, v101
	v_sub_u32_e32 v101, v101, v10
	v_not_b32_e32 v111, v110
	v_or_b32_e32 v112, 0x80000000, v110
	v_cmp_gt_i32_e32 vcc, 0, v110
	v_add_u32_e32 v109, 0x7e, v109
	v_add_u32_e32 v101, 0x7f, v101
	v_cndmask_b32_e32 v110, v112, v111, vcc
	v_not_b32_e32 v111, v94
	v_or_b32_e32 v112, 0x80000000, v94
	v_cmp_gt_i32_e32 vcc, 0, v94
	v_and_b32_e32 v110, 0xffffff80, v110
	v_sub_u32_e32 v110, v110, v8
	v_cndmask_b32_e32 v94, v112, v111, vcc
	v_cvt_f32_f16_sdwa v111, v95 dst_sel:DWORD dst_unused:UNUSED_PAD src0_sel:WORD_1
	v_cvt_f32_f16_e32 v95, v95
	v_and_b32_e32 v94, 0xffffff80, v94
	v_sub_u32_e32 v94, v94, v8
	v_not_b32_e32 v112, v111
	v_or_b32_e32 v114, 0x80000000, v111
	v_cmp_gt_i32_e32 vcc, 0, v111
	v_add_u32_e32 v110, 0x7e, v110
	v_add_u32_e32 v94, 0x7f, v94
	v_cndmask_b32_e32 v111, v114, v112, vcc
	v_not_b32_e32 v112, v95
	v_or_b32_e32 v114, 0x80000000, v95
	v_cmp_gt_i32_e32 vcc, 0, v95
	v_and_b32_e32 v111, 0xffffff80, v111
	v_sub_u32_e32 v111, v111, v16
	v_cndmask_b32_e32 v95, v114, v112, vcc
	v_cvt_f32_f16_sdwa v112, v96 dst_sel:DWORD dst_unused:UNUSED_PAD src0_sel:WORD_1
	v_cvt_f32_f16_e32 v96, v96
	v_and_b32_e32 v95, 0xffffff80, v95
	v_sub_u32_e32 v95, v95, v16
	v_not_b32_e32 v114, v112
	v_or_b32_e32 v115, 0x80000000, v112
	v_cmp_gt_i32_e32 vcc, 0, v112
	v_add_u32_e32 v111, 0x7e, v111
	v_add_u32_e32 v95, 0x7f, v95
	v_cndmask_b32_e32 v112, v115, v114, vcc
	v_not_b32_e32 v114, v96
	v_or_b32_e32 v115, 0x80000000, v96
	v_cmp_gt_i32_e32 vcc, 0, v96
	v_and_b32_e32 v112, 0xffffff80, v112
	v_sub_u32_e32 v112, v112, v17
	v_cndmask_b32_e32 v96, v115, v114, vcc
	v_cvt_f32_f16_sdwa v114, v97 dst_sel:DWORD dst_unused:UNUSED_PAD src0_sel:WORD_1
	v_cvt_f32_f16_e32 v97, v97
	v_and_b32_e32 v96, 0xffffff80, v96
	v_sub_u32_e32 v96, v96, v17
	v_not_b32_e32 v115, v114
	v_or_b32_e32 v116, 0x80000000, v114
	v_cmp_gt_i32_e32 vcc, 0, v114
	v_add_u32_e32 v112, 0x7e, v112
	v_add_u32_e32 v96, 0x7f, v96
	v_cndmask_b32_e32 v114, v116, v115, vcc
	v_not_b32_e32 v115, v97
	v_or_b32_e32 v116, 0x80000000, v97
	v_cmp_gt_i32_e32 vcc, 0, v97
	v_and_b32_e32 v114, 0xffffff80, v114
	v_sub_u32_e32 v114, v114, v18
	v_cndmask_b32_e32 v97, v116, v115, vcc
	s_waitcnt vmcnt(0)
; __device__ __forceinline__ unsigned f2key(float f) { const unsigned u = __float_as_uint(f); return (u & 0x80000000u) ? ~u : (u | 0x80000000u); }
; #define CE_DESC(a, b) do { const unsigned _mx = (a) > (b) ? (a) : (b), _mn = (a) > (b) ? (b) : (a); (a) = _mx; (b) = _mn; } while (0)
; __device__ __forceinline__ void sort16_desc(unsigned (&k)[16]) {
; #pragma unroll
;     for (int size = 2; size <= 16; size <<= 1)
; #pragma unroll
;         for (int stride = size >> 1; stride > 0; stride >>= 1)
; #pragma unroll
;             for (int i = 0; i < 16; ++i) { const int j = i ^ stride;
;                 if (j > i) { if ((i & size) == 0) CE_DESC(k[i], k[j]); else CE_DESC(k[j], k[i]); } }
; }
; __device__ __forceinline__ void peer_tile(const Args& A, LAS unsigned char* lds, int tile) {
;     ...
;                   for (int i = 0; i < 16; ++i) {
;                       const float lo = (float)__builtin_bit_cast(_Float16, (unsigned short)(sw[i] & 0xffffu)), hi = (float)__builtin_bit_cast(_Float16, (unsigned short)(sw[i] >> 16));
;                       const unsigned klo = (f2key(lo) & ~127u) | (unsigned)(127 - (32 * g + 2 * i)), khi = (f2key(hi) & ~127u) | (unsigned)(127 - (32 * g + 2 * i + 1));
;                       if (i < 8) { k0[2 * i] = klo; k0[2 * i + 1] = khi; } else { k1[2 * (i - 8)] = klo; k1[2 * (i - 8) + 1] = khi; } } }
	v_cvt_f32_f16_sdwa v115, v102 dst_sel:DWORD dst_unused:UNUSED_PAD src0_sel:WORD_1
	v_cvt_f32_f16_e32 v102, v102
	v_and_b32_e32 v97, 0xffffff80, v97
	v_sub_u32_e32 v97, v97, v18
	v_not_b32_e32 v116, v115
	v_or_b32_e32 v117, 0x80000000, v115
	v_cmp_gt_i32_e32 vcc, 0, v115
	v_add_u32_e32 v114, 0x7e, v114
	v_add_u32_e32 v97, 0x7f, v97
	v_cndmask_b32_e32 v115, v117, v116, vcc
	v_not_b32_e32 v116, v102
	v_or_b32_e32 v117, 0x80000000, v102
	v_cmp_gt_i32_e32 vcc, 0, v102
	v_and_b32_e32 v115, 0xffffff80, v115
	v_sub_u32_e32 v115, v115, v20
	v_cndmask_b32_e32 v102, v117, v116, vcc
	v_cvt_f32_f16_sdwa v116, v103 dst_sel:DWORD dst_unused:UNUSED_PAD src0_sel:WORD_1
	v_cvt_f32_f16_e32 v103, v103
	v_and_b32_e32 v102, 0xffffff80, v102
	v_sub_u32_e32 v102, v102, v20
	v_not_b32_e32 v117, v116
	v_or_b32_e32 v118, 0x80000000, v116
	v_cmp_gt_i32_e32 vcc, 0, v116
	v_add_u32_e32 v115, 0x7e, v115
	v_add_u32_e32 v102, 0x7f, v102
	v_cndmask_b32_e32 v116, v118, v117, vcc
	v_not_b32_e32 v117, v103
	v_or_b32_e32 v118, 0x80000000, v103
	v_cmp_gt_i32_e32 vcc, 0, v103
	v_and_b32_e32 v116, 0xffffff80, v116
	v_sub_u32_e32 v116, v116, v21
	v_cndmask_b32_e32 v103, v118, v117, vcc
	v_cvt_f32_f16_sdwa v117, v104 dst_sel:DWORD dst_unused:UNUSED_PAD src0_sel:WORD_1
	v_cvt_f32_f16_e32 v104, v104
	v_and_b32_e32 v103, 0xffffff80, v103
	v_sub_u32_e32 v103, v103, v21
	v_not_b32_e32 v118, v117
	v_or_b32_e32 v119, 0x80000000, v117
	v_cmp_gt_i32_e32 vcc, 0, v117
	v_add_u32_e32 v116, 0x7e, v116
	v_add_u32_e32 v103, 0x7f, v103
	v_cndmask_b32_e32 v117, v119, v118, vcc
	v_not_b32_e32 v118, v104
	v_or_b32_e32 v119, 0x80000000, v104
	v_cmp_gt_i32_e32 vcc, 0, v104
	v_and_b32_e32 v117, 0xffffff80, v117
	v_sub_u32_e32 v117, v117, v22
	v_cndmask_b32_e32 v104, v119, v118, vcc
	v_cvt_f32_f16_sdwa v118, v105 dst_sel:DWORD dst_unused:UNUSED_PAD src0_sel:WORD_1
	v_cvt_f32_f16_e32 v105, v105
	v_and_b32_e32 v104, 0xffffff80, v104
	v_sub_u32_e32 v104, v104, v22
	v_not_b32_e32 v119, v118
	v_or_b32_e32 v120, 0x80000000, v118
	v_cmp_gt_i32_e32 vcc, 0, v118
	v_add_u32_e32 v117, 0x7e, v117
	v_add_u32_e32 v104, 0x7f, v104
	v_cndmask_b32_e32 v118, v120, v119, vcc
	v_not_b32_e32 v119, v105
	v_or_b32_e32 v120, 0x80000000, v105
	v_cmp_gt_i32_e32 vcc, 0, v105
	v_and_b32_e32 v118, 0xffffff80, v118
	v_sub_u32_e32 v118, v118, v23
	v_cndmask_b32_e32 v105, v120, v119, vcc
	v_cvt_f32_f16_sdwa v119, v0 dst_sel:DWORD dst_unused:UNUSED_PAD src0_sel:WORD_1
	v_cvt_f32_f16_e32 v0, v0
	v_and_b32_e32 v105, 0xffffff80, v105
	v_sub_u32_e32 v105, v105, v23
	v_not_b32_e32 v120, v119
	v_or_b32_e32 v121, 0x80000000, v119
	v_cmp_gt_i32_e32 vcc, 0, v119
	v_add_u32_e32 v118, 0x7e, v118
	v_add_u32_e32 v105, 0x7f, v105
	v_cndmask_b32_e32 v119, v121, v120, vcc
	v_not_b32_e32 v120, v0
	v_or_b32_e32 v121, 0x80000000, v0
	v_cmp_gt_i32_e32 vcc, 0, v0
	v_and_b32_e32 v119, 0xffffff80, v119
	v_sub_u32_e32 v119, v119, v24
	v_cndmask_b32_e32 v0, v121, v120, vcc
	v_cvt_f32_f16_sdwa v120, v1 dst_sel:DWORD dst_unused:UNUSED_PAD src0_sel:WORD_1
	v_cvt_f32_f16_e32 v1, v1
	v_and_b32_e32 v0, 0xffffff80, v0
	v_sub_u32_e32 v0, v0, v24
	v_not_b32_e32 v121, v120
	v_or_b32_e32 v122, 0x80000000, v120
	v_cmp_gt_i32_e32 vcc, 0, v120
	v_add_u32_e32 v119, 0x7e, v119
	v_add_u32_e32 v0, 0x7f, v0
	v_cndmask_b32_e32 v120, v122, v121, vcc
	v_not_b32_e32 v121, v1
	v_or_b32_e32 v122, 0x80000000, v1
	v_cmp_gt_i32_e32 vcc, 0, v1
	v_and_b32_e32 v120, 0xffffff80, v120
	v_sub_u32_e32 v120, v120, v25
	v_cndmask_b32_e32 v1, v122, v121, vcc
	v_cvt_f32_f16_sdwa v121, v2 dst_sel:DWORD dst_unused:UNUSED_PAD src0_sel:WORD_1
	v_cvt_f32_f16_e32 v2, v2
	v_and_b32_e32 v1, 0xffffff80, v1
	v_sub_u32_e32 v1, v1, v25
	v_not_b32_e32 v122, v121
	v_or_b32_e32 v123, 0x80000000, v121
	v_cmp_gt_i32_e32 vcc, 0, v121
	v_add_u32_e32 v120, 0x7e, v120
	v_add_u32_e32 v1, 0x7f, v1
	v_cndmask_b32_e32 v121, v123, v122, vcc
	v_not_b32_e32 v122, v2
	v_or_b32_e32 v123, 0x80000000, v2
	v_cmp_gt_i32_e32 vcc, 0, v2
	v_and_b32_e32 v121, 0xffffff80, v121
	v_sub_u32_e32 v121, v121, v26
	v_cndmask_b32_e32 v2, v123, v122, vcc
	v_cvt_f32_f16_sdwa v122, v3 dst_sel:DWORD dst_unused:UNUSED_PAD src0_sel:WORD_1
	v_cvt_f32_f16_e32 v3, v3
	v_and_b32_e32 v2, 0xffffff80, v2
	v_sub_u32_e32 v2, v2, v26
	v_not_b32_e32 v123, v122
	v_or_b32_e32 v124, 0x80000000, v122
	v_cmp_gt_i32_e32 vcc, 0, v122
	v_add_u32_e32 v121, 0x7e, v121
	v_add_u32_e32 v2, 0x7f, v2
	v_cndmask_b32_e32 v122, v124, v123, vcc
	v_not_b32_e32 v123, v3
	v_or_b32_e32 v124, 0x80000000, v3
	v_cmp_gt_i32_e32 vcc, 0, v3
	v_and_b32_e32 v122, 0xffffff80, v122
	v_sub_u32_e32 v122, v122, v28
	v_cndmask_b32_e32 v3, v124, v123, vcc
	v_and_b32_e32 v3, 0xffffff80, v3
	v_sub_u32_e32 v3, v3, v28
	v_add_u32_e32 v122, 0x7e, v122
	v_add_u32_e32 v3, 0x7f, v3
	v_max_u32_e32 v123, v98, v106
	v_min_u32_e32 v98, v98, v106
	v_max_u32_e32 v106, v107, v99
	v_min_u32_e32 v99, v107, v99
	v_max_u32_e32 v107, v100, v108
	v_min_u32_e32 v100, v100, v108
	v_max_u32_e32 v108, v109, v101
	v_min_u32_e32 v101, v109, v101
	v_max_u32_e32 v109, v94, v110
	v_min_u32_e32 v94, v94, v110
	v_max_u32_e32 v110, v111, v95
	v_min_u32_e32 v95, v111, v95
	v_max_u32_e32 v111, v96, v112
	v_min_u32_e32 v96, v96, v112
	v_max_u32_e32 v112, v114, v97
	v_min_u32_e32 v97, v114, v97
	v_max_u32_e32 v131, v102, v115
	v_min_u32_e32 v102, v102, v115
	v_max_u32_e32 v115, v116, v103
	v_min_u32_e32 v103, v116, v103
	v_max_u32_e32 v116, v104, v117
	v_min_u32_e32 v104, v104, v117
	v_max_u32_e32 v117, v118, v105
	v_min_u32_e32 v105, v118, v105
	v_max_u32_e32 v118, v0, v119
	v_min_u32_e32 v0, v0, v119
	v_max_u32_e32 v119, v120, v1
	v_min_u32_e32 v1, v120, v1
	v_max_u32_e32 v120, v2, v121
	v_min_u32_e32 v2, v2, v121
; #define CE_DESC(a, b) do { const unsigned _mx = (a) > (b) ? (a) : (b), _mn = (a) > (b) ? (b) : (a); (a) = _mx; (b) = _mn; } while (0)
; __device__ __forceinline__ void sort16_desc(unsigned (&k)[16]) {
; #pragma unroll
;     for (int size = 2; size <= 16; size <<= 1)
; #pragma unroll
;         for (int stride = size >> 1; stride > 0; stride >>= 1)
; #pragma unroll
;             for (int i = 0; i < 16; ++i) { const int j = i ^ stride;
;                 if (j > i) { if ((i & size) == 0) CE_DESC(k[i], k[j]); else CE_DESC(k[j], k[i]); } }
; }
	v_max_u32_e32 v121, v122, v3
	v_min_u32_e32 v3, v122, v3
	v_max_u32_e32 v114, v123, v99
	v_min_u32_e32 v99, v123, v99
	v_max_u32_e32 v123, v98, v106
	v_min_u32_e32 v98, v98, v106
	v_max_u32_e32 v106, v101, v107
	v_min_u32_e32 v101, v101, v107
	v_max_u32_e32 v107, v108, v100
	v_min_u32_e32 v100, v108, v100
	v_max_u32_e32 v108, v109, v95
	v_min_u32_e32 v95, v109, v95
	v_max_u32_e32 v109, v94, v110
	v_min_u32_e32 v94, v94, v110
	v_max_u32_e32 v110, v97, v111
	v_min_u32_e32 v97, v97, v111
	v_max_u32_e32 v111, v112, v96
	v_min_u32_e32 v96, v112, v96
	v_max_u32_e32 v122, v131, v103
	v_min_u32_e32 v103, v131, v103
	v_max_u32_e32 v131, v102, v115
	v_min_u32_e32 v102, v102, v115
	v_max_u32_e32 v115, v105, v116
	v_min_u32_e32 v105, v105, v116
	v_max_u32_e32 v116, v117, v104
	v_min_u32_e32 v104, v117, v104
	v_max_u32_e32 v117, v118, v1
	v_min_u32_e32 v1, v118, v1
	v_max_u32_e32 v118, v0, v119
	v_min_u32_e32 v0, v0, v119
	v_max_u32_e32 v119, v3, v120
	v_min_u32_e32 v3, v3, v120
	v_max_u32_e32 v120, v121, v2
	v_min_u32_e32 v2, v121, v2
	v_max_u32_e32 v112, v114, v123
	v_min_u32_e32 v114, v114, v123
	v_max_u32_e32 v123, v99, v98
	v_min_u32_e32 v98, v99, v98
	v_max_u32_e32 v99, v100, v101
	v_min_u32_e32 v100, v100, v101
	v_max_u32_e32 v101, v107, v106
	v_min_u32_e32 v106, v107, v106
	v_max_u32_e32 v107, v108, v109
	v_min_u32_e32 v108, v108, v109
	v_max_u32_e32 v109, v95, v94
	v_min_u32_e32 v94, v95, v94
	v_max_u32_e32 v95, v96, v97
	v_min_u32_e32 v96, v96, v97
	v_max_u32_e32 v97, v111, v110
	v_min_u32_e32 v110, v111, v110
	v_max_u32_e32 v121, v122, v131
	v_min_u32_e32 v122, v122, v131
	v_max_u32_e32 v131, v103, v102
	v_min_u32_e32 v102, v103, v102
	v_max_u32_e32 v103, v104, v105
	v_min_u32_e32 v104, v104, v105
	v_max_u32_e32 v105, v116, v115
	v_min_u32_e32 v115, v116, v115
	v_max_u32_e32 v116, v117, v118
	v_min_u32_e32 v117, v117, v118
	v_max_u32_e32 v118, v1, v0
	v_min_u32_e32 v0, v1, v0
	v_max_u32_e32 v1, v2, v3
	v_min_u32_e32 v2, v2, v3
	v_max_u32_e32 v3, v120, v119
	v_min_u32_e32 v119, v120, v119
	v_max_u32_e32 v111, v112, v100
	v_min_u32_e32 v100, v112, v100
	v_max_u32_e32 v112, v114, v99
	v_min_u32_e32 v99, v114, v99
	v_max_u32_e32 v114, v123, v106
	v_min_u32_e32 v106, v123, v106
	v_max_u32_e32 v123, v98, v101
	v_min_u32_e32 v98, v98, v101
	v_max_u32_e32 v101, v96, v107
	v_min_u32_e32 v96, v96, v107
	v_max_u32_e32 v107, v95, v108
	v_min_u32_e32 v95, v95, v108
	v_max_u32_e32 v108, v110, v109
	v_min_u32_e32 v109, v110, v109
	v_max_u32_e32 v110, v97, v94
	v_min_u32_e32 v94, v97, v94
	v_max_u32_e32 v120, v121, v104
	v_min_u32_e32 v104, v121, v104
	v_max_u32_e32 v121, v122, v103
	v_min_u32_e32 v103, v122, v103
	v_max_u32_e32 v122, v131, v115
	v_min_u32_e32 v115, v131, v115
	v_max_u32_e32 v131, v102, v105
	v_min_u32_e32 v102, v102, v105
	v_max_u32_e32 v105, v2, v116
	v_min_u32_e32 v2, v2, v116
	v_max_u32_e32 v116, v1, v117
	v_min_u32_e32 v1, v1, v117
	v_max_u32_e32 v117, v119, v118
	v_min_u32_e32 v118, v119, v118
	v_max_u32_e32 v119, v3, v0
	v_min_u32_e32 v0, v3, v0
	v_max_u32_e32 v97, v111, v114
	v_min_u32_e32 v111, v111, v114
	v_max_u32_e32 v114, v112, v123
	v_min_u32_e32 v112, v112, v123
	v_max_u32_e32 v123, v100, v106
	v_min_u32_e32 v100, v100, v106
	v_max_u32_e32 v106, v99, v98
	v_min_u32_e32 v98, v99, v98
	v_max_u32_e32 v99, v109, v96
	v_min_u32_e32 v96, v109, v96
	v_max_u32_e32 v109, v94, v95
	v_min_u32_e32 v94, v94, v95
	v_max_u32_e32 v95, v108, v101
	v_min_u32_e32 v101, v108, v101
	v_max_u32_e32 v108, v110, v107
	v_min_u32_e32 v107, v110, v107
	v_max_u32_e32 v3, v120, v122
	v_min_u32_e32 v120, v120, v122
	v_max_u32_e32 v122, v121, v131
	v_min_u32_e32 v121, v121, v131
	v_max_u32_e32 v131, v104, v115
	v_min_u32_e32 v104, v104, v115
	v_max_u32_e32 v115, v103, v102
	v_min_u32_e32 v102, v103, v102
	v_max_u32_e32 v103, v118, v2
	v_min_u32_e32 v2, v118, v2
	v_max_u32_e32 v118, v0, v1
	v_min_u32_e32 v0, v0, v1
	v_max_u32_e32 v1, v117, v105
	v_min_u32_e32 v105, v117, v105
	v_max_u32_e32 v117, v119, v116
	v_min_u32_e32 v116, v119, v116
	v_max_u32_e32 v110, v97, v114
	v_min_u32_e32 v97, v97, v114
	v_max_u32_e32 v114, v111, v112
	v_min_u32_e32 v111, v111, v112
	v_max_u32_e32 v112, v123, v106
	v_min_u32_e32 v106, v123, v106
	v_max_u32_e32 v123, v100, v98
	v_min_u32_e32 v98, v100, v98
	v_max_u32_e32 v100, v94, v96
	v_min_u32_e32 v94, v94, v96
	v_max_u32_e32 v96, v109, v99
	v_min_u32_e32 v99, v109, v99
	v_max_u32_e32 v109, v107, v101
	v_min_u32_e32 v101, v107, v101
	v_max_u32_e32 v107, v108, v95
	v_min_u32_e32 v95, v108, v95
	v_max_u32_e32 v119, v3, v122
	v_min_u32_e32 v3, v3, v122
	v_max_u32_e32 v122, v120, v121
	v_min_u32_e32 v120, v120, v121
	v_max_u32_e32 v121, v131, v115
	v_min_u32_e32 v115, v131, v115
	v_max_u32_e32 v131, v104, v102
	v_min_u32_e32 v102, v104, v102
	v_max_u32_e32 v104, v0, v2
	v_min_u32_e32 v0, v0, v2
	v_max_u32_e32 v2, v118, v103
	v_min_u32_e32 v103, v118, v103
	v_max_u32_e32 v118, v116, v105
	v_min_u32_e32 v105, v116, v105
	v_max_u32_e32 v116, v117, v1
	v_min_u32_e32 v1, v117, v1
	v_max_u32_e32 v108, v110, v94
	v_min_u32_e32 v94, v110, v94
	v_max_u32_e32 v110, v97, v100
	v_min_u32_e32 v97, v97, v100
	v_max_u32_e32 v100, v114, v99
	v_min_u32_e32 v99, v114, v99
	v_max_u32_e32 v114, v111, v96
	v_min_u32_e32 v96, v111, v96
	v_max_u32_e32 v111, v112, v101
	v_min_u32_e32 v101, v112, v101
	v_max_u32_e32 v112, v106, v109
	v_min_u32_e32 v106, v106, v109
	v_max_u32_e32 v109, v123, v95
	v_min_u32_e32 v95, v123, v95
	v_max_u32_e32 v123, v98, v107
	v_min_u32_e32 v98, v98, v107
	v_max_u32_e32 v117, v119, v0
	v_min_u32_e32 v0, v119, v0
	v_max_u32_e32 v119, v3, v104
	v_min_u32_e32 v3, v3, v104
	v_max_u32_e32 v104, v122, v103
	v_min_u32_e32 v103, v122, v103
; #define CE_DESC(a, b) do { const unsigned _mx = (a) > (b) ? (a) : (b), _mn = (a) > (b) ? (b) : (a); (a) = _mx; (b) = _mn; } while (0)
; __device__ __forceinline__ void sort16_desc(unsigned (&k)[16]) {
; #pragma unroll
;     for (int size = 2; size <= 16; size <<= 1)
; #pragma unroll
;         for (int stride = size >> 1; stride > 0; stride >>= 1)
; #pragma unroll
;             for (int i = 0; i < 16; ++i) { const int j = i ^ stride;
;                 if (j > i) { if ((i & size) == 0) CE_DESC(k[i], k[j]); else CE_DESC(k[j], k[i]); } }
; }
; __device__ __forceinline__ void merge16(unsigned (&a)[16], const unsigned (&b)[16]) {
; #pragma unroll
;     for (int i = 0; i < 16; ++i) a[i] = a[i] > b[15 - i] ? a[i] : b[15 - i];
; #pragma unroll
;     for (int stride = 8; stride > 0; stride >>= 1)
; #pragma unroll
;         for (int i = 0; i < 16; ++i) { const int j = i ^ stride; if (j > i) CE_DESC(a[i], a[j]); }
; }
; __device__ __forceinline__ void peer_tile(const Args& A, LAS unsigned char* lds, int tile) {
;     ...
;                 for (int msk = 16; msk <= 32; msk <<= 1) {
; #pragma unroll
;                     for (int i = 0; i < 16; ++i) k1[i] = (unsigned)__shfl_xor((int)k0[i], msk);
;                     merge16(k0, k1); }
	v_max_u32_e32 v122, v120, v2
	v_min_u32_e32 v2, v120, v2
	v_max_u32_e32 v120, v121, v105
	v_min_u32_e32 v105, v121, v105
	v_max_u32_e32 v121, v115, v118
	v_min_u32_e32 v115, v115, v118
	v_max_u32_e32 v118, v131, v1
	v_min_u32_e32 v1, v131, v1
	v_max_u32_e32 v131, v102, v116
	v_min_u32_e32 v102, v102, v116
	v_max_u32_e32 v107, v108, v111
	v_min_u32_e32 v108, v108, v111
	v_max_u32_e32 v111, v110, v112
	v_min_u32_e32 v110, v110, v112
	v_max_u32_e32 v112, v100, v109
	v_min_u32_e32 v100, v100, v109
	v_max_u32_e32 v109, v114, v123
	v_min_u32_e32 v114, v114, v123
	v_max_u32_e32 v123, v94, v101
	v_min_u32_e32 v94, v94, v101
	v_max_u32_e32 v101, v97, v106
	v_min_u32_e32 v97, v97, v106
	v_max_u32_e32 v106, v99, v95
	v_min_u32_e32 v95, v99, v95
	v_max_u32_e32 v99, v96, v98
	v_min_u32_e32 v96, v96, v98
	v_max_u32_e32 v116, v117, v120
	v_min_u32_e32 v117, v117, v120
	v_max_u32_e32 v120, v119, v121
	v_min_u32_e32 v119, v119, v121
	v_max_u32_e32 v121, v104, v118
	v_min_u32_e32 v104, v104, v118
	v_max_u32_e32 v118, v122, v131
	v_min_u32_e32 v122, v122, v131
	v_max_u32_e32 v131, v0, v105
	v_min_u32_e32 v0, v0, v105
	v_max_u32_e32 v105, v3, v115
	v_min_u32_e32 v3, v3, v115
	v_max_u32_e32 v115, v103, v1
	v_min_u32_e32 v1, v103, v1
	v_max_u32_e32 v103, v2, v102
	v_min_u32_e32 v2, v2, v102
	v_max_u32_e32 v98, v107, v112
	v_min_u32_e32 v107, v107, v112
	v_max_u32_e32 v112, v111, v109
	v_min_u32_e32 v109, v111, v109
	v_max_u32_e32 v111, v108, v100
	v_min_u32_e32 v100, v108, v100
	v_max_u32_e32 v108, v110, v114
	v_min_u32_e32 v110, v110, v114
	v_max_u32_e32 v114, v123, v106
	v_min_u32_e32 v106, v123, v106
	v_max_u32_e32 v123, v101, v99
	v_min_u32_e32 v99, v101, v99
	v_max_u32_e32 v101, v94, v95
	v_min_u32_e32 v94, v94, v95
	v_max_u32_e32 v95, v97, v96
	v_min_u32_e32 v96, v97, v96
	v_max_u32_e32 v102, v116, v121
	v_min_u32_e32 v116, v116, v121
	v_max_u32_e32 v121, v120, v118
	v_min_u32_e32 v118, v120, v118
	v_max_u32_e32 v120, v117, v104
	v_min_u32_e32 v104, v117, v104
	v_max_u32_e32 v117, v119, v122
	v_min_u32_e32 v119, v119, v122
	v_max_u32_e32 v122, v131, v115
	v_min_u32_e32 v115, v131, v115
	v_max_u32_e32 v131, v105, v103
	v_min_u32_e32 v103, v105, v103
	v_max_u32_e32 v105, v0, v1
	v_min_u32_e32 v0, v0, v1
	v_max_u32_e32 v1, v3, v2
	v_min_u32_e32 v2, v3, v2
	v_min_u32_e32 v97, v98, v112
	v_min_u32_e32 v124, v107, v109
	v_min_u32_e32 v125, v111, v108
	v_min_u32_e32 v126, v100, v110
	v_min_u32_e32 v127, v114, v123
	v_min_u32_e32 v128, v106, v99
	v_min_u32_e32 v129, v101, v95
	v_min_u32_e32 v130, v94, v96
	v_min_u32_e32 v3, v102, v121
	v_min_u32_e32 v132, v116, v118
	v_min_u32_e32 v133, v120, v117
	v_min_u32_e32 v134, v104, v119
	v_min_u32_e32 v135, v122, v131
	v_min_u32_e32 v136, v115, v103
	v_min_u32_e32 v137, v105, v1
	v_min_u32_e32 v138, v0, v2
	v_max3_u32 v98, v98, v112, v138
	v_max3_u32 v0, v97, v0, v2
	v_max3_u32 v2, v107, v109, v137
	v_max3_u32 v1, v124, v105, v1
	v_max3_u32 v97, v111, v108, v136
	v_max3_u32 v103, v125, v115, v103
	v_max3_u32 v100, v100, v110, v135
	v_max3_u32 v105, v126, v122, v131
	v_max3_u32 v107, v114, v123, v134
	v_max3_u32 v104, v127, v104, v119
	v_max3_u32 v99, v106, v99, v133
	v_max3_u32 v106, v128, v120, v117
	v_max3_u32 v95, v101, v95, v132
	v_max3_u32 v101, v129, v116, v118
	v_max3_u32 v3, v94, v96, v3
	v_max3_u32 v94, v130, v102, v121
	v_max_u32_e32 v96, v98, v107
	v_min_u32_e32 v98, v98, v107
	v_max_u32_e32 v102, v0, v104
	v_min_u32_e32 v0, v0, v104
	v_max_u32_e32 v104, v2, v99
	v_min_u32_e32 v2, v2, v99
	v_max_u32_e32 v99, v1, v106
	v_min_u32_e32 v1, v1, v106
	v_max_u32_e32 v106, v97, v95
	v_min_u32_e32 v95, v97, v95
	v_max_u32_e32 v97, v103, v101
	v_min_u32_e32 v101, v103, v101
	v_max_u32_e32 v103, v100, v3
	v_min_u32_e32 v3, v100, v3
	v_max_u32_e32 v100, v105, v94
	v_min_u32_e32 v94, v105, v94
	v_max_u32_e32 v105, v96, v106
	v_min_u32_e32 v96, v96, v106
	v_max_u32_e32 v106, v102, v97
	v_min_u32_e32 v97, v102, v97
	v_max_u32_e32 v102, v104, v103
	v_min_u32_e32 v103, v104, v103
	v_max_u32_e32 v104, v99, v100
	v_min_u32_e32 v99, v99, v100
	v_max_u32_e32 v100, v98, v95
	v_min_u32_e32 v95, v98, v95
	v_max_u32_e32 v98, v0, v101
	v_min_u32_e32 v0, v0, v101
	v_max_u32_e32 v101, v2, v3
	v_min_u32_e32 v2, v2, v3
	v_max_u32_e32 v3, v1, v94
	v_min_u32_e32 v1, v1, v94
	v_max_u32_e32 v94, v105, v102
	v_min_u32_e32 v102, v105, v102
	v_max_u32_e32 v105, v106, v104
	v_min_u32_e32 v104, v106, v104
	v_max_u32_e32 v106, v96, v103
	v_min_u32_e32 v96, v96, v103
	v_max_u32_e32 v103, v97, v99
	v_min_u32_e32 v97, v97, v99
	v_max_u32_e32 v99, v100, v101
	v_min_u32_e32 v100, v100, v101
	v_max_u32_e32 v101, v98, v3
	v_min_u32_e32 v3, v98, v3
	v_max_u32_e32 v98, v95, v2
	v_min_u32_e32 v2, v95, v2
	v_max_u32_e32 v95, v0, v1
	v_min_u32_e32 v0, v0, v1
	v_max_u32_e32 v1, v94, v105
	v_min_u32_e32 v94, v94, v105
	v_max_u32_e32 v105, v102, v104
	v_min_u32_e32 v102, v102, v104
	v_max_u32_e32 v104, v106, v103
	v_min_u32_e32 v103, v106, v103
	v_max_u32_e32 v106, v96, v97
	v_min_u32_e32 v96, v96, v97
	v_max_u32_e32 v97, v99, v101
	v_min_u32_e32 v99, v99, v101
	v_max_u32_e32 v101, v100, v3
	v_min_u32_e32 v3, v100, v3
	v_max_u32_e32 v100, v98, v95
	v_min_u32_e32 v95, v98, v95
	v_max_u32_e32 v98, v2, v0
	v_min_u32_e32 v0, v2, v0
	ds_bpermute_b32 v2, v27, v1
	ds_bpermute_b32 v107, v27, v94
	ds_bpermute_b32 v108, v27, v105
	ds_bpermute_b32 v109, v27, v102
	ds_bpermute_b32 v110, v27, v104
	ds_bpermute_b32 v111, v27, v103
	ds_bpermute_b32 v112, v27, v106
	ds_bpermute_b32 v114, v27, v96
	ds_bpermute_b32 v115, v27, v97
	ds_bpermute_b32 v116, v27, v99
	ds_bpermute_b32 v117, v27, v101
	ds_bpermute_b32 v118, v27, v0
	ds_bpermute_b32 v119, v27, v98
	ds_bpermute_b32 v120, v27, v95
	ds_bpermute_b32 v121, v27, v100
	ds_bpermute_b32 v122, v27, v3
	s_waitcnt lgkmcnt(4)
; __device__ __forceinline__ void peer_tile(const Args& A, LAS unsigned char* lds, int tile) {
;     ...
;                 { const bf16_t* sp = QRY + m * 2048 + hp * 128 + 32 * g;
;                   const u32x4 s0 = *(const u32x4*)sp, s1 = *(const u32x4*)(sp + 8), s2 = *(const u32x4*)(sp + 16), s3 = *(const u32x4*)(sp + 24);
;     ...
;                 sort16_desc(k0); sort16_desc(k1); merge16(k0, k1);
; #pragma unroll
;                 for (int msk = 16; msk <= 32; msk <<= 1) {
; #pragma unroll
;                     for (int i = 0; i < 16; ++i) k1[i] = (unsigned)__shfl_xor((int)k0[i], msk);
;                     merge16(k0, k1); }
	v_max_u32_e32 v1, v1, v118
	s_waitcnt lgkmcnt(3)
	v_max_u32_e32 v94, v94, v119
	s_waitcnt lgkmcnt(2)
	v_max_u32_e32 v105, v105, v120
	s_waitcnt lgkmcnt(1)
	v_max_u32_e32 v102, v102, v121
	s_waitcnt lgkmcnt(0)
	v_max_u32_e32 v104, v104, v122
	v_max_u32_e32 v103, v103, v117
	v_max_u32_e32 v106, v106, v116
	v_max_u32_e32 v96, v96, v115
	v_max_u32_e32 v97, v97, v114
	v_max_u32_e32 v99, v99, v112
	v_max_u32_e32 v101, v101, v111
	v_max_u32_e32 v3, v3, v110
	v_max_u32_e32 v100, v100, v109
	v_max_u32_e32 v95, v95, v108
	v_max_u32_e32 v98, v98, v107
	v_max_u32_e32 v0, v0, v2
	v_max_u32_e32 v2, v1, v97
	v_min_u32_e32 v1, v1, v97
	v_max_u32_e32 v97, v94, v99
	v_min_u32_e32 v94, v94, v99
	v_max_u32_e32 v99, v105, v101
	v_min_u32_e32 v101, v105, v101
	v_max_u32_e32 v105, v102, v3
	v_min_u32_e32 v3, v102, v3
	v_max_u32_e32 v102, v104, v100
	v_min_u32_e32 v100, v104, v100
	v_max_u32_e32 v104, v103, v95
	v_min_u32_e32 v95, v103, v95
	v_max_u32_e32 v103, v106, v98
	v_min_u32_e32 v98, v106, v98
	v_max_u32_e32 v106, v96, v0
	v_min_u32_e32 v0, v96, v0
	v_max_u32_e32 v96, v2, v102
	v_min_u32_e32 v2, v2, v102
	v_max_u32_e32 v102, v97, v104
	v_min_u32_e32 v97, v97, v104
	v_max_u32_e32 v104, v99, v103
	v_min_u32_e32 v99, v99, v103
	v_max_u32_e32 v103, v105, v106
	v_min_u32_e32 v105, v105, v106
	v_max_u32_e32 v106, v1, v100
	v_min_u32_e32 v1, v1, v100
	v_max_u32_e32 v100, v94, v95
	v_min_u32_e32 v94, v94, v95
	v_max_u32_e32 v95, v101, v98
	v_min_u32_e32 v98, v101, v98
	v_max_u32_e32 v101, v3, v0
	v_min_u32_e32 v0, v3, v0
	v_max_u32_e32 v3, v96, v104
	v_min_u32_e32 v96, v96, v104
	v_max_u32_e32 v104, v102, v103
	v_min_u32_e32 v102, v102, v103
	v_max_u32_e32 v103, v2, v99
	v_min_u32_e32 v2, v2, v99
	v_max_u32_e32 v99, v97, v105
	v_min_u32_e32 v97, v97, v105
	v_max_u32_e32 v105, v106, v95
	v_min_u32_e32 v95, v106, v95
	v_max_u32_e32 v106, v100, v101
	v_min_u32_e32 v100, v100, v101
	v_max_u32_e32 v101, v1, v98
	v_min_u32_e32 v1, v1, v98
	v_max_u32_e32 v98, v94, v0
	v_min_u32_e32 v0, v94, v0
	v_max_u32_e32 v94, v3, v104
	v_min_u32_e32 v3, v3, v104
	v_max_u32_e32 v104, v96, v102
	v_min_u32_e32 v96, v96, v102
	v_max_u32_e32 v102, v103, v99
	v_min_u32_e32 v99, v103, v99
	v_max_u32_e32 v103, v2, v97
	v_min_u32_e32 v2, v2, v97
	v_max_u32_e32 v97, v105, v106
	v_min_u32_e32 v105, v105, v106
	v_max_u32_e32 v106, v95, v100
	v_min_u32_e32 v95, v95, v100
	v_max_u32_e32 v100, v101, v98
	v_min_u32_e32 v98, v101, v98
	v_max_u32_e32 v101, v1, v0
	v_min_u32_e32 v0, v1, v0
	ds_bpermute_b32 v114, v29, v0
	ds_bpermute_b32 v1, v29, v94
	ds_bpermute_b32 v107, v29, v3
	ds_bpermute_b32 v108, v29, v104
	ds_bpermute_b32 v109, v29, v96
	s_waitcnt lgkmcnt(4)
	v_max_u32_e32 v94, v94, v114
	global_load_dwordx4 v[114:117], v[4:5], off offset:1296
	global_load_dwordx4 v[118:121], v[4:5], off offset:1280
	ds_bpermute_b32 v110, v29, v102
	ds_bpermute_b32 v111, v29, v99
	ds_bpermute_b32 v112, v29, v103
	ds_bpermute_b32 v122, v29, v2
	ds_bpermute_b32 v123, v29, v97
	ds_bpermute_b32 v124, v29, v105
	ds_bpermute_b32 v125, v29, v106
	ds_bpermute_b32 v126, v29, v95
	ds_bpermute_b32 v127, v29, v100
	ds_bpermute_b32 v128, v29, v101
	ds_bpermute_b32 v129, v29, v98
	s_waitcnt lgkmcnt(4)
	v_max_u32_e32 v99, v99, v125
	s_waitcnt lgkmcnt(3)
	v_max_u32_e32 v102, v102, v126
	s_waitcnt lgkmcnt(2)
	v_max_u32_e32 v96, v96, v127
	s_waitcnt lgkmcnt(1)
	v_max_u32_e32 v3, v3, v128
	s_waitcnt lgkmcnt(0)
	v_max_u32_e32 v104, v104, v129
	v_max_u32_e32 v103, v103, v124
	v_max_u32_e32 v2, v2, v123
	v_max_u32_e32 v97, v97, v122
	v_max_u32_e32 v105, v105, v112
	v_max_u32_e32 v106, v106, v111
	v_max_u32_e32 v95, v95, v110
	v_max_u32_e32 v100, v100, v109
	v_max_u32_e32 v98, v98, v108
	v_max_u32_e32 v101, v101, v107
	v_max_u32_e32 v0, v0, v1
	v_max_u32_e32 v1, v94, v97
	v_min_u32_e32 v94, v94, v97
	v_max_u32_e32 v97, v3, v105
	v_min_u32_e32 v3, v3, v105
	v_max_u32_e32 v105, v104, v106
	v_min_u32_e32 v104, v104, v106
	v_max_u32_e32 v106, v96, v95
	v_min_u32_e32 v95, v96, v95
	v_max_u32_e32 v96, v102, v100
	v_min_u32_e32 v100, v102, v100
	v_max_u32_e32 v102, v99, v98
	v_min_u32_e32 v98, v99, v98
	v_max_u32_e32 v99, v103, v101
	v_min_u32_e32 v101, v103, v101
	v_max_u32_e32 v103, v2, v0
	v_min_u32_e32 v0, v2, v0
	v_max_u32_e32 v2, v1, v96
	v_min_u32_e32 v1, v1, v96
	v_max_u32_e32 v96, v97, v102
	v_min_u32_e32 v97, v97, v102
	v_max_u32_e32 v102, v105, v99
	v_min_u32_e32 v99, v105, v99
	v_max_u32_e32 v105, v106, v103
	v_min_u32_e32 v103, v106, v103
	v_max_u32_e32 v106, v94, v100
	v_min_u32_e32 v94, v94, v100
	v_max_u32_e32 v100, v3, v98
	v_min_u32_e32 v3, v3, v98
	v_max_u32_e32 v98, v104, v101
	v_min_u32_e32 v101, v104, v101
	v_max_u32_e32 v104, v95, v0
	v_min_u32_e32 v0, v95, v0
	v_max_u32_e32 v95, v2, v102
	v_min_u32_e32 v2, v2, v102
	v_max_u32_e32 v102, v96, v105
	v_min_u32_e32 v96, v96, v105
	v_max_u32_e32 v110, v1, v99
	v_min_u32_e32 v1, v1, v99
	v_max_u32_e32 v99, v97, v103
	v_min_u32_e32 v97, v97, v103
	v_max_u32_e32 v111, v106, v98
	v_min_u32_e32 v98, v106, v98
	v_min_u32_e32 v122, v100, v104
	v_max_u32_e32 v123, v94, v101
	v_min_u32_e32 v94, v94, v101
	v_max_u32_e32 v124, v3, v0
	v_min_u32_e32 v0, v3, v0
	v_max_u32_e32 v112, v100, v104
	v_max_u32_e32 v109, v95, v102
	v_min_u32_e32 v108, v95, v102
	v_max_u32_e32 v107, v2, v96
	v_min_u32_e32 v106, v2, v96
	v_max_u32_e32 v105, v110, v99
	v_min_u32_e32 v104, v110, v99
	v_max_u32_e32 v103, v1, v97
	v_min_u32_e32 v102, v1, v97
	v_max_u32_e32 v99, v98, v122
	v_min_u32_e32 v98, v98, v122
	v_max_u32_e32 v97, v123, v124
	v_min_u32_e32 v96, v123, v124
	v_max_u32_e32 v95, v94, v0
	v_min_u32_e32 v94, v94, v0
	global_load_dwordx4 v[0:3], v[4:5], off offset:1328
	global_load_dwordx4 v[122:125], v[4:5], off offset:1312
	s_waitcnt vmcnt(2)
; __device__ __forceinline__ unsigned f2key(float f) { const unsigned u = __float_as_uint(f); return (u & 0x80000000u) ? ~u : (u | 0x80000000u); }
; __device__ __forceinline__ void peer_tile(const Args& A, LAS unsigned char* lds, int tile) {
;     ...
;                   for (int i = 0; i < 16; ++i) {
;                       const float lo = (float)__builtin_bit_cast(_Float16, (unsigned short)(sw[i] & 0xffffu)), hi = (float)__builtin_bit_cast(_Float16, (unsigned short)(sw[i] >> 16));
;                       const unsigned klo = (f2key(lo) & ~127u) | (unsigned)(127 - (32 * g + 2 * i)), khi = (f2key(hi) & ~127u) | (unsigned)(127 - (32 * g + 2 * i + 1));
;                       if (i < 8) { k0[2 * i] = klo; k0[2 * i + 1] = khi; } else { k1[2 * (i - 8)] = klo; k1[2 * (i - 8) + 1] = khi; } } }
;     ...
;             for (int p = 0; p < 2; ++p)
; #pragma unroll
;                 for (int i = 0; i < 16; ++i) L2[p][i] = (g & 2) ? ((g & 1) ? LA[3][p][i] : LA[2][p][i]) : ((g & 1) ? LA[1][p][i] : LA[0][p][i]);
	v_cvt_f32_f16_sdwa v110, v118 dst_sel:DWORD dst_unused:UNUSED_PAD src0_sel:WORD_1
	v_max_u32_e32 v101, v111, v112
	v_min_u32_e32 v100, v111, v112
	v_cvt_f32_f16_e32 v111, v118
	v_not_b32_e32 v112, v110
	v_or_b32_e32 v118, 0x80000000, v110
	v_cmp_gt_i32_e32 vcc, 0, v110
	v_cndmask_b32_e64 v30, v62, v30, s[0:1]
	s_nop 0
	v_cndmask_b32_e32 v110, v118, v112, vcc
	v_not_b32_e32 v112, v111
	v_or_b32_e32 v118, 0x80000000, v111
	v_cmp_gt_i32_e32 vcc, 0, v111
	v_and_b32_e32 v110, 0xffffff80, v110
	v_sub_u32_e32 v110, v110, v15
	v_cndmask_b32_e32 v111, v118, v112, vcc
	v_cvt_f32_f16_sdwa v112, v119 dst_sel:DWORD dst_unused:UNUSED_PAD src0_sel:WORD_1
	v_cvt_f32_f16_e32 v118, v119
	v_and_b32_e32 v111, 0xffffff80, v111
	v_sub_u32_e32 v111, v111, v15
	v_not_b32_e32 v119, v112
	v_or_b32_e32 v126, 0x80000000, v112
	v_cmp_gt_i32_e32 vcc, 0, v112
	v_add_u32_e32 v110, 0x7e, v110
	v_add_u32_e32 v111, 0x7f, v111
	v_cndmask_b32_e32 v112, v126, v119, vcc
	v_not_b32_e32 v119, v118
	v_or_b32_e32 v126, 0x80000000, v118
	v_cmp_gt_i32_e32 vcc, 0, v118
	v_and_b32_e32 v112, 0xffffff80, v112
	v_sub_u32_e32 v112, v112, v14
	v_cndmask_b32_e32 v118, v126, v119, vcc
	v_cvt_f32_f16_sdwa v119, v120 dst_sel:DWORD dst_unused:UNUSED_PAD src0_sel:WORD_1
	v_cvt_f32_f16_e32 v120, v120
	v_and_b32_e32 v118, 0xffffff80, v118
	v_sub_u32_e32 v118, v118, v14
	v_not_b32_e32 v126, v119
	v_or_b32_e32 v127, 0x80000000, v119
	v_cmp_gt_i32_e32 vcc, 0, v119
	v_add_u32_e32 v112, 0x7e, v112
	v_add_u32_e32 v118, 0x7f, v118
	v_cndmask_b32_e32 v119, v127, v126, vcc
	v_not_b32_e32 v126, v120
	v_or_b32_e32 v127, 0x80000000, v120
	v_cmp_gt_i32_e32 vcc, 0, v120
	v_and_b32_e32 v119, 0xffffff80, v119
	v_sub_u32_e32 v119, v119, v12
	v_cndmask_b32_e32 v120, v127, v126, vcc
	v_cvt_f32_f16_sdwa v126, v121 dst_sel:DWORD dst_unused:UNUSED_PAD src0_sel:WORD_1
	v_cvt_f32_f16_e32 v121, v121
	v_and_b32_e32 v120, 0xffffff80, v120
	v_sub_u32_e32 v120, v120, v12
	v_not_b32_e32 v127, v126
	v_or_b32_e32 v128, 0x80000000, v126
	v_cmp_gt_i32_e32 vcc, 0, v126
	v_add_u32_e32 v119, 0x7e, v119
	v_add_u32_e32 v120, 0x7f, v120
	v_cndmask_b32_e32 v126, v128, v127, vcc
	v_not_b32_e32 v127, v121
	v_or_b32_e32 v128, 0x80000000, v121
	v_cmp_gt_i32_e32 vcc, 0, v121
	v_and_b32_e32 v126, 0xffffff80, v126
	v_sub_u32_e32 v126, v126, v10
	v_cndmask_b32_e32 v121, v128, v127, vcc
	v_cvt_f32_f16_sdwa v127, v114 dst_sel:DWORD dst_unused:UNUSED_PAD src0_sel:WORD_1
	v_cvt_f32_f16_e32 v114, v114
	v_and_b32_e32 v121, 0xffffff80, v121
	v_sub_u32_e32 v121, v121, v10
	v_not_b32_e32 v128, v127
	v_or_b32_e32 v129, 0x80000000, v127
	v_cmp_gt_i32_e32 vcc, 0, v127
	v_add_u32_e32 v126, 0x7e, v126
	v_add_u32_e32 v121, 0x7f, v121
	v_cndmask_b32_e32 v127, v129, v128, vcc
	v_not_b32_e32 v128, v114
	v_or_b32_e32 v129, 0x80000000, v114
	v_cmp_gt_i32_e32 vcc, 0, v114
	v_and_b32_e32 v127, 0xffffff80, v127
	v_sub_u32_e32 v127, v127, v8
	v_cndmask_b32_e32 v114, v129, v128, vcc
	v_cvt_f32_f16_sdwa v128, v115 dst_sel:DWORD dst_unused:UNUSED_PAD src0_sel:WORD_1
	v_cvt_f32_f16_e32 v115, v115
	v_and_b32_e32 v114, 0xffffff80, v114
	v_sub_u32_e32 v114, v114, v8
	v_not_b32_e32 v129, v128
	v_or_b32_e32 v130, 0x80000000, v128
	v_cmp_gt_i32_e32 vcc, 0, v128
	v_add_u32_e32 v127, 0x7e, v127
	v_add_u32_e32 v114, 0x7f, v114
	v_cndmask_b32_e32 v128, v130, v129, vcc
	v_not_b32_e32 v129, v115
	v_or_b32_e32 v130, 0x80000000, v115
	v_cmp_gt_i32_e32 vcc, 0, v115
	v_and_b32_e32 v128, 0xffffff80, v128
	v_sub_u32_e32 v128, v128, v16
	v_cndmask_b32_e32 v115, v130, v129, vcc
	v_cvt_f32_f16_sdwa v129, v116 dst_sel:DWORD dst_unused:UNUSED_PAD src0_sel:WORD_1
	v_cvt_f32_f16_e32 v116, v116
	v_and_b32_e32 v115, 0xffffff80, v115
	v_sub_u32_e32 v115, v115, v16
	v_not_b32_e32 v130, v129
	v_or_b32_e32 v131, 0x80000000, v129
	v_cmp_gt_i32_e32 vcc, 0, v129
	v_add_u32_e32 v128, 0x7e, v128
	v_add_u32_e32 v115, 0x7f, v115
	v_cndmask_b32_e32 v129, v131, v130, vcc
	v_not_b32_e32 v130, v116
	v_or_b32_e32 v131, 0x80000000, v116
	v_cmp_gt_i32_e32 vcc, 0, v116
	v_and_b32_e32 v129, 0xffffff80, v129
	v_sub_u32_e32 v129, v129, v17
	v_cndmask_b32_e32 v116, v131, v130, vcc
	v_cvt_f32_f16_sdwa v130, v117 dst_sel:DWORD dst_unused:UNUSED_PAD src0_sel:WORD_1
	v_cvt_f32_f16_e32 v117, v117
	v_and_b32_e32 v116, 0xffffff80, v116
	v_sub_u32_e32 v116, v116, v17
	v_not_b32_e32 v131, v130
	v_or_b32_e32 v132, 0x80000000, v130
	v_cmp_gt_i32_e32 vcc, 0, v130
	v_add_u32_e32 v129, 0x7e, v129
	v_add_u32_e32 v116, 0x7f, v116
	v_cndmask_b32_e32 v130, v132, v131, vcc
	v_not_b32_e32 v131, v117
	v_or_b32_e32 v132, 0x80000000, v117
	v_cmp_gt_i32_e32 vcc, 0, v117
	v_and_b32_e32 v130, 0xffffff80, v130
	v_sub_u32_e32 v130, v130, v18
	v_cndmask_b32_e32 v117, v132, v131, vcc
	s_waitcnt vmcnt(0)
; __device__ __forceinline__ unsigned f2key(float f) { const unsigned u = __float_as_uint(f); return (u & 0x80000000u) ? ~u : (u | 0x80000000u); }
; #define CE_DESC(a, b) do { const unsigned _mx = (a) > (b) ? (a) : (b), _mn = (a) > (b) ? (b) : (a); (a) = _mx; (b) = _mn; } while (0)
; __device__ __forceinline__ void sort16_desc(unsigned (&k)[16]) {
; #pragma unroll
;     for (int size = 2; size <= 16; size <<= 1)
; #pragma unroll
;         for (int stride = size >> 1; stride > 0; stride >>= 1)
; #pragma unroll
;             for (int i = 0; i < 16; ++i) { const int j = i ^ stride;
;                 if (j > i) { if ((i & size) == 0) CE_DESC(k[i], k[j]); else CE_DESC(k[j], k[i]); } }
; }
; __device__ __forceinline__ void peer_tile(const Args& A, LAS unsigned char* lds, int tile) {
;     ...
;                   for (int i = 0; i < 16; ++i) {
;                       const float lo = (float)__builtin_bit_cast(_Float16, (unsigned short)(sw[i] & 0xffffu)), hi = (float)__builtin_bit_cast(_Float16, (unsigned short)(sw[i] >> 16));
;                       const unsigned klo = (f2key(lo) & ~127u) | (unsigned)(127 - (32 * g + 2 * i)), khi = (f2key(hi) & ~127u) | (unsigned)(127 - (32 * g + 2 * i + 1));
;                       if (i < 8) { k0[2 * i] = klo; k0[2 * i + 1] = khi; } else { k1[2 * (i - 8)] = klo; k1[2 * (i - 8) + 1] = khi; } } }
	v_cvt_f32_f16_sdwa v131, v122 dst_sel:DWORD dst_unused:UNUSED_PAD src0_sel:WORD_1
	v_cvt_f32_f16_e32 v122, v122
	v_and_b32_e32 v117, 0xffffff80, v117
	v_sub_u32_e32 v117, v117, v18
	v_not_b32_e32 v132, v131
	v_or_b32_e32 v133, 0x80000000, v131
	v_cmp_gt_i32_e32 vcc, 0, v131
	v_add_u32_e32 v130, 0x7e, v130
	v_add_u32_e32 v117, 0x7f, v117
	v_cndmask_b32_e32 v131, v133, v132, vcc
	v_not_b32_e32 v132, v122
	v_or_b32_e32 v133, 0x80000000, v122
	v_cmp_gt_i32_e32 vcc, 0, v122
	v_and_b32_e32 v131, 0xffffff80, v131
	v_sub_u32_e32 v131, v131, v20
	v_cndmask_b32_e32 v122, v133, v132, vcc
	v_cvt_f32_f16_sdwa v132, v123 dst_sel:DWORD dst_unused:UNUSED_PAD src0_sel:WORD_1
	v_cvt_f32_f16_e32 v123, v123
	v_and_b32_e32 v122, 0xffffff80, v122
	v_sub_u32_e32 v122, v122, v20
	v_not_b32_e32 v133, v132
	v_or_b32_e32 v134, 0x80000000, v132
	v_cmp_gt_i32_e32 vcc, 0, v132
	v_add_u32_e32 v131, 0x7e, v131
	v_add_u32_e32 v122, 0x7f, v122
	v_cndmask_b32_e32 v132, v134, v133, vcc
	v_not_b32_e32 v133, v123
	v_or_b32_e32 v134, 0x80000000, v123
	v_cmp_gt_i32_e32 vcc, 0, v123
	v_and_b32_e32 v132, 0xffffff80, v132
	v_sub_u32_e32 v132, v132, v21
	v_cndmask_b32_e32 v123, v134, v133, vcc
	v_cvt_f32_f16_sdwa v133, v124 dst_sel:DWORD dst_unused:UNUSED_PAD src0_sel:WORD_1
	v_cvt_f32_f16_e32 v124, v124
	v_and_b32_e32 v123, 0xffffff80, v123
	v_sub_u32_e32 v123, v123, v21
	v_not_b32_e32 v134, v133
	v_or_b32_e32 v135, 0x80000000, v133
	v_cmp_gt_i32_e32 vcc, 0, v133
	v_add_u32_e32 v132, 0x7e, v132
	v_add_u32_e32 v123, 0x7f, v123
	v_cndmask_b32_e32 v133, v135, v134, vcc
	v_not_b32_e32 v134, v124
	v_or_b32_e32 v135, 0x80000000, v124
	v_cmp_gt_i32_e32 vcc, 0, v124
	v_and_b32_e32 v133, 0xffffff80, v133
	v_sub_u32_e32 v133, v133, v22
	v_cndmask_b32_e32 v124, v135, v134, vcc
	v_cvt_f32_f16_sdwa v134, v125 dst_sel:DWORD dst_unused:UNUSED_PAD src0_sel:WORD_1
	v_cvt_f32_f16_e32 v125, v125
	v_and_b32_e32 v124, 0xffffff80, v124
	v_sub_u32_e32 v124, v124, v22
	v_not_b32_e32 v135, v134
	v_or_b32_e32 v136, 0x80000000, v134
	v_cmp_gt_i32_e32 vcc, 0, v134
	v_add_u32_e32 v133, 0x7e, v133
	v_add_u32_e32 v124, 0x7f, v124
	v_cndmask_b32_e32 v134, v136, v135, vcc
	v_not_b32_e32 v135, v125
	v_or_b32_e32 v136, 0x80000000, v125
	v_cmp_gt_i32_e32 vcc, 0, v125
	v_and_b32_e32 v134, 0xffffff80, v134
	v_sub_u32_e32 v134, v134, v23
	v_cndmask_b32_e32 v125, v136, v135, vcc
	v_cvt_f32_f16_sdwa v135, v0 dst_sel:DWORD dst_unused:UNUSED_PAD src0_sel:WORD_1
	v_cvt_f32_f16_e32 v0, v0
	v_and_b32_e32 v125, 0xffffff80, v125
	v_sub_u32_e32 v125, v125, v23
	v_not_b32_e32 v136, v135
	v_or_b32_e32 v137, 0x80000000, v135
	v_cmp_gt_i32_e32 vcc, 0, v135
	v_add_u32_e32 v134, 0x7e, v134
	v_add_u32_e32 v125, 0x7f, v125
	v_cndmask_b32_e32 v135, v137, v136, vcc
	v_not_b32_e32 v136, v0
	v_or_b32_e32 v137, 0x80000000, v0
	v_cmp_gt_i32_e32 vcc, 0, v0
	v_and_b32_e32 v135, 0xffffff80, v135
	v_sub_u32_e32 v135, v135, v24
	v_cndmask_b32_e32 v0, v137, v136, vcc
	v_cvt_f32_f16_sdwa v136, v1 dst_sel:DWORD dst_unused:UNUSED_PAD src0_sel:WORD_1
	v_cvt_f32_f16_e32 v1, v1
	v_and_b32_e32 v0, 0xffffff80, v0
	v_sub_u32_e32 v0, v0, v24
	v_not_b32_e32 v137, v136
	v_or_b32_e32 v138, 0x80000000, v136
	v_cmp_gt_i32_e32 vcc, 0, v136
	v_add_u32_e32 v135, 0x7e, v135
	v_add_u32_e32 v0, 0x7f, v0
	v_cndmask_b32_e32 v136, v138, v137, vcc
	v_not_b32_e32 v137, v1
	v_or_b32_e32 v138, 0x80000000, v1
	v_cmp_gt_i32_e32 vcc, 0, v1
	v_and_b32_e32 v136, 0xffffff80, v136
	v_sub_u32_e32 v136, v136, v25
	v_cndmask_b32_e32 v1, v138, v137, vcc
	v_cvt_f32_f16_sdwa v137, v2 dst_sel:DWORD dst_unused:UNUSED_PAD src0_sel:WORD_1
	v_cvt_f32_f16_e32 v2, v2
	v_and_b32_e32 v1, 0xffffff80, v1
	v_sub_u32_e32 v1, v1, v25
	v_not_b32_e32 v138, v137
	v_or_b32_e32 v139, 0x80000000, v137
	v_cmp_gt_i32_e32 vcc, 0, v137
	v_add_u32_e32 v136, 0x7e, v136
	v_add_u32_e32 v1, 0x7f, v1
	v_cndmask_b32_e32 v137, v139, v138, vcc
	v_not_b32_e32 v138, v2
	v_or_b32_e32 v139, 0x80000000, v2
	v_cmp_gt_i32_e32 vcc, 0, v2
	v_and_b32_e32 v137, 0xffffff80, v137
	v_sub_u32_e32 v137, v137, v26
	v_cndmask_b32_e32 v2, v139, v138, vcc
	v_cvt_f32_f16_sdwa v138, v3 dst_sel:DWORD dst_unused:UNUSED_PAD src0_sel:WORD_1
	v_cvt_f32_f16_e32 v3, v3
	v_and_b32_e32 v2, 0xffffff80, v2
	v_sub_u32_e32 v2, v2, v26
	v_not_b32_e32 v139, v138
	v_or_b32_e32 v140, 0x80000000, v138
	v_cmp_gt_i32_e32 vcc, 0, v138
	v_add_u32_e32 v137, 0x7e, v137
	v_add_u32_e32 v2, 0x7f, v2
	v_cndmask_b32_e32 v138, v140, v139, vcc
	v_not_b32_e32 v139, v3
	v_or_b32_e32 v140, 0x80000000, v3
	v_cmp_gt_i32_e32 vcc, 0, v3
	v_and_b32_e32 v138, 0xffffff80, v138
	v_sub_u32_e32 v138, v138, v28
	v_cndmask_b32_e32 v3, v140, v139, vcc
	v_and_b32_e32 v3, 0xffffff80, v3
	v_sub_u32_e32 v3, v3, v28
	v_add_u32_e32 v138, 0x7e, v138
	v_add_u32_e32 v3, 0x7f, v3
	v_max_u32_e32 v139, v111, v110
	v_min_u32_e32 v110, v111, v110
	v_max_u32_e32 v111, v112, v118
	v_min_u32_e32 v112, v112, v118
	v_max_u32_e32 v118, v120, v119
	v_min_u32_e32 v119, v120, v119
	v_max_u32_e32 v120, v126, v121
	v_min_u32_e32 v121, v126, v121
	v_max_u32_e32 v126, v114, v127
	v_min_u32_e32 v114, v114, v127
	v_max_u32_e32 v127, v128, v115
	v_min_u32_e32 v115, v128, v115
	v_max_u32_e32 v128, v116, v129
	v_min_u32_e32 v116, v116, v129
	v_max_u32_e32 v129, v130, v117
	v_min_u32_e32 v117, v130, v117
	v_max_u32_e32 v147, v122, v131
	v_min_u32_e32 v122, v122, v131
	v_max_u32_e32 v131, v132, v123
	v_min_u32_e32 v123, v132, v123
	v_max_u32_e32 v132, v124, v133
	v_min_u32_e32 v124, v124, v133
	v_max_u32_e32 v133, v134, v125
	v_min_u32_e32 v125, v134, v125
	v_max_u32_e32 v134, v0, v135
	v_min_u32_e32 v0, v0, v135
	v_max_u32_e32 v135, v136, v1
	v_min_u32_e32 v1, v136, v1
	v_max_u32_e32 v136, v2, v137
	v_min_u32_e32 v2, v2, v137
; #define CE_DESC(a, b) do { const unsigned _mx = (a) > (b) ? (a) : (b), _mn = (a) > (b) ? (b) : (a); (a) = _mx; (b) = _mn; } while (0)
; __device__ __forceinline__ void sort16_desc(unsigned (&k)[16]) {
; #pragma unroll
;     for (int size = 2; size <= 16; size <<= 1)
; #pragma unroll
;         for (int stride = size >> 1; stride > 0; stride >>= 1)
; #pragma unroll
;             for (int i = 0; i < 16; ++i) { const int j = i ^ stride;
;                 if (j > i) { if ((i & size) == 0) CE_DESC(k[i], k[j]); else CE_DESC(k[j], k[i]); } }
; }
	v_max_u32_e32 v137, v138, v3
	v_min_u32_e32 v3, v138, v3
	v_max_u32_e32 v130, v139, v112
	v_min_u32_e32 v112, v139, v112
	v_max_u32_e32 v139, v110, v111
	v_min_u32_e32 v110, v110, v111
	v_max_u32_e32 v111, v121, v118
	v_min_u32_e32 v118, v121, v118
	v_max_u32_e32 v121, v120, v119
	v_min_u32_e32 v119, v120, v119
	v_max_u32_e32 v120, v126, v115
	v_min_u32_e32 v115, v126, v115
	v_max_u32_e32 v126, v114, v127
	v_min_u32_e32 v114, v114, v127
	v_max_u32_e32 v127, v117, v128
	v_min_u32_e32 v117, v117, v128
	v_max_u32_e32 v128, v129, v116
	v_min_u32_e32 v116, v129, v116
	v_max_u32_e32 v138, v147, v123
	v_min_u32_e32 v123, v147, v123
	v_max_u32_e32 v147, v122, v131
	v_min_u32_e32 v122, v122, v131
	v_max_u32_e32 v131, v125, v132
	v_min_u32_e32 v125, v125, v132
	v_max_u32_e32 v132, v133, v124
	v_min_u32_e32 v124, v133, v124
	v_max_u32_e32 v133, v134, v1
	v_min_u32_e32 v1, v134, v1
	v_max_u32_e32 v134, v0, v135
	v_min_u32_e32 v0, v0, v135
	v_max_u32_e32 v135, v3, v136
	v_min_u32_e32 v3, v3, v136
	v_max_u32_e32 v136, v137, v2
	v_min_u32_e32 v2, v137, v2
	v_max_u32_e32 v129, v130, v139
	v_min_u32_e32 v130, v130, v139
	v_max_u32_e32 v139, v112, v110
	v_min_u32_e32 v110, v112, v110
	v_max_u32_e32 v112, v119, v118
	v_min_u32_e32 v118, v119, v118
	v_max_u32_e32 v119, v121, v111
	v_min_u32_e32 v111, v121, v111
	v_max_u32_e32 v121, v120, v126
	v_min_u32_e32 v120, v120, v126
	v_max_u32_e32 v126, v115, v114
	v_min_u32_e32 v114, v115, v114
	v_max_u32_e32 v115, v116, v117
	v_min_u32_e32 v116, v116, v117
	v_max_u32_e32 v117, v128, v127
	v_min_u32_e32 v127, v128, v127
	v_max_u32_e32 v137, v138, v147
	v_min_u32_e32 v138, v138, v147
	v_max_u32_e32 v147, v123, v122
	v_min_u32_e32 v122, v123, v122
	v_max_u32_e32 v123, v124, v125
	v_min_u32_e32 v124, v124, v125
	v_max_u32_e32 v125, v132, v131
	v_min_u32_e32 v131, v132, v131
	v_max_u32_e32 v132, v133, v134
	v_min_u32_e32 v133, v133, v134
	v_max_u32_e32 v134, v1, v0
	v_min_u32_e32 v0, v1, v0
	v_max_u32_e32 v1, v2, v3
	v_min_u32_e32 v2, v2, v3
	v_max_u32_e32 v3, v136, v135
	v_min_u32_e32 v135, v136, v135
	v_max_u32_e32 v128, v129, v118
	v_min_u32_e32 v118, v129, v118
	v_max_u32_e32 v129, v130, v112
	v_min_u32_e32 v112, v130, v112
	v_max_u32_e32 v130, v139, v111
	v_min_u32_e32 v111, v139, v111
	v_max_u32_e32 v139, v110, v119
	v_min_u32_e32 v110, v110, v119
	v_max_u32_e32 v119, v116, v121
	v_min_u32_e32 v116, v116, v121
	v_max_u32_e32 v121, v115, v120
	v_min_u32_e32 v115, v115, v120
	v_max_u32_e32 v120, v127, v126
	v_min_u32_e32 v126, v127, v126
	v_max_u32_e32 v127, v117, v114
	v_min_u32_e32 v114, v117, v114
	v_max_u32_e32 v136, v137, v124
	v_min_u32_e32 v124, v137, v124
	v_max_u32_e32 v137, v138, v123
	v_min_u32_e32 v123, v138, v123
	v_max_u32_e32 v138, v147, v131
	v_min_u32_e32 v131, v147, v131
	v_max_u32_e32 v147, v122, v125
	v_min_u32_e32 v122, v122, v125
	v_max_u32_e32 v125, v2, v132
	v_min_u32_e32 v2, v2, v132
	v_max_u32_e32 v132, v1, v133
	v_min_u32_e32 v1, v1, v133
	v_max_u32_e32 v133, v135, v134
	v_min_u32_e32 v134, v135, v134
	v_max_u32_e32 v135, v3, v0
	v_min_u32_e32 v0, v3, v0
	v_max_u32_e32 v117, v128, v130
	v_min_u32_e32 v128, v128, v130
	v_max_u32_e32 v130, v129, v139
	v_min_u32_e32 v129, v129, v139
	v_max_u32_e32 v139, v118, v111
	v_min_u32_e32 v111, v118, v111
	v_max_u32_e32 v118, v112, v110
	v_min_u32_e32 v110, v112, v110
	v_max_u32_e32 v112, v126, v116
	v_min_u32_e32 v116, v126, v116
	v_max_u32_e32 v126, v114, v115
	v_min_u32_e32 v114, v114, v115
	v_max_u32_e32 v115, v120, v119
	v_min_u32_e32 v119, v120, v119
	v_max_u32_e32 v120, v127, v121
	v_min_u32_e32 v121, v127, v121
	v_max_u32_e32 v3, v136, v138
	v_min_u32_e32 v136, v136, v138
	v_max_u32_e32 v138, v137, v147
	v_min_u32_e32 v137, v137, v147
	v_max_u32_e32 v147, v124, v131
	v_min_u32_e32 v124, v124, v131
	v_max_u32_e32 v131, v123, v122
	v_min_u32_e32 v122, v123, v122
	v_max_u32_e32 v123, v134, v2
	v_min_u32_e32 v2, v134, v2
	v_max_u32_e32 v134, v0, v1
	v_min_u32_e32 v0, v0, v1
	v_max_u32_e32 v1, v133, v125
	v_min_u32_e32 v125, v133, v125
	v_max_u32_e32 v133, v135, v132
	v_min_u32_e32 v132, v135, v132
	v_max_u32_e32 v127, v117, v130
	v_min_u32_e32 v117, v117, v130
	v_max_u32_e32 v130, v128, v129
	v_min_u32_e32 v128, v128, v129
	v_max_u32_e32 v129, v139, v118
	v_min_u32_e32 v118, v139, v118
	v_max_u32_e32 v139, v111, v110
	v_min_u32_e32 v110, v111, v110
	v_max_u32_e32 v111, v114, v116
	v_min_u32_e32 v114, v114, v116
	v_max_u32_e32 v116, v126, v112
	v_min_u32_e32 v112, v126, v112
	v_max_u32_e32 v126, v121, v119
	v_min_u32_e32 v119, v121, v119
	v_max_u32_e32 v121, v120, v115
	v_min_u32_e32 v115, v120, v115
	v_max_u32_e32 v135, v3, v138
	v_min_u32_e32 v3, v3, v138
	v_max_u32_e32 v138, v136, v137
	v_min_u32_e32 v136, v136, v137
	v_max_u32_e32 v137, v147, v131
	v_min_u32_e32 v131, v147, v131
	v_max_u32_e32 v147, v124, v122
	v_min_u32_e32 v122, v124, v122
	v_max_u32_e32 v124, v0, v2
	v_min_u32_e32 v0, v0, v2
	v_max_u32_e32 v2, v134, v123
	v_min_u32_e32 v123, v134, v123
	v_max_u32_e32 v134, v132, v125
	v_min_u32_e32 v125, v132, v125
	v_max_u32_e32 v132, v133, v1
	v_min_u32_e32 v1, v133, v1
	v_max_u32_e32 v120, v127, v114
	v_min_u32_e32 v114, v127, v114
	v_max_u32_e32 v127, v117, v111
	v_min_u32_e32 v111, v117, v111
	v_max_u32_e32 v117, v130, v112
	v_min_u32_e32 v112, v130, v112
	v_max_u32_e32 v130, v128, v116
	v_min_u32_e32 v116, v128, v116
	v_max_u32_e32 v128, v129, v119
	v_min_u32_e32 v119, v129, v119
	v_max_u32_e32 v129, v118, v126
	v_min_u32_e32 v118, v118, v126
	v_max_u32_e32 v126, v139, v115
	v_min_u32_e32 v115, v139, v115
	v_max_u32_e32 v139, v110, v121
	v_min_u32_e32 v110, v110, v121
	v_max_u32_e32 v133, v135, v0
	v_min_u32_e32 v0, v135, v0
; #define CE_DESC(a, b) do { const unsigned _mx = (a) > (b) ? (a) : (b), _mn = (a) > (b) ? (b) : (a); (a) = _mx; (b) = _mn; } while (0)
; __device__ __forceinline__ void sort16_desc(unsigned (&k)[16]) {
; #pragma unroll
;     for (int size = 2; size <= 16; size <<= 1)
; #pragma unroll
;         for (int stride = size >> 1; stride > 0; stride >>= 1)
; #pragma unroll
;             for (int i = 0; i < 16; ++i) { const int j = i ^ stride;
;                 if (j > i) { if ((i & size) == 0) CE_DESC(k[i], k[j]); else CE_DESC(k[j], k[i]); } }
; }
; __device__ __forceinline__ void merge16(unsigned (&a)[16], const unsigned (&b)[16]) {
; #pragma unroll
;     for (int i = 0; i < 16; ++i) a[i] = a[i] > b[15 - i] ? a[i] : b[15 - i];
; #pragma unroll
;     for (int stride = 8; stride > 0; stride >>= 1)
; #pragma unroll
;         for (int i = 0; i < 16; ++i) { const int j = i ^ stride; if (j > i) CE_DESC(a[i], a[j]); }
; }
; __device__ __forceinline__ void peer_tile(const Args& A, LAS unsigned char* lds, int tile) {
;     ...
;                 for (int msk = 16; msk <= 32; msk <<= 1) {
; #pragma unroll
;                     for (int i = 0; i < 16; ++i) k1[i] = (unsigned)__shfl_xor((int)k0[i], msk);
;                     merge16(k0, k1); }
	v_max_u32_e32 v135, v3, v124
	v_min_u32_e32 v3, v3, v124
	v_max_u32_e32 v124, v138, v123
	v_min_u32_e32 v123, v138, v123
	v_max_u32_e32 v138, v136, v2
	v_min_u32_e32 v2, v136, v2
	v_max_u32_e32 v136, v137, v125
	v_min_u32_e32 v125, v137, v125
	v_max_u32_e32 v137, v131, v134
	v_min_u32_e32 v131, v131, v134
	v_max_u32_e32 v134, v147, v1
	v_min_u32_e32 v1, v147, v1
	v_max_u32_e32 v147, v122, v132
	v_min_u32_e32 v122, v122, v132
	v_max_u32_e32 v121, v120, v128
	v_min_u32_e32 v120, v120, v128
	v_max_u32_e32 v128, v127, v129
	v_min_u32_e32 v127, v127, v129
	v_max_u32_e32 v129, v117, v126
	v_min_u32_e32 v117, v117, v126
	v_max_u32_e32 v126, v130, v139
	v_min_u32_e32 v130, v130, v139
	v_max_u32_e32 v139, v114, v119
	v_min_u32_e32 v114, v114, v119
	v_max_u32_e32 v119, v111, v118
	v_min_u32_e32 v111, v111, v118
	v_max_u32_e32 v118, v112, v115
	v_min_u32_e32 v112, v112, v115
	v_max_u32_e32 v115, v116, v110
	v_min_u32_e32 v110, v116, v110
	v_max_u32_e32 v132, v133, v136
	v_min_u32_e32 v133, v133, v136
	v_max_u32_e32 v136, v135, v137
	v_min_u32_e32 v135, v135, v137
	v_max_u32_e32 v137, v124, v134
	v_min_u32_e32 v124, v124, v134
	v_max_u32_e32 v134, v138, v147
	v_min_u32_e32 v138, v138, v147
	v_max_u32_e32 v147, v0, v125
	v_min_u32_e32 v0, v0, v125
	v_max_u32_e32 v125, v3, v131
	v_min_u32_e32 v3, v3, v131
	v_max_u32_e32 v131, v123, v1
	v_min_u32_e32 v1, v123, v1
	v_max_u32_e32 v123, v2, v122
	v_min_u32_e32 v2, v2, v122
	v_max_u32_e32 v116, v121, v129
	v_min_u32_e32 v121, v121, v129
	v_max_u32_e32 v129, v128, v126
	v_min_u32_e32 v126, v128, v126
	v_max_u32_e32 v128, v120, v117
	v_min_u32_e32 v117, v120, v117
	v_max_u32_e32 v120, v127, v130
	v_min_u32_e32 v127, v127, v130
	v_max_u32_e32 v130, v139, v118
	v_min_u32_e32 v118, v139, v118
	v_max_u32_e32 v139, v119, v115
	v_min_u32_e32 v115, v119, v115
	v_max_u32_e32 v119, v114, v112
	v_min_u32_e32 v112, v114, v112
	v_max_u32_e32 v114, v111, v110
	v_min_u32_e32 v110, v111, v110
	v_max_u32_e32 v122, v132, v137
	v_min_u32_e32 v132, v132, v137
	v_max_u32_e32 v137, v136, v134
	v_min_u32_e32 v134, v136, v134
	v_max_u32_e32 v136, v133, v124
	v_min_u32_e32 v124, v133, v124
	v_max_u32_e32 v133, v135, v138
	v_min_u32_e32 v135, v135, v138
	v_max_u32_e32 v138, v147, v131
	v_min_u32_e32 v131, v147, v131
	v_max_u32_e32 v147, v125, v123
	v_min_u32_e32 v123, v125, v123
	v_max_u32_e32 v125, v0, v1
	v_min_u32_e32 v0, v0, v1
	v_max_u32_e32 v1, v3, v2
	v_min_u32_e32 v2, v3, v2
	v_min_u32_e32 v111, v116, v129
	v_min_u32_e32 v140, v121, v126
	v_min_u32_e32 v141, v128, v120
	v_min_u32_e32 v142, v117, v127
	v_min_u32_e32 v143, v130, v139
	v_min_u32_e32 v144, v118, v115
	v_min_u32_e32 v145, v119, v114
	v_min_u32_e32 v146, v112, v110
	v_min_u32_e32 v3, v122, v137
	v_min_u32_e32 v148, v132, v134
	v_min_u32_e32 v149, v136, v133
	v_min_u32_e32 v150, v124, v135
	v_min_u32_e32 v151, v138, v147
	v_min_u32_e32 v152, v131, v123
	v_min_u32_e32 v153, v125, v1
	v_min_u32_e32 v154, v0, v2
	v_max3_u32 v116, v116, v129, v154
	v_max3_u32 v0, v111, v0, v2
	v_max3_u32 v2, v121, v126, v153
	v_max3_u32 v1, v140, v125, v1
	v_max3_u32 v111, v128, v120, v152
	v_max3_u32 v120, v141, v131, v123
	v_max3_u32 v117, v117, v127, v151
	v_max3_u32 v121, v142, v138, v147
	v_max3_u32 v123, v130, v139, v150
	v_max3_u32 v124, v143, v124, v135
	v_max3_u32 v115, v118, v115, v149
	v_max3_u32 v118, v144, v136, v133
	v_max3_u32 v114, v119, v114, v148
	v_max3_u32 v119, v145, v132, v134
	v_max3_u32 v3, v112, v110, v3
	v_max3_u32 v110, v146, v122, v137
	v_max_u32_e32 v112, v116, v123
	v_min_u32_e32 v116, v116, v123
	v_max_u32_e32 v122, v0, v124
	v_min_u32_e32 v0, v0, v124
	v_max_u32_e32 v123, v2, v115
	v_min_u32_e32 v2, v2, v115
	v_max_u32_e32 v115, v1, v118
	v_min_u32_e32 v1, v1, v118
	v_max_u32_e32 v118, v111, v114
	v_min_u32_e32 v111, v111, v114
	v_max_u32_e32 v114, v120, v119
	v_min_u32_e32 v119, v120, v119
	v_max_u32_e32 v120, v117, v3
	v_min_u32_e32 v3, v117, v3
	v_max_u32_e32 v117, v121, v110
	v_min_u32_e32 v110, v121, v110
	v_max_u32_e32 v121, v112, v118
	v_min_u32_e32 v112, v112, v118
	v_max_u32_e32 v118, v122, v114
	v_min_u32_e32 v114, v122, v114
	v_max_u32_e32 v122, v123, v120
	v_min_u32_e32 v120, v123, v120
	v_max_u32_e32 v123, v115, v117
	v_min_u32_e32 v115, v115, v117
	v_max_u32_e32 v117, v116, v111
	v_min_u32_e32 v111, v116, v111
	v_max_u32_e32 v116, v0, v119
	v_min_u32_e32 v0, v0, v119
	v_max_u32_e32 v119, v2, v3
	v_min_u32_e32 v2, v2, v3
	v_max_u32_e32 v3, v1, v110
	v_min_u32_e32 v1, v1, v110
	v_max_u32_e32 v110, v121, v122
	v_min_u32_e32 v121, v121, v122
	v_max_u32_e32 v122, v118, v123
	v_min_u32_e32 v118, v118, v123
	v_max_u32_e32 v123, v112, v120
	v_min_u32_e32 v112, v112, v120
	v_max_u32_e32 v120, v114, v115
	v_min_u32_e32 v114, v114, v115
	v_max_u32_e32 v115, v117, v119
	v_min_u32_e32 v117, v117, v119
	v_max_u32_e32 v119, v116, v3
	v_min_u32_e32 v3, v116, v3
	v_max_u32_e32 v116, v111, v2
	v_min_u32_e32 v2, v111, v2
	v_max_u32_e32 v111, v0, v1
	v_min_u32_e32 v0, v0, v1
	v_max_u32_e32 v1, v110, v122
	v_min_u32_e32 v110, v110, v122
	v_max_u32_e32 v122, v121, v118
	v_min_u32_e32 v118, v121, v118
	v_max_u32_e32 v121, v123, v120
	v_min_u32_e32 v120, v123, v120
	v_max_u32_e32 v123, v112, v114
	v_min_u32_e32 v112, v112, v114
	v_max_u32_e32 v114, v115, v119
	v_min_u32_e32 v115, v115, v119
	v_max_u32_e32 v119, v117, v3
	v_min_u32_e32 v3, v117, v3
	v_max_u32_e32 v117, v116, v111
	v_min_u32_e32 v111, v116, v111
	v_max_u32_e32 v116, v2, v0
	v_min_u32_e32 v0, v2, v0
	ds_bpermute_b32 v2, v27, v1
	ds_bpermute_b32 v124, v27, v110
	ds_bpermute_b32 v125, v27, v122
	ds_bpermute_b32 v126, v27, v118
	ds_bpermute_b32 v127, v27, v121
	ds_bpermute_b32 v128, v27, v120
	ds_bpermute_b32 v129, v27, v123
	ds_bpermute_b32 v130, v27, v112
	ds_bpermute_b32 v131, v27, v114
	ds_bpermute_b32 v132, v27, v115
	ds_bpermute_b32 v133, v27, v119
	ds_bpermute_b32 v134, v27, v0
	ds_bpermute_b32 v135, v27, v116
	ds_bpermute_b32 v136, v27, v111
	ds_bpermute_b32 v137, v27, v117
	ds_bpermute_b32 v138, v27, v3
	s_waitcnt lgkmcnt(4)
; __device__ __forceinline__ void peer_tile(const Args& A, LAS unsigned char* lds, int tile) {
;     ...
;                 { const bf16_t* sp = QRY + m * 2048 + hp * 128 + 32 * g;
;                   const u32x4 s0 = *(const u32x4*)sp, s1 = *(const u32x4*)(sp + 8), s2 = *(const u32x4*)(sp + 16), s3 = *(const u32x4*)(sp + 24);
;     ...
;                 sort16_desc(k0); sort16_desc(k1); merge16(k0, k1);
; #pragma unroll
;                 for (int msk = 16; msk <= 32; msk <<= 1) {
; #pragma unroll
;                     for (int i = 0; i < 16; ++i) k1[i] = (unsigned)__shfl_xor((int)k0[i], msk);
;                     merge16(k0, k1); }
	v_max_u32_e32 v1, v1, v134
	s_waitcnt lgkmcnt(3)
	v_max_u32_e32 v110, v110, v135
	s_waitcnt lgkmcnt(2)
	v_max_u32_e32 v122, v122, v136
	s_waitcnt lgkmcnt(1)
	v_max_u32_e32 v118, v118, v137
	s_waitcnt lgkmcnt(0)
	v_max_u32_e32 v121, v121, v138
	v_max_u32_e32 v120, v120, v133
	v_max_u32_e32 v123, v123, v132
	v_max_u32_e32 v112, v112, v131
	v_max_u32_e32 v114, v114, v130
	v_max_u32_e32 v115, v115, v129
	v_max_u32_e32 v119, v119, v128
	v_max_u32_e32 v3, v3, v127
	v_max_u32_e32 v117, v117, v126
	v_max_u32_e32 v111, v111, v125
	v_max_u32_e32 v116, v116, v124
	v_max_u32_e32 v0, v0, v2
	v_max_u32_e32 v2, v1, v114
	v_min_u32_e32 v1, v1, v114
	v_max_u32_e32 v114, v110, v115
	v_min_u32_e32 v110, v110, v115
	v_max_u32_e32 v115, v122, v119
	v_min_u32_e32 v119, v122, v119
	v_max_u32_e32 v122, v118, v3
	v_min_u32_e32 v3, v118, v3
	v_max_u32_e32 v118, v121, v117
	v_min_u32_e32 v117, v121, v117
	v_max_u32_e32 v121, v120, v111
	v_min_u32_e32 v111, v120, v111
	v_max_u32_e32 v120, v123, v116
	v_min_u32_e32 v116, v123, v116
	v_max_u32_e32 v123, v112, v0
	v_min_u32_e32 v0, v112, v0
	v_max_u32_e32 v112, v2, v118
	v_min_u32_e32 v2, v2, v118
	v_max_u32_e32 v118, v114, v121
	v_min_u32_e32 v114, v114, v121
	v_max_u32_e32 v121, v115, v120
	v_min_u32_e32 v115, v115, v120
	v_max_u32_e32 v120, v122, v123
	v_min_u32_e32 v122, v122, v123
	v_max_u32_e32 v123, v1, v117
	v_min_u32_e32 v1, v1, v117
	v_max_u32_e32 v117, v110, v111
	v_min_u32_e32 v110, v110, v111
	v_max_u32_e32 v111, v119, v116
	v_min_u32_e32 v116, v119, v116
	v_max_u32_e32 v119, v3, v0
	v_min_u32_e32 v0, v3, v0
	v_max_u32_e32 v3, v112, v121
	v_min_u32_e32 v112, v112, v121
	v_max_u32_e32 v121, v118, v120
	v_min_u32_e32 v118, v118, v120
	v_max_u32_e32 v120, v2, v115
	v_min_u32_e32 v2, v2, v115
	v_max_u32_e32 v115, v114, v122
	v_min_u32_e32 v114, v114, v122
	v_max_u32_e32 v122, v123, v111
	v_min_u32_e32 v111, v123, v111
	v_max_u32_e32 v123, v117, v119
	v_min_u32_e32 v117, v117, v119
	v_max_u32_e32 v119, v1, v116
	v_min_u32_e32 v1, v1, v116
	v_max_u32_e32 v116, v110, v0
	v_min_u32_e32 v0, v110, v0
	v_max_u32_e32 v110, v3, v121
	v_min_u32_e32 v3, v3, v121
	v_max_u32_e32 v121, v112, v118
	v_min_u32_e32 v112, v112, v118
	v_max_u32_e32 v118, v120, v115
	v_min_u32_e32 v115, v120, v115
	v_max_u32_e32 v120, v2, v114
	v_min_u32_e32 v2, v2, v114
	v_max_u32_e32 v114, v122, v123
	v_min_u32_e32 v122, v122, v123
	v_max_u32_e32 v123, v111, v117
	v_min_u32_e32 v111, v111, v117
	v_max_u32_e32 v117, v119, v116
	v_min_u32_e32 v116, v119, v116
	v_max_u32_e32 v119, v1, v0
	v_min_u32_e32 v0, v1, v0
	ds_bpermute_b32 v128, v29, v0
	ds_bpermute_b32 v1, v29, v110
	ds_bpermute_b32 v124, v29, v3
	ds_bpermute_b32 v125, v29, v121
	ds_bpermute_b32 v126, v29, v112
	s_waitcnt lgkmcnt(4)
	v_max_u32_e32 v110, v110, v128
	global_load_dwordx4 v[128:131], v[4:5], off offset:1552
	global_load_dwordx4 v[132:135], v[4:5], off offset:1536
	ds_bpermute_b32 v127, v29, v118
	ds_bpermute_b32 v136, v29, v115
	ds_bpermute_b32 v137, v29, v120
	ds_bpermute_b32 v138, v29, v2
	ds_bpermute_b32 v139, v29, v114
	ds_bpermute_b32 v140, v29, v122
	ds_bpermute_b32 v141, v29, v123
	ds_bpermute_b32 v142, v29, v111
	ds_bpermute_b32 v143, v29, v117
	ds_bpermute_b32 v144, v29, v119
	ds_bpermute_b32 v145, v29, v116
	s_waitcnt lgkmcnt(4)
	v_max_u32_e32 v115, v115, v141
	s_waitcnt lgkmcnt(3)
	v_max_u32_e32 v118, v118, v142
	s_waitcnt lgkmcnt(2)
	v_max_u32_e32 v112, v112, v143
	s_waitcnt lgkmcnt(1)
	v_max_u32_e32 v3, v3, v144
	s_waitcnt lgkmcnt(0)
	v_max_u32_e32 v121, v121, v145
	v_max_u32_e32 v120, v120, v140
	v_max_u32_e32 v2, v2, v139
	v_max_u32_e32 v114, v114, v138
	v_max_u32_e32 v122, v122, v137
	v_max_u32_e32 v123, v123, v136
	v_max_u32_e32 v111, v111, v127
	v_max_u32_e32 v117, v117, v126
	v_max_u32_e32 v116, v116, v125
	v_max_u32_e32 v119, v119, v124
	v_max_u32_e32 v0, v0, v1
	v_max_u32_e32 v1, v110, v114
	v_min_u32_e32 v110, v110, v114
	v_max_u32_e32 v114, v3, v122
	v_min_u32_e32 v3, v3, v122
	v_max_u32_e32 v122, v121, v123
	v_min_u32_e32 v121, v121, v123
	v_max_u32_e32 v123, v112, v111
	v_min_u32_e32 v111, v112, v111
	v_max_u32_e32 v112, v118, v117
	v_min_u32_e32 v117, v118, v117
	v_max_u32_e32 v118, v115, v116
	v_min_u32_e32 v115, v115, v116
	v_max_u32_e32 v116, v120, v119
	v_min_u32_e32 v119, v120, v119
	v_max_u32_e32 v120, v2, v0
	v_min_u32_e32 v0, v2, v0
	v_max_u32_e32 v2, v1, v112
	v_min_u32_e32 v1, v1, v112
	v_max_u32_e32 v112, v114, v118
	v_min_u32_e32 v114, v114, v118
	v_max_u32_e32 v118, v122, v116
	v_min_u32_e32 v116, v122, v116
	v_max_u32_e32 v122, v123, v120
	v_min_u32_e32 v120, v123, v120
	v_max_u32_e32 v123, v110, v117
	v_min_u32_e32 v110, v110, v117
	v_max_u32_e32 v117, v3, v115
	v_min_u32_e32 v3, v3, v115
	v_max_u32_e32 v115, v121, v119
	v_min_u32_e32 v119, v121, v119
	v_max_u32_e32 v121, v111, v0
	v_min_u32_e32 v0, v111, v0
	v_max_u32_e32 v111, v2, v118
	v_min_u32_e32 v2, v2, v118
	v_max_u32_e32 v118, v112, v122
	v_min_u32_e32 v112, v112, v122
	v_max_u32_e32 v127, v1, v116
	v_min_u32_e32 v1, v1, v116
	v_max_u32_e32 v116, v114, v120
	v_min_u32_e32 v114, v114, v120
	v_max_u32_e32 v136, v123, v115
	v_min_u32_e32 v115, v123, v115
	v_max_u32_e32 v137, v117, v121
	v_min_u32_e32 v138, v117, v121
	v_max_u32_e32 v139, v110, v119
	v_min_u32_e32 v110, v110, v119
	v_max_u32_e32 v140, v3, v0
	v_min_u32_e32 v0, v3, v0
	v_max_u32_e32 v126, v111, v118
	v_min_u32_e32 v125, v111, v118
	v_max_u32_e32 v124, v2, v112
	v_min_u32_e32 v123, v2, v112
	v_max_u32_e32 v122, v127, v116
	v_min_u32_e32 v121, v127, v116
	v_max_u32_e32 v120, v1, v114
	v_min_u32_e32 v119, v1, v114
	v_max_u32_e32 v118, v136, v137
	v_min_u32_e32 v117, v136, v137
	v_max_u32_e32 v116, v115, v138
	v_min_u32_e32 v115, v115, v138
	v_max_u32_e32 v114, v139, v140
	v_min_u32_e32 v112, v139, v140
	v_max_u32_e32 v111, v110, v0
	v_min_u32_e32 v110, v110, v0
	global_load_dwordx4 v[0:3], v[4:5], off offset:1584
	global_load_dwordx4 v[136:139], v[4:5], off offset:1568
	s_waitcnt vmcnt(2)
; __device__ __forceinline__ unsigned f2key(float f) { const unsigned u = __float_as_uint(f); return (u & 0x80000000u) ? ~u : (u | 0x80000000u); }
; __device__ __forceinline__ void peer_tile(const Args& A, LAS unsigned char* lds, int tile) {
;     ...
;                   for (int i = 0; i < 16; ++i) {
;                       const float lo = (float)__builtin_bit_cast(_Float16, (unsigned short)(sw[i] & 0xffffu)), hi = (float)__builtin_bit_cast(_Float16, (unsigned short)(sw[i] >> 16));
;                       const unsigned klo = (f2key(lo) & ~127u) | (unsigned)(127 - (32 * g + 2 * i)), khi = (f2key(hi) & ~127u) | (unsigned)(127 - (32 * g + 2 * i + 1));
;                       if (i < 8) { k0[2 * i] = klo; k0[2 * i + 1] = khi; } else { k1[2 * (i - 8)] = klo; k1[2 * (i - 8) + 1] = khi; } } }
	v_cvt_f32_f16_sdwa v127, v132 dst_sel:DWORD dst_unused:UNUSED_PAD src0_sel:WORD_1
	v_cvt_f32_f16_e32 v132, v132
	v_not_b32_e32 v140, v127
	v_or_b32_e32 v141, 0x80000000, v127
	v_cmp_gt_i32_e32 vcc, 0, v127
	s_nop 1
	v_cndmask_b32_e32 v127, v141, v140, vcc
	v_not_b32_e32 v140, v132
	v_or_b32_e32 v141, 0x80000000, v132
	v_cmp_gt_i32_e32 vcc, 0, v132
	v_and_b32_e32 v127, 0xffffff80, v127
	v_sub_u32_e32 v127, v127, v15
	v_cndmask_b32_e32 v132, v141, v140, vcc
	v_cvt_f32_f16_sdwa v140, v133 dst_sel:DWORD dst_unused:UNUSED_PAD src0_sel:WORD_1
	v_cvt_f32_f16_e32 v133, v133
	v_and_b32_e32 v132, 0xffffff80, v132
	v_sub_u32_e32 v132, v132, v15
	v_not_b32_e32 v141, v140
	v_or_b32_e32 v142, 0x80000000, v140
	v_cmp_gt_i32_e32 vcc, 0, v140
	v_add_u32_e32 v127, 0x7e, v127
	v_add_u32_e32 v132, 0x7f, v132
	v_cndmask_b32_e32 v140, v142, v141, vcc
	v_not_b32_e32 v141, v133
	v_or_b32_e32 v142, 0x80000000, v133
	v_cmp_gt_i32_e32 vcc, 0, v133
	v_and_b32_e32 v140, 0xffffff80, v140
	v_sub_u32_e32 v140, v140, v14
	v_cndmask_b32_e32 v133, v142, v141, vcc
	v_cvt_f32_f16_sdwa v141, v134 dst_sel:DWORD dst_unused:UNUSED_PAD src0_sel:WORD_1
	v_cvt_f32_f16_e32 v134, v134
	v_and_b32_e32 v133, 0xffffff80, v133
	v_sub_u32_e32 v133, v133, v14
	v_not_b32_e32 v142, v141
	v_or_b32_e32 v143, 0x80000000, v141
	v_cmp_gt_i32_e32 vcc, 0, v141
	v_add_u32_e32 v140, 0x7e, v140
	v_add_u32_e32 v133, 0x7f, v133
	v_cndmask_b32_e32 v141, v143, v142, vcc
	v_not_b32_e32 v142, v134
	v_or_b32_e32 v143, 0x80000000, v134
	v_cmp_gt_i32_e32 vcc, 0, v134
	v_and_b32_e32 v141, 0xffffff80, v141
	v_sub_u32_e32 v141, v141, v12
	v_cndmask_b32_e32 v134, v143, v142, vcc
	v_cvt_f32_f16_sdwa v142, v135 dst_sel:DWORD dst_unused:UNUSED_PAD src0_sel:WORD_1
	v_cvt_f32_f16_e32 v135, v135
	v_and_b32_e32 v134, 0xffffff80, v134
	v_sub_u32_e32 v134, v134, v12
	v_not_b32_e32 v143, v142
	v_or_b32_e32 v144, 0x80000000, v142
	v_cmp_gt_i32_e32 vcc, 0, v142
	v_add_u32_e32 v141, 0x7e, v141
	v_add_u32_e32 v134, 0x7f, v134
	v_cndmask_b32_e32 v142, v144, v143, vcc
	v_not_b32_e32 v143, v135
	v_or_b32_e32 v144, 0x80000000, v135
	v_cmp_gt_i32_e32 vcc, 0, v135
	v_and_b32_e32 v142, 0xffffff80, v142
	v_sub_u32_e32 v142, v142, v10
	v_cndmask_b32_e32 v135, v144, v143, vcc
	v_cvt_f32_f16_sdwa v143, v128 dst_sel:DWORD dst_unused:UNUSED_PAD src0_sel:WORD_1
	v_cvt_f32_f16_e32 v128, v128
	v_and_b32_e32 v135, 0xffffff80, v135
	v_sub_u32_e32 v135, v135, v10
	v_not_b32_e32 v144, v143
	v_or_b32_e32 v145, 0x80000000, v143
	v_cmp_gt_i32_e32 vcc, 0, v143
	v_add_u32_e32 v142, 0x7e, v142
	v_add_u32_e32 v135, 0x7f, v135
	v_cndmask_b32_e32 v143, v145, v144, vcc
	v_not_b32_e32 v144, v128
	v_or_b32_e32 v145, 0x80000000, v128
	v_cmp_gt_i32_e32 vcc, 0, v128
	v_and_b32_e32 v143, 0xffffff80, v143
	v_sub_u32_e32 v143, v143, v8
	v_cndmask_b32_e32 v128, v145, v144, vcc
	v_cvt_f32_f16_sdwa v144, v129 dst_sel:DWORD dst_unused:UNUSED_PAD src0_sel:WORD_1
	v_cvt_f32_f16_e32 v129, v129
	v_and_b32_e32 v128, 0xffffff80, v128
	v_sub_u32_e32 v128, v128, v8
	v_not_b32_e32 v145, v144
	v_or_b32_e32 v146, 0x80000000, v144
	v_cmp_gt_i32_e32 vcc, 0, v144
	v_add_u32_e32 v143, 0x7e, v143
	v_add_u32_e32 v128, 0x7f, v128
	v_cndmask_b32_e32 v144, v146, v145, vcc
	v_not_b32_e32 v145, v129
	v_or_b32_e32 v146, 0x80000000, v129
	v_cmp_gt_i32_e32 vcc, 0, v129
	v_and_b32_e32 v144, 0xffffff80, v144
	v_sub_u32_e32 v144, v144, v16
	v_cndmask_b32_e32 v129, v146, v145, vcc
	v_cvt_f32_f16_sdwa v145, v130 dst_sel:DWORD dst_unused:UNUSED_PAD src0_sel:WORD_1
	v_cvt_f32_f16_e32 v130, v130
	v_and_b32_e32 v129, 0xffffff80, v129
	v_sub_u32_e32 v129, v129, v16
	v_not_b32_e32 v146, v145
	v_or_b32_e32 v147, 0x80000000, v145
	v_cmp_gt_i32_e32 vcc, 0, v145
	v_add_u32_e32 v144, 0x7e, v144
	v_add_u32_e32 v129, 0x7f, v129
	v_cndmask_b32_e32 v145, v147, v146, vcc
	v_not_b32_e32 v146, v130
	v_or_b32_e32 v147, 0x80000000, v130
	v_cmp_gt_i32_e32 vcc, 0, v130
	v_and_b32_e32 v145, 0xffffff80, v145
	v_sub_u32_e32 v145, v145, v17
	v_cndmask_b32_e32 v130, v147, v146, vcc
	v_cvt_f32_f16_sdwa v146, v131 dst_sel:DWORD dst_unused:UNUSED_PAD src0_sel:WORD_1
	v_cvt_f32_f16_e32 v131, v131
	v_and_b32_e32 v130, 0xffffff80, v130
	v_sub_u32_e32 v130, v130, v17
	v_not_b32_e32 v147, v146
	v_or_b32_e32 v148, 0x80000000, v146
	v_cmp_gt_i32_e32 vcc, 0, v146
	v_add_u32_e32 v145, 0x7e, v145
	v_add_u32_e32 v130, 0x7f, v130
	v_cndmask_b32_e32 v146, v148, v147, vcc
	v_not_b32_e32 v147, v131
	v_or_b32_e32 v148, 0x80000000, v131
	v_cmp_gt_i32_e32 vcc, 0, v131
	v_and_b32_e32 v146, 0xffffff80, v146
	v_sub_u32_e32 v146, v146, v18
	v_cndmask_b32_e32 v131, v148, v147, vcc
	s_waitcnt vmcnt(0)
; __device__ __forceinline__ unsigned f2key(float f) { const unsigned u = __float_as_uint(f); return (u & 0x80000000u) ? ~u : (u | 0x80000000u); }
; #define CE_DESC(a, b) do { const unsigned _mx = (a) > (b) ? (a) : (b), _mn = (a) > (b) ? (b) : (a); (a) = _mx; (b) = _mn; } while (0)
; __device__ __forceinline__ void sort16_desc(unsigned (&k)[16]) {
; #pragma unroll
;     for (int size = 2; size <= 16; size <<= 1)
; #pragma unroll
;         for (int stride = size >> 1; stride > 0; stride >>= 1)
; #pragma unroll
;             for (int i = 0; i < 16; ++i) { const int j = i ^ stride;
;                 if (j > i) { if ((i & size) == 0) CE_DESC(k[i], k[j]); else CE_DESC(k[j], k[i]); } }
; }
; __device__ __forceinline__ void peer_tile(const Args& A, LAS unsigned char* lds, int tile) {
;     ...
;                   for (int i = 0; i < 16; ++i) {
;                       const float lo = (float)__builtin_bit_cast(_Float16, (unsigned short)(sw[i] & 0xffffu)), hi = (float)__builtin_bit_cast(_Float16, (unsigned short)(sw[i] >> 16));
;                       const unsigned klo = (f2key(lo) & ~127u) | (unsigned)(127 - (32 * g + 2 * i)), khi = (f2key(hi) & ~127u) | (unsigned)(127 - (32 * g + 2 * i + 1));
;                       if (i < 8) { k0[2 * i] = klo; k0[2 * i + 1] = khi; } else { k1[2 * (i - 8)] = klo; k1[2 * (i - 8) + 1] = khi; } } }
	v_cvt_f32_f16_sdwa v147, v136 dst_sel:DWORD dst_unused:UNUSED_PAD src0_sel:WORD_1
	v_cvt_f32_f16_e32 v136, v136
	v_and_b32_e32 v131, 0xffffff80, v131
	v_sub_u32_e32 v131, v131, v18
	v_not_b32_e32 v148, v147
	v_or_b32_e32 v149, 0x80000000, v147
	v_cmp_gt_i32_e32 vcc, 0, v147
	v_add_u32_e32 v146, 0x7e, v146
	v_add_u32_e32 v131, 0x7f, v131
	v_cndmask_b32_e32 v147, v149, v148, vcc
	v_not_b32_e32 v148, v136
	v_or_b32_e32 v149, 0x80000000, v136
	v_cmp_gt_i32_e32 vcc, 0, v136
	v_and_b32_e32 v147, 0xffffff80, v147
	v_sub_u32_e32 v147, v147, v20
	v_cndmask_b32_e32 v136, v149, v148, vcc
	v_cvt_f32_f16_sdwa v148, v137 dst_sel:DWORD dst_unused:UNUSED_PAD src0_sel:WORD_1
	v_cvt_f32_f16_e32 v137, v137
	v_and_b32_e32 v136, 0xffffff80, v136
	v_sub_u32_e32 v136, v136, v20
	v_not_b32_e32 v149, v148
	v_or_b32_e32 v150, 0x80000000, v148
	v_cmp_gt_i32_e32 vcc, 0, v148
	v_add_u32_e32 v147, 0x7e, v147
	v_add_u32_e32 v136, 0x7f, v136
	v_cndmask_b32_e32 v148, v150, v149, vcc
	v_not_b32_e32 v149, v137
	v_or_b32_e32 v150, 0x80000000, v137
	v_cmp_gt_i32_e32 vcc, 0, v137
	v_and_b32_e32 v148, 0xffffff80, v148
	v_sub_u32_e32 v148, v148, v21
	v_cndmask_b32_e32 v137, v150, v149, vcc
	v_cvt_f32_f16_sdwa v149, v138 dst_sel:DWORD dst_unused:UNUSED_PAD src0_sel:WORD_1
	v_cvt_f32_f16_e32 v138, v138
	v_and_b32_e32 v137, 0xffffff80, v137
	v_sub_u32_e32 v137, v137, v21
	v_not_b32_e32 v150, v149
	v_or_b32_e32 v151, 0x80000000, v149
	v_cmp_gt_i32_e32 vcc, 0, v149
	v_add_u32_e32 v148, 0x7e, v148
	v_add_u32_e32 v137, 0x7f, v137
	v_cndmask_b32_e32 v149, v151, v150, vcc
	v_not_b32_e32 v150, v138
	v_or_b32_e32 v151, 0x80000000, v138
	v_cmp_gt_i32_e32 vcc, 0, v138
	v_and_b32_e32 v149, 0xffffff80, v149
	v_sub_u32_e32 v149, v149, v22
	v_cndmask_b32_e32 v138, v151, v150, vcc
	v_cvt_f32_f16_sdwa v150, v139 dst_sel:DWORD dst_unused:UNUSED_PAD src0_sel:WORD_1
	v_cvt_f32_f16_e32 v139, v139
	v_and_b32_e32 v138, 0xffffff80, v138
	v_sub_u32_e32 v138, v138, v22
	v_not_b32_e32 v151, v150
	v_or_b32_e32 v152, 0x80000000, v150
	v_cmp_gt_i32_e32 vcc, 0, v150
	v_add_u32_e32 v149, 0x7e, v149
	v_add_u32_e32 v138, 0x7f, v138
	v_cndmask_b32_e32 v150, v152, v151, vcc
	v_not_b32_e32 v151, v139
	v_or_b32_e32 v152, 0x80000000, v139
	v_cmp_gt_i32_e32 vcc, 0, v139
	v_and_b32_e32 v150, 0xffffff80, v150
	v_sub_u32_e32 v150, v150, v23
	v_cndmask_b32_e32 v139, v152, v151, vcc
	v_cvt_f32_f16_sdwa v151, v0 dst_sel:DWORD dst_unused:UNUSED_PAD src0_sel:WORD_1
	v_cvt_f32_f16_e32 v0, v0
	v_and_b32_e32 v139, 0xffffff80, v139
	v_sub_u32_e32 v139, v139, v23
	v_not_b32_e32 v152, v151
	v_or_b32_e32 v153, 0x80000000, v151
	v_cmp_gt_i32_e32 vcc, 0, v151
	v_add_u32_e32 v150, 0x7e, v150
	v_add_u32_e32 v139, 0x7f, v139
	v_cndmask_b32_e32 v151, v153, v152, vcc
	v_not_b32_e32 v152, v0
	v_or_b32_e32 v153, 0x80000000, v0
	v_cmp_gt_i32_e32 vcc, 0, v0
	v_and_b32_e32 v151, 0xffffff80, v151
	v_sub_u32_e32 v151, v151, v24
	v_cndmask_b32_e32 v0, v153, v152, vcc
	v_cvt_f32_f16_sdwa v152, v1 dst_sel:DWORD dst_unused:UNUSED_PAD src0_sel:WORD_1
	v_cvt_f32_f16_e32 v1, v1
	v_and_b32_e32 v0, 0xffffff80, v0
	v_sub_u32_e32 v0, v0, v24
	v_not_b32_e32 v153, v152
	v_or_b32_e32 v154, 0x80000000, v152
	v_cmp_gt_i32_e32 vcc, 0, v152
	v_add_u32_e32 v151, 0x7e, v151
	v_add_u32_e32 v0, 0x7f, v0
	v_cndmask_b32_e32 v152, v154, v153, vcc
	v_not_b32_e32 v153, v1
	v_or_b32_e32 v154, 0x80000000, v1
	v_cmp_gt_i32_e32 vcc, 0, v1
	v_and_b32_e32 v152, 0xffffff80, v152
	v_sub_u32_e32 v152, v152, v25
	v_cndmask_b32_e32 v1, v154, v153, vcc
	v_cvt_f32_f16_sdwa v153, v2 dst_sel:DWORD dst_unused:UNUSED_PAD src0_sel:WORD_1
	v_cvt_f32_f16_e32 v2, v2
	v_and_b32_e32 v1, 0xffffff80, v1
	v_sub_u32_e32 v1, v1, v25
	v_not_b32_e32 v154, v153
	v_or_b32_e32 v155, 0x80000000, v153
	v_cmp_gt_i32_e32 vcc, 0, v153
	v_add_u32_e32 v152, 0x7e, v152
	v_add_u32_e32 v1, 0x7f, v1
	v_cndmask_b32_e32 v153, v155, v154, vcc
	v_not_b32_e32 v154, v2
	v_or_b32_e32 v155, 0x80000000, v2
	v_cmp_gt_i32_e32 vcc, 0, v2
	v_and_b32_e32 v153, 0xffffff80, v153
	v_sub_u32_e32 v153, v153, v26
	v_cndmask_b32_e32 v2, v155, v154, vcc
	v_cvt_f32_f16_sdwa v154, v3 dst_sel:DWORD dst_unused:UNUSED_PAD src0_sel:WORD_1
	v_cvt_f32_f16_e32 v3, v3
	v_and_b32_e32 v2, 0xffffff80, v2
	v_sub_u32_e32 v2, v2, v26
	v_not_b32_e32 v155, v154
	v_or_b32_e32 v156, 0x80000000, v154
	v_cmp_gt_i32_e32 vcc, 0, v154
	v_add_u32_e32 v153, 0x7e, v153
	v_add_u32_e32 v2, 0x7f, v2
	v_cndmask_b32_e32 v154, v156, v155, vcc
	v_not_b32_e32 v155, v3
	v_or_b32_e32 v156, 0x80000000, v3
	v_cmp_gt_i32_e32 vcc, 0, v3
	v_and_b32_e32 v154, 0xffffff80, v154
	v_sub_u32_e32 v154, v154, v28
	v_cndmask_b32_e32 v3, v156, v155, vcc
	v_and_b32_e32 v3, 0xffffff80, v3
	v_sub_u32_e32 v3, v3, v28
	v_add_u32_e32 v154, 0x7e, v154
	v_add_u32_e32 v3, 0x7f, v3
	v_max_u32_e32 v155, v132, v127
	v_min_u32_e32 v127, v132, v127
	v_max_u32_e32 v132, v140, v133
	v_min_u32_e32 v133, v140, v133
	v_max_u32_e32 v140, v134, v141
	v_min_u32_e32 v134, v134, v141
	v_max_u32_e32 v141, v142, v135
	v_min_u32_e32 v135, v142, v135
	v_max_u32_e32 v142, v128, v143
	v_min_u32_e32 v128, v128, v143
	v_max_u32_e32 v143, v144, v129
	v_min_u32_e32 v129, v144, v129
	v_max_u32_e32 v144, v130, v145
	v_min_u32_e32 v130, v130, v145
	v_max_u32_e32 v145, v146, v131
	v_min_u32_e32 v131, v146, v131
	v_max_u32_e32 v163, v136, v147
	v_min_u32_e32 v136, v136, v147
	v_max_u32_e32 v147, v148, v137
	v_min_u32_e32 v137, v148, v137
	v_max_u32_e32 v148, v138, v149
	v_min_u32_e32 v138, v138, v149
	v_max_u32_e32 v149, v150, v139
	v_min_u32_e32 v139, v150, v139
	v_max_u32_e32 v150, v0, v151
	v_min_u32_e32 v0, v0, v151
	v_max_u32_e32 v151, v152, v1
	v_min_u32_e32 v1, v152, v1
	v_max_u32_e32 v152, v2, v153
	v_min_u32_e32 v2, v2, v153
; #define CE_DESC(a, b) do { const unsigned _mx = (a) > (b) ? (a) : (b), _mn = (a) > (b) ? (b) : (a); (a) = _mx; (b) = _mn; } while (0)
; __device__ __forceinline__ void sort16_desc(unsigned (&k)[16]) {
; #pragma unroll
;     for (int size = 2; size <= 16; size <<= 1)
; #pragma unroll
;         for (int stride = size >> 1; stride > 0; stride >>= 1)
; #pragma unroll
;             for (int i = 0; i < 16; ++i) { const int j = i ^ stride;
;                 if (j > i) { if ((i & size) == 0) CE_DESC(k[i], k[j]); else CE_DESC(k[j], k[i]); } }
; }
; __device__ __forceinline__ void merge16(unsigned (&a)[16], const unsigned (&b)[16]) {
; #pragma unroll
;     for (int i = 0; i < 16; ++i) a[i] = a[i] > b[15 - i] ? a[i] : b[15 - i];
; #pragma unroll
;     for (int stride = 8; stride > 0; stride >>= 1)
; #pragma unroll
;         for (int i = 0; i < 16; ++i) { const int j = i ^ stride; if (j > i) CE_DESC(a[i], a[j]); }
; }
; __device__ __forceinline__ void peer_tile(const Args& A, LAS unsigned char* lds, int tile) {
;     ...
;                 sort16_desc(k0); sort16_desc(k1); merge16(k0, k1);
; #pragma unroll
;                 for (int msk = 16; msk <= 32; msk <<= 1) {
; #pragma unroll
;                     for (int i = 0; i < 16; ++i) k1[i] = (unsigned)__shfl_xor((int)k0[i], msk);
;                     merge16(k0, k1); }
	v_max_u32_e32 v153, v154, v3
	v_min_u32_e32 v3, v154, v3
	v_max_u32_e32 v146, v155, v133
	v_min_u32_e32 v133, v155, v133
	v_max_u32_e32 v155, v127, v132
	v_min_u32_e32 v127, v127, v132
	v_max_u32_e32 v132, v135, v140
	v_min_u32_e32 v135, v135, v140
	v_max_u32_e32 v140, v141, v134
	v_min_u32_e32 v134, v141, v134
	v_max_u32_e32 v141, v142, v129
	v_min_u32_e32 v129, v142, v129
	v_max_u32_e32 v142, v128, v143
	v_min_u32_e32 v128, v128, v143
	v_max_u32_e32 v143, v131, v144
	v_min_u32_e32 v131, v131, v144
	v_max_u32_e32 v144, v145, v130
	v_min_u32_e32 v130, v145, v130
	v_max_u32_e32 v154, v163, v137
	v_min_u32_e32 v137, v163, v137
	v_max_u32_e32 v163, v136, v147
	v_min_u32_e32 v136, v136, v147
	v_max_u32_e32 v147, v139, v148
	v_min_u32_e32 v139, v139, v148
	v_max_u32_e32 v148, v149, v138
	v_min_u32_e32 v138, v149, v138
	v_max_u32_e32 v149, v150, v1
	v_min_u32_e32 v1, v150, v1
	v_max_u32_e32 v150, v0, v151
	v_min_u32_e32 v0, v0, v151
	v_max_u32_e32 v151, v3, v152
	v_min_u32_e32 v3, v3, v152
	v_max_u32_e32 v152, v153, v2
	v_min_u32_e32 v2, v153, v2
	v_max_u32_e32 v145, v146, v155
	v_min_u32_e32 v146, v146, v155
	v_max_u32_e32 v155, v133, v127
	v_min_u32_e32 v127, v133, v127
	v_max_u32_e32 v133, v134, v135
	v_min_u32_e32 v134, v134, v135
	v_max_u32_e32 v135, v140, v132
	v_min_u32_e32 v132, v140, v132
	v_max_u32_e32 v140, v141, v142
	v_min_u32_e32 v141, v141, v142
	v_max_u32_e32 v142, v129, v128
	v_min_u32_e32 v128, v129, v128
	v_max_u32_e32 v129, v130, v131
	v_min_u32_e32 v130, v130, v131
	v_max_u32_e32 v131, v144, v143
	v_min_u32_e32 v143, v144, v143
	v_max_u32_e32 v153, v154, v163
	v_min_u32_e32 v154, v154, v163
	v_max_u32_e32 v163, v137, v136
	v_min_u32_e32 v136, v137, v136
	v_max_u32_e32 v137, v138, v139
	v_min_u32_e32 v138, v138, v139
	v_max_u32_e32 v139, v148, v147
	v_min_u32_e32 v147, v148, v147
	v_max_u32_e32 v148, v149, v150
	v_min_u32_e32 v149, v149, v150
	v_max_u32_e32 v150, v1, v0
	v_min_u32_e32 v0, v1, v0
	v_max_u32_e32 v1, v2, v3
	v_min_u32_e32 v2, v2, v3
	v_max_u32_e32 v3, v152, v151
	v_min_u32_e32 v151, v152, v151
	v_max_u32_e32 v144, v145, v134
	v_min_u32_e32 v134, v145, v134
	v_max_u32_e32 v145, v146, v133
	v_min_u32_e32 v133, v146, v133
	v_max_u32_e32 v146, v155, v132
	v_min_u32_e32 v132, v155, v132
	v_max_u32_e32 v155, v127, v135
	v_min_u32_e32 v127, v127, v135
	v_max_u32_e32 v135, v130, v140
	v_min_u32_e32 v130, v130, v140
	v_max_u32_e32 v140, v129, v141
	v_min_u32_e32 v129, v129, v141
	v_max_u32_e32 v141, v143, v142
	v_min_u32_e32 v142, v143, v142
	v_max_u32_e32 v143, v131, v128
	v_min_u32_e32 v128, v131, v128
	v_max_u32_e32 v152, v153, v138
	v_min_u32_e32 v138, v153, v138
	v_max_u32_e32 v153, v154, v137
	v_min_u32_e32 v137, v154, v137
	v_max_u32_e32 v154, v163, v147
	v_min_u32_e32 v147, v163, v147
	v_max_u32_e32 v163, v136, v139
	v_min_u32_e32 v136, v136, v139
	v_max_u32_e32 v139, v2, v148
	v_min_u32_e32 v2, v2, v148
	v_max_u32_e32 v148, v1, v149
	v_min_u32_e32 v1, v1, v149
	v_max_u32_e32 v149, v151, v150
	v_min_u32_e32 v150, v151, v150
	v_max_u32_e32 v151, v3, v0
	v_min_u32_e32 v0, v3, v0
	v_max_u32_e32 v131, v144, v146
	v_min_u32_e32 v144, v144, v146
	v_max_u32_e32 v146, v145, v155
	v_min_u32_e32 v145, v145, v155
	v_max_u32_e32 v155, v134, v132
	v_min_u32_e32 v132, v134, v132
	v_max_u32_e32 v134, v133, v127
	v_min_u32_e32 v127, v133, v127
	v_max_u32_e32 v133, v142, v130
	v_min_u32_e32 v130, v142, v130
	v_max_u32_e32 v142, v128, v129
	v_min_u32_e32 v128, v128, v129
	v_max_u32_e32 v129, v141, v135
	v_min_u32_e32 v135, v141, v135
	v_max_u32_e32 v141, v143, v140
	v_min_u32_e32 v140, v143, v140
	v_max_u32_e32 v3, v152, v154
	v_min_u32_e32 v152, v152, v154
	v_max_u32_e32 v154, v153, v163
	v_min_u32_e32 v153, v153, v163
	v_max_u32_e32 v163, v138, v147
	v_min_u32_e32 v138, v138, v147
	v_max_u32_e32 v147, v137, v136
	v_min_u32_e32 v136, v137, v136
	v_max_u32_e32 v137, v150, v2
	v_min_u32_e32 v2, v150, v2
	v_max_u32_e32 v150, v0, v1
	v_min_u32_e32 v0, v0, v1
	v_max_u32_e32 v1, v149, v139
	v_min_u32_e32 v139, v149, v139
	v_max_u32_e32 v149, v151, v148
	v_min_u32_e32 v148, v151, v148
	v_max_u32_e32 v143, v131, v146
	v_min_u32_e32 v131, v131, v146
	v_max_u32_e32 v146, v144, v145
	v_min_u32_e32 v144, v144, v145
	v_max_u32_e32 v145, v155, v134
	v_min_u32_e32 v134, v155, v134
	v_max_u32_e32 v155, v132, v127
	v_min_u32_e32 v127, v132, v127
	v_max_u32_e32 v132, v128, v130
	v_min_u32_e32 v128, v128, v130
	v_max_u32_e32 v130, v142, v133
	v_min_u32_e32 v133, v142, v133
	v_max_u32_e32 v142, v140, v135
	v_min_u32_e32 v135, v140, v135
	v_max_u32_e32 v140, v141, v129
	v_min_u32_e32 v129, v141, v129
	v_max_u32_e32 v151, v3, v154
	v_min_u32_e32 v3, v3, v154
	v_max_u32_e32 v154, v152, v153
	v_min_u32_e32 v152, v152, v153
	v_max_u32_e32 v153, v163, v147
	v_min_u32_e32 v147, v163, v147
	v_max_u32_e32 v163, v138, v136
	v_min_u32_e32 v136, v138, v136
	v_max_u32_e32 v138, v0, v2
	v_min_u32_e32 v0, v0, v2
	v_max_u32_e32 v2, v150, v137
	v_min_u32_e32 v137, v150, v137
	v_max_u32_e32 v150, v148, v139
	v_min_u32_e32 v139, v148, v139
	v_max_u32_e32 v148, v149, v1
	v_min_u32_e32 v1, v149, v1
	v_max_u32_e32 v141, v143, v128
	v_min_u32_e32 v128, v143, v128
	v_max_u32_e32 v143, v131, v132
	v_min_u32_e32 v131, v131, v132
	v_max_u32_e32 v132, v146, v133
	v_min_u32_e32 v133, v146, v133
	v_max_u32_e32 v146, v144, v130
	v_min_u32_e32 v130, v144, v130
	v_max_u32_e32 v144, v145, v135
	v_min_u32_e32 v135, v145, v135
	v_max_u32_e32 v145, v134, v142
	v_min_u32_e32 v134, v134, v142
	v_max_u32_e32 v142, v155, v129
	v_min_u32_e32 v129, v155, v129
	v_max_u32_e32 v155, v127, v140
	v_min_u32_e32 v127, v127, v140
	v_max_u32_e32 v149, v151, v0
	v_min_u32_e32 v0, v151, v0
; #define CE_DESC(a, b) do { const unsigned _mx = (a) > (b) ? (a) : (b), _mn = (a) > (b) ? (b) : (a); (a) = _mx; (b) = _mn; } while (0)
; __device__ __forceinline__ void sort16_desc(unsigned (&k)[16]) {
; #pragma unroll
;     for (int size = 2; size <= 16; size <<= 1)
; #pragma unroll
;         for (int stride = size >> 1; stride > 0; stride >>= 1)
; #pragma unroll
;             for (int i = 0; i < 16; ++i) { const int j = i ^ stride;
;                 if (j > i) { if ((i & size) == 0) CE_DESC(k[i], k[j]); else CE_DESC(k[j], k[i]); } }
; }
; __device__ __forceinline__ void merge16(unsigned (&a)[16], const unsigned (&b)[16]) {
; #pragma unroll
;     for (int i = 0; i < 16; ++i) a[i] = a[i] > b[15 - i] ? a[i] : b[15 - i];
; #pragma unroll
;     for (int stride = 8; stride > 0; stride >>= 1)
; #pragma unroll
;         for (int i = 0; i < 16; ++i) { const int j = i ^ stride; if (j > i) CE_DESC(a[i], a[j]); }
; }
; __device__ __forceinline__ void peer_tile(const Args& A, LAS unsigned char* lds, int tile) {
;     ...
;                 sort16_desc(k0); sort16_desc(k1); merge16(k0, k1);
; #pragma unroll
;                 for (int msk = 16; msk <= 32; msk <<= 1) {
; #pragma unroll
;                     for (int i = 0; i < 16; ++i) k1[i] = (unsigned)__shfl_xor((int)k0[i], msk);
;                     merge16(k0, k1); }
	v_max_u32_e32 v151, v3, v138
	v_min_u32_e32 v3, v3, v138
	v_max_u32_e32 v138, v154, v137
	v_min_u32_e32 v137, v154, v137
	v_max_u32_e32 v154, v152, v2
	v_min_u32_e32 v2, v152, v2
	v_max_u32_e32 v152, v153, v139
	v_min_u32_e32 v139, v153, v139
	v_max_u32_e32 v153, v147, v150
	v_min_u32_e32 v147, v147, v150
	v_max_u32_e32 v150, v163, v1
	v_min_u32_e32 v1, v163, v1
	v_max_u32_e32 v163, v136, v148
	v_min_u32_e32 v136, v136, v148
	v_max_u32_e32 v140, v141, v144
	v_min_u32_e32 v141, v141, v144
	v_max_u32_e32 v144, v143, v145
	v_min_u32_e32 v143, v143, v145
	v_max_u32_e32 v145, v132, v142
	v_min_u32_e32 v132, v132, v142
	v_max_u32_e32 v142, v146, v155
	v_min_u32_e32 v146, v146, v155
	v_max_u32_e32 v155, v128, v135
	v_min_u32_e32 v128, v128, v135
	v_max_u32_e32 v135, v131, v134
	v_min_u32_e32 v131, v131, v134
	v_max_u32_e32 v134, v133, v129
	v_min_u32_e32 v129, v133, v129
	v_max_u32_e32 v133, v130, v127
	v_min_u32_e32 v127, v130, v127
	v_max_u32_e32 v148, v149, v152
	v_min_u32_e32 v149, v149, v152
	v_max_u32_e32 v152, v151, v153
	v_min_u32_e32 v151, v151, v153
	v_max_u32_e32 v153, v138, v150
	v_min_u32_e32 v138, v138, v150
	v_max_u32_e32 v150, v154, v163
	v_min_u32_e32 v154, v154, v163
	v_max_u32_e32 v163, v0, v139
	v_min_u32_e32 v0, v0, v139
	v_max_u32_e32 v139, v3, v147
	v_min_u32_e32 v3, v3, v147
	v_max_u32_e32 v147, v137, v1
	v_min_u32_e32 v1, v137, v1
	v_max_u32_e32 v137, v2, v136
	v_min_u32_e32 v2, v2, v136
	v_max_u32_e32 v130, v140, v145
	v_min_u32_e32 v140, v140, v145
	v_max_u32_e32 v145, v144, v142
	v_min_u32_e32 v142, v144, v142
	v_max_u32_e32 v144, v141, v132
	v_min_u32_e32 v132, v141, v132
	v_max_u32_e32 v141, v143, v146
	v_min_u32_e32 v143, v143, v146
	v_max_u32_e32 v146, v155, v134
	v_min_u32_e32 v134, v155, v134
	v_max_u32_e32 v155, v135, v133
	v_min_u32_e32 v133, v135, v133
	v_max_u32_e32 v135, v128, v129
	v_min_u32_e32 v128, v128, v129
	v_max_u32_e32 v129, v131, v127
	v_min_u32_e32 v127, v131, v127
	v_max_u32_e32 v136, v148, v153
	v_min_u32_e32 v148, v148, v153
	v_max_u32_e32 v153, v152, v150
	v_min_u32_e32 v150, v152, v150
	v_max_u32_e32 v152, v149, v138
	v_min_u32_e32 v138, v149, v138
	v_max_u32_e32 v149, v151, v154
	v_min_u32_e32 v151, v151, v154
	v_max_u32_e32 v154, v163, v147
	v_min_u32_e32 v147, v163, v147
	v_max_u32_e32 v163, v139, v137
	v_min_u32_e32 v137, v139, v137
	v_max_u32_e32 v139, v0, v1
	v_min_u32_e32 v0, v0, v1
	v_max_u32_e32 v1, v3, v2
	v_min_u32_e32 v2, v3, v2
	v_min_u32_e32 v131, v130, v145
	v_min_u32_e32 v156, v140, v142
	v_min_u32_e32 v157, v144, v141
	v_min_u32_e32 v158, v132, v143
	v_min_u32_e32 v159, v146, v155
	v_min_u32_e32 v160, v134, v133
	v_min_u32_e32 v161, v135, v129
	v_min_u32_e32 v162, v128, v127
	v_min_u32_e32 v3, v136, v153
	v_min_u32_e32 v164, v148, v150
	v_min_u32_e32 v165, v152, v149
	v_min_u32_e32 v166, v138, v151
	v_min_u32_e32 v167, v154, v163
	v_min_u32_e32 v168, v147, v137
	v_min_u32_e32 v169, v139, v1
	v_min_u32_e32 v170, v0, v2
	v_max3_u32 v130, v130, v145, v170
	v_max3_u32 v0, v131, v0, v2
	v_max3_u32 v2, v140, v142, v169
	v_max3_u32 v1, v156, v139, v1
	v_max3_u32 v131, v144, v141, v168
	v_max3_u32 v137, v157, v147, v137
	v_max3_u32 v132, v132, v143, v167
	v_max3_u32 v139, v158, v154, v163
	v_max3_u32 v140, v146, v155, v166
	v_max3_u32 v138, v159, v138, v151
	v_max3_u32 v133, v134, v133, v165
	v_max3_u32 v134, v160, v152, v149
	v_max3_u32 v129, v135, v129, v164
	v_max3_u32 v135, v161, v148, v150
	v_max3_u32 v3, v128, v127, v3
	v_max3_u32 v127, v162, v136, v153
	v_max_u32_e32 v128, v130, v140
	v_min_u32_e32 v130, v130, v140
	v_max_u32_e32 v136, v0, v138
	v_min_u32_e32 v0, v0, v138
	v_max_u32_e32 v138, v2, v133
	v_min_u32_e32 v2, v2, v133
	v_max_u32_e32 v133, v1, v134
	v_min_u32_e32 v1, v1, v134
	v_max_u32_e32 v134, v131, v129
	v_min_u32_e32 v129, v131, v129
	v_max_u32_e32 v131, v137, v135
	v_min_u32_e32 v135, v137, v135
	v_max_u32_e32 v137, v132, v3
	v_min_u32_e32 v3, v132, v3
	v_max_u32_e32 v132, v139, v127
	v_min_u32_e32 v127, v139, v127
	v_max_u32_e32 v139, v128, v134
	v_min_u32_e32 v128, v128, v134
	v_max_u32_e32 v134, v136, v131
	v_min_u32_e32 v131, v136, v131
	v_max_u32_e32 v136, v138, v137
	v_min_u32_e32 v137, v138, v137
	v_max_u32_e32 v138, v133, v132
	v_min_u32_e32 v132, v133, v132
	v_max_u32_e32 v133, v130, v129
	v_min_u32_e32 v129, v130, v129
	v_max_u32_e32 v130, v0, v135
	v_min_u32_e32 v0, v0, v135
	v_max_u32_e32 v135, v2, v3
	v_min_u32_e32 v2, v2, v3
	v_max_u32_e32 v3, v1, v127
	v_min_u32_e32 v1, v1, v127
	v_max_u32_e32 v127, v139, v136
	v_min_u32_e32 v136, v139, v136
	v_max_u32_e32 v139, v134, v138
	v_min_u32_e32 v134, v134, v138
	v_max_u32_e32 v138, v128, v137
	v_min_u32_e32 v128, v128, v137
	v_max_u32_e32 v137, v131, v132
	v_min_u32_e32 v131, v131, v132
	v_max_u32_e32 v132, v133, v135
	v_min_u32_e32 v133, v133, v135
	v_max_u32_e32 v135, v130, v3
	v_min_u32_e32 v3, v130, v3
	v_max_u32_e32 v130, v129, v2
	v_min_u32_e32 v2, v129, v2
	v_max_u32_e32 v129, v0, v1
	v_min_u32_e32 v0, v0, v1
	v_max_u32_e32 v1, v127, v139
	v_min_u32_e32 v127, v127, v139
	v_max_u32_e32 v139, v136, v134
	v_min_u32_e32 v134, v136, v134
	v_max_u32_e32 v136, v138, v137
	v_min_u32_e32 v137, v138, v137
	v_max_u32_e32 v138, v128, v131
	v_min_u32_e32 v128, v128, v131
	v_max_u32_e32 v131, v132, v135
	v_min_u32_e32 v132, v132, v135
	v_max_u32_e32 v135, v133, v3
	v_min_u32_e32 v3, v133, v3
	v_max_u32_e32 v133, v130, v129
	v_min_u32_e32 v129, v130, v129
	v_max_u32_e32 v130, v2, v0
	v_min_u32_e32 v0, v2, v0
	ds_bpermute_b32 v2, v27, v1
	ds_bpermute_b32 v140, v27, v127
	ds_bpermute_b32 v141, v27, v139
	ds_bpermute_b32 v142, v27, v134
	ds_bpermute_b32 v143, v27, v136
	ds_bpermute_b32 v144, v27, v137
	ds_bpermute_b32 v145, v27, v138
	ds_bpermute_b32 v146, v27, v128
	ds_bpermute_b32 v147, v27, v131
	ds_bpermute_b32 v148, v27, v132
	ds_bpermute_b32 v149, v27, v135
	ds_bpermute_b32 v150, v27, v0
	ds_bpermute_b32 v151, v27, v130
	ds_bpermute_b32 v152, v27, v129
	ds_bpermute_b32 v153, v27, v133
	ds_bpermute_b32 v154, v27, v3
	s_waitcnt lgkmcnt(4)
; __device__ __forceinline__ void peer_tile(const Args& A, LAS unsigned char* lds, int tile) {
;     ...
;                 { const bf16_t* sp = QRY + m * 2048 + hp * 128 + 32 * g;
;                   const u32x4 s0 = *(const u32x4*)sp, s1 = *(const u32x4*)(sp + 8), s2 = *(const u32x4*)(sp + 16), s3 = *(const u32x4*)(sp + 24);
;     ...
;                 for (int msk = 16; msk <= 32; msk <<= 1) {
; #pragma unroll
;                     for (int i = 0; i < 16; ++i) k1[i] = (unsigned)__shfl_xor((int)k0[i], msk);
;                     merge16(k0, k1); }
	v_max_u32_e32 v1, v1, v150
	s_waitcnt lgkmcnt(3)
	v_max_u32_e32 v127, v127, v151
	s_waitcnt lgkmcnt(2)
	v_max_u32_e32 v139, v139, v152
	s_waitcnt lgkmcnt(1)
	v_max_u32_e32 v134, v134, v153
	s_waitcnt lgkmcnt(0)
	v_max_u32_e32 v136, v136, v154
	v_max_u32_e32 v137, v137, v149
	v_max_u32_e32 v138, v138, v148
	v_max_u32_e32 v128, v128, v147
	v_max_u32_e32 v131, v131, v146
	v_max_u32_e32 v132, v132, v145
	v_max_u32_e32 v135, v135, v144
	v_max_u32_e32 v3, v3, v143
	v_max_u32_e32 v133, v133, v142
	v_max_u32_e32 v129, v129, v141
	v_max_u32_e32 v130, v130, v140
	v_max_u32_e32 v0, v0, v2
	v_max_u32_e32 v2, v1, v131
	v_min_u32_e32 v1, v1, v131
	v_max_u32_e32 v131, v127, v132
	v_min_u32_e32 v127, v127, v132
	v_max_u32_e32 v132, v139, v135
	v_min_u32_e32 v135, v139, v135
	v_max_u32_e32 v139, v134, v3
	v_min_u32_e32 v3, v134, v3
	v_max_u32_e32 v134, v136, v133
	v_min_u32_e32 v133, v136, v133
	v_max_u32_e32 v136, v137, v129
	v_min_u32_e32 v129, v137, v129
	v_max_u32_e32 v137, v138, v130
	v_min_u32_e32 v130, v138, v130
	v_max_u32_e32 v138, v128, v0
	v_min_u32_e32 v0, v128, v0
	v_max_u32_e32 v128, v2, v134
	v_min_u32_e32 v2, v2, v134
	v_max_u32_e32 v134, v131, v136
	v_min_u32_e32 v131, v131, v136
	v_max_u32_e32 v136, v132, v137
	v_min_u32_e32 v132, v132, v137
	v_max_u32_e32 v137, v139, v138
	v_min_u32_e32 v138, v139, v138
	v_max_u32_e32 v139, v1, v133
	v_min_u32_e32 v1, v1, v133
	v_max_u32_e32 v133, v127, v129
	v_min_u32_e32 v127, v127, v129
	v_max_u32_e32 v129, v135, v130
	v_min_u32_e32 v130, v135, v130
	v_max_u32_e32 v135, v3, v0
	v_min_u32_e32 v0, v3, v0
	v_max_u32_e32 v3, v128, v136
	v_min_u32_e32 v128, v128, v136
	v_max_u32_e32 v136, v134, v137
	v_min_u32_e32 v134, v134, v137
	v_max_u32_e32 v137, v2, v132
	v_min_u32_e32 v2, v2, v132
	v_max_u32_e32 v132, v131, v138
	v_min_u32_e32 v131, v131, v138
	v_max_u32_e32 v138, v139, v129
	v_min_u32_e32 v129, v139, v129
	v_max_u32_e32 v139, v133, v135
	v_min_u32_e32 v133, v133, v135
	v_max_u32_e32 v135, v1, v130
	v_min_u32_e32 v1, v1, v130
	v_max_u32_e32 v130, v127, v0
	v_min_u32_e32 v0, v127, v0
	v_max_u32_e32 v127, v3, v136
	v_min_u32_e32 v3, v3, v136
	v_max_u32_e32 v136, v128, v134
	v_min_u32_e32 v128, v128, v134
	v_max_u32_e32 v134, v137, v132
	v_min_u32_e32 v132, v137, v132
	v_max_u32_e32 v137, v2, v131
	v_min_u32_e32 v2, v2, v131
	v_max_u32_e32 v131, v138, v139
	v_min_u32_e32 v138, v138, v139
	v_max_u32_e32 v139, v129, v133
	v_min_u32_e32 v129, v129, v133
	v_max_u32_e32 v133, v135, v130
	v_min_u32_e32 v130, v135, v130
	v_max_u32_e32 v135, v1, v0
	v_min_u32_e32 v0, v1, v0
	ds_bpermute_b32 v144, v29, v0
	ds_bpermute_b32 v1, v29, v127
	ds_bpermute_b32 v140, v29, v3
	ds_bpermute_b32 v141, v29, v136
	ds_bpermute_b32 v142, v29, v128
	s_waitcnt lgkmcnt(4)
	v_max_u32_e32 v127, v127, v144
	global_load_dwordx4 v[144:147], v[4:5], off offset:1808
	global_load_dwordx4 v[148:151], v[4:5], off offset:1792
	ds_bpermute_b32 v143, v29, v134
	ds_bpermute_b32 v152, v29, v132
	ds_bpermute_b32 v153, v29, v137
	ds_bpermute_b32 v154, v29, v2
	ds_bpermute_b32 v155, v29, v131
	ds_bpermute_b32 v156, v29, v138
	ds_bpermute_b32 v157, v29, v139
	ds_bpermute_b32 v158, v29, v129
	ds_bpermute_b32 v159, v29, v133
	ds_bpermute_b32 v160, v29, v135
	ds_bpermute_b32 v161, v29, v130
	s_waitcnt lgkmcnt(4)
	v_max_u32_e32 v132, v132, v157
	s_waitcnt lgkmcnt(3)
	v_max_u32_e32 v134, v134, v158
	s_waitcnt lgkmcnt(2)
	v_max_u32_e32 v128, v128, v159
	s_waitcnt lgkmcnt(1)
	v_max_u32_e32 v3, v3, v160
	s_waitcnt lgkmcnt(0)
	v_max_u32_e32 v136, v136, v161
	v_max_u32_e32 v137, v137, v156
	v_max_u32_e32 v2, v2, v155
	v_max_u32_e32 v131, v131, v154
	v_max_u32_e32 v138, v138, v153
	v_max_u32_e32 v139, v139, v152
	v_max_u32_e32 v129, v129, v143
	v_max_u32_e32 v133, v133, v142
	v_max_u32_e32 v130, v130, v141
	v_max_u32_e32 v135, v135, v140
	v_max_u32_e32 v0, v0, v1
	v_max_u32_e32 v1, v127, v131
	v_min_u32_e32 v127, v127, v131
	v_max_u32_e32 v131, v3, v138
	v_min_u32_e32 v3, v3, v138
	v_max_u32_e32 v138, v136, v139
	v_min_u32_e32 v136, v136, v139
	v_max_u32_e32 v139, v128, v129
	v_min_u32_e32 v128, v128, v129
	v_max_u32_e32 v129, v134, v133
	v_min_u32_e32 v133, v134, v133
	v_max_u32_e32 v134, v132, v130
	v_min_u32_e32 v130, v132, v130
	v_max_u32_e32 v132, v137, v135
	v_min_u32_e32 v135, v137, v135
	v_max_u32_e32 v137, v2, v0
	v_min_u32_e32 v0, v2, v0
	v_max_u32_e32 v2, v1, v129
	v_min_u32_e32 v1, v1, v129
	v_max_u32_e32 v129, v131, v134
	v_min_u32_e32 v131, v131, v134
	v_max_u32_e32 v134, v138, v132
	v_min_u32_e32 v132, v138, v132
	v_max_u32_e32 v138, v139, v137
	v_min_u32_e32 v137, v139, v137
	v_max_u32_e32 v139, v127, v133
	v_min_u32_e32 v127, v127, v133
	v_max_u32_e32 v133, v3, v130
	v_min_u32_e32 v3, v3, v130
	v_max_u32_e32 v130, v136, v135
	v_min_u32_e32 v135, v136, v135
	v_max_u32_e32 v136, v128, v0
	v_min_u32_e32 v0, v128, v0
	v_max_u32_e32 v128, v2, v134
	v_min_u32_e32 v2, v2, v134
	v_max_u32_e32 v134, v129, v138
	v_min_u32_e32 v129, v129, v138
	v_max_u32_e32 v143, v1, v132
	v_min_u32_e32 v1, v1, v132
	v_max_u32_e32 v132, v131, v137
	v_min_u32_e32 v131, v131, v137
	v_max_u32_e32 v152, v139, v130
	v_min_u32_e32 v130, v139, v130
	v_max_u32_e32 v153, v133, v136
	v_min_u32_e32 v154, v133, v136
	v_max_u32_e32 v155, v127, v135
	v_min_u32_e32 v127, v127, v135
	v_max_u32_e32 v156, v3, v0
	v_min_u32_e32 v0, v3, v0
	v_max_u32_e32 v142, v128, v134
	v_min_u32_e32 v141, v128, v134
	v_max_u32_e32 v140, v2, v129
	v_min_u32_e32 v139, v2, v129
	v_max_u32_e32 v138, v143, v132
	v_min_u32_e32 v137, v143, v132
	v_max_u32_e32 v136, v1, v131
	v_min_u32_e32 v135, v1, v131
	v_max_u32_e32 v134, v152, v153
	v_min_u32_e32 v133, v152, v153
	v_max_u32_e32 v132, v130, v154
	v_min_u32_e32 v131, v130, v154
	v_max_u32_e32 v130, v155, v156
	v_min_u32_e32 v129, v155, v156
	v_max_u32_e32 v128, v127, v0
	v_min_u32_e32 v127, v127, v0
	global_load_dwordx4 v[0:3], v[4:5], off offset:1840
	global_load_dwordx4 v[152:155], v[4:5], off offset:1824
	s_waitcnt vmcnt(2)
; __device__ __forceinline__ unsigned f2key(float f) { const unsigned u = __float_as_uint(f); return (u & 0x80000000u) ? ~u : (u | 0x80000000u); }
; __device__ __forceinline__ void peer_tile(const Args& A, LAS unsigned char* lds, int tile) {
;     ...
;                 { const bf16_t* sp = QRY + m * 2048 + hp * 128 + 32 * g;
;                   const u32x4 s0 = *(const u32x4*)sp, s1 = *(const u32x4*)(sp + 8), s2 = *(const u32x4*)(sp + 16), s3 = *(const u32x4*)(sp + 24);
;                   const unsigned sw[16] = {s0.x, s0.y, s0.z, s0.w, s1.x, s1.y, s1.z, s1.w, s2.x, s2.y, s2.z, s2.w, s3.x, s3.y, s3.z, s3.w};
; #pragma unroll
;                   for (int i = 0; i < 16; ++i) {
;                       const float lo = (float)__builtin_bit_cast(_Float16, (unsigned short)(sw[i] & 0xffffu)), hi = (float)__builtin_bit_cast(_Float16, (unsigned short)(sw[i] >> 16));
;                       const unsigned klo = (f2key(lo) & ~127u) | (unsigned)(127 - (32 * g + 2 * i)), khi = (f2key(hi) & ~127u) | (unsigned)(127 - (32 * g + 2 * i + 1));
;                       if (i < 8) { k0[2 * i] = klo; k0[2 * i + 1] = khi; } else { k1[2 * (i - 8)] = klo; k1[2 * (i - 8) + 1] = khi; } } }
	v_cvt_f32_f16_sdwa v143, v148 dst_sel:DWORD dst_unused:UNUSED_PAD src0_sel:WORD_1
	v_cvt_f32_f16_e32 v4, v148
	v_not_b32_e32 v5, v143
	v_or_b32_e32 v148, 0x80000000, v143
	v_cmp_gt_i32_e32 vcc, 0, v143
	v_not_b32_e32 v143, v4
	s_nop 0
	v_cndmask_b32_e32 v5, v148, v5, vcc
	v_or_b32_e32 v148, 0x80000000, v4
	v_cmp_gt_i32_e32 vcc, 0, v4
	v_and_b32_e32 v5, 0xffffff80, v5
	v_sub_u32_e32 v5, v5, v15
	v_cndmask_b32_e32 v4, v148, v143, vcc
	v_and_b32_e32 v4, 0xffffff80, v4
	v_cvt_f32_f16_sdwa v143, v149 dst_sel:DWORD dst_unused:UNUSED_PAD src0_sel:WORD_1
	v_sub_u32_e32 v4, v4, v15
	v_cvt_f32_f16_e32 v15, v149
	v_add_u32_e32 v5, 0x7e, v5
	v_not_b32_e32 v148, v143
	v_or_b32_e32 v149, 0x80000000, v143
	v_cmp_gt_i32_e32 vcc, 0, v143
	v_add_u32_e32 v4, 0x7f, v4
	s_nop 0
	v_cndmask_b32_e32 v143, v149, v148, vcc
	v_not_b32_e32 v148, v15
	v_or_b32_e32 v149, 0x80000000, v15
	v_cmp_gt_i32_e32 vcc, 0, v15
	v_and_b32_e32 v143, 0xffffff80, v143
	v_sub_u32_e32 v143, v143, v14
	v_cndmask_b32_e32 v15, v149, v148, vcc
	v_and_b32_e32 v15, 0xffffff80, v15
	v_cvt_f32_f16_sdwa v148, v150 dst_sel:DWORD dst_unused:UNUSED_PAD src0_sel:WORD_1
	v_sub_u32_e32 v14, v15, v14
	v_cvt_f32_f16_e32 v15, v150
	v_add_u32_e32 v143, 0x7e, v143
	v_not_b32_e32 v149, v148
	v_or_b32_e32 v150, 0x80000000, v148
	v_cmp_gt_i32_e32 vcc, 0, v148
	v_add_u32_e32 v14, 0x7f, v14
	s_nop 0
	v_cndmask_b32_e32 v148, v150, v149, vcc
	v_not_b32_e32 v149, v15
	v_or_b32_e32 v150, 0x80000000, v15
	v_cmp_gt_i32_e32 vcc, 0, v15
	v_and_b32_e32 v148, 0xffffff80, v148
	v_sub_u32_e32 v148, v148, v12
	v_cndmask_b32_e32 v15, v150, v149, vcc
	v_and_b32_e32 v15, 0xffffff80, v15
	v_cvt_f32_f16_sdwa v149, v151 dst_sel:DWORD dst_unused:UNUSED_PAD src0_sel:WORD_1
	v_sub_u32_e32 v12, v15, v12
	v_cvt_f32_f16_e32 v15, v151
	v_add_u32_e32 v148, 0x7e, v148
	v_not_b32_e32 v150, v149
	v_or_b32_e32 v151, 0x80000000, v149
	v_cmp_gt_i32_e32 vcc, 0, v149
	v_add_u32_e32 v12, 0x7f, v12
	s_nop 0
	v_cndmask_b32_e32 v149, v151, v150, vcc
	v_not_b32_e32 v150, v15
	v_or_b32_e32 v151, 0x80000000, v15
	v_cmp_gt_i32_e32 vcc, 0, v15
	v_and_b32_e32 v149, 0xffffff80, v149
	v_sub_u32_e32 v149, v149, v10
	v_cndmask_b32_e32 v15, v151, v150, vcc
	v_and_b32_e32 v15, 0xffffff80, v15
	v_cvt_f32_f16_sdwa v150, v144 dst_sel:DWORD dst_unused:UNUSED_PAD src0_sel:WORD_1
	v_sub_u32_e32 v10, v15, v10
	v_cvt_f32_f16_e32 v15, v144
	v_add_u32_e32 v149, 0x7e, v149
	v_not_b32_e32 v144, v150
	v_or_b32_e32 v151, 0x80000000, v150
	v_cmp_gt_i32_e32 vcc, 0, v150
	v_not_b32_e32 v150, v15
	v_add_u32_e32 v10, 0x7f, v10
	v_cndmask_b32_e32 v144, v151, v144, vcc
	v_or_b32_e32 v151, 0x80000000, v15
	v_cmp_gt_i32_e32 vcc, 0, v15
	v_and_b32_e32 v144, 0xffffff80, v144
	v_sub_u32_e32 v144, v144, v8
	v_cndmask_b32_e32 v15, v151, v150, vcc
	v_and_b32_e32 v15, 0xffffff80, v15
	v_cvt_f32_f16_sdwa v150, v145 dst_sel:DWORD dst_unused:UNUSED_PAD src0_sel:WORD_1
	v_sub_u32_e32 v8, v15, v8
	v_cvt_f32_f16_e32 v15, v145
	v_add_u32_e32 v144, 0x7e, v144
	v_not_b32_e32 v145, v150
	v_or_b32_e32 v151, 0x80000000, v150
	v_cmp_gt_i32_e32 vcc, 0, v150
	v_not_b32_e32 v150, v15
	v_add_u32_e32 v8, 0x7f, v8
	v_cndmask_b32_e32 v145, v151, v145, vcc
	v_or_b32_e32 v151, 0x80000000, v15
	v_cmp_gt_i32_e32 vcc, 0, v15
	v_and_b32_e32 v145, 0xffffff80, v145
	v_sub_u32_e32 v145, v145, v16
	v_cndmask_b32_e32 v15, v151, v150, vcc
	v_and_b32_e32 v15, 0xffffff80, v15
	v_cvt_f32_f16_sdwa v150, v146 dst_sel:DWORD dst_unused:UNUSED_PAD src0_sel:WORD_1
	v_sub_u32_e32 v15, v15, v16
	v_cvt_f32_f16_e32 v16, v146
	v_add_u32_e32 v145, 0x7e, v145
	v_not_b32_e32 v146, v150
	v_or_b32_e32 v151, 0x80000000, v150
	v_cmp_gt_i32_e32 vcc, 0, v150
	v_not_b32_e32 v150, v16
	v_add_u32_e32 v15, 0x7f, v15
	v_cndmask_b32_e32 v146, v151, v146, vcc
	v_or_b32_e32 v151, 0x80000000, v16
	v_cmp_gt_i32_e32 vcc, 0, v16
	v_and_b32_e32 v146, 0xffffff80, v146
	v_sub_u32_e32 v146, v146, v17
	v_cndmask_b32_e32 v16, v151, v150, vcc
	v_and_b32_e32 v16, 0xffffff80, v16
	v_cvt_f32_f16_sdwa v150, v147 dst_sel:DWORD dst_unused:UNUSED_PAD src0_sel:WORD_1
	v_sub_u32_e32 v16, v16, v17
	v_cvt_f32_f16_e32 v17, v147
	v_add_u32_e32 v146, 0x7e, v146
	v_not_b32_e32 v147, v150
	v_or_b32_e32 v151, 0x80000000, v150
	v_cmp_gt_i32_e32 vcc, 0, v150
	v_not_b32_e32 v150, v17
	v_add_u32_e32 v16, 0x7f, v16
	v_cndmask_b32_e32 v147, v151, v147, vcc
	v_or_b32_e32 v151, 0x80000000, v17
	v_cmp_gt_i32_e32 vcc, 0, v17
	v_and_b32_e32 v147, 0xffffff80, v147
	v_sub_u32_e32 v147, v147, v18
	v_cndmask_b32_e32 v17, v151, v150, vcc
	v_and_b32_e32 v17, 0xffffff80, v17
	s_waitcnt vmcnt(0)
; __device__ __forceinline__ unsigned f2key(float f) { const unsigned u = __float_as_uint(f); return (u & 0x80000000u) ? ~u : (u | 0x80000000u); }
; #define CE_DESC(a, b) do { const unsigned _mx = (a) > (b) ? (a) : (b), _mn = (a) > (b) ? (b) : (a); (a) = _mx; (b) = _mn; } while (0)
; __device__ __forceinline__ void sort16_desc(unsigned (&k)[16]) {
; #pragma unroll
;     for (int size = 2; size <= 16; size <<= 1)
; #pragma unroll
;         for (int stride = size >> 1; stride > 0; stride >>= 1)
; #pragma unroll
;             for (int i = 0; i < 16; ++i) { const int j = i ^ stride;
;                 if (j > i) { if ((i & size) == 0) CE_DESC(k[i], k[j]); else CE_DESC(k[j], k[i]); } }
; }
; __device__ __forceinline__ void peer_tile(const Args& A, LAS unsigned char* lds, int tile) {
;     ...
;                 { const bf16_t* sp = QRY + m * 2048 + hp * 128 + 32 * g;
;                   const u32x4 s0 = *(const u32x4*)sp, s1 = *(const u32x4*)(sp + 8), s2 = *(const u32x4*)(sp + 16), s3 = *(const u32x4*)(sp + 24);
;                   const unsigned sw[16] = {s0.x, s0.y, s0.z, s0.w, s1.x, s1.y, s1.z, s1.w, s2.x, s2.y, s2.z, s2.w, s3.x, s3.y, s3.z, s3.w};
; #pragma unroll
;                   for (int i = 0; i < 16; ++i) {
;                       const float lo = (float)__builtin_bit_cast(_Float16, (unsigned short)(sw[i] & 0xffffu)), hi = (float)__builtin_bit_cast(_Float16, (unsigned short)(sw[i] >> 16));
;                       const unsigned klo = (f2key(lo) & ~127u) | (unsigned)(127 - (32 * g + 2 * i)), khi = (f2key(hi) & ~127u) | (unsigned)(127 - (32 * g + 2 * i + 1));
;                       if (i < 8) { k0[2 * i] = klo; k0[2 * i + 1] = khi; } else { k1[2 * (i - 8)] = klo; k1[2 * (i - 8) + 1] = khi; } } }
;                 sort16_desc(k0); sort16_desc(k1); merge16(k0, k1);
	v_cvt_f32_f16_sdwa v150, v152 dst_sel:DWORD dst_unused:UNUSED_PAD src0_sel:WORD_1
	v_sub_u32_e32 v17, v17, v18
	v_cvt_f32_f16_e32 v18, v152
	v_add_u32_e32 v147, 0x7e, v147
	v_not_b32_e32 v151, v150
	v_or_b32_e32 v152, 0x80000000, v150
	v_cmp_gt_i32_e32 vcc, 0, v150
	v_add_u32_e32 v17, 0x7f, v17
	s_nop 0
	v_cndmask_b32_e32 v150, v152, v151, vcc
	v_not_b32_e32 v151, v18
	v_or_b32_e32 v152, 0x80000000, v18
	v_cmp_gt_i32_e32 vcc, 0, v18
	v_and_b32_e32 v150, 0xffffff80, v150
	v_sub_u32_e32 v150, v150, v20
	v_cndmask_b32_e32 v18, v152, v151, vcc
	v_and_b32_e32 v18, 0xffffff80, v18
	v_cvt_f32_f16_sdwa v151, v153 dst_sel:DWORD dst_unused:UNUSED_PAD src0_sel:WORD_1
	v_sub_u32_e32 v18, v18, v20
	v_cvt_f32_f16_e32 v20, v153
	v_add_u32_e32 v150, 0x7e, v150
	v_not_b32_e32 v152, v151
	v_or_b32_e32 v153, 0x80000000, v151
	v_cmp_gt_i32_e32 vcc, 0, v151
	v_add_u32_e32 v18, 0x7f, v18
	v_max_u32_e32 v161, v18, v150
	v_cndmask_b32_e32 v151, v153, v152, vcc
	v_not_b32_e32 v152, v20
	v_or_b32_e32 v153, 0x80000000, v20
	v_cmp_gt_i32_e32 vcc, 0, v20
	v_and_b32_e32 v151, 0xffffff80, v151
	v_sub_u32_e32 v151, v151, v21
	v_cndmask_b32_e32 v20, v153, v152, vcc
	v_and_b32_e32 v20, 0xffffff80, v20
	v_cvt_f32_f16_sdwa v152, v154 dst_sel:DWORD dst_unused:UNUSED_PAD src0_sel:WORD_1
	v_sub_u32_e32 v20, v20, v21
	v_cvt_f32_f16_e32 v21, v154
	v_add_u32_e32 v151, 0x7e, v151
	v_not_b32_e32 v153, v152
	v_or_b32_e32 v154, 0x80000000, v152
	v_cmp_gt_i32_e32 vcc, 0, v152
	v_add_u32_e32 v20, 0x7f, v20
	v_min_u32_e32 v18, v18, v150
	v_cndmask_b32_e32 v152, v154, v153, vcc
	v_not_b32_e32 v153, v21
	v_or_b32_e32 v154, 0x80000000, v21
	v_cmp_gt_i32_e32 vcc, 0, v21
	v_and_b32_e32 v152, 0xffffff80, v152
	v_sub_u32_e32 v152, v152, v22
	v_cndmask_b32_e32 v21, v154, v153, vcc
	v_and_b32_e32 v21, 0xffffff80, v21
	v_cvt_f32_f16_sdwa v153, v155 dst_sel:DWORD dst_unused:UNUSED_PAD src0_sel:WORD_1
	v_sub_u32_e32 v21, v21, v22
	v_cvt_f32_f16_e32 v22, v155
	v_add_u32_e32 v152, 0x7e, v152
	v_not_b32_e32 v154, v153
	v_or_b32_e32 v155, 0x80000000, v153
	v_cmp_gt_i32_e32 vcc, 0, v153
	v_add_u32_e32 v21, 0x7f, v21
	v_max_u32_e32 v150, v151, v20
	v_cndmask_b32_e32 v153, v155, v154, vcc
	v_not_b32_e32 v154, v22
	v_or_b32_e32 v155, 0x80000000, v22
	v_cmp_gt_i32_e32 vcc, 0, v22
	v_and_b32_e32 v153, 0xffffff80, v153
	v_sub_u32_e32 v153, v153, v23
	v_cndmask_b32_e32 v22, v155, v154, vcc
	v_cvt_f32_f16_sdwa v154, v0 dst_sel:DWORD dst_unused:UNUSED_PAD src0_sel:WORD_1
	v_cvt_f32_f16_e32 v0, v0
	v_and_b32_e32 v22, 0xffffff80, v22
	v_sub_u32_e32 v22, v22, v23
	v_not_b32_e32 v23, v154
	v_or_b32_e32 v155, 0x80000000, v154
	v_cmp_gt_i32_e32 vcc, 0, v154
	v_not_b32_e32 v154, v0
	v_add_u32_e32 v153, 0x7e, v153
	v_cndmask_b32_e32 v23, v155, v23, vcc
	v_or_b32_e32 v155, 0x80000000, v0
	v_cmp_gt_i32_e32 vcc, 0, v0
	v_and_b32_e32 v23, 0xffffff80, v23
	v_sub_u32_e32 v23, v23, v24
	v_cndmask_b32_e32 v0, v155, v154, vcc
	v_cvt_f32_f16_sdwa v154, v1 dst_sel:DWORD dst_unused:UNUSED_PAD src0_sel:WORD_1
	v_cvt_f32_f16_e32 v1, v1
	v_and_b32_e32 v0, 0xffffff80, v0
	v_sub_u32_e32 v0, v0, v24
	v_not_b32_e32 v24, v154
	v_or_b32_e32 v155, 0x80000000, v154
	v_cmp_gt_i32_e32 vcc, 0, v154
	v_not_b32_e32 v154, v1
	v_add_u32_e32 v22, 0x7f, v22
	v_cndmask_b32_e32 v24, v155, v24, vcc
	v_or_b32_e32 v155, 0x80000000, v1
	v_cmp_gt_i32_e32 vcc, 0, v1
	v_and_b32_e32 v24, 0xffffff80, v24
	v_sub_u32_e32 v24, v24, v25
	v_cndmask_b32_e32 v1, v155, v154, vcc
	v_cvt_f32_f16_sdwa v154, v2 dst_sel:DWORD dst_unused:UNUSED_PAD src0_sel:WORD_1
	v_cvt_f32_f16_e32 v2, v2
	v_and_b32_e32 v1, 0xffffff80, v1
	v_sub_u32_e32 v1, v1, v25
	v_not_b32_e32 v25, v154
	v_or_b32_e32 v155, 0x80000000, v154
	v_cmp_gt_i32_e32 vcc, 0, v154
	v_not_b32_e32 v154, v2
	v_add_u32_e32 v23, 0x7e, v23
	v_cndmask_b32_e32 v25, v155, v25, vcc
	v_or_b32_e32 v155, 0x80000000, v2
	v_cmp_gt_i32_e32 vcc, 0, v2
	v_and_b32_e32 v25, 0xffffff80, v25
	v_sub_u32_e32 v25, v25, v26
	v_cndmask_b32_e32 v2, v155, v154, vcc
	v_cvt_f32_f16_sdwa v154, v3 dst_sel:DWORD dst_unused:UNUSED_PAD src0_sel:WORD_1
	v_cvt_f32_f16_e32 v3, v3
	v_and_b32_e32 v2, 0xffffff80, v2
	v_sub_u32_e32 v2, v2, v26
	v_not_b32_e32 v26, v154
	v_or_b32_e32 v155, 0x80000000, v154
	v_cmp_gt_i32_e32 vcc, 0, v154
	v_not_b32_e32 v154, v3
	v_add_u32_e32 v0, 0x7f, v0
	v_cndmask_b32_e32 v26, v155, v26, vcc
	v_or_b32_e32 v155, 0x80000000, v3
	v_cmp_gt_i32_e32 vcc, 0, v3
	v_and_b32_e32 v26, 0xffffff80, v26
	v_sub_u32_e32 v26, v26, v28
	v_cndmask_b32_e32 v3, v155, v154, vcc
	v_and_b32_e32 v3, 0xffffff80, v3
	v_sub_u32_e32 v3, v3, v28
	v_add_u32_e32 v24, 0x7e, v24
	v_add_u32_e32 v1, 0x7f, v1
	v_add_u32_e32 v25, 0x7e, v25
	v_add_u32_e32 v2, 0x7f, v2
	v_add_u32_e32 v26, 0x7e, v26
	v_add_u32_e32 v3, 0x7f, v3
	v_max_u32_e32 v28, v4, v5
	v_min_u32_e32 v4, v4, v5
	v_max_u32_e32 v5, v143, v14
	v_min_u32_e32 v14, v143, v14
	v_max_u32_e32 v143, v12, v148
	v_min_u32_e32 v12, v12, v148
	v_max_u32_e32 v148, v149, v10
	v_min_u32_e32 v10, v149, v10
	v_max_u32_e32 v149, v8, v144
	v_min_u32_e32 v8, v8, v144
	v_max_u32_e32 v144, v145, v15
	v_min_u32_e32 v15, v145, v15
	v_max_u32_e32 v145, v16, v146
	v_min_u32_e32 v16, v16, v146
	v_max_u32_e32 v146, v147, v17
	v_min_u32_e32 v17, v147, v17
	v_min_u32_e32 v20, v151, v20
	v_max_u32_e32 v151, v21, v152
	v_min_u32_e32 v21, v21, v152
	v_max_u32_e32 v152, v153, v22
	v_min_u32_e32 v22, v153, v22
	v_max_u32_e32 v153, v0, v23
	v_min_u32_e32 v0, v0, v23
	v_max_u32_e32 v23, v24, v1
	v_min_u32_e32 v1, v24, v1
	v_max_u32_e32 v24, v2, v25
	v_min_u32_e32 v2, v2, v25
	v_max_u32_e32 v25, v26, v3
	v_min_u32_e32 v3, v26, v3
	v_max_u32_e32 v147, v28, v14
	v_min_u32_e32 v14, v28, v14
	v_max_u32_e32 v28, v4, v5
	v_min_u32_e32 v4, v4, v5
; #define CE_DESC(a, b) do { const unsigned _mx = (a) > (b) ? (a) : (b), _mn = (a) > (b) ? (b) : (a); (a) = _mx; (b) = _mn; } while (0)
; __device__ __forceinline__ void sort16_desc(unsigned (&k)[16]) {
; #pragma unroll
;     for (int size = 2; size <= 16; size <<= 1)
; #pragma unroll
;         for (int stride = size >> 1; stride > 0; stride >>= 1)
; #pragma unroll
;             for (int i = 0; i < 16; ++i) { const int j = i ^ stride;
;                 if (j > i) { if ((i & size) == 0) CE_DESC(k[i], k[j]); else CE_DESC(k[j], k[i]); } }
; }
	v_max_u32_e32 v5, v10, v143
	v_min_u32_e32 v10, v10, v143
	v_max_u32_e32 v143, v148, v12
	v_min_u32_e32 v12, v148, v12
	v_max_u32_e32 v148, v149, v15
	v_min_u32_e32 v15, v149, v15
	v_max_u32_e32 v149, v8, v144
	v_min_u32_e32 v8, v8, v144
	v_max_u32_e32 v144, v17, v145
	v_min_u32_e32 v17, v17, v145
	v_max_u32_e32 v145, v146, v16
	v_min_u32_e32 v16, v146, v16
	v_max_u32_e32 v26, v161, v20
	v_min_u32_e32 v20, v161, v20
	v_max_u32_e32 v161, v18, v150
	v_min_u32_e32 v18, v18, v150
	v_max_u32_e32 v150, v22, v151
	v_min_u32_e32 v22, v22, v151
	v_max_u32_e32 v151, v152, v21
	v_min_u32_e32 v21, v152, v21
	v_max_u32_e32 v152, v153, v1
	v_min_u32_e32 v1, v153, v1
	v_max_u32_e32 v153, v0, v23
	v_min_u32_e32 v0, v0, v23
	v_max_u32_e32 v23, v3, v24
	v_min_u32_e32 v3, v3, v24
	v_max_u32_e32 v24, v25, v2
	v_min_u32_e32 v2, v25, v2
	v_max_u32_e32 v146, v147, v28
	v_min_u32_e32 v28, v147, v28
	v_max_u32_e32 v147, v14, v4
	v_min_u32_e32 v4, v14, v4
	v_max_u32_e32 v14, v12, v10
	v_min_u32_e32 v10, v12, v10
	v_max_u32_e32 v12, v143, v5
	v_min_u32_e32 v5, v143, v5
	v_max_u32_e32 v143, v148, v149
	v_min_u32_e32 v148, v148, v149
	v_max_u32_e32 v149, v15, v8
	v_min_u32_e32 v8, v15, v8
	v_max_u32_e32 v15, v16, v17
	v_min_u32_e32 v16, v16, v17
	v_max_u32_e32 v17, v145, v144
	v_min_u32_e32 v144, v145, v144
	v_max_u32_e32 v25, v26, v161
	v_min_u32_e32 v26, v26, v161
	v_max_u32_e32 v161, v20, v18
	v_min_u32_e32 v18, v20, v18
	v_max_u32_e32 v20, v21, v22
	v_min_u32_e32 v21, v21, v22
	v_max_u32_e32 v22, v151, v150
	v_min_u32_e32 v150, v151, v150
	v_max_u32_e32 v151, v152, v153
	v_min_u32_e32 v152, v152, v153
	v_max_u32_e32 v153, v1, v0
	v_min_u32_e32 v0, v1, v0
	v_max_u32_e32 v1, v2, v3
	v_min_u32_e32 v2, v2, v3
	v_max_u32_e32 v3, v24, v23
	v_min_u32_e32 v23, v24, v23
	v_max_u32_e32 v145, v146, v10
	v_min_u32_e32 v10, v146, v10
	v_max_u32_e32 v146, v28, v14
	v_min_u32_e32 v14, v28, v14
	v_max_u32_e32 v28, v147, v5
	v_min_u32_e32 v5, v147, v5
	v_max_u32_e32 v147, v4, v12
	v_min_u32_e32 v4, v4, v12
	v_max_u32_e32 v12, v16, v143
	v_min_u32_e32 v16, v16, v143
	v_max_u32_e32 v143, v15, v148
	v_min_u32_e32 v15, v15, v148
	v_max_u32_e32 v148, v144, v149
	v_min_u32_e32 v144, v144, v149
	v_max_u32_e32 v149, v17, v8
	v_min_u32_e32 v8, v17, v8
	v_max_u32_e32 v24, v25, v21
	v_min_u32_e32 v21, v25, v21
	v_max_u32_e32 v25, v26, v20
	v_min_u32_e32 v20, v26, v20
	v_max_u32_e32 v26, v161, v150
	v_min_u32_e32 v150, v161, v150
	v_max_u32_e32 v161, v18, v22
	v_min_u32_e32 v18, v18, v22
	v_max_u32_e32 v22, v2, v151
	v_min_u32_e32 v2, v2, v151
	v_max_u32_e32 v151, v1, v152
	v_min_u32_e32 v1, v1, v152
	v_max_u32_e32 v152, v23, v153
	v_min_u32_e32 v23, v23, v153
	v_max_u32_e32 v153, v3, v0
	v_min_u32_e32 v0, v3, v0
	v_max_u32_e32 v17, v145, v28
	v_min_u32_e32 v28, v145, v28
	v_max_u32_e32 v145, v146, v147
	v_min_u32_e32 v146, v146, v147
	v_max_u32_e32 v147, v10, v5
	v_min_u32_e32 v5, v10, v5
	v_max_u32_e32 v10, v14, v4
	v_min_u32_e32 v4, v14, v4
	v_max_u32_e32 v14, v144, v16
	v_min_u32_e32 v16, v144, v16
	v_max_u32_e32 v144, v8, v15
	v_min_u32_e32 v8, v8, v15
	v_max_u32_e32 v15, v148, v12
	v_min_u32_e32 v12, v148, v12
	v_max_u32_e32 v148, v149, v143
	v_min_u32_e32 v143, v149, v143
	v_max_u32_e32 v3, v24, v26
	v_min_u32_e32 v24, v24, v26
	v_max_u32_e32 v26, v25, v161
	v_min_u32_e32 v25, v25, v161
	v_max_u32_e32 v161, v21, v150
	v_min_u32_e32 v21, v21, v150
	v_max_u32_e32 v150, v20, v18
	v_min_u32_e32 v18, v20, v18
	v_max_u32_e32 v20, v23, v2
	v_min_u32_e32 v2, v23, v2
	v_max_u32_e32 v23, v0, v1
	v_min_u32_e32 v0, v0, v1
	v_max_u32_e32 v1, v152, v22
	v_min_u32_e32 v22, v152, v22
	v_max_u32_e32 v152, v153, v151
	v_min_u32_e32 v151, v153, v151
	v_max_u32_e32 v149, v17, v145
	v_min_u32_e32 v17, v17, v145
	v_max_u32_e32 v145, v28, v146
	v_min_u32_e32 v28, v28, v146
	v_max_u32_e32 v146, v147, v10
	v_min_u32_e32 v10, v147, v10
	v_max_u32_e32 v147, v5, v4
	v_min_u32_e32 v4, v5, v4
	v_max_u32_e32 v5, v8, v16
	v_min_u32_e32 v8, v8, v16
	v_max_u32_e32 v16, v144, v14
	v_min_u32_e32 v14, v144, v14
	v_max_u32_e32 v144, v143, v12
	v_min_u32_e32 v12, v143, v12
	v_max_u32_e32 v143, v148, v15
	v_min_u32_e32 v15, v148, v15
	v_max_u32_e32 v153, v3, v26
	v_min_u32_e32 v3, v3, v26
	v_max_u32_e32 v26, v24, v25
	v_min_u32_e32 v24, v24, v25
	v_max_u32_e32 v25, v161, v150
	v_min_u32_e32 v150, v161, v150
	v_max_u32_e32 v161, v21, v18
	v_min_u32_e32 v18, v21, v18
	v_max_u32_e32 v21, v0, v2
	v_min_u32_e32 v0, v0, v2
	v_max_u32_e32 v2, v23, v20
	v_min_u32_e32 v20, v23, v20
	v_max_u32_e32 v23, v151, v22
	v_min_u32_e32 v22, v151, v22
	v_max_u32_e32 v151, v152, v1
	v_min_u32_e32 v1, v152, v1
	v_max_u32_e32 v148, v149, v8
	v_min_u32_e32 v8, v149, v8
	v_max_u32_e32 v149, v17, v5
	v_min_u32_e32 v5, v17, v5
	v_max_u32_e32 v17, v145, v14
	v_min_u32_e32 v14, v145, v14
	v_max_u32_e32 v145, v28, v16
	v_min_u32_e32 v16, v28, v16
	v_max_u32_e32 v28, v146, v12
	v_min_u32_e32 v12, v146, v12
	v_max_u32_e32 v146, v10, v144
	v_min_u32_e32 v10, v10, v144
	v_max_u32_e32 v144, v147, v15
	v_min_u32_e32 v15, v147, v15
	v_max_u32_e32 v147, v4, v143
	v_min_u32_e32 v4, v4, v143
	v_max_u32_e32 v152, v153, v0
	v_min_u32_e32 v0, v153, v0
	v_max_u32_e32 v153, v3, v21
	v_min_u32_e32 v3, v3, v21
	v_max_u32_e32 v21, v26, v20
	v_min_u32_e32 v20, v26, v20
	v_max_u32_e32 v26, v24, v2
	v_min_u32_e32 v2, v24, v2
	v_max_u32_e32 v24, v25, v22
	v_min_u32_e32 v22, v25, v22
	v_max_u32_e32 v25, v150, v23
	v_min_u32_e32 v23, v150, v23
	v_max_u32_e32 v150, v161, v1
	v_min_u32_e32 v1, v161, v1
	v_max_u32_e32 v161, v18, v151
	v_min_u32_e32 v18, v18, v151
	v_max_u32_e32 v143, v148, v28
	v_min_u32_e32 v28, v148, v28
	v_max_u32_e32 v148, v149, v146
	v_min_u32_e32 v146, v149, v146
; #define CE_DESC(a, b) do { const unsigned _mx = (a) > (b) ? (a) : (b), _mn = (a) > (b) ? (b) : (a); (a) = _mx; (b) = _mn; } while (0)
; __device__ __forceinline__ void sort16_desc(unsigned (&k)[16]) {
; #pragma unroll
;     for (int size = 2; size <= 16; size <<= 1)
; #pragma unroll
;         for (int stride = size >> 1; stride > 0; stride >>= 1)
; #pragma unroll
;             for (int i = 0; i < 16; ++i) { const int j = i ^ stride;
;                 if (j > i) { if ((i & size) == 0) CE_DESC(k[i], k[j]); else CE_DESC(k[j], k[i]); } }
; }
; __device__ __forceinline__ void merge16(unsigned (&a)[16], const unsigned (&b)[16]) {
; #pragma unroll
;     for (int i = 0; i < 16; ++i) a[i] = a[i] > b[15 - i] ? a[i] : b[15 - i];
; #pragma unroll
;     for (int stride = 8; stride > 0; stride >>= 1)
; #pragma unroll
;         for (int i = 0; i < 16; ++i) { const int j = i ^ stride; if (j > i) CE_DESC(a[i], a[j]); }
; }
; __device__ __forceinline__ void peer_tile(const Args& A, LAS unsigned char* lds, int tile) {
;     ...
;                 for (int msk = 16; msk <= 32; msk <<= 1) {
; #pragma unroll
;                     for (int i = 0; i < 16; ++i) k1[i] = (unsigned)__shfl_xor((int)k0[i], msk);
;                     merge16(k0, k1); }
	v_max_u32_e32 v149, v17, v144
	v_min_u32_e32 v17, v17, v144
	v_max_u32_e32 v144, v145, v147
	v_min_u32_e32 v145, v145, v147
	v_max_u32_e32 v147, v8, v12
	v_min_u32_e32 v8, v8, v12
	v_max_u32_e32 v12, v5, v10
	v_min_u32_e32 v5, v5, v10
	v_max_u32_e32 v10, v14, v15
	v_min_u32_e32 v14, v14, v15
	v_max_u32_e32 v15, v16, v4
	v_min_u32_e32 v4, v16, v4
	v_max_u32_e32 v151, v152, v24
	v_min_u32_e32 v24, v152, v24
	v_max_u32_e32 v152, v153, v25
	v_min_u32_e32 v25, v153, v25
	v_max_u32_e32 v153, v21, v150
	v_min_u32_e32 v21, v21, v150
	v_max_u32_e32 v150, v26, v161
	v_min_u32_e32 v26, v26, v161
	v_max_u32_e32 v161, v0, v22
	v_min_u32_e32 v0, v0, v22
	v_max_u32_e32 v22, v3, v23
	v_min_u32_e32 v3, v3, v23
	v_max_u32_e32 v23, v20, v1
	v_min_u32_e32 v1, v20, v1
	v_max_u32_e32 v20, v2, v18
	v_min_u32_e32 v2, v2, v18
	v_max_u32_e32 v16, v143, v149
	v_min_u32_e32 v143, v143, v149
	v_max_u32_e32 v149, v148, v144
	v_min_u32_e32 v144, v148, v144
	v_max_u32_e32 v148, v28, v17
	v_min_u32_e32 v17, v28, v17
	v_max_u32_e32 v28, v146, v145
	v_min_u32_e32 v145, v146, v145
	v_max_u32_e32 v146, v147, v10
	v_min_u32_e32 v10, v147, v10
	v_max_u32_e32 v147, v12, v15
	v_min_u32_e32 v12, v12, v15
	v_max_u32_e32 v15, v8, v14
	v_min_u32_e32 v8, v8, v14
	v_max_u32_e32 v14, v5, v4
	v_min_u32_e32 v4, v5, v4
	v_max_u32_e32 v18, v151, v153
	v_min_u32_e32 v151, v151, v153
	v_max_u32_e32 v153, v152, v150
	v_min_u32_e32 v150, v152, v150
	v_max_u32_e32 v152, v24, v21
	v_min_u32_e32 v21, v24, v21
	v_max_u32_e32 v24, v25, v26
	v_min_u32_e32 v25, v25, v26
	v_max_u32_e32 v26, v161, v23
	v_min_u32_e32 v23, v161, v23
	v_max_u32_e32 v161, v22, v20
	v_min_u32_e32 v20, v22, v20
	v_max_u32_e32 v22, v0, v1
	v_min_u32_e32 v0, v0, v1
	v_max_u32_e32 v1, v3, v2
	v_min_u32_e32 v2, v3, v2
	v_min_u32_e32 v5, v16, v149
	v_min_u32_e32 v154, v143, v144
	v_min_u32_e32 v155, v148, v28
	v_min_u32_e32 v156, v17, v145
	v_min_u32_e32 v157, v146, v147
	v_min_u32_e32 v158, v10, v12
	v_min_u32_e32 v159, v15, v14
	v_min_u32_e32 v160, v8, v4
	v_min_u32_e32 v3, v18, v153
	v_min_u32_e32 v162, v151, v150
	v_min_u32_e32 v163, v152, v24
	v_min_u32_e32 v164, v21, v25
	v_min_u32_e32 v165, v26, v161
	v_min_u32_e32 v166, v23, v20
	v_min_u32_e32 v167, v22, v1
	v_min_u32_e32 v168, v0, v2
	v_max3_u32 v16, v16, v149, v168
	v_max3_u32 v0, v5, v0, v2
	v_max3_u32 v2, v143, v144, v167
	v_max3_u32 v1, v154, v22, v1
	v_max3_u32 v5, v148, v28, v166
	v_max3_u32 v20, v155, v23, v20
	v_max3_u32 v17, v17, v145, v165
	v_max3_u32 v22, v156, v26, v161
	v_max3_u32 v23, v146, v147, v164
	v_max3_u32 v21, v157, v21, v25
	v_max3_u32 v10, v10, v12, v163
	v_max3_u32 v12, v158, v152, v24
	v_max3_u32 v14, v15, v14, v162
	v_max3_u32 v15, v159, v151, v150
	v_max3_u32 v3, v8, v4, v3
	v_max3_u32 v4, v160, v18, v153
	v_max_u32_e32 v8, v16, v23
	v_min_u32_e32 v16, v16, v23
	v_max_u32_e32 v18, v0, v21
	v_min_u32_e32 v0, v0, v21
	v_max_u32_e32 v21, v2, v10
	v_min_u32_e32 v2, v2, v10
	v_max_u32_e32 v10, v1, v12
	v_min_u32_e32 v1, v1, v12
	v_max_u32_e32 v12, v5, v14
	v_min_u32_e32 v5, v5, v14
	v_max_u32_e32 v14, v20, v15
	v_min_u32_e32 v15, v20, v15
	v_max_u32_e32 v20, v17, v3
	v_min_u32_e32 v3, v17, v3
	v_max_u32_e32 v17, v22, v4
	v_min_u32_e32 v4, v22, v4
	v_max_u32_e32 v22, v8, v12
	v_min_u32_e32 v8, v8, v12
	v_max_u32_e32 v12, v18, v14
	v_min_u32_e32 v14, v18, v14
	v_max_u32_e32 v18, v21, v20
	v_min_u32_e32 v20, v21, v20
	v_max_u32_e32 v21, v10, v17
	v_min_u32_e32 v10, v10, v17
	v_max_u32_e32 v17, v16, v5
	v_min_u32_e32 v5, v16, v5
	v_max_u32_e32 v16, v0, v15
	v_min_u32_e32 v0, v0, v15
	v_max_u32_e32 v15, v2, v3
	v_min_u32_e32 v2, v2, v3
	v_max_u32_e32 v3, v1, v4
	v_min_u32_e32 v1, v1, v4
	v_max_u32_e32 v4, v22, v18
	v_min_u32_e32 v18, v22, v18
	v_max_u32_e32 v22, v12, v21
	v_min_u32_e32 v12, v12, v21
	v_max_u32_e32 v21, v8, v20
	v_min_u32_e32 v8, v8, v20
	v_max_u32_e32 v20, v14, v10
	v_min_u32_e32 v10, v14, v10
	v_max_u32_e32 v14, v17, v15
	v_min_u32_e32 v15, v17, v15
	v_max_u32_e32 v17, v16, v3
	v_min_u32_e32 v3, v16, v3
	v_max_u32_e32 v16, v5, v2
	v_min_u32_e32 v2, v5, v2
	v_max_u32_e32 v5, v0, v1
	v_min_u32_e32 v0, v0, v1
	v_max_u32_e32 v1, v4, v22
	v_min_u32_e32 v4, v4, v22
	v_max_u32_e32 v22, v18, v12
	v_min_u32_e32 v12, v18, v12
	v_max_u32_e32 v18, v21, v20
	v_min_u32_e32 v20, v21, v20
	v_max_u32_e32 v21, v8, v10
	v_min_u32_e32 v8, v8, v10
	v_max_u32_e32 v10, v14, v17
	v_min_u32_e32 v14, v14, v17
	v_max_u32_e32 v17, v15, v3
	v_min_u32_e32 v3, v15, v3
	v_max_u32_e32 v15, v16, v5
	v_min_u32_e32 v5, v16, v5
	v_max_u32_e32 v16, v2, v0
	v_min_u32_e32 v0, v2, v0
	ds_bpermute_b32 v2, v27, v1
	ds_bpermute_b32 v23, v27, v4
	ds_bpermute_b32 v24, v27, v22
	ds_bpermute_b32 v25, v27, v12
	ds_bpermute_b32 v26, v27, v18
	ds_bpermute_b32 v28, v27, v20
	ds_bpermute_b32 v143, v27, v21
	ds_bpermute_b32 v144, v27, v8
	ds_bpermute_b32 v145, v27, v10
	ds_bpermute_b32 v146, v27, v14
	ds_bpermute_b32 v147, v27, v17
	ds_bpermute_b32 v148, v27, v0
	ds_bpermute_b32 v149, v27, v16
	ds_bpermute_b32 v150, v27, v5
	ds_bpermute_b32 v151, v27, v15
	ds_bpermute_b32 v27, v27, v3
	s_waitcnt lgkmcnt(4)
	v_max_u32_e32 v1, v1, v148
	s_waitcnt lgkmcnt(3)
	v_max_u32_e32 v4, v4, v149
	s_waitcnt lgkmcnt(2)
	v_max_u32_e32 v22, v22, v150
	s_waitcnt lgkmcnt(1)
	v_max_u32_e32 v12, v12, v151
	s_waitcnt lgkmcnt(0)
; __device__ __forceinline__ void peer_tile(const Args& A, LAS unsigned char* lds, int tile) {
;     ...
;                 for (int msk = 16; msk <= 32; msk <<= 1) {
; #pragma unroll
;                     for (int i = 0; i < 16; ++i) k1[i] = (unsigned)__shfl_xor((int)k0[i], msk);
;                     merge16(k0, k1); }
; #pragma unroll
;                 for (int i = 0; i < 16; ++i) LA[hh][p][i] = k0[i];
;             }
;         }
;         {
;             const int h = 4 * hg + g;
;             unsigned L2[2][16];
; #pragma unroll
;             for (int p = 0; p < 2; ++p)
; #pragma unroll
;                 for (int i = 0; i < 16; ++i) L2[p][i] = (g & 2) ? ((g & 1) ? LA[3][p][i] : LA[2][p][i]) : ((g & 1) ? LA[1][p][i] : LA[0][p][i]);
	v_max_u32_e32 v18, v18, v27
	v_max_u32_e32 v20, v20, v147
	v_max_u32_e32 v21, v21, v146
	v_max_u32_e32 v8, v8, v145
	v_max_u32_e32 v10, v10, v144
	v_max_u32_e32 v14, v14, v143
	v_max_u32_e32 v17, v17, v28
	v_max_u32_e32 v3, v3, v26
	v_max_u32_e32 v15, v15, v25
	v_max_u32_e32 v5, v5, v24
	v_max_u32_e32 v16, v16, v23
	v_max_u32_e32 v0, v0, v2
	v_max_u32_e32 v2, v1, v10
	v_min_u32_e32 v1, v1, v10
	v_max_u32_e32 v10, v4, v14
	v_min_u32_e32 v4, v4, v14
	v_max_u32_e32 v14, v22, v17
	v_min_u32_e32 v17, v22, v17
	v_max_u32_e32 v22, v12, v3
	v_min_u32_e32 v3, v12, v3
	v_max_u32_e32 v12, v18, v15
	v_min_u32_e32 v15, v18, v15
	v_max_u32_e32 v18, v20, v5
	v_min_u32_e32 v5, v20, v5
	v_max_u32_e32 v20, v21, v16
	v_min_u32_e32 v16, v21, v16
	v_max_u32_e32 v21, v8, v0
	v_min_u32_e32 v0, v8, v0
	v_max_u32_e32 v8, v2, v12
	v_min_u32_e32 v2, v2, v12
	v_max_u32_e32 v12, v10, v18
	v_min_u32_e32 v10, v10, v18
	v_max_u32_e32 v18, v14, v20
	v_min_u32_e32 v14, v14, v20
	v_max_u32_e32 v20, v22, v21
	v_min_u32_e32 v21, v22, v21
	v_max_u32_e32 v22, v1, v15
	v_min_u32_e32 v1, v1, v15
	v_max_u32_e32 v15, v4, v5
	v_min_u32_e32 v4, v4, v5
	v_max_u32_e32 v5, v17, v16
	v_min_u32_e32 v16, v17, v16
	v_max_u32_e32 v17, v3, v0
	v_min_u32_e32 v0, v3, v0
	v_max_u32_e32 v3, v8, v18
	v_min_u32_e32 v8, v8, v18
	v_max_u32_e32 v18, v12, v20
	v_min_u32_e32 v12, v12, v20
	v_max_u32_e32 v20, v2, v14
	v_min_u32_e32 v2, v2, v14
	v_max_u32_e32 v14, v10, v21
	v_min_u32_e32 v10, v10, v21
	v_max_u32_e32 v21, v22, v5
	v_min_u32_e32 v5, v22, v5
	v_max_u32_e32 v22, v15, v17
	v_min_u32_e32 v15, v15, v17
	v_max_u32_e32 v17, v1, v16
	v_min_u32_e32 v1, v1, v16
	v_max_u32_e32 v16, v4, v0
	v_min_u32_e32 v0, v4, v0
	v_max_u32_e32 v4, v3, v18
	v_min_u32_e32 v3, v3, v18
	v_max_u32_e32 v18, v8, v12
	v_min_u32_e32 v8, v8, v12
	v_max_u32_e32 v12, v20, v14
	v_min_u32_e32 v14, v20, v14
	v_max_u32_e32 v20, v2, v10
	v_min_u32_e32 v2, v2, v10
	v_max_u32_e32 v10, v21, v22
	v_min_u32_e32 v21, v21, v22
	v_max_u32_e32 v22, v5, v15
	v_min_u32_e32 v5, v5, v15
	v_max_u32_e32 v15, v17, v16
	v_min_u32_e32 v16, v17, v16
	v_max_u32_e32 v17, v1, v0
	v_min_u32_e32 v0, v1, v0
	ds_bpermute_b32 v1, v29, v4
	ds_bpermute_b32 v23, v29, v3
	ds_bpermute_b32 v24, v29, v18
	ds_bpermute_b32 v25, v29, v8
	ds_bpermute_b32 v26, v29, v12
	ds_bpermute_b32 v27, v29, v14
	ds_bpermute_b32 v28, v29, v20
	ds_bpermute_b32 v143, v29, v2
	ds_bpermute_b32 v144, v29, v10
	ds_bpermute_b32 v145, v29, v21
	ds_bpermute_b32 v146, v29, v22
	ds_bpermute_b32 v147, v29, v0
	ds_bpermute_b32 v148, v29, v17
	ds_bpermute_b32 v149, v29, v16
	ds_bpermute_b32 v150, v29, v15
	ds_bpermute_b32 v29, v29, v5
	s_waitcnt lgkmcnt(4)
	v_max_u32_e32 v4, v4, v147
	s_waitcnt lgkmcnt(3)
	v_max_u32_e32 v3, v3, v148
	s_waitcnt lgkmcnt(2)
	v_max_u32_e32 v18, v18, v149
	s_waitcnt lgkmcnt(1)
	v_max_u32_e32 v8, v8, v150
	s_waitcnt lgkmcnt(0)
	v_max_u32_e32 v12, v12, v29
	v_max_u32_e32 v14, v14, v146
	v_max_u32_e32 v20, v20, v145
	v_max_u32_e32 v2, v2, v144
	v_max_u32_e32 v10, v10, v143
	v_max_u32_e32 v21, v21, v28
	v_max_u32_e32 v22, v22, v27
	v_max_u32_e32 v5, v5, v26
	v_max_u32_e32 v15, v15, v25
	v_max_u32_e32 v16, v16, v24
	v_max_u32_e32 v17, v17, v23
	v_max_u32_e32 v0, v0, v1
	v_max_u32_e32 v1, v4, v10
	v_min_u32_e32 v4, v4, v10
	v_max_u32_e32 v10, v3, v21
	v_min_u32_e32 v3, v3, v21
	v_max_u32_e32 v21, v18, v22
	v_min_u32_e32 v18, v18, v22
	v_max_u32_e32 v22, v8, v5
	v_min_u32_e32 v5, v8, v5
	v_max_u32_e32 v8, v12, v15
	v_min_u32_e32 v12, v12, v15
	v_max_u32_e32 v15, v14, v16
	v_min_u32_e32 v14, v14, v16
	v_max_u32_e32 v16, v20, v17
	v_min_u32_e32 v17, v20, v17
	v_max_u32_e32 v20, v2, v0
	v_min_u32_e32 v0, v2, v0
	v_max_u32_e32 v2, v1, v8
	v_min_u32_e32 v1, v1, v8
	v_max_u32_e32 v8, v10, v15
	v_min_u32_e32 v10, v10, v15
	v_max_u32_e32 v15, v21, v16
	v_min_u32_e32 v16, v21, v16
	v_max_u32_e32 v21, v22, v20
	v_min_u32_e32 v20, v22, v20
	v_max_u32_e32 v22, v4, v12
	v_min_u32_e32 v4, v4, v12
	v_max_u32_e32 v12, v3, v14
	v_min_u32_e32 v3, v3, v14
	v_max_u32_e32 v14, v18, v17
	v_min_u32_e32 v17, v18, v17
	v_max_u32_e32 v18, v5, v0
	v_min_u32_e32 v0, v5, v0
	v_max_u32_e32 v5, v2, v15
	v_min_u32_e32 v2, v2, v15
	v_max_u32_e32 v15, v8, v21
	v_min_u32_e32 v8, v8, v21
	v_max_u32_e32 v21, v1, v16
	v_min_u32_e32 v1, v1, v16
	v_max_u32_e32 v16, v10, v20
	v_min_u32_e32 v10, v10, v20
	v_max_u32_e32 v20, v22, v14
	v_min_u32_e32 v14, v22, v14
	v_max_u32_e32 v22, v12, v18
	v_min_u32_e32 v12, v12, v18
	v_max_u32_e32 v18, v4, v17
	v_min_u32_e32 v4, v4, v17
	v_max_u32_e32 v17, v3, v0
	v_min_u32_e32 v0, v3, v0
	v_max_u32_e32 v3, v5, v15
	v_min_u32_e32 v5, v5, v15
	v_max_u32_e32 v15, v2, v8
	v_min_u32_e32 v2, v2, v8
	v_max_u32_e32 v8, v21, v16
	v_min_u32_e32 v16, v21, v16
	v_max_u32_e32 v21, v1, v10
	v_min_u32_e32 v1, v1, v10
	v_max_u32_e32 v10, v20, v22
	v_min_u32_e32 v20, v20, v22
	v_max_u32_e32 v22, v14, v12
	v_min_u32_e32 v12, v14, v12
	v_max_u32_e32 v14, v18, v17
	v_min_u32_e32 v17, v18, v17
	v_max_u32_e32 v18, v4, v0
	v_min_u32_e32 v0, v4, v0
	v_and_b32_e32 v4, 16, v19
	v_cmp_eq_u32_e32 vcc, 0, v4
	v_cndmask_b32_e64 v23, v77, v45, s[0:1]
	v_cndmask_b32_e64 v24, v76, v44, s[0:1]
	v_cndmask_b32_e32 v4, v142, v109, vcc
	v_cndmask_b32_e64 v4, v4, v23, s[4:5]
	v_cndmask_b32_e32 v23, v141, v108, vcc
	v_cndmask_b32_e64 v23, v23, v24, s[4:5]
	v_cndmask_b32_e32 v24, v140, v107, vcc
	v_cndmask_b32_e64 v25, v75, v43, s[0:1]
	v_cndmask_b32_e64 v24, v24, v25, s[4:5]
	v_cndmask_b32_e32 v25, v139, v106, vcc
	v_cndmask_b32_e64 v26, v74, v42, s[0:1]
	v_cndmask_b32_e64 v25, v25, v26, s[4:5]
	v_cndmask_b32_e32 v26, v138, v105, vcc
	v_cndmask_b32_e64 v27, v73, v41, s[0:1]
	v_cndmask_b32_e64 v26, v26, v27, s[4:5]
; __device__ __forceinline__ float key2f(unsigned k) { const unsigned u = (k & 0x80000000u) ? (k & 0x7fffffffu) : ~k; return __uint_as_float(u); }
; __device__ __forceinline__ void peer_tile(const Args& A, LAS unsigned char* lds, int tile) {
;     ...
;                 for (int i = 0; i < 16; ++i) L2[p][i] = (g & 2) ? ((g & 1) ? LA[3][p][i] : LA[2][p][i]) : ((g & 1) ? LA[1][p][i] : LA[0][p][i]);
;             float va[16], vb[16];
; #pragma unroll
;             for (int i = 0; i < 16; ++i) { va[i] = key2f(L2[0][i] & ~127u); vb[i] = key2f(L2[1][i] & ~127u); idx[i] = 127u - (L2[0][i] & 127u); idx[16 + i] = 127u - (L2[1][i] & 127u); }
	v_cndmask_b32_e32 v27, v137, v104, vcc
	v_cndmask_b32_e64 v28, v72, v40, s[0:1]
	v_cndmask_b32_e64 v27, v27, v28, s[4:5]
	v_cndmask_b32_e32 v28, v136, v103, vcc
	v_cndmask_b32_e64 v29, v71, v39, s[0:1]
	v_cndmask_b32_e64 v28, v28, v29, s[4:5]
	v_cndmask_b32_e32 v29, v135, v102, vcc
	v_cndmask_b32_e64 v29, v29, v38, s[4:5]
	v_cndmask_b32_e32 v38, v134, v101, vcc
	v_cndmask_b32_e64 v37, v38, v37, s[4:5]
	v_cndmask_b32_e32 v38, v133, v100, vcc
	v_cndmask_b32_e64 v36, v38, v36, s[4:5]
	v_cndmask_b32_e32 v38, v132, v99, vcc
	v_cndmask_b32_e64 v38, v38, v35, s[4:5]
	v_cndmask_b32_e32 v35, v131, v98, vcc
	v_cndmask_b32_e64 v39, v35, v34, s[4:5]
	v_cndmask_b32_e32 v34, v130, v97, vcc
	v_cndmask_b32_e64 v33, v34, v33, s[4:5]
	v_cndmask_b32_e32 v34, v129, v96, vcc
	v_cndmask_b32_e64 v40, v34, v32, s[4:5]
	v_cndmask_b32_e32 v32, v128, v95, vcc
	v_cndmask_b32_e64 v42, v32, v31, s[4:5]
	v_cndmask_b32_e32 v31, v127, v94, vcc
	v_cndmask_b32_e64 v43, v31, v30, s[4:5]
	v_cndmask_b32_e32 v3, v3, v126, vcc
	v_cndmask_b32_e64 v30, v93, v61, s[0:1]
	v_cndmask_b32_e64 v3, v3, v30, s[4:5]
	v_cndmask_b32_e32 v5, v5, v125, vcc
	v_cndmask_b32_e64 v30, v92, v60, s[0:1]
	v_cndmask_b32_e64 v30, v5, v30, s[4:5]
	v_cndmask_b32_e32 v5, v15, v124, vcc
	v_cndmask_b32_e64 v15, v91, v59, s[0:1]
	v_cndmask_b32_e64 v15, v5, v15, s[4:5]
	v_cndmask_b32_e32 v2, v2, v123, vcc
	v_cndmask_b32_e64 v5, v90, v58, s[0:1]
	v_cndmask_b32_e64 v31, v2, v5, s[4:5]
	v_cndmask_b32_e32 v2, v8, v122, vcc
	v_cndmask_b32_e64 v5, v89, v57, s[0:1]
	v_cndmask_b32_e64 v8, v2, v5, s[4:5]
	v_cndmask_b32_e32 v2, v16, v121, vcc
	v_cndmask_b32_e64 v5, v88, v56, s[0:1]
	v_cndmask_b32_e64 v32, v2, v5, s[4:5]
	v_cndmask_b32_e32 v2, v21, v120, vcc
	v_cndmask_b32_e64 v5, v87, v55, s[0:1]
	v_cndmask_b32_e64 v21, v2, v5, s[4:5]
	v_cndmask_b32_e32 v1, v1, v119, vcc
	v_cndmask_b32_e64 v2, v86, v54, s[0:1]
	v_cndmask_b32_e64 v34, v1, v2, s[4:5]
	v_cndmask_b32_e32 v1, v10, v118, vcc
	v_cndmask_b32_e64 v2, v85, v53, s[0:1]
	v_cndmask_b32_e64 v41, v1, v2, s[4:5]
	v_cndmask_b32_e32 v1, v20, v117, vcc
	v_cndmask_b32_e64 v2, v84, v52, s[0:1]
	v_cndmask_b32_e64 v44, v1, v2, s[4:5]
	v_cndmask_b32_e32 v1, v22, v116, vcc
	v_cndmask_b32_e64 v2, v83, v51, s[0:1]
	v_cndmask_b32_e64 v45, v1, v2, s[4:5]
	v_cndmask_b32_e32 v1, v12, v115, vcc
	v_cndmask_b32_e64 v2, v82, v50, s[0:1]
	v_cndmask_b32_e64 v50, v1, v2, s[4:5]
	v_cndmask_b32_e32 v1, v14, v114, vcc
	v_cndmask_b32_e64 v2, v81, v49, s[0:1]
	v_cndmask_b32_e64 v49, v1, v2, s[4:5]
	v_cndmask_b32_e32 v1, v17, v112, vcc
	v_cndmask_b32_e64 v2, v80, v48, s[0:1]
	v_cndmask_b32_e64 v48, v1, v2, s[4:5]
	v_cndmask_b32_e32 v1, v18, v111, vcc
	v_cndmask_b32_e64 v2, v79, v47, s[0:1]
	v_cndmask_b32_e64 v47, v1, v2, s[4:5]
	v_cndmask_b32_e32 v0, v0, v110, vcc
	v_cndmask_b32_e64 v1, v78, v46, s[0:1]
	v_cndmask_b32_e64 v46, v0, v1, s[4:5]
	v_and_b32_e32 v0, 0x7fffff80, v4
	v_bitop3_b32 v1, v4, s19, v4 bitop3:0xcf
	v_cmp_gt_i32_e32 vcc, 0, v4
	v_bitop3_b32 v2, v4, s19, v4 bitop3:0xc
	v_bitop3_b32 v4, v23, s19, v23 bitop3:0xcf
	v_cndmask_b32_e32 v20, v1, v0, vcc
	v_and_b32_e32 v0, 0x7fffff80, v3
	v_bitop3_b32 v1, v3, s19, v3 bitop3:0xcf
	v_cmp_gt_i32_e32 vcc, 0, v3
	v_add_u32_e32 v5, 0, v6
	v_bitop3_b32 v3, v3, s19, v3 bitop3:0xc
	v_cndmask_b32_e32 v1, v1, v0, vcc
	v_and_b32_e32 v0, 0x7fffff80, v23
	v_cmp_gt_i32_e32 vcc, 0, v23
	v_bitop3_b32 v14, v31, s19, v31 bitop3:0xcf
	v_bitop3_b32 v6, v24, s19, v24 bitop3:0xc
	v_cndmask_b32_e32 v18, v4, v0, vcc
	v_and_b32_e32 v0, 0x7fffff80, v30
	v_bitop3_b32 v4, v30, s19, v30 bitop3:0xcf
	v_cmp_gt_i32_e32 vcc, 0, v30
	v_bitop3_b32 v10, v15, s19, v15 bitop3:0xc
	v_bitop3_b32 v16, v32, s19, v32 bitop3:0xcf
	v_cndmask_b32_e32 v0, v4, v0, vcc
	v_bitop3_b32 v4, v23, s19, v23 bitop3:0xc
	ds_write2_b32 v5, v2, v4 offset1:1
	v_bitop3_b32 v2, v30, s19, v30 bitop3:0xc
	ds_write2_b32 v5, v3, v2 offset0:16 offset1:17
	v_and_b32_e32 v2, 0x7fffff80, v24
	v_bitop3_b32 v3, v24, s19, v24 bitop3:0xcf
	v_cmp_gt_i32_e32 vcc, 0, v24
	v_bitop3_b32 v4, v25, s19, v25 bitop3:0xcf
	v_bitop3_b32 v22, v29, s19, v29 bitop3:0xcf
	v_cndmask_b32_e32 v12, v3, v2, vcc
	v_and_b32_e32 v2, 0x7fffff80, v15
	v_bitop3_b32 v3, v15, s19, v15 bitop3:0xcf
	v_cmp_gt_i32_e32 vcc, 0, v15
	v_bitop3_b32 v15, v27, s19, v27 bitop3:0xcf
	v_bitop3_b32 v24, v34, s19, v34 bitop3:0xcf
	v_cndmask_b32_e32 v3, v3, v2, vcc
	v_and_b32_e32 v2, 0x7fffff80, v25
	v_cmp_gt_i32_e32 vcc, 0, v25
	s_nop 1
	v_cndmask_b32_e32 v4, v4, v2, vcc
	v_and_b32_e32 v2, 0x7fffff80, v31
	v_cmp_gt_i32_e32 vcc, 0, v31
	s_nop 1
	v_cndmask_b32_e32 v2, v14, v2, vcc
	v_bitop3_b32 v14, v25, s19, v25 bitop3:0xc
	ds_write2_b32 v5, v6, v14 offset0:2 offset1:3
	v_bitop3_b32 v6, v31, s19, v31 bitop3:0xc
	ds_write2_b32 v5, v10, v6 offset0:18 offset1:19
	v_and_b32_e32 v6, 0x7fffff80, v26
	v_bitop3_b32 v10, v26, s19, v26 bitop3:0xcf
	v_cmp_gt_i32_e32 vcc, 0, v26
	v_bitop3_b32 v25, v36, s19, v36 bitop3:0xcf
	s_nop 0
	v_cndmask_b32_e32 v14, v10, v6, vcc
	v_and_b32_e32 v6, 0x7fffff80, v8
	v_bitop3_b32 v10, v8, s19, v8 bitop3:0xcf
	v_cmp_gt_i32_e32 vcc, 0, v8
	v_bitop3_b32 v8, v8, s19, v8 bitop3:0xc
	s_nop 0
	v_cndmask_b32_e32 v17, v10, v6, vcc
	v_and_b32_e32 v10, 0x7fffff80, v27
	v_cmp_gt_i32_e32 vcc, 0, v27
	v_bitop3_b32 v6, v26, s19, v26 bitop3:0xc
	v_bitop3_b32 v26, v43, s19, v43 bitop3:0xcf
	v_cndmask_b32_e32 v10, v15, v10, vcc
	v_and_b32_e32 v15, 0x7fffff80, v32
	v_cmp_gt_i32_e32 vcc, 0, v32
	s_nop 1
	v_cndmask_b32_e32 v16, v16, v15, vcc
	v_bitop3_b32 v15, v27, s19, v27 bitop3:0xc
	ds_write2_b32 v5, v6, v15 offset0:4 offset1:5
	v_bitop3_b32 v6, v32, s19, v32 bitop3:0xc
	ds_write2_b32 v5, v8, v6 offset0:20 offset1:21
	v_and_b32_e32 v6, 0x7fffff80, v28
; __device__ __forceinline__ float key2f(unsigned k) { const unsigned u = (k & 0x80000000u) ? (k & 0x7fffffffu) : ~k; return __uint_as_float(u); }
; #define CK(i, j) ((f2key(va[i] + vb[j]) & ~255u) | (unsigned)(255 - (16 * (i) + (j))))
; __device__ __forceinline__ void peer_tile(const Args& A, LAS unsigned char* lds, int tile) {
;     ...
;             float va[16], vb[16];
; #pragma unroll
;             for (int i = 0; i < 16; ++i) { va[i] = key2f(L2[0][i] & ~127u); vb[i] = key2f(L2[1][i] & ~127u); idx[i] = 127u - (L2[0][i] & 127u); idx[16 + i] = 127u - (L2[1][i] & 127u); }
;     ...
;             unsigned Lf[16], Bt[16];
; #pragma unroll
;             for (int j = 0; j < 16; ++j) Lf[j] = CK(0, j);
	v_bitop3_b32 v8, v28, s19, v28 bitop3:0xcf
	v_cmp_gt_i32_e32 vcc, 0, v28
	v_bitop3_b32 v15, v21, s19, v21 bitop3:0xcf
	s_nop 0
	v_cndmask_b32_e32 v8, v8, v6, vcc
	v_and_b32_e32 v6, 0x7fffff80, v21
	v_cmp_gt_i32_e32 vcc, 0, v21
	v_bitop3_b32 v21, v21, s19, v21 bitop3:0xc
	s_nop 0
	v_cndmask_b32_e32 v23, v15, v6, vcc
	v_and_b32_e32 v6, 0x7fffff80, v29
	v_cmp_gt_i32_e32 vcc, 0, v29
	v_bitop3_b32 v15, v28, s19, v28 bitop3:0xc
	s_nop 0
	v_cndmask_b32_e32 v6, v22, v6, vcc
	v_and_b32_e32 v22, 0x7fffff80, v34
	v_cmp_gt_i32_e32 vcc, 0, v34
	s_nop 1
	v_cndmask_b32_e32 v22, v24, v22, vcc
	v_bitop3_b32 v24, v29, s19, v29 bitop3:0xc
	ds_write2_b32 v5, v15, v24 offset0:6 offset1:7
	v_bitop3_b32 v15, v34, s19, v34 bitop3:0xc
	ds_write2_b32 v5, v21, v15 offset0:22 offset1:23
	v_and_b32_e32 v15, 0x7fffff80, v37
	v_bitop3_b32 v21, v37, s19, v37 bitop3:0xcf
	v_cmp_gt_i32_e32 vcc, 0, v37
	v_and_b32_e32 v24, 0x7fffff80, v36
	s_nop 0
	v_cndmask_b32_e32 v27, v21, v15, vcc
	v_and_b32_e32 v15, 0x7fffff80, v41
	v_bitop3_b32 v21, v41, s19, v41 bitop3:0xcf
	v_cmp_gt_i32_e32 vcc, 0, v41
	s_nop 1
	v_cndmask_b32_e32 v35, v21, v15, vcc
	v_cmp_gt_i32_e32 vcc, 0, v36
	v_bitop3_b32 v15, v37, s19, v37 bitop3:0xc
	v_bitop3_b32 v21, v41, s19, v41 bitop3:0xc
	v_cndmask_b32_e32 v28, v25, v24, vcc
	v_and_b32_e32 v24, 0x7fffff80, v44
	v_bitop3_b32 v25, v44, s19, v44 bitop3:0xcf
	v_cmp_gt_i32_e32 vcc, 0, v44
	s_nop 1
	v_cndmask_b32_e32 v34, v25, v24, vcc
	v_bitop3_b32 v24, v36, s19, v36 bitop3:0xc
	ds_write2_b32 v5, v15, v24 offset0:8 offset1:9
	v_bitop3_b32 v15, v44, s19, v44 bitop3:0xc
	ds_write2_b32 v5, v21, v15 offset0:24 offset1:25
	v_and_b32_e32 v15, 0x7fffff80, v38
	v_bitop3_b32 v21, v38, s19, v38 bitop3:0xcf
	v_cmp_gt_i32_e32 vcc, 0, v38
	v_and_b32_e32 v24, 0x7fffff80, v39
	v_bitop3_b32 v25, v39, s19, v39 bitop3:0xcf
	v_cndmask_b32_e32 v29, v21, v15, vcc
	v_and_b32_e32 v15, 0x7fffff80, v45
	v_bitop3_b32 v21, v45, s19, v45 bitop3:0xcf
	v_cmp_gt_i32_e32 vcc, 0, v45
	s_nop 1
	v_cndmask_b32_e32 v37, v21, v15, vcc
	v_cmp_gt_i32_e32 vcc, 0, v39
	v_bitop3_b32 v15, v38, s19, v38 bitop3:0xc
	v_bitop3_b32 v21, v45, s19, v45 bitop3:0xc
	v_cndmask_b32_e32 v30, v25, v24, vcc
	v_and_b32_e32 v24, 0x7fffff80, v50
	v_bitop3_b32 v25, v50, s19, v50 bitop3:0xcf
	v_cmp_gt_i32_e32 vcc, 0, v50
	s_nop 1
	v_cndmask_b32_e32 v36, v25, v24, vcc
	v_bitop3_b32 v24, v39, s19, v39 bitop3:0xc
	ds_write2_b32 v5, v15, v24 offset0:10 offset1:11
	v_bitop3_b32 v15, v50, s19, v50 bitop3:0xc
	ds_write2_b32 v5, v21, v15 offset0:26 offset1:27
	v_and_b32_e32 v15, 0x7fffff80, v33
	v_bitop3_b32 v21, v33, s19, v33 bitop3:0xcf
	v_cmp_gt_i32_e32 vcc, 0, v33
	v_and_b32_e32 v24, 0x7fffff80, v40
	v_bitop3_b32 v25, v40, s19, v40 bitop3:0xcf
	v_cndmask_b32_e32 v31, v21, v15, vcc
	v_and_b32_e32 v15, 0x7fffff80, v49
	v_bitop3_b32 v21, v49, s19, v49 bitop3:0xcf
	v_cmp_gt_i32_e32 vcc, 0, v49
	s_nop 1
	v_cndmask_b32_e32 v39, v21, v15, vcc
	v_cmp_gt_i32_e32 vcc, 0, v40
	v_bitop3_b32 v15, v33, s19, v33 bitop3:0xc
	v_bitop3_b32 v21, v49, s19, v49 bitop3:0xc
	v_cndmask_b32_e32 v32, v25, v24, vcc
	v_and_b32_e32 v24, 0x7fffff80, v48
	v_bitop3_b32 v25, v48, s19, v48 bitop3:0xcf
	v_cmp_gt_i32_e32 vcc, 0, v48
	v_bitop3_b32 v33, v46, s19, v46 bitop3:0xcf
	s_nop 0
	v_cndmask_b32_e32 v38, v25, v24, vcc
	v_bitop3_b32 v24, v40, s19, v40 bitop3:0xc
	ds_write2_b32 v5, v15, v24 offset0:12 offset1:13
	v_bitop3_b32 v15, v48, s19, v48 bitop3:0xc
	ds_write2_b32 v5, v21, v15 offset0:28 offset1:29
	v_and_b32_e32 v15, 0x7fffff80, v42
	v_bitop3_b32 v21, v42, s19, v42 bitop3:0xcf
	v_cmp_gt_i32_e32 vcc, 0, v42
	v_and_b32_e32 v24, 0x7fffff80, v43
	s_nop 0
	v_cndmask_b32_e32 v25, v21, v15, vcc
	v_and_b32_e32 v15, 0x7fffff80, v47
	v_bitop3_b32 v21, v47, s19, v47 bitop3:0xcf
	v_cmp_gt_i32_e32 vcc, 0, v47
	s_nop 1
	v_cndmask_b32_e32 v41, v21, v15, vcc
	v_cmp_gt_i32_e32 vcc, 0, v43
	v_bitop3_b32 v21, v47, s19, v47 bitop3:0xc
	v_bitop3_b32 v15, v42, s19, v42 bitop3:0xc
	v_cndmask_b32_e32 v26, v26, v24, vcc
	v_and_b32_e32 v24, 0x7fffff80, v46
	v_cmp_gt_i32_e32 vcc, 0, v46
	v_pk_add_f32 v[34:35], v[20:21], v[34:35] op_sel_hi:[0,1]
	s_nop 0
	v_cndmask_b32_e32 v40, v33, v24, vcc
	v_bitop3_b32 v24, v43, s19, v43 bitop3:0xc
	v_pk_add_f32 v[42:43], v[20:21], v[0:1] op_sel_hi:[0,1]
	ds_write2_b32 v5, v15, v24 offset0:14 offset1:15
	v_not_b32_e32 v15, v43
	v_or_b32_e32 v33, 0x80000000, v43
	v_cmp_gt_i32_e32 vcc, 0, v43
	v_or_b32_e32 v43, 0x80000000, v42
	v_bitop3_b32 v24, v46, s19, v46 bitop3:0xc
	v_cndmask_b32_e32 v15, v33, v15, vcc
	v_or_b32_e32 v33, 0xff, v15
	v_not_b32_e32 v15, v42
	v_cmp_gt_i32_e32 vcc, 0, v42
	ds_write2_b32 v5, v21, v24 offset0:30 offset1:31
	s_waitcnt lgkmcnt(0)
; #define CK(i, j) ((f2key(va[i] + vb[j]) & ~255u) | (unsigned)(255 - (16 * (i) + (j))))
; __device__ __forceinline__ void peer_tile(const Args& A, LAS unsigned char* lds, int tile) {
;     ...
;             unsigned Lf[16], Bt[16];
; #pragma unroll
;             for (int j = 0; j < 16; ++j) Lf[j] = CK(0, j);
; #pragma unroll
;             for (int j = 0; j < 8; ++j) Bt[j] = CK(1, j);
; #pragma unroll
;             for (int j = 0; j < 5; ++j) Bt[8 + j] = CK(2, j);
; #pragma unroll
;             for (int j = 0; j < 3; ++j) Bt[13 + j] = CK(4, j);
;             sort16_desc(Bt); merge16(Lf, Bt);
	s_nop 0
	v_cndmask_b32_e32 v15, v43, v15, vcc
	v_and_b32_e32 v15, 0xffffff00, v15
	v_pk_add_f32 v[42:43], v[20:21], v[2:3] op_sel_hi:[0,1]
	v_or_b32_e32 v44, 0xfe, v15
	v_not_b32_e32 v15, v43
	v_or_b32_e32 v45, 0x80000000, v43
	v_cmp_gt_i32_e32 vcc, 0, v43
	v_or_b32_e32 v43, 0x80000000, v42
	s_nop 0
	v_cndmask_b32_e32 v15, v45, v15, vcc
	v_and_b32_e32 v15, 0xffffff00, v15
	v_or_b32_e32 v45, 0xfd, v15
	v_not_b32_e32 v15, v42
	v_cmp_gt_i32_e32 vcc, 0, v42
	s_nop 1
	v_cndmask_b32_e32 v15, v43, v15, vcc
	v_and_b32_e32 v15, 0xffffff00, v15
	v_pk_add_f32 v[42:43], v[20:21], v[16:17] op_sel_hi:[0,1]
	v_or_b32_e32 v46, 0xfc, v15
	v_not_b32_e32 v15, v43
	v_or_b32_e32 v47, 0x80000000, v43
	v_cmp_gt_i32_e32 vcc, 0, v43
	v_or_b32_e32 v43, 0x80000000, v42
	s_nop 0
	v_cndmask_b32_e32 v15, v47, v15, vcc
	v_and_b32_e32 v15, 0xffffff00, v15
	v_or_b32_e32 v47, 0xfb, v15
	v_not_b32_e32 v15, v42
	v_cmp_gt_i32_e32 vcc, 0, v42
	s_nop 1
	v_cndmask_b32_e32 v15, v43, v15, vcc
	v_and_b32_e32 v15, 0xffffff00, v15
	v_pk_add_f32 v[42:43], v[20:21], v[22:23] op_sel_hi:[0,1]
	v_or_b32_e32 v48, 0xfa, v15
	v_not_b32_e32 v15, v43
	v_or_b32_e32 v49, 0x80000000, v43
	v_cmp_gt_i32_e32 vcc, 0, v43
	v_pk_add_f32 v[22:23], v[18:19], v[22:23] op_sel_hi:[0,1]
	s_nop 0
	v_cndmask_b32_e32 v15, v49, v15, vcc
	v_and_b32_e32 v15, 0xffffff00, v15
	v_or_b32_e32 v43, 0xf9, v15
	v_not_b32_e32 v15, v42
	v_or_b32_e32 v49, 0x80000000, v42
	v_cmp_gt_i32_e32 vcc, 0, v42
	s_nop 1
	v_cndmask_b32_e32 v15, v49, v15, vcc
	v_and_b32_e32 v15, 0xffffff00, v15
	v_or_b32_e32 v42, 0xf8, v15
	v_not_b32_e32 v15, v35
	v_or_b32_e32 v49, 0x80000000, v35
	v_cmp_gt_i32_e32 vcc, 0, v35
	v_or_b32_e32 v35, 0x80000000, v34
	s_nop 0
	v_cndmask_b32_e32 v15, v49, v15, vcc
	v_and_b32_e32 v15, 0xffffff00, v15
	v_or_b32_e32 v49, 0xf7, v15
	v_not_b32_e32 v15, v34
	v_cmp_gt_i32_e32 vcc, 0, v34
	s_nop 1
	v_cndmask_b32_e32 v15, v35, v15, vcc
	v_and_b32_e32 v15, 0xffffff00, v15
	v_pk_add_f32 v[34:35], v[20:21], v[36:37] op_sel_hi:[0,1]
	v_or_b32_e32 v50, 0xf6, v15
	v_not_b32_e32 v15, v35
	v_or_b32_e32 v36, 0x80000000, v35
	v_cmp_gt_i32_e32 vcc, 0, v35
	v_or_b32_e32 v35, 0x80000000, v34
	s_nop 0
	v_cndmask_b32_e32 v15, v36, v15, vcc
	v_and_b32_e32 v15, 0xffffff00, v15
	v_or_b32_e32 v36, 0xf5, v15
	v_not_b32_e32 v15, v34
	v_cmp_gt_i32_e32 vcc, 0, v34
	s_nop 1
	v_cndmask_b32_e32 v15, v35, v15, vcc
	v_and_b32_e32 v15, 0xffffff00, v15
	v_pk_add_f32 v[34:35], v[20:21], v[38:39] op_sel_hi:[0,1]
	v_or_b32_e32 v37, 0xf4, v15
	v_not_b32_e32 v15, v35
	v_or_b32_e32 v38, 0x80000000, v35
	v_cmp_gt_i32_e32 vcc, 0, v35
	v_or_b32_e32 v35, 0x80000000, v34
	s_nop 0
	v_cndmask_b32_e32 v15, v38, v15, vcc
	v_and_b32_e32 v15, 0xffffff00, v15
	v_or_b32_e32 v38, 0xf3, v15
	v_not_b32_e32 v15, v34
	v_cmp_gt_i32_e32 vcc, 0, v34
	s_nop 1
	v_cndmask_b32_e32 v15, v35, v15, vcc
	v_and_b32_e32 v15, 0xffffff00, v15
	v_pk_add_f32 v[34:35], v[20:21], v[40:41] op_sel_hi:[0,1]
	v_or_b32_e32 v39, 0xf2, v15
	v_not_b32_e32 v15, v35
	v_or_b32_e32 v20, 0x80000000, v35
	v_cmp_gt_i32_e32 vcc, 0, v35
	v_or_b32_e32 v35, 0x80000000, v34
	s_nop 0
	v_cndmask_b32_e32 v15, v20, v15, vcc
	v_and_b32_e32 v15, 0xffffff00, v15
	v_or_b32_e32 v20, 0xf1, v15
	v_not_b32_e32 v15, v34
	v_cmp_gt_i32_e32 vcc, 0, v34
	s_nop 1
	v_cndmask_b32_e32 v15, v35, v15, vcc
	v_and_b32_e32 v15, 0xffffff00, v15
	v_pk_add_f32 v[34:35], v[18:19], v[0:1] op_sel_hi:[0,1]
	v_or_b32_e32 v40, 0xf0, v15
	v_not_b32_e32 v15, v35
	v_or_b32_e32 v41, 0x80000000, v35
	v_cmp_gt_i32_e32 vcc, 0, v35
	v_or_b32_e32 v35, 0x80000000, v34
	s_nop 0
	v_cndmask_b32_e32 v15, v41, v15, vcc
	v_and_b32_e32 v15, 0xffffff00, v15
	v_or_b32_e32 v41, 0xef, v15
	v_not_b32_e32 v15, v34
	v_cmp_gt_i32_e32 vcc, 0, v34
	s_nop 1
	v_cndmask_b32_e32 v15, v35, v15, vcc
	v_and_b32_e32 v15, 0xffffff00, v15
	v_pk_add_f32 v[34:35], v[18:19], v[2:3] op_sel_hi:[0,1]
	v_or_b32_e32 v51, 0xee, v15
	v_not_b32_e32 v15, v35
	v_or_b32_e32 v52, 0x80000000, v35
	v_cmp_gt_i32_e32 vcc, 0, v35
	v_or_b32_e32 v35, 0x80000000, v34
	s_nop 0
	v_cndmask_b32_e32 v15, v52, v15, vcc
	v_and_b32_e32 v15, 0xffffff00, v15
	v_or_b32_e32 v52, 0xed, v15
	v_not_b32_e32 v15, v34
	v_cmp_gt_i32_e32 vcc, 0, v34
	s_nop 1
	v_cndmask_b32_e32 v15, v35, v15, vcc
	v_and_b32_e32 v15, 0xffffff00, v15
	v_pk_add_f32 v[34:35], v[18:19], v[16:17] op_sel_hi:[0,1]
	v_or_b32_e32 v53, 0xec, v15
	v_not_b32_e32 v15, v35
	v_or_b32_e32 v16, 0x80000000, v35
	v_cmp_gt_i32_e32 vcc, 0, v35
	s_nop 1
	v_cndmask_b32_e32 v15, v16, v15, vcc
	v_and_b32_e32 v15, 0xffffff00, v15
	v_or_b32_e32 v35, 0xeb, v15
	v_not_b32_e32 v15, v34
	v_or_b32_e32 v16, 0x80000000, v34
	v_cmp_gt_i32_e32 vcc, 0, v34
	s_nop 1
	v_cndmask_b32_e32 v15, v16, v15, vcc
	v_and_b32_e32 v15, 0xffffff00, v15
	v_or_b32_e32 v34, 0xea, v15
	v_not_b32_e32 v15, v23
	v_or_b32_e32 v16, 0x80000000, v23
	v_cmp_gt_i32_e32 vcc, 0, v23
	s_nop 1
	v_cndmask_b32_e32 v15, v16, v15, vcc
	v_and_b32_e32 v15, 0xffffff00, v15
	v_or_b32_e32 v18, 0xe9, v15
	v_not_b32_e32 v15, v22
	v_or_b32_e32 v16, 0x80000000, v22
	v_cmp_gt_i32_e32 vcc, 0, v22
	v_pk_add_f32 v[22:23], v[12:13], v[0:1] op_sel_hi:[0,1]
	s_nop 0
	v_cndmask_b32_e32 v15, v16, v15, vcc
	v_and_b32_e32 v15, 0xffffff00, v15
	v_or_b32_e32 v54, 0xe8, v15
	v_not_b32_e32 v15, v23
	v_or_b32_e32 v16, 0x80000000, v23
	v_cmp_gt_i32_e32 vcc, 0, v23
	s_nop 1
	v_cndmask_b32_e32 v15, v16, v15, vcc
	v_and_b32_e32 v15, 0xffffff00, v15
	v_or_b32_e32 v55, 0xdf, v15
	v_not_b32_e32 v15, v22
	v_or_b32_e32 v16, 0x80000000, v22
	v_cmp_gt_i32_e32 vcc, 0, v22
	v_pk_add_f32 v[22:23], v[12:13], v[2:3] op_sel_hi:[0,1]
	v_lshl_add_u32 v13, v13, 10, s35
	v_cndmask_b32_e32 v15, v16, v15, vcc
	v_and_b32_e32 v15, 0xffffff00, v15
; #define CE_DESC(a, b) do { const unsigned _mx = (a) > (b) ? (a) : (b), _mn = (a) > (b) ? (b) : (a); (a) = _mx; (b) = _mn; } while (0)
; #define CK(i, j) ((f2key(va[i] + vb[j]) & ~255u) | (unsigned)(255 - (16 * (i) + (j))))
; __device__ __forceinline__ void sort16_desc(unsigned (&k)[16]) {
; #pragma unroll
;     for (int size = 2; size <= 16; size <<= 1)
; #pragma unroll
;         for (int stride = size >> 1; stride > 0; stride >>= 1)
; #pragma unroll
;             for (int i = 0; i < 16; ++i) { const int j = i ^ stride;
;                 if (j > i) { if ((i & size) == 0) CE_DESC(k[i], k[j]); else CE_DESC(k[j], k[i]); } }
; }
; __device__ __forceinline__ void peer_tile(const Args& A, LAS unsigned char* lds, int tile) {
;     ...
;             unsigned Lf[16], Bt[16];
; #pragma unroll
;             for (int j = 0; j < 16; ++j) Lf[j] = CK(0, j);
; #pragma unroll
;             for (int j = 0; j < 8; ++j) Bt[j] = CK(1, j);
; #pragma unroll
;             for (int j = 0; j < 5; ++j) Bt[8 + j] = CK(2, j);
; #pragma unroll
;             for (int j = 0; j < 3; ++j) Bt[13 + j] = CK(4, j);
;             sort16_desc(Bt); merge16(Lf, Bt);
	v_or_b32_e32 v56, 0xde, v15
	v_not_b32_e32 v15, v23
	v_or_b32_e32 v16, 0x80000000, v23
	v_cmp_gt_i32_e32 vcc, 0, v23
	s_nop 1
	v_cndmask_b32_e32 v15, v16, v15, vcc
	v_and_b32_e32 v15, 0xffffff00, v15
	v_or_b32_e32 v23, 0xdd, v15
	v_not_b32_e32 v15, v22
	v_or_b32_e32 v16, 0x80000000, v22
	v_cmp_gt_i32_e32 vcc, 0, v22
	s_nop 1
	v_cndmask_b32_e32 v15, v16, v15, vcc
	v_and_b32_e32 v15, 0xffffff00, v15
	v_or_b32_e32 v22, 0xdc, v15
	v_mov_b32_e32 v15, v12
	v_mov_b32_e32 v16, v1
	v_pk_add_f32 v[16:17], v[14:15], v[16:17]
	s_nop 0
	v_not_b32_e32 v12, v17
	v_or_b32_e32 v15, 0x80000000, v17
	v_cmp_gt_i32_e32 vcc, 0, v17
	v_or_b32_e32 v17, 0x80000000, v16
	s_nop 0
	v_cndmask_b32_e32 v12, v15, v12, vcc
	v_not_b32_e32 v15, v16
	v_cmp_gt_i32_e32 vcc, 0, v16
	v_mov_b32_e32 v16, v3
	v_and_b32_e32 v12, 0xffffff00, v12
	v_cndmask_b32_e32 v15, v17, v15, vcc
	v_and_b32_e32 v15, 0xffffff00, v15
	v_mov_b32_e32 v17, v0
	v_or_b32_e32 v57, 0xbf, v15
	v_pk_add_f32 v[14:15], v[14:15], v[16:17] op_sel_hi:[0,1]
	v_not_b32_e32 v16, v15
	v_or_b32_e32 v17, 0x80000000, v15
	v_cmp_gt_i32_e32 vcc, 0, v15
	v_or_b32_e32 v12, 0xdb, v12
	v_pk_add_f32 v[2:3], v[4:5], v[2:3] op_sel_hi:[0,1]
	v_cndmask_b32_e32 v15, v17, v16, vcc
	v_not_b32_e32 v16, v14
	v_or_b32_e32 v17, 0x80000000, v14
	v_cmp_gt_i32_e32 vcc, 0, v14
	v_and_b32_e32 v15, 0xffffff00, v15
	v_or_b32_e32 v15, 0xbe, v15
	v_cndmask_b32_e32 v14, v17, v16, vcc
	v_and_b32_e32 v14, 0xffffff00, v14
	v_or_b32_e32 v14, 0xbd, v14
	v_max_u32_e32 v16, v41, v51
	v_min_u32_e32 v17, v41, v51
	v_max_u32_e32 v41, v53, v52
	v_min_u32_e32 v51, v53, v52
	v_max_u32_e32 v52, v35, v34
	v_min_u32_e32 v34, v35, v34
	v_max_u32_e32 v35, v54, v18
	v_min_u32_e32 v18, v54, v18
	v_max_u32_e32 v53, v55, v56
	v_min_u32_e32 v54, v55, v56
	v_max_u32_e32 v55, v22, v23
	v_min_u32_e32 v22, v22, v23
	v_max_u32_e32 v23, v12, v57
	v_min_u32_e32 v12, v12, v57
	v_max_u32_e32 v56, v14, v15
	v_min_u32_e32 v14, v14, v15
	v_max_u32_e32 v15, v16, v51
	v_min_u32_e32 v16, v16, v51
	v_max_u32_e32 v51, v17, v41
	v_min_u32_e32 v17, v17, v41
	v_max_u32_e32 v41, v18, v52
	v_min_u32_e32 v18, v18, v52
	v_max_u32_e32 v52, v35, v34
	v_min_u32_e32 v34, v35, v34
	v_max_u32_e32 v35, v53, v22
	v_min_u32_e32 v22, v53, v22
	v_max_u32_e32 v53, v54, v55
	v_min_u32_e32 v54, v54, v55
	v_max_u32_e32 v55, v14, v23
	v_min_u32_e32 v14, v14, v23
	v_max_u32_e32 v23, v56, v12
	v_min_u32_e32 v12, v56, v12
	v_max_u32_e32 v56, v15, v51
	v_min_u32_e32 v15, v15, v51
	v_max_u32_e32 v51, v16, v17
	v_min_u32_e32 v16, v16, v17
	v_max_u32_e32 v17, v34, v18
	v_min_u32_e32 v18, v34, v18
	v_max_u32_e32 v34, v52, v41
	v_min_u32_e32 v41, v52, v41
	v_max_u32_e32 v52, v35, v53
	v_min_u32_e32 v35, v35, v53
	v_max_u32_e32 v53, v22, v54
	v_min_u32_e32 v22, v22, v54
	v_max_u32_e32 v54, v12, v14
	v_min_u32_e32 v12, v12, v14
	v_max_u32_e32 v14, v23, v55
	v_min_u32_e32 v23, v23, v55
	v_max_u32_e32 v55, v56, v18
	v_min_u32_e32 v18, v56, v18
	v_max_u32_e32 v56, v15, v17
	v_min_u32_e32 v15, v15, v17
	v_max_u32_e32 v17, v51, v41
	v_min_u32_e32 v41, v51, v41
	v_max_u32_e32 v51, v16, v34
	v_min_u32_e32 v16, v16, v34
	v_max_u32_e32 v34, v12, v52
	v_min_u32_e32 v12, v12, v52
	v_max_u32_e32 v52, v54, v35
	v_min_u32_e32 v35, v54, v35
	v_max_u32_e32 v54, v23, v53
	v_min_u32_e32 v23, v23, v53
	v_max_u32_e32 v53, v14, v22
	v_min_u32_e32 v14, v14, v22
	v_max_u32_e32 v22, v55, v17
	v_min_u32_e32 v17, v55, v17
	v_max_u32_e32 v55, v56, v51
	v_min_u32_e32 v51, v56, v51
	v_max_u32_e32 v56, v18, v41
	v_min_u32_e32 v18, v18, v41
	v_max_u32_e32 v41, v15, v16
	v_min_u32_e32 v15, v15, v16
	v_max_u32_e32 v16, v23, v12
	v_min_u32_e32 v12, v23, v12
	v_max_u32_e32 v23, v14, v35
	v_min_u32_e32 v14, v14, v35
	v_max_u32_e32 v35, v54, v34
	v_min_u32_e32 v34, v54, v34
	v_max_u32_e32 v54, v53, v52
	v_min_u32_e32 v52, v53, v52
	v_max_u32_e32 v53, v22, v55
	v_min_u32_e32 v22, v22, v55
	v_max_u32_e32 v55, v17, v51
	v_min_u32_e32 v17, v17, v51
	v_max_u32_e32 v51, v56, v41
	v_min_u32_e32 v41, v56, v41
	v_max_u32_e32 v56, v18, v15
	v_min_u32_e32 v15, v18, v15
	v_max_u32_e32 v18, v14, v12
	v_min_u32_e32 v12, v14, v12
	v_max_u32_e32 v14, v23, v16
	v_min_u32_e32 v16, v23, v16
	v_max_u32_e32 v23, v52, v34
	v_min_u32_e32 v34, v52, v34
	v_max_u32_e32 v52, v54, v35
	v_min_u32_e32 v35, v54, v35
	v_max_u32_e32 v54, v53, v12
	v_min_u32_e32 v12, v53, v12
	v_max_u32_e32 v53, v22, v18
	v_min_u32_e32 v18, v22, v18
	v_max_u32_e32 v22, v55, v16
	v_min_u32_e32 v16, v55, v16
	v_max_u32_e32 v55, v17, v14
	v_min_u32_e32 v14, v17, v14
	v_max_u32_e32 v17, v51, v34
	v_min_u32_e32 v34, v51, v34
	v_max_u32_e32 v51, v41, v23
	v_min_u32_e32 v23, v41, v23
	v_max_u32_e32 v41, v56, v35
	v_min_u32_e32 v35, v56, v35
	v_max_u32_e32 v56, v15, v52
	v_min_u32_e32 v15, v15, v52
	v_max_u32_e32 v52, v54, v17
	v_min_u32_e32 v17, v54, v17
	v_max_u32_e32 v54, v53, v51
	v_min_u32_e32 v51, v53, v51
	v_max_u32_e32 v53, v22, v41
	v_min_u32_e32 v22, v22, v41
	v_max_u32_e32 v41, v55, v56
	v_min_u32_e32 v55, v55, v56
	v_max_u32_e32 v56, v12, v34
	v_min_u32_e32 v12, v12, v34
	v_max_u32_e32 v34, v18, v23
	v_min_u32_e32 v18, v18, v23
	v_max_u32_e32 v23, v16, v35
	v_min_u32_e32 v16, v16, v35
	v_max_u32_e32 v35, v14, v15
	v_min_u32_e32 v14, v14, v15
	v_max_u32_e32 v15, v52, v53
	v_min_u32_e32 v52, v52, v53
	v_max_u32_e32 v53, v54, v41
	v_min_u32_e32 v41, v54, v41
	v_max_u32_e32 v54, v17, v22
	v_min_u32_e32 v17, v17, v22
	v_max_u32_e32 v22, v51, v55
	v_min_u32_e32 v51, v51, v55
	v_max_u32_e32 v55, v56, v23
	v_min_u32_e32 v23, v56, v23
	v_max_u32_e32 v56, v34, v35
	v_min_u32_e32 v34, v34, v35
	v_max_u32_e32 v35, v12, v16
	v_min_u32_e32 v12, v12, v16
	v_max_u32_e32 v16, v18, v14
	v_min_u32_e32 v14, v18, v14
; #define CK(i, j) ((f2key(va[i] + vb[j]) & ~255u) | (unsigned)(255 - (16 * (i) + (j))))
; __device__ __forceinline__ void peer_tile(const Args& A, LAS unsigned char* lds, int tile) {
;     ...
;             sort16_desc(Bt); merge16(Lf, Bt);
; #pragma unroll
;             for (int j = 0; j < 4; ++j) Bt[j] = CK(3, j);
;             Bt[4] = CK(5, 0); Bt[5] = CK(5, 1); Bt[6] = CK(6, 0); Bt[7] = CK(6, 1); Bt[8] = CK(7, 0); Bt[9] = CK(7, 1);
;             Bt[10] = CK(8, 0); Bt[11] = CK(9, 0); Bt[12] = CK(10, 0); Bt[13] = CK(11, 0); Bt[14] = CK(12, 0); Bt[15] = CK(13, 0);
	v_min_u32_e32 v18, v15, v53
	v_min_u32_e32 v57, v52, v41
	v_min_u32_e32 v58, v54, v22
	v_min_u32_e32 v59, v17, v51
	v_min_u32_e32 v60, v55, v56
	v_min_u32_e32 v61, v23, v34
	v_min_u32_e32 v62, v35, v16
	v_min_u32_e32 v63, v12, v14
	v_max_u32_e32 v33, v33, v63
	v_max3_u32 v12, v44, v12, v14
	v_max_u32_e32 v14, v45, v62
	v_max3_u32 v16, v46, v35, v16
	v_max_u32_e32 v35, v47, v61
	v_max3_u32 v23, v48, v23, v34
	v_max_u32_e32 v34, v43, v60
	v_max3_u32 v42, v42, v55, v56
	v_max_u32_e32 v43, v49, v59
	v_max3_u32 v17, v50, v17, v51
	v_max_u32_e32 v36, v36, v58
	v_max3_u32 v22, v37, v54, v22
	v_max_u32_e32 v37, v38, v57
	v_max3_u32 v38, v39, v52, v41
	v_max_u32_e32 v18, v20, v18
	v_max3_u32 v15, v40, v15, v53
	v_max_u32_e32 v20, v33, v43
	v_min_u32_e32 v33, v33, v43
	v_max_u32_e32 v39, v12, v17
	v_min_u32_e32 v12, v12, v17
	v_max_u32_e32 v17, v14, v36
	v_min_u32_e32 v14, v14, v36
	v_max_u32_e32 v36, v16, v22
	v_min_u32_e32 v16, v16, v22
	v_max_u32_e32 v22, v35, v37
	v_min_u32_e32 v35, v35, v37
	v_max_u32_e32 v37, v23, v38
	v_min_u32_e32 v23, v23, v38
	v_max_u32_e32 v38, v34, v18
	v_min_u32_e32 v18, v34, v18
	v_max_u32_e32 v34, v42, v15
	v_min_u32_e32 v15, v42, v15
	v_max_u32_e32 v40, v20, v22
	v_min_u32_e32 v20, v20, v22
	v_max_u32_e32 v22, v39, v37
	v_min_u32_e32 v37, v39, v37
	v_max_u32_e32 v39, v17, v38
	v_min_u32_e32 v17, v17, v38
	v_max_u32_e32 v38, v36, v34
	v_min_u32_e32 v34, v36, v34
	v_max_u32_e32 v36, v33, v35
	v_min_u32_e32 v33, v33, v35
	v_max_u32_e32 v35, v12, v23
	v_min_u32_e32 v12, v12, v23
	v_max_u32_e32 v23, v14, v18
	v_min_u32_e32 v14, v14, v18
	v_max_u32_e32 v18, v16, v15
	v_min_u32_e32 v15, v16, v15
	v_max_u32_e32 v16, v40, v39
	v_min_u32_e32 v39, v40, v39
	v_max_u32_e32 v40, v22, v38
	v_min_u32_e32 v22, v22, v38
	v_max_u32_e32 v38, v20, v17
	v_min_u32_e32 v17, v20, v17
	v_max_u32_e32 v20, v37, v34
	v_min_u32_e32 v34, v37, v34
	v_max_u32_e32 v37, v36, v23
	v_min_u32_e32 v23, v36, v23
	v_max_u32_e32 v36, v35, v18
	v_min_u32_e32 v18, v35, v18
	v_max_u32_e32 v35, v33, v14
	v_min_u32_e32 v33, v33, v14
	v_max_u32_e32 v41, v12, v15
	v_min_u32_e32 v12, v12, v15
	v_pk_add_f32 v[14:15], v[4:5], v[0:1] op_sel_hi:[0,1]
	v_not_b32_e32 v50, v15
	v_or_b32_e32 v51, 0x80000000, v15
	v_cmp_gt_i32_e32 vcc, 0, v15
	v_not_b32_e32 v4, v3
	v_min_u32_e32 v42, v16, v40
	v_cndmask_b32_e32 v15, v51, v50, vcc
	v_not_b32_e32 v50, v14
	v_or_b32_e32 v51, 0x80000000, v14
	v_cmp_gt_i32_e32 vcc, 0, v14
	v_and_b32_e32 v15, 0xffffff00, v15
	v_or_b32_e32 v15, 0xcf, v15
	v_cndmask_b32_e32 v14, v51, v50, vcc
	v_or_b32_e32 v50, 0x80000000, v3
	v_cmp_gt_i32_e32 vcc, 0, v3
	v_and_b32_e32 v14, 0xffffff00, v14
	v_or_b32_e32 v14, 0xce, v14
	v_cndmask_b32_e32 v3, v50, v4, vcc
	v_and_b32_e32 v3, 0xffffff00, v3
	v_or_b32_e32 v4, 0xcd, v3
	v_not_b32_e32 v3, v2
	v_or_b32_e32 v50, 0x80000000, v2
	v_cmp_gt_i32_e32 vcc, 0, v2
	v_min_u32_e32 v43, v39, v22
	v_min_u32_e32 v44, v38, v20
	v_cndmask_b32_e32 v2, v50, v3, vcc
	v_and_b32_e32 v2, 0xffffff00, v2
	v_or_b32_e32 v50, 0xcc, v2
	v_pk_add_f32 v[2:3], v[10:11], v[0:1] op_sel_hi:[0,1]
	v_not_b32_e32 v10, v3
	v_or_b32_e32 v51, 0x80000000, v3
	v_cmp_gt_i32_e32 vcc, 0, v3
	v_min_u32_e32 v45, v17, v34
	v_min_u32_e32 v46, v37, v36
	v_cndmask_b32_e32 v3, v51, v10, vcc
	v_and_b32_e32 v3, 0xffffff00, v3
	v_or_b32_e32 v10, 0xaf, v3
	v_not_b32_e32 v3, v2
	v_or_b32_e32 v51, 0x80000000, v2
	v_cmp_gt_i32_e32 vcc, 0, v2
	v_min_u32_e32 v47, v23, v18
	v_min_u32_e32 v48, v35, v41
	v_cndmask_b32_e32 v2, v51, v3, vcc
	v_and_b32_e32 v2, 0xffffff00, v2
	v_or_b32_e32 v51, 0xae, v2
	v_pk_add_f32 v[2:3], v[8:9], v[0:1] op_sel_hi:[0,1]
	v_not_b32_e32 v8, v3
	v_or_b32_e32 v52, 0x80000000, v3
	v_cmp_gt_i32_e32 vcc, 0, v3
	v_min_u32_e32 v49, v33, v12
	v_lshlrev_b32_e32 v11, 9, v11
	v_cndmask_b32_e32 v3, v52, v8, vcc
	v_and_b32_e32 v3, 0xffffff00, v3
	v_or_b32_e32 v8, 0x9f, v3
	v_not_b32_e32 v3, v2
	v_or_b32_e32 v52, 0x80000000, v2
	v_cmp_gt_i32_e32 vcc, 0, v2
	s_nop 1
	v_cndmask_b32_e32 v2, v52, v3, vcc
	v_and_b32_e32 v2, 0xffffff00, v2
	v_or_b32_e32 v52, 0x9e, v2
	v_pk_add_f32 v[2:3], v[6:7], v[0:1] op_sel_hi:[0,1]
	v_not_b32_e32 v0, v3
	v_or_b32_e32 v6, 0x80000000, v3
	v_cmp_gt_i32_e32 vcc, 0, v3
	v_not_b32_e32 v3, v2
	s_nop 0
	v_cndmask_b32_e32 v0, v6, v0, vcc
	v_or_b32_e32 v6, 0x80000000, v2
	v_cmp_gt_i32_e32 vcc, 0, v2
	v_and_b32_e32 v0, 0xffffff00, v0
	v_or_b32_e32 v0, 0x8f, v0
	v_cndmask_b32_e32 v2, v6, v3, vcc
	v_add_f32_e32 v3, v27, v1
	v_not_b32_e32 v6, v3
	v_or_b32_e32 v27, 0x80000000, v3
	v_cmp_gt_i32_e32 vcc, 0, v3
	v_and_b32_e32 v2, 0xffffff00, v2
	v_or_b32_e32 v2, 0x8e, v2
	v_cndmask_b32_e32 v3, v27, v6, vcc
	v_add_f32_e32 v6, v28, v1
	v_not_b32_e32 v27, v6
	v_or_b32_e32 v28, 0x80000000, v6
	v_cmp_gt_i32_e32 vcc, 0, v6
	v_and_b32_e32 v3, 0xffffff00, v3
	v_or_b32_e32 v3, 0x7f, v3
	v_cndmask_b32_e32 v6, v28, v27, vcc
	v_add_f32_e32 v27, v29, v1
	v_not_b32_e32 v28, v27
	v_or_b32_e32 v29, 0x80000000, v27
	v_cmp_gt_i32_e32 vcc, 0, v27
	v_and_b32_e32 v6, 0xffffff00, v6
	v_or_b32_e32 v6, 0x6f, v6
	v_cndmask_b32_e32 v27, v29, v28, vcc
	v_add_f32_e32 v28, v30, v1
	v_not_b32_e32 v29, v28
	v_or_b32_e32 v30, 0x80000000, v28
	v_cmp_gt_i32_e32 vcc, 0, v28
	v_and_b32_e32 v27, 0xffffff00, v27
	v_or_b32_e32 v27, 0x5f, v27
	v_cndmask_b32_e32 v28, v30, v29, vcc
	v_add_f32_e32 v29, v31, v1
	v_not_b32_e32 v30, v29
	v_or_b32_e32 v31, 0x80000000, v29
	v_cmp_gt_i32_e32 vcc, 0, v29
	v_and_b32_e32 v28, 0xffffff00, v28
	v_or_b32_e32 v28, 0x4f, v28
	v_cndmask_b32_e32 v29, v31, v30, vcc
	v_add_f32_e32 v30, v32, v1
	v_not_b32_e32 v31, v30
	v_or_b32_e32 v32, 0x80000000, v30
	v_cmp_gt_i32_e32 vcc, 0, v30
	v_and_or_b32 v29, v29, s34, 63
	s_nop 0
	v_cndmask_b32_e32 v30, v32, v31, vcc
; #define CE_DESC(a, b) do { const unsigned _mx = (a) > (b) ? (a) : (b), _mn = (a) > (b) ? (b) : (a); (a) = _mx; (b) = _mn; } while (0)
; __device__ __forceinline__ void sort16_desc(unsigned (&k)[16]) {
; #pragma unroll
;     for (int size = 2; size <= 16; size <<= 1)
; #pragma unroll
;         for (int stride = size >> 1; stride > 0; stride >>= 1)
; #pragma unroll
;             for (int i = 0; i < 16; ++i) { const int j = i ^ stride;
;                 if (j > i) { if ((i & size) == 0) CE_DESC(k[i], k[j]); else CE_DESC(k[j], k[i]); } }
; }
; __device__ __forceinline__ void merge16(unsigned (&a)[16], const unsigned (&b)[16]) {
; #pragma unroll
;     for (int i = 0; i < 16; ++i) a[i] = a[i] > b[15 - i] ? a[i] : b[15 - i];
; #pragma unroll
;     for (int stride = 8; stride > 0; stride >>= 1)
; #pragma unroll
;         for (int i = 0; i < 16; ++i) { const int j = i ^ stride; if (j > i) CE_DESC(a[i], a[j]); }
; }
; __device__ __forceinline__ void peer_tile(const Args& A, LAS unsigned char* lds, int tile) {
;     ...
;             sort16_desc(Bt); merge16(Lf, Bt);
	v_and_or_b32 v30, v30, s34, 47
	v_max_u32_e32 v31, v15, v14
	v_min_u32_e32 v14, v15, v14
	v_max_u32_e32 v15, v50, v4
	v_min_u32_e32 v4, v50, v4
	v_max_u32_e32 v32, v10, v51
	v_min_u32_e32 v10, v10, v51
	v_max_u32_e32 v50, v52, v8
	v_min_u32_e32 v8, v52, v8
	v_max_u32_e32 v51, v0, v2
	v_min_u32_e32 v0, v0, v2
	v_max_u32_e32 v2, v6, v3
	v_min_u32_e32 v3, v6, v3
	v_max_u32_e32 v6, v27, v28
	v_min_u32_e32 v27, v27, v28
	v_max_u32_e32 v28, v30, v29
	v_min_u32_e32 v29, v30, v29
	v_max_u32_e32 v30, v31, v4
	v_min_u32_e32 v4, v31, v4
	v_max_u32_e32 v31, v14, v15
	v_min_u32_e32 v14, v14, v15
	v_max_u32_e32 v15, v8, v32
	v_min_u32_e32 v8, v8, v32
	v_max_u32_e32 v32, v50, v10
	v_min_u32_e32 v10, v50, v10
	v_max_u32_e32 v50, v51, v3
	v_min_u32_e32 v3, v51, v3
	v_max_u32_e32 v51, v0, v2
	v_min_u32_e32 v0, v0, v2
	v_max_u32_e32 v2, v29, v6
	v_min_u32_e32 v6, v29, v6
	v_max_u32_e32 v29, v28, v27
	v_min_u32_e32 v27, v28, v27
	v_max_u32_e32 v28, v30, v31
	v_min_u32_e32 v30, v30, v31
	v_max_u32_e32 v31, v4, v14
	v_min_u32_e32 v4, v4, v14
	v_max_u32_e32 v14, v10, v8
	v_min_u32_e32 v8, v10, v8
	v_max_u32_e32 v10, v32, v15
	v_min_u32_e32 v15, v32, v15
	v_max_u32_e32 v32, v50, v51
	v_min_u32_e32 v50, v50, v51
	v_max_u32_e32 v51, v3, v0
	v_min_u32_e32 v0, v3, v0
	v_max_u32_e32 v3, v27, v6
	v_min_u32_e32 v6, v27, v6
	v_max_u32_e32 v27, v29, v2
	v_min_u32_e32 v2, v29, v2
	v_max_u32_e32 v29, v28, v8
	v_min_u32_e32 v8, v28, v8
	v_max_u32_e32 v28, v30, v14
	v_min_u32_e32 v14, v30, v14
	v_max_u32_e32 v30, v31, v15
	v_min_u32_e32 v15, v31, v15
	v_max_u32_e32 v31, v4, v10
	v_min_u32_e32 v4, v4, v10
	v_max_u32_e32 v10, v6, v32
	v_min_u32_e32 v6, v6, v32
	v_max_u32_e32 v32, v3, v50
	v_min_u32_e32 v3, v3, v50
	v_max_u32_e32 v50, v2, v51
	v_min_u32_e32 v2, v2, v51
	v_max_u32_e32 v51, v27, v0
	v_min_u32_e32 v0, v27, v0
	v_max_u32_e32 v27, v29, v30
	v_min_u32_e32 v29, v29, v30
	v_max_u32_e32 v30, v28, v31
	v_min_u32_e32 v28, v28, v31
	v_max_u32_e32 v31, v8, v15
	v_min_u32_e32 v8, v8, v15
	v_max_u32_e32 v15, v14, v4
	v_min_u32_e32 v4, v14, v4
	v_max_u32_e32 v14, v2, v6
	v_min_u32_e32 v2, v2, v6
	v_max_u32_e32 v6, v0, v3
	v_min_u32_e32 v0, v0, v3
	v_max_u32_e32 v3, v50, v10
	v_min_u32_e32 v10, v50, v10
	v_max_u32_e32 v50, v51, v32
	v_min_u32_e32 v32, v51, v32
	v_max_u32_e32 v51, v27, v30
	v_min_u32_e32 v27, v27, v30
	v_max_u32_e32 v30, v29, v28
	v_min_u32_e32 v28, v29, v28
	v_max_u32_e32 v29, v31, v15
	v_min_u32_e32 v15, v31, v15
	v_max_u32_e32 v31, v8, v4
	v_min_u32_e32 v4, v8, v4
	v_max_u32_e32 v8, v0, v2
	v_min_u32_e32 v0, v0, v2
	v_max_u32_e32 v2, v6, v14
	v_min_u32_e32 v6, v6, v14
	v_max_u32_e32 v14, v32, v10
	v_min_u32_e32 v10, v32, v10
	v_max_u32_e32 v32, v50, v3
	v_min_u32_e32 v3, v50, v3
	v_max_u32_e32 v50, v51, v0
	v_min_u32_e32 v0, v51, v0
	v_max_u32_e32 v51, v27, v8
	v_min_u32_e32 v8, v27, v8
	v_max_u32_e32 v27, v30, v6
	v_min_u32_e32 v6, v30, v6
	v_max_u32_e32 v30, v28, v2
	v_min_u32_e32 v2, v28, v2
	v_max_u32_e32 v28, v29, v10
	v_min_u32_e32 v10, v29, v10
	v_max_u32_e32 v29, v15, v14
	v_min_u32_e32 v14, v15, v14
	v_max_u32_e32 v15, v31, v3
	v_min_u32_e32 v3, v31, v3
	v_max_u32_e32 v31, v4, v32
	v_min_u32_e32 v4, v4, v32
	v_max_u32_e32 v32, v50, v28
	v_min_u32_e32 v28, v50, v28
	v_max_u32_e32 v50, v51, v29
	v_min_u32_e32 v29, v51, v29
	v_max_u32_e32 v51, v27, v15
	v_min_u32_e32 v15, v27, v15
	v_max_u32_e32 v27, v30, v31
	v_min_u32_e32 v30, v30, v31
	v_max_u32_e32 v31, v0, v10
	v_min_u32_e32 v0, v0, v10
	v_max_u32_e32 v10, v8, v14
	v_min_u32_e32 v8, v8, v14
	v_max_u32_e32 v14, v6, v3
	v_min_u32_e32 v3, v6, v3
	v_max_u32_e32 v6, v2, v4
	v_min_u32_e32 v2, v2, v4
	v_max_u32_e32 v4, v32, v51
	v_min_u32_e32 v32, v32, v51
	v_max_u32_e32 v51, v50, v27
	v_min_u32_e32 v27, v50, v27
	v_max_u32_e32 v50, v28, v15
	v_min_u32_e32 v15, v28, v15
	v_max_u32_e32 v28, v29, v30
	v_min_u32_e32 v29, v29, v30
	v_max_u32_e32 v30, v31, v14
	v_min_u32_e32 v14, v31, v14
	v_max_u32_e32 v31, v10, v6
	v_min_u32_e32 v6, v10, v6
	v_max_u32_e32 v10, v0, v3
	v_min_u32_e32 v0, v0, v3
	v_max_u32_e32 v3, v8, v2
	v_min_u32_e32 v2, v8, v2
	v_min_u32_e32 v8, v4, v51
	v_min_u32_e32 v52, v32, v27
	v_min_u32_e32 v53, v50, v28
	v_min_u32_e32 v54, v15, v29
	v_min_u32_e32 v55, v30, v31
	v_min_u32_e32 v56, v14, v6
	v_min_u32_e32 v57, v10, v3
	v_min_u32_e32 v58, v0, v2
	v_max3_u32 v16, v16, v40, v58
	v_max3_u32 v0, v42, v0, v2
	v_max3_u32 v2, v39, v22, v57
	v_max3_u32 v3, v43, v10, v3
	v_max3_u32 v10, v38, v20, v56
	v_max3_u32 v6, v44, v14, v6
	v_max3_u32 v14, v17, v34, v55
	v_max3_u32 v17, v45, v30, v31
	v_max3_u32 v20, v37, v36, v54
	v_max3_u32 v15, v46, v15, v29
	v_max3_u32 v18, v23, v18, v53
	v_max3_u32 v22, v47, v50, v28
	v_max3_u32 v23, v35, v41, v52
	v_max3_u32 v27, v48, v32, v27
	v_max3_u32 v8, v33, v12, v8
	v_max3_u32 v4, v49, v4, v51
	v_max_u32_e32 v12, v16, v20
	v_min_u32_e32 v16, v16, v20
	v_max_u32_e32 v20, v0, v15
	v_min_u32_e32 v0, v0, v15
	v_max_u32_e32 v15, v2, v18
	v_min_u32_e32 v2, v2, v18
	v_max_u32_e32 v18, v3, v22
	v_min_u32_e32 v3, v3, v22
	v_max_u32_e32 v22, v10, v23
	v_min_u32_e32 v10, v10, v23
	v_max_u32_e32 v23, v6, v27
	v_min_u32_e32 v6, v6, v27
	v_max_u32_e32 v27, v14, v8
	v_min_u32_e32 v8, v14, v8
	v_max_u32_e32 v14, v17, v4
	v_min_u32_e32 v4, v17, v4
	v_max_u32_e32 v17, v12, v22
	v_min_u32_e32 v12, v12, v22
	v_max_u32_e32 v22, v20, v23
	v_min_u32_e32 v20, v20, v23
	v_max_u32_e32 v23, v15, v27
	v_min_u32_e32 v15, v15, v27
	v_max_u32_e32 v27, v18, v14
	v_min_u32_e32 v14, v18, v14
	v_max_u32_e32 v18, v16, v10
	v_min_u32_e32 v10, v16, v10
	v_max_u32_e32 v16, v0, v6
	v_min_u32_e32 v0, v0, v6
	v_max_u32_e32 v6, v2, v8
	v_min_u32_e32 v2, v2, v8
	v_max_u32_e32 v8, v3, v4
; __device__ __forceinline__ float key2f(unsigned k) { const unsigned u = (k & 0x80000000u) ? (k & 0x7fffffffu) : ~k; return __uint_as_float(u); }
; #define CE_DESC(a, b) do { const unsigned _mx = (a) > (b) ? (a) : (b), _mn = (a) > (b) ? (b) : (a); (a) = _mx; (b) = _mn; } while (0)
; #define CK(i, j) ((f2key(va[i] + vb[j]) & ~255u) | (unsigned)(255 - (16 * (i) + (j))))
; __device__ __forceinline__ void peer_tile(const Args& A, LAS unsigned char* lds, int tile) {
;     ...
;             { unsigned x0 = CK(14, 0), x1 = CK(15, 0);
; #pragma unroll
;               for (int i = 0; i < 16; ++i) CE_DESC(Lf[i], x0);
; #pragma unroll
;               for (int i = 0; i < 16; ++i) CE_DESC(Lf[i], x1); }
;     ...
;             float fv[16], den = 0.f; const float f0 = key2f(Lf[0] & ~255u);
; #pragma unroll
;             for (int k = 0; k < 16; ++k) { fv[k] = __expf(key2f(Lf[k] & ~255u) - f0); den += fv[k]; }
	v_min_u32_e32 v3, v3, v4
	v_max_u32_e32 v4, v17, v23
	v_min_u32_e32 v17, v17, v23
	v_max_u32_e32 v23, v22, v27
	v_min_u32_e32 v22, v22, v27
	v_max_u32_e32 v27, v12, v15
	v_min_u32_e32 v12, v12, v15
	v_max_u32_e32 v15, v20, v14
	v_min_u32_e32 v14, v20, v14
	v_max_u32_e32 v20, v18, v6
	v_min_u32_e32 v6, v18, v6
	v_max_u32_e32 v18, v16, v8
	v_min_u32_e32 v8, v16, v8
	v_max_u32_e32 v16, v10, v2
	v_min_u32_e32 v2, v10, v2
	v_max_u32_e32 v10, v0, v3
	v_min_u32_e32 v0, v0, v3
	v_max_u32_e32 v41, v2, v0
	v_min_u32_e32 v0, v2, v0
	v_add_f32_e32 v2, v25, v1
	v_not_b32_e32 v25, v2
	v_or_b32_e32 v42, 0x80000000, v2
	v_cmp_gt_i32_e32 vcc, 0, v2
	v_add_f32_e32 v1, v26, v1
	v_max_u32_e32 v3, v4, v23
	v_cndmask_b32_e32 v2, v42, v25, vcc
	v_and_or_b32 v2, v2, s34, 31
	v_not_b32_e32 v25, v1
	v_or_b32_e32 v26, 0x80000000, v1
	v_cmp_gt_i32_e32 vcc, 0, v1
	v_min_u32_e32 v28, v4, v23
	v_max_u32_e32 v29, v17, v22
	v_cndmask_b32_e32 v1, v26, v25, vcc
	v_max_u32_e32 v25, v3, v2
	v_min_u32_e32 v3, v3, v2
	v_min_u32_e32 v3, v28, v3
	v_min_u32_e32 v30, v17, v22
	v_med3_u32 v2, v4, v23, v2
	v_min_u32_e32 v23, v29, v3
	v_max_u32_e32 v31, v27, v15
	v_max_u32_e32 v4, v29, v3
	v_med3_u32 v3, v17, v22, v3
	v_min_u32_e32 v17, v30, v23
	v_min_u32_e32 v32, v27, v15
	v_min_u32_e32 v23, v31, v17
	v_max_u32_e32 v33, v12, v14
	v_max_u32_e32 v22, v31, v17
	v_med3_u32 v15, v27, v15, v17
	v_min_u32_e32 v17, v32, v23
	v_min_u32_e32 v34, v12, v14
	v_min_u32_e32 v26, v33, v17
	v_max_u32_e32 v35, v20, v18
	v_med3_u32 v12, v12, v14, v17
	v_min_u32_e32 v14, v34, v26
	v_min_u32_e32 v36, v20, v18
	v_min_u32_e32 v26, v35, v14
	v_max_u32_e32 v37, v6, v8
	v_max_u32_e32 v23, v33, v17
	v_max_u32_e32 v17, v35, v14
	v_med3_u32 v14, v20, v18, v14
	v_min_u32_e32 v18, v36, v26
	v_min_u32_e32 v38, v6, v8
	v_min_u32_e32 v26, v37, v18
	v_max_u32_e32 v39, v16, v10
	v_med3_u32 v6, v6, v8, v18
	v_min_u32_e32 v8, v38, v26
	v_min_u32_e32 v40, v16, v10
	v_min_u32_e32 v26, v39, v8
	v_and_or_b32 v1, v1, s34, 15
	v_max_u32_e32 v20, v37, v18
	v_max_u32_e32 v18, v39, v8
	v_med3_u32 v8, v16, v10, v8
	v_min_u32_e32 v10, v40, v26
	v_max_u32_e32 v26, v25, v1
	v_min_u32_e32 v1, v25, v1
	v_max_u32_e32 v25, v2, v1
	v_min_u32_e32 v1, v2, v1
	v_max_u32_e32 v2, v4, v1
	v_min_u32_e32 v1, v4, v1
	v_max_u32_e32 v4, v3, v1
	v_min_u32_e32 v1, v3, v1
	v_max_u32_e32 v3, v22, v1
	v_min_u32_e32 v1, v22, v1
	v_max_u32_e32 v22, v15, v1
	v_min_u32_e32 v1, v15, v1
	v_max_u32_e32 v15, v23, v1
	v_min_u32_e32 v1, v23, v1
	v_max_u32_e32 v23, v12, v1
	v_min_u32_e32 v1, v12, v1
	v_max_u32_e32 v12, v17, v1
	v_min_u32_e32 v1, v17, v1
	v_max_u32_e32 v17, v14, v1
	v_min_u32_e32 v1, v14, v1
	v_max_u32_e32 v14, v20, v1
	v_min_u32_e32 v1, v20, v1
	v_max_u32_e32 v20, v6, v1
	v_min_u32_e32 v1, v6, v1
	v_max_u32_e32 v6, v18, v1
	v_min_u32_e32 v1, v18, v1
	v_max_u32_e32 v16, v41, v10
	v_max_u32_e32 v18, v8, v1
	v_min_u32_e32 v1, v8, v1
	v_min_u32_e32 v10, v41, v10
	v_max_u32_e32 v8, v16, v1
	v_min_u32_e32 v1, v16, v1
	v_max3_u32 v10, v0, v10, v1
	v_and_b32_e32 v0, 0x7fffff00, v26
	v_bitop3_b32 v1, v26, s33, v26 bitop3:0xcf
	v_cmp_gt_i32_e32 vcc, 0, v26
	v_and_b32_e32 v16, 0x7fffff00, v25
	v_bitop3_b32 v27, v25, s33, v25 bitop3:0xcf
	v_cndmask_b32_e32 v0, v1, v0, vcc
	v_cmp_gt_i32_e32 vcc, 0, v25
	v_sub_f32_e32 v1, v0, v0
	v_bitop3_b32 v28, v2, s33, v2 bitop3:0xcf
	v_cndmask_b32_e32 v16, v27, v16, vcc
	v_and_b32_e32 v27, 0x7fffff00, v2
	v_cmp_gt_i32_e32 vcc, 0, v2
	v_mul_f32_e32 v1, 0x3fb8aa3b, v1
	v_sub_f32_e32 v16, v16, v0
	v_cndmask_b32_e32 v27, v28, v27, vcc
	v_and_b32_e32 v28, 0x7fffff00, v4
	v_bitop3_b32 v29, v4, s33, v4 bitop3:0xcf
	v_cmp_gt_i32_e32 vcc, 0, v4
	v_exp_f32_e32 v1, v1
	v_mul_f32_e32 v16, 0x3fb8aa3b, v16
	v_sub_f32_e32 v27, v27, v0
	v_cndmask_b32_e32 v28, v29, v28, vcc
	v_and_b32_e32 v30, 0x7fffff00, v3
	v_bitop3_b32 v31, v3, s33, v3 bitop3:0xcf
	v_cmp_gt_i32_e32 vcc, 0, v3
	v_exp_f32_e32 v16, v16
	v_mul_f32_e32 v27, 0x3fb8aa3b, v27
	v_sub_f32_e32 v28, v28, v0
	v_cndmask_b32_e32 v30, v31, v30, vcc
	v_and_b32_e32 v31, 0x7fffff00, v22
	v_bitop3_b32 v32, v22, s33, v22 bitop3:0xcf
	v_cmp_gt_i32_e32 vcc, 0, v22
	v_exp_f32_e32 v27, v27
	v_mul_f32_e32 v28, 0x3fb8aa3b, v28
	v_sub_f32_e32 v30, v30, v0
	v_cndmask_b32_e32 v31, v32, v31, vcc
	v_and_b32_e32 v32, 0x7fffff00, v15
	v_bitop3_b32 v33, v15, s33, v15 bitop3:0xcf
	v_cmp_gt_i32_e32 vcc, 0, v15
	v_exp_f32_e32 v28, v28
	v_mul_f32_e32 v30, 0x3fb8aa3b, v30
	v_sub_f32_e32 v31, v31, v0
	v_cndmask_b32_e32 v32, v33, v32, vcc
	v_and_b32_e32 v33, 0x7fffff00, v23
	v_bitop3_b32 v34, v23, s33, v23 bitop3:0xcf
	v_cmp_gt_i32_e32 vcc, 0, v23
	v_add_f32_e32 v29, 0, v1
	v_exp_f32_e32 v30, v30
	v_mul_f32_e32 v31, 0x3fb8aa3b, v31
	v_sub_f32_e32 v32, v32, v0
	v_cndmask_b32_e32 v33, v34, v33, vcc
	v_and_b32_e32 v34, 0x7fffff00, v12
	v_bitop3_b32 v35, v12, s33, v12 bitop3:0xcf
	v_cmp_gt_i32_e32 vcc, 0, v12
	v_add_f32_e32 v29, v29, v16
	v_exp_f32_e32 v31, v31
	v_mul_f32_e32 v32, 0x3fb8aa3b, v32
	v_sub_f32_e32 v33, v33, v0
	v_cndmask_b32_e32 v34, v35, v34, vcc
	v_and_b32_e32 v35, 0x7fffff00, v17
	v_bitop3_b32 v36, v17, s33, v17 bitop3:0xcf
	v_cmp_gt_i32_e32 vcc, 0, v17
	v_add_f32_e32 v29, v29, v27
	v_exp_f32_e32 v32, v32
	v_mul_f32_e32 v33, 0x3fb8aa3b, v33
	v_sub_f32_e32 v34, v34, v0
	v_cndmask_b32_e32 v35, v36, v35, vcc
	v_and_b32_e32 v36, 0x7fffff00, v14
	v_bitop3_b32 v37, v14, s33, v14 bitop3:0xcf
	v_cmp_gt_i32_e32 vcc, 0, v14
	v_add_f32_e32 v29, v29, v28
	v_exp_f32_e32 v33, v33
	v_mul_f32_e32 v34, 0x3fb8aa3b, v34
	v_sub_f32_e32 v35, v35, v0
	v_cndmask_b32_e32 v36, v37, v36, vcc
	v_and_b32_e32 v37, 0x7fffff00, v20
	v_bitop3_b32 v38, v20, s33, v20 bitop3:0xcf
	v_cmp_gt_i32_e32 vcc, 0, v20
	v_add_f32_e32 v29, v29, v30
; #define LDS_WAIT() asm volatile("s_waitcnt lgkmcnt(0)" ::: "memory")
; __device__ __forceinline__ float key2f(unsigned k) { const unsigned u = (k & 0x80000000u) ? (k & 0x7fffffffu) : ~k; return __uint_as_float(u); }
; __device__ __forceinline__ void peer_tile(const Args& A, LAS unsigned char* lds, int tile) {
;     ...
;             for (int k = 0; k < 16; ++k) { fv[k] = __expf(key2f(Lf[k] & ~255u) - f0); den += fv[k]; }
;             const float rden = 1.f / den;
;             LDS_WAIT();
; #pragma unroll
;             for (int k = 0; k < 16; ++k) { const unsigned code = 255u - (Lf[k] & 255u); const unsigned e = idx[code >> 4] * 128u + idx[16 + (code & 15u)];
;                 u32x2 sv; sv.x = e; sv.y = __float_as_uint(fv[k] * rden); SEL[(tl * 8 + h) * 16 + k] = sv; }
	v_exp_f32_e32 v34, v34
	v_mul_f32_e32 v35, 0x3fb8aa3b, v35
	v_sub_f32_e32 v36, v36, v0
	v_cndmask_b32_e32 v37, v38, v37, vcc
	v_and_b32_e32 v38, 0x7fffff00, v6
	v_bitop3_b32 v39, v6, s33, v6 bitop3:0xcf
	v_cmp_gt_i32_e32 vcc, 0, v6
	v_add_f32_e32 v29, v29, v31
	v_exp_f32_e32 v35, v35
	v_mul_f32_e32 v36, 0x3fb8aa3b, v36
	v_sub_f32_e32 v37, v37, v0
	v_cndmask_b32_e32 v38, v39, v38, vcc
	v_and_b32_e32 v39, 0x7fffff00, v18
	v_bitop3_b32 v40, v18, s33, v18 bitop3:0xcf
	v_cmp_gt_i32_e32 vcc, 0, v18
	v_add_f32_e32 v29, v29, v32
	v_exp_f32_e32 v36, v36
	v_mul_f32_e32 v37, 0x3fb8aa3b, v37
	v_sub_f32_e32 v38, v38, v0
	v_cndmask_b32_e32 v39, v40, v39, vcc
	v_and_b32_e32 v40, 0x7fffff00, v8
	v_bitop3_b32 v41, v8, s33, v8 bitop3:0xcf
	v_cmp_gt_i32_e32 vcc, 0, v8
	v_add_f32_e32 v29, v29, v33
	v_exp_f32_e32 v37, v37
	v_mul_f32_e32 v38, 0x3fb8aa3b, v38
	v_sub_f32_e32 v39, v39, v0
	v_cndmask_b32_e32 v40, v41, v40, vcc
	v_and_b32_e32 v41, 0x7fffff00, v10
	v_bitop3_b32 v42, v10, s33, v10 bitop3:0xcf
	v_cmp_gt_i32_e32 vcc, 0, v10
	v_add_f32_e32 v29, v29, v34
	v_exp_f32_e32 v38, v38
	v_mul_f32_e32 v39, 0x3fb8aa3b, v39
	v_sub_f32_e32 v40, v40, v0
	v_cndmask_b32_e32 v41, v42, v41, vcc
	v_add_f32_e32 v29, v29, v35
	v_exp_f32_e32 v39, v39
	v_mul_f32_e32 v40, 0x3fb8aa3b, v40
	v_sub_f32_e32 v0, v41, v0
	v_add_f32_e32 v29, v29, v36
	v_exp_f32_e32 v40, v40
	v_mul_f32_e32 v0, 0x3fb8aa3b, v0
	v_add_f32_e32 v29, v29, v37
	v_exp_f32_e32 v41, v0
	v_add_f32_e32 v0, v29, v38
	v_add_f32_e32 v0, v0, v39
	v_add_f32_e32 v0, v0, v40
	v_add_f32_e32 v0, v0, v41
	v_div_scale_f32 v29, s[0:1], v0, v0, 1.0
	v_rcp_f32_e32 v42, v29
	v_not_b32_e32 v21, v26
	v_not_b32_e32 v24, v25
	v_fma_f32 v43, -v29, v42, 1.0
	v_fmac_f32_e32 v42, v43, v42
	v_div_scale_f32 v43, vcc, 1.0, v0, 1.0
	v_mul_f32_e32 v44, v43, v42
	v_fma_f32 v45, -v29, v44, v43
	v_fmac_f32_e32 v44, v45, v42
	v_fma_f32 v29, -v29, v44, v43
	v_div_fmas_f32 v29, v29, v42, v44
	v_div_fixup_f32 v29, v29, v0, 1.0
	v_and_b32_e32 v0, 48, v19
	v_lshrrev_b32_e32 v19, 2, v21
	v_and_b32_e32 v19, 60, v19
	v_bitop3_b32 v21, v26, 15, v26 bitop3:0xc
	v_add_u32_e32 v19, v5, v19
	v_lshl_add_u32 v21, v21, 2, v5
	ds_read_b32 v19, v19
	ds_read_b32 v21, v21 offset:64
	v_lshlrev_b32_e32 v0, 3, v0
	v_add3_u32 v11, v13, v11, v0
	v_mul_f32_e32 v1, v1, v29
	v_not_b32_e32 v13, v2
	s_waitcnt lgkmcnt(0)
	v_lshl_add_u32 v0, v19, 7, v21
	ds_write_b64 v11, v[0:1]
	v_lshrrev_b32_e32 v0, 2, v24
	v_and_b32_e32 v0, 60, v0
	v_bitop3_b32 v1, v25, 15, v25 bitop3:0xc
	v_add_u32_e32 v0, v5, v0
	v_lshl_add_u32 v1, v1, 2, v5
	ds_read_b32 v0, v0
	ds_read_b32 v1, v1 offset:64
	v_cmp_eq_u32_e32 vcc, 0, v9
	s_waitcnt lgkmcnt(0)
	v_lshl_add_u32 v0, v0, 7, v1
	v_mul_f32_e32 v1, v16, v29
	ds_write_b64 v11, v[0:1] offset:8
	v_lshrrev_b32_e32 v0, 2, v13
	v_and_b32_e32 v0, 60, v0
	v_bitop3_b32 v1, v2, 15, v2 bitop3:0xc
	v_add_u32_e32 v0, v5, v0
	v_lshl_add_u32 v1, v1, 2, v5
	ds_read_b32 v0, v0
	ds_read_b32 v1, v1 offset:64
	v_not_b32_e32 v2, v4
	s_waitcnt lgkmcnt(0)
	v_lshl_add_u32 v0, v0, 7, v1
	v_mul_f32_e32 v1, v27, v29
	ds_write_b64 v11, v[0:1] offset:16
	v_lshrrev_b32_e32 v0, 2, v2
	v_and_b32_e32 v0, 60, v0
	v_bitop3_b32 v1, v4, 15, v4 bitop3:0xc
	v_add_u32_e32 v0, v5, v0
	v_lshl_add_u32 v1, v1, 2, v5
	ds_read_b32 v0, v0
	ds_read_b32 v1, v1 offset:64
	v_not_b32_e32 v2, v3
	v_mul_lo_u32 v4, v7, s36
	s_waitcnt lgkmcnt(0)
	v_lshl_add_u32 v0, v0, 7, v1
	v_mul_f32_e32 v1, v28, v29
	ds_write_b64 v11, v[0:1] offset:24
	v_lshrrev_b32_e32 v0, 2, v2
	v_and_b32_e32 v0, 60, v0
	v_bitop3_b32 v1, v3, 15, v3 bitop3:0xc
	v_add_u32_e32 v0, v5, v0
	v_lshl_add_u32 v1, v1, 2, v5
	ds_read_b32 v0, v0
	ds_read_b32 v1, v1 offset:64
	v_not_b32_e32 v2, v22
	s_waitcnt lgkmcnt(0)
	v_lshl_add_u32 v0, v0, 7, v1
	v_mul_f32_e32 v1, v30, v29
	ds_write_b64 v11, v[0:1] offset:32
	v_lshrrev_b32_e32 v0, 2, v2
	v_and_b32_e32 v0, 60, v0
	v_bitop3_b32 v1, v22, 15, v22 bitop3:0xc
	v_add_u32_e32 v0, v5, v0
	v_lshl_add_u32 v1, v1, 2, v5
	ds_read_b32 v0, v0
	ds_read_b32 v1, v1 offset:64
	v_not_b32_e32 v2, v15
	s_waitcnt lgkmcnt(0)
	v_lshl_add_u32 v0, v0, 7, v1
	v_mul_f32_e32 v1, v31, v29
	ds_write_b64 v11, v[0:1] offset:40
	v_lshrrev_b32_e32 v0, 2, v2
	v_and_b32_e32 v0, 60, v0
	v_bitop3_b32 v1, v15, 15, v15 bitop3:0xc
	v_add_u32_e32 v0, v5, v0
	v_lshl_add_u32 v1, v1, 2, v5
	ds_read_b32 v0, v0
	ds_read_b32 v1, v1 offset:64
	v_not_b32_e32 v2, v23
	s_waitcnt lgkmcnt(0)
	v_lshl_add_u32 v0, v0, 7, v1
	v_mul_f32_e32 v1, v32, v29
	ds_write_b64 v11, v[0:1] offset:48
	v_lshrrev_b32_e32 v0, 2, v2
	v_and_b32_e32 v0, 60, v0
	v_bitop3_b32 v1, v23, 15, v23 bitop3:0xc
	v_add_u32_e32 v0, v5, v0
	v_lshl_add_u32 v1, v1, 2, v5
	ds_read_b32 v0, v0
	ds_read_b32 v1, v1 offset:64
	v_not_b32_e32 v2, v12
	s_waitcnt lgkmcnt(0)
	v_lshl_add_u32 v0, v0, 7, v1
	v_mul_f32_e32 v1, v33, v29
	ds_write_b64 v11, v[0:1] offset:56
	v_lshrrev_b32_e32 v0, 2, v2
	v_and_b32_e32 v0, 60, v0
	v_bitop3_b32 v1, v12, 15, v12 bitop3:0xc
	v_add_u32_e32 v0, v5, v0
	v_lshl_add_u32 v1, v1, 2, v5
	ds_read_b32 v0, v0
	ds_read_b32 v1, v1 offset:64
	v_not_b32_e32 v2, v17
	s_waitcnt lgkmcnt(0)
	v_lshl_add_u32 v0, v0, 7, v1
	v_mul_f32_e32 v1, v34, v29
	ds_write_b64 v11, v[0:1] offset:64
	v_lshrrev_b32_e32 v0, 2, v2
	v_and_b32_e32 v0, 60, v0
	v_bitop3_b32 v1, v17, 15, v17 bitop3:0xc
	v_add_u32_e32 v0, v5, v0
	v_lshl_add_u32 v1, v1, 2, v5
	ds_read_b32 v0, v0
	ds_read_b32 v1, v1 offset:64
	v_not_b32_e32 v2, v14
	s_waitcnt lgkmcnt(0)
	v_lshl_add_u32 v0, v0, 7, v1
	v_mul_f32_e32 v1, v35, v29
	ds_write_b64 v11, v[0:1] offset:72
	v_lshrrev_b32_e32 v0, 2, v2
	v_and_b32_e32 v0, 60, v0
	v_bitop3_b32 v1, v14, 15, v14 bitop3:0xc
	v_add_u32_e32 v0, v5, v0
	v_lshl_add_u32 v1, v1, 2, v5
	ds_read_b32 v0, v0
	ds_read_b32 v1, v1 offset:64
	v_not_b32_e32 v2, v20
	s_waitcnt lgkmcnt(0)
; __device__ __forceinline__ unsigned pk2(float lo, float hi) { const f32x2 v = {lo, hi}; const bf16x2_t b = __builtin_convertvector(v, bf16x2_t); return __builtin_bit_cast(unsigned, b); }
; __device__ __forceinline__ float bflo(unsigned u) { return __uint_as_float(u << 16); }
; __device__ __forceinline__ float bfhi(unsigned u) { return __uint_as_float(u & 0xffff0000u); }
; __device__ __forceinline__ void peer_tile(const Args& A, LAS unsigned char* lds, int tile) {
;     ...
;             for (int k = 0; k < 16; ++k) { const unsigned code = 255u - (Lf[k] & 255u); const unsigned e = idx[code >> 4] * 128u + idx[16 + (code & 15u)];
;                 u32x2 sv; sv.x = e; sv.y = __float_as_uint(fv[k] * rden); SEL[(tl * 8 + h) * 16 + k] = sv; }
;         }
;     }
;     __syncthreads();
;     ...
;     const unsigned char* T8v = T8 + (size_t)16384 * 1024;
;     const bf16_t* A3 = (const bf16_t*)(A.ws + WS_A3); const float* RSq = (const float*)(A.ws + WS_RS);
;     for (int pass = 0; pass < 2; ++pass) {
;         const int tb = 8 * w + 4 * pass;
;         u32x4 xpa[4], xpb[4]; f32x2 oacc[4][8];
; #pragma unroll
;         for (int tk = 0; tk < 4; ++tk) { const size_t m = (size_t)tile * 64 + tb + tk;
;             { const u32x4 ra = *(const u32x4*)(A3 + m * 1024 + 16 * lane), rb = *(const u32x4*)(A3 + m * 1024 + 16 * lane + 8);
;               float xr_; { const f32x4 p0 = *(const f32x4*)(RSq + m * 16), p1 = *(const f32x4*)(RSq + m * 16 + 4), p2 = *(const f32x4*)(RSq + m * 16 + 8), p3 = *(const f32x4*)(RSq + m * 16 + 12);
;                 const f32x4 ps = (p0 + p1) + (p2 + p3); xr_ = rsqrtf(((ps[0] + ps[1]) + (ps[2] + ps[3])) * (1.f / 1024.f) + 1e-6f); }
;               const unsigned rr[8] = {ra.x, ra.y, ra.z, ra.w, rb.x, rb.y, rb.z, rb.w}; unsigned hh[8];
;               const float* sp = MOD + (int)(m >> 11) * 6144 + 3072 + 16 * lane;
; #pragma unroll
;               for (int q = 0; q < 8; ++q) { const f32x2 sh = *(const f32x2*)(sp + 2 * q); hh[q] = pk2(bflo(rr[q]) * xr_ + sh[0], bfhi(rr[q]) * xr_ + sh[1]); }
;               xpa[tk] = (u32x4){hh[0], hh[1], hh[2], hh[3]}; xpb[tk] = (u32x4){hh[4], hh[5], hh[6], hh[7]}; }
	v_lshl_add_u32 v0, v0, 7, v1
	v_mul_f32_e32 v1, v36, v29
	ds_write_b64 v11, v[0:1] offset:80
	v_lshrrev_b32_e32 v0, 2, v2
	v_and_b32_e32 v0, 60, v0
	v_bitop3_b32 v1, v20, 15, v20 bitop3:0xc
	v_add_u32_e32 v0, v5, v0
	v_lshl_add_u32 v1, v1, 2, v5
	ds_read_b32 v0, v0
	ds_read_b32 v1, v1 offset:64
	v_not_b32_e32 v2, v6
	s_waitcnt lgkmcnt(0)
	v_lshl_add_u32 v0, v0, 7, v1
	v_mul_f32_e32 v1, v37, v29
	ds_write_b64 v11, v[0:1] offset:88
	v_lshrrev_b32_e32 v0, 2, v2
	v_and_b32_e32 v0, 60, v0
	v_bitop3_b32 v1, v6, 15, v6 bitop3:0xc
	v_add_u32_e32 v0, v5, v0
	v_lshl_add_u32 v1, v1, 2, v5
	ds_read_b32 v0, v0
	ds_read_b32 v1, v1 offset:64
	v_not_b32_e32 v2, v18
	s_waitcnt lgkmcnt(0)
	v_lshl_add_u32 v0, v0, 7, v1
	v_mul_f32_e32 v1, v38, v29
	ds_write_b64 v11, v[0:1] offset:96
	v_lshrrev_b32_e32 v0, 2, v2
	v_and_b32_e32 v0, 60, v0
	v_bitop3_b32 v1, v18, 15, v18 bitop3:0xc
	v_add_u32_e32 v0, v5, v0
	v_lshl_add_u32 v1, v1, 2, v5
	ds_read_b32 v0, v0
	ds_read_b32 v1, v1 offset:64
	v_not_b32_e32 v2, v8
	s_waitcnt lgkmcnt(0)
	v_lshl_add_u32 v0, v0, 7, v1
	v_mul_f32_e32 v1, v39, v29
	ds_write_b64 v11, v[0:1] offset:104
	v_lshrrev_b32_e32 v0, 2, v2
	v_and_b32_e32 v0, 60, v0
	v_bitop3_b32 v1, v8, 15, v8 bitop3:0xc
	v_add_u32_e32 v0, v5, v0
	v_lshl_add_u32 v1, v1, 2, v5
	ds_read_b32 v0, v0
	ds_read_b32 v1, v1 offset:64
	v_not_b32_e32 v2, v10
	s_waitcnt lgkmcnt(0)
	v_lshl_add_u32 v0, v0, 7, v1
	v_mul_f32_e32 v1, v40, v29
	ds_write_b64 v11, v[0:1] offset:112
	v_lshrrev_b32_e32 v0, 2, v2
	v_and_b32_e32 v0, 60, v0
	v_bitop3_b32 v1, v10, 15, v10 bitop3:0xc
	v_add_u32_e32 v0, v5, v0
	v_lshl_add_u32 v1, v1, 2, v5
	ds_read_b32 v0, v0
	ds_read_b32 v1, v1 offset:64
	v_lshlrev_b32_e32 v5, 13, v7
	v_lshl_or_b32 v6, v9, 3, v5
	s_waitcnt lgkmcnt(0)
	v_lshl_add_u32 v0, v0, 7, v1
	v_mul_f32_e32 v1, v41, v29
	ds_write_b64 v11, v[0:1] offset:120
	s_waitcnt lgkmcnt(0)
	s_barrier
	s_mov_b64 exec, -1
	v_and_b32_e32 v240, 63, v214
	v_lshrrev_b32_e32 v242, 6, v214
	v_lshlrev_b32_e32 v240, 4, v240
	v_readfirstlane_b32 s16, v242
	v_lshlrev_b32_e32 v245, 1, v240
	v_lshlrev_b32_e32 v246, 2, v240
	v_lshrrev_b32_e32 v247, 4, v240
	v_and_b32_e32 v247, 48, v247
	v_mov_b32_e32 v244, 0
	v_mov_b32_e32 v243, 0x358637bd
	v_mov_b32_e32 v242, 0xbf3a00e3
	s_add_u32 s4, s50, 0x1000000
	s_addc_u32 s5, s51, 0
	s_add_u32 s6, s50, 0x2000000
	s_addc_u32 s7, s51, 0
	s_add_u32 s8, s50, 0x3000000
	s_addc_u32 s9, s51, 0
	s_add_u32 s52, s50, 0x3010000
	s_addc_u32 s53, s51, 0
	s_add_u32 s12, s50, 0xb000000
	s_addc_u32 s13, s51, 0
	s_add_u32 s14, s50, 0xd000000
	s_addc_u32 s15, s51, 0
	s_lshr_b32 s0, s2, 5
	s_mul_i32 s0, s0, 0x6000
	s_add_u32 s10, s50, s0
	s_addc_u32 s11, s51, 0
	s_add_u32 s80, s10, 0x4000
	s_addc_u32 s81, s11, 0
	s_add_u32 s82, s10, 0x6000
	s_addc_u32 s83, s11, 0
	s_mul_i32 s22, s16, 9728
	s_cmp_eq_u32 s16, 7
	s_cselect_b32 s22, 0x21000, s22
	s_mov_b32 s85, 0xfffffc00
	s_mov_b32 s72, 0x3e6d3388
	s_lshl_b32 s76, s16, 3
	s_lshl_b32 s0, s2, 6
	s_add_i32 s77, s0, s76
	global_load_dwordx4 v[192:195], v246, s[80:81] offset:0
	global_load_dwordx4 v[196:199], v246, s[80:81] offset:16
	global_load_dwordx4 v[200:203], v246, s[80:81] offset:32
	global_load_dwordx4 v[204:207], v246, s[80:81] offset:48
	s_add_i32 s0, s77, 0
	s_lshl_b32 s1, s0, 11
	s_add_u32 s78, s12, s1
	s_addc_u32 s79, s13, 0
	global_load_dwordx4 v[128:131], v245, s[78:79]
	global_load_dwordx4 v[132:135], v245, s[78:79] offset:16
	global_load_dwordx4 v[136:139], v245, s[78:79] offset:2048
	global_load_dwordx4 v[140:143], v245, s[78:79] offset:2064
	s_lshl_b32 s1, s0, 6
	s_add_u32 s78, s14, s1
	s_addc_u32 s79, s15, 0
	global_load_dwordx4 v[144:147], v244, s[78:79] offset:0
	global_load_dwordx4 v[148:151], v244, s[78:79] offset:16
	global_load_dwordx4 v[152:155], v244, s[78:79] offset:32
	global_load_dwordx4 v[156:159], v244, s[78:79] offset:48
	global_load_dwordx4 v[160:163], v244, s[78:79] offset:64
	global_load_dwordx4 v[164:167], v244, s[78:79] offset:80
	global_load_dwordx4 v[168:171], v244, s[78:79] offset:96
	global_load_dwordx4 v[172:175], v244, s[78:79] offset:112
	s_waitcnt vmcnt(0)
	v_pk_add_f32 v[144:145], v[144:145], v[148:149]
	v_pk_add_f32 v[146:147], v[146:147], v[150:151]
	v_pk_add_f32 v[152:153], v[152:153], v[156:157]
	v_pk_add_f32 v[154:155], v[154:155], v[158:159]
	v_pk_add_f32 v[144:145], v[144:145], v[152:153]
	v_pk_add_f32 v[146:147], v[146:147], v[154:155]
	v_add_f32_e32 v144, v144, v145
	v_add_f32_e32 v146, v146, v147
	v_add_f32_e32 v144, v144, v146
	v_fmamk_f32 v144, v144, 0x3a800000, v243
	v_rsq_f32_e32 v144, v144
	v_pk_add_f32 v[160:161], v[160:161], v[164:165]
	v_pk_add_f32 v[162:163], v[162:163], v[166:167]
	v_pk_add_f32 v[168:169], v[168:169], v[172:173]
	v_pk_add_f32 v[170:171], v[170:171], v[174:175]
	v_pk_add_f32 v[160:161], v[160:161], v[168:169]
	v_pk_add_f32 v[162:163], v[162:163], v[170:171]
	v_add_f32_e32 v160, v160, v161
	v_add_f32_e32 v162, v162, v163
	v_add_f32_e32 v160, v160, v162
	v_fmamk_f32 v160, v160, 0x3a800000, v243
	v_rsq_f32_e32 v160, v160
	v_lshlrev_b32_e32 v208, 16, v128
	v_and_b32_e32 v209, 0xffff0000, v128
	v_fma_f32 v208, v208, v144, v192
	v_fma_f32 v209, v209, v144, v193
	v_cvt_pk_bf16_f32 v210, v208, v209
	v_lshlrev_b32_e32 v0, 16, v210
	v_and_b32_e32 v1, 0xffff0000, v210
	v_lshlrev_b32_e32 v208, 16, v129
	v_and_b32_e32 v209, 0xffff0000, v129
	v_fma_f32 v208, v208, v144, v194
	v_fma_f32 v209, v209, v144, v195
	v_cvt_pk_bf16_f32 v210, v208, v209
	v_lshlrev_b32_e32 v2, 16, v210
	v_and_b32_e32 v3, 0xffff0000, v210
	v_lshlrev_b32_e32 v208, 16, v130
	v_and_b32_e32 v209, 0xffff0000, v130
	v_fma_f32 v208, v208, v144, v196
	v_fma_f32 v209, v209, v144, v197
	v_cvt_pk_bf16_f32 v210, v208, v209
; __device__ __forceinline__ unsigned pk2(float lo, float hi) { const f32x2 v = {lo, hi}; const bf16x2_t b = __builtin_convertvector(v, bf16x2_t); return __builtin_bit_cast(unsigned, b); }
; __device__ __forceinline__ float bflo(unsigned u) { return __uint_as_float(u << 16); }
; __device__ __forceinline__ float bfhi(unsigned u) { return __uint_as_float(u & 0xffff0000u); }
; __device__ __forceinline__ void peer_tile(const Args& A, LAS unsigned char* lds, int tile) {
;     ...
;         for (int tk = 0; tk < 4; ++tk) { const size_t m = (size_t)tile * 64 + tb + tk;
;             { const u32x4 ra = *(const u32x4*)(A3 + m * 1024 + 16 * lane), rb = *(const u32x4*)(A3 + m * 1024 + 16 * lane + 8);
;               float xr_; { const f32x4 p0 = *(const f32x4*)(RSq + m * 16), p1 = *(const f32x4*)(RSq + m * 16 + 4), p2 = *(const f32x4*)(RSq + m * 16 + 8), p3 = *(const f32x4*)(RSq + m * 16 + 12);
;                 const f32x4 ps = (p0 + p1) + (p2 + p3); xr_ = rsqrtf(((ps[0] + ps[1]) + (ps[2] + ps[3])) * (1.f / 1024.f) + 1e-6f); }
;               const unsigned rr[8] = {ra.x, ra.y, ra.z, ra.w, rb.x, rb.y, rb.z, rb.w}; unsigned hh[8];
;               const float* sp = MOD + (int)(m >> 11) * 6144 + 3072 + 16 * lane;
; #pragma unroll
;               for (int q = 0; q < 8; ++q) { const f32x2 sh = *(const f32x2*)(sp + 2 * q); hh[q] = pk2(bflo(rr[q]) * xr_ + sh[0], bfhi(rr[q]) * xr_ + sh[1]); }
;               xpa[tk] = (u32x4){hh[0], hh[1], hh[2], hh[3]}; xpb[tk] = (u32x4){hh[4], hh[5], hh[6], hh[7]}; }
	v_lshlrev_b32_e32 v4, 16, v210
	v_and_b32_e32 v5, 0xffff0000, v210
	v_lshlrev_b32_e32 v208, 16, v131
	v_and_b32_e32 v209, 0xffff0000, v131
	v_fma_f32 v208, v208, v144, v198
	v_fma_f32 v209, v209, v144, v199
	v_cvt_pk_bf16_f32 v210, v208, v209
	v_lshlrev_b32_e32 v6, 16, v210
	v_and_b32_e32 v7, 0xffff0000, v210
	v_lshlrev_b32_e32 v208, 16, v132
	v_and_b32_e32 v209, 0xffff0000, v132
	v_fma_f32 v208, v208, v144, v200
	v_fma_f32 v209, v209, v144, v201
	v_cvt_pk_bf16_f32 v210, v208, v209
	v_lshlrev_b32_e32 v8, 16, v210
	v_and_b32_e32 v9, 0xffff0000, v210
	v_lshlrev_b32_e32 v208, 16, v133
	v_and_b32_e32 v209, 0xffff0000, v133
	v_fma_f32 v208, v208, v144, v202
	v_fma_f32 v209, v209, v144, v203
	v_cvt_pk_bf16_f32 v210, v208, v209
	v_lshlrev_b32_e32 v10, 16, v210
	v_and_b32_e32 v11, 0xffff0000, v210
	v_lshlrev_b32_e32 v208, 16, v134
	v_and_b32_e32 v209, 0xffff0000, v134
	v_fma_f32 v208, v208, v144, v204
	v_fma_f32 v209, v209, v144, v205
	v_cvt_pk_bf16_f32 v210, v208, v209
	v_lshlrev_b32_e32 v12, 16, v210
	v_and_b32_e32 v13, 0xffff0000, v210
	v_lshlrev_b32_e32 v208, 16, v135
	v_and_b32_e32 v209, 0xffff0000, v135
	v_fma_f32 v208, v208, v144, v206
	v_fma_f32 v209, v209, v144, v207
	v_cvt_pk_bf16_f32 v210, v208, v209
	v_lshlrev_b32_e32 v14, 16, v210
	v_and_b32_e32 v15, 0xffff0000, v210
	v_lshlrev_b32_e32 v208, 16, v136
	v_and_b32_e32 v209, 0xffff0000, v136
	v_fma_f32 v208, v208, v160, v192
	v_fma_f32 v209, v209, v160, v193
	v_cvt_pk_bf16_f32 v210, v208, v209
	v_lshlrev_b32_e32 v16, 16, v210
	v_and_b32_e32 v17, 0xffff0000, v210
	v_lshlrev_b32_e32 v208, 16, v137
	v_and_b32_e32 v209, 0xffff0000, v137
	v_fma_f32 v208, v208, v160, v194
	v_fma_f32 v209, v209, v160, v195
	v_cvt_pk_bf16_f32 v210, v208, v209
	v_lshlrev_b32_e32 v18, 16, v210
	v_and_b32_e32 v19, 0xffff0000, v210
	v_lshlrev_b32_e32 v208, 16, v138
	v_and_b32_e32 v209, 0xffff0000, v138
	v_fma_f32 v208, v208, v160, v196
	v_fma_f32 v209, v209, v160, v197
	v_cvt_pk_bf16_f32 v210, v208, v209
	v_lshlrev_b32_e32 v20, 16, v210
	v_and_b32_e32 v21, 0xffff0000, v210
	v_lshlrev_b32_e32 v208, 16, v139
	v_and_b32_e32 v209, 0xffff0000, v139
	v_fma_f32 v208, v208, v160, v198
	v_fma_f32 v209, v209, v160, v199
	v_cvt_pk_bf16_f32 v210, v208, v209
	v_lshlrev_b32_e32 v22, 16, v210
	v_and_b32_e32 v23, 0xffff0000, v210
	v_lshlrev_b32_e32 v208, 16, v140
	v_and_b32_e32 v209, 0xffff0000, v140
	v_fma_f32 v208, v208, v160, v200
	v_fma_f32 v209, v209, v160, v201
	v_cvt_pk_bf16_f32 v210, v208, v209
	v_lshlrev_b32_e32 v24, 16, v210
	v_and_b32_e32 v25, 0xffff0000, v210
	v_lshlrev_b32_e32 v208, 16, v141
	v_and_b32_e32 v209, 0xffff0000, v141
	v_fma_f32 v208, v208, v160, v202
	v_fma_f32 v209, v209, v160, v203
	v_cvt_pk_bf16_f32 v210, v208, v209
	v_lshlrev_b32_e32 v26, 16, v210
	v_and_b32_e32 v27, 0xffff0000, v210
	v_lshlrev_b32_e32 v208, 16, v142
	v_and_b32_e32 v209, 0xffff0000, v142
	v_fma_f32 v208, v208, v160, v204
	v_fma_f32 v209, v209, v160, v205
	v_cvt_pk_bf16_f32 v210, v208, v209
	v_lshlrev_b32_e32 v28, 16, v210
	v_and_b32_e32 v29, 0xffff0000, v210
	v_lshlrev_b32_e32 v208, 16, v143
	v_and_b32_e32 v209, 0xffff0000, v143
	v_fma_f32 v208, v208, v160, v206
	v_fma_f32 v209, v209, v160, v207
	v_cvt_pk_bf16_f32 v210, v208, v209
	v_lshlrev_b32_e32 v30, 16, v210
	v_and_b32_e32 v31, 0xffff0000, v210
	s_add_i32 s0, s77, 2
	s_lshl_b32 s1, s0, 11
	s_add_u32 s78, s12, s1
	s_addc_u32 s79, s13, 0
	global_load_dwordx4 v[128:131], v245, s[78:79]
	global_load_dwordx4 v[132:135], v245, s[78:79] offset:16
	global_load_dwordx4 v[136:139], v245, s[78:79] offset:2048
	global_load_dwordx4 v[140:143], v245, s[78:79] offset:2064
	s_lshl_b32 s1, s0, 6
	s_add_u32 s78, s14, s1
	s_addc_u32 s79, s15, 0
	global_load_dwordx4 v[144:147], v244, s[78:79] offset:0
	global_load_dwordx4 v[148:151], v244, s[78:79] offset:16
	global_load_dwordx4 v[152:155], v244, s[78:79] offset:32
	global_load_dwordx4 v[156:159], v244, s[78:79] offset:48
	global_load_dwordx4 v[160:163], v244, s[78:79] offset:64
	global_load_dwordx4 v[164:167], v244, s[78:79] offset:80
	global_load_dwordx4 v[168:171], v244, s[78:79] offset:96
	global_load_dwordx4 v[172:175], v244, s[78:79] offset:112
	s_waitcnt vmcnt(0)
	v_pk_add_f32 v[144:145], v[144:145], v[148:149]
	v_pk_add_f32 v[146:147], v[146:147], v[150:151]
	v_pk_add_f32 v[152:153], v[152:153], v[156:157]
	v_pk_add_f32 v[154:155], v[154:155], v[158:159]
	v_pk_add_f32 v[144:145], v[144:145], v[152:153]
	v_pk_add_f32 v[146:147], v[146:147], v[154:155]
	v_add_f32_e32 v144, v144, v145
	v_add_f32_e32 v146, v146, v147
	v_add_f32_e32 v144, v144, v146
	v_fmamk_f32 v144, v144, 0x3a800000, v243
	v_rsq_f32_e32 v144, v144
	v_pk_add_f32 v[160:161], v[160:161], v[164:165]
	v_pk_add_f32 v[162:163], v[162:163], v[166:167]
	v_pk_add_f32 v[168:169], v[168:169], v[172:173]
	v_pk_add_f32 v[170:171], v[170:171], v[174:175]
	v_pk_add_f32 v[160:161], v[160:161], v[168:169]
	v_pk_add_f32 v[162:163], v[162:163], v[170:171]
	v_add_f32_e32 v160, v160, v161
	v_add_f32_e32 v162, v162, v163
	v_add_f32_e32 v160, v160, v162
	v_fmamk_f32 v160, v160, 0x3a800000, v243
	v_rsq_f32_e32 v160, v160
	v_lshlrev_b32_e32 v208, 16, v128
	v_and_b32_e32 v209, 0xffff0000, v128
	v_fma_f32 v208, v208, v144, v192
	v_fma_f32 v209, v209, v144, v193
	v_cvt_pk_bf16_f32 v210, v208, v209
	v_lshlrev_b32_e32 v32, 16, v210
	v_and_b32_e32 v33, 0xffff0000, v210
	v_lshlrev_b32_e32 v208, 16, v129
	v_and_b32_e32 v209, 0xffff0000, v129
	v_fma_f32 v208, v208, v144, v194
	v_fma_f32 v209, v209, v144, v195
	v_cvt_pk_bf16_f32 v210, v208, v209
	v_lshlrev_b32_e32 v34, 16, v210
	v_and_b32_e32 v35, 0xffff0000, v210
	v_lshlrev_b32_e32 v208, 16, v130
	v_and_b32_e32 v209, 0xffff0000, v130
	v_fma_f32 v208, v208, v144, v196
; __device__ __forceinline__ unsigned pk2(float lo, float hi) { const f32x2 v = {lo, hi}; const bf16x2_t b = __builtin_convertvector(v, bf16x2_t); return __builtin_bit_cast(unsigned, b); }
; __device__ __forceinline__ float bflo(unsigned u) { return __uint_as_float(u << 16); }
; __device__ __forceinline__ float bfhi(unsigned u) { return __uint_as_float(u & 0xffff0000u); }
; __device__ __forceinline__ void peer_tile(const Args& A, LAS unsigned char* lds, int tile) {
;     ...
;         for (int tk = 0; tk < 4; ++tk) { const size_t m = (size_t)tile * 64 + tb + tk;
;             { const u32x4 ra = *(const u32x4*)(A3 + m * 1024 + 16 * lane), rb = *(const u32x4*)(A3 + m * 1024 + 16 * lane + 8);
;               float xr_; { const f32x4 p0 = *(const f32x4*)(RSq + m * 16), p1 = *(const f32x4*)(RSq + m * 16 + 4), p2 = *(const f32x4*)(RSq + m * 16 + 8), p3 = *(const f32x4*)(RSq + m * 16 + 12);
;                 const f32x4 ps = (p0 + p1) + (p2 + p3); xr_ = rsqrtf(((ps[0] + ps[1]) + (ps[2] + ps[3])) * (1.f / 1024.f) + 1e-6f); }
;               const unsigned rr[8] = {ra.x, ra.y, ra.z, ra.w, rb.x, rb.y, rb.z, rb.w}; unsigned hh[8];
;               const float* sp = MOD + (int)(m >> 11) * 6144 + 3072 + 16 * lane;
; #pragma unroll
;               for (int q = 0; q < 8; ++q) { const f32x2 sh = *(const f32x2*)(sp + 2 * q); hh[q] = pk2(bflo(rr[q]) * xr_ + sh[0], bfhi(rr[q]) * xr_ + sh[1]); }
;               xpa[tk] = (u32x4){hh[0], hh[1], hh[2], hh[3]}; xpb[tk] = (u32x4){hh[4], hh[5], hh[6], hh[7]}; }
	v_fma_f32 v209, v209, v144, v197
	v_cvt_pk_bf16_f32 v210, v208, v209
	v_lshlrev_b32_e32 v36, 16, v210
	v_and_b32_e32 v37, 0xffff0000, v210
	v_lshlrev_b32_e32 v208, 16, v131
	v_and_b32_e32 v209, 0xffff0000, v131
	v_fma_f32 v208, v208, v144, v198
	v_fma_f32 v209, v209, v144, v199
	v_cvt_pk_bf16_f32 v210, v208, v209
	v_lshlrev_b32_e32 v38, 16, v210
	v_and_b32_e32 v39, 0xffff0000, v210
	v_lshlrev_b32_e32 v208, 16, v132
	v_and_b32_e32 v209, 0xffff0000, v132
	v_fma_f32 v208, v208, v144, v200
	v_fma_f32 v209, v209, v144, v201
	v_cvt_pk_bf16_f32 v210, v208, v209
	v_lshlrev_b32_e32 v40, 16, v210
	v_and_b32_e32 v41, 0xffff0000, v210
	v_lshlrev_b32_e32 v208, 16, v133
	v_and_b32_e32 v209, 0xffff0000, v133
	v_fma_f32 v208, v208, v144, v202
	v_fma_f32 v209, v209, v144, v203
	v_cvt_pk_bf16_f32 v210, v208, v209
	v_lshlrev_b32_e32 v42, 16, v210
	v_and_b32_e32 v43, 0xffff0000, v210
	v_lshlrev_b32_e32 v208, 16, v134
	v_and_b32_e32 v209, 0xffff0000, v134
	v_fma_f32 v208, v208, v144, v204
	v_fma_f32 v209, v209, v144, v205
	v_cvt_pk_bf16_f32 v210, v208, v209
	v_lshlrev_b32_e32 v44, 16, v210
	v_and_b32_e32 v45, 0xffff0000, v210
	v_lshlrev_b32_e32 v208, 16, v135
	v_and_b32_e32 v209, 0xffff0000, v135
	v_fma_f32 v208, v208, v144, v206
	v_fma_f32 v209, v209, v144, v207
	v_cvt_pk_bf16_f32 v210, v208, v209
	v_lshlrev_b32_e32 v46, 16, v210
	v_and_b32_e32 v47, 0xffff0000, v210
	v_lshlrev_b32_e32 v208, 16, v136
	v_and_b32_e32 v209, 0xffff0000, v136
	v_fma_f32 v208, v208, v160, v192
	v_fma_f32 v209, v209, v160, v193
	v_cvt_pk_bf16_f32 v210, v208, v209
	v_lshlrev_b32_e32 v48, 16, v210
	v_and_b32_e32 v49, 0xffff0000, v210
	v_lshlrev_b32_e32 v208, 16, v137
	v_and_b32_e32 v209, 0xffff0000, v137
	v_fma_f32 v208, v208, v160, v194
	v_fma_f32 v209, v209, v160, v195
	v_cvt_pk_bf16_f32 v210, v208, v209
	v_lshlrev_b32_e32 v50, 16, v210
	v_and_b32_e32 v51, 0xffff0000, v210
	v_lshlrev_b32_e32 v208, 16, v138
	v_and_b32_e32 v209, 0xffff0000, v138
	v_fma_f32 v208, v208, v160, v196
	v_fma_f32 v209, v209, v160, v197
	v_cvt_pk_bf16_f32 v210, v208, v209
	v_lshlrev_b32_e32 v52, 16, v210
	v_and_b32_e32 v53, 0xffff0000, v210
	v_lshlrev_b32_e32 v208, 16, v139
	v_and_b32_e32 v209, 0xffff0000, v139
	v_fma_f32 v208, v208, v160, v198
	v_fma_f32 v209, v209, v160, v199
	v_cvt_pk_bf16_f32 v210, v208, v209
	v_lshlrev_b32_e32 v54, 16, v210
	v_and_b32_e32 v55, 0xffff0000, v210
	v_lshlrev_b32_e32 v208, 16, v140
	v_and_b32_e32 v209, 0xffff0000, v140
	v_fma_f32 v208, v208, v160, v200
	v_fma_f32 v209, v209, v160, v201
	v_cvt_pk_bf16_f32 v210, v208, v209
	v_lshlrev_b32_e32 v56, 16, v210
	v_and_b32_e32 v57, 0xffff0000, v210
	v_lshlrev_b32_e32 v208, 16, v141
	v_and_b32_e32 v209, 0xffff0000, v141
	v_fma_f32 v208, v208, v160, v202
	v_fma_f32 v209, v209, v160, v203
	v_cvt_pk_bf16_f32 v210, v208, v209
	v_lshlrev_b32_e32 v58, 16, v210
	v_and_b32_e32 v59, 0xffff0000, v210
	v_lshlrev_b32_e32 v208, 16, v142
	v_and_b32_e32 v209, 0xffff0000, v142
	v_fma_f32 v208, v208, v160, v204
	v_fma_f32 v209, v209, v160, v205
	v_cvt_pk_bf16_f32 v210, v208, v209
	v_lshlrev_b32_e32 v60, 16, v210
	v_and_b32_e32 v61, 0xffff0000, v210
	v_lshlrev_b32_e32 v208, 16, v143
	v_and_b32_e32 v209, 0xffff0000, v143
	v_fma_f32 v208, v208, v160, v206
	v_fma_f32 v209, v209, v160, v207
	v_cvt_pk_bf16_f32 v210, v208, v209
	v_lshlrev_b32_e32 v62, 16, v210
	v_and_b32_e32 v63, 0xffff0000, v210
	s_add_i32 s0, s77, 4
	s_lshl_b32 s1, s0, 11
	s_add_u32 s78, s12, s1
	s_addc_u32 s79, s13, 0
	global_load_dwordx4 v[128:131], v245, s[78:79]
	global_load_dwordx4 v[132:135], v245, s[78:79] offset:16
	global_load_dwordx4 v[136:139], v245, s[78:79] offset:2048
	global_load_dwordx4 v[140:143], v245, s[78:79] offset:2064
	s_lshl_b32 s1, s0, 6
	s_add_u32 s78, s14, s1
	s_addc_u32 s79, s15, 0
	global_load_dwordx4 v[144:147], v244, s[78:79] offset:0
	global_load_dwordx4 v[148:151], v244, s[78:79] offset:16
	global_load_dwordx4 v[152:155], v244, s[78:79] offset:32
	global_load_dwordx4 v[156:159], v244, s[78:79] offset:48
	global_load_dwordx4 v[160:163], v244, s[78:79] offset:64
	global_load_dwordx4 v[164:167], v244, s[78:79] offset:80
	global_load_dwordx4 v[168:171], v244, s[78:79] offset:96
	global_load_dwordx4 v[172:175], v244, s[78:79] offset:112
	s_waitcnt vmcnt(0)
	v_pk_add_f32 v[144:145], v[144:145], v[148:149]
	v_pk_add_f32 v[146:147], v[146:147], v[150:151]
	v_pk_add_f32 v[152:153], v[152:153], v[156:157]
	v_pk_add_f32 v[154:155], v[154:155], v[158:159]
	v_pk_add_f32 v[144:145], v[144:145], v[152:153]
	v_pk_add_f32 v[146:147], v[146:147], v[154:155]
	v_add_f32_e32 v144, v144, v145
	v_add_f32_e32 v146, v146, v147
	v_add_f32_e32 v144, v144, v146
	v_fmamk_f32 v144, v144, 0x3a800000, v243
	v_rsq_f32_e32 v144, v144
	v_pk_add_f32 v[160:161], v[160:161], v[164:165]
	v_pk_add_f32 v[162:163], v[162:163], v[166:167]
	v_pk_add_f32 v[168:169], v[168:169], v[172:173]
	v_pk_add_f32 v[170:171], v[170:171], v[174:175]
	v_pk_add_f32 v[160:161], v[160:161], v[168:169]
	v_pk_add_f32 v[162:163], v[162:163], v[170:171]
	v_add_f32_e32 v160, v160, v161
	v_add_f32_e32 v162, v162, v163
	v_add_f32_e32 v160, v160, v162
	v_fmamk_f32 v160, v160, 0x3a800000, v243
	v_rsq_f32_e32 v160, v160
	v_lshlrev_b32_e32 v208, 16, v128
	v_and_b32_e32 v209, 0xffff0000, v128
	v_fma_f32 v208, v208, v144, v192
	v_fma_f32 v209, v209, v144, v193
	v_cvt_pk_bf16_f32 v210, v208, v209
	v_lshlrev_b32_e32 v64, 16, v210
	v_and_b32_e32 v65, 0xffff0000, v210
	v_lshlrev_b32_e32 v208, 16, v129
	v_and_b32_e32 v209, 0xffff0000, v129
	v_fma_f32 v208, v208, v144, v194
	v_fma_f32 v209, v209, v144, v195
	v_cvt_pk_bf16_f32 v210, v208, v209
	v_lshlrev_b32_e32 v66, 16, v210
	v_and_b32_e32 v67, 0xffff0000, v210
	v_lshlrev_b32_e32 v208, 16, v130
; __device__ __forceinline__ unsigned pk2(float lo, float hi) { const f32x2 v = {lo, hi}; const bf16x2_t b = __builtin_convertvector(v, bf16x2_t); return __builtin_bit_cast(unsigned, b); }
; __device__ __forceinline__ float bflo(unsigned u) { return __uint_as_float(u << 16); }
; __device__ __forceinline__ float bfhi(unsigned u) { return __uint_as_float(u & 0xffff0000u); }
; __device__ __forceinline__ void peer_tile(const Args& A, LAS unsigned char* lds, int tile) {
;     ...
;         for (int tk = 0; tk < 4; ++tk) { const size_t m = (size_t)tile * 64 + tb + tk;
;             { const u32x4 ra = *(const u32x4*)(A3 + m * 1024 + 16 * lane), rb = *(const u32x4*)(A3 + m * 1024 + 16 * lane + 8);
;               float xr_; { const f32x4 p0 = *(const f32x4*)(RSq + m * 16), p1 = *(const f32x4*)(RSq + m * 16 + 4), p2 = *(const f32x4*)(RSq + m * 16 + 8), p3 = *(const f32x4*)(RSq + m * 16 + 12);
;                 const f32x4 ps = (p0 + p1) + (p2 + p3); xr_ = rsqrtf(((ps[0] + ps[1]) + (ps[2] + ps[3])) * (1.f / 1024.f) + 1e-6f); }
;               const unsigned rr[8] = {ra.x, ra.y, ra.z, ra.w, rb.x, rb.y, rb.z, rb.w}; unsigned hh[8];
;               const float* sp = MOD + (int)(m >> 11) * 6144 + 3072 + 16 * lane;
; #pragma unroll
;               for (int q = 0; q < 8; ++q) { const f32x2 sh = *(const f32x2*)(sp + 2 * q); hh[q] = pk2(bflo(rr[q]) * xr_ + sh[0], bfhi(rr[q]) * xr_ + sh[1]); }
;               xpa[tk] = (u32x4){hh[0], hh[1], hh[2], hh[3]}; xpb[tk] = (u32x4){hh[4], hh[5], hh[6], hh[7]}; }
	v_and_b32_e32 v209, 0xffff0000, v130
	v_fma_f32 v208, v208, v144, v196
	v_fma_f32 v209, v209, v144, v197
	v_cvt_pk_bf16_f32 v210, v208, v209
	v_lshlrev_b32_e32 v68, 16, v210
	v_and_b32_e32 v69, 0xffff0000, v210
	v_lshlrev_b32_e32 v208, 16, v131
	v_and_b32_e32 v209, 0xffff0000, v131
	v_fma_f32 v208, v208, v144, v198
	v_fma_f32 v209, v209, v144, v199
	v_cvt_pk_bf16_f32 v210, v208, v209
	v_lshlrev_b32_e32 v70, 16, v210
	v_and_b32_e32 v71, 0xffff0000, v210
	v_lshlrev_b32_e32 v208, 16, v132
	v_and_b32_e32 v209, 0xffff0000, v132
	v_fma_f32 v208, v208, v144, v200
	v_fma_f32 v209, v209, v144, v201
	v_cvt_pk_bf16_f32 v210, v208, v209
	v_lshlrev_b32_e32 v72, 16, v210
	v_and_b32_e32 v73, 0xffff0000, v210
	v_lshlrev_b32_e32 v208, 16, v133
	v_and_b32_e32 v209, 0xffff0000, v133
	v_fma_f32 v208, v208, v144, v202
	v_fma_f32 v209, v209, v144, v203
	v_cvt_pk_bf16_f32 v210, v208, v209
	v_lshlrev_b32_e32 v74, 16, v210
	v_and_b32_e32 v75, 0xffff0000, v210
	v_lshlrev_b32_e32 v208, 16, v134
	v_and_b32_e32 v209, 0xffff0000, v134
	v_fma_f32 v208, v208, v144, v204
	v_fma_f32 v209, v209, v144, v205
	v_cvt_pk_bf16_f32 v210, v208, v209
	v_lshlrev_b32_e32 v76, 16, v210
	v_and_b32_e32 v77, 0xffff0000, v210
	v_lshlrev_b32_e32 v208, 16, v135
	v_and_b32_e32 v209, 0xffff0000, v135
	v_fma_f32 v208, v208, v144, v206
	v_fma_f32 v209, v209, v144, v207
	v_cvt_pk_bf16_f32 v210, v208, v209
	v_lshlrev_b32_e32 v78, 16, v210
	v_and_b32_e32 v79, 0xffff0000, v210
	v_lshlrev_b32_e32 v208, 16, v136
	v_and_b32_e32 v209, 0xffff0000, v136
	v_fma_f32 v208, v208, v160, v192
	v_fma_f32 v209, v209, v160, v193
	v_cvt_pk_bf16_f32 v210, v208, v209
	v_lshlrev_b32_e32 v80, 16, v210
	v_and_b32_e32 v81, 0xffff0000, v210
	v_lshlrev_b32_e32 v208, 16, v137
	v_and_b32_e32 v209, 0xffff0000, v137
	v_fma_f32 v208, v208, v160, v194
	v_fma_f32 v209, v209, v160, v195
	v_cvt_pk_bf16_f32 v210, v208, v209
	v_lshlrev_b32_e32 v82, 16, v210
	v_and_b32_e32 v83, 0xffff0000, v210
	v_lshlrev_b32_e32 v208, 16, v138
	v_and_b32_e32 v209, 0xffff0000, v138
	v_fma_f32 v208, v208, v160, v196
	v_fma_f32 v209, v209, v160, v197
	v_cvt_pk_bf16_f32 v210, v208, v209
	v_lshlrev_b32_e32 v84, 16, v210
	v_and_b32_e32 v85, 0xffff0000, v210
	v_lshlrev_b32_e32 v208, 16, v139
	v_and_b32_e32 v209, 0xffff0000, v139
	v_fma_f32 v208, v208, v160, v198
	v_fma_f32 v209, v209, v160, v199
	v_cvt_pk_bf16_f32 v210, v208, v209
	v_lshlrev_b32_e32 v86, 16, v210
	v_and_b32_e32 v87, 0xffff0000, v210
	v_lshlrev_b32_e32 v208, 16, v140
	v_and_b32_e32 v209, 0xffff0000, v140
	v_fma_f32 v208, v208, v160, v200
	v_fma_f32 v209, v209, v160, v201
	v_cvt_pk_bf16_f32 v210, v208, v209
	v_lshlrev_b32_e32 v88, 16, v210
	v_and_b32_e32 v89, 0xffff0000, v210
	v_lshlrev_b32_e32 v208, 16, v141
	v_and_b32_e32 v209, 0xffff0000, v141
	v_fma_f32 v208, v208, v160, v202
	v_fma_f32 v209, v209, v160, v203
	v_cvt_pk_bf16_f32 v210, v208, v209
	v_lshlrev_b32_e32 v90, 16, v210
	v_and_b32_e32 v91, 0xffff0000, v210
	v_lshlrev_b32_e32 v208, 16, v142
	v_and_b32_e32 v209, 0xffff0000, v142
	v_fma_f32 v208, v208, v160, v204
	v_fma_f32 v209, v209, v160, v205
	v_cvt_pk_bf16_f32 v210, v208, v209
	v_lshlrev_b32_e32 v92, 16, v210
	v_and_b32_e32 v93, 0xffff0000, v210
	v_lshlrev_b32_e32 v208, 16, v143
	v_and_b32_e32 v209, 0xffff0000, v143
	v_fma_f32 v208, v208, v160, v206
	v_fma_f32 v209, v209, v160, v207
	v_cvt_pk_bf16_f32 v210, v208, v209
	v_lshlrev_b32_e32 v94, 16, v210
	v_and_b32_e32 v95, 0xffff0000, v210
	s_add_i32 s0, s77, 6
	s_lshl_b32 s1, s0, 11
	s_add_u32 s78, s12, s1
	s_addc_u32 s79, s13, 0
	global_load_dwordx4 v[128:131], v245, s[78:79]
	global_load_dwordx4 v[132:135], v245, s[78:79] offset:16
	global_load_dwordx4 v[136:139], v245, s[78:79] offset:2048
	global_load_dwordx4 v[140:143], v245, s[78:79] offset:2064
	s_lshl_b32 s1, s0, 6
	s_add_u32 s78, s14, s1
	s_addc_u32 s79, s15, 0
	global_load_dwordx4 v[144:147], v244, s[78:79] offset:0
	global_load_dwordx4 v[148:151], v244, s[78:79] offset:16
	global_load_dwordx4 v[152:155], v244, s[78:79] offset:32
	global_load_dwordx4 v[156:159], v244, s[78:79] offset:48
	global_load_dwordx4 v[160:163], v244, s[78:79] offset:64
	global_load_dwordx4 v[164:167], v244, s[78:79] offset:80
	global_load_dwordx4 v[168:171], v244, s[78:79] offset:96
	global_load_dwordx4 v[172:175], v244, s[78:79] offset:112
	s_waitcnt vmcnt(0)
; __device__ __forceinline__ unsigned pk2(float lo, float hi) { const f32x2 v = {lo, hi}; const bf16x2_t b = __builtin_convertvector(v, bf16x2_t); return __builtin_bit_cast(unsigned, b); }
; __device__ __forceinline__ float bflo(unsigned u) { return __uint_as_float(u << 16); }
; __device__ __forceinline__ float bfhi(unsigned u) { return __uint_as_float(u & 0xffff0000u); }
; __device__ __forceinline__ void peer_tile(const Args& A, LAS unsigned char* lds, int tile) {
;     ...
;     for (int ti = 0; ti < 8; ++ti) {
;         const int tl = 8 * w + ti;
;         const u32x2 e0 = SEL[tl * 128 + lane], e1 = SEL[tl * 128 + 64 + lane];
;     ...
;         for (int tk = 0; tk < 4; ++tk) { const size_t m = (size_t)tile * 64 + tb + tk;
;             { const u32x4 ra = *(const u32x4*)(A3 + m * 1024 + 16 * lane), rb = *(const u32x4*)(A3 + m * 1024 + 16 * lane + 8);
;               float xr_; { const f32x4 p0 = *(const f32x4*)(RSq + m * 16), p1 = *(const f32x4*)(RSq + m * 16 + 4), p2 = *(const f32x4*)(RSq + m * 16 + 8), p3 = *(const f32x4*)(RSq + m * 16 + 12);
;                 const f32x4 ps = (p0 + p1) + (p2 + p3); xr_ = rsqrtf(((ps[0] + ps[1]) + (ps[2] + ps[3])) * (1.f / 1024.f) + 1e-6f); }
;               const unsigned rr[8] = {ra.x, ra.y, ra.z, ra.w, rb.x, rb.y, rb.z, rb.w}; unsigned hh[8];
;               const float* sp = MOD + (int)(m >> 11) * 6144 + 3072 + 16 * lane;
; #pragma unroll
;               for (int q = 0; q < 8; ++q) { const f32x2 sh = *(const f32x2*)(sp + 2 * q); hh[q] = pk2(bflo(rr[q]) * xr_ + sh[0], bfhi(rr[q]) * xr_ + sh[1]); }
;               xpa[tk] = (u32x4){hh[0], hh[1], hh[2], hh[3]}; xpb[tk] = (u32x4){hh[4], hh[5], hh[6], hh[7]}; }
	v_pk_add_f32 v[144:145], v[144:145], v[148:149]
	v_pk_add_f32 v[146:147], v[146:147], v[150:151]
	v_pk_add_f32 v[152:153], v[152:153], v[156:157]
	v_pk_add_f32 v[154:155], v[154:155], v[158:159]
	v_pk_add_f32 v[144:145], v[144:145], v[152:153]
	v_pk_add_f32 v[146:147], v[146:147], v[154:155]
	v_add_f32_e32 v144, v144, v145
	v_add_f32_e32 v146, v146, v147
	v_add_f32_e32 v144, v144, v146
	v_fmamk_f32 v144, v144, 0x3a800000, v243
	v_rsq_f32_e32 v144, v144
	v_pk_add_f32 v[160:161], v[160:161], v[164:165]
	v_pk_add_f32 v[162:163], v[162:163], v[166:167]
	v_pk_add_f32 v[168:169], v[168:169], v[172:173]
	v_pk_add_f32 v[170:171], v[170:171], v[174:175]
	v_pk_add_f32 v[160:161], v[160:161], v[168:169]
	v_pk_add_f32 v[162:163], v[162:163], v[170:171]
	v_add_f32_e32 v160, v160, v161
	v_add_f32_e32 v162, v162, v163
	v_add_f32_e32 v160, v160, v162
	v_fmamk_f32 v160, v160, 0x3a800000, v243
	v_rsq_f32_e32 v160, v160
	v_lshlrev_b32_e32 v208, 16, v128
	v_and_b32_e32 v209, 0xffff0000, v128
	v_fma_f32 v208, v208, v144, v192
	v_fma_f32 v209, v209, v144, v193
	v_cvt_pk_bf16_f32 v210, v208, v209
	v_lshlrev_b32_e32 v96, 16, v210
	v_and_b32_e32 v97, 0xffff0000, v210
	v_lshlrev_b32_e32 v208, 16, v129
	v_and_b32_e32 v209, 0xffff0000, v129
	v_fma_f32 v208, v208, v144, v194
	v_fma_f32 v209, v209, v144, v195
	v_cvt_pk_bf16_f32 v210, v208, v209
	v_lshlrev_b32_e32 v98, 16, v210
	v_and_b32_e32 v99, 0xffff0000, v210
	v_lshlrev_b32_e32 v208, 16, v130
	v_and_b32_e32 v209, 0xffff0000, v130
	v_fma_f32 v208, v208, v144, v196
	v_fma_f32 v209, v209, v144, v197
	v_cvt_pk_bf16_f32 v210, v208, v209
	v_lshlrev_b32_e32 v100, 16, v210
	v_and_b32_e32 v101, 0xffff0000, v210
	v_lshlrev_b32_e32 v208, 16, v131
	v_and_b32_e32 v209, 0xffff0000, v131
	v_fma_f32 v208, v208, v144, v198
	v_fma_f32 v209, v209, v144, v199
	v_cvt_pk_bf16_f32 v210, v208, v209
	v_lshlrev_b32_e32 v102, 16, v210
	v_and_b32_e32 v103, 0xffff0000, v210
	v_lshlrev_b32_e32 v208, 16, v132
	v_and_b32_e32 v209, 0xffff0000, v132
	v_fma_f32 v208, v208, v144, v200
	v_fma_f32 v209, v209, v144, v201
	v_cvt_pk_bf16_f32 v210, v208, v209
	v_lshlrev_b32_e32 v104, 16, v210
	v_and_b32_e32 v105, 0xffff0000, v210
	v_lshlrev_b32_e32 v208, 16, v133
	v_and_b32_e32 v209, 0xffff0000, v133
	v_fma_f32 v208, v208, v144, v202
	v_fma_f32 v209, v209, v144, v203
	v_cvt_pk_bf16_f32 v210, v208, v209
	v_lshlrev_b32_e32 v106, 16, v210
	v_and_b32_e32 v107, 0xffff0000, v210
	v_lshlrev_b32_e32 v208, 16, v134
	v_and_b32_e32 v209, 0xffff0000, v134
	v_fma_f32 v208, v208, v144, v204
	v_fma_f32 v209, v209, v144, v205
	v_cvt_pk_bf16_f32 v210, v208, v209
	v_lshlrev_b32_e32 v108, 16, v210
	v_and_b32_e32 v109, 0xffff0000, v210
	v_lshlrev_b32_e32 v208, 16, v135
	v_and_b32_e32 v209, 0xffff0000, v135
	v_fma_f32 v208, v208, v144, v206
	v_fma_f32 v209, v209, v144, v207
	v_cvt_pk_bf16_f32 v210, v208, v209
	v_lshlrev_b32_e32 v110, 16, v210
	v_and_b32_e32 v111, 0xffff0000, v210
	v_lshlrev_b32_e32 v208, 16, v136
	v_and_b32_e32 v209, 0xffff0000, v136
	v_fma_f32 v208, v208, v160, v192
	v_fma_f32 v209, v209, v160, v193
	v_cvt_pk_bf16_f32 v210, v208, v209
	v_lshlrev_b32_e32 v112, 16, v210
	v_and_b32_e32 v113, 0xffff0000, v210
	v_lshlrev_b32_e32 v208, 16, v137
	v_and_b32_e32 v209, 0xffff0000, v137
	v_fma_f32 v208, v208, v160, v194
	v_fma_f32 v209, v209, v160, v195
	v_cvt_pk_bf16_f32 v210, v208, v209
	v_lshlrev_b32_e32 v114, 16, v210
	v_and_b32_e32 v115, 0xffff0000, v210
	v_lshlrev_b32_e32 v208, 16, v138
	v_and_b32_e32 v209, 0xffff0000, v138
	v_fma_f32 v208, v208, v160, v196
	v_fma_f32 v209, v209, v160, v197
	v_cvt_pk_bf16_f32 v210, v208, v209
	v_lshlrev_b32_e32 v116, 16, v210
	v_and_b32_e32 v117, 0xffff0000, v210
	v_lshlrev_b32_e32 v208, 16, v139
	v_and_b32_e32 v209, 0xffff0000, v139
	v_fma_f32 v208, v208, v160, v198
	v_fma_f32 v209, v209, v160, v199
	v_cvt_pk_bf16_f32 v210, v208, v209
	v_lshlrev_b32_e32 v118, 16, v210
	v_and_b32_e32 v119, 0xffff0000, v210
	v_lshlrev_b32_e32 v208, 16, v140
	v_and_b32_e32 v209, 0xffff0000, v140
	v_fma_f32 v208, v208, v160, v200
	v_fma_f32 v209, v209, v160, v201
	v_cvt_pk_bf16_f32 v210, v208, v209
	v_lshlrev_b32_e32 v120, 16, v210
	v_and_b32_e32 v121, 0xffff0000, v210
	v_lshlrev_b32_e32 v208, 16, v141
	v_and_b32_e32 v209, 0xffff0000, v141
	v_fma_f32 v208, v208, v160, v202
	v_fma_f32 v209, v209, v160, v203
	v_cvt_pk_bf16_f32 v210, v208, v209
	v_lshlrev_b32_e32 v122, 16, v210
	v_and_b32_e32 v123, 0xffff0000, v210
	v_lshlrev_b32_e32 v208, 16, v142
	v_and_b32_e32 v209, 0xffff0000, v142
	v_fma_f32 v208, v208, v160, v204
	v_fma_f32 v209, v209, v160, v205
	v_cvt_pk_bf16_f32 v210, v208, v209
	v_lshlrev_b32_e32 v124, 16, v210
	v_and_b32_e32 v125, 0xffff0000, v210
	v_lshlrev_b32_e32 v208, 16, v143
	v_and_b32_e32 v209, 0xffff0000, v143
	v_fma_f32 v208, v208, v160, v206
	v_fma_f32 v209, v209, v160, v207
	v_cvt_pk_bf16_f32 v210, v208, v209
	v_lshlrev_b32_e32 v126, 16, v210
	v_and_b32_e32 v127, 0xffff0000, v210
	v_mov_b32_e32 v216, 0
	v_mov_b32_e32 v217, 0
	v_mov_b32_e32 v218, 0
	v_mov_b32_e32 v219, 0
	v_add_u32_e32 v220, s22, v240
	ds_write_b128 v220, v[216:219] offset:0
	ds_write_b128 v220, v[216:219] offset:1024
	ds_write_b128 v220, v[216:219] offset:2048
	ds_write_b128 v220, v[216:219] offset:3072
	ds_write_b128 v220, v[216:219] offset:4096
	ds_write_b128 v220, v[216:219] offset:5120
	ds_write_b128 v220, v[216:219] offset:6144
	ds_write_b128 v220, v[216:219] offset:7168
	ds_write_b128 v220, v[216:219] offset:8192
	v_lshrrev_b32_e32 v222, 1, v240
	v_add_u32_e32 v220, s22, v222
	ds_write_b64 v220, v[216:217] offset:9216
	s_lshl_b32 s0, s76, 10
	s_add_i32 s0, s0, 0x11000
	v_add_u32_e32 v221, s0, v222
	ds_read_b64 v[128:129], v221 offset:0
	ds_read_b64 v[130:131], v221 offset:512
	ds_read_b64 v[132:133], v221 offset:1024
	ds_read_b64 v[134:135], v221 offset:1536
	ds_read_b64 v[136:137], v221 offset:2048
	ds_read_b64 v[138:139], v221 offset:2560
	ds_read_b64 v[140:141], v221 offset:3072
	ds_read_b64 v[142:143], v221 offset:3584
	ds_read_b64 v[144:145], v221 offset:4096
	ds_read_b64 v[146:147], v221 offset:4608
	ds_read_b64 v[148:149], v221 offset:5120
	ds_read_b64 v[150:151], v221 offset:5632
	ds_read_b64 v[152:153], v221 offset:6144
	ds_read_b64 v[154:155], v221 offset:6656
	ds_read_b64 v[156:157], v221 offset:7168
	ds_read_b64 v[158:159], v221 offset:7680
	v_mov_b32_e32 v212, 0
	s_waitcnt lgkmcnt(0)
; __device__ __forceinline__ void peer_tile(const Args& A, LAS unsigned char* lds, int tile) {
;     ...
;     for (int ti = 0; ti < 8; ++ti) {
;         const int tl = 8 * w + ti;
;         const u32x2 e0 = SEL[tl * 128 + lane], e1 = SEL[tl * 128 + 64 + lane];
;         const int p0 = (int)(e0.x >> 10), p1 = (int)(e1.x >> 10);
;         int off = 0;
;         for (int p = 0; p < 16; ++p) {
;             const unsigned long long m0 = __ballot(p0 == p), m1 = __ballot(p1 == p);
;             const int c0 = __popcll(m0), c1 = __popcll(m1);
;             const int r0 = __builtin_amdgcn_mbcnt_hi((unsigned)(m0 >> 32), __builtin_amdgcn_mbcnt_lo((unsigned)m0, 0u));
;             const int r1 = __builtin_amdgcn_mbcnt_hi((unsigned)(m1 >> 32), __builtin_amdgcn_mbcnt_lo((unsigned)m1, 0u));
;             if (p0 == p) SORT[tl * 128 + off + r0] = e0;
;             if (p1 == p) SORT[tl * 128 + off + c0 + r1] = e1;
;             if (lane == 0) OFFS[tl * 17 + p] = off;
;             off += c0 + c1;
;         }
;         if (lane == 0) OFFS[tl * 17 + 16] = off;
	v_lshrrev_b32_e32 v160, 12, v128
	v_lshlrev_b32_e32 v128, 10, v128
	v_lshrrev_b32_e32 v161, 12, v130
	v_lshlrev_b32_e32 v130, 10, v130
	v_lshrrev_b32_e32 v162, 12, v132
	v_lshlrev_b32_e32 v132, 10, v132
	v_lshrrev_b32_e32 v163, 12, v134
	v_lshlrev_b32_e32 v134, 10, v134
	v_lshrrev_b32_e32 v164, 12, v136
	v_lshlrev_b32_e32 v136, 10, v136
	v_lshrrev_b32_e32 v165, 12, v138
	v_lshlrev_b32_e32 v138, 10, v138
	v_lshrrev_b32_e32 v166, 12, v140
	v_lshlrev_b32_e32 v140, 10, v140
	v_lshrrev_b32_e32 v167, 12, v142
	v_lshlrev_b32_e32 v142, 10, v142
	v_lshrrev_b32_e32 v168, 12, v144
	v_lshlrev_b32_e32 v144, 10, v144
	v_lshrrev_b32_e32 v169, 12, v146
	v_lshlrev_b32_e32 v146, 10, v146
	v_lshrrev_b32_e32 v170, 12, v148
	v_lshlrev_b32_e32 v148, 10, v148
	v_lshrrev_b32_e32 v171, 12, v150
	v_lshlrev_b32_e32 v150, 10, v150
	v_lshrrev_b32_e32 v172, 12, v152
	v_lshlrev_b32_e32 v152, 10, v152
	v_lshrrev_b32_e32 v173, 12, v154
	v_lshlrev_b32_e32 v154, 10, v154
	v_lshrrev_b32_e32 v174, 12, v156
	v_lshlrev_b32_e32 v156, 10, v156
	v_lshrrev_b32_e32 v175, 12, v158
	v_lshlrev_b32_e32 v158, 10, v158
	s_mov_b32 s74, 0
	s_mov_b32 s75, 0
	s_mov_b32 s37, 0
.Lbuild_c:
	v_cmp_eq_u32_e64 s[68:69], s74, v160
	v_cmp_eq_u32_e64 s[70:71], s74, v161
	s_nop 0
	s_lshl_b32 s3, s75, 4
	s_add_i32 s3, s3, s22
	s_bcnt1_i32_b64 s0, s[68:69]
	s_bcnt1_i32_b64 s1, s[70:71]
	v_mbcnt_lo_u32_b32 v222, s68, 0
	v_mbcnt_hi_u32_b32 v222, s69, v222
	v_mbcnt_lo_u32_b32 v223, s70, 0
	v_mbcnt_hi_u32_b32 v223, s71, v223
	v_add_u32_e32 v223, s0, v223
	v_lshl_add_u32 v222, v222, 2, s3
	v_lshl_add_u32 v223, v223, 2, s3
	s_mov_b64 exec, s[68:69]
	ds_write_b32 v222, v128
	ds_write_b32 v222, v129 offset:4864
	s_mov_b64 exec, s[70:71]
	ds_write_b32 v223, v130
	ds_write_b32 v223, v131 offset:4864
	s_add_i32 s0, s0, s1
	s_add_i32 s0, s0, 3
	s_lshr_b32 s0, s0, 2
	s_lshl_b64 s[38:39], 1, s37
	s_mov_b64 exec, s[38:39]
	v_mov_b32_e32 v212, s0
	s_mov_b64 exec, -1
	s_add_i32 s75, s75, s0
	s_add_i32 s37, s37, 1
	v_cmp_eq_u32_e64 s[68:69], s74, v162
	v_cmp_eq_u32_e64 s[70:71], s74, v163
	s_nop 0
	s_lshl_b32 s3, s75, 4
	s_add_i32 s3, s3, s22
	s_bcnt1_i32_b64 s0, s[68:69]
	s_bcnt1_i32_b64 s1, s[70:71]
	v_mbcnt_lo_u32_b32 v222, s68, 0
	v_mbcnt_hi_u32_b32 v222, s69, v222
	v_mbcnt_lo_u32_b32 v223, s70, 0
	v_mbcnt_hi_u32_b32 v223, s71, v223
	v_add_u32_e32 v223, s0, v223
	v_lshl_add_u32 v222, v222, 2, s3
	v_lshl_add_u32 v223, v223, 2, s3
	s_mov_b64 exec, s[68:69]
	ds_write_b32 v222, v132
	ds_write_b32 v222, v133 offset:4864
	s_mov_b64 exec, s[70:71]
	ds_write_b32 v223, v134
	ds_write_b32 v223, v135 offset:4864
	s_add_i32 s0, s0, s1
	s_add_i32 s0, s0, 3
	s_lshr_b32 s0, s0, 2
	s_lshl_b64 s[38:39], 1, s37
	s_mov_b64 exec, s[38:39]
	v_mov_b32_e32 v212, s0
	s_mov_b64 exec, -1
	s_add_i32 s75, s75, s0
	s_add_i32 s37, s37, 1
	v_cmp_eq_u32_e64 s[68:69], s74, v164
	v_cmp_eq_u32_e64 s[70:71], s74, v165
	s_nop 0
	s_lshl_b32 s3, s75, 4
	s_add_i32 s3, s3, s22
	s_bcnt1_i32_b64 s0, s[68:69]
	s_bcnt1_i32_b64 s1, s[70:71]
	v_mbcnt_lo_u32_b32 v222, s68, 0
	v_mbcnt_hi_u32_b32 v222, s69, v222
	v_mbcnt_lo_u32_b32 v223, s70, 0
	v_mbcnt_hi_u32_b32 v223, s71, v223
	v_add_u32_e32 v223, s0, v223
	v_lshl_add_u32 v222, v222, 2, s3
	v_lshl_add_u32 v223, v223, 2, s3
	s_mov_b64 exec, s[68:69]
	ds_write_b32 v222, v136
	ds_write_b32 v222, v137 offset:4864
	s_mov_b64 exec, s[70:71]
	ds_write_b32 v223, v138
	ds_write_b32 v223, v139 offset:4864
	s_add_i32 s0, s0, s1
	s_add_i32 s0, s0, 3
	s_lshr_b32 s0, s0, 2
	s_lshl_b64 s[38:39], 1, s37
	s_mov_b64 exec, s[38:39]
	v_mov_b32_e32 v212, s0
	s_mov_b64 exec, -1
	s_add_i32 s75, s75, s0
	s_add_i32 s37, s37, 1
	v_cmp_eq_u32_e64 s[68:69], s74, v166
	v_cmp_eq_u32_e64 s[70:71], s74, v167
	s_nop 0
	s_lshl_b32 s3, s75, 4
	s_add_i32 s3, s3, s22
	s_bcnt1_i32_b64 s0, s[68:69]
	s_bcnt1_i32_b64 s1, s[70:71]
	v_mbcnt_lo_u32_b32 v222, s68, 0
	v_mbcnt_hi_u32_b32 v222, s69, v222
	v_mbcnt_lo_u32_b32 v223, s70, 0
	v_mbcnt_hi_u32_b32 v223, s71, v223
	v_add_u32_e32 v223, s0, v223
	v_lshl_add_u32 v222, v222, 2, s3
	v_lshl_add_u32 v223, v223, 2, s3
	s_mov_b64 exec, s[68:69]
	ds_write_b32 v222, v140
	ds_write_b32 v222, v141 offset:4864
	s_mov_b64 exec, s[70:71]
	ds_write_b32 v223, v142
	ds_write_b32 v223, v143 offset:4864
	s_add_i32 s0, s0, s1
	s_add_i32 s0, s0, 3
	s_lshr_b32 s0, s0, 2
	s_lshl_b64 s[38:39], 1, s37
	s_mov_b64 exec, s[38:39]
	v_mov_b32_e32 v212, s0
	s_mov_b64 exec, -1
	s_add_i32 s75, s75, s0
	s_add_i32 s37, s37, 1
	v_cmp_eq_u32_e64 s[68:69], s74, v168
	v_cmp_eq_u32_e64 s[70:71], s74, v169
	s_nop 0
	s_lshl_b32 s3, s75, 4
	s_add_i32 s3, s3, s22
	s_bcnt1_i32_b64 s0, s[68:69]
	s_bcnt1_i32_b64 s1, s[70:71]
	v_mbcnt_lo_u32_b32 v222, s68, 0
	v_mbcnt_hi_u32_b32 v222, s69, v222
	v_mbcnt_lo_u32_b32 v223, s70, 0
	v_mbcnt_hi_u32_b32 v223, s71, v223
	v_add_u32_e32 v223, s0, v223
	v_lshl_add_u32 v222, v222, 2, s3
	v_lshl_add_u32 v223, v223, 2, s3
	s_mov_b64 exec, s[68:69]
	ds_write_b32 v222, v144
	ds_write_b32 v222, v145 offset:4864
	s_mov_b64 exec, s[70:71]
	ds_write_b32 v223, v146
	ds_write_b32 v223, v147 offset:4864
	s_add_i32 s0, s0, s1
	s_add_i32 s0, s0, 3
	s_lshr_b32 s0, s0, 2
	s_lshl_b64 s[38:39], 1, s37
	s_mov_b64 exec, s[38:39]
	v_mov_b32_e32 v212, s0
	s_mov_b64 exec, -1
	s_add_i32 s75, s75, s0
	s_add_i32 s37, s37, 1
	v_cmp_eq_u32_e64 s[68:69], s74, v170
	v_cmp_eq_u32_e64 s[70:71], s74, v171
	s_nop 0
	s_lshl_b32 s3, s75, 4
	s_add_i32 s3, s3, s22
	s_bcnt1_i32_b64 s0, s[68:69]
	s_bcnt1_i32_b64 s1, s[70:71]
	v_mbcnt_lo_u32_b32 v222, s68, 0
	v_mbcnt_hi_u32_b32 v222, s69, v222
	v_mbcnt_lo_u32_b32 v223, s70, 0
	v_mbcnt_hi_u32_b32 v223, s71, v223
	v_add_u32_e32 v223, s0, v223
	v_lshl_add_u32 v222, v222, 2, s3
	v_lshl_add_u32 v223, v223, 2, s3
; #define IT_ADVANCE() do { it_j += 4; while (it_j >= it_end) { if (it_done) break; ++it_tk; if (it_tk == 4) { it_tk = 0; ++it_p; if (it_p == 16) { it_done = true; it_p = 15; it_j = 0; it_end = 1; break; } } \
;             it_j = __builtin_amdgcn_readfirstlane(OFFS[(tb + it_tk) * 17 + it_p]); it_end = __builtin_amdgcn_readfirstlane(OFFS[(tb + it_tk) * 17 + it_p + 1]); } } while (0)
; __device__ __forceinline__ void peer_tile(const Args& A, LAS unsigned char* lds, int tile) {
;     ...
;         for (int p = 0; p < 16; ++p) {
;             const unsigned long long m0 = __ballot(p0 == p), m1 = __ballot(p1 == p);
;             const int c0 = __popcll(m0), c1 = __popcll(m1);
;             const int r0 = __builtin_amdgcn_mbcnt_hi((unsigned)(m0 >> 32), __builtin_amdgcn_mbcnt_lo((unsigned)m0, 0u));
;             const int r1 = __builtin_amdgcn_mbcnt_hi((unsigned)(m1 >> 32), __builtin_amdgcn_mbcnt_lo((unsigned)m1, 0u));
;             if (p0 == p) SORT[tl * 128 + off + r0] = e0;
;             if (p1 == p) SORT[tl * 128 + off + c0 + r1] = e1;
;             if (lane == 0) OFFS[tl * 17 + p] = off;
;             off += c0 + c1;
;         }
;         if (lane == 0) OFFS[tl * 17 + 16] = off;
;     ...
;         int it_p = 0, it_tk = -1, it_j = 0, it_end = 0; bool it_done = false;
;     ...
;         u32x4 uA[4], vA[4], uB[4], vB[4]; float cgA = 0.f, suA = 0.f, svA = 0.f, cgB = 0.f, suB = 0.f, svB = 0.f;
; #pragma unroll
;         for (int k = 0; k < 4; ++k) { uA[k] = (u32x4){0u, 0u, 0u, 0u}; vA[k] = uA[k]; uB[k] = uA[k]; vB[k] = uA[k]; }
;         IT_ADVANCE();
;         LOAD_SET(uA, vA, cgA, suA, svA);
	s_mov_b64 exec, s[68:69]
	ds_write_b32 v222, v148
	ds_write_b32 v222, v149 offset:4864
	s_mov_b64 exec, s[70:71]
	ds_write_b32 v223, v150
	ds_write_b32 v223, v151 offset:4864
	s_add_i32 s0, s0, s1
	s_add_i32 s0, s0, 3
	s_lshr_b32 s0, s0, 2
	s_lshl_b64 s[38:39], 1, s37
	s_mov_b64 exec, s[38:39]
	v_mov_b32_e32 v212, s0
	s_mov_b64 exec, -1
	s_add_i32 s75, s75, s0
	s_add_i32 s37, s37, 1
	v_cmp_eq_u32_e64 s[68:69], s74, v172
	v_cmp_eq_u32_e64 s[70:71], s74, v173
	s_nop 0
	s_lshl_b32 s3, s75, 4
	s_add_i32 s3, s3, s22
	s_bcnt1_i32_b64 s0, s[68:69]
	s_bcnt1_i32_b64 s1, s[70:71]
	v_mbcnt_lo_u32_b32 v222, s68, 0
	v_mbcnt_hi_u32_b32 v222, s69, v222
	v_mbcnt_lo_u32_b32 v223, s70, 0
	v_mbcnt_hi_u32_b32 v223, s71, v223
	v_add_u32_e32 v223, s0, v223
	v_lshl_add_u32 v222, v222, 2, s3
	v_lshl_add_u32 v223, v223, 2, s3
	s_mov_b64 exec, s[68:69]
	ds_write_b32 v222, v152
	ds_write_b32 v222, v153 offset:4864
	s_mov_b64 exec, s[70:71]
	ds_write_b32 v223, v154
	ds_write_b32 v223, v155 offset:4864
	s_add_i32 s0, s0, s1
	s_add_i32 s0, s0, 3
	s_lshr_b32 s0, s0, 2
	s_lshl_b64 s[38:39], 1, s37
	s_mov_b64 exec, s[38:39]
	v_mov_b32_e32 v212, s0
	s_mov_b64 exec, -1
	s_add_i32 s75, s75, s0
	s_add_i32 s37, s37, 1
	v_cmp_eq_u32_e64 s[68:69], s74, v174
	v_cmp_eq_u32_e64 s[70:71], s74, v175
	s_nop 0
	s_lshl_b32 s3, s75, 4
	s_add_i32 s3, s3, s22
	s_bcnt1_i32_b64 s0, s[68:69]
	s_bcnt1_i32_b64 s1, s[70:71]
	v_mbcnt_lo_u32_b32 v222, s68, 0
	v_mbcnt_hi_u32_b32 v222, s69, v222
	v_mbcnt_lo_u32_b32 v223, s70, 0
	v_mbcnt_hi_u32_b32 v223, s71, v223
	v_add_u32_e32 v223, s0, v223
	v_lshl_add_u32 v222, v222, 2, s3
	v_lshl_add_u32 v223, v223, 2, s3
	s_mov_b64 exec, s[68:69]
	ds_write_b32 v222, v156
	ds_write_b32 v222, v157 offset:4864
	s_mov_b64 exec, s[70:71]
	ds_write_b32 v223, v158
	ds_write_b32 v223, v159 offset:4864
	s_add_i32 s0, s0, s1
	s_add_i32 s0, s0, 3
	s_lshr_b32 s0, s0, 2
	s_lshl_b64 s[38:39], 1, s37
	s_mov_b64 exec, s[38:39]
	v_mov_b32_e32 v212, s0
	s_mov_b64 exec, -1
	s_add_i32 s75, s75, s0
	s_add_i32 s37, s37, 1
	s_add_i32 s74, s74, 1
	s_cmp_lt_u32 s74, 4
	s_cbranch_scc1 .Lbuild_c
	s_mov_b32 s91, s75
	s_add_i32 s20, s91, 3
	s_and_b32 s20, s20, -4
	s_waitcnt vmcnt(0) lgkmcnt(0)
	v_mov_b32_e32 v213, s22
	ds_read_b128 v[232:235], v213 offset:0
	s_waitcnt lgkmcnt(0)
	v_add_u32_e32 v236, v232, v240
	v_add_u32_e32 v237, v233, v240
	v_add_u32_e32 v238, v234, v240
	v_add_u32_e32 v239, v235, v240
	global_load_dwordx4 v[128:131], v236, s[4:5]
	global_load_dwordx4 v[132:135], v237, s[4:5]
	global_load_dwordx4 v[136:139], v238, s[4:5]
	global_load_dwordx4 v[140:143], v239, s[4:5]
	ds_read_b128 v[232:235], v213 offset:16
	s_waitcnt lgkmcnt(0)
	v_add_u32_e32 v236, v232, v240
	v_add_u32_e32 v237, v233, v240
	v_add_u32_e32 v238, v234, v240
	v_add_u32_e32 v239, v235, v240
	global_load_dwordx4 v[144:147], v236, s[4:5]
	global_load_dwordx4 v[148:151], v237, s[4:5]
	global_load_dwordx4 v[152:155], v238, s[4:5]
	global_load_dwordx4 v[156:159], v239, s[4:5]
	ds_read_b128 v[232:235], v213 offset:32
	s_waitcnt lgkmcnt(0)
	v_add_u32_e32 v236, v232, v240
	v_add_u32_e32 v237, v233, v240
	v_add_u32_e32 v238, v234, v240
	v_add_u32_e32 v239, v235, v240
	global_load_dwordx4 v[160:163], v236, s[4:5]
	global_load_dwordx4 v[164:167], v237, s[4:5]
	global_load_dwordx4 v[168:171], v238, s[4:5]
	global_load_dwordx4 v[172:175], v239, s[4:5]
	ds_read_b128 v[232:235], v213 offset:48
	s_mov_b32 s21, 0
	s_mov_b32 s89, -1
	v_lshrrev_b32_e32 v208, 6, v240
	v_and_b32_e32 v208, 3, v208
	v_lshrrev_b32_e32 v209, 1, v208
	v_lshlrev_b32_e32 v208, 1, v208
	v_and_b32_e32 v208, 2, v208
	v_or_b32_e32 v208, v208, v209
	v_lshlrev_b32_e32 v208, 2, v208
	v_add3_u32 v211, v208, v247, s22
	ds_read_b32 v248, v211
	ds_read_b32 v249, v211 offset:4864
	s_branch .LU_sw0
.LU_t0_s0:
	s_cmp_ge_u32 s21, s20
	s_cbranch_scc1 .LU_done
	s_waitcnt lgkmcnt(0)
	v_add_u32_e32 v236, v232, v240
	v_add_u32_e32 v237, v233, v240
	v_add_u32_e32 v238, v234, v240
	v_add_u32_e32 v239, v235, v240
	v_lshrrev_b32_e32 v208, 8, v248
	global_load_dword v252, v208, s[8:9]
	global_load_dword v253, v208, s[52:53]
	global_load_dwordx4 v[176:179], v236, s[4:5]
	global_load_dwordx4 v[180:183], v237, s[4:5]
	global_load_dwordx4 v[184:187], v238, s[4:5]
	global_load_dwordx4 v[188:191], v239, s[4:5]
	ds_read_b128 v[232:235], v213 offset:64
	s_waitcnt vmcnt(14)
; #define IT_ADVANCE() do { it_j += 4; while (it_j >= it_end) { if (it_done) break; ++it_tk; if (it_tk == 4) { it_tk = 0; ++it_p; if (it_p == 16) { it_done = true; it_p = 15; it_j = 0; it_end = 1; break; } } \
;             it_j = __builtin_amdgcn_readfirstlane(OFFS[(tb + it_tk) * 17 + it_p]); it_end = __builtin_amdgcn_readfirstlane(OFFS[(tb + it_tk) * 17 + it_p + 1]); } } while (0)
; __device__ __forceinline__ void peer_tile(const Args& A, LAS unsigned char* lds, int tile) {
;     ...
;                 for (int j0 = beg; j0 < end; j0 += 8) {
;                     IT_ADVANCE();
;                     LOAD_SET(uB, vB, cgB, suB, svB);
;                     COMPUTE_SET(uA, vA, cgA, suA, svA);
;                     if (j0 + 4 < end) {
;                         IT_ADVANCE();
;                         LOAD_SET(uA, vA, cgA, suA, svA);
;                         COMPUTE_SET(uB, vB, cgB, suB, svB);
	v_cvt_pk_f32_fp8_e32 v[224:225], v128
	v_cvt_pk_f32_fp8_e32 v[226:227], v132
	v_cvt_pk_f32_fp8_e32 v[228:229], v136
	v_cvt_pk_f32_fp8_e32 v[230:231], v140
	v_pk_mul_f32 v[216:217], v[224:225], v[0:1]
	v_pk_mul_f32 v[218:219], v[226:227], v[0:1]
	v_pk_mul_f32 v[220:221], v[228:229], v[0:1]
	v_pk_mul_f32 v[222:223], v[230:231], v[0:1]
	v_cvt_pk_f32_fp8_sdwa v[224:225], v128 src0_sel:WORD_1
	v_cvt_pk_f32_fp8_sdwa v[226:227], v132 src0_sel:WORD_1
	v_cvt_pk_f32_fp8_sdwa v[228:229], v136 src0_sel:WORD_1
	v_cvt_pk_f32_fp8_sdwa v[230:231], v140 src0_sel:WORD_1
	v_pk_fma_f32 v[216:217], v[224:225], v[2:3], v[216:217]
	v_pk_fma_f32 v[218:219], v[226:227], v[2:3], v[218:219]
	v_pk_fma_f32 v[220:221], v[228:229], v[2:3], v[220:221]
	v_pk_fma_f32 v[222:223], v[230:231], v[2:3], v[222:223]
	v_cvt_pk_f32_fp8_e32 v[224:225], v129
	v_cvt_pk_f32_fp8_e32 v[226:227], v133
	v_cvt_pk_f32_fp8_e32 v[228:229], v137
	v_cvt_pk_f32_fp8_e32 v[230:231], v141
	v_pk_fma_f32 v[216:217], v[224:225], v[4:5], v[216:217]
	v_pk_fma_f32 v[218:219], v[226:227], v[4:5], v[218:219]
	v_pk_fma_f32 v[220:221], v[228:229], v[4:5], v[220:221]
	v_pk_fma_f32 v[222:223], v[230:231], v[4:5], v[222:223]
	v_cvt_pk_f32_fp8_sdwa v[224:225], v129 src0_sel:WORD_1
	v_cvt_pk_f32_fp8_sdwa v[226:227], v133 src0_sel:WORD_1
	v_cvt_pk_f32_fp8_sdwa v[228:229], v137 src0_sel:WORD_1
	v_cvt_pk_f32_fp8_sdwa v[230:231], v141 src0_sel:WORD_1
	v_pk_fma_f32 v[216:217], v[224:225], v[6:7], v[216:217]
	v_pk_fma_f32 v[218:219], v[226:227], v[6:7], v[218:219]
	v_pk_fma_f32 v[220:221], v[228:229], v[6:7], v[220:221]
	v_pk_fma_f32 v[222:223], v[230:231], v[6:7], v[222:223]
	v_cvt_pk_f32_fp8_e32 v[224:225], v130
	v_cvt_pk_f32_fp8_e32 v[226:227], v134
	v_cvt_pk_f32_fp8_e32 v[228:229], v138
	v_cvt_pk_f32_fp8_e32 v[230:231], v142
	v_pk_fma_f32 v[216:217], v[224:225], v[8:9], v[216:217]
	v_pk_fma_f32 v[218:219], v[226:227], v[8:9], v[218:219]
	v_pk_fma_f32 v[220:221], v[228:229], v[8:9], v[220:221]
	v_pk_fma_f32 v[222:223], v[230:231], v[8:9], v[222:223]
	v_cvt_pk_f32_fp8_sdwa v[224:225], v130 src0_sel:WORD_1
	v_cvt_pk_f32_fp8_sdwa v[226:227], v134 src0_sel:WORD_1
	v_cvt_pk_f32_fp8_sdwa v[228:229], v138 src0_sel:WORD_1
	v_cvt_pk_f32_fp8_sdwa v[230:231], v142 src0_sel:WORD_1
	v_pk_fma_f32 v[216:217], v[224:225], v[10:11], v[216:217]
	v_pk_fma_f32 v[218:219], v[226:227], v[10:11], v[218:219]
	v_pk_fma_f32 v[220:221], v[228:229], v[10:11], v[220:221]
	v_pk_fma_f32 v[222:223], v[230:231], v[10:11], v[222:223]
	v_cvt_pk_f32_fp8_e32 v[224:225], v131
	v_cvt_pk_f32_fp8_e32 v[226:227], v135
	v_cvt_pk_f32_fp8_e32 v[228:229], v139
	v_cvt_pk_f32_fp8_e32 v[230:231], v143
	v_pk_fma_f32 v[216:217], v[224:225], v[12:13], v[216:217]
	v_pk_fma_f32 v[218:219], v[226:227], v[12:13], v[218:219]
	v_pk_fma_f32 v[220:221], v[228:229], v[12:13], v[220:221]
	v_pk_fma_f32 v[222:223], v[230:231], v[12:13], v[222:223]
	v_cvt_pk_f32_fp8_sdwa v[224:225], v131 src0_sel:WORD_1
	v_cvt_pk_f32_fp8_sdwa v[226:227], v135 src0_sel:WORD_1
	v_cvt_pk_f32_fp8_sdwa v[228:229], v139 src0_sel:WORD_1
	v_cvt_pk_f32_fp8_sdwa v[230:231], v143 src0_sel:WORD_1
	v_pk_fma_f32 v[216:217], v[224:225], v[14:15], v[216:217]
	v_pk_fma_f32 v[218:219], v[226:227], v[14:15], v[218:219]
	v_pk_fma_f32 v[220:221], v[228:229], v[14:15], v[220:221]
	v_pk_fma_f32 v[222:223], v[230:231], v[14:15], v[222:223]
	v_add_f32_e32 v192, v216, v217
	v_add_f32_e32 v193, v218, v219
	v_add_f32_e32 v194, v220, v221
	v_add_f32_e32 v195, v222, v223
	s_sub_i32 s90, s90, 1
	s_cmp_eq_u32 s90, 0
	s_cbranch_scc1 .LU_sw1
.LU_t0_s1:
	s_waitcnt lgkmcnt(0)
	v_add_u32_e32 v236, v232, v240
	v_add_u32_e32 v237, v233, v240
	v_add_u32_e32 v238, v234, v240
	v_add_u32_e32 v239, v235, v240
	global_load_dwordx4 v[128:131], v236, s[4:5]
	global_load_dwordx4 v[132:135], v237, s[4:5]
	global_load_dwordx4 v[136:139], v238, s[4:5]
	global_load_dwordx4 v[140:143], v239, s[4:5]
	ds_read_b128 v[232:235], v213 offset:80
	s_waitcnt vmcnt(14)
	v_cvt_pk_f32_fp8_e32 v[224:225], v144
	v_cvt_pk_f32_fp8_e32 v[226:227], v148
	v_cvt_pk_f32_fp8_e32 v[228:229], v152
	v_cvt_pk_f32_fp8_e32 v[230:231], v156
	v_pk_mul_f32 v[216:217], v[224:225], v[0:1]
	v_pk_mul_f32 v[218:219], v[226:227], v[0:1]
	v_pk_mul_f32 v[220:221], v[228:229], v[0:1]
	v_pk_mul_f32 v[222:223], v[230:231], v[0:1]
	v_cvt_pk_f32_fp8_sdwa v[224:225], v144 src0_sel:WORD_1
	v_cvt_pk_f32_fp8_sdwa v[226:227], v148 src0_sel:WORD_1
	v_cvt_pk_f32_fp8_sdwa v[228:229], v152 src0_sel:WORD_1
	v_cvt_pk_f32_fp8_sdwa v[230:231], v156 src0_sel:WORD_1
	v_pk_fma_f32 v[216:217], v[224:225], v[2:3], v[216:217]
	v_pk_fma_f32 v[218:219], v[226:227], v[2:3], v[218:219]
	v_pk_fma_f32 v[220:221], v[228:229], v[2:3], v[220:221]
	v_pk_fma_f32 v[222:223], v[230:231], v[2:3], v[222:223]
	v_cvt_pk_f32_fp8_e32 v[224:225], v145
	v_cvt_pk_f32_fp8_e32 v[226:227], v149
	v_cvt_pk_f32_fp8_e32 v[228:229], v153
	v_cvt_pk_f32_fp8_e32 v[230:231], v157
	v_pk_fma_f32 v[216:217], v[224:225], v[4:5], v[216:217]
	v_pk_fma_f32 v[218:219], v[226:227], v[4:5], v[218:219]
	v_pk_fma_f32 v[220:221], v[228:229], v[4:5], v[220:221]
	v_pk_fma_f32 v[222:223], v[230:231], v[4:5], v[222:223]
	v_cvt_pk_f32_fp8_sdwa v[224:225], v145 src0_sel:WORD_1
	v_cvt_pk_f32_fp8_sdwa v[226:227], v149 src0_sel:WORD_1
	v_cvt_pk_f32_fp8_sdwa v[228:229], v153 src0_sel:WORD_1
	v_cvt_pk_f32_fp8_sdwa v[230:231], v157 src0_sel:WORD_1
	v_pk_fma_f32 v[216:217], v[224:225], v[6:7], v[216:217]
	v_pk_fma_f32 v[218:219], v[226:227], v[6:7], v[218:219]
	v_pk_fma_f32 v[220:221], v[228:229], v[6:7], v[220:221]
	v_pk_fma_f32 v[222:223], v[230:231], v[6:7], v[222:223]
	v_cvt_pk_f32_fp8_e32 v[224:225], v146
	v_cvt_pk_f32_fp8_e32 v[226:227], v150
	v_cvt_pk_f32_fp8_e32 v[228:229], v154
	v_cvt_pk_f32_fp8_e32 v[230:231], v158
	v_pk_fma_f32 v[216:217], v[224:225], v[8:9], v[216:217]
	v_pk_fma_f32 v[218:219], v[226:227], v[8:9], v[218:219]
	v_pk_fma_f32 v[220:221], v[228:229], v[8:9], v[220:221]
	v_pk_fma_f32 v[222:223], v[230:231], v[8:9], v[222:223]
	v_cvt_pk_f32_fp8_sdwa v[224:225], v146 src0_sel:WORD_1
	v_cvt_pk_f32_fp8_sdwa v[226:227], v150 src0_sel:WORD_1
	v_cvt_pk_f32_fp8_sdwa v[228:229], v154 src0_sel:WORD_1
	v_cvt_pk_f32_fp8_sdwa v[230:231], v158 src0_sel:WORD_1
	v_pk_fma_f32 v[216:217], v[224:225], v[10:11], v[216:217]
	v_pk_fma_f32 v[218:219], v[226:227], v[10:11], v[218:219]
	v_pk_fma_f32 v[220:221], v[228:229], v[10:11], v[220:221]
	v_pk_fma_f32 v[222:223], v[230:231], v[10:11], v[222:223]
	v_cvt_pk_f32_fp8_e32 v[224:225], v147
	v_cvt_pk_f32_fp8_e32 v[226:227], v151
	v_cvt_pk_f32_fp8_e32 v[228:229], v155
	v_cvt_pk_f32_fp8_e32 v[230:231], v159
	v_pk_fma_f32 v[216:217], v[224:225], v[12:13], v[216:217]
	v_pk_fma_f32 v[218:219], v[226:227], v[12:13], v[218:219]
	v_pk_fma_f32 v[220:221], v[228:229], v[12:13], v[220:221]
	v_pk_fma_f32 v[222:223], v[230:231], v[12:13], v[222:223]
	v_cvt_pk_f32_fp8_sdwa v[224:225], v147 src0_sel:WORD_1
	v_cvt_pk_f32_fp8_sdwa v[226:227], v151 src0_sel:WORD_1
	v_cvt_pk_f32_fp8_sdwa v[228:229], v155 src0_sel:WORD_1
	v_cvt_pk_f32_fp8_sdwa v[230:231], v159 src0_sel:WORD_1
	v_pk_fma_f32 v[216:217], v[224:225], v[14:15], v[216:217]
	v_pk_fma_f32 v[218:219], v[226:227], v[14:15], v[218:219]
	v_pk_fma_f32 v[220:221], v[228:229], v[14:15], v[220:221]
	v_pk_fma_f32 v[222:223], v[230:231], v[14:15], v[222:223]
	v_add_f32_e32 v196, v216, v217
	v_add_f32_e32 v197, v218, v219
	v_add_f32_e32 v198, v220, v221
	v_add_f32_e32 v199, v222, v223
	s_sub_i32 s90, s90, 1
	s_cmp_eq_u32 s90, 0
	s_cbranch_scc1 .LU_sw2
.LU_t0_s2:
	s_waitcnt lgkmcnt(0)
	v_add_u32_e32 v236, v232, v240
	v_add_u32_e32 v237, v233, v240
	v_add_u32_e32 v238, v234, v240
	v_add_u32_e32 v239, v235, v240
	global_load_dwordx4 v[144:147], v236, s[4:5]
	global_load_dwordx4 v[148:151], v237, s[4:5]
	global_load_dwordx4 v[152:155], v238, s[4:5]
	global_load_dwordx4 v[156:159], v239, s[4:5]
	ds_read_b128 v[232:235], v213 offset:96
	s_waitcnt vmcnt(14)
	v_cvt_pk_f32_fp8_e32 v[224:225], v160
	v_cvt_pk_f32_fp8_e32 v[226:227], v164
	v_cvt_pk_f32_fp8_e32 v[228:229], v168
	v_cvt_pk_f32_fp8_e32 v[230:231], v172
	v_pk_mul_f32 v[216:217], v[224:225], v[0:1]
	v_pk_mul_f32 v[218:219], v[226:227], v[0:1]
	v_pk_mul_f32 v[220:221], v[228:229], v[0:1]
	v_pk_mul_f32 v[222:223], v[230:231], v[0:1]
	v_cvt_pk_f32_fp8_sdwa v[224:225], v160 src0_sel:WORD_1
	v_cvt_pk_f32_fp8_sdwa v[226:227], v164 src0_sel:WORD_1
	v_cvt_pk_f32_fp8_sdwa v[228:229], v168 src0_sel:WORD_1
	v_cvt_pk_f32_fp8_sdwa v[230:231], v172 src0_sel:WORD_1
	v_pk_fma_f32 v[216:217], v[224:225], v[2:3], v[216:217]
	v_pk_fma_f32 v[218:219], v[226:227], v[2:3], v[218:219]
	v_pk_fma_f32 v[220:221], v[228:229], v[2:3], v[220:221]
	v_pk_fma_f32 v[222:223], v[230:231], v[2:3], v[222:223]
	v_cvt_pk_f32_fp8_e32 v[224:225], v161
	v_cvt_pk_f32_fp8_e32 v[226:227], v165
	v_cvt_pk_f32_fp8_e32 v[228:229], v169
	v_cvt_pk_f32_fp8_e32 v[230:231], v173
	v_pk_fma_f32 v[216:217], v[224:225], v[4:5], v[216:217]
	v_pk_fma_f32 v[218:219], v[226:227], v[4:5], v[218:219]
	v_pk_fma_f32 v[220:221], v[228:229], v[4:5], v[220:221]
	v_pk_fma_f32 v[222:223], v[230:231], v[4:5], v[222:223]
	v_cvt_pk_f32_fp8_sdwa v[224:225], v161 src0_sel:WORD_1
	v_cvt_pk_f32_fp8_sdwa v[226:227], v165 src0_sel:WORD_1
	v_cvt_pk_f32_fp8_sdwa v[228:229], v169 src0_sel:WORD_1
	v_cvt_pk_f32_fp8_sdwa v[230:231], v173 src0_sel:WORD_1
	v_pk_fma_f32 v[216:217], v[224:225], v[6:7], v[216:217]
	v_pk_fma_f32 v[218:219], v[226:227], v[6:7], v[218:219]
	v_pk_fma_f32 v[220:221], v[228:229], v[6:7], v[220:221]
	v_pk_fma_f32 v[222:223], v[230:231], v[6:7], v[222:223]
	v_cvt_pk_f32_fp8_e32 v[224:225], v162
	v_cvt_pk_f32_fp8_e32 v[226:227], v166
	v_cvt_pk_f32_fp8_e32 v[228:229], v170
	v_cvt_pk_f32_fp8_e32 v[230:231], v174
	v_pk_fma_f32 v[216:217], v[224:225], v[8:9], v[216:217]
	v_pk_fma_f32 v[218:219], v[226:227], v[8:9], v[218:219]
	v_pk_fma_f32 v[220:221], v[228:229], v[8:9], v[220:221]
	v_pk_fma_f32 v[222:223], v[230:231], v[8:9], v[222:223]
	v_cvt_pk_f32_fp8_sdwa v[224:225], v162 src0_sel:WORD_1
	v_cvt_pk_f32_fp8_sdwa v[226:227], v166 src0_sel:WORD_1
	v_cvt_pk_f32_fp8_sdwa v[228:229], v170 src0_sel:WORD_1
	v_cvt_pk_f32_fp8_sdwa v[230:231], v174 src0_sel:WORD_1
	v_pk_fma_f32 v[216:217], v[224:225], v[10:11], v[216:217]
	v_pk_fma_f32 v[218:219], v[226:227], v[10:11], v[218:219]
	v_pk_fma_f32 v[220:221], v[228:229], v[10:11], v[220:221]
	v_pk_fma_f32 v[222:223], v[230:231], v[10:11], v[222:223]
	v_cvt_pk_f32_fp8_e32 v[224:225], v163
	v_cvt_pk_f32_fp8_e32 v[226:227], v167
	v_cvt_pk_f32_fp8_e32 v[228:229], v171
	v_cvt_pk_f32_fp8_e32 v[230:231], v175
	v_pk_fma_f32 v[216:217], v[224:225], v[12:13], v[216:217]
	v_pk_fma_f32 v[218:219], v[226:227], v[12:13], v[218:219]
	v_pk_fma_f32 v[220:221], v[228:229], v[12:13], v[220:221]
	v_pk_fma_f32 v[222:223], v[230:231], v[12:13], v[222:223]
	v_cvt_pk_f32_fp8_sdwa v[224:225], v163 src0_sel:WORD_1
	v_cvt_pk_f32_fp8_sdwa v[226:227], v167 src0_sel:WORD_1
	v_cvt_pk_f32_fp8_sdwa v[228:229], v171 src0_sel:WORD_1
	v_cvt_pk_f32_fp8_sdwa v[230:231], v175 src0_sel:WORD_1
	v_pk_fma_f32 v[216:217], v[224:225], v[14:15], v[216:217]
	v_pk_fma_f32 v[218:219], v[226:227], v[14:15], v[218:219]
	v_pk_fma_f32 v[220:221], v[228:229], v[14:15], v[220:221]
	v_pk_fma_f32 v[222:223], v[230:231], v[14:15], v[222:223]
	v_add_f32_e32 v200, v216, v217
	v_add_f32_e32 v201, v218, v219
	v_add_f32_e32 v202, v220, v221
	v_add_f32_e32 v203, v222, v223
	s_sub_i32 s90, s90, 1
	s_cmp_eq_u32 s90, 0
	s_cbranch_scc1 .LU_sw3
.LU_t0_s3:
	s_waitcnt lgkmcnt(0)
	v_add_u32_e32 v236, v232, v240
	v_add_u32_e32 v237, v233, v240
	v_add_u32_e32 v238, v234, v240
	v_add_u32_e32 v239, v235, v240
	global_load_dwordx4 v[160:163], v236, s[4:5]
	global_load_dwordx4 v[164:167], v237, s[4:5]
	global_load_dwordx4 v[168:171], v238, s[4:5]
	global_load_dwordx4 v[172:175], v239, s[4:5]
	ds_read_b128 v[232:235], v213 offset:112
	s_waitcnt vmcnt(12)
	v_cvt_pk_f32_fp8_e32 v[224:225], v176
	v_cvt_pk_f32_fp8_e32 v[226:227], v180
	v_cvt_pk_f32_fp8_e32 v[228:229], v184
	v_cvt_pk_f32_fp8_e32 v[230:231], v188
	v_pk_mul_f32 v[216:217], v[224:225], v[0:1]
	v_pk_mul_f32 v[218:219], v[226:227], v[0:1]
	v_pk_mul_f32 v[220:221], v[228:229], v[0:1]
	v_pk_mul_f32 v[222:223], v[230:231], v[0:1]
	v_cvt_pk_f32_fp8_sdwa v[224:225], v176 src0_sel:WORD_1
	v_cvt_pk_f32_fp8_sdwa v[226:227], v180 src0_sel:WORD_1
	v_cvt_pk_f32_fp8_sdwa v[228:229], v184 src0_sel:WORD_1
	v_cvt_pk_f32_fp8_sdwa v[230:231], v188 src0_sel:WORD_1
	v_pk_fma_f32 v[216:217], v[224:225], v[2:3], v[216:217]
	v_pk_fma_f32 v[218:219], v[226:227], v[2:3], v[218:219]
	v_pk_fma_f32 v[220:221], v[228:229], v[2:3], v[220:221]
	v_pk_fma_f32 v[222:223], v[230:231], v[2:3], v[222:223]
	v_cvt_pk_f32_fp8_e32 v[224:225], v177
	v_cvt_pk_f32_fp8_e32 v[226:227], v181
	v_cvt_pk_f32_fp8_e32 v[228:229], v185
	v_cvt_pk_f32_fp8_e32 v[230:231], v189
	v_pk_fma_f32 v[216:217], v[224:225], v[4:5], v[216:217]
	v_pk_fma_f32 v[218:219], v[226:227], v[4:5], v[218:219]
	v_pk_fma_f32 v[220:221], v[228:229], v[4:5], v[220:221]
	v_pk_fma_f32 v[222:223], v[230:231], v[4:5], v[222:223]
	v_cvt_pk_f32_fp8_sdwa v[224:225], v177 src0_sel:WORD_1
	v_cvt_pk_f32_fp8_sdwa v[226:227], v181 src0_sel:WORD_1
	v_cvt_pk_f32_fp8_sdwa v[228:229], v185 src0_sel:WORD_1
	v_cvt_pk_f32_fp8_sdwa v[230:231], v189 src0_sel:WORD_1
	v_pk_fma_f32 v[216:217], v[224:225], v[6:7], v[216:217]
	v_pk_fma_f32 v[218:219], v[226:227], v[6:7], v[218:219]
	v_pk_fma_f32 v[220:221], v[228:229], v[6:7], v[220:221]
	v_pk_fma_f32 v[222:223], v[230:231], v[6:7], v[222:223]
	v_cvt_pk_f32_fp8_e32 v[224:225], v178
	v_cvt_pk_f32_fp8_e32 v[226:227], v182
	v_cvt_pk_f32_fp8_e32 v[228:229], v186
	v_cvt_pk_f32_fp8_e32 v[230:231], v190
	v_pk_fma_f32 v[216:217], v[224:225], v[8:9], v[216:217]
	v_pk_fma_f32 v[218:219], v[226:227], v[8:9], v[218:219]
	v_pk_fma_f32 v[220:221], v[228:229], v[8:9], v[220:221]
	v_pk_fma_f32 v[222:223], v[230:231], v[8:9], v[222:223]
	v_cvt_pk_f32_fp8_sdwa v[224:225], v178 src0_sel:WORD_1
	v_cvt_pk_f32_fp8_sdwa v[226:227], v182 src0_sel:WORD_1
	v_cvt_pk_f32_fp8_sdwa v[228:229], v186 src0_sel:WORD_1
	v_cvt_pk_f32_fp8_sdwa v[230:231], v190 src0_sel:WORD_1
	v_pk_fma_f32 v[216:217], v[224:225], v[10:11], v[216:217]
	v_pk_fma_f32 v[218:219], v[226:227], v[10:11], v[218:219]
	v_pk_fma_f32 v[220:221], v[228:229], v[10:11], v[220:221]
	v_pk_fma_f32 v[222:223], v[230:231], v[10:11], v[222:223]
	v_cvt_pk_f32_fp8_e32 v[224:225], v179
	v_cvt_pk_f32_fp8_e32 v[226:227], v183
	v_cvt_pk_f32_fp8_e32 v[228:229], v187
	v_cvt_pk_f32_fp8_e32 v[230:231], v191
	v_pk_fma_f32 v[216:217], v[224:225], v[12:13], v[216:217]
	v_pk_fma_f32 v[218:219], v[226:227], v[12:13], v[218:219]
	v_pk_fma_f32 v[220:221], v[228:229], v[12:13], v[220:221]
	v_pk_fma_f32 v[222:223], v[230:231], v[12:13], v[222:223]
	v_cvt_pk_f32_fp8_sdwa v[224:225], v179 src0_sel:WORD_1
	v_cvt_pk_f32_fp8_sdwa v[226:227], v183 src0_sel:WORD_1
	v_cvt_pk_f32_fp8_sdwa v[228:229], v187 src0_sel:WORD_1
	v_cvt_pk_f32_fp8_sdwa v[230:231], v191 src0_sel:WORD_1
	v_pk_fma_f32 v[216:217], v[224:225], v[14:15], v[216:217]
	v_pk_fma_f32 v[218:219], v[226:227], v[14:15], v[218:219]
	v_pk_fma_f32 v[220:221], v[228:229], v[14:15], v[220:221]
	v_pk_fma_f32 v[222:223], v[230:231], v[14:15], v[222:223]
	v_add_f32_e32 v204, v216, v217
	v_add_f32_e32 v205, v218, v219
	v_add_f32_e32 v206, v220, v221
	v_add_f32_e32 v207, v222, v223
	s_nop 0
	v_permlane32_swap_b32_e32 v192, v200
	v_permlane32_swap_b32_e32 v193, v201
	v_permlane32_swap_b32_e32 v194, v202
	v_permlane32_swap_b32_e32 v195, v203
	v_permlane32_swap_b32_e32 v196, v204
	v_permlane32_swap_b32_e32 v197, v205
	v_permlane32_swap_b32_e32 v198, v206
	v_permlane32_swap_b32_e32 v199, v207
	v_add_f32_e32 v192, v192, v200
	v_add_f32_e32 v193, v193, v201
	v_add_f32_e32 v194, v194, v202
	v_add_f32_e32 v195, v195, v203
	v_add_f32_e32 v196, v196, v204
	v_add_f32_e32 v197, v197, v205
	v_add_f32_e32 v198, v198, v206
	v_add_f32_e32 v199, v199, v207
	v_permlane16_swap_b32_e32 v192, v196
	v_permlane16_swap_b32_e32 v193, v197
	v_permlane16_swap_b32_e32 v194, v198
	v_permlane16_swap_b32_e32 v195, v199
	v_add_f32_e32 v192, v192, v196
	v_add_f32_e32 v193, v193, v197
	v_add_f32_e32 v194, v194, v198
	v_add_f32_e32 v195, v195, v199
	v_add_f32_dpp v216, v192, v192 row_ror:8 row_mask:0xf bank_mask:0xf
	v_add_f32_dpp v218, v194, v194 row_ror:8 row_mask:0xf bank_mask:0xf
	v_add_f32_dpp v216, v193, v193 row_ror:8 row_mask:0xf bank_mask:0xc
	v_add_f32_dpp v218, v195, v195 row_ror:8 row_mask:0xf bank_mask:0xc
	s_nop 1
	v_add_f32_dpp v220, v216, v216 row_half_mirror row_mask:0xf bank_mask:0xf
	v_add_f32_dpp v220, v218, v218 row_half_mirror row_mask:0xf bank_mask:0xa
	s_nop 1
	v_add_f32_dpp v220, v220, v220 quad_perm:[1,0,3,2] row_mask:0xf bank_mask:0xf
	s_nop 1
	v_add_f32_dpp v220, v220, v220 quad_perm:[2,3,0,1] row_mask:0xf bank_mask:0xf
	v_mul_f32_e32 v216, v252, v220
	v_fma_f32 v218, |v216|, s72, 1.0
	v_mul_f32_e32 v222, v216, v216
	v_rcp_f32_e32 v218, v218
	v_mul_f32_e32 v222, 0xbf38aa3b, v222
	v_exp_f32_e32 v222, v222
	v_fmamk_f32 v224, v218, 0x3f07dc22, v242
	v_fmaak_f32 v224, v218, v224, 0x3f35f0e3
	v_fmaak_f32 v224, v218, v224, 0xbe11a98e
	v_fmaak_f32 v224, v218, v224, 0x3e027906
	v_mul_f32_e32 v224, v218, v224
	v_mul_f32_e32 v224, v222, v224
	v_mul_f32_e32 v226, v216, v224
	v_fma_f32 v224, -v216, v224, v216
	v_cmp_gt_f32_e32 vcc, 0, v216
	s_nop 1
	v_cndmask_b32_e32 v224, v224, v226, vcc
	v_mul_f32_e32 v224, v249, v224
	v_mul_f32_e32 v224, v253, v224
	ds_write_b32 v211, v224 offset:4864
	v_add_u32_e32 v211, 64, v211
	v_add_u32_e32 v213, 64, v213
	ds_read_b32 v248, v211
	ds_read_b32 v249, v211 offset:4864
	s_add_i32 s21, s21, 4
	s_sub_i32 s90, s90, 1
	s_cmp_eq_u32 s90, 0
	s_cbranch_scc1 .LU_sw0
	s_branch .LU_t0_s0
.LU_t1_s0:
	s_cmp_ge_u32 s21, s20
	s_cbranch_scc1 .LU_done
	s_waitcnt lgkmcnt(0)
	v_add_u32_e32 v236, v232, v240
	v_add_u32_e32 v237, v233, v240
	v_add_u32_e32 v238, v234, v240
	v_add_u32_e32 v239, v235, v240
	v_lshrrev_b32_e32 v208, 8, v248
	global_load_dword v252, v208, s[8:9]
	global_load_dword v253, v208, s[52:53]
	global_load_dwordx4 v[176:179], v236, s[4:5]
	global_load_dwordx4 v[180:183], v237, s[4:5]
	global_load_dwordx4 v[184:187], v238, s[4:5]
	global_load_dwordx4 v[188:191], v239, s[4:5]
	ds_read_b128 v[232:235], v213 offset:64
	s_waitcnt vmcnt(14)
	v_cvt_pk_f32_fp8_e32 v[224:225], v128
	v_cvt_pk_f32_fp8_e32 v[226:227], v132
	v_cvt_pk_f32_fp8_e32 v[228:229], v136
	v_cvt_pk_f32_fp8_e32 v[230:231], v140
	v_pk_mul_f32 v[216:217], v[224:225], v[16:17]
	v_pk_mul_f32 v[218:219], v[226:227], v[16:17]
	v_pk_mul_f32 v[220:221], v[228:229], v[16:17]
	v_pk_mul_f32 v[222:223], v[230:231], v[16:17]
	v_cvt_pk_f32_fp8_sdwa v[224:225], v128 src0_sel:WORD_1
	v_cvt_pk_f32_fp8_sdwa v[226:227], v132 src0_sel:WORD_1
	v_cvt_pk_f32_fp8_sdwa v[228:229], v136 src0_sel:WORD_1
	v_cvt_pk_f32_fp8_sdwa v[230:231], v140 src0_sel:WORD_1
	v_pk_fma_f32 v[216:217], v[224:225], v[18:19], v[216:217]
	v_pk_fma_f32 v[218:219], v[226:227], v[18:19], v[218:219]
	v_pk_fma_f32 v[220:221], v[228:229], v[18:19], v[220:221]
	v_pk_fma_f32 v[222:223], v[230:231], v[18:19], v[222:223]
	v_cvt_pk_f32_fp8_e32 v[224:225], v129
	v_cvt_pk_f32_fp8_e32 v[226:227], v133
	v_cvt_pk_f32_fp8_e32 v[228:229], v137
	v_cvt_pk_f32_fp8_e32 v[230:231], v141
	v_pk_fma_f32 v[216:217], v[224:225], v[20:21], v[216:217]
	v_pk_fma_f32 v[218:219], v[226:227], v[20:21], v[218:219]
	v_pk_fma_f32 v[220:221], v[228:229], v[20:21], v[220:221]
	v_pk_fma_f32 v[222:223], v[230:231], v[20:21], v[222:223]
	v_cvt_pk_f32_fp8_sdwa v[224:225], v129 src0_sel:WORD_1
	v_cvt_pk_f32_fp8_sdwa v[226:227], v133 src0_sel:WORD_1
	v_cvt_pk_f32_fp8_sdwa v[228:229], v137 src0_sel:WORD_1
	v_cvt_pk_f32_fp8_sdwa v[230:231], v141 src0_sel:WORD_1
	v_pk_fma_f32 v[216:217], v[224:225], v[22:23], v[216:217]
	v_pk_fma_f32 v[218:219], v[226:227], v[22:23], v[218:219]
	v_pk_fma_f32 v[220:221], v[228:229], v[22:23], v[220:221]
	v_pk_fma_f32 v[222:223], v[230:231], v[22:23], v[222:223]
	v_cvt_pk_f32_fp8_e32 v[224:225], v130
	v_cvt_pk_f32_fp8_e32 v[226:227], v134
	v_cvt_pk_f32_fp8_e32 v[228:229], v138
	v_cvt_pk_f32_fp8_e32 v[230:231], v142
	v_pk_fma_f32 v[216:217], v[224:225], v[24:25], v[216:217]
	v_pk_fma_f32 v[218:219], v[226:227], v[24:25], v[218:219]
	v_pk_fma_f32 v[220:221], v[228:229], v[24:25], v[220:221]
	v_pk_fma_f32 v[222:223], v[230:231], v[24:25], v[222:223]
	v_cvt_pk_f32_fp8_sdwa v[224:225], v130 src0_sel:WORD_1
	v_cvt_pk_f32_fp8_sdwa v[226:227], v134 src0_sel:WORD_1
	v_cvt_pk_f32_fp8_sdwa v[228:229], v138 src0_sel:WORD_1
	v_cvt_pk_f32_fp8_sdwa v[230:231], v142 src0_sel:WORD_1
	v_pk_fma_f32 v[216:217], v[224:225], v[26:27], v[216:217]
	v_pk_fma_f32 v[218:219], v[226:227], v[26:27], v[218:219]
	v_pk_fma_f32 v[220:221], v[228:229], v[26:27], v[220:221]
	v_pk_fma_f32 v[222:223], v[230:231], v[26:27], v[222:223]
	v_cvt_pk_f32_fp8_e32 v[224:225], v131
	v_cvt_pk_f32_fp8_e32 v[226:227], v135
	v_cvt_pk_f32_fp8_e32 v[228:229], v139
	v_cvt_pk_f32_fp8_e32 v[230:231], v143
	v_pk_fma_f32 v[216:217], v[224:225], v[28:29], v[216:217]
	v_pk_fma_f32 v[218:219], v[226:227], v[28:29], v[218:219]
	v_pk_fma_f32 v[220:221], v[228:229], v[28:29], v[220:221]
	v_pk_fma_f32 v[222:223], v[230:231], v[28:29], v[222:223]
	v_cvt_pk_f32_fp8_sdwa v[224:225], v131 src0_sel:WORD_1
	v_cvt_pk_f32_fp8_sdwa v[226:227], v135 src0_sel:WORD_1
	v_cvt_pk_f32_fp8_sdwa v[228:229], v139 src0_sel:WORD_1
	v_cvt_pk_f32_fp8_sdwa v[230:231], v143 src0_sel:WORD_1
	v_pk_fma_f32 v[216:217], v[224:225], v[30:31], v[216:217]
	v_pk_fma_f32 v[218:219], v[226:227], v[30:31], v[218:219]
	v_pk_fma_f32 v[220:221], v[228:229], v[30:31], v[220:221]
	v_pk_fma_f32 v[222:223], v[230:231], v[30:31], v[222:223]
	v_add_f32_e32 v192, v216, v217
	v_add_f32_e32 v193, v218, v219
	v_add_f32_e32 v194, v220, v221
	v_add_f32_e32 v195, v222, v223
	s_sub_i32 s90, s90, 1
	s_cmp_eq_u32 s90, 0
	s_cbranch_scc1 .LU_sw1
.LU_t1_s1:
	s_waitcnt lgkmcnt(0)
	v_add_u32_e32 v236, v232, v240
	v_add_u32_e32 v237, v233, v240
	v_add_u32_e32 v238, v234, v240
	v_add_u32_e32 v239, v235, v240
	global_load_dwordx4 v[128:131], v236, s[4:5]
	global_load_dwordx4 v[132:135], v237, s[4:5]
	global_load_dwordx4 v[136:139], v238, s[4:5]
	global_load_dwordx4 v[140:143], v239, s[4:5]
	ds_read_b128 v[232:235], v213 offset:80
	s_waitcnt vmcnt(14)
	v_cvt_pk_f32_fp8_e32 v[224:225], v144
	v_cvt_pk_f32_fp8_e32 v[226:227], v148
	v_cvt_pk_f32_fp8_e32 v[228:229], v152
	v_cvt_pk_f32_fp8_e32 v[230:231], v156
	v_pk_mul_f32 v[216:217], v[224:225], v[16:17]
	v_pk_mul_f32 v[218:219], v[226:227], v[16:17]
	v_pk_mul_f32 v[220:221], v[228:229], v[16:17]
	v_pk_mul_f32 v[222:223], v[230:231], v[16:17]
	v_cvt_pk_f32_fp8_sdwa v[224:225], v144 src0_sel:WORD_1
	v_cvt_pk_f32_fp8_sdwa v[226:227], v148 src0_sel:WORD_1
	v_cvt_pk_f32_fp8_sdwa v[228:229], v152 src0_sel:WORD_1
	v_cvt_pk_f32_fp8_sdwa v[230:231], v156 src0_sel:WORD_1
	v_pk_fma_f32 v[216:217], v[224:225], v[18:19], v[216:217]
	v_pk_fma_f32 v[218:219], v[226:227], v[18:19], v[218:219]
	v_pk_fma_f32 v[220:221], v[228:229], v[18:19], v[220:221]
	v_pk_fma_f32 v[222:223], v[230:231], v[18:19], v[222:223]
	v_cvt_pk_f32_fp8_e32 v[224:225], v145
	v_cvt_pk_f32_fp8_e32 v[226:227], v149
	v_cvt_pk_f32_fp8_e32 v[228:229], v153
	v_cvt_pk_f32_fp8_e32 v[230:231], v157
	v_pk_fma_f32 v[216:217], v[224:225], v[20:21], v[216:217]
	v_pk_fma_f32 v[218:219], v[226:227], v[20:21], v[218:219]
	v_pk_fma_f32 v[220:221], v[228:229], v[20:21], v[220:221]
	v_pk_fma_f32 v[222:223], v[230:231], v[20:21], v[222:223]
	v_cvt_pk_f32_fp8_sdwa v[224:225], v145 src0_sel:WORD_1
	v_cvt_pk_f32_fp8_sdwa v[226:227], v149 src0_sel:WORD_1
	v_cvt_pk_f32_fp8_sdwa v[228:229], v153 src0_sel:WORD_1
	v_cvt_pk_f32_fp8_sdwa v[230:231], v157 src0_sel:WORD_1
	v_pk_fma_f32 v[216:217], v[224:225], v[22:23], v[216:217]
	v_pk_fma_f32 v[218:219], v[226:227], v[22:23], v[218:219]
	v_pk_fma_f32 v[220:221], v[228:229], v[22:23], v[220:221]
	v_pk_fma_f32 v[222:223], v[230:231], v[22:23], v[222:223]
	v_cvt_pk_f32_fp8_e32 v[224:225], v146
	v_cvt_pk_f32_fp8_e32 v[226:227], v150
	v_cvt_pk_f32_fp8_e32 v[228:229], v154
	v_cvt_pk_f32_fp8_e32 v[230:231], v158
	v_pk_fma_f32 v[216:217], v[224:225], v[24:25], v[216:217]
	v_pk_fma_f32 v[218:219], v[226:227], v[24:25], v[218:219]
	v_pk_fma_f32 v[220:221], v[228:229], v[24:25], v[220:221]
	v_pk_fma_f32 v[222:223], v[230:231], v[24:25], v[222:223]
	v_cvt_pk_f32_fp8_sdwa v[224:225], v146 src0_sel:WORD_1
	v_cvt_pk_f32_fp8_sdwa v[226:227], v150 src0_sel:WORD_1
	v_cvt_pk_f32_fp8_sdwa v[228:229], v154 src0_sel:WORD_1
	v_cvt_pk_f32_fp8_sdwa v[230:231], v158 src0_sel:WORD_1
	v_pk_fma_f32 v[216:217], v[224:225], v[26:27], v[216:217]
	v_pk_fma_f32 v[218:219], v[226:227], v[26:27], v[218:219]
	v_pk_fma_f32 v[220:221], v[228:229], v[26:27], v[220:221]
	v_pk_fma_f32 v[222:223], v[230:231], v[26:27], v[222:223]
	v_cvt_pk_f32_fp8_e32 v[224:225], v147
	v_cvt_pk_f32_fp8_e32 v[226:227], v151
	v_cvt_pk_f32_fp8_e32 v[228:229], v155
	v_cvt_pk_f32_fp8_e32 v[230:231], v159
	v_pk_fma_f32 v[216:217], v[224:225], v[28:29], v[216:217]
	v_pk_fma_f32 v[218:219], v[226:227], v[28:29], v[218:219]
	v_pk_fma_f32 v[220:221], v[228:229], v[28:29], v[220:221]
	v_pk_fma_f32 v[222:223], v[230:231], v[28:29], v[222:223]
	v_cvt_pk_f32_fp8_sdwa v[224:225], v147 src0_sel:WORD_1
	v_cvt_pk_f32_fp8_sdwa v[226:227], v151 src0_sel:WORD_1
	v_cvt_pk_f32_fp8_sdwa v[228:229], v155 src0_sel:WORD_1
	v_cvt_pk_f32_fp8_sdwa v[230:231], v159 src0_sel:WORD_1
	v_pk_fma_f32 v[216:217], v[224:225], v[30:31], v[216:217]
	v_pk_fma_f32 v[218:219], v[226:227], v[30:31], v[218:219]
	v_pk_fma_f32 v[220:221], v[228:229], v[30:31], v[220:221]
	v_pk_fma_f32 v[222:223], v[230:231], v[30:31], v[222:223]
	v_add_f32_e32 v196, v216, v217
	v_add_f32_e32 v197, v218, v219
	v_add_f32_e32 v198, v220, v221
	v_add_f32_e32 v199, v222, v223
	s_sub_i32 s90, s90, 1
	s_cmp_eq_u32 s90, 0
	s_cbranch_scc1 .LU_sw2
.LU_t1_s2:
	s_waitcnt lgkmcnt(0)
	v_add_u32_e32 v236, v232, v240
	v_add_u32_e32 v237, v233, v240
	v_add_u32_e32 v238, v234, v240
	v_add_u32_e32 v239, v235, v240
	global_load_dwordx4 v[144:147], v236, s[4:5]
	global_load_dwordx4 v[148:151], v237, s[4:5]
	global_load_dwordx4 v[152:155], v238, s[4:5]
	global_load_dwordx4 v[156:159], v239, s[4:5]
	ds_read_b128 v[232:235], v213 offset:96
	s_waitcnt vmcnt(14)
	v_cvt_pk_f32_fp8_e32 v[224:225], v160
	v_cvt_pk_f32_fp8_e32 v[226:227], v164
	v_cvt_pk_f32_fp8_e32 v[228:229], v168
	v_cvt_pk_f32_fp8_e32 v[230:231], v172
	v_pk_mul_f32 v[216:217], v[224:225], v[16:17]
	v_pk_mul_f32 v[218:219], v[226:227], v[16:17]
	v_pk_mul_f32 v[220:221], v[228:229], v[16:17]
	v_pk_mul_f32 v[222:223], v[230:231], v[16:17]
	v_cvt_pk_f32_fp8_sdwa v[224:225], v160 src0_sel:WORD_1
	v_cvt_pk_f32_fp8_sdwa v[226:227], v164 src0_sel:WORD_1
	v_cvt_pk_f32_fp8_sdwa v[228:229], v168 src0_sel:WORD_1
	v_cvt_pk_f32_fp8_sdwa v[230:231], v172 src0_sel:WORD_1
	v_pk_fma_f32 v[216:217], v[224:225], v[18:19], v[216:217]
	v_pk_fma_f32 v[218:219], v[226:227], v[18:19], v[218:219]
	v_pk_fma_f32 v[220:221], v[228:229], v[18:19], v[220:221]
	v_pk_fma_f32 v[222:223], v[230:231], v[18:19], v[222:223]
	v_cvt_pk_f32_fp8_e32 v[224:225], v161
	v_cvt_pk_f32_fp8_e32 v[226:227], v165
	v_cvt_pk_f32_fp8_e32 v[228:229], v169
	v_cvt_pk_f32_fp8_e32 v[230:231], v173
	v_pk_fma_f32 v[216:217], v[224:225], v[20:21], v[216:217]
	v_pk_fma_f32 v[218:219], v[226:227], v[20:21], v[218:219]
	v_pk_fma_f32 v[220:221], v[228:229], v[20:21], v[220:221]
	v_pk_fma_f32 v[222:223], v[230:231], v[20:21], v[222:223]
	v_cvt_pk_f32_fp8_sdwa v[224:225], v161 src0_sel:WORD_1
	v_cvt_pk_f32_fp8_sdwa v[226:227], v165 src0_sel:WORD_1
	v_cvt_pk_f32_fp8_sdwa v[228:229], v169 src0_sel:WORD_1
	v_cvt_pk_f32_fp8_sdwa v[230:231], v173 src0_sel:WORD_1
	v_pk_fma_f32 v[216:217], v[224:225], v[22:23], v[216:217]
	v_pk_fma_f32 v[218:219], v[226:227], v[22:23], v[218:219]
	v_pk_fma_f32 v[220:221], v[228:229], v[22:23], v[220:221]
	v_pk_fma_f32 v[222:223], v[230:231], v[22:23], v[222:223]
	v_cvt_pk_f32_fp8_e32 v[224:225], v162
	v_cvt_pk_f32_fp8_e32 v[226:227], v166
	v_cvt_pk_f32_fp8_e32 v[228:229], v170
	v_cvt_pk_f32_fp8_e32 v[230:231], v174
	v_pk_fma_f32 v[216:217], v[224:225], v[24:25], v[216:217]
	v_pk_fma_f32 v[218:219], v[226:227], v[24:25], v[218:219]
	v_pk_fma_f32 v[220:221], v[228:229], v[24:25], v[220:221]
	v_pk_fma_f32 v[222:223], v[230:231], v[24:25], v[222:223]
	v_cvt_pk_f32_fp8_sdwa v[224:225], v162 src0_sel:WORD_1
	v_cvt_pk_f32_fp8_sdwa v[226:227], v166 src0_sel:WORD_1
	v_cvt_pk_f32_fp8_sdwa v[228:229], v170 src0_sel:WORD_1
	v_cvt_pk_f32_fp8_sdwa v[230:231], v174 src0_sel:WORD_1
	v_pk_fma_f32 v[216:217], v[224:225], v[26:27], v[216:217]
	v_pk_fma_f32 v[218:219], v[226:227], v[26:27], v[218:219]
	v_pk_fma_f32 v[220:221], v[228:229], v[26:27], v[220:221]
	v_pk_fma_f32 v[222:223], v[230:231], v[26:27], v[222:223]
	v_cvt_pk_f32_fp8_e32 v[224:225], v163
	v_cvt_pk_f32_fp8_e32 v[226:227], v167
	v_cvt_pk_f32_fp8_e32 v[228:229], v171
	v_cvt_pk_f32_fp8_e32 v[230:231], v175
	v_pk_fma_f32 v[216:217], v[224:225], v[28:29], v[216:217]
	v_pk_fma_f32 v[218:219], v[226:227], v[28:29], v[218:219]
	v_pk_fma_f32 v[220:221], v[228:229], v[28:29], v[220:221]
	v_pk_fma_f32 v[222:223], v[230:231], v[28:29], v[222:223]
	v_cvt_pk_f32_fp8_sdwa v[224:225], v163 src0_sel:WORD_1
	v_cvt_pk_f32_fp8_sdwa v[226:227], v167 src0_sel:WORD_1
	v_cvt_pk_f32_fp8_sdwa v[228:229], v171 src0_sel:WORD_1
	v_cvt_pk_f32_fp8_sdwa v[230:231], v175 src0_sel:WORD_1
	v_pk_fma_f32 v[216:217], v[224:225], v[30:31], v[216:217]
	v_pk_fma_f32 v[218:219], v[226:227], v[30:31], v[218:219]
	v_pk_fma_f32 v[220:221], v[228:229], v[30:31], v[220:221]
	v_pk_fma_f32 v[222:223], v[230:231], v[30:31], v[222:223]
	v_add_f32_e32 v200, v216, v217
	v_add_f32_e32 v201, v218, v219
	v_add_f32_e32 v202, v220, v221
	v_add_f32_e32 v203, v222, v223
	s_sub_i32 s90, s90, 1
	s_cmp_eq_u32 s90, 0
	s_cbranch_scc1 .LU_sw3
.LU_t1_s3:
	s_waitcnt lgkmcnt(0)
	v_add_u32_e32 v236, v232, v240
	v_add_u32_e32 v237, v233, v240
	v_add_u32_e32 v238, v234, v240
	v_add_u32_e32 v239, v235, v240
	global_load_dwordx4 v[160:163], v236, s[4:5]
	global_load_dwordx4 v[164:167], v237, s[4:5]
	global_load_dwordx4 v[168:171], v238, s[4:5]
	global_load_dwordx4 v[172:175], v239, s[4:5]
	ds_read_b128 v[232:235], v213 offset:112
	s_waitcnt vmcnt(12)
	v_cvt_pk_f32_fp8_e32 v[224:225], v176
	v_cvt_pk_f32_fp8_e32 v[226:227], v180
	v_cvt_pk_f32_fp8_e32 v[228:229], v184
	v_cvt_pk_f32_fp8_e32 v[230:231], v188
	v_pk_mul_f32 v[216:217], v[224:225], v[16:17]
	v_pk_mul_f32 v[218:219], v[226:227], v[16:17]
	v_pk_mul_f32 v[220:221], v[228:229], v[16:17]
	v_pk_mul_f32 v[222:223], v[230:231], v[16:17]
	v_cvt_pk_f32_fp8_sdwa v[224:225], v176 src0_sel:WORD_1
	v_cvt_pk_f32_fp8_sdwa v[226:227], v180 src0_sel:WORD_1
	v_cvt_pk_f32_fp8_sdwa v[228:229], v184 src0_sel:WORD_1
	v_cvt_pk_f32_fp8_sdwa v[230:231], v188 src0_sel:WORD_1
	v_pk_fma_f32 v[216:217], v[224:225], v[18:19], v[216:217]
	v_pk_fma_f32 v[218:219], v[226:227], v[18:19], v[218:219]
	v_pk_fma_f32 v[220:221], v[228:229], v[18:19], v[220:221]
	v_pk_fma_f32 v[222:223], v[230:231], v[18:19], v[222:223]
	v_cvt_pk_f32_fp8_e32 v[224:225], v177
	v_cvt_pk_f32_fp8_e32 v[226:227], v181
	v_cvt_pk_f32_fp8_e32 v[228:229], v185
	v_cvt_pk_f32_fp8_e32 v[230:231], v189
	v_pk_fma_f32 v[216:217], v[224:225], v[20:21], v[216:217]
	v_pk_fma_f32 v[218:219], v[226:227], v[20:21], v[218:219]
	v_pk_fma_f32 v[220:221], v[228:229], v[20:21], v[220:221]
	v_pk_fma_f32 v[222:223], v[230:231], v[20:21], v[222:223]
	v_cvt_pk_f32_fp8_sdwa v[224:225], v177 src0_sel:WORD_1
	v_cvt_pk_f32_fp8_sdwa v[226:227], v181 src0_sel:WORD_1
	v_cvt_pk_f32_fp8_sdwa v[228:229], v185 src0_sel:WORD_1
	v_cvt_pk_f32_fp8_sdwa v[230:231], v189 src0_sel:WORD_1
	v_pk_fma_f32 v[216:217], v[224:225], v[22:23], v[216:217]
	v_pk_fma_f32 v[218:219], v[226:227], v[22:23], v[218:219]
	v_pk_fma_f32 v[220:221], v[228:229], v[22:23], v[220:221]
	v_pk_fma_f32 v[222:223], v[230:231], v[22:23], v[222:223]
	v_cvt_pk_f32_fp8_e32 v[224:225], v178
	v_cvt_pk_f32_fp8_e32 v[226:227], v182
	v_cvt_pk_f32_fp8_e32 v[228:229], v186
	v_cvt_pk_f32_fp8_e32 v[230:231], v190
	v_pk_fma_f32 v[216:217], v[224:225], v[24:25], v[216:217]
	v_pk_fma_f32 v[218:219], v[226:227], v[24:25], v[218:219]
	v_pk_fma_f32 v[220:221], v[228:229], v[24:25], v[220:221]
	v_pk_fma_f32 v[222:223], v[230:231], v[24:25], v[222:223]
	v_cvt_pk_f32_fp8_sdwa v[224:225], v178 src0_sel:WORD_1
	v_cvt_pk_f32_fp8_sdwa v[226:227], v182 src0_sel:WORD_1
	v_cvt_pk_f32_fp8_sdwa v[228:229], v186 src0_sel:WORD_1
	v_cvt_pk_f32_fp8_sdwa v[230:231], v190 src0_sel:WORD_1
	v_pk_fma_f32 v[216:217], v[224:225], v[26:27], v[216:217]
	v_pk_fma_f32 v[218:219], v[226:227], v[26:27], v[218:219]
	v_pk_fma_f32 v[220:221], v[228:229], v[26:27], v[220:221]
	v_pk_fma_f32 v[222:223], v[230:231], v[26:27], v[222:223]
	v_cvt_pk_f32_fp8_e32 v[224:225], v179
	v_cvt_pk_f32_fp8_e32 v[226:227], v183
	v_cvt_pk_f32_fp8_e32 v[228:229], v187
	v_cvt_pk_f32_fp8_e32 v[230:231], v191
	v_pk_fma_f32 v[216:217], v[224:225], v[28:29], v[216:217]
	v_pk_fma_f32 v[218:219], v[226:227], v[28:29], v[218:219]
	v_pk_fma_f32 v[220:221], v[228:229], v[28:29], v[220:221]
	v_pk_fma_f32 v[222:223], v[230:231], v[28:29], v[222:223]
	v_cvt_pk_f32_fp8_sdwa v[224:225], v179 src0_sel:WORD_1
	v_cvt_pk_f32_fp8_sdwa v[226:227], v183 src0_sel:WORD_1
	v_cvt_pk_f32_fp8_sdwa v[228:229], v187 src0_sel:WORD_1
	v_cvt_pk_f32_fp8_sdwa v[230:231], v191 src0_sel:WORD_1
	v_pk_fma_f32 v[216:217], v[224:225], v[30:31], v[216:217]
	v_pk_fma_f32 v[218:219], v[226:227], v[30:31], v[218:219]
	v_pk_fma_f32 v[220:221], v[228:229], v[30:31], v[220:221]
	v_pk_fma_f32 v[222:223], v[230:231], v[30:31], v[222:223]
	v_add_f32_e32 v204, v216, v217
	v_add_f32_e32 v205, v218, v219
	v_add_f32_e32 v206, v220, v221
	v_add_f32_e32 v207, v222, v223
	s_nop 0
	v_permlane32_swap_b32_e32 v192, v200
	v_permlane32_swap_b32_e32 v193, v201
	v_permlane32_swap_b32_e32 v194, v202
	v_permlane32_swap_b32_e32 v195, v203
	v_permlane32_swap_b32_e32 v196, v204
	v_permlane32_swap_b32_e32 v197, v205
	v_permlane32_swap_b32_e32 v198, v206
	v_permlane32_swap_b32_e32 v199, v207
	v_add_f32_e32 v192, v192, v200
	v_add_f32_e32 v193, v193, v201
	v_add_f32_e32 v194, v194, v202
	v_add_f32_e32 v195, v195, v203
	v_add_f32_e32 v196, v196, v204
	v_add_f32_e32 v197, v197, v205
	v_add_f32_e32 v198, v198, v206
	v_add_f32_e32 v199, v199, v207
	v_permlane16_swap_b32_e32 v192, v196
	v_permlane16_swap_b32_e32 v193, v197
	v_permlane16_swap_b32_e32 v194, v198
	v_permlane16_swap_b32_e32 v195, v199
	v_add_f32_e32 v192, v192, v196
	v_add_f32_e32 v193, v193, v197
	v_add_f32_e32 v194, v194, v198
	v_add_f32_e32 v195, v195, v199
	v_add_f32_dpp v216, v192, v192 row_ror:8 row_mask:0xf bank_mask:0xf
	v_add_f32_dpp v218, v194, v194 row_ror:8 row_mask:0xf bank_mask:0xf
	v_add_f32_dpp v216, v193, v193 row_ror:8 row_mask:0xf bank_mask:0xc
	v_add_f32_dpp v218, v195, v195 row_ror:8 row_mask:0xf bank_mask:0xc
	s_nop 1
	v_add_f32_dpp v220, v216, v216 row_half_mirror row_mask:0xf bank_mask:0xf
	v_add_f32_dpp v220, v218, v218 row_half_mirror row_mask:0xf bank_mask:0xa
	s_nop 1
	v_add_f32_dpp v220, v220, v220 quad_perm:[1,0,3,2] row_mask:0xf bank_mask:0xf
	s_nop 1
	v_add_f32_dpp v220, v220, v220 quad_perm:[2,3,0,1] row_mask:0xf bank_mask:0xf
	v_mul_f32_e32 v216, v252, v220
	v_fma_f32 v218, |v216|, s72, 1.0
	v_mul_f32_e32 v222, v216, v216
	v_rcp_f32_e32 v218, v218
	v_mul_f32_e32 v222, 0xbf38aa3b, v222
	v_exp_f32_e32 v222, v222
	v_fmamk_f32 v224, v218, 0x3f07dc22, v242
	v_fmaak_f32 v224, v218, v224, 0x3f35f0e3
	v_fmaak_f32 v224, v218, v224, 0xbe11a98e
	v_fmaak_f32 v224, v218, v224, 0x3e027906
	v_mul_f32_e32 v224, v218, v224
	v_mul_f32_e32 v224, v222, v224
	v_mul_f32_e32 v226, v216, v224
	v_fma_f32 v224, -v216, v224, v216
	v_cmp_gt_f32_e32 vcc, 0, v216
	s_nop 1
	v_cndmask_b32_e32 v224, v224, v226, vcc
	v_mul_f32_e32 v224, v249, v224
	v_mul_f32_e32 v224, v253, v224
	ds_write_b32 v211, v224 offset:4864
	v_add_u32_e32 v211, 64, v211
	v_add_u32_e32 v213, 64, v213
	ds_read_b32 v248, v211
	ds_read_b32 v249, v211 offset:4864
	s_add_i32 s21, s21, 4
	s_sub_i32 s90, s90, 1
	s_cmp_eq_u32 s90, 0
	s_cbranch_scc1 .LU_sw0
	s_branch .LU_t1_s0
.LU_t2_s0:
	s_cmp_ge_u32 s21, s20
	s_cbranch_scc1 .LU_done
	s_waitcnt lgkmcnt(0)
	v_add_u32_e32 v236, v232, v240
	v_add_u32_e32 v237, v233, v240
	v_add_u32_e32 v238, v234, v240
	v_add_u32_e32 v239, v235, v240
	v_lshrrev_b32_e32 v208, 8, v248
	global_load_dword v252, v208, s[8:9]
	global_load_dword v253, v208, s[52:53]
	global_load_dwordx4 v[176:179], v236, s[4:5]
	global_load_dwordx4 v[180:183], v237, s[4:5]
	global_load_dwordx4 v[184:187], v238, s[4:5]
	global_load_dwordx4 v[188:191], v239, s[4:5]
	ds_read_b128 v[232:235], v213 offset:64
	s_waitcnt vmcnt(14)
	v_cvt_pk_f32_fp8_e32 v[224:225], v128
	v_cvt_pk_f32_fp8_e32 v[226:227], v132
	v_cvt_pk_f32_fp8_e32 v[228:229], v136
	v_cvt_pk_f32_fp8_e32 v[230:231], v140
	v_pk_mul_f32 v[216:217], v[224:225], v[32:33]
	v_pk_mul_f32 v[218:219], v[226:227], v[32:33]
	v_pk_mul_f32 v[220:221], v[228:229], v[32:33]
	v_pk_mul_f32 v[222:223], v[230:231], v[32:33]
	v_cvt_pk_f32_fp8_sdwa v[224:225], v128 src0_sel:WORD_1
	v_cvt_pk_f32_fp8_sdwa v[226:227], v132 src0_sel:WORD_1
	v_cvt_pk_f32_fp8_sdwa v[228:229], v136 src0_sel:WORD_1
	v_cvt_pk_f32_fp8_sdwa v[230:231], v140 src0_sel:WORD_1
	v_pk_fma_f32 v[216:217], v[224:225], v[34:35], v[216:217]
	v_pk_fma_f32 v[218:219], v[226:227], v[34:35], v[218:219]
	v_pk_fma_f32 v[220:221], v[228:229], v[34:35], v[220:221]
	v_pk_fma_f32 v[222:223], v[230:231], v[34:35], v[222:223]
	v_cvt_pk_f32_fp8_e32 v[224:225], v129
	v_cvt_pk_f32_fp8_e32 v[226:227], v133
	v_cvt_pk_f32_fp8_e32 v[228:229], v137
	v_cvt_pk_f32_fp8_e32 v[230:231], v141
	v_pk_fma_f32 v[216:217], v[224:225], v[36:37], v[216:217]
	v_pk_fma_f32 v[218:219], v[226:227], v[36:37], v[218:219]
	v_pk_fma_f32 v[220:221], v[228:229], v[36:37], v[220:221]
	v_pk_fma_f32 v[222:223], v[230:231], v[36:37], v[222:223]
	v_cvt_pk_f32_fp8_sdwa v[224:225], v129 src0_sel:WORD_1
	v_cvt_pk_f32_fp8_sdwa v[226:227], v133 src0_sel:WORD_1
	v_cvt_pk_f32_fp8_sdwa v[228:229], v137 src0_sel:WORD_1
	v_cvt_pk_f32_fp8_sdwa v[230:231], v141 src0_sel:WORD_1
	v_pk_fma_f32 v[216:217], v[224:225], v[38:39], v[216:217]
	v_pk_fma_f32 v[218:219], v[226:227], v[38:39], v[218:219]
	v_pk_fma_f32 v[220:221], v[228:229], v[38:39], v[220:221]
	v_pk_fma_f32 v[222:223], v[230:231], v[38:39], v[222:223]
	v_cvt_pk_f32_fp8_e32 v[224:225], v130
	v_cvt_pk_f32_fp8_e32 v[226:227], v134
	v_cvt_pk_f32_fp8_e32 v[228:229], v138
	v_cvt_pk_f32_fp8_e32 v[230:231], v142
	v_pk_fma_f32 v[216:217], v[224:225], v[40:41], v[216:217]
	v_pk_fma_f32 v[218:219], v[226:227], v[40:41], v[218:219]
	v_pk_fma_f32 v[220:221], v[228:229], v[40:41], v[220:221]
	v_pk_fma_f32 v[222:223], v[230:231], v[40:41], v[222:223]
	v_cvt_pk_f32_fp8_sdwa v[224:225], v130 src0_sel:WORD_1
	v_cvt_pk_f32_fp8_sdwa v[226:227], v134 src0_sel:WORD_1
	v_cvt_pk_f32_fp8_sdwa v[228:229], v138 src0_sel:WORD_1
	v_cvt_pk_f32_fp8_sdwa v[230:231], v142 src0_sel:WORD_1
	v_pk_fma_f32 v[216:217], v[224:225], v[42:43], v[216:217]
	v_pk_fma_f32 v[218:219], v[226:227], v[42:43], v[218:219]
	v_pk_fma_f32 v[220:221], v[228:229], v[42:43], v[220:221]
	v_pk_fma_f32 v[222:223], v[230:231], v[42:43], v[222:223]
	v_cvt_pk_f32_fp8_e32 v[224:225], v131
	v_cvt_pk_f32_fp8_e32 v[226:227], v135
	v_cvt_pk_f32_fp8_e32 v[228:229], v139
	v_cvt_pk_f32_fp8_e32 v[230:231], v143
	v_pk_fma_f32 v[216:217], v[224:225], v[44:45], v[216:217]
	v_pk_fma_f32 v[218:219], v[226:227], v[44:45], v[218:219]
	v_pk_fma_f32 v[220:221], v[228:229], v[44:45], v[220:221]
	v_pk_fma_f32 v[222:223], v[230:231], v[44:45], v[222:223]
	v_cvt_pk_f32_fp8_sdwa v[224:225], v131 src0_sel:WORD_1
	v_cvt_pk_f32_fp8_sdwa v[226:227], v135 src0_sel:WORD_1
	v_cvt_pk_f32_fp8_sdwa v[228:229], v139 src0_sel:WORD_1
	v_cvt_pk_f32_fp8_sdwa v[230:231], v143 src0_sel:WORD_1
	v_pk_fma_f32 v[216:217], v[224:225], v[46:47], v[216:217]
	v_pk_fma_f32 v[218:219], v[226:227], v[46:47], v[218:219]
	v_pk_fma_f32 v[220:221], v[228:229], v[46:47], v[220:221]
	v_pk_fma_f32 v[222:223], v[230:231], v[46:47], v[222:223]
	v_add_f32_e32 v192, v216, v217
	v_add_f32_e32 v193, v218, v219
	v_add_f32_e32 v194, v220, v221
	v_add_f32_e32 v195, v222, v223
	s_sub_i32 s90, s90, 1
	s_cmp_eq_u32 s90, 0
	s_cbranch_scc1 .LU_sw1
.LU_t2_s1:
	s_waitcnt lgkmcnt(0)
	v_add_u32_e32 v236, v232, v240
	v_add_u32_e32 v237, v233, v240
	v_add_u32_e32 v238, v234, v240
	v_add_u32_e32 v239, v235, v240
	global_load_dwordx4 v[128:131], v236, s[4:5]
	global_load_dwordx4 v[132:135], v237, s[4:5]
	global_load_dwordx4 v[136:139], v238, s[4:5]
	global_load_dwordx4 v[140:143], v239, s[4:5]
	ds_read_b128 v[232:235], v213 offset:80
	s_waitcnt vmcnt(14)
	v_cvt_pk_f32_fp8_e32 v[224:225], v144
	v_cvt_pk_f32_fp8_e32 v[226:227], v148
	v_cvt_pk_f32_fp8_e32 v[228:229], v152
	v_cvt_pk_f32_fp8_e32 v[230:231], v156
	v_pk_mul_f32 v[216:217], v[224:225], v[32:33]
	v_pk_mul_f32 v[218:219], v[226:227], v[32:33]
	v_pk_mul_f32 v[220:221], v[228:229], v[32:33]
	v_pk_mul_f32 v[222:223], v[230:231], v[32:33]
	v_cvt_pk_f32_fp8_sdwa v[224:225], v144 src0_sel:WORD_1
	v_cvt_pk_f32_fp8_sdwa v[226:227], v148 src0_sel:WORD_1
	v_cvt_pk_f32_fp8_sdwa v[228:229], v152 src0_sel:WORD_1
	v_cvt_pk_f32_fp8_sdwa v[230:231], v156 src0_sel:WORD_1
	v_pk_fma_f32 v[216:217], v[224:225], v[34:35], v[216:217]
	v_pk_fma_f32 v[218:219], v[226:227], v[34:35], v[218:219]
	v_pk_fma_f32 v[220:221], v[228:229], v[34:35], v[220:221]
	v_pk_fma_f32 v[222:223], v[230:231], v[34:35], v[222:223]
	v_cvt_pk_f32_fp8_e32 v[224:225], v145
	v_cvt_pk_f32_fp8_e32 v[226:227], v149
	v_cvt_pk_f32_fp8_e32 v[228:229], v153
	v_cvt_pk_f32_fp8_e32 v[230:231], v157
	v_pk_fma_f32 v[216:217], v[224:225], v[36:37], v[216:217]
	v_pk_fma_f32 v[218:219], v[226:227], v[36:37], v[218:219]
	v_pk_fma_f32 v[220:221], v[228:229], v[36:37], v[220:221]
	v_pk_fma_f32 v[222:223], v[230:231], v[36:37], v[222:223]
	v_cvt_pk_f32_fp8_sdwa v[224:225], v145 src0_sel:WORD_1
	v_cvt_pk_f32_fp8_sdwa v[226:227], v149 src0_sel:WORD_1
	v_cvt_pk_f32_fp8_sdwa v[228:229], v153 src0_sel:WORD_1
	v_cvt_pk_f32_fp8_sdwa v[230:231], v157 src0_sel:WORD_1
	v_pk_fma_f32 v[216:217], v[224:225], v[38:39], v[216:217]
	v_pk_fma_f32 v[218:219], v[226:227], v[38:39], v[218:219]
	v_pk_fma_f32 v[220:221], v[228:229], v[38:39], v[220:221]
	v_pk_fma_f32 v[222:223], v[230:231], v[38:39], v[222:223]
	v_cvt_pk_f32_fp8_e32 v[224:225], v146
	v_cvt_pk_f32_fp8_e32 v[226:227], v150
	v_cvt_pk_f32_fp8_e32 v[228:229], v154
	v_cvt_pk_f32_fp8_e32 v[230:231], v158
	v_pk_fma_f32 v[216:217], v[224:225], v[40:41], v[216:217]
	v_pk_fma_f32 v[218:219], v[226:227], v[40:41], v[218:219]
	v_pk_fma_f32 v[220:221], v[228:229], v[40:41], v[220:221]
	v_pk_fma_f32 v[222:223], v[230:231], v[40:41], v[222:223]
	v_cvt_pk_f32_fp8_sdwa v[224:225], v146 src0_sel:WORD_1
	v_cvt_pk_f32_fp8_sdwa v[226:227], v150 src0_sel:WORD_1
	v_cvt_pk_f32_fp8_sdwa v[228:229], v154 src0_sel:WORD_1
	v_cvt_pk_f32_fp8_sdwa v[230:231], v158 src0_sel:WORD_1
	v_pk_fma_f32 v[216:217], v[224:225], v[42:43], v[216:217]
	v_pk_fma_f32 v[218:219], v[226:227], v[42:43], v[218:219]
	v_pk_fma_f32 v[220:221], v[228:229], v[42:43], v[220:221]
	v_pk_fma_f32 v[222:223], v[230:231], v[42:43], v[222:223]
	v_cvt_pk_f32_fp8_e32 v[224:225], v147
	v_cvt_pk_f32_fp8_e32 v[226:227], v151
	v_cvt_pk_f32_fp8_e32 v[228:229], v155
	v_cvt_pk_f32_fp8_e32 v[230:231], v159
	v_pk_fma_f32 v[216:217], v[224:225], v[44:45], v[216:217]
	v_pk_fma_f32 v[218:219], v[226:227], v[44:45], v[218:219]
	v_pk_fma_f32 v[220:221], v[228:229], v[44:45], v[220:221]
	v_pk_fma_f32 v[222:223], v[230:231], v[44:45], v[222:223]
	v_cvt_pk_f32_fp8_sdwa v[224:225], v147 src0_sel:WORD_1
	v_cvt_pk_f32_fp8_sdwa v[226:227], v151 src0_sel:WORD_1
	v_cvt_pk_f32_fp8_sdwa v[228:229], v155 src0_sel:WORD_1
	v_cvt_pk_f32_fp8_sdwa v[230:231], v159 src0_sel:WORD_1
	v_pk_fma_f32 v[216:217], v[224:225], v[46:47], v[216:217]
	v_pk_fma_f32 v[218:219], v[226:227], v[46:47], v[218:219]
	v_pk_fma_f32 v[220:221], v[228:229], v[46:47], v[220:221]
	v_pk_fma_f32 v[222:223], v[230:231], v[46:47], v[222:223]
	v_add_f32_e32 v196, v216, v217
	v_add_f32_e32 v197, v218, v219
	v_add_f32_e32 v198, v220, v221
	v_add_f32_e32 v199, v222, v223
	s_sub_i32 s90, s90, 1
	s_cmp_eq_u32 s90, 0
	s_cbranch_scc1 .LU_sw2
.LU_t2_s2:
	s_waitcnt lgkmcnt(0)
	v_add_u32_e32 v236, v232, v240
	v_add_u32_e32 v237, v233, v240
	v_add_u32_e32 v238, v234, v240
	v_add_u32_e32 v239, v235, v240
	global_load_dwordx4 v[144:147], v236, s[4:5]
	global_load_dwordx4 v[148:151], v237, s[4:5]
	global_load_dwordx4 v[152:155], v238, s[4:5]
	global_load_dwordx4 v[156:159], v239, s[4:5]
	ds_read_b128 v[232:235], v213 offset:96
	s_waitcnt vmcnt(14)
	v_cvt_pk_f32_fp8_e32 v[224:225], v160
	v_cvt_pk_f32_fp8_e32 v[226:227], v164
	v_cvt_pk_f32_fp8_e32 v[228:229], v168
	v_cvt_pk_f32_fp8_e32 v[230:231], v172
	v_pk_mul_f32 v[216:217], v[224:225], v[32:33]
	v_pk_mul_f32 v[218:219], v[226:227], v[32:33]
	v_pk_mul_f32 v[220:221], v[228:229], v[32:33]
	v_pk_mul_f32 v[222:223], v[230:231], v[32:33]
	v_cvt_pk_f32_fp8_sdwa v[224:225], v160 src0_sel:WORD_1
	v_cvt_pk_f32_fp8_sdwa v[226:227], v164 src0_sel:WORD_1
	v_cvt_pk_f32_fp8_sdwa v[228:229], v168 src0_sel:WORD_1
	v_cvt_pk_f32_fp8_sdwa v[230:231], v172 src0_sel:WORD_1
	v_pk_fma_f32 v[216:217], v[224:225], v[34:35], v[216:217]
	v_pk_fma_f32 v[218:219], v[226:227], v[34:35], v[218:219]
	v_pk_fma_f32 v[220:221], v[228:229], v[34:35], v[220:221]
	v_pk_fma_f32 v[222:223], v[230:231], v[34:35], v[222:223]
	v_cvt_pk_f32_fp8_e32 v[224:225], v161
	v_cvt_pk_f32_fp8_e32 v[226:227], v165
	v_cvt_pk_f32_fp8_e32 v[228:229], v169
	v_cvt_pk_f32_fp8_e32 v[230:231], v173
	v_pk_fma_f32 v[216:217], v[224:225], v[36:37], v[216:217]
	v_pk_fma_f32 v[218:219], v[226:227], v[36:37], v[218:219]
	v_pk_fma_f32 v[220:221], v[228:229], v[36:37], v[220:221]
	v_pk_fma_f32 v[222:223], v[230:231], v[36:37], v[222:223]
	v_cvt_pk_f32_fp8_sdwa v[224:225], v161 src0_sel:WORD_1
	v_cvt_pk_f32_fp8_sdwa v[226:227], v165 src0_sel:WORD_1
	v_cvt_pk_f32_fp8_sdwa v[228:229], v169 src0_sel:WORD_1
	v_cvt_pk_f32_fp8_sdwa v[230:231], v173 src0_sel:WORD_1
	v_pk_fma_f32 v[216:217], v[224:225], v[38:39], v[216:217]
	v_pk_fma_f32 v[218:219], v[226:227], v[38:39], v[218:219]
	v_pk_fma_f32 v[220:221], v[228:229], v[38:39], v[220:221]
	v_pk_fma_f32 v[222:223], v[230:231], v[38:39], v[222:223]
	v_cvt_pk_f32_fp8_e32 v[224:225], v162
	v_cvt_pk_f32_fp8_e32 v[226:227], v166
	v_cvt_pk_f32_fp8_e32 v[228:229], v170
	v_cvt_pk_f32_fp8_e32 v[230:231], v174
	v_pk_fma_f32 v[216:217], v[224:225], v[40:41], v[216:217]
	v_pk_fma_f32 v[218:219], v[226:227], v[40:41], v[218:219]
	v_pk_fma_f32 v[220:221], v[228:229], v[40:41], v[220:221]
	v_pk_fma_f32 v[222:223], v[230:231], v[40:41], v[222:223]
	v_cvt_pk_f32_fp8_sdwa v[224:225], v162 src0_sel:WORD_1
	v_cvt_pk_f32_fp8_sdwa v[226:227], v166 src0_sel:WORD_1
	v_cvt_pk_f32_fp8_sdwa v[228:229], v170 src0_sel:WORD_1
	v_cvt_pk_f32_fp8_sdwa v[230:231], v174 src0_sel:WORD_1
	v_pk_fma_f32 v[216:217], v[224:225], v[42:43], v[216:217]
	v_pk_fma_f32 v[218:219], v[226:227], v[42:43], v[218:219]
	v_pk_fma_f32 v[220:221], v[228:229], v[42:43], v[220:221]
	v_pk_fma_f32 v[222:223], v[230:231], v[42:43], v[222:223]
	v_cvt_pk_f32_fp8_e32 v[224:225], v163
	v_cvt_pk_f32_fp8_e32 v[226:227], v167
	v_cvt_pk_f32_fp8_e32 v[228:229], v171
	v_cvt_pk_f32_fp8_e32 v[230:231], v175
	v_pk_fma_f32 v[216:217], v[224:225], v[44:45], v[216:217]
	v_pk_fma_f32 v[218:219], v[226:227], v[44:45], v[218:219]
	v_pk_fma_f32 v[220:221], v[228:229], v[44:45], v[220:221]
	v_pk_fma_f32 v[222:223], v[230:231], v[44:45], v[222:223]
	v_cvt_pk_f32_fp8_sdwa v[224:225], v163 src0_sel:WORD_1
	v_cvt_pk_f32_fp8_sdwa v[226:227], v167 src0_sel:WORD_1
	v_cvt_pk_f32_fp8_sdwa v[228:229], v171 src0_sel:WORD_1
	v_cvt_pk_f32_fp8_sdwa v[230:231], v175 src0_sel:WORD_1
	v_pk_fma_f32 v[216:217], v[224:225], v[46:47], v[216:217]
	v_pk_fma_f32 v[218:219], v[226:227], v[46:47], v[218:219]
	v_pk_fma_f32 v[220:221], v[228:229], v[46:47], v[220:221]
	v_pk_fma_f32 v[222:223], v[230:231], v[46:47], v[222:223]
	v_add_f32_e32 v200, v216, v217
	v_add_f32_e32 v201, v218, v219
	v_add_f32_e32 v202, v220, v221
	v_add_f32_e32 v203, v222, v223
	s_sub_i32 s90, s90, 1
	s_cmp_eq_u32 s90, 0
	s_cbranch_scc1 .LU_sw3
.LU_t2_s3:
	s_waitcnt lgkmcnt(0)
	v_add_u32_e32 v236, v232, v240
	v_add_u32_e32 v237, v233, v240
	v_add_u32_e32 v238, v234, v240
	v_add_u32_e32 v239, v235, v240
	global_load_dwordx4 v[160:163], v236, s[4:5]
	global_load_dwordx4 v[164:167], v237, s[4:5]
	global_load_dwordx4 v[168:171], v238, s[4:5]
	global_load_dwordx4 v[172:175], v239, s[4:5]
	ds_read_b128 v[232:235], v213 offset:112
	s_waitcnt vmcnt(12)
	v_cvt_pk_f32_fp8_e32 v[224:225], v176
	v_cvt_pk_f32_fp8_e32 v[226:227], v180
	v_cvt_pk_f32_fp8_e32 v[228:229], v184
	v_cvt_pk_f32_fp8_e32 v[230:231], v188
	v_pk_mul_f32 v[216:217], v[224:225], v[32:33]
	v_pk_mul_f32 v[218:219], v[226:227], v[32:33]
	v_pk_mul_f32 v[220:221], v[228:229], v[32:33]
	v_pk_mul_f32 v[222:223], v[230:231], v[32:33]
	v_cvt_pk_f32_fp8_sdwa v[224:225], v176 src0_sel:WORD_1
	v_cvt_pk_f32_fp8_sdwa v[226:227], v180 src0_sel:WORD_1
	v_cvt_pk_f32_fp8_sdwa v[228:229], v184 src0_sel:WORD_1
	v_cvt_pk_f32_fp8_sdwa v[230:231], v188 src0_sel:WORD_1
	v_pk_fma_f32 v[216:217], v[224:225], v[34:35], v[216:217]
	v_pk_fma_f32 v[218:219], v[226:227], v[34:35], v[218:219]
	v_pk_fma_f32 v[220:221], v[228:229], v[34:35], v[220:221]
	v_pk_fma_f32 v[222:223], v[230:231], v[34:35], v[222:223]
	v_cvt_pk_f32_fp8_e32 v[224:225], v177
	v_cvt_pk_f32_fp8_e32 v[226:227], v181
	v_cvt_pk_f32_fp8_e32 v[228:229], v185
	v_cvt_pk_f32_fp8_e32 v[230:231], v189
	v_pk_fma_f32 v[216:217], v[224:225], v[36:37], v[216:217]
	v_pk_fma_f32 v[218:219], v[226:227], v[36:37], v[218:219]
	v_pk_fma_f32 v[220:221], v[228:229], v[36:37], v[220:221]
	v_pk_fma_f32 v[222:223], v[230:231], v[36:37], v[222:223]
	v_cvt_pk_f32_fp8_sdwa v[224:225], v177 src0_sel:WORD_1
	v_cvt_pk_f32_fp8_sdwa v[226:227], v181 src0_sel:WORD_1
	v_cvt_pk_f32_fp8_sdwa v[228:229], v185 src0_sel:WORD_1
	v_cvt_pk_f32_fp8_sdwa v[230:231], v189 src0_sel:WORD_1
	v_pk_fma_f32 v[216:217], v[224:225], v[38:39], v[216:217]
	v_pk_fma_f32 v[218:219], v[226:227], v[38:39], v[218:219]
	v_pk_fma_f32 v[220:221], v[228:229], v[38:39], v[220:221]
	v_pk_fma_f32 v[222:223], v[230:231], v[38:39], v[222:223]
	v_cvt_pk_f32_fp8_e32 v[224:225], v178
	v_cvt_pk_f32_fp8_e32 v[226:227], v182
	v_cvt_pk_f32_fp8_e32 v[228:229], v186
	v_cvt_pk_f32_fp8_e32 v[230:231], v190
	v_pk_fma_f32 v[216:217], v[224:225], v[40:41], v[216:217]
	v_pk_fma_f32 v[218:219], v[226:227], v[40:41], v[218:219]
	v_pk_fma_f32 v[220:221], v[228:229], v[40:41], v[220:221]
	v_pk_fma_f32 v[222:223], v[230:231], v[40:41], v[222:223]
	v_cvt_pk_f32_fp8_sdwa v[224:225], v178 src0_sel:WORD_1
	v_cvt_pk_f32_fp8_sdwa v[226:227], v182 src0_sel:WORD_1
	v_cvt_pk_f32_fp8_sdwa v[228:229], v186 src0_sel:WORD_1
	v_cvt_pk_f32_fp8_sdwa v[230:231], v190 src0_sel:WORD_1
	v_pk_fma_f32 v[216:217], v[224:225], v[42:43], v[216:217]
	v_pk_fma_f32 v[218:219], v[226:227], v[42:43], v[218:219]
	v_pk_fma_f32 v[220:221], v[228:229], v[42:43], v[220:221]
	v_pk_fma_f32 v[222:223], v[230:231], v[42:43], v[222:223]
	v_cvt_pk_f32_fp8_e32 v[224:225], v179
	v_cvt_pk_f32_fp8_e32 v[226:227], v183
	v_cvt_pk_f32_fp8_e32 v[228:229], v187
	v_cvt_pk_f32_fp8_e32 v[230:231], v191
	v_pk_fma_f32 v[216:217], v[224:225], v[44:45], v[216:217]
	v_pk_fma_f32 v[218:219], v[226:227], v[44:45], v[218:219]
	v_pk_fma_f32 v[220:221], v[228:229], v[44:45], v[220:221]
	v_pk_fma_f32 v[222:223], v[230:231], v[44:45], v[222:223]
	v_cvt_pk_f32_fp8_sdwa v[224:225], v179 src0_sel:WORD_1
	v_cvt_pk_f32_fp8_sdwa v[226:227], v183 src0_sel:WORD_1
	v_cvt_pk_f32_fp8_sdwa v[228:229], v187 src0_sel:WORD_1
	v_cvt_pk_f32_fp8_sdwa v[230:231], v191 src0_sel:WORD_1
	v_pk_fma_f32 v[216:217], v[224:225], v[46:47], v[216:217]
	v_pk_fma_f32 v[218:219], v[226:227], v[46:47], v[218:219]
	v_pk_fma_f32 v[220:221], v[228:229], v[46:47], v[220:221]
	v_pk_fma_f32 v[222:223], v[230:231], v[46:47], v[222:223]
	v_add_f32_e32 v204, v216, v217
	v_add_f32_e32 v205, v218, v219
	v_add_f32_e32 v206, v220, v221
	v_add_f32_e32 v207, v222, v223
	s_nop 0
	v_permlane32_swap_b32_e32 v192, v200
	v_permlane32_swap_b32_e32 v193, v201
	v_permlane32_swap_b32_e32 v194, v202
	v_permlane32_swap_b32_e32 v195, v203
	v_permlane32_swap_b32_e32 v196, v204
	v_permlane32_swap_b32_e32 v197, v205
	v_permlane32_swap_b32_e32 v198, v206
	v_permlane32_swap_b32_e32 v199, v207
	v_add_f32_e32 v192, v192, v200
	v_add_f32_e32 v193, v193, v201
	v_add_f32_e32 v194, v194, v202
	v_add_f32_e32 v195, v195, v203
	v_add_f32_e32 v196, v196, v204
	v_add_f32_e32 v197, v197, v205
	v_add_f32_e32 v198, v198, v206
	v_add_f32_e32 v199, v199, v207
	v_permlane16_swap_b32_e32 v192, v196
	v_permlane16_swap_b32_e32 v193, v197
	v_permlane16_swap_b32_e32 v194, v198
	v_permlane16_swap_b32_e32 v195, v199
	v_add_f32_e32 v192, v192, v196
	v_add_f32_e32 v193, v193, v197
	v_add_f32_e32 v194, v194, v198
	v_add_f32_e32 v195, v195, v199
	v_add_f32_dpp v216, v192, v192 row_ror:8 row_mask:0xf bank_mask:0xf
	v_add_f32_dpp v218, v194, v194 row_ror:8 row_mask:0xf bank_mask:0xf
	v_add_f32_dpp v216, v193, v193 row_ror:8 row_mask:0xf bank_mask:0xc
	v_add_f32_dpp v218, v195, v195 row_ror:8 row_mask:0xf bank_mask:0xc
	s_nop 1
	v_add_f32_dpp v220, v216, v216 row_half_mirror row_mask:0xf bank_mask:0xf
	v_add_f32_dpp v220, v218, v218 row_half_mirror row_mask:0xf bank_mask:0xa
	s_nop 1
	v_add_f32_dpp v220, v220, v220 quad_perm:[1,0,3,2] row_mask:0xf bank_mask:0xf
	s_nop 1
	v_add_f32_dpp v220, v220, v220 quad_perm:[2,3,0,1] row_mask:0xf bank_mask:0xf
	v_mul_f32_e32 v216, v252, v220
	v_fma_f32 v218, |v216|, s72, 1.0
	v_mul_f32_e32 v222, v216, v216
	v_rcp_f32_e32 v218, v218
	v_mul_f32_e32 v222, 0xbf38aa3b, v222
	v_exp_f32_e32 v222, v222
	v_fmamk_f32 v224, v218, 0x3f07dc22, v242
	v_fmaak_f32 v224, v218, v224, 0x3f35f0e3
	v_fmaak_f32 v224, v218, v224, 0xbe11a98e
	v_fmaak_f32 v224, v218, v224, 0x3e027906
	v_mul_f32_e32 v224, v218, v224
	v_mul_f32_e32 v224, v222, v224
	v_mul_f32_e32 v226, v216, v224
	v_fma_f32 v224, -v216, v224, v216
	v_cmp_gt_f32_e32 vcc, 0, v216
	s_nop 1
	v_cndmask_b32_e32 v224, v224, v226, vcc
	v_mul_f32_e32 v224, v249, v224
	v_mul_f32_e32 v224, v253, v224
	ds_write_b32 v211, v224 offset:4864
	v_add_u32_e32 v211, 64, v211
	v_add_u32_e32 v213, 64, v213
	ds_read_b32 v248, v211
	ds_read_b32 v249, v211 offset:4864
	s_add_i32 s21, s21, 4
	s_sub_i32 s90, s90, 1
	s_cmp_eq_u32 s90, 0
	s_cbranch_scc1 .LU_sw0
	s_branch .LU_t2_s0
.LU_t3_s0:
	s_cmp_ge_u32 s21, s20
	s_cbranch_scc1 .LU_done
	s_waitcnt lgkmcnt(0)
	v_add_u32_e32 v236, v232, v240
	v_add_u32_e32 v237, v233, v240
	v_add_u32_e32 v238, v234, v240
	v_add_u32_e32 v239, v235, v240
	v_lshrrev_b32_e32 v208, 8, v248
	global_load_dword v252, v208, s[8:9]
	global_load_dword v253, v208, s[52:53]
	global_load_dwordx4 v[176:179], v236, s[4:5]
	global_load_dwordx4 v[180:183], v237, s[4:5]
	global_load_dwordx4 v[184:187], v238, s[4:5]
	global_load_dwordx4 v[188:191], v239, s[4:5]
	ds_read_b128 v[232:235], v213 offset:64
	s_waitcnt vmcnt(14)
	v_cvt_pk_f32_fp8_e32 v[224:225], v128
	v_cvt_pk_f32_fp8_e32 v[226:227], v132
	v_cvt_pk_f32_fp8_e32 v[228:229], v136
	v_cvt_pk_f32_fp8_e32 v[230:231], v140
	v_pk_mul_f32 v[216:217], v[224:225], v[48:49]
	v_pk_mul_f32 v[218:219], v[226:227], v[48:49]
	v_pk_mul_f32 v[220:221], v[228:229], v[48:49]
	v_pk_mul_f32 v[222:223], v[230:231], v[48:49]
	v_cvt_pk_f32_fp8_sdwa v[224:225], v128 src0_sel:WORD_1
	v_cvt_pk_f32_fp8_sdwa v[226:227], v132 src0_sel:WORD_1
	v_cvt_pk_f32_fp8_sdwa v[228:229], v136 src0_sel:WORD_1
	v_cvt_pk_f32_fp8_sdwa v[230:231], v140 src0_sel:WORD_1
	v_pk_fma_f32 v[216:217], v[224:225], v[50:51], v[216:217]
	v_pk_fma_f32 v[218:219], v[226:227], v[50:51], v[218:219]
	v_pk_fma_f32 v[220:221], v[228:229], v[50:51], v[220:221]
	v_pk_fma_f32 v[222:223], v[230:231], v[50:51], v[222:223]
	v_cvt_pk_f32_fp8_e32 v[224:225], v129
	v_cvt_pk_f32_fp8_e32 v[226:227], v133
	v_cvt_pk_f32_fp8_e32 v[228:229], v137
	v_cvt_pk_f32_fp8_e32 v[230:231], v141
	v_pk_fma_f32 v[216:217], v[224:225], v[52:53], v[216:217]
	v_pk_fma_f32 v[218:219], v[226:227], v[52:53], v[218:219]
	v_pk_fma_f32 v[220:221], v[228:229], v[52:53], v[220:221]
	v_pk_fma_f32 v[222:223], v[230:231], v[52:53], v[222:223]
	v_cvt_pk_f32_fp8_sdwa v[224:225], v129 src0_sel:WORD_1
	v_cvt_pk_f32_fp8_sdwa v[226:227], v133 src0_sel:WORD_1
	v_cvt_pk_f32_fp8_sdwa v[228:229], v137 src0_sel:WORD_1
	v_cvt_pk_f32_fp8_sdwa v[230:231], v141 src0_sel:WORD_1
	v_pk_fma_f32 v[216:217], v[224:225], v[54:55], v[216:217]
	v_pk_fma_f32 v[218:219], v[226:227], v[54:55], v[218:219]
	v_pk_fma_f32 v[220:221], v[228:229], v[54:55], v[220:221]
	v_pk_fma_f32 v[222:223], v[230:231], v[54:55], v[222:223]
	v_cvt_pk_f32_fp8_e32 v[224:225], v130
	v_cvt_pk_f32_fp8_e32 v[226:227], v134
	v_cvt_pk_f32_fp8_e32 v[228:229], v138
	v_cvt_pk_f32_fp8_e32 v[230:231], v142
	v_pk_fma_f32 v[216:217], v[224:225], v[56:57], v[216:217]
	v_pk_fma_f32 v[218:219], v[226:227], v[56:57], v[218:219]
	v_pk_fma_f32 v[220:221], v[228:229], v[56:57], v[220:221]
	v_pk_fma_f32 v[222:223], v[230:231], v[56:57], v[222:223]
	v_cvt_pk_f32_fp8_sdwa v[224:225], v130 src0_sel:WORD_1
	v_cvt_pk_f32_fp8_sdwa v[226:227], v134 src0_sel:WORD_1
	v_cvt_pk_f32_fp8_sdwa v[228:229], v138 src0_sel:WORD_1
	v_cvt_pk_f32_fp8_sdwa v[230:231], v142 src0_sel:WORD_1
	v_pk_fma_f32 v[216:217], v[224:225], v[58:59], v[216:217]
	v_pk_fma_f32 v[218:219], v[226:227], v[58:59], v[218:219]
	v_pk_fma_f32 v[220:221], v[228:229], v[58:59], v[220:221]
	v_pk_fma_f32 v[222:223], v[230:231], v[58:59], v[222:223]
	v_cvt_pk_f32_fp8_e32 v[224:225], v131
	v_cvt_pk_f32_fp8_e32 v[226:227], v135
	v_cvt_pk_f32_fp8_e32 v[228:229], v139
	v_cvt_pk_f32_fp8_e32 v[230:231], v143
	v_pk_fma_f32 v[216:217], v[224:225], v[60:61], v[216:217]
	v_pk_fma_f32 v[218:219], v[226:227], v[60:61], v[218:219]
	v_pk_fma_f32 v[220:221], v[228:229], v[60:61], v[220:221]
	v_pk_fma_f32 v[222:223], v[230:231], v[60:61], v[222:223]
	v_cvt_pk_f32_fp8_sdwa v[224:225], v131 src0_sel:WORD_1
	v_cvt_pk_f32_fp8_sdwa v[226:227], v135 src0_sel:WORD_1
	v_cvt_pk_f32_fp8_sdwa v[228:229], v139 src0_sel:WORD_1
	v_cvt_pk_f32_fp8_sdwa v[230:231], v143 src0_sel:WORD_1
	v_pk_fma_f32 v[216:217], v[224:225], v[62:63], v[216:217]
	v_pk_fma_f32 v[218:219], v[226:227], v[62:63], v[218:219]
	v_pk_fma_f32 v[220:221], v[228:229], v[62:63], v[220:221]
	v_pk_fma_f32 v[222:223], v[230:231], v[62:63], v[222:223]
	v_add_f32_e32 v192, v216, v217
	v_add_f32_e32 v193, v218, v219
	v_add_f32_e32 v194, v220, v221
	v_add_f32_e32 v195, v222, v223
	s_sub_i32 s90, s90, 1
	s_cmp_eq_u32 s90, 0
	s_cbranch_scc1 .LU_sw1
.LU_t3_s1:
	s_waitcnt lgkmcnt(0)
	v_add_u32_e32 v236, v232, v240
	v_add_u32_e32 v237, v233, v240
	v_add_u32_e32 v238, v234, v240
	v_add_u32_e32 v239, v235, v240
	global_load_dwordx4 v[128:131], v236, s[4:5]
	global_load_dwordx4 v[132:135], v237, s[4:5]
	global_load_dwordx4 v[136:139], v238, s[4:5]
	global_load_dwordx4 v[140:143], v239, s[4:5]
	ds_read_b128 v[232:235], v213 offset:80
	s_waitcnt vmcnt(14)
	v_cvt_pk_f32_fp8_e32 v[224:225], v144
	v_cvt_pk_f32_fp8_e32 v[226:227], v148
	v_cvt_pk_f32_fp8_e32 v[228:229], v152
	v_cvt_pk_f32_fp8_e32 v[230:231], v156
	v_pk_mul_f32 v[216:217], v[224:225], v[48:49]
	v_pk_mul_f32 v[218:219], v[226:227], v[48:49]
	v_pk_mul_f32 v[220:221], v[228:229], v[48:49]
	v_pk_mul_f32 v[222:223], v[230:231], v[48:49]
	v_cvt_pk_f32_fp8_sdwa v[224:225], v144 src0_sel:WORD_1
	v_cvt_pk_f32_fp8_sdwa v[226:227], v148 src0_sel:WORD_1
	v_cvt_pk_f32_fp8_sdwa v[228:229], v152 src0_sel:WORD_1
	v_cvt_pk_f32_fp8_sdwa v[230:231], v156 src0_sel:WORD_1
	v_pk_fma_f32 v[216:217], v[224:225], v[50:51], v[216:217]
	v_pk_fma_f32 v[218:219], v[226:227], v[50:51], v[218:219]
	v_pk_fma_f32 v[220:221], v[228:229], v[50:51], v[220:221]
	v_pk_fma_f32 v[222:223], v[230:231], v[50:51], v[222:223]
	v_cvt_pk_f32_fp8_e32 v[224:225], v145
	v_cvt_pk_f32_fp8_e32 v[226:227], v149
	v_cvt_pk_f32_fp8_e32 v[228:229], v153
	v_cvt_pk_f32_fp8_e32 v[230:231], v157
	v_pk_fma_f32 v[216:217], v[224:225], v[52:53], v[216:217]
	v_pk_fma_f32 v[218:219], v[226:227], v[52:53], v[218:219]
	v_pk_fma_f32 v[220:221], v[228:229], v[52:53], v[220:221]
	v_pk_fma_f32 v[222:223], v[230:231], v[52:53], v[222:223]
	v_cvt_pk_f32_fp8_sdwa v[224:225], v145 src0_sel:WORD_1
	v_cvt_pk_f32_fp8_sdwa v[226:227], v149 src0_sel:WORD_1
	v_cvt_pk_f32_fp8_sdwa v[228:229], v153 src0_sel:WORD_1
	v_cvt_pk_f32_fp8_sdwa v[230:231], v157 src0_sel:WORD_1
	v_pk_fma_f32 v[216:217], v[224:225], v[54:55], v[216:217]
	v_pk_fma_f32 v[218:219], v[226:227], v[54:55], v[218:219]
	v_pk_fma_f32 v[220:221], v[228:229], v[54:55], v[220:221]
	v_pk_fma_f32 v[222:223], v[230:231], v[54:55], v[222:223]
	v_cvt_pk_f32_fp8_e32 v[224:225], v146
	v_cvt_pk_f32_fp8_e32 v[226:227], v150
	v_cvt_pk_f32_fp8_e32 v[228:229], v154
	v_cvt_pk_f32_fp8_e32 v[230:231], v158
	v_pk_fma_f32 v[216:217], v[224:225], v[56:57], v[216:217]
	v_pk_fma_f32 v[218:219], v[226:227], v[56:57], v[218:219]
	v_pk_fma_f32 v[220:221], v[228:229], v[56:57], v[220:221]
	v_pk_fma_f32 v[222:223], v[230:231], v[56:57], v[222:223]
	v_cvt_pk_f32_fp8_sdwa v[224:225], v146 src0_sel:WORD_1
	v_cvt_pk_f32_fp8_sdwa v[226:227], v150 src0_sel:WORD_1
	v_cvt_pk_f32_fp8_sdwa v[228:229], v154 src0_sel:WORD_1
	v_cvt_pk_f32_fp8_sdwa v[230:231], v158 src0_sel:WORD_1
	v_pk_fma_f32 v[216:217], v[224:225], v[58:59], v[216:217]
	v_pk_fma_f32 v[218:219], v[226:227], v[58:59], v[218:219]
	v_pk_fma_f32 v[220:221], v[228:229], v[58:59], v[220:221]
	v_pk_fma_f32 v[222:223], v[230:231], v[58:59], v[222:223]
	v_cvt_pk_f32_fp8_e32 v[224:225], v147
	v_cvt_pk_f32_fp8_e32 v[226:227], v151
	v_cvt_pk_f32_fp8_e32 v[228:229], v155
	v_cvt_pk_f32_fp8_e32 v[230:231], v159
	v_pk_fma_f32 v[216:217], v[224:225], v[60:61], v[216:217]
	v_pk_fma_f32 v[218:219], v[226:227], v[60:61], v[218:219]
	v_pk_fma_f32 v[220:221], v[228:229], v[60:61], v[220:221]
	v_pk_fma_f32 v[222:223], v[230:231], v[60:61], v[222:223]
	v_cvt_pk_f32_fp8_sdwa v[224:225], v147 src0_sel:WORD_1
	v_cvt_pk_f32_fp8_sdwa v[226:227], v151 src0_sel:WORD_1
	v_cvt_pk_f32_fp8_sdwa v[228:229], v155 src0_sel:WORD_1
	v_cvt_pk_f32_fp8_sdwa v[230:231], v159 src0_sel:WORD_1
	v_pk_fma_f32 v[216:217], v[224:225], v[62:63], v[216:217]
	v_pk_fma_f32 v[218:219], v[226:227], v[62:63], v[218:219]
	v_pk_fma_f32 v[220:221], v[228:229], v[62:63], v[220:221]
	v_pk_fma_f32 v[222:223], v[230:231], v[62:63], v[222:223]
	v_add_f32_e32 v196, v216, v217
	v_add_f32_e32 v197, v218, v219
	v_add_f32_e32 v198, v220, v221
	v_add_f32_e32 v199, v222, v223
	s_sub_i32 s90, s90, 1
	s_cmp_eq_u32 s90, 0
	s_cbranch_scc1 .LU_sw2
.LU_t3_s2:
	s_waitcnt lgkmcnt(0)
	v_add_u32_e32 v236, v232, v240
	v_add_u32_e32 v237, v233, v240
	v_add_u32_e32 v238, v234, v240
	v_add_u32_e32 v239, v235, v240
	global_load_dwordx4 v[144:147], v236, s[4:5]
	global_load_dwordx4 v[148:151], v237, s[4:5]
	global_load_dwordx4 v[152:155], v238, s[4:5]
	global_load_dwordx4 v[156:159], v239, s[4:5]
	ds_read_b128 v[232:235], v213 offset:96
	s_waitcnt vmcnt(14)
	v_cvt_pk_f32_fp8_e32 v[224:225], v160
	v_cvt_pk_f32_fp8_e32 v[226:227], v164
	v_cvt_pk_f32_fp8_e32 v[228:229], v168
	v_cvt_pk_f32_fp8_e32 v[230:231], v172
	v_pk_mul_f32 v[216:217], v[224:225], v[48:49]
	v_pk_mul_f32 v[218:219], v[226:227], v[48:49]
	v_pk_mul_f32 v[220:221], v[228:229], v[48:49]
	v_pk_mul_f32 v[222:223], v[230:231], v[48:49]
	v_cvt_pk_f32_fp8_sdwa v[224:225], v160 src0_sel:WORD_1
	v_cvt_pk_f32_fp8_sdwa v[226:227], v164 src0_sel:WORD_1
	v_cvt_pk_f32_fp8_sdwa v[228:229], v168 src0_sel:WORD_1
	v_cvt_pk_f32_fp8_sdwa v[230:231], v172 src0_sel:WORD_1
	v_pk_fma_f32 v[216:217], v[224:225], v[50:51], v[216:217]
	v_pk_fma_f32 v[218:219], v[226:227], v[50:51], v[218:219]
	v_pk_fma_f32 v[220:221], v[228:229], v[50:51], v[220:221]
	v_pk_fma_f32 v[222:223], v[230:231], v[50:51], v[222:223]
	v_cvt_pk_f32_fp8_e32 v[224:225], v161
	v_cvt_pk_f32_fp8_e32 v[226:227], v165
	v_cvt_pk_f32_fp8_e32 v[228:229], v169
	v_cvt_pk_f32_fp8_e32 v[230:231], v173
	v_pk_fma_f32 v[216:217], v[224:225], v[52:53], v[216:217]
	v_pk_fma_f32 v[218:219], v[226:227], v[52:53], v[218:219]
	v_pk_fma_f32 v[220:221], v[228:229], v[52:53], v[220:221]
	v_pk_fma_f32 v[222:223], v[230:231], v[52:53], v[222:223]
	v_cvt_pk_f32_fp8_sdwa v[224:225], v161 src0_sel:WORD_1
	v_cvt_pk_f32_fp8_sdwa v[226:227], v165 src0_sel:WORD_1
	v_cvt_pk_f32_fp8_sdwa v[228:229], v169 src0_sel:WORD_1
	v_cvt_pk_f32_fp8_sdwa v[230:231], v173 src0_sel:WORD_1
	v_pk_fma_f32 v[216:217], v[224:225], v[54:55], v[216:217]
	v_pk_fma_f32 v[218:219], v[226:227], v[54:55], v[218:219]
	v_pk_fma_f32 v[220:221], v[228:229], v[54:55], v[220:221]
	v_pk_fma_f32 v[222:223], v[230:231], v[54:55], v[222:223]
	v_cvt_pk_f32_fp8_e32 v[224:225], v162
	v_cvt_pk_f32_fp8_e32 v[226:227], v166
	v_cvt_pk_f32_fp8_e32 v[228:229], v170
	v_cvt_pk_f32_fp8_e32 v[230:231], v174
	v_pk_fma_f32 v[216:217], v[224:225], v[56:57], v[216:217]
	v_pk_fma_f32 v[218:219], v[226:227], v[56:57], v[218:219]
	v_pk_fma_f32 v[220:221], v[228:229], v[56:57], v[220:221]
	v_pk_fma_f32 v[222:223], v[230:231], v[56:57], v[222:223]
	v_cvt_pk_f32_fp8_sdwa v[224:225], v162 src0_sel:WORD_1
	v_cvt_pk_f32_fp8_sdwa v[226:227], v166 src0_sel:WORD_1
	v_cvt_pk_f32_fp8_sdwa v[228:229], v170 src0_sel:WORD_1
	v_cvt_pk_f32_fp8_sdwa v[230:231], v174 src0_sel:WORD_1
	v_pk_fma_f32 v[216:217], v[224:225], v[58:59], v[216:217]
	v_pk_fma_f32 v[218:219], v[226:227], v[58:59], v[218:219]
	v_pk_fma_f32 v[220:221], v[228:229], v[58:59], v[220:221]
	v_pk_fma_f32 v[222:223], v[230:231], v[58:59], v[222:223]
	v_cvt_pk_f32_fp8_e32 v[224:225], v163
	v_cvt_pk_f32_fp8_e32 v[226:227], v167
	v_cvt_pk_f32_fp8_e32 v[228:229], v171
	v_cvt_pk_f32_fp8_e32 v[230:231], v175
	v_pk_fma_f32 v[216:217], v[224:225], v[60:61], v[216:217]
	v_pk_fma_f32 v[218:219], v[226:227], v[60:61], v[218:219]
	v_pk_fma_f32 v[220:221], v[228:229], v[60:61], v[220:221]
	v_pk_fma_f32 v[222:223], v[230:231], v[60:61], v[222:223]
	v_cvt_pk_f32_fp8_sdwa v[224:225], v163 src0_sel:WORD_1
	v_cvt_pk_f32_fp8_sdwa v[226:227], v167 src0_sel:WORD_1
	v_cvt_pk_f32_fp8_sdwa v[228:229], v171 src0_sel:WORD_1
	v_cvt_pk_f32_fp8_sdwa v[230:231], v175 src0_sel:WORD_1
	v_pk_fma_f32 v[216:217], v[224:225], v[62:63], v[216:217]
	v_pk_fma_f32 v[218:219], v[226:227], v[62:63], v[218:219]
	v_pk_fma_f32 v[220:221], v[228:229], v[62:63], v[220:221]
	v_pk_fma_f32 v[222:223], v[230:231], v[62:63], v[222:223]
	v_add_f32_e32 v200, v216, v217
	v_add_f32_e32 v201, v218, v219
	v_add_f32_e32 v202, v220, v221
	v_add_f32_e32 v203, v222, v223
	s_sub_i32 s90, s90, 1
	s_cmp_eq_u32 s90, 0
	s_cbranch_scc1 .LU_sw3
.LU_t3_s3:
	s_waitcnt lgkmcnt(0)
	v_add_u32_e32 v236, v232, v240
	v_add_u32_e32 v237, v233, v240
	v_add_u32_e32 v238, v234, v240
	v_add_u32_e32 v239, v235, v240
	global_load_dwordx4 v[160:163], v236, s[4:5]
	global_load_dwordx4 v[164:167], v237, s[4:5]
	global_load_dwordx4 v[168:171], v238, s[4:5]
	global_load_dwordx4 v[172:175], v239, s[4:5]
	ds_read_b128 v[232:235], v213 offset:112
	s_waitcnt vmcnt(12)
	v_cvt_pk_f32_fp8_e32 v[224:225], v176
	v_cvt_pk_f32_fp8_e32 v[226:227], v180
	v_cvt_pk_f32_fp8_e32 v[228:229], v184
	v_cvt_pk_f32_fp8_e32 v[230:231], v188
	v_pk_mul_f32 v[216:217], v[224:225], v[48:49]
	v_pk_mul_f32 v[218:219], v[226:227], v[48:49]
	v_pk_mul_f32 v[220:221], v[228:229], v[48:49]
	v_pk_mul_f32 v[222:223], v[230:231], v[48:49]
	v_cvt_pk_f32_fp8_sdwa v[224:225], v176 src0_sel:WORD_1
	v_cvt_pk_f32_fp8_sdwa v[226:227], v180 src0_sel:WORD_1
	v_cvt_pk_f32_fp8_sdwa v[228:229], v184 src0_sel:WORD_1
	v_cvt_pk_f32_fp8_sdwa v[230:231], v188 src0_sel:WORD_1
	v_pk_fma_f32 v[216:217], v[224:225], v[50:51], v[216:217]
	v_pk_fma_f32 v[218:219], v[226:227], v[50:51], v[218:219]
	v_pk_fma_f32 v[220:221], v[228:229], v[50:51], v[220:221]
	v_pk_fma_f32 v[222:223], v[230:231], v[50:51], v[222:223]
	v_cvt_pk_f32_fp8_e32 v[224:225], v177
	v_cvt_pk_f32_fp8_e32 v[226:227], v181
	v_cvt_pk_f32_fp8_e32 v[228:229], v185
	v_cvt_pk_f32_fp8_e32 v[230:231], v189
	v_pk_fma_f32 v[216:217], v[224:225], v[52:53], v[216:217]
	v_pk_fma_f32 v[218:219], v[226:227], v[52:53], v[218:219]
	v_pk_fma_f32 v[220:221], v[228:229], v[52:53], v[220:221]
	v_pk_fma_f32 v[222:223], v[230:231], v[52:53], v[222:223]
	v_cvt_pk_f32_fp8_sdwa v[224:225], v177 src0_sel:WORD_1
	v_cvt_pk_f32_fp8_sdwa v[226:227], v181 src0_sel:WORD_1
	v_cvt_pk_f32_fp8_sdwa v[228:229], v185 src0_sel:WORD_1
	v_cvt_pk_f32_fp8_sdwa v[230:231], v189 src0_sel:WORD_1
	v_pk_fma_f32 v[216:217], v[224:225], v[54:55], v[216:217]
	v_pk_fma_f32 v[218:219], v[226:227], v[54:55], v[218:219]
	v_pk_fma_f32 v[220:221], v[228:229], v[54:55], v[220:221]
	v_pk_fma_f32 v[222:223], v[230:231], v[54:55], v[222:223]
	v_cvt_pk_f32_fp8_e32 v[224:225], v178
	v_cvt_pk_f32_fp8_e32 v[226:227], v182
	v_cvt_pk_f32_fp8_e32 v[228:229], v186
	v_cvt_pk_f32_fp8_e32 v[230:231], v190
	v_pk_fma_f32 v[216:217], v[224:225], v[56:57], v[216:217]
	v_pk_fma_f32 v[218:219], v[226:227], v[56:57], v[218:219]
	v_pk_fma_f32 v[220:221], v[228:229], v[56:57], v[220:221]
	v_pk_fma_f32 v[222:223], v[230:231], v[56:57], v[222:223]
	v_cvt_pk_f32_fp8_sdwa v[224:225], v178 src0_sel:WORD_1
	v_cvt_pk_f32_fp8_sdwa v[226:227], v182 src0_sel:WORD_1
	v_cvt_pk_f32_fp8_sdwa v[228:229], v186 src0_sel:WORD_1
	v_cvt_pk_f32_fp8_sdwa v[230:231], v190 src0_sel:WORD_1
	v_pk_fma_f32 v[216:217], v[224:225], v[58:59], v[216:217]
	v_pk_fma_f32 v[218:219], v[226:227], v[58:59], v[218:219]
	v_pk_fma_f32 v[220:221], v[228:229], v[58:59], v[220:221]
	v_pk_fma_f32 v[222:223], v[230:231], v[58:59], v[222:223]
	v_cvt_pk_f32_fp8_e32 v[224:225], v179
	v_cvt_pk_f32_fp8_e32 v[226:227], v183
	v_cvt_pk_f32_fp8_e32 v[228:229], v187
	v_cvt_pk_f32_fp8_e32 v[230:231], v191
	v_pk_fma_f32 v[216:217], v[224:225], v[60:61], v[216:217]
	v_pk_fma_f32 v[218:219], v[226:227], v[60:61], v[218:219]
	v_pk_fma_f32 v[220:221], v[228:229], v[60:61], v[220:221]
	v_pk_fma_f32 v[222:223], v[230:231], v[60:61], v[222:223]
	v_cvt_pk_f32_fp8_sdwa v[224:225], v179 src0_sel:WORD_1
	v_cvt_pk_f32_fp8_sdwa v[226:227], v183 src0_sel:WORD_1
	v_cvt_pk_f32_fp8_sdwa v[228:229], v187 src0_sel:WORD_1
	v_cvt_pk_f32_fp8_sdwa v[230:231], v191 src0_sel:WORD_1
	v_pk_fma_f32 v[216:217], v[224:225], v[62:63], v[216:217]
	v_pk_fma_f32 v[218:219], v[226:227], v[62:63], v[218:219]
	v_pk_fma_f32 v[220:221], v[228:229], v[62:63], v[220:221]
	v_pk_fma_f32 v[222:223], v[230:231], v[62:63], v[222:223]
	v_add_f32_e32 v204, v216, v217
	v_add_f32_e32 v205, v218, v219
	v_add_f32_e32 v206, v220, v221
	v_add_f32_e32 v207, v222, v223
	s_nop 0
	v_permlane32_swap_b32_e32 v192, v200
	v_permlane32_swap_b32_e32 v193, v201
	v_permlane32_swap_b32_e32 v194, v202
	v_permlane32_swap_b32_e32 v195, v203
	v_permlane32_swap_b32_e32 v196, v204
	v_permlane32_swap_b32_e32 v197, v205
	v_permlane32_swap_b32_e32 v198, v206
	v_permlane32_swap_b32_e32 v199, v207
	v_add_f32_e32 v192, v192, v200
	v_add_f32_e32 v193, v193, v201
	v_add_f32_e32 v194, v194, v202
	v_add_f32_e32 v195, v195, v203
	v_add_f32_e32 v196, v196, v204
	v_add_f32_e32 v197, v197, v205
	v_add_f32_e32 v198, v198, v206
	v_add_f32_e32 v199, v199, v207
	v_permlane16_swap_b32_e32 v192, v196
	v_permlane16_swap_b32_e32 v193, v197
	v_permlane16_swap_b32_e32 v194, v198
	v_permlane16_swap_b32_e32 v195, v199
	v_add_f32_e32 v192, v192, v196
	v_add_f32_e32 v193, v193, v197
	v_add_f32_e32 v194, v194, v198
	v_add_f32_e32 v195, v195, v199
	v_add_f32_dpp v216, v192, v192 row_ror:8 row_mask:0xf bank_mask:0xf
	v_add_f32_dpp v218, v194, v194 row_ror:8 row_mask:0xf bank_mask:0xf
	v_add_f32_dpp v216, v193, v193 row_ror:8 row_mask:0xf bank_mask:0xc
	v_add_f32_dpp v218, v195, v195 row_ror:8 row_mask:0xf bank_mask:0xc
	s_nop 1
	v_add_f32_dpp v220, v216, v216 row_half_mirror row_mask:0xf bank_mask:0xf
	v_add_f32_dpp v220, v218, v218 row_half_mirror row_mask:0xf bank_mask:0xa
	s_nop 1
	v_add_f32_dpp v220, v220, v220 quad_perm:[1,0,3,2] row_mask:0xf bank_mask:0xf
	s_nop 1
	v_add_f32_dpp v220, v220, v220 quad_perm:[2,3,0,1] row_mask:0xf bank_mask:0xf
	v_mul_f32_e32 v216, v252, v220
	v_fma_f32 v218, |v216|, s72, 1.0
	v_mul_f32_e32 v222, v216, v216
	v_rcp_f32_e32 v218, v218
	v_mul_f32_e32 v222, 0xbf38aa3b, v222
	v_exp_f32_e32 v222, v222
	v_fmamk_f32 v224, v218, 0x3f07dc22, v242
	v_fmaak_f32 v224, v218, v224, 0x3f35f0e3
	v_fmaak_f32 v224, v218, v224, 0xbe11a98e
	v_fmaak_f32 v224, v218, v224, 0x3e027906
	v_mul_f32_e32 v224, v218, v224
	v_mul_f32_e32 v224, v222, v224
	v_mul_f32_e32 v226, v216, v224
	v_fma_f32 v224, -v216, v224, v216
	v_cmp_gt_f32_e32 vcc, 0, v216
	s_nop 1
	v_cndmask_b32_e32 v224, v224, v226, vcc
	v_mul_f32_e32 v224, v249, v224
	v_mul_f32_e32 v224, v253, v224
	ds_write_b32 v211, v224 offset:4864
	v_add_u32_e32 v211, 64, v211
	v_add_u32_e32 v213, 64, v213
	ds_read_b32 v248, v211
	ds_read_b32 v249, v211 offset:4864
	s_add_i32 s21, s21, 4
	s_sub_i32 s90, s90, 1
	s_cmp_eq_u32 s90, 0
	s_cbranch_scc1 .LU_sw0
	s_branch .LU_t3_s0
.LU_t4_s0:
	s_cmp_ge_u32 s21, s20
	s_cbranch_scc1 .LU_done
	s_waitcnt lgkmcnt(0)
	v_add_u32_e32 v236, v232, v240
	v_add_u32_e32 v237, v233, v240
	v_add_u32_e32 v238, v234, v240
	v_add_u32_e32 v239, v235, v240
	v_lshrrev_b32_e32 v208, 8, v248
	global_load_dword v252, v208, s[8:9]
	global_load_dword v253, v208, s[52:53]
	global_load_dwordx4 v[176:179], v236, s[4:5]
	global_load_dwordx4 v[180:183], v237, s[4:5]
	global_load_dwordx4 v[184:187], v238, s[4:5]
	global_load_dwordx4 v[188:191], v239, s[4:5]
	ds_read_b128 v[232:235], v213 offset:64
	s_waitcnt vmcnt(14)
	v_cvt_pk_f32_fp8_e32 v[224:225], v128
	v_cvt_pk_f32_fp8_e32 v[226:227], v132
	v_cvt_pk_f32_fp8_e32 v[228:229], v136
	v_cvt_pk_f32_fp8_e32 v[230:231], v140
	v_pk_mul_f32 v[216:217], v[224:225], v[64:65]
	v_pk_mul_f32 v[218:219], v[226:227], v[64:65]
	v_pk_mul_f32 v[220:221], v[228:229], v[64:65]
	v_pk_mul_f32 v[222:223], v[230:231], v[64:65]
	v_cvt_pk_f32_fp8_sdwa v[224:225], v128 src0_sel:WORD_1
	v_cvt_pk_f32_fp8_sdwa v[226:227], v132 src0_sel:WORD_1
	v_cvt_pk_f32_fp8_sdwa v[228:229], v136 src0_sel:WORD_1
	v_cvt_pk_f32_fp8_sdwa v[230:231], v140 src0_sel:WORD_1
	v_pk_fma_f32 v[216:217], v[224:225], v[66:67], v[216:217]
	v_pk_fma_f32 v[218:219], v[226:227], v[66:67], v[218:219]
	v_pk_fma_f32 v[220:221], v[228:229], v[66:67], v[220:221]
	v_pk_fma_f32 v[222:223], v[230:231], v[66:67], v[222:223]
	v_cvt_pk_f32_fp8_e32 v[224:225], v129
	v_cvt_pk_f32_fp8_e32 v[226:227], v133
	v_cvt_pk_f32_fp8_e32 v[228:229], v137
	v_cvt_pk_f32_fp8_e32 v[230:231], v141
	v_pk_fma_f32 v[216:217], v[224:225], v[68:69], v[216:217]
	v_pk_fma_f32 v[218:219], v[226:227], v[68:69], v[218:219]
	v_pk_fma_f32 v[220:221], v[228:229], v[68:69], v[220:221]
	v_pk_fma_f32 v[222:223], v[230:231], v[68:69], v[222:223]
	v_cvt_pk_f32_fp8_sdwa v[224:225], v129 src0_sel:WORD_1
	v_cvt_pk_f32_fp8_sdwa v[226:227], v133 src0_sel:WORD_1
	v_cvt_pk_f32_fp8_sdwa v[228:229], v137 src0_sel:WORD_1
	v_cvt_pk_f32_fp8_sdwa v[230:231], v141 src0_sel:WORD_1
	v_pk_fma_f32 v[216:217], v[224:225], v[70:71], v[216:217]
	v_pk_fma_f32 v[218:219], v[226:227], v[70:71], v[218:219]
	v_pk_fma_f32 v[220:221], v[228:229], v[70:71], v[220:221]
	v_pk_fma_f32 v[222:223], v[230:231], v[70:71], v[222:223]
	v_cvt_pk_f32_fp8_e32 v[224:225], v130
	v_cvt_pk_f32_fp8_e32 v[226:227], v134
	v_cvt_pk_f32_fp8_e32 v[228:229], v138
	v_cvt_pk_f32_fp8_e32 v[230:231], v142
	v_pk_fma_f32 v[216:217], v[224:225], v[72:73], v[216:217]
	v_pk_fma_f32 v[218:219], v[226:227], v[72:73], v[218:219]
	v_pk_fma_f32 v[220:221], v[228:229], v[72:73], v[220:221]
	v_pk_fma_f32 v[222:223], v[230:231], v[72:73], v[222:223]
	v_cvt_pk_f32_fp8_sdwa v[224:225], v130 src0_sel:WORD_1
	v_cvt_pk_f32_fp8_sdwa v[226:227], v134 src0_sel:WORD_1
	v_cvt_pk_f32_fp8_sdwa v[228:229], v138 src0_sel:WORD_1
	v_cvt_pk_f32_fp8_sdwa v[230:231], v142 src0_sel:WORD_1
	v_pk_fma_f32 v[216:217], v[224:225], v[74:75], v[216:217]
	v_pk_fma_f32 v[218:219], v[226:227], v[74:75], v[218:219]
	v_pk_fma_f32 v[220:221], v[228:229], v[74:75], v[220:221]
	v_pk_fma_f32 v[222:223], v[230:231], v[74:75], v[222:223]
	v_cvt_pk_f32_fp8_e32 v[224:225], v131
	v_cvt_pk_f32_fp8_e32 v[226:227], v135
	v_cvt_pk_f32_fp8_e32 v[228:229], v139
	v_cvt_pk_f32_fp8_e32 v[230:231], v143
	v_pk_fma_f32 v[216:217], v[224:225], v[76:77], v[216:217]
	v_pk_fma_f32 v[218:219], v[226:227], v[76:77], v[218:219]
	v_pk_fma_f32 v[220:221], v[228:229], v[76:77], v[220:221]
	v_pk_fma_f32 v[222:223], v[230:231], v[76:77], v[222:223]
	v_cvt_pk_f32_fp8_sdwa v[224:225], v131 src0_sel:WORD_1
	v_cvt_pk_f32_fp8_sdwa v[226:227], v135 src0_sel:WORD_1
	v_cvt_pk_f32_fp8_sdwa v[228:229], v139 src0_sel:WORD_1
	v_cvt_pk_f32_fp8_sdwa v[230:231], v143 src0_sel:WORD_1
	v_pk_fma_f32 v[216:217], v[224:225], v[78:79], v[216:217]
	v_pk_fma_f32 v[218:219], v[226:227], v[78:79], v[218:219]
	v_pk_fma_f32 v[220:221], v[228:229], v[78:79], v[220:221]
	v_pk_fma_f32 v[222:223], v[230:231], v[78:79], v[222:223]
	v_add_f32_e32 v192, v216, v217
	v_add_f32_e32 v193, v218, v219
	v_add_f32_e32 v194, v220, v221
	v_add_f32_e32 v195, v222, v223
	s_sub_i32 s90, s90, 1
	s_cmp_eq_u32 s90, 0
	s_cbranch_scc1 .LU_sw1
.LU_t4_s1:
	s_waitcnt lgkmcnt(0)
	v_add_u32_e32 v236, v232, v240
	v_add_u32_e32 v237, v233, v240
	v_add_u32_e32 v238, v234, v240
	v_add_u32_e32 v239, v235, v240
	global_load_dwordx4 v[128:131], v236, s[4:5]
	global_load_dwordx4 v[132:135], v237, s[4:5]
	global_load_dwordx4 v[136:139], v238, s[4:5]
	global_load_dwordx4 v[140:143], v239, s[4:5]
	ds_read_b128 v[232:235], v213 offset:80
	s_waitcnt vmcnt(14)
	v_cvt_pk_f32_fp8_e32 v[224:225], v144
	v_cvt_pk_f32_fp8_e32 v[226:227], v148
	v_cvt_pk_f32_fp8_e32 v[228:229], v152
	v_cvt_pk_f32_fp8_e32 v[230:231], v156
	v_pk_mul_f32 v[216:217], v[224:225], v[64:65]
	v_pk_mul_f32 v[218:219], v[226:227], v[64:65]
	v_pk_mul_f32 v[220:221], v[228:229], v[64:65]
	v_pk_mul_f32 v[222:223], v[230:231], v[64:65]
	v_cvt_pk_f32_fp8_sdwa v[224:225], v144 src0_sel:WORD_1
	v_cvt_pk_f32_fp8_sdwa v[226:227], v148 src0_sel:WORD_1
	v_cvt_pk_f32_fp8_sdwa v[228:229], v152 src0_sel:WORD_1
	v_cvt_pk_f32_fp8_sdwa v[230:231], v156 src0_sel:WORD_1
	v_pk_fma_f32 v[216:217], v[224:225], v[66:67], v[216:217]
	v_pk_fma_f32 v[218:219], v[226:227], v[66:67], v[218:219]
	v_pk_fma_f32 v[220:221], v[228:229], v[66:67], v[220:221]
	v_pk_fma_f32 v[222:223], v[230:231], v[66:67], v[222:223]
	v_cvt_pk_f32_fp8_e32 v[224:225], v145
	v_cvt_pk_f32_fp8_e32 v[226:227], v149
	v_cvt_pk_f32_fp8_e32 v[228:229], v153
	v_cvt_pk_f32_fp8_e32 v[230:231], v157
	v_pk_fma_f32 v[216:217], v[224:225], v[68:69], v[216:217]
	v_pk_fma_f32 v[218:219], v[226:227], v[68:69], v[218:219]
	v_pk_fma_f32 v[220:221], v[228:229], v[68:69], v[220:221]
	v_pk_fma_f32 v[222:223], v[230:231], v[68:69], v[222:223]
	v_cvt_pk_f32_fp8_sdwa v[224:225], v145 src0_sel:WORD_1
	v_cvt_pk_f32_fp8_sdwa v[226:227], v149 src0_sel:WORD_1
	v_cvt_pk_f32_fp8_sdwa v[228:229], v153 src0_sel:WORD_1
	v_cvt_pk_f32_fp8_sdwa v[230:231], v157 src0_sel:WORD_1
	v_pk_fma_f32 v[216:217], v[224:225], v[70:71], v[216:217]
	v_pk_fma_f32 v[218:219], v[226:227], v[70:71], v[218:219]
	v_pk_fma_f32 v[220:221], v[228:229], v[70:71], v[220:221]
	v_pk_fma_f32 v[222:223], v[230:231], v[70:71], v[222:223]
	v_cvt_pk_f32_fp8_e32 v[224:225], v146
	v_cvt_pk_f32_fp8_e32 v[226:227], v150
	v_cvt_pk_f32_fp8_e32 v[228:229], v154
	v_cvt_pk_f32_fp8_e32 v[230:231], v158
	v_pk_fma_f32 v[216:217], v[224:225], v[72:73], v[216:217]
	v_pk_fma_f32 v[218:219], v[226:227], v[72:73], v[218:219]
	v_pk_fma_f32 v[220:221], v[228:229], v[72:73], v[220:221]
	v_pk_fma_f32 v[222:223], v[230:231], v[72:73], v[222:223]
	v_cvt_pk_f32_fp8_sdwa v[224:225], v146 src0_sel:WORD_1
	v_cvt_pk_f32_fp8_sdwa v[226:227], v150 src0_sel:WORD_1
	v_cvt_pk_f32_fp8_sdwa v[228:229], v154 src0_sel:WORD_1
	v_cvt_pk_f32_fp8_sdwa v[230:231], v158 src0_sel:WORD_1
	v_pk_fma_f32 v[216:217], v[224:225], v[74:75], v[216:217]
	v_pk_fma_f32 v[218:219], v[226:227], v[74:75], v[218:219]
	v_pk_fma_f32 v[220:221], v[228:229], v[74:75], v[220:221]
	v_pk_fma_f32 v[222:223], v[230:231], v[74:75], v[222:223]
	v_cvt_pk_f32_fp8_e32 v[224:225], v147
	v_cvt_pk_f32_fp8_e32 v[226:227], v151
	v_cvt_pk_f32_fp8_e32 v[228:229], v155
	v_cvt_pk_f32_fp8_e32 v[230:231], v159
	v_pk_fma_f32 v[216:217], v[224:225], v[76:77], v[216:217]
	v_pk_fma_f32 v[218:219], v[226:227], v[76:77], v[218:219]
	v_pk_fma_f32 v[220:221], v[228:229], v[76:77], v[220:221]
	v_pk_fma_f32 v[222:223], v[230:231], v[76:77], v[222:223]
	v_cvt_pk_f32_fp8_sdwa v[224:225], v147 src0_sel:WORD_1
	v_cvt_pk_f32_fp8_sdwa v[226:227], v151 src0_sel:WORD_1
	v_cvt_pk_f32_fp8_sdwa v[228:229], v155 src0_sel:WORD_1
	v_cvt_pk_f32_fp8_sdwa v[230:231], v159 src0_sel:WORD_1
	v_pk_fma_f32 v[216:217], v[224:225], v[78:79], v[216:217]
	v_pk_fma_f32 v[218:219], v[226:227], v[78:79], v[218:219]
	v_pk_fma_f32 v[220:221], v[228:229], v[78:79], v[220:221]
	v_pk_fma_f32 v[222:223], v[230:231], v[78:79], v[222:223]
	v_add_f32_e32 v196, v216, v217
	v_add_f32_e32 v197, v218, v219
	v_add_f32_e32 v198, v220, v221
	v_add_f32_e32 v199, v222, v223
	s_sub_i32 s90, s90, 1
	s_cmp_eq_u32 s90, 0
	s_cbranch_scc1 .LU_sw2
.LU_t4_s2:
	s_waitcnt lgkmcnt(0)
	v_add_u32_e32 v236, v232, v240
	v_add_u32_e32 v237, v233, v240
	v_add_u32_e32 v238, v234, v240
	v_add_u32_e32 v239, v235, v240
	global_load_dwordx4 v[144:147], v236, s[4:5]
	global_load_dwordx4 v[148:151], v237, s[4:5]
	global_load_dwordx4 v[152:155], v238, s[4:5]
	global_load_dwordx4 v[156:159], v239, s[4:5]
	ds_read_b128 v[232:235], v213 offset:96
	s_waitcnt vmcnt(14)
	v_cvt_pk_f32_fp8_e32 v[224:225], v160
	v_cvt_pk_f32_fp8_e32 v[226:227], v164
	v_cvt_pk_f32_fp8_e32 v[228:229], v168
	v_cvt_pk_f32_fp8_e32 v[230:231], v172
	v_pk_mul_f32 v[216:217], v[224:225], v[64:65]
	v_pk_mul_f32 v[218:219], v[226:227], v[64:65]
	v_pk_mul_f32 v[220:221], v[228:229], v[64:65]
	v_pk_mul_f32 v[222:223], v[230:231], v[64:65]
	v_cvt_pk_f32_fp8_sdwa v[224:225], v160 src0_sel:WORD_1
	v_cvt_pk_f32_fp8_sdwa v[226:227], v164 src0_sel:WORD_1
	v_cvt_pk_f32_fp8_sdwa v[228:229], v168 src0_sel:WORD_1
	v_cvt_pk_f32_fp8_sdwa v[230:231], v172 src0_sel:WORD_1
	v_pk_fma_f32 v[216:217], v[224:225], v[66:67], v[216:217]
	v_pk_fma_f32 v[218:219], v[226:227], v[66:67], v[218:219]
	v_pk_fma_f32 v[220:221], v[228:229], v[66:67], v[220:221]
	v_pk_fma_f32 v[222:223], v[230:231], v[66:67], v[222:223]
	v_cvt_pk_f32_fp8_e32 v[224:225], v161
	v_cvt_pk_f32_fp8_e32 v[226:227], v165
	v_cvt_pk_f32_fp8_e32 v[228:229], v169
	v_cvt_pk_f32_fp8_e32 v[230:231], v173
	v_pk_fma_f32 v[216:217], v[224:225], v[68:69], v[216:217]
	v_pk_fma_f32 v[218:219], v[226:227], v[68:69], v[218:219]
	v_pk_fma_f32 v[220:221], v[228:229], v[68:69], v[220:221]
	v_pk_fma_f32 v[222:223], v[230:231], v[68:69], v[222:223]
	v_cvt_pk_f32_fp8_sdwa v[224:225], v161 src0_sel:WORD_1
	v_cvt_pk_f32_fp8_sdwa v[226:227], v165 src0_sel:WORD_1
	v_cvt_pk_f32_fp8_sdwa v[228:229], v169 src0_sel:WORD_1
	v_cvt_pk_f32_fp8_sdwa v[230:231], v173 src0_sel:WORD_1
	v_pk_fma_f32 v[216:217], v[224:225], v[70:71], v[216:217]
	v_pk_fma_f32 v[218:219], v[226:227], v[70:71], v[218:219]
	v_pk_fma_f32 v[220:221], v[228:229], v[70:71], v[220:221]
	v_pk_fma_f32 v[222:223], v[230:231], v[70:71], v[222:223]
	v_cvt_pk_f32_fp8_e32 v[224:225], v162
	v_cvt_pk_f32_fp8_e32 v[226:227], v166
	v_cvt_pk_f32_fp8_e32 v[228:229], v170
	v_cvt_pk_f32_fp8_e32 v[230:231], v174
	v_pk_fma_f32 v[216:217], v[224:225], v[72:73], v[216:217]
	v_pk_fma_f32 v[218:219], v[226:227], v[72:73], v[218:219]
	v_pk_fma_f32 v[220:221], v[228:229], v[72:73], v[220:221]
	v_pk_fma_f32 v[222:223], v[230:231], v[72:73], v[222:223]
	v_cvt_pk_f32_fp8_sdwa v[224:225], v162 src0_sel:WORD_1
	v_cvt_pk_f32_fp8_sdwa v[226:227], v166 src0_sel:WORD_1
	v_cvt_pk_f32_fp8_sdwa v[228:229], v170 src0_sel:WORD_1
	v_cvt_pk_f32_fp8_sdwa v[230:231], v174 src0_sel:WORD_1
	v_pk_fma_f32 v[216:217], v[224:225], v[74:75], v[216:217]
	v_pk_fma_f32 v[218:219], v[226:227], v[74:75], v[218:219]
	v_pk_fma_f32 v[220:221], v[228:229], v[74:75], v[220:221]
	v_pk_fma_f32 v[222:223], v[230:231], v[74:75], v[222:223]
	v_cvt_pk_f32_fp8_e32 v[224:225], v163
	v_cvt_pk_f32_fp8_e32 v[226:227], v167
	v_cvt_pk_f32_fp8_e32 v[228:229], v171
	v_cvt_pk_f32_fp8_e32 v[230:231], v175
	v_pk_fma_f32 v[216:217], v[224:225], v[76:77], v[216:217]
	v_pk_fma_f32 v[218:219], v[226:227], v[76:77], v[218:219]
	v_pk_fma_f32 v[220:221], v[228:229], v[76:77], v[220:221]
	v_pk_fma_f32 v[222:223], v[230:231], v[76:77], v[222:223]
	v_cvt_pk_f32_fp8_sdwa v[224:225], v163 src0_sel:WORD_1
	v_cvt_pk_f32_fp8_sdwa v[226:227], v167 src0_sel:WORD_1
	v_cvt_pk_f32_fp8_sdwa v[228:229], v171 src0_sel:WORD_1
	v_cvt_pk_f32_fp8_sdwa v[230:231], v175 src0_sel:WORD_1
	v_pk_fma_f32 v[216:217], v[224:225], v[78:79], v[216:217]
	v_pk_fma_f32 v[218:219], v[226:227], v[78:79], v[218:219]
	v_pk_fma_f32 v[220:221], v[228:229], v[78:79], v[220:221]
	v_pk_fma_f32 v[222:223], v[230:231], v[78:79], v[222:223]
	v_add_f32_e32 v200, v216, v217
	v_add_f32_e32 v201, v218, v219
	v_add_f32_e32 v202, v220, v221
	v_add_f32_e32 v203, v222, v223
	s_sub_i32 s90, s90, 1
	s_cmp_eq_u32 s90, 0
	s_cbranch_scc1 .LU_sw3
.LU_t4_s3:
	s_waitcnt lgkmcnt(0)
	v_add_u32_e32 v236, v232, v240
	v_add_u32_e32 v237, v233, v240
	v_add_u32_e32 v238, v234, v240
	v_add_u32_e32 v239, v235, v240
	global_load_dwordx4 v[160:163], v236, s[4:5]
	global_load_dwordx4 v[164:167], v237, s[4:5]
	global_load_dwordx4 v[168:171], v238, s[4:5]
	global_load_dwordx4 v[172:175], v239, s[4:5]
	ds_read_b128 v[232:235], v213 offset:112
	s_waitcnt vmcnt(12)
	v_cvt_pk_f32_fp8_e32 v[224:225], v176
	v_cvt_pk_f32_fp8_e32 v[226:227], v180
	v_cvt_pk_f32_fp8_e32 v[228:229], v184
	v_cvt_pk_f32_fp8_e32 v[230:231], v188
	v_pk_mul_f32 v[216:217], v[224:225], v[64:65]
	v_pk_mul_f32 v[218:219], v[226:227], v[64:65]
	v_pk_mul_f32 v[220:221], v[228:229], v[64:65]
	v_pk_mul_f32 v[222:223], v[230:231], v[64:65]
	v_cvt_pk_f32_fp8_sdwa v[224:225], v176 src0_sel:WORD_1
	v_cvt_pk_f32_fp8_sdwa v[226:227], v180 src0_sel:WORD_1
	v_cvt_pk_f32_fp8_sdwa v[228:229], v184 src0_sel:WORD_1
	v_cvt_pk_f32_fp8_sdwa v[230:231], v188 src0_sel:WORD_1
	v_pk_fma_f32 v[216:217], v[224:225], v[66:67], v[216:217]
	v_pk_fma_f32 v[218:219], v[226:227], v[66:67], v[218:219]
	v_pk_fma_f32 v[220:221], v[228:229], v[66:67], v[220:221]
	v_pk_fma_f32 v[222:223], v[230:231], v[66:67], v[222:223]
	v_cvt_pk_f32_fp8_e32 v[224:225], v177
	v_cvt_pk_f32_fp8_e32 v[226:227], v181
	v_cvt_pk_f32_fp8_e32 v[228:229], v185
	v_cvt_pk_f32_fp8_e32 v[230:231], v189
	v_pk_fma_f32 v[216:217], v[224:225], v[68:69], v[216:217]
	v_pk_fma_f32 v[218:219], v[226:227], v[68:69], v[218:219]
	v_pk_fma_f32 v[220:221], v[228:229], v[68:69], v[220:221]
	v_pk_fma_f32 v[222:223], v[230:231], v[68:69], v[222:223]
	v_cvt_pk_f32_fp8_sdwa v[224:225], v177 src0_sel:WORD_1
	v_cvt_pk_f32_fp8_sdwa v[226:227], v181 src0_sel:WORD_1
	v_cvt_pk_f32_fp8_sdwa v[228:229], v185 src0_sel:WORD_1
	v_cvt_pk_f32_fp8_sdwa v[230:231], v189 src0_sel:WORD_1
	v_pk_fma_f32 v[216:217], v[224:225], v[70:71], v[216:217]
	v_pk_fma_f32 v[218:219], v[226:227], v[70:71], v[218:219]
	v_pk_fma_f32 v[220:221], v[228:229], v[70:71], v[220:221]
	v_pk_fma_f32 v[222:223], v[230:231], v[70:71], v[222:223]
	v_cvt_pk_f32_fp8_e32 v[224:225], v178
	v_cvt_pk_f32_fp8_e32 v[226:227], v182
	v_cvt_pk_f32_fp8_e32 v[228:229], v186
	v_cvt_pk_f32_fp8_e32 v[230:231], v190
	v_pk_fma_f32 v[216:217], v[224:225], v[72:73], v[216:217]
	v_pk_fma_f32 v[218:219], v[226:227], v[72:73], v[218:219]
	v_pk_fma_f32 v[220:221], v[228:229], v[72:73], v[220:221]
	v_pk_fma_f32 v[222:223], v[230:231], v[72:73], v[222:223]
	v_cvt_pk_f32_fp8_sdwa v[224:225], v178 src0_sel:WORD_1
	v_cvt_pk_f32_fp8_sdwa v[226:227], v182 src0_sel:WORD_1
	v_cvt_pk_f32_fp8_sdwa v[228:229], v186 src0_sel:WORD_1
	v_cvt_pk_f32_fp8_sdwa v[230:231], v190 src0_sel:WORD_1
	v_pk_fma_f32 v[216:217], v[224:225], v[74:75], v[216:217]
	v_pk_fma_f32 v[218:219], v[226:227], v[74:75], v[218:219]
	v_pk_fma_f32 v[220:221], v[228:229], v[74:75], v[220:221]
	v_pk_fma_f32 v[222:223], v[230:231], v[74:75], v[222:223]
	v_cvt_pk_f32_fp8_e32 v[224:225], v179
	v_cvt_pk_f32_fp8_e32 v[226:227], v183
	v_cvt_pk_f32_fp8_e32 v[228:229], v187
	v_cvt_pk_f32_fp8_e32 v[230:231], v191
	v_pk_fma_f32 v[216:217], v[224:225], v[76:77], v[216:217]
	v_pk_fma_f32 v[218:219], v[226:227], v[76:77], v[218:219]
	v_pk_fma_f32 v[220:221], v[228:229], v[76:77], v[220:221]
	v_pk_fma_f32 v[222:223], v[230:231], v[76:77], v[222:223]
	v_cvt_pk_f32_fp8_sdwa v[224:225], v179 src0_sel:WORD_1
	v_cvt_pk_f32_fp8_sdwa v[226:227], v183 src0_sel:WORD_1
	v_cvt_pk_f32_fp8_sdwa v[228:229], v187 src0_sel:WORD_1
	v_cvt_pk_f32_fp8_sdwa v[230:231], v191 src0_sel:WORD_1
	v_pk_fma_f32 v[216:217], v[224:225], v[78:79], v[216:217]
	v_pk_fma_f32 v[218:219], v[226:227], v[78:79], v[218:219]
	v_pk_fma_f32 v[220:221], v[228:229], v[78:79], v[220:221]
	v_pk_fma_f32 v[222:223], v[230:231], v[78:79], v[222:223]
	v_add_f32_e32 v204, v216, v217
	v_add_f32_e32 v205, v218, v219
	v_add_f32_e32 v206, v220, v221
	v_add_f32_e32 v207, v222, v223
	s_nop 0
	v_permlane32_swap_b32_e32 v192, v200
	v_permlane32_swap_b32_e32 v193, v201
	v_permlane32_swap_b32_e32 v194, v202
	v_permlane32_swap_b32_e32 v195, v203
	v_permlane32_swap_b32_e32 v196, v204
	v_permlane32_swap_b32_e32 v197, v205
	v_permlane32_swap_b32_e32 v198, v206
	v_permlane32_swap_b32_e32 v199, v207
	v_add_f32_e32 v192, v192, v200
	v_add_f32_e32 v193, v193, v201
	v_add_f32_e32 v194, v194, v202
	v_add_f32_e32 v195, v195, v203
	v_add_f32_e32 v196, v196, v204
	v_add_f32_e32 v197, v197, v205
	v_add_f32_e32 v198, v198, v206
	v_add_f32_e32 v199, v199, v207
	v_permlane16_swap_b32_e32 v192, v196
	v_permlane16_swap_b32_e32 v193, v197
	v_permlane16_swap_b32_e32 v194, v198
	v_permlane16_swap_b32_e32 v195, v199
	v_add_f32_e32 v192, v192, v196
	v_add_f32_e32 v193, v193, v197
	v_add_f32_e32 v194, v194, v198
	v_add_f32_e32 v195, v195, v199
	v_add_f32_dpp v216, v192, v192 row_ror:8 row_mask:0xf bank_mask:0xf
	v_add_f32_dpp v218, v194, v194 row_ror:8 row_mask:0xf bank_mask:0xf
	v_add_f32_dpp v216, v193, v193 row_ror:8 row_mask:0xf bank_mask:0xc
	v_add_f32_dpp v218, v195, v195 row_ror:8 row_mask:0xf bank_mask:0xc
	s_nop 1
	v_add_f32_dpp v220, v216, v216 row_half_mirror row_mask:0xf bank_mask:0xf
	v_add_f32_dpp v220, v218, v218 row_half_mirror row_mask:0xf bank_mask:0xa
	s_nop 1
	v_add_f32_dpp v220, v220, v220 quad_perm:[1,0,3,2] row_mask:0xf bank_mask:0xf
	s_nop 1
	v_add_f32_dpp v220, v220, v220 quad_perm:[2,3,0,1] row_mask:0xf bank_mask:0xf
	v_mul_f32_e32 v216, v252, v220
	v_fma_f32 v218, |v216|, s72, 1.0
	v_mul_f32_e32 v222, v216, v216
	v_rcp_f32_e32 v218, v218
	v_mul_f32_e32 v222, 0xbf38aa3b, v222
	v_exp_f32_e32 v222, v222
	v_fmamk_f32 v224, v218, 0x3f07dc22, v242
	v_fmaak_f32 v224, v218, v224, 0x3f35f0e3
	v_fmaak_f32 v224, v218, v224, 0xbe11a98e
	v_fmaak_f32 v224, v218, v224, 0x3e027906
	v_mul_f32_e32 v224, v218, v224
	v_mul_f32_e32 v224, v222, v224
	v_mul_f32_e32 v226, v216, v224
	v_fma_f32 v224, -v216, v224, v216
	v_cmp_gt_f32_e32 vcc, 0, v216
	s_nop 1
	v_cndmask_b32_e32 v224, v224, v226, vcc
	v_mul_f32_e32 v224, v249, v224
	v_mul_f32_e32 v224, v253, v224
	ds_write_b32 v211, v224 offset:4864
	v_add_u32_e32 v211, 64, v211
	v_add_u32_e32 v213, 64, v213
	ds_read_b32 v248, v211
	ds_read_b32 v249, v211 offset:4864
	s_add_i32 s21, s21, 4
	s_sub_i32 s90, s90, 1
	s_cmp_eq_u32 s90, 0
	s_cbranch_scc1 .LU_sw0
	s_branch .LU_t4_s0
.LU_t5_s0:
	s_cmp_ge_u32 s21, s20
	s_cbranch_scc1 .LU_done
	s_waitcnt lgkmcnt(0)
	v_add_u32_e32 v236, v232, v240
	v_add_u32_e32 v237, v233, v240
	v_add_u32_e32 v238, v234, v240
	v_add_u32_e32 v239, v235, v240
	v_lshrrev_b32_e32 v208, 8, v248
	global_load_dword v252, v208, s[8:9]
	global_load_dword v253, v208, s[52:53]
	global_load_dwordx4 v[176:179], v236, s[4:5]
	global_load_dwordx4 v[180:183], v237, s[4:5]
	global_load_dwordx4 v[184:187], v238, s[4:5]
	global_load_dwordx4 v[188:191], v239, s[4:5]
	ds_read_b128 v[232:235], v213 offset:64
	s_waitcnt vmcnt(14)
	v_cvt_pk_f32_fp8_e32 v[224:225], v128
	v_cvt_pk_f32_fp8_e32 v[226:227], v132
	v_cvt_pk_f32_fp8_e32 v[228:229], v136
	v_cvt_pk_f32_fp8_e32 v[230:231], v140
	v_pk_mul_f32 v[216:217], v[224:225], v[80:81]
	v_pk_mul_f32 v[218:219], v[226:227], v[80:81]
	v_pk_mul_f32 v[220:221], v[228:229], v[80:81]
	v_pk_mul_f32 v[222:223], v[230:231], v[80:81]
	v_cvt_pk_f32_fp8_sdwa v[224:225], v128 src0_sel:WORD_1
	v_cvt_pk_f32_fp8_sdwa v[226:227], v132 src0_sel:WORD_1
	v_cvt_pk_f32_fp8_sdwa v[228:229], v136 src0_sel:WORD_1
	v_cvt_pk_f32_fp8_sdwa v[230:231], v140 src0_sel:WORD_1
	v_pk_fma_f32 v[216:217], v[224:225], v[82:83], v[216:217]
	v_pk_fma_f32 v[218:219], v[226:227], v[82:83], v[218:219]
	v_pk_fma_f32 v[220:221], v[228:229], v[82:83], v[220:221]
	v_pk_fma_f32 v[222:223], v[230:231], v[82:83], v[222:223]
	v_cvt_pk_f32_fp8_e32 v[224:225], v129
	v_cvt_pk_f32_fp8_e32 v[226:227], v133
	v_cvt_pk_f32_fp8_e32 v[228:229], v137
	v_cvt_pk_f32_fp8_e32 v[230:231], v141
	v_pk_fma_f32 v[216:217], v[224:225], v[84:85], v[216:217]
	v_pk_fma_f32 v[218:219], v[226:227], v[84:85], v[218:219]
	v_pk_fma_f32 v[220:221], v[228:229], v[84:85], v[220:221]
	v_pk_fma_f32 v[222:223], v[230:231], v[84:85], v[222:223]
	v_cvt_pk_f32_fp8_sdwa v[224:225], v129 src0_sel:WORD_1
	v_cvt_pk_f32_fp8_sdwa v[226:227], v133 src0_sel:WORD_1
	v_cvt_pk_f32_fp8_sdwa v[228:229], v137 src0_sel:WORD_1
	v_cvt_pk_f32_fp8_sdwa v[230:231], v141 src0_sel:WORD_1
	v_pk_fma_f32 v[216:217], v[224:225], v[86:87], v[216:217]
	v_pk_fma_f32 v[218:219], v[226:227], v[86:87], v[218:219]
	v_pk_fma_f32 v[220:221], v[228:229], v[86:87], v[220:221]
	v_pk_fma_f32 v[222:223], v[230:231], v[86:87], v[222:223]
	v_cvt_pk_f32_fp8_e32 v[224:225], v130
	v_cvt_pk_f32_fp8_e32 v[226:227], v134
	v_cvt_pk_f32_fp8_e32 v[228:229], v138
	v_cvt_pk_f32_fp8_e32 v[230:231], v142
	v_pk_fma_f32 v[216:217], v[224:225], v[88:89], v[216:217]
	v_pk_fma_f32 v[218:219], v[226:227], v[88:89], v[218:219]
	v_pk_fma_f32 v[220:221], v[228:229], v[88:89], v[220:221]
	v_pk_fma_f32 v[222:223], v[230:231], v[88:89], v[222:223]
	v_cvt_pk_f32_fp8_sdwa v[224:225], v130 src0_sel:WORD_1
	v_cvt_pk_f32_fp8_sdwa v[226:227], v134 src0_sel:WORD_1
	v_cvt_pk_f32_fp8_sdwa v[228:229], v138 src0_sel:WORD_1
	v_cvt_pk_f32_fp8_sdwa v[230:231], v142 src0_sel:WORD_1
	v_pk_fma_f32 v[216:217], v[224:225], v[90:91], v[216:217]
	v_pk_fma_f32 v[218:219], v[226:227], v[90:91], v[218:219]
	v_pk_fma_f32 v[220:221], v[228:229], v[90:91], v[220:221]
	v_pk_fma_f32 v[222:223], v[230:231], v[90:91], v[222:223]
	v_cvt_pk_f32_fp8_e32 v[224:225], v131
	v_cvt_pk_f32_fp8_e32 v[226:227], v135
	v_cvt_pk_f32_fp8_e32 v[228:229], v139
	v_cvt_pk_f32_fp8_e32 v[230:231], v143
	v_pk_fma_f32 v[216:217], v[224:225], v[92:93], v[216:217]
	v_pk_fma_f32 v[218:219], v[226:227], v[92:93], v[218:219]
	v_pk_fma_f32 v[220:221], v[228:229], v[92:93], v[220:221]
	v_pk_fma_f32 v[222:223], v[230:231], v[92:93], v[222:223]
	v_cvt_pk_f32_fp8_sdwa v[224:225], v131 src0_sel:WORD_1
	v_cvt_pk_f32_fp8_sdwa v[226:227], v135 src0_sel:WORD_1
	v_cvt_pk_f32_fp8_sdwa v[228:229], v139 src0_sel:WORD_1
	v_cvt_pk_f32_fp8_sdwa v[230:231], v143 src0_sel:WORD_1
	v_pk_fma_f32 v[216:217], v[224:225], v[94:95], v[216:217]
	v_pk_fma_f32 v[218:219], v[226:227], v[94:95], v[218:219]
	v_pk_fma_f32 v[220:221], v[228:229], v[94:95], v[220:221]
	v_pk_fma_f32 v[222:223], v[230:231], v[94:95], v[222:223]
	v_add_f32_e32 v192, v216, v217
	v_add_f32_e32 v193, v218, v219
	v_add_f32_e32 v194, v220, v221
	v_add_f32_e32 v195, v222, v223
	s_sub_i32 s90, s90, 1
	s_cmp_eq_u32 s90, 0
	s_cbranch_scc1 .LU_sw1
.LU_t5_s1:
	s_waitcnt lgkmcnt(0)
	v_add_u32_e32 v236, v232, v240
	v_add_u32_e32 v237, v233, v240
	v_add_u32_e32 v238, v234, v240
	v_add_u32_e32 v239, v235, v240
	global_load_dwordx4 v[128:131], v236, s[4:5]
	global_load_dwordx4 v[132:135], v237, s[4:5]
	global_load_dwordx4 v[136:139], v238, s[4:5]
	global_load_dwordx4 v[140:143], v239, s[4:5]
	ds_read_b128 v[232:235], v213 offset:80
	s_waitcnt vmcnt(14)
	v_cvt_pk_f32_fp8_e32 v[224:225], v144
	v_cvt_pk_f32_fp8_e32 v[226:227], v148
	v_cvt_pk_f32_fp8_e32 v[228:229], v152
	v_cvt_pk_f32_fp8_e32 v[230:231], v156
	v_pk_mul_f32 v[216:217], v[224:225], v[80:81]
	v_pk_mul_f32 v[218:219], v[226:227], v[80:81]
	v_pk_mul_f32 v[220:221], v[228:229], v[80:81]
	v_pk_mul_f32 v[222:223], v[230:231], v[80:81]
	v_cvt_pk_f32_fp8_sdwa v[224:225], v144 src0_sel:WORD_1
	v_cvt_pk_f32_fp8_sdwa v[226:227], v148 src0_sel:WORD_1
	v_cvt_pk_f32_fp8_sdwa v[228:229], v152 src0_sel:WORD_1
	v_cvt_pk_f32_fp8_sdwa v[230:231], v156 src0_sel:WORD_1
	v_pk_fma_f32 v[216:217], v[224:225], v[82:83], v[216:217]
	v_pk_fma_f32 v[218:219], v[226:227], v[82:83], v[218:219]
	v_pk_fma_f32 v[220:221], v[228:229], v[82:83], v[220:221]
	v_pk_fma_f32 v[222:223], v[230:231], v[82:83], v[222:223]
	v_cvt_pk_f32_fp8_e32 v[224:225], v145
	v_cvt_pk_f32_fp8_e32 v[226:227], v149
	v_cvt_pk_f32_fp8_e32 v[228:229], v153
	v_cvt_pk_f32_fp8_e32 v[230:231], v157
	v_pk_fma_f32 v[216:217], v[224:225], v[84:85], v[216:217]
	v_pk_fma_f32 v[218:219], v[226:227], v[84:85], v[218:219]
	v_pk_fma_f32 v[220:221], v[228:229], v[84:85], v[220:221]
	v_pk_fma_f32 v[222:223], v[230:231], v[84:85], v[222:223]
	v_cvt_pk_f32_fp8_sdwa v[224:225], v145 src0_sel:WORD_1
	v_cvt_pk_f32_fp8_sdwa v[226:227], v149 src0_sel:WORD_1
	v_cvt_pk_f32_fp8_sdwa v[228:229], v153 src0_sel:WORD_1
	v_cvt_pk_f32_fp8_sdwa v[230:231], v157 src0_sel:WORD_1
	v_pk_fma_f32 v[216:217], v[224:225], v[86:87], v[216:217]
	v_pk_fma_f32 v[218:219], v[226:227], v[86:87], v[218:219]
	v_pk_fma_f32 v[220:221], v[228:229], v[86:87], v[220:221]
	v_pk_fma_f32 v[222:223], v[230:231], v[86:87], v[222:223]
	v_cvt_pk_f32_fp8_e32 v[224:225], v146
	v_cvt_pk_f32_fp8_e32 v[226:227], v150
	v_cvt_pk_f32_fp8_e32 v[228:229], v154
	v_cvt_pk_f32_fp8_e32 v[230:231], v158
	v_pk_fma_f32 v[216:217], v[224:225], v[88:89], v[216:217]
	v_pk_fma_f32 v[218:219], v[226:227], v[88:89], v[218:219]
	v_pk_fma_f32 v[220:221], v[228:229], v[88:89], v[220:221]
	v_pk_fma_f32 v[222:223], v[230:231], v[88:89], v[222:223]
	v_cvt_pk_f32_fp8_sdwa v[224:225], v146 src0_sel:WORD_1
	v_cvt_pk_f32_fp8_sdwa v[226:227], v150 src0_sel:WORD_1
	v_cvt_pk_f32_fp8_sdwa v[228:229], v154 src0_sel:WORD_1
	v_cvt_pk_f32_fp8_sdwa v[230:231], v158 src0_sel:WORD_1
	v_pk_fma_f32 v[216:217], v[224:225], v[90:91], v[216:217]
	v_pk_fma_f32 v[218:219], v[226:227], v[90:91], v[218:219]
	v_pk_fma_f32 v[220:221], v[228:229], v[90:91], v[220:221]
	v_pk_fma_f32 v[222:223], v[230:231], v[90:91], v[222:223]
	v_cvt_pk_f32_fp8_e32 v[224:225], v147
	v_cvt_pk_f32_fp8_e32 v[226:227], v151
	v_cvt_pk_f32_fp8_e32 v[228:229], v155
	v_cvt_pk_f32_fp8_e32 v[230:231], v159
	v_pk_fma_f32 v[216:217], v[224:225], v[92:93], v[216:217]
	v_pk_fma_f32 v[218:219], v[226:227], v[92:93], v[218:219]
	v_pk_fma_f32 v[220:221], v[228:229], v[92:93], v[220:221]
	v_pk_fma_f32 v[222:223], v[230:231], v[92:93], v[222:223]
	v_cvt_pk_f32_fp8_sdwa v[224:225], v147 src0_sel:WORD_1
	v_cvt_pk_f32_fp8_sdwa v[226:227], v151 src0_sel:WORD_1
	v_cvt_pk_f32_fp8_sdwa v[228:229], v155 src0_sel:WORD_1
	v_cvt_pk_f32_fp8_sdwa v[230:231], v159 src0_sel:WORD_1
	v_pk_fma_f32 v[216:217], v[224:225], v[94:95], v[216:217]
	v_pk_fma_f32 v[218:219], v[226:227], v[94:95], v[218:219]
	v_pk_fma_f32 v[220:221], v[228:229], v[94:95], v[220:221]
	v_pk_fma_f32 v[222:223], v[230:231], v[94:95], v[222:223]
	v_add_f32_e32 v196, v216, v217
	v_add_f32_e32 v197, v218, v219
	v_add_f32_e32 v198, v220, v221
	v_add_f32_e32 v199, v222, v223
	s_sub_i32 s90, s90, 1
	s_cmp_eq_u32 s90, 0
	s_cbranch_scc1 .LU_sw2
.LU_t5_s2:
	s_waitcnt lgkmcnt(0)
	v_add_u32_e32 v236, v232, v240
	v_add_u32_e32 v237, v233, v240
	v_add_u32_e32 v238, v234, v240
	v_add_u32_e32 v239, v235, v240
	global_load_dwordx4 v[144:147], v236, s[4:5]
	global_load_dwordx4 v[148:151], v237, s[4:5]
	global_load_dwordx4 v[152:155], v238, s[4:5]
	global_load_dwordx4 v[156:159], v239, s[4:5]
	ds_read_b128 v[232:235], v213 offset:96
	s_waitcnt vmcnt(14)
	v_cvt_pk_f32_fp8_e32 v[224:225], v160
	v_cvt_pk_f32_fp8_e32 v[226:227], v164
	v_cvt_pk_f32_fp8_e32 v[228:229], v168
	v_cvt_pk_f32_fp8_e32 v[230:231], v172
	v_pk_mul_f32 v[216:217], v[224:225], v[80:81]
	v_pk_mul_f32 v[218:219], v[226:227], v[80:81]
	v_pk_mul_f32 v[220:221], v[228:229], v[80:81]
	v_pk_mul_f32 v[222:223], v[230:231], v[80:81]
	v_cvt_pk_f32_fp8_sdwa v[224:225], v160 src0_sel:WORD_1
	v_cvt_pk_f32_fp8_sdwa v[226:227], v164 src0_sel:WORD_1
	v_cvt_pk_f32_fp8_sdwa v[228:229], v168 src0_sel:WORD_1
	v_cvt_pk_f32_fp8_sdwa v[230:231], v172 src0_sel:WORD_1
	v_pk_fma_f32 v[216:217], v[224:225], v[82:83], v[216:217]
	v_pk_fma_f32 v[218:219], v[226:227], v[82:83], v[218:219]
	v_pk_fma_f32 v[220:221], v[228:229], v[82:83], v[220:221]
	v_pk_fma_f32 v[222:223], v[230:231], v[82:83], v[222:223]
	v_cvt_pk_f32_fp8_e32 v[224:225], v161
	v_cvt_pk_f32_fp8_e32 v[226:227], v165
	v_cvt_pk_f32_fp8_e32 v[228:229], v169
	v_cvt_pk_f32_fp8_e32 v[230:231], v173
	v_pk_fma_f32 v[216:217], v[224:225], v[84:85], v[216:217]
	v_pk_fma_f32 v[218:219], v[226:227], v[84:85], v[218:219]
	v_pk_fma_f32 v[220:221], v[228:229], v[84:85], v[220:221]
	v_pk_fma_f32 v[222:223], v[230:231], v[84:85], v[222:223]
	v_cvt_pk_f32_fp8_sdwa v[224:225], v161 src0_sel:WORD_1
	v_cvt_pk_f32_fp8_sdwa v[226:227], v165 src0_sel:WORD_1
	v_cvt_pk_f32_fp8_sdwa v[228:229], v169 src0_sel:WORD_1
	v_cvt_pk_f32_fp8_sdwa v[230:231], v173 src0_sel:WORD_1
	v_pk_fma_f32 v[216:217], v[224:225], v[86:87], v[216:217]
	v_pk_fma_f32 v[218:219], v[226:227], v[86:87], v[218:219]
	v_pk_fma_f32 v[220:221], v[228:229], v[86:87], v[220:221]
	v_pk_fma_f32 v[222:223], v[230:231], v[86:87], v[222:223]
	v_cvt_pk_f32_fp8_e32 v[224:225], v162
	v_cvt_pk_f32_fp8_e32 v[226:227], v166
	v_cvt_pk_f32_fp8_e32 v[228:229], v170
	v_cvt_pk_f32_fp8_e32 v[230:231], v174
	v_pk_fma_f32 v[216:217], v[224:225], v[88:89], v[216:217]
	v_pk_fma_f32 v[218:219], v[226:227], v[88:89], v[218:219]
	v_pk_fma_f32 v[220:221], v[228:229], v[88:89], v[220:221]
	v_pk_fma_f32 v[222:223], v[230:231], v[88:89], v[222:223]
	v_cvt_pk_f32_fp8_sdwa v[224:225], v162 src0_sel:WORD_1
	v_cvt_pk_f32_fp8_sdwa v[226:227], v166 src0_sel:WORD_1
	v_cvt_pk_f32_fp8_sdwa v[228:229], v170 src0_sel:WORD_1
	v_cvt_pk_f32_fp8_sdwa v[230:231], v174 src0_sel:WORD_1
	v_pk_fma_f32 v[216:217], v[224:225], v[90:91], v[216:217]
	v_pk_fma_f32 v[218:219], v[226:227], v[90:91], v[218:219]
	v_pk_fma_f32 v[220:221], v[228:229], v[90:91], v[220:221]
	v_pk_fma_f32 v[222:223], v[230:231], v[90:91], v[222:223]
	v_cvt_pk_f32_fp8_e32 v[224:225], v163
	v_cvt_pk_f32_fp8_e32 v[226:227], v167
	v_cvt_pk_f32_fp8_e32 v[228:229], v171
	v_cvt_pk_f32_fp8_e32 v[230:231], v175
	v_pk_fma_f32 v[216:217], v[224:225], v[92:93], v[216:217]
	v_pk_fma_f32 v[218:219], v[226:227], v[92:93], v[218:219]
	v_pk_fma_f32 v[220:221], v[228:229], v[92:93], v[220:221]
	v_pk_fma_f32 v[222:223], v[230:231], v[92:93], v[222:223]
	v_cvt_pk_f32_fp8_sdwa v[224:225], v163 src0_sel:WORD_1
	v_cvt_pk_f32_fp8_sdwa v[226:227], v167 src0_sel:WORD_1
	v_cvt_pk_f32_fp8_sdwa v[228:229], v171 src0_sel:WORD_1
	v_cvt_pk_f32_fp8_sdwa v[230:231], v175 src0_sel:WORD_1
	v_pk_fma_f32 v[216:217], v[224:225], v[94:95], v[216:217]
	v_pk_fma_f32 v[218:219], v[226:227], v[94:95], v[218:219]
	v_pk_fma_f32 v[220:221], v[228:229], v[94:95], v[220:221]
	v_pk_fma_f32 v[222:223], v[230:231], v[94:95], v[222:223]
	v_add_f32_e32 v200, v216, v217
	v_add_f32_e32 v201, v218, v219
	v_add_f32_e32 v202, v220, v221
	v_add_f32_e32 v203, v222, v223
	s_sub_i32 s90, s90, 1
	s_cmp_eq_u32 s90, 0
	s_cbranch_scc1 .LU_sw3
.LU_t5_s3:
	s_waitcnt lgkmcnt(0)
	v_add_u32_e32 v236, v232, v240
	v_add_u32_e32 v237, v233, v240
	v_add_u32_e32 v238, v234, v240
	v_add_u32_e32 v239, v235, v240
	global_load_dwordx4 v[160:163], v236, s[4:5]
	global_load_dwordx4 v[164:167], v237, s[4:5]
	global_load_dwordx4 v[168:171], v238, s[4:5]
	global_load_dwordx4 v[172:175], v239, s[4:5]
	ds_read_b128 v[232:235], v213 offset:112
	s_waitcnt vmcnt(12)
	v_cvt_pk_f32_fp8_e32 v[224:225], v176
	v_cvt_pk_f32_fp8_e32 v[226:227], v180
	v_cvt_pk_f32_fp8_e32 v[228:229], v184
	v_cvt_pk_f32_fp8_e32 v[230:231], v188
	v_pk_mul_f32 v[216:217], v[224:225], v[80:81]
	v_pk_mul_f32 v[218:219], v[226:227], v[80:81]
	v_pk_mul_f32 v[220:221], v[228:229], v[80:81]
	v_pk_mul_f32 v[222:223], v[230:231], v[80:81]
	v_cvt_pk_f32_fp8_sdwa v[224:225], v176 src0_sel:WORD_1
	v_cvt_pk_f32_fp8_sdwa v[226:227], v180 src0_sel:WORD_1
	v_cvt_pk_f32_fp8_sdwa v[228:229], v184 src0_sel:WORD_1
	v_cvt_pk_f32_fp8_sdwa v[230:231], v188 src0_sel:WORD_1
	v_pk_fma_f32 v[216:217], v[224:225], v[82:83], v[216:217]
	v_pk_fma_f32 v[218:219], v[226:227], v[82:83], v[218:219]
	v_pk_fma_f32 v[220:221], v[228:229], v[82:83], v[220:221]
	v_pk_fma_f32 v[222:223], v[230:231], v[82:83], v[222:223]
	v_cvt_pk_f32_fp8_e32 v[224:225], v177
	v_cvt_pk_f32_fp8_e32 v[226:227], v181
	v_cvt_pk_f32_fp8_e32 v[228:229], v185
	v_cvt_pk_f32_fp8_e32 v[230:231], v189
	v_pk_fma_f32 v[216:217], v[224:225], v[84:85], v[216:217]
	v_pk_fma_f32 v[218:219], v[226:227], v[84:85], v[218:219]
	v_pk_fma_f32 v[220:221], v[228:229], v[84:85], v[220:221]
	v_pk_fma_f32 v[222:223], v[230:231], v[84:85], v[222:223]
	v_cvt_pk_f32_fp8_sdwa v[224:225], v177 src0_sel:WORD_1
	v_cvt_pk_f32_fp8_sdwa v[226:227], v181 src0_sel:WORD_1
	v_cvt_pk_f32_fp8_sdwa v[228:229], v185 src0_sel:WORD_1
	v_cvt_pk_f32_fp8_sdwa v[230:231], v189 src0_sel:WORD_1
	v_pk_fma_f32 v[216:217], v[224:225], v[86:87], v[216:217]
	v_pk_fma_f32 v[218:219], v[226:227], v[86:87], v[218:219]
	v_pk_fma_f32 v[220:221], v[228:229], v[86:87], v[220:221]
	v_pk_fma_f32 v[222:223], v[230:231], v[86:87], v[222:223]
	v_cvt_pk_f32_fp8_e32 v[224:225], v178
	v_cvt_pk_f32_fp8_e32 v[226:227], v182
	v_cvt_pk_f32_fp8_e32 v[228:229], v186
	v_cvt_pk_f32_fp8_e32 v[230:231], v190
	v_pk_fma_f32 v[216:217], v[224:225], v[88:89], v[216:217]
	v_pk_fma_f32 v[218:219], v[226:227], v[88:89], v[218:219]
	v_pk_fma_f32 v[220:221], v[228:229], v[88:89], v[220:221]
	v_pk_fma_f32 v[222:223], v[230:231], v[88:89], v[222:223]
	v_cvt_pk_f32_fp8_sdwa v[224:225], v178 src0_sel:WORD_1
	v_cvt_pk_f32_fp8_sdwa v[226:227], v182 src0_sel:WORD_1
	v_cvt_pk_f32_fp8_sdwa v[228:229], v186 src0_sel:WORD_1
	v_cvt_pk_f32_fp8_sdwa v[230:231], v190 src0_sel:WORD_1
	v_pk_fma_f32 v[216:217], v[224:225], v[90:91], v[216:217]
	v_pk_fma_f32 v[218:219], v[226:227], v[90:91], v[218:219]
	v_pk_fma_f32 v[220:221], v[228:229], v[90:91], v[220:221]
	v_pk_fma_f32 v[222:223], v[230:231], v[90:91], v[222:223]
	v_cvt_pk_f32_fp8_e32 v[224:225], v179
	v_cvt_pk_f32_fp8_e32 v[226:227], v183
	v_cvt_pk_f32_fp8_e32 v[228:229], v187
	v_cvt_pk_f32_fp8_e32 v[230:231], v191
	v_pk_fma_f32 v[216:217], v[224:225], v[92:93], v[216:217]
	v_pk_fma_f32 v[218:219], v[226:227], v[92:93], v[218:219]
	v_pk_fma_f32 v[220:221], v[228:229], v[92:93], v[220:221]
	v_pk_fma_f32 v[222:223], v[230:231], v[92:93], v[222:223]
	v_cvt_pk_f32_fp8_sdwa v[224:225], v179 src0_sel:WORD_1
	v_cvt_pk_f32_fp8_sdwa v[226:227], v183 src0_sel:WORD_1
	v_cvt_pk_f32_fp8_sdwa v[228:229], v187 src0_sel:WORD_1
	v_cvt_pk_f32_fp8_sdwa v[230:231], v191 src0_sel:WORD_1
	v_pk_fma_f32 v[216:217], v[224:225], v[94:95], v[216:217]
	v_pk_fma_f32 v[218:219], v[226:227], v[94:95], v[218:219]
	v_pk_fma_f32 v[220:221], v[228:229], v[94:95], v[220:221]
	v_pk_fma_f32 v[222:223], v[230:231], v[94:95], v[222:223]
	v_add_f32_e32 v204, v216, v217
	v_add_f32_e32 v205, v218, v219
	v_add_f32_e32 v206, v220, v221
	v_add_f32_e32 v207, v222, v223
	s_nop 0
	v_permlane32_swap_b32_e32 v192, v200
	v_permlane32_swap_b32_e32 v193, v201
	v_permlane32_swap_b32_e32 v194, v202
	v_permlane32_swap_b32_e32 v195, v203
	v_permlane32_swap_b32_e32 v196, v204
	v_permlane32_swap_b32_e32 v197, v205
	v_permlane32_swap_b32_e32 v198, v206
	v_permlane32_swap_b32_e32 v199, v207
	v_add_f32_e32 v192, v192, v200
	v_add_f32_e32 v193, v193, v201
	v_add_f32_e32 v194, v194, v202
	v_add_f32_e32 v195, v195, v203
	v_add_f32_e32 v196, v196, v204
	v_add_f32_e32 v197, v197, v205
	v_add_f32_e32 v198, v198, v206
	v_add_f32_e32 v199, v199, v207
	v_permlane16_swap_b32_e32 v192, v196
	v_permlane16_swap_b32_e32 v193, v197
	v_permlane16_swap_b32_e32 v194, v198
	v_permlane16_swap_b32_e32 v195, v199
	v_add_f32_e32 v192, v192, v196
	v_add_f32_e32 v193, v193, v197
	v_add_f32_e32 v194, v194, v198
	v_add_f32_e32 v195, v195, v199
	v_add_f32_dpp v216, v192, v192 row_ror:8 row_mask:0xf bank_mask:0xf
	v_add_f32_dpp v218, v194, v194 row_ror:8 row_mask:0xf bank_mask:0xf
	v_add_f32_dpp v216, v193, v193 row_ror:8 row_mask:0xf bank_mask:0xc
	v_add_f32_dpp v218, v195, v195 row_ror:8 row_mask:0xf bank_mask:0xc
	s_nop 1
	v_add_f32_dpp v220, v216, v216 row_half_mirror row_mask:0xf bank_mask:0xf
	v_add_f32_dpp v220, v218, v218 row_half_mirror row_mask:0xf bank_mask:0xa
	s_nop 1
	v_add_f32_dpp v220, v220, v220 quad_perm:[1,0,3,2] row_mask:0xf bank_mask:0xf
	s_nop 1
	v_add_f32_dpp v220, v220, v220 quad_perm:[2,3,0,1] row_mask:0xf bank_mask:0xf
	v_mul_f32_e32 v216, v252, v220
	v_fma_f32 v218, |v216|, s72, 1.0
	v_mul_f32_e32 v222, v216, v216
	v_rcp_f32_e32 v218, v218
	v_mul_f32_e32 v222, 0xbf38aa3b, v222
	v_exp_f32_e32 v222, v222
	v_fmamk_f32 v224, v218, 0x3f07dc22, v242
	v_fmaak_f32 v224, v218, v224, 0x3f35f0e3
	v_fmaak_f32 v224, v218, v224, 0xbe11a98e
	v_fmaak_f32 v224, v218, v224, 0x3e027906
	v_mul_f32_e32 v224, v218, v224
	v_mul_f32_e32 v224, v222, v224
	v_mul_f32_e32 v226, v216, v224
	v_fma_f32 v224, -v216, v224, v216
	v_cmp_gt_f32_e32 vcc, 0, v216
	s_nop 1
	v_cndmask_b32_e32 v224, v224, v226, vcc
	v_mul_f32_e32 v224, v249, v224
	v_mul_f32_e32 v224, v253, v224
	ds_write_b32 v211, v224 offset:4864
	v_add_u32_e32 v211, 64, v211
	v_add_u32_e32 v213, 64, v213
	ds_read_b32 v248, v211
	ds_read_b32 v249, v211 offset:4864
	s_add_i32 s21, s21, 4
	s_sub_i32 s90, s90, 1
	s_cmp_eq_u32 s90, 0
	s_cbranch_scc1 .LU_sw0
	s_branch .LU_t5_s0
.LU_t6_s0:
	s_cmp_ge_u32 s21, s20
	s_cbranch_scc1 .LU_done
	s_waitcnt lgkmcnt(0)
	v_add_u32_e32 v236, v232, v240
	v_add_u32_e32 v237, v233, v240
	v_add_u32_e32 v238, v234, v240
	v_add_u32_e32 v239, v235, v240
	v_lshrrev_b32_e32 v208, 8, v248
	global_load_dword v252, v208, s[8:9]
	global_load_dword v253, v208, s[52:53]
	global_load_dwordx4 v[176:179], v236, s[4:5]
	global_load_dwordx4 v[180:183], v237, s[4:5]
	global_load_dwordx4 v[184:187], v238, s[4:5]
	global_load_dwordx4 v[188:191], v239, s[4:5]
	ds_read_b128 v[232:235], v213 offset:64
	s_waitcnt vmcnt(14)
	v_cvt_pk_f32_fp8_e32 v[224:225], v128
	v_cvt_pk_f32_fp8_e32 v[226:227], v132
	v_cvt_pk_f32_fp8_e32 v[228:229], v136
	v_cvt_pk_f32_fp8_e32 v[230:231], v140
	v_pk_mul_f32 v[216:217], v[224:225], v[96:97]
	v_pk_mul_f32 v[218:219], v[226:227], v[96:97]
	v_pk_mul_f32 v[220:221], v[228:229], v[96:97]
	v_pk_mul_f32 v[222:223], v[230:231], v[96:97]
	v_cvt_pk_f32_fp8_sdwa v[224:225], v128 src0_sel:WORD_1
	v_cvt_pk_f32_fp8_sdwa v[226:227], v132 src0_sel:WORD_1
	v_cvt_pk_f32_fp8_sdwa v[228:229], v136 src0_sel:WORD_1
	v_cvt_pk_f32_fp8_sdwa v[230:231], v140 src0_sel:WORD_1
	v_pk_fma_f32 v[216:217], v[224:225], v[98:99], v[216:217]
	v_pk_fma_f32 v[218:219], v[226:227], v[98:99], v[218:219]
	v_pk_fma_f32 v[220:221], v[228:229], v[98:99], v[220:221]
	v_pk_fma_f32 v[222:223], v[230:231], v[98:99], v[222:223]
	v_cvt_pk_f32_fp8_e32 v[224:225], v129
	v_cvt_pk_f32_fp8_e32 v[226:227], v133
	v_cvt_pk_f32_fp8_e32 v[228:229], v137
	v_cvt_pk_f32_fp8_e32 v[230:231], v141
	v_pk_fma_f32 v[216:217], v[224:225], v[100:101], v[216:217]
	v_pk_fma_f32 v[218:219], v[226:227], v[100:101], v[218:219]
	v_pk_fma_f32 v[220:221], v[228:229], v[100:101], v[220:221]
	v_pk_fma_f32 v[222:223], v[230:231], v[100:101], v[222:223]
	v_cvt_pk_f32_fp8_sdwa v[224:225], v129 src0_sel:WORD_1
	v_cvt_pk_f32_fp8_sdwa v[226:227], v133 src0_sel:WORD_1
	v_cvt_pk_f32_fp8_sdwa v[228:229], v137 src0_sel:WORD_1
	v_cvt_pk_f32_fp8_sdwa v[230:231], v141 src0_sel:WORD_1
	v_pk_fma_f32 v[216:217], v[224:225], v[102:103], v[216:217]
	v_pk_fma_f32 v[218:219], v[226:227], v[102:103], v[218:219]
	v_pk_fma_f32 v[220:221], v[228:229], v[102:103], v[220:221]
	v_pk_fma_f32 v[222:223], v[230:231], v[102:103], v[222:223]
	v_cvt_pk_f32_fp8_e32 v[224:225], v130
	v_cvt_pk_f32_fp8_e32 v[226:227], v134
	v_cvt_pk_f32_fp8_e32 v[228:229], v138
	v_cvt_pk_f32_fp8_e32 v[230:231], v142
	v_pk_fma_f32 v[216:217], v[224:225], v[104:105], v[216:217]
	v_pk_fma_f32 v[218:219], v[226:227], v[104:105], v[218:219]
	v_pk_fma_f32 v[220:221], v[228:229], v[104:105], v[220:221]
	v_pk_fma_f32 v[222:223], v[230:231], v[104:105], v[222:223]
	v_cvt_pk_f32_fp8_sdwa v[224:225], v130 src0_sel:WORD_1
	v_cvt_pk_f32_fp8_sdwa v[226:227], v134 src0_sel:WORD_1
	v_cvt_pk_f32_fp8_sdwa v[228:229], v138 src0_sel:WORD_1
	v_cvt_pk_f32_fp8_sdwa v[230:231], v142 src0_sel:WORD_1
	v_pk_fma_f32 v[216:217], v[224:225], v[106:107], v[216:217]
	v_pk_fma_f32 v[218:219], v[226:227], v[106:107], v[218:219]
	v_pk_fma_f32 v[220:221], v[228:229], v[106:107], v[220:221]
	v_pk_fma_f32 v[222:223], v[230:231], v[106:107], v[222:223]
	v_cvt_pk_f32_fp8_e32 v[224:225], v131
	v_cvt_pk_f32_fp8_e32 v[226:227], v135
	v_cvt_pk_f32_fp8_e32 v[228:229], v139
	v_cvt_pk_f32_fp8_e32 v[230:231], v143
	v_pk_fma_f32 v[216:217], v[224:225], v[108:109], v[216:217]
	v_pk_fma_f32 v[218:219], v[226:227], v[108:109], v[218:219]
	v_pk_fma_f32 v[220:221], v[228:229], v[108:109], v[220:221]
	v_pk_fma_f32 v[222:223], v[230:231], v[108:109], v[222:223]
	v_cvt_pk_f32_fp8_sdwa v[224:225], v131 src0_sel:WORD_1
	v_cvt_pk_f32_fp8_sdwa v[226:227], v135 src0_sel:WORD_1
	v_cvt_pk_f32_fp8_sdwa v[228:229], v139 src0_sel:WORD_1
	v_cvt_pk_f32_fp8_sdwa v[230:231], v143 src0_sel:WORD_1
	v_pk_fma_f32 v[216:217], v[224:225], v[110:111], v[216:217]
	v_pk_fma_f32 v[218:219], v[226:227], v[110:111], v[218:219]
	v_pk_fma_f32 v[220:221], v[228:229], v[110:111], v[220:221]
	v_pk_fma_f32 v[222:223], v[230:231], v[110:111], v[222:223]
	v_add_f32_e32 v192, v216, v217
	v_add_f32_e32 v193, v218, v219
	v_add_f32_e32 v194, v220, v221
	v_add_f32_e32 v195, v222, v223
	s_sub_i32 s90, s90, 1
	s_cmp_eq_u32 s90, 0
	s_cbranch_scc1 .LU_sw1
.LU_t6_s1:
	s_waitcnt lgkmcnt(0)
	v_add_u32_e32 v236, v232, v240
	v_add_u32_e32 v237, v233, v240
	v_add_u32_e32 v238, v234, v240
	v_add_u32_e32 v239, v235, v240
	global_load_dwordx4 v[128:131], v236, s[4:5]
	global_load_dwordx4 v[132:135], v237, s[4:5]
	global_load_dwordx4 v[136:139], v238, s[4:5]
	global_load_dwordx4 v[140:143], v239, s[4:5]
	ds_read_b128 v[232:235], v213 offset:80
	s_waitcnt vmcnt(14)
	v_cvt_pk_f32_fp8_e32 v[224:225], v144
	v_cvt_pk_f32_fp8_e32 v[226:227], v148
	v_cvt_pk_f32_fp8_e32 v[228:229], v152
	v_cvt_pk_f32_fp8_e32 v[230:231], v156
	v_pk_mul_f32 v[216:217], v[224:225], v[96:97]
	v_pk_mul_f32 v[218:219], v[226:227], v[96:97]
	v_pk_mul_f32 v[220:221], v[228:229], v[96:97]
	v_pk_mul_f32 v[222:223], v[230:231], v[96:97]
	v_cvt_pk_f32_fp8_sdwa v[224:225], v144 src0_sel:WORD_1
	v_cvt_pk_f32_fp8_sdwa v[226:227], v148 src0_sel:WORD_1
	v_cvt_pk_f32_fp8_sdwa v[228:229], v152 src0_sel:WORD_1
	v_cvt_pk_f32_fp8_sdwa v[230:231], v156 src0_sel:WORD_1
	v_pk_fma_f32 v[216:217], v[224:225], v[98:99], v[216:217]
	v_pk_fma_f32 v[218:219], v[226:227], v[98:99], v[218:219]
	v_pk_fma_f32 v[220:221], v[228:229], v[98:99], v[220:221]
	v_pk_fma_f32 v[222:223], v[230:231], v[98:99], v[222:223]
	v_cvt_pk_f32_fp8_e32 v[224:225], v145
	v_cvt_pk_f32_fp8_e32 v[226:227], v149
	v_cvt_pk_f32_fp8_e32 v[228:229], v153
	v_cvt_pk_f32_fp8_e32 v[230:231], v157
	v_pk_fma_f32 v[216:217], v[224:225], v[100:101], v[216:217]
	v_pk_fma_f32 v[218:219], v[226:227], v[100:101], v[218:219]
	v_pk_fma_f32 v[220:221], v[228:229], v[100:101], v[220:221]
	v_pk_fma_f32 v[222:223], v[230:231], v[100:101], v[222:223]
	v_cvt_pk_f32_fp8_sdwa v[224:225], v145 src0_sel:WORD_1
	v_cvt_pk_f32_fp8_sdwa v[226:227], v149 src0_sel:WORD_1
	v_cvt_pk_f32_fp8_sdwa v[228:229], v153 src0_sel:WORD_1
	v_cvt_pk_f32_fp8_sdwa v[230:231], v157 src0_sel:WORD_1
	v_pk_fma_f32 v[216:217], v[224:225], v[102:103], v[216:217]
	v_pk_fma_f32 v[218:219], v[226:227], v[102:103], v[218:219]
	v_pk_fma_f32 v[220:221], v[228:229], v[102:103], v[220:221]
	v_pk_fma_f32 v[222:223], v[230:231], v[102:103], v[222:223]
	v_cvt_pk_f32_fp8_e32 v[224:225], v146
	v_cvt_pk_f32_fp8_e32 v[226:227], v150
	v_cvt_pk_f32_fp8_e32 v[228:229], v154
	v_cvt_pk_f32_fp8_e32 v[230:231], v158
	v_pk_fma_f32 v[216:217], v[224:225], v[104:105], v[216:217]
	v_pk_fma_f32 v[218:219], v[226:227], v[104:105], v[218:219]
	v_pk_fma_f32 v[220:221], v[228:229], v[104:105], v[220:221]
	v_pk_fma_f32 v[222:223], v[230:231], v[104:105], v[222:223]
	v_cvt_pk_f32_fp8_sdwa v[224:225], v146 src0_sel:WORD_1
	v_cvt_pk_f32_fp8_sdwa v[226:227], v150 src0_sel:WORD_1
	v_cvt_pk_f32_fp8_sdwa v[228:229], v154 src0_sel:WORD_1
	v_cvt_pk_f32_fp8_sdwa v[230:231], v158 src0_sel:WORD_1
	v_pk_fma_f32 v[216:217], v[224:225], v[106:107], v[216:217]
	v_pk_fma_f32 v[218:219], v[226:227], v[106:107], v[218:219]
	v_pk_fma_f32 v[220:221], v[228:229], v[106:107], v[220:221]
	v_pk_fma_f32 v[222:223], v[230:231], v[106:107], v[222:223]
	v_cvt_pk_f32_fp8_e32 v[224:225], v147
	v_cvt_pk_f32_fp8_e32 v[226:227], v151
	v_cvt_pk_f32_fp8_e32 v[228:229], v155
	v_cvt_pk_f32_fp8_e32 v[230:231], v159
	v_pk_fma_f32 v[216:217], v[224:225], v[108:109], v[216:217]
	v_pk_fma_f32 v[218:219], v[226:227], v[108:109], v[218:219]
	v_pk_fma_f32 v[220:221], v[228:229], v[108:109], v[220:221]
	v_pk_fma_f32 v[222:223], v[230:231], v[108:109], v[222:223]
	v_cvt_pk_f32_fp8_sdwa v[224:225], v147 src0_sel:WORD_1
	v_cvt_pk_f32_fp8_sdwa v[226:227], v151 src0_sel:WORD_1
	v_cvt_pk_f32_fp8_sdwa v[228:229], v155 src0_sel:WORD_1
	v_cvt_pk_f32_fp8_sdwa v[230:231], v159 src0_sel:WORD_1
	v_pk_fma_f32 v[216:217], v[224:225], v[110:111], v[216:217]
	v_pk_fma_f32 v[218:219], v[226:227], v[110:111], v[218:219]
	v_pk_fma_f32 v[220:221], v[228:229], v[110:111], v[220:221]
	v_pk_fma_f32 v[222:223], v[230:231], v[110:111], v[222:223]
	v_add_f32_e32 v196, v216, v217
	v_add_f32_e32 v197, v218, v219
	v_add_f32_e32 v198, v220, v221
	v_add_f32_e32 v199, v222, v223
	s_sub_i32 s90, s90, 1
	s_cmp_eq_u32 s90, 0
	s_cbranch_scc1 .LU_sw2
.LU_t6_s2:
	s_waitcnt lgkmcnt(0)
	v_add_u32_e32 v236, v232, v240
	v_add_u32_e32 v237, v233, v240
	v_add_u32_e32 v238, v234, v240
	v_add_u32_e32 v239, v235, v240
	global_load_dwordx4 v[144:147], v236, s[4:5]
	global_load_dwordx4 v[148:151], v237, s[4:5]
	global_load_dwordx4 v[152:155], v238, s[4:5]
	global_load_dwordx4 v[156:159], v239, s[4:5]
	ds_read_b128 v[232:235], v213 offset:96
	s_waitcnt vmcnt(14)
	v_cvt_pk_f32_fp8_e32 v[224:225], v160
	v_cvt_pk_f32_fp8_e32 v[226:227], v164
	v_cvt_pk_f32_fp8_e32 v[228:229], v168
	v_cvt_pk_f32_fp8_e32 v[230:231], v172
	v_pk_mul_f32 v[216:217], v[224:225], v[96:97]
	v_pk_mul_f32 v[218:219], v[226:227], v[96:97]
	v_pk_mul_f32 v[220:221], v[228:229], v[96:97]
	v_pk_mul_f32 v[222:223], v[230:231], v[96:97]
	v_cvt_pk_f32_fp8_sdwa v[224:225], v160 src0_sel:WORD_1
	v_cvt_pk_f32_fp8_sdwa v[226:227], v164 src0_sel:WORD_1
	v_cvt_pk_f32_fp8_sdwa v[228:229], v168 src0_sel:WORD_1
	v_cvt_pk_f32_fp8_sdwa v[230:231], v172 src0_sel:WORD_1
	v_pk_fma_f32 v[216:217], v[224:225], v[98:99], v[216:217]
	v_pk_fma_f32 v[218:219], v[226:227], v[98:99], v[218:219]
	v_pk_fma_f32 v[220:221], v[228:229], v[98:99], v[220:221]
	v_pk_fma_f32 v[222:223], v[230:231], v[98:99], v[222:223]
	v_cvt_pk_f32_fp8_e32 v[224:225], v161
	v_cvt_pk_f32_fp8_e32 v[226:227], v165
	v_cvt_pk_f32_fp8_e32 v[228:229], v169
	v_cvt_pk_f32_fp8_e32 v[230:231], v173
	v_pk_fma_f32 v[216:217], v[224:225], v[100:101], v[216:217]
	v_pk_fma_f32 v[218:219], v[226:227], v[100:101], v[218:219]
	v_pk_fma_f32 v[220:221], v[228:229], v[100:101], v[220:221]
	v_pk_fma_f32 v[222:223], v[230:231], v[100:101], v[222:223]
	v_cvt_pk_f32_fp8_sdwa v[224:225], v161 src0_sel:WORD_1
	v_cvt_pk_f32_fp8_sdwa v[226:227], v165 src0_sel:WORD_1
	v_cvt_pk_f32_fp8_sdwa v[228:229], v169 src0_sel:WORD_1
	v_cvt_pk_f32_fp8_sdwa v[230:231], v173 src0_sel:WORD_1
	v_pk_fma_f32 v[216:217], v[224:225], v[102:103], v[216:217]
	v_pk_fma_f32 v[218:219], v[226:227], v[102:103], v[218:219]
	v_pk_fma_f32 v[220:221], v[228:229], v[102:103], v[220:221]
	v_pk_fma_f32 v[222:223], v[230:231], v[102:103], v[222:223]
	v_cvt_pk_f32_fp8_e32 v[224:225], v162
	v_cvt_pk_f32_fp8_e32 v[226:227], v166
	v_cvt_pk_f32_fp8_e32 v[228:229], v170
	v_cvt_pk_f32_fp8_e32 v[230:231], v174
	v_pk_fma_f32 v[216:217], v[224:225], v[104:105], v[216:217]
	v_pk_fma_f32 v[218:219], v[226:227], v[104:105], v[218:219]
	v_pk_fma_f32 v[220:221], v[228:229], v[104:105], v[220:221]
	v_pk_fma_f32 v[222:223], v[230:231], v[104:105], v[222:223]
	v_cvt_pk_f32_fp8_sdwa v[224:225], v162 src0_sel:WORD_1
	v_cvt_pk_f32_fp8_sdwa v[226:227], v166 src0_sel:WORD_1
	v_cvt_pk_f32_fp8_sdwa v[228:229], v170 src0_sel:WORD_1
	v_cvt_pk_f32_fp8_sdwa v[230:231], v174 src0_sel:WORD_1
	v_pk_fma_f32 v[216:217], v[224:225], v[106:107], v[216:217]
	v_pk_fma_f32 v[218:219], v[226:227], v[106:107], v[218:219]
	v_pk_fma_f32 v[220:221], v[228:229], v[106:107], v[220:221]
	v_pk_fma_f32 v[222:223], v[230:231], v[106:107], v[222:223]
	v_cvt_pk_f32_fp8_e32 v[224:225], v163
	v_cvt_pk_f32_fp8_e32 v[226:227], v167
	v_cvt_pk_f32_fp8_e32 v[228:229], v171
	v_cvt_pk_f32_fp8_e32 v[230:231], v175
	v_pk_fma_f32 v[216:217], v[224:225], v[108:109], v[216:217]
	v_pk_fma_f32 v[218:219], v[226:227], v[108:109], v[218:219]
	v_pk_fma_f32 v[220:221], v[228:229], v[108:109], v[220:221]
	v_pk_fma_f32 v[222:223], v[230:231], v[108:109], v[222:223]
	v_cvt_pk_f32_fp8_sdwa v[224:225], v163 src0_sel:WORD_1
	v_cvt_pk_f32_fp8_sdwa v[226:227], v167 src0_sel:WORD_1
	v_cvt_pk_f32_fp8_sdwa v[228:229], v171 src0_sel:WORD_1
	v_cvt_pk_f32_fp8_sdwa v[230:231], v175 src0_sel:WORD_1
	v_pk_fma_f32 v[216:217], v[224:225], v[110:111], v[216:217]
	v_pk_fma_f32 v[218:219], v[226:227], v[110:111], v[218:219]
	v_pk_fma_f32 v[220:221], v[228:229], v[110:111], v[220:221]
	v_pk_fma_f32 v[222:223], v[230:231], v[110:111], v[222:223]
	v_add_f32_e32 v200, v216, v217
	v_add_f32_e32 v201, v218, v219
	v_add_f32_e32 v202, v220, v221
	v_add_f32_e32 v203, v222, v223
	s_sub_i32 s90, s90, 1
	s_cmp_eq_u32 s90, 0
	s_cbranch_scc1 .LU_sw3
; __device__ __forceinline__ float gelu_fast(float v) {
;     const float av = fabsf(v), tt = __builtin_amdgcn_rcpf(av * 0.2316418882f + 1.0f);
;     float q = tt * 0.5307027145f + (-0.7265760135f); q = q * tt + 0.7107068705f; q = q * tt + (-0.142248368f); q = q * tt + 0.127414796f; q = q * tt;
;     const float e = __builtin_amdgcn_exp2f((v * v) * (-0.72134752044f));
;     const float m = v * (q * e);
;     return v < 0.f ? m : v - m;
; }
.LU_t6_s3:
	s_waitcnt lgkmcnt(0)
	v_add_u32_e32 v236, v232, v240
	v_add_u32_e32 v237, v233, v240
	v_add_u32_e32 v238, v234, v240
	v_add_u32_e32 v239, v235, v240
	global_load_dwordx4 v[160:163], v236, s[4:5]
	global_load_dwordx4 v[164:167], v237, s[4:5]
	global_load_dwordx4 v[168:171], v238, s[4:5]
	global_load_dwordx4 v[172:175], v239, s[4:5]
	ds_read_b128 v[232:235], v213 offset:112
	s_waitcnt vmcnt(12)
	v_cvt_pk_f32_fp8_e32 v[224:225], v176
	v_cvt_pk_f32_fp8_e32 v[226:227], v180
	v_cvt_pk_f32_fp8_e32 v[228:229], v184
	v_cvt_pk_f32_fp8_e32 v[230:231], v188
	v_pk_mul_f32 v[216:217], v[224:225], v[96:97]
	v_pk_mul_f32 v[218:219], v[226:227], v[96:97]
	v_pk_mul_f32 v[220:221], v[228:229], v[96:97]
	v_pk_mul_f32 v[222:223], v[230:231], v[96:97]
	v_cvt_pk_f32_fp8_sdwa v[224:225], v176 src0_sel:WORD_1
	v_cvt_pk_f32_fp8_sdwa v[226:227], v180 src0_sel:WORD_1
	v_cvt_pk_f32_fp8_sdwa v[228:229], v184 src0_sel:WORD_1
	v_cvt_pk_f32_fp8_sdwa v[230:231], v188 src0_sel:WORD_1
	v_pk_fma_f32 v[216:217], v[224:225], v[98:99], v[216:217]
	v_pk_fma_f32 v[218:219], v[226:227], v[98:99], v[218:219]
	v_pk_fma_f32 v[220:221], v[228:229], v[98:99], v[220:221]
	v_pk_fma_f32 v[222:223], v[230:231], v[98:99], v[222:223]
	v_cvt_pk_f32_fp8_e32 v[224:225], v177
	v_cvt_pk_f32_fp8_e32 v[226:227], v181
	v_cvt_pk_f32_fp8_e32 v[228:229], v185
	v_cvt_pk_f32_fp8_e32 v[230:231], v189
	v_pk_fma_f32 v[216:217], v[224:225], v[100:101], v[216:217]
	v_pk_fma_f32 v[218:219], v[226:227], v[100:101], v[218:219]
	v_pk_fma_f32 v[220:221], v[228:229], v[100:101], v[220:221]
	v_pk_fma_f32 v[222:223], v[230:231], v[100:101], v[222:223]
	v_cvt_pk_f32_fp8_sdwa v[224:225], v177 src0_sel:WORD_1
	v_cvt_pk_f32_fp8_sdwa v[226:227], v181 src0_sel:WORD_1
	v_cvt_pk_f32_fp8_sdwa v[228:229], v185 src0_sel:WORD_1
	v_cvt_pk_f32_fp8_sdwa v[230:231], v189 src0_sel:WORD_1
	v_pk_fma_f32 v[216:217], v[224:225], v[102:103], v[216:217]
	v_pk_fma_f32 v[218:219], v[226:227], v[102:103], v[218:219]
	v_pk_fma_f32 v[220:221], v[228:229], v[102:103], v[220:221]
	v_pk_fma_f32 v[222:223], v[230:231], v[102:103], v[222:223]
	v_cvt_pk_f32_fp8_e32 v[224:225], v178
	v_cvt_pk_f32_fp8_e32 v[226:227], v182
	v_cvt_pk_f32_fp8_e32 v[228:229], v186
	v_cvt_pk_f32_fp8_e32 v[230:231], v190
	v_pk_fma_f32 v[216:217], v[224:225], v[104:105], v[216:217]
	v_pk_fma_f32 v[218:219], v[226:227], v[104:105], v[218:219]
	v_pk_fma_f32 v[220:221], v[228:229], v[104:105], v[220:221]
	v_pk_fma_f32 v[222:223], v[230:231], v[104:105], v[222:223]
	v_cvt_pk_f32_fp8_sdwa v[224:225], v178 src0_sel:WORD_1
	v_cvt_pk_f32_fp8_sdwa v[226:227], v182 src0_sel:WORD_1
	v_cvt_pk_f32_fp8_sdwa v[228:229], v186 src0_sel:WORD_1
	v_cvt_pk_f32_fp8_sdwa v[230:231], v190 src0_sel:WORD_1
	v_pk_fma_f32 v[216:217], v[224:225], v[106:107], v[216:217]
	v_pk_fma_f32 v[218:219], v[226:227], v[106:107], v[218:219]
	v_pk_fma_f32 v[220:221], v[228:229], v[106:107], v[220:221]
	v_pk_fma_f32 v[222:223], v[230:231], v[106:107], v[222:223]
	v_cvt_pk_f32_fp8_e32 v[224:225], v179
	v_cvt_pk_f32_fp8_e32 v[226:227], v183
	v_cvt_pk_f32_fp8_e32 v[228:229], v187
	v_cvt_pk_f32_fp8_e32 v[230:231], v191
	v_pk_fma_f32 v[216:217], v[224:225], v[108:109], v[216:217]
	v_pk_fma_f32 v[218:219], v[226:227], v[108:109], v[218:219]
	v_pk_fma_f32 v[220:221], v[228:229], v[108:109], v[220:221]
	v_pk_fma_f32 v[222:223], v[230:231], v[108:109], v[222:223]
	v_cvt_pk_f32_fp8_sdwa v[224:225], v179 src0_sel:WORD_1
	v_cvt_pk_f32_fp8_sdwa v[226:227], v183 src0_sel:WORD_1
	v_cvt_pk_f32_fp8_sdwa v[228:229], v187 src0_sel:WORD_1
	v_cvt_pk_f32_fp8_sdwa v[230:231], v191 src0_sel:WORD_1
	v_pk_fma_f32 v[216:217], v[224:225], v[110:111], v[216:217]
	v_pk_fma_f32 v[218:219], v[226:227], v[110:111], v[218:219]
	v_pk_fma_f32 v[220:221], v[228:229], v[110:111], v[220:221]
	v_pk_fma_f32 v[222:223], v[230:231], v[110:111], v[222:223]
	v_add_f32_e32 v204, v216, v217
	v_add_f32_e32 v205, v218, v219
	v_add_f32_e32 v206, v220, v221
	v_add_f32_e32 v207, v222, v223
	s_nop 0
	v_permlane32_swap_b32_e32 v192, v200
	v_permlane32_swap_b32_e32 v193, v201
	v_permlane32_swap_b32_e32 v194, v202
	v_permlane32_swap_b32_e32 v195, v203
	v_permlane32_swap_b32_e32 v196, v204
	v_permlane32_swap_b32_e32 v197, v205
	v_permlane32_swap_b32_e32 v198, v206
	v_permlane32_swap_b32_e32 v199, v207
	v_add_f32_e32 v192, v192, v200
	v_add_f32_e32 v193, v193, v201
	v_add_f32_e32 v194, v194, v202
	v_add_f32_e32 v195, v195, v203
	v_add_f32_e32 v196, v196, v204
	v_add_f32_e32 v197, v197, v205
	v_add_f32_e32 v198, v198, v206
	v_add_f32_e32 v199, v199, v207
	v_permlane16_swap_b32_e32 v192, v196
	v_permlane16_swap_b32_e32 v193, v197
	v_permlane16_swap_b32_e32 v194, v198
	v_permlane16_swap_b32_e32 v195, v199
	v_add_f32_e32 v192, v192, v196
	v_add_f32_e32 v193, v193, v197
	v_add_f32_e32 v194, v194, v198
	v_add_f32_e32 v195, v195, v199
	v_add_f32_dpp v216, v192, v192 row_ror:8 row_mask:0xf bank_mask:0xf
	v_add_f32_dpp v218, v194, v194 row_ror:8 row_mask:0xf bank_mask:0xf
	v_add_f32_dpp v216, v193, v193 row_ror:8 row_mask:0xf bank_mask:0xc
	v_add_f32_dpp v218, v195, v195 row_ror:8 row_mask:0xf bank_mask:0xc
	s_nop 1
	v_add_f32_dpp v220, v216, v216 row_half_mirror row_mask:0xf bank_mask:0xf
	v_add_f32_dpp v220, v218, v218 row_half_mirror row_mask:0xf bank_mask:0xa
	s_nop 1
	v_add_f32_dpp v220, v220, v220 quad_perm:[1,0,3,2] row_mask:0xf bank_mask:0xf
	s_nop 1
	v_add_f32_dpp v220, v220, v220 quad_perm:[2,3,0,1] row_mask:0xf bank_mask:0xf
	v_mul_f32_e32 v216, v252, v220
	v_fma_f32 v218, |v216|, s72, 1.0
	v_mul_f32_e32 v222, v216, v216
	v_rcp_f32_e32 v218, v218
	v_mul_f32_e32 v222, 0xbf38aa3b, v222
	v_exp_f32_e32 v222, v222
	v_fmamk_f32 v224, v218, 0x3f07dc22, v242
	v_fmaak_f32 v224, v218, v224, 0x3f35f0e3
	v_fmaak_f32 v224, v218, v224, 0xbe11a98e
	v_fmaak_f32 v224, v218, v224, 0x3e027906
	v_mul_f32_e32 v224, v218, v224
	v_mul_f32_e32 v224, v222, v224
	v_mul_f32_e32 v226, v216, v224
	v_fma_f32 v224, -v216, v224, v216
	v_cmp_gt_f32_e32 vcc, 0, v216
	s_nop 1
	v_cndmask_b32_e32 v224, v224, v226, vcc
	v_mul_f32_e32 v224, v249, v224
	v_mul_f32_e32 v224, v253, v224
	ds_write_b32 v211, v224 offset:4864
	v_add_u32_e32 v211, 64, v211
	v_add_u32_e32 v213, 64, v213
	ds_read_b32 v248, v211
	ds_read_b32 v249, v211 offset:4864
	s_add_i32 s21, s21, 4
	s_sub_i32 s90, s90, 1
	s_cmp_eq_u32 s90, 0
	s_cbranch_scc1 .LU_sw0
	s_branch .LU_t6_s0
.LU_t7_s0:
	s_cmp_ge_u32 s21, s20
	s_cbranch_scc1 .LU_done
	s_waitcnt lgkmcnt(0)
	v_add_u32_e32 v236, v232, v240
	v_add_u32_e32 v237, v233, v240
	v_add_u32_e32 v238, v234, v240
	v_add_u32_e32 v239, v235, v240
	v_lshrrev_b32_e32 v208, 8, v248
	global_load_dword v252, v208, s[8:9]
	global_load_dword v253, v208, s[52:53]
	global_load_dwordx4 v[176:179], v236, s[4:5]
	global_load_dwordx4 v[180:183], v237, s[4:5]
	global_load_dwordx4 v[184:187], v238, s[4:5]
	global_load_dwordx4 v[188:191], v239, s[4:5]
	ds_read_b128 v[232:235], v213 offset:64
	s_waitcnt vmcnt(14)
	v_cvt_pk_f32_fp8_e32 v[224:225], v128
	v_cvt_pk_f32_fp8_e32 v[226:227], v132
	v_cvt_pk_f32_fp8_e32 v[228:229], v136
	v_cvt_pk_f32_fp8_e32 v[230:231], v140
	v_pk_mul_f32 v[216:217], v[224:225], v[112:113]
	v_pk_mul_f32 v[218:219], v[226:227], v[112:113]
	v_pk_mul_f32 v[220:221], v[228:229], v[112:113]
	v_pk_mul_f32 v[222:223], v[230:231], v[112:113]
	v_cvt_pk_f32_fp8_sdwa v[224:225], v128 src0_sel:WORD_1
	v_cvt_pk_f32_fp8_sdwa v[226:227], v132 src0_sel:WORD_1
	v_cvt_pk_f32_fp8_sdwa v[228:229], v136 src0_sel:WORD_1
	v_cvt_pk_f32_fp8_sdwa v[230:231], v140 src0_sel:WORD_1
	v_pk_fma_f32 v[216:217], v[224:225], v[114:115], v[216:217]
	v_pk_fma_f32 v[218:219], v[226:227], v[114:115], v[218:219]
	v_pk_fma_f32 v[220:221], v[228:229], v[114:115], v[220:221]
	v_pk_fma_f32 v[222:223], v[230:231], v[114:115], v[222:223]
	v_cvt_pk_f32_fp8_e32 v[224:225], v129
	v_cvt_pk_f32_fp8_e32 v[226:227], v133
	v_cvt_pk_f32_fp8_e32 v[228:229], v137
	v_cvt_pk_f32_fp8_e32 v[230:231], v141
	v_pk_fma_f32 v[216:217], v[224:225], v[116:117], v[216:217]
	v_pk_fma_f32 v[218:219], v[226:227], v[116:117], v[218:219]
	v_pk_fma_f32 v[220:221], v[228:229], v[116:117], v[220:221]
	v_pk_fma_f32 v[222:223], v[230:231], v[116:117], v[222:223]
	v_cvt_pk_f32_fp8_sdwa v[224:225], v129 src0_sel:WORD_1
	v_cvt_pk_f32_fp8_sdwa v[226:227], v133 src0_sel:WORD_1
	v_cvt_pk_f32_fp8_sdwa v[228:229], v137 src0_sel:WORD_1
	v_cvt_pk_f32_fp8_sdwa v[230:231], v141 src0_sel:WORD_1
	v_pk_fma_f32 v[216:217], v[224:225], v[118:119], v[216:217]
	v_pk_fma_f32 v[218:219], v[226:227], v[118:119], v[218:219]
	v_pk_fma_f32 v[220:221], v[228:229], v[118:119], v[220:221]
	v_pk_fma_f32 v[222:223], v[230:231], v[118:119], v[222:223]
	v_cvt_pk_f32_fp8_e32 v[224:225], v130
	v_cvt_pk_f32_fp8_e32 v[226:227], v134
	v_cvt_pk_f32_fp8_e32 v[228:229], v138
	v_cvt_pk_f32_fp8_e32 v[230:231], v142
	v_pk_fma_f32 v[216:217], v[224:225], v[120:121], v[216:217]
	v_pk_fma_f32 v[218:219], v[226:227], v[120:121], v[218:219]
	v_pk_fma_f32 v[220:221], v[228:229], v[120:121], v[220:221]
	v_pk_fma_f32 v[222:223], v[230:231], v[120:121], v[222:223]
	v_cvt_pk_f32_fp8_sdwa v[224:225], v130 src0_sel:WORD_1
	v_cvt_pk_f32_fp8_sdwa v[226:227], v134 src0_sel:WORD_1
	v_cvt_pk_f32_fp8_sdwa v[228:229], v138 src0_sel:WORD_1
	v_cvt_pk_f32_fp8_sdwa v[230:231], v142 src0_sel:WORD_1
	v_pk_fma_f32 v[216:217], v[224:225], v[122:123], v[216:217]
	v_pk_fma_f32 v[218:219], v[226:227], v[122:123], v[218:219]
	v_pk_fma_f32 v[220:221], v[228:229], v[122:123], v[220:221]
	v_pk_fma_f32 v[222:223], v[230:231], v[122:123], v[222:223]
	v_cvt_pk_f32_fp8_e32 v[224:225], v131
	v_cvt_pk_f32_fp8_e32 v[226:227], v135
	v_cvt_pk_f32_fp8_e32 v[228:229], v139
	v_cvt_pk_f32_fp8_e32 v[230:231], v143
	v_pk_fma_f32 v[216:217], v[224:225], v[124:125], v[216:217]
	v_pk_fma_f32 v[218:219], v[226:227], v[124:125], v[218:219]
	v_pk_fma_f32 v[220:221], v[228:229], v[124:125], v[220:221]
	v_pk_fma_f32 v[222:223], v[230:231], v[124:125], v[222:223]
	v_cvt_pk_f32_fp8_sdwa v[224:225], v131 src0_sel:WORD_1
	v_cvt_pk_f32_fp8_sdwa v[226:227], v135 src0_sel:WORD_1
	v_cvt_pk_f32_fp8_sdwa v[228:229], v139 src0_sel:WORD_1
	v_cvt_pk_f32_fp8_sdwa v[230:231], v143 src0_sel:WORD_1
	v_pk_fma_f32 v[216:217], v[224:225], v[126:127], v[216:217]
	v_pk_fma_f32 v[218:219], v[226:227], v[126:127], v[218:219]
	v_pk_fma_f32 v[220:221], v[228:229], v[126:127], v[220:221]
	v_pk_fma_f32 v[222:223], v[230:231], v[126:127], v[222:223]
	v_add_f32_e32 v192, v216, v217
	v_add_f32_e32 v193, v218, v219
	v_add_f32_e32 v194, v220, v221
	v_add_f32_e32 v195, v222, v223
	s_sub_i32 s90, s90, 1
	s_cmp_eq_u32 s90, 0
	s_cbranch_scc1 .LU_sw1
.LU_t7_s1:
	s_waitcnt lgkmcnt(0)
	v_add_u32_e32 v236, v232, v240
	v_add_u32_e32 v237, v233, v240
	v_add_u32_e32 v238, v234, v240
	v_add_u32_e32 v239, v235, v240
	global_load_dwordx4 v[128:131], v236, s[4:5]
	global_load_dwordx4 v[132:135], v237, s[4:5]
	global_load_dwordx4 v[136:139], v238, s[4:5]
	global_load_dwordx4 v[140:143], v239, s[4:5]
	ds_read_b128 v[232:235], v213 offset:80
	s_waitcnt vmcnt(14)
	v_cvt_pk_f32_fp8_e32 v[224:225], v144
	v_cvt_pk_f32_fp8_e32 v[226:227], v148
	v_cvt_pk_f32_fp8_e32 v[228:229], v152
	v_cvt_pk_f32_fp8_e32 v[230:231], v156
	v_pk_mul_f32 v[216:217], v[224:225], v[112:113]
	v_pk_mul_f32 v[218:219], v[226:227], v[112:113]
	v_pk_mul_f32 v[220:221], v[228:229], v[112:113]
	v_pk_mul_f32 v[222:223], v[230:231], v[112:113]
	v_cvt_pk_f32_fp8_sdwa v[224:225], v144 src0_sel:WORD_1
	v_cvt_pk_f32_fp8_sdwa v[226:227], v148 src0_sel:WORD_1
	v_cvt_pk_f32_fp8_sdwa v[228:229], v152 src0_sel:WORD_1
	v_cvt_pk_f32_fp8_sdwa v[230:231], v156 src0_sel:WORD_1
	v_pk_fma_f32 v[216:217], v[224:225], v[114:115], v[216:217]
	v_pk_fma_f32 v[218:219], v[226:227], v[114:115], v[218:219]
	v_pk_fma_f32 v[220:221], v[228:229], v[114:115], v[220:221]
	v_pk_fma_f32 v[222:223], v[230:231], v[114:115], v[222:223]
	v_cvt_pk_f32_fp8_e32 v[224:225], v145
	v_cvt_pk_f32_fp8_e32 v[226:227], v149
	v_cvt_pk_f32_fp8_e32 v[228:229], v153
	v_cvt_pk_f32_fp8_e32 v[230:231], v157
	v_pk_fma_f32 v[216:217], v[224:225], v[116:117], v[216:217]
	v_pk_fma_f32 v[218:219], v[226:227], v[116:117], v[218:219]
	v_pk_fma_f32 v[220:221], v[228:229], v[116:117], v[220:221]
	v_pk_fma_f32 v[222:223], v[230:231], v[116:117], v[222:223]
	v_cvt_pk_f32_fp8_sdwa v[224:225], v145 src0_sel:WORD_1
	v_cvt_pk_f32_fp8_sdwa v[226:227], v149 src0_sel:WORD_1
	v_cvt_pk_f32_fp8_sdwa v[228:229], v153 src0_sel:WORD_1
	v_cvt_pk_f32_fp8_sdwa v[230:231], v157 src0_sel:WORD_1
	v_pk_fma_f32 v[216:217], v[224:225], v[118:119], v[216:217]
	v_pk_fma_f32 v[218:219], v[226:227], v[118:119], v[218:219]
	v_pk_fma_f32 v[220:221], v[228:229], v[118:119], v[220:221]
	v_pk_fma_f32 v[222:223], v[230:231], v[118:119], v[222:223]
	v_cvt_pk_f32_fp8_e32 v[224:225], v146
	v_cvt_pk_f32_fp8_e32 v[226:227], v150
	v_cvt_pk_f32_fp8_e32 v[228:229], v154
	v_cvt_pk_f32_fp8_e32 v[230:231], v158
	v_pk_fma_f32 v[216:217], v[224:225], v[120:121], v[216:217]
	v_pk_fma_f32 v[218:219], v[226:227], v[120:121], v[218:219]
	v_pk_fma_f32 v[220:221], v[228:229], v[120:121], v[220:221]
	v_pk_fma_f32 v[222:223], v[230:231], v[120:121], v[222:223]
	v_cvt_pk_f32_fp8_sdwa v[224:225], v146 src0_sel:WORD_1
	v_cvt_pk_f32_fp8_sdwa v[226:227], v150 src0_sel:WORD_1
	v_cvt_pk_f32_fp8_sdwa v[228:229], v154 src0_sel:WORD_1
	v_cvt_pk_f32_fp8_sdwa v[230:231], v158 src0_sel:WORD_1
	v_pk_fma_f32 v[216:217], v[224:225], v[122:123], v[216:217]
	v_pk_fma_f32 v[218:219], v[226:227], v[122:123], v[218:219]
	v_pk_fma_f32 v[220:221], v[228:229], v[122:123], v[220:221]
	v_pk_fma_f32 v[222:223], v[230:231], v[122:123], v[222:223]
	v_cvt_pk_f32_fp8_e32 v[224:225], v147
	v_cvt_pk_f32_fp8_e32 v[226:227], v151
	v_cvt_pk_f32_fp8_e32 v[228:229], v155
	v_cvt_pk_f32_fp8_e32 v[230:231], v159
	v_pk_fma_f32 v[216:217], v[224:225], v[124:125], v[216:217]
	v_pk_fma_f32 v[218:219], v[226:227], v[124:125], v[218:219]
	v_pk_fma_f32 v[220:221], v[228:229], v[124:125], v[220:221]
	v_pk_fma_f32 v[222:223], v[230:231], v[124:125], v[222:223]
	v_cvt_pk_f32_fp8_sdwa v[224:225], v147 src0_sel:WORD_1
	v_cvt_pk_f32_fp8_sdwa v[226:227], v151 src0_sel:WORD_1
	v_cvt_pk_f32_fp8_sdwa v[228:229], v155 src0_sel:WORD_1
	v_cvt_pk_f32_fp8_sdwa v[230:231], v159 src0_sel:WORD_1
	v_pk_fma_f32 v[216:217], v[224:225], v[126:127], v[216:217]
	v_pk_fma_f32 v[218:219], v[226:227], v[126:127], v[218:219]
	v_pk_fma_f32 v[220:221], v[228:229], v[126:127], v[220:221]
	v_pk_fma_f32 v[222:223], v[230:231], v[126:127], v[222:223]
	v_add_f32_e32 v196, v216, v217
	v_add_f32_e32 v197, v218, v219
	v_add_f32_e32 v198, v220, v221
	v_add_f32_e32 v199, v222, v223
	s_sub_i32 s90, s90, 1
	s_cmp_eq_u32 s90, 0
	s_cbranch_scc1 .LU_sw2
.LU_t7_s2:
	s_waitcnt lgkmcnt(0)
	v_add_u32_e32 v236, v232, v240
	v_add_u32_e32 v237, v233, v240
	v_add_u32_e32 v238, v234, v240
	v_add_u32_e32 v239, v235, v240
	global_load_dwordx4 v[144:147], v236, s[4:5]
	global_load_dwordx4 v[148:151], v237, s[4:5]
	global_load_dwordx4 v[152:155], v238, s[4:5]
	global_load_dwordx4 v[156:159], v239, s[4:5]
	ds_read_b128 v[232:235], v213 offset:96
	s_waitcnt vmcnt(14)
	v_cvt_pk_f32_fp8_e32 v[224:225], v160
	v_cvt_pk_f32_fp8_e32 v[226:227], v164
	v_cvt_pk_f32_fp8_e32 v[228:229], v168
	v_cvt_pk_f32_fp8_e32 v[230:231], v172
	v_pk_mul_f32 v[216:217], v[224:225], v[112:113]
	v_pk_mul_f32 v[218:219], v[226:227], v[112:113]
	v_pk_mul_f32 v[220:221], v[228:229], v[112:113]
	v_pk_mul_f32 v[222:223], v[230:231], v[112:113]
	v_cvt_pk_f32_fp8_sdwa v[224:225], v160 src0_sel:WORD_1
	v_cvt_pk_f32_fp8_sdwa v[226:227], v164 src0_sel:WORD_1
	v_cvt_pk_f32_fp8_sdwa v[228:229], v168 src0_sel:WORD_1
	v_cvt_pk_f32_fp8_sdwa v[230:231], v172 src0_sel:WORD_1
	v_pk_fma_f32 v[216:217], v[224:225], v[114:115], v[216:217]
	v_pk_fma_f32 v[218:219], v[226:227], v[114:115], v[218:219]
	v_pk_fma_f32 v[220:221], v[228:229], v[114:115], v[220:221]
	v_pk_fma_f32 v[222:223], v[230:231], v[114:115], v[222:223]
	v_cvt_pk_f32_fp8_e32 v[224:225], v161
	v_cvt_pk_f32_fp8_e32 v[226:227], v165
	v_cvt_pk_f32_fp8_e32 v[228:229], v169
	v_cvt_pk_f32_fp8_e32 v[230:231], v173
	v_pk_fma_f32 v[216:217], v[224:225], v[116:117], v[216:217]
	v_pk_fma_f32 v[218:219], v[226:227], v[116:117], v[218:219]
	v_pk_fma_f32 v[220:221], v[228:229], v[116:117], v[220:221]
	v_pk_fma_f32 v[222:223], v[230:231], v[116:117], v[222:223]
	v_cvt_pk_f32_fp8_sdwa v[224:225], v161 src0_sel:WORD_1
	v_cvt_pk_f32_fp8_sdwa v[226:227], v165 src0_sel:WORD_1
	v_cvt_pk_f32_fp8_sdwa v[228:229], v169 src0_sel:WORD_1
	v_cvt_pk_f32_fp8_sdwa v[230:231], v173 src0_sel:WORD_1
	v_pk_fma_f32 v[216:217], v[224:225], v[118:119], v[216:217]
	v_pk_fma_f32 v[218:219], v[226:227], v[118:119], v[218:219]
	v_pk_fma_f32 v[220:221], v[228:229], v[118:119], v[220:221]
	v_pk_fma_f32 v[222:223], v[230:231], v[118:119], v[222:223]
	v_cvt_pk_f32_fp8_e32 v[224:225], v162
	v_cvt_pk_f32_fp8_e32 v[226:227], v166
	v_cvt_pk_f32_fp8_e32 v[228:229], v170
	v_cvt_pk_f32_fp8_e32 v[230:231], v174
	v_pk_fma_f32 v[216:217], v[224:225], v[120:121], v[216:217]
	v_pk_fma_f32 v[218:219], v[226:227], v[120:121], v[218:219]
	v_pk_fma_f32 v[220:221], v[228:229], v[120:121], v[220:221]
	v_pk_fma_f32 v[222:223], v[230:231], v[120:121], v[222:223]
	v_cvt_pk_f32_fp8_sdwa v[224:225], v162 src0_sel:WORD_1
	v_cvt_pk_f32_fp8_sdwa v[226:227], v166 src0_sel:WORD_1
	v_cvt_pk_f32_fp8_sdwa v[228:229], v170 src0_sel:WORD_1
	v_cvt_pk_f32_fp8_sdwa v[230:231], v174 src0_sel:WORD_1
	v_pk_fma_f32 v[216:217], v[224:225], v[122:123], v[216:217]
	v_pk_fma_f32 v[218:219], v[226:227], v[122:123], v[218:219]
	v_pk_fma_f32 v[220:221], v[228:229], v[122:123], v[220:221]
	v_pk_fma_f32 v[222:223], v[230:231], v[122:123], v[222:223]
	v_cvt_pk_f32_fp8_e32 v[224:225], v163
	v_cvt_pk_f32_fp8_e32 v[226:227], v167
	v_cvt_pk_f32_fp8_e32 v[228:229], v171
	v_cvt_pk_f32_fp8_e32 v[230:231], v175
	v_pk_fma_f32 v[216:217], v[224:225], v[124:125], v[216:217]
	v_pk_fma_f32 v[218:219], v[226:227], v[124:125], v[218:219]
	v_pk_fma_f32 v[220:221], v[228:229], v[124:125], v[220:221]
	v_pk_fma_f32 v[222:223], v[230:231], v[124:125], v[222:223]
	v_cvt_pk_f32_fp8_sdwa v[224:225], v163 src0_sel:WORD_1
	v_cvt_pk_f32_fp8_sdwa v[226:227], v167 src0_sel:WORD_1
	v_cvt_pk_f32_fp8_sdwa v[228:229], v171 src0_sel:WORD_1
	v_cvt_pk_f32_fp8_sdwa v[230:231], v175 src0_sel:WORD_1
	v_pk_fma_f32 v[216:217], v[224:225], v[126:127], v[216:217]
	v_pk_fma_f32 v[218:219], v[226:227], v[126:127], v[218:219]
	v_pk_fma_f32 v[220:221], v[228:229], v[126:127], v[220:221]
	v_pk_fma_f32 v[222:223], v[230:231], v[126:127], v[222:223]
	v_add_f32_e32 v200, v216, v217
	v_add_f32_e32 v201, v218, v219
	v_add_f32_e32 v202, v220, v221
	v_add_f32_e32 v203, v222, v223
	s_sub_i32 s90, s90, 1
	s_cmp_eq_u32 s90, 0
	s_cbranch_scc1 .LU_sw3
; __device__ __forceinline__ void peer_tile(const Args& A, LAS unsigned char* lds, int tile) {
;     ...
;         for (int p = 0; p < 16; ++p) {
; #pragma unroll
;             for (int tk = 0; tk < 4; ++tk) {
;                 const int tl = tb + tk;
;                 const int beg = __builtin_amdgcn_readfirstlane(OFFS[tl * 17 + p]), end = __builtin_amdgcn_readfirstlane(OFFS[tl * 17 + p + 1]);
.LU_t7_s3:
	s_waitcnt lgkmcnt(0)
	v_add_u32_e32 v236, v232, v240
	v_add_u32_e32 v237, v233, v240
	v_add_u32_e32 v238, v234, v240
	v_add_u32_e32 v239, v235, v240
	global_load_dwordx4 v[160:163], v236, s[4:5]
	global_load_dwordx4 v[164:167], v237, s[4:5]
	global_load_dwordx4 v[168:171], v238, s[4:5]
	global_load_dwordx4 v[172:175], v239, s[4:5]
	ds_read_b128 v[232:235], v213 offset:112
	s_waitcnt vmcnt(12)
	v_cvt_pk_f32_fp8_e32 v[224:225], v176
	v_cvt_pk_f32_fp8_e32 v[226:227], v180
	v_cvt_pk_f32_fp8_e32 v[228:229], v184
	v_cvt_pk_f32_fp8_e32 v[230:231], v188
	v_pk_mul_f32 v[216:217], v[224:225], v[112:113]
	v_pk_mul_f32 v[218:219], v[226:227], v[112:113]
	v_pk_mul_f32 v[220:221], v[228:229], v[112:113]
	v_pk_mul_f32 v[222:223], v[230:231], v[112:113]
	v_cvt_pk_f32_fp8_sdwa v[224:225], v176 src0_sel:WORD_1
	v_cvt_pk_f32_fp8_sdwa v[226:227], v180 src0_sel:WORD_1
	v_cvt_pk_f32_fp8_sdwa v[228:229], v184 src0_sel:WORD_1
	v_cvt_pk_f32_fp8_sdwa v[230:231], v188 src0_sel:WORD_1
	v_pk_fma_f32 v[216:217], v[224:225], v[114:115], v[216:217]
	v_pk_fma_f32 v[218:219], v[226:227], v[114:115], v[218:219]
	v_pk_fma_f32 v[220:221], v[228:229], v[114:115], v[220:221]
	v_pk_fma_f32 v[222:223], v[230:231], v[114:115], v[222:223]
	v_cvt_pk_f32_fp8_e32 v[224:225], v177
	v_cvt_pk_f32_fp8_e32 v[226:227], v181
	v_cvt_pk_f32_fp8_e32 v[228:229], v185
	v_cvt_pk_f32_fp8_e32 v[230:231], v189
	v_pk_fma_f32 v[216:217], v[224:225], v[116:117], v[216:217]
	v_pk_fma_f32 v[218:219], v[226:227], v[116:117], v[218:219]
	v_pk_fma_f32 v[220:221], v[228:229], v[116:117], v[220:221]
	v_pk_fma_f32 v[222:223], v[230:231], v[116:117], v[222:223]
	v_cvt_pk_f32_fp8_sdwa v[224:225], v177 src0_sel:WORD_1
	v_cvt_pk_f32_fp8_sdwa v[226:227], v181 src0_sel:WORD_1
	v_cvt_pk_f32_fp8_sdwa v[228:229], v185 src0_sel:WORD_1
	v_cvt_pk_f32_fp8_sdwa v[230:231], v189 src0_sel:WORD_1
	v_pk_fma_f32 v[216:217], v[224:225], v[118:119], v[216:217]
	v_pk_fma_f32 v[218:219], v[226:227], v[118:119], v[218:219]
	v_pk_fma_f32 v[220:221], v[228:229], v[118:119], v[220:221]
	v_pk_fma_f32 v[222:223], v[230:231], v[118:119], v[222:223]
	v_cvt_pk_f32_fp8_e32 v[224:225], v178
	v_cvt_pk_f32_fp8_e32 v[226:227], v182
	v_cvt_pk_f32_fp8_e32 v[228:229], v186
	v_cvt_pk_f32_fp8_e32 v[230:231], v190
	v_pk_fma_f32 v[216:217], v[224:225], v[120:121], v[216:217]
	v_pk_fma_f32 v[218:219], v[226:227], v[120:121], v[218:219]
	v_pk_fma_f32 v[220:221], v[228:229], v[120:121], v[220:221]
	v_pk_fma_f32 v[222:223], v[230:231], v[120:121], v[222:223]
	v_cvt_pk_f32_fp8_sdwa v[224:225], v178 src0_sel:WORD_1
	v_cvt_pk_f32_fp8_sdwa v[226:227], v182 src0_sel:WORD_1
	v_cvt_pk_f32_fp8_sdwa v[228:229], v186 src0_sel:WORD_1
	v_cvt_pk_f32_fp8_sdwa v[230:231], v190 src0_sel:WORD_1
	v_pk_fma_f32 v[216:217], v[224:225], v[122:123], v[216:217]
	v_pk_fma_f32 v[218:219], v[226:227], v[122:123], v[218:219]
	v_pk_fma_f32 v[220:221], v[228:229], v[122:123], v[220:221]
	v_pk_fma_f32 v[222:223], v[230:231], v[122:123], v[222:223]
	v_cvt_pk_f32_fp8_e32 v[224:225], v179
	v_cvt_pk_f32_fp8_e32 v[226:227], v183
	v_cvt_pk_f32_fp8_e32 v[228:229], v187
	v_cvt_pk_f32_fp8_e32 v[230:231], v191
	v_pk_fma_f32 v[216:217], v[224:225], v[124:125], v[216:217]
	v_pk_fma_f32 v[218:219], v[226:227], v[124:125], v[218:219]
	v_pk_fma_f32 v[220:221], v[228:229], v[124:125], v[220:221]
	v_pk_fma_f32 v[222:223], v[230:231], v[124:125], v[222:223]
	v_cvt_pk_f32_fp8_sdwa v[224:225], v179 src0_sel:WORD_1
	v_cvt_pk_f32_fp8_sdwa v[226:227], v183 src0_sel:WORD_1
	v_cvt_pk_f32_fp8_sdwa v[228:229], v187 src0_sel:WORD_1
	v_cvt_pk_f32_fp8_sdwa v[230:231], v191 src0_sel:WORD_1
	v_pk_fma_f32 v[216:217], v[224:225], v[126:127], v[216:217]
	v_pk_fma_f32 v[218:219], v[226:227], v[126:127], v[218:219]
	v_pk_fma_f32 v[220:221], v[228:229], v[126:127], v[220:221]
	v_pk_fma_f32 v[222:223], v[230:231], v[126:127], v[222:223]
	v_add_f32_e32 v204, v216, v217
	v_add_f32_e32 v205, v218, v219
	v_add_f32_e32 v206, v220, v221
	v_add_f32_e32 v207, v222, v223
	s_nop 0
	v_permlane32_swap_b32_e32 v192, v200
	v_permlane32_swap_b32_e32 v193, v201
	v_permlane32_swap_b32_e32 v194, v202
	v_permlane32_swap_b32_e32 v195, v203
	v_permlane32_swap_b32_e32 v196, v204
	v_permlane32_swap_b32_e32 v197, v205
	v_permlane32_swap_b32_e32 v198, v206
	v_permlane32_swap_b32_e32 v199, v207
	v_add_f32_e32 v192, v192, v200
	v_add_f32_e32 v193, v193, v201
	v_add_f32_e32 v194, v194, v202
	v_add_f32_e32 v195, v195, v203
	v_add_f32_e32 v196, v196, v204
	v_add_f32_e32 v197, v197, v205
	v_add_f32_e32 v198, v198, v206
	v_add_f32_e32 v199, v199, v207
	v_permlane16_swap_b32_e32 v192, v196
	v_permlane16_swap_b32_e32 v193, v197
	v_permlane16_swap_b32_e32 v194, v198
	v_permlane16_swap_b32_e32 v195, v199
	v_add_f32_e32 v192, v192, v196
	v_add_f32_e32 v193, v193, v197
	v_add_f32_e32 v194, v194, v198
	v_add_f32_e32 v195, v195, v199
	v_add_f32_dpp v216, v192, v192 row_ror:8 row_mask:0xf bank_mask:0xf
	v_add_f32_dpp v218, v194, v194 row_ror:8 row_mask:0xf bank_mask:0xf
	v_add_f32_dpp v216, v193, v193 row_ror:8 row_mask:0xf bank_mask:0xc
	v_add_f32_dpp v218, v195, v195 row_ror:8 row_mask:0xf bank_mask:0xc
	s_nop 1
	v_add_f32_dpp v220, v216, v216 row_half_mirror row_mask:0xf bank_mask:0xf
	v_add_f32_dpp v220, v218, v218 row_half_mirror row_mask:0xf bank_mask:0xa
	s_nop 1
	v_add_f32_dpp v220, v220, v220 quad_perm:[1,0,3,2] row_mask:0xf bank_mask:0xf
	s_nop 1
	v_add_f32_dpp v220, v220, v220 quad_perm:[2,3,0,1] row_mask:0xf bank_mask:0xf
	v_mul_f32_e32 v216, v252, v220
	v_fma_f32 v218, |v216|, s72, 1.0
	v_mul_f32_e32 v222, v216, v216
	v_rcp_f32_e32 v218, v218
	v_mul_f32_e32 v222, 0xbf38aa3b, v222
	v_exp_f32_e32 v222, v222
	v_fmamk_f32 v224, v218, 0x3f07dc22, v242
	v_fmaak_f32 v224, v218, v224, 0x3f35f0e3
	v_fmaak_f32 v224, v218, v224, 0xbe11a98e
	v_fmaak_f32 v224, v218, v224, 0x3e027906
	v_mul_f32_e32 v224, v218, v224
	v_mul_f32_e32 v224, v222, v224
	v_mul_f32_e32 v226, v216, v224
	v_fma_f32 v224, -v216, v224, v216
	v_cmp_gt_f32_e32 vcc, 0, v216
	s_nop 1
	v_cndmask_b32_e32 v224, v224, v226, vcc
	v_mul_f32_e32 v224, v249, v224
	v_mul_f32_e32 v224, v253, v224
	ds_write_b32 v211, v224 offset:4864
	v_add_u32_e32 v211, 64, v211
	v_add_u32_e32 v213, 64, v213
	ds_read_b32 v248, v211
	ds_read_b32 v249, v211 offset:4864
	s_add_i32 s21, s21, 4
	s_sub_i32 s90, s90, 1
	s_cmp_eq_u32 s90, 0
	s_cbranch_scc1 .LU_sw0
	s_branch .LU_t7_s0
.LU_sw0:
	s_add_i32 s89, s89, 1
	s_cmp_ge_u32 s89, 32
	s_cbranch_scc1 .LU_sw0_end
	s_nop 0
	v_readlane_b32 s90, v212, s89
	s_and_b32 s23, s89, 7
	s_cmp_eq_u32 s90, 0
	s_cbranch_scc1 .LU_sw0
	s_cmp_ge_u32 s23, 4
	s_cbranch_scc1 .LU_sw0_h
	s_cmp_ge_u32 s23, 2
	s_cbranch_scc1 .LU_sw0_23
	s_cmp_eq_u32 s23, 0
	s_cbranch_scc1 .LU_t0_s0
	s_branch .LU_t1_s0

; __device__ __forceinline__ void peer_tile(const Args& A, LAS unsigned char* lds, int tile) {
;     ...
;         for (int p = 0; p < 16; ++p) {
; #pragma unroll
;             for (int tk = 0; tk < 4; ++tk) {
;                 const int tl = tb + tk;
;                 const int beg = __builtin_amdgcn_readfirstlane(OFFS[tl * 17 + p]), end = __builtin_amdgcn_readfirstlane(OFFS[tl * 17 + p + 1]);
.LU_sw0_end:
	s_mov_b32 s90, 0x7fffffff
	s_branch .LU_t0_s0

; #define IT_ADVANCE() do { it_j += 4; while (it_j >= it_end) { if (it_done) break; ++it_tk; if (it_tk == 4) { it_tk = 0; ++it_p; if (it_p == 16) { it_done = true; it_p = 15; it_j = 0; it_end = 1; break; } } \
;             it_j = __builtin_amdgcn_readfirstlane(OFFS[(tb + it_tk) * 17 + it_p]); it_end = __builtin_amdgcn_readfirstlane(OFFS[(tb + it_tk) * 17 + it_p + 1]); } } while (0)
; __device__ __forceinline__ void peer_tile(const Args& A, LAS unsigned char* lds, int tile) {
;     ...
;             for (int q = 0; q < 8; ++q) oacc[tk][q] = (f32x2){0.f, 0.f}; }
;         int it_p = 0, it_tk = -1, it_j = 0, it_end = 0; bool it_done = false;
;     ...
;         u32x4 uA[4], vA[4], uB[4], vB[4]; float cgA = 0.f, suA = 0.f, svA = 0.f, cgB = 0.f, suB = 0.f, svB = 0.f;
; #pragma unroll
;         for (int k = 0; k < 4; ++k) { uA[k] = (u32x4){0u, 0u, 0u, 0u}; vA[k] = uA[k]; uB[k] = uA[k]; vB[k] = uA[k]; }
;         IT_ADVANCE();
;         LOAD_SET(uA, vA, cgA, suA, svA);
.LU_done:
	s_waitcnt vmcnt(0) lgkmcnt(0)
	v_mov_b64_e32 v[0:1], 0
	v_mov_b64_e32 v[2:3], 0
	v_mov_b64_e32 v[4:5], 0
	v_mov_b64_e32 v[6:7], 0
	v_mov_b64_e32 v[8:9], 0
	v_mov_b64_e32 v[10:11], 0
	v_mov_b64_e32 v[12:13], 0
	v_mov_b64_e32 v[14:15], 0
	v_mov_b64_e32 v[16:17], 0
	v_mov_b64_e32 v[18:19], 0
	v_mov_b64_e32 v[20:21], 0
	v_mov_b64_e32 v[22:23], 0
	v_mov_b64_e32 v[24:25], 0
	v_mov_b64_e32 v[26:27], 0
	v_mov_b64_e32 v[28:29], 0
	v_mov_b64_e32 v[30:31], 0
	v_mov_b64_e32 v[32:33], 0
	v_mov_b64_e32 v[34:35], 0
	v_mov_b64_e32 v[36:37], 0
	v_mov_b64_e32 v[38:39], 0
	v_mov_b64_e32 v[40:41], 0
	v_mov_b64_e32 v[42:43], 0
	v_mov_b64_e32 v[44:45], 0
	v_mov_b64_e32 v[46:47], 0
	v_mov_b64_e32 v[48:49], 0
	v_mov_b64_e32 v[50:51], 0
	v_mov_b64_e32 v[52:53], 0
	v_mov_b64_e32 v[54:55], 0
	v_mov_b64_e32 v[56:57], 0
	v_mov_b64_e32 v[58:59], 0
	v_mov_b64_e32 v[60:61], 0
	v_mov_b64_e32 v[62:63], 0
	v_mov_b64_e32 v[64:65], 0
	v_mov_b64_e32 v[66:67], 0
	v_mov_b64_e32 v[68:69], 0
	v_mov_b64_e32 v[70:71], 0
	v_mov_b64_e32 v[72:73], 0
	v_mov_b64_e32 v[74:75], 0
	v_mov_b64_e32 v[76:77], 0
	v_mov_b64_e32 v[78:79], 0
	v_mov_b64_e32 v[80:81], 0
	v_mov_b64_e32 v[82:83], 0
	v_mov_b64_e32 v[84:85], 0
	v_mov_b64_e32 v[86:87], 0
	v_mov_b64_e32 v[88:89], 0
	v_mov_b64_e32 v[90:91], 0
	v_mov_b64_e32 v[92:93], 0
	v_mov_b64_e32 v[94:95], 0
	v_mov_b64_e32 v[96:97], 0
	v_mov_b64_e32 v[98:99], 0
	v_mov_b64_e32 v[100:101], 0
	v_mov_b64_e32 v[102:103], 0
	v_mov_b64_e32 v[104:105], 0
	v_mov_b64_e32 v[106:107], 0
	v_mov_b64_e32 v[108:109], 0
	v_mov_b64_e32 v[110:111], 0
	v_mov_b64_e32 v[112:113], 0
	v_mov_b64_e32 v[114:115], 0
	v_mov_b64_e32 v[116:117], 0
	v_mov_b64_e32 v[118:119], 0
	v_mov_b64_e32 v[120:121], 0
	v_mov_b64_e32 v[122:123], 0
	v_mov_b64_e32 v[124:125], 0
	v_mov_b64_e32 v[126:127], 0
	s_add_i32 s20, s91, 3
	s_and_b32 s20, s20, -4
	s_waitcnt vmcnt(0) lgkmcnt(0)
	v_mov_b32_e32 v213, s22
	ds_read_b128 v[232:235], v213 offset:0
	s_waitcnt lgkmcnt(0)
	v_add_u32_e32 v236, v232, v240
	v_add_u32_e32 v237, v233, v240
	v_add_u32_e32 v238, v234, v240
	v_add_u32_e32 v239, v235, v240
	global_load_dwordx4 v[128:131], v236, s[6:7]
	global_load_dwordx4 v[132:135], v237, s[6:7]
	global_load_dwordx4 v[136:139], v238, s[6:7]
	global_load_dwordx4 v[140:143], v239, s[6:7]
	ds_read_b128 v[232:235], v213 offset:16
	s_waitcnt lgkmcnt(0)
	v_add_u32_e32 v236, v232, v240
	v_add_u32_e32 v237, v233, v240
	v_add_u32_e32 v238, v234, v240
	v_add_u32_e32 v239, v235, v240
	global_load_dwordx4 v[144:147], v236, s[6:7]
	global_load_dwordx4 v[148:151], v237, s[6:7]
	global_load_dwordx4 v[152:155], v238, s[6:7]
	global_load_dwordx4 v[156:159], v239, s[6:7]
	ds_read_b128 v[232:235], v213 offset:32
	s_waitcnt lgkmcnt(0)
	v_add_u32_e32 v236, v232, v240
	v_add_u32_e32 v237, v233, v240
	v_add_u32_e32 v238, v234, v240
	v_add_u32_e32 v239, v235, v240
	global_load_dwordx4 v[160:163], v236, s[6:7]
	global_load_dwordx4 v[164:167], v237, s[6:7]
	global_load_dwordx4 v[168:171], v238, s[6:7]
	global_load_dwordx4 v[172:175], v239, s[6:7]
	ds_read_b128 v[232:235], v213 offset:48
	s_mov_b32 s21, 0
	s_mov_b32 s89, -1
	ds_read_b128 v[248:251], v213 offset:4864
	s_branch .LV_sw0
.LV_t0_s0:
	s_cmp_ge_u32 s21, s20
	s_cbranch_scc1 .LV_done
	s_waitcnt lgkmcnt(0)
	v_add_u32_e32 v236, v232, v240
	v_add_u32_e32 v237, v233, v240
	v_add_u32_e32 v238, v234, v240
	v_add_u32_e32 v239, v235, v240
	global_load_dwordx4 v[176:179], v236, s[6:7]
	global_load_dwordx4 v[180:183], v237, s[6:7]
	global_load_dwordx4 v[184:187], v238, s[6:7]
	global_load_dwordx4 v[188:191], v239, s[6:7]
	ds_read_b128 v[232:235], v213 offset:64
	ds_read_b128 v[252:255], v213 offset:4880
	s_waitcnt vmcnt(12)
	v_cvt_pk_f32_fp8_e32 v[224:225], v128
	v_cvt_pk_f32_fp8_sdwa v[226:227], v128 src0_sel:WORD_1
	v_cvt_pk_f32_fp8_e32 v[228:229], v129
	v_cvt_pk_f32_fp8_sdwa v[230:231], v129 src0_sel:WORD_1
	v_pk_fma_f32 v[0:1], v[224:225], v[248:249], v[0:1] op_sel_hi:[1,0,1]
	v_pk_fma_f32 v[2:3], v[226:227], v[248:249], v[2:3] op_sel_hi:[1,0,1]
	v_pk_fma_f32 v[4:5], v[228:229], v[248:249], v[4:5] op_sel_hi:[1,0,1]
	v_pk_fma_f32 v[6:7], v[230:231], v[248:249], v[6:7] op_sel_hi:[1,0,1]
	v_cvt_pk_f32_fp8_e32 v[224:225], v130
	v_cvt_pk_f32_fp8_sdwa v[226:227], v130 src0_sel:WORD_1
	v_cvt_pk_f32_fp8_e32 v[228:229], v131
	v_cvt_pk_f32_fp8_sdwa v[230:231], v131 src0_sel:WORD_1
	v_pk_fma_f32 v[8:9], v[224:225], v[248:249], v[8:9] op_sel_hi:[1,0,1]
	v_pk_fma_f32 v[10:11], v[226:227], v[248:249], v[10:11] op_sel_hi:[1,0,1]
	v_pk_fma_f32 v[12:13], v[228:229], v[248:249], v[12:13] op_sel_hi:[1,0,1]
	v_pk_fma_f32 v[14:15], v[230:231], v[248:249], v[14:15] op_sel_hi:[1,0,1]
	v_cvt_pk_f32_fp8_e32 v[224:225], v132
	v_cvt_pk_f32_fp8_sdwa v[226:227], v132 src0_sel:WORD_1
	v_cvt_pk_f32_fp8_e32 v[228:229], v133
	v_cvt_pk_f32_fp8_sdwa v[230:231], v133 src0_sel:WORD_1
	v_pk_fma_f32 v[0:1], v[224:225], v[248:249], v[0:1] op_sel:[0,1,0] op_sel_hi:[1,1,1]
	v_pk_fma_f32 v[2:3], v[226:227], v[248:249], v[2:3] op_sel:[0,1,0] op_sel_hi:[1,1,1]
	v_pk_fma_f32 v[4:5], v[228:229], v[248:249], v[4:5] op_sel:[0,1,0] op_sel_hi:[1,1,1]
	v_pk_fma_f32 v[6:7], v[230:231], v[248:249], v[6:7] op_sel:[0,1,0] op_sel_hi:[1,1,1]
	v_cvt_pk_f32_fp8_e32 v[224:225], v134
	v_cvt_pk_f32_fp8_sdwa v[226:227], v134 src0_sel:WORD_1
	v_cvt_pk_f32_fp8_e32 v[228:229], v135
	v_cvt_pk_f32_fp8_sdwa v[230:231], v135 src0_sel:WORD_1
	v_pk_fma_f32 v[8:9], v[224:225], v[248:249], v[8:9] op_sel:[0,1,0] op_sel_hi:[1,1,1]
	v_pk_fma_f32 v[10:11], v[226:227], v[248:249], v[10:11] op_sel:[0,1,0] op_sel_hi:[1,1,1]
	v_pk_fma_f32 v[12:13], v[228:229], v[248:249], v[12:13] op_sel:[0,1,0] op_sel_hi:[1,1,1]
	v_pk_fma_f32 v[14:15], v[230:231], v[248:249], v[14:15] op_sel:[0,1,0] op_sel_hi:[1,1,1]
	v_cvt_pk_f32_fp8_e32 v[224:225], v136
	v_cvt_pk_f32_fp8_sdwa v[226:227], v136 src0_sel:WORD_1
	v_cvt_pk_f32_fp8_e32 v[228:229], v137
	v_cvt_pk_f32_fp8_sdwa v[230:231], v137 src0_sel:WORD_1
	v_pk_fma_f32 v[0:1], v[224:225], v[250:251], v[0:1] op_sel_hi:[1,0,1]
	v_pk_fma_f32 v[2:3], v[226:227], v[250:251], v[2:3] op_sel_hi:[1,0,1]
	v_pk_fma_f32 v[4:5], v[228:229], v[250:251], v[4:5] op_sel_hi:[1,0,1]
	v_pk_fma_f32 v[6:7], v[230:231], v[250:251], v[6:7] op_sel_hi:[1,0,1]
	v_cvt_pk_f32_fp8_e32 v[224:225], v138
	v_cvt_pk_f32_fp8_sdwa v[226:227], v138 src0_sel:WORD_1
	v_cvt_pk_f32_fp8_e32 v[228:229], v139
	v_cvt_pk_f32_fp8_sdwa v[230:231], v139 src0_sel:WORD_1
	v_pk_fma_f32 v[8:9], v[224:225], v[250:251], v[8:9] op_sel_hi:[1,0,1]
	v_pk_fma_f32 v[10:11], v[226:227], v[250:251], v[10:11] op_sel_hi:[1,0,1]
	v_pk_fma_f32 v[12:13], v[228:229], v[250:251], v[12:13] op_sel_hi:[1,0,1]
	v_pk_fma_f32 v[14:15], v[230:231], v[250:251], v[14:15] op_sel_hi:[1,0,1]
	v_cvt_pk_f32_fp8_e32 v[224:225], v140
	v_cvt_pk_f32_fp8_sdwa v[226:227], v140 src0_sel:WORD_1
	v_cvt_pk_f32_fp8_e32 v[228:229], v141
	v_cvt_pk_f32_fp8_sdwa v[230:231], v141 src0_sel:WORD_1
	v_pk_fma_f32 v[0:1], v[224:225], v[250:251], v[0:1] op_sel:[0,1,0] op_sel_hi:[1,1,1]
	v_pk_fma_f32 v[2:3], v[226:227], v[250:251], v[2:3] op_sel:[0,1,0] op_sel_hi:[1,1,1]
	v_pk_fma_f32 v[4:5], v[228:229], v[250:251], v[4:5] op_sel:[0,1,0] op_sel_hi:[1,1,1]
	v_pk_fma_f32 v[6:7], v[230:231], v[250:251], v[6:7] op_sel:[0,1,0] op_sel_hi:[1,1,1]
	v_cvt_pk_f32_fp8_e32 v[224:225], v142
	v_cvt_pk_f32_fp8_sdwa v[226:227], v142 src0_sel:WORD_1
	v_cvt_pk_f32_fp8_e32 v[228:229], v143
	v_cvt_pk_f32_fp8_sdwa v[230:231], v143 src0_sel:WORD_1
	v_pk_fma_f32 v[8:9], v[224:225], v[250:251], v[8:9] op_sel:[0,1,0] op_sel_hi:[1,1,1]
	v_pk_fma_f32 v[10:11], v[226:227], v[250:251], v[10:11] op_sel:[0,1,0] op_sel_hi:[1,1,1]
	v_pk_fma_f32 v[12:13], v[228:229], v[250:251], v[12:13] op_sel:[0,1,0] op_sel_hi:[1,1,1]
	v_pk_fma_f32 v[14:15], v[230:231], v[250:251], v[14:15] op_sel:[0,1,0] op_sel_hi:[1,1,1]
	s_sub_i32 s90, s90, 1
	s_cmp_eq_u32 s90, 0
	s_cbranch_scc1 .LV_sw1
.LV_t0_s1:
	s_waitcnt lgkmcnt(0)
	v_add_u32_e32 v236, v232, v240
	v_add_u32_e32 v237, v233, v240
	v_add_u32_e32 v238, v234, v240
	v_add_u32_e32 v239, v235, v240
	global_load_dwordx4 v[128:131], v236, s[6:7]
	global_load_dwordx4 v[132:135], v237, s[6:7]
	global_load_dwordx4 v[136:139], v238, s[6:7]
	global_load_dwordx4 v[140:143], v239, s[6:7]
	ds_read_b128 v[232:235], v213 offset:80
	ds_read_b128 v[248:251], v213 offset:4896
	s_waitcnt vmcnt(12)
	v_cvt_pk_f32_fp8_e32 v[224:225], v144
	v_cvt_pk_f32_fp8_sdwa v[226:227], v144 src0_sel:WORD_1
	v_cvt_pk_f32_fp8_e32 v[228:229], v145
	v_cvt_pk_f32_fp8_sdwa v[230:231], v145 src0_sel:WORD_1
	v_pk_fma_f32 v[0:1], v[224:225], v[252:253], v[0:1] op_sel_hi:[1,0,1]
	v_pk_fma_f32 v[2:3], v[226:227], v[252:253], v[2:3] op_sel_hi:[1,0,1]
	v_pk_fma_f32 v[4:5], v[228:229], v[252:253], v[4:5] op_sel_hi:[1,0,1]
	v_pk_fma_f32 v[6:7], v[230:231], v[252:253], v[6:7] op_sel_hi:[1,0,1]
	v_cvt_pk_f32_fp8_e32 v[224:225], v146
	v_cvt_pk_f32_fp8_sdwa v[226:227], v146 src0_sel:WORD_1
	v_cvt_pk_f32_fp8_e32 v[228:229], v147
	v_cvt_pk_f32_fp8_sdwa v[230:231], v147 src0_sel:WORD_1
	v_pk_fma_f32 v[8:9], v[224:225], v[252:253], v[8:9] op_sel_hi:[1,0,1]
	v_pk_fma_f32 v[10:11], v[226:227], v[252:253], v[10:11] op_sel_hi:[1,0,1]
	v_pk_fma_f32 v[12:13], v[228:229], v[252:253], v[12:13] op_sel_hi:[1,0,1]
	v_pk_fma_f32 v[14:15], v[230:231], v[252:253], v[14:15] op_sel_hi:[1,0,1]
	v_cvt_pk_f32_fp8_e32 v[224:225], v148
	v_cvt_pk_f32_fp8_sdwa v[226:227], v148 src0_sel:WORD_1
	v_cvt_pk_f32_fp8_e32 v[228:229], v149
	v_cvt_pk_f32_fp8_sdwa v[230:231], v149 src0_sel:WORD_1
	v_pk_fma_f32 v[0:1], v[224:225], v[252:253], v[0:1] op_sel:[0,1,0] op_sel_hi:[1,1,1]
	v_pk_fma_f32 v[2:3], v[226:227], v[252:253], v[2:3] op_sel:[0,1,0] op_sel_hi:[1,1,1]
	v_pk_fma_f32 v[4:5], v[228:229], v[252:253], v[4:5] op_sel:[0,1,0] op_sel_hi:[1,1,1]
	v_pk_fma_f32 v[6:7], v[230:231], v[252:253], v[6:7] op_sel:[0,1,0] op_sel_hi:[1,1,1]
	v_cvt_pk_f32_fp8_e32 v[224:225], v150
	v_cvt_pk_f32_fp8_sdwa v[226:227], v150 src0_sel:WORD_1
	v_cvt_pk_f32_fp8_e32 v[228:229], v151
	v_cvt_pk_f32_fp8_sdwa v[230:231], v151 src0_sel:WORD_1
	v_pk_fma_f32 v[8:9], v[224:225], v[252:253], v[8:9] op_sel:[0,1,0] op_sel_hi:[1,1,1]
	v_pk_fma_f32 v[10:11], v[226:227], v[252:253], v[10:11] op_sel:[0,1,0] op_sel_hi:[1,1,1]
	v_pk_fma_f32 v[12:13], v[228:229], v[252:253], v[12:13] op_sel:[0,1,0] op_sel_hi:[1,1,1]
	v_pk_fma_f32 v[14:15], v[230:231], v[252:253], v[14:15] op_sel:[0,1,0] op_sel_hi:[1,1,1]
	v_cvt_pk_f32_fp8_e32 v[224:225], v152
	v_cvt_pk_f32_fp8_sdwa v[226:227], v152 src0_sel:WORD_1
	v_cvt_pk_f32_fp8_e32 v[228:229], v153
	v_cvt_pk_f32_fp8_sdwa v[230:231], v153 src0_sel:WORD_1
	v_pk_fma_f32 v[0:1], v[224:225], v[254:255], v[0:1] op_sel_hi:[1,0,1]
	v_pk_fma_f32 v[2:3], v[226:227], v[254:255], v[2:3] op_sel_hi:[1,0,1]
	v_pk_fma_f32 v[4:5], v[228:229], v[254:255], v[4:5] op_sel_hi:[1,0,1]
	v_pk_fma_f32 v[6:7], v[230:231], v[254:255], v[6:7] op_sel_hi:[1,0,1]
	v_cvt_pk_f32_fp8_e32 v[224:225], v154
	v_cvt_pk_f32_fp8_sdwa v[226:227], v154 src0_sel:WORD_1
	v_cvt_pk_f32_fp8_e32 v[228:229], v155
	v_cvt_pk_f32_fp8_sdwa v[230:231], v155 src0_sel:WORD_1
	v_pk_fma_f32 v[8:9], v[224:225], v[254:255], v[8:9] op_sel_hi:[1,0,1]
	v_pk_fma_f32 v[10:11], v[226:227], v[254:255], v[10:11] op_sel_hi:[1,0,1]
	v_pk_fma_f32 v[12:13], v[228:229], v[254:255], v[12:13] op_sel_hi:[1,0,1]
	v_pk_fma_f32 v[14:15], v[230:231], v[254:255], v[14:15] op_sel_hi:[1,0,1]
	v_cvt_pk_f32_fp8_e32 v[224:225], v156
	v_cvt_pk_f32_fp8_sdwa v[226:227], v156 src0_sel:WORD_1
	v_cvt_pk_f32_fp8_e32 v[228:229], v157
	v_cvt_pk_f32_fp8_sdwa v[230:231], v157 src0_sel:WORD_1
	v_pk_fma_f32 v[0:1], v[224:225], v[254:255], v[0:1] op_sel:[0,1,0] op_sel_hi:[1,1,1]
	v_pk_fma_f32 v[2:3], v[226:227], v[254:255], v[2:3] op_sel:[0,1,0] op_sel_hi:[1,1,1]
	v_pk_fma_f32 v[4:5], v[228:229], v[254:255], v[4:5] op_sel:[0,1,0] op_sel_hi:[1,1,1]
	v_pk_fma_f32 v[6:7], v[230:231], v[254:255], v[6:7] op_sel:[0,1,0] op_sel_hi:[1,1,1]
	v_cvt_pk_f32_fp8_e32 v[224:225], v158
	v_cvt_pk_f32_fp8_sdwa v[226:227], v158 src0_sel:WORD_1
	v_cvt_pk_f32_fp8_e32 v[228:229], v159
	v_cvt_pk_f32_fp8_sdwa v[230:231], v159 src0_sel:WORD_1
	v_pk_fma_f32 v[8:9], v[224:225], v[254:255], v[8:9] op_sel:[0,1,0] op_sel_hi:[1,1,1]
	v_pk_fma_f32 v[10:11], v[226:227], v[254:255], v[10:11] op_sel:[0,1,0] op_sel_hi:[1,1,1]
	v_pk_fma_f32 v[12:13], v[228:229], v[254:255], v[12:13] op_sel:[0,1,0] op_sel_hi:[1,1,1]
	v_pk_fma_f32 v[14:15], v[230:231], v[254:255], v[14:15] op_sel:[0,1,0] op_sel_hi:[1,1,1]
	s_sub_i32 s90, s90, 1
	s_cmp_eq_u32 s90, 0
	s_cbranch_scc1 .LV_sw2
.LV_t0_s2:
	s_waitcnt lgkmcnt(0)
	v_add_u32_e32 v236, v232, v240
	v_add_u32_e32 v237, v233, v240
	v_add_u32_e32 v238, v234, v240
	v_add_u32_e32 v239, v235, v240
	global_load_dwordx4 v[144:147], v236, s[6:7]
	global_load_dwordx4 v[148:151], v237, s[6:7]
	global_load_dwordx4 v[152:155], v238, s[6:7]
	global_load_dwordx4 v[156:159], v239, s[6:7]
	ds_read_b128 v[232:235], v213 offset:96
	ds_read_b128 v[252:255], v213 offset:4912
	s_waitcnt vmcnt(12)
	v_cvt_pk_f32_fp8_e32 v[224:225], v160
	v_cvt_pk_f32_fp8_sdwa v[226:227], v160 src0_sel:WORD_1
	v_cvt_pk_f32_fp8_e32 v[228:229], v161
	v_cvt_pk_f32_fp8_sdwa v[230:231], v161 src0_sel:WORD_1
	v_pk_fma_f32 v[0:1], v[224:225], v[248:249], v[0:1] op_sel_hi:[1,0,1]
	v_pk_fma_f32 v[2:3], v[226:227], v[248:249], v[2:3] op_sel_hi:[1,0,1]
	v_pk_fma_f32 v[4:5], v[228:229], v[248:249], v[4:5] op_sel_hi:[1,0,1]
	v_pk_fma_f32 v[6:7], v[230:231], v[248:249], v[6:7] op_sel_hi:[1,0,1]
	v_cvt_pk_f32_fp8_e32 v[224:225], v162
	v_cvt_pk_f32_fp8_sdwa v[226:227], v162 src0_sel:WORD_1
	v_cvt_pk_f32_fp8_e32 v[228:229], v163
	v_cvt_pk_f32_fp8_sdwa v[230:231], v163 src0_sel:WORD_1
	v_pk_fma_f32 v[8:9], v[224:225], v[248:249], v[8:9] op_sel_hi:[1,0,1]
	v_pk_fma_f32 v[10:11], v[226:227], v[248:249], v[10:11] op_sel_hi:[1,0,1]
	v_pk_fma_f32 v[12:13], v[228:229], v[248:249], v[12:13] op_sel_hi:[1,0,1]
	v_pk_fma_f32 v[14:15], v[230:231], v[248:249], v[14:15] op_sel_hi:[1,0,1]
	v_cvt_pk_f32_fp8_e32 v[224:225], v164
	v_cvt_pk_f32_fp8_sdwa v[226:227], v164 src0_sel:WORD_1
	v_cvt_pk_f32_fp8_e32 v[228:229], v165
	v_cvt_pk_f32_fp8_sdwa v[230:231], v165 src0_sel:WORD_1
	v_pk_fma_f32 v[0:1], v[224:225], v[248:249], v[0:1] op_sel:[0,1,0] op_sel_hi:[1,1,1]
	v_pk_fma_f32 v[2:3], v[226:227], v[248:249], v[2:3] op_sel:[0,1,0] op_sel_hi:[1,1,1]
	v_pk_fma_f32 v[4:5], v[228:229], v[248:249], v[4:5] op_sel:[0,1,0] op_sel_hi:[1,1,1]
	v_pk_fma_f32 v[6:7], v[230:231], v[248:249], v[6:7] op_sel:[0,1,0] op_sel_hi:[1,1,1]
	v_cvt_pk_f32_fp8_e32 v[224:225], v166
	v_cvt_pk_f32_fp8_sdwa v[226:227], v166 src0_sel:WORD_1
	v_cvt_pk_f32_fp8_e32 v[228:229], v167
	v_cvt_pk_f32_fp8_sdwa v[230:231], v167 src0_sel:WORD_1
	v_pk_fma_f32 v[8:9], v[224:225], v[248:249], v[8:9] op_sel:[0,1,0] op_sel_hi:[1,1,1]
	v_pk_fma_f32 v[10:11], v[226:227], v[248:249], v[10:11] op_sel:[0,1,0] op_sel_hi:[1,1,1]
	v_pk_fma_f32 v[12:13], v[228:229], v[248:249], v[12:13] op_sel:[0,1,0] op_sel_hi:[1,1,1]
	v_pk_fma_f32 v[14:15], v[230:231], v[248:249], v[14:15] op_sel:[0,1,0] op_sel_hi:[1,1,1]
	v_cvt_pk_f32_fp8_e32 v[224:225], v168
	v_cvt_pk_f32_fp8_sdwa v[226:227], v168 src0_sel:WORD_1
	v_cvt_pk_f32_fp8_e32 v[228:229], v169
	v_cvt_pk_f32_fp8_sdwa v[230:231], v169 src0_sel:WORD_1
	v_pk_fma_f32 v[0:1], v[224:225], v[250:251], v[0:1] op_sel_hi:[1,0,1]
	v_pk_fma_f32 v[2:3], v[226:227], v[250:251], v[2:3] op_sel_hi:[1,0,1]
	v_pk_fma_f32 v[4:5], v[228:229], v[250:251], v[4:5] op_sel_hi:[1,0,1]
	v_pk_fma_f32 v[6:7], v[230:231], v[250:251], v[6:7] op_sel_hi:[1,0,1]
	v_cvt_pk_f32_fp8_e32 v[224:225], v170
	v_cvt_pk_f32_fp8_sdwa v[226:227], v170 src0_sel:WORD_1
	v_cvt_pk_f32_fp8_e32 v[228:229], v171
	v_cvt_pk_f32_fp8_sdwa v[230:231], v171 src0_sel:WORD_1
	v_pk_fma_f32 v[8:9], v[224:225], v[250:251], v[8:9] op_sel_hi:[1,0,1]
	v_pk_fma_f32 v[10:11], v[226:227], v[250:251], v[10:11] op_sel_hi:[1,0,1]
	v_pk_fma_f32 v[12:13], v[228:229], v[250:251], v[12:13] op_sel_hi:[1,0,1]
	v_pk_fma_f32 v[14:15], v[230:231], v[250:251], v[14:15] op_sel_hi:[1,0,1]
	v_cvt_pk_f32_fp8_e32 v[224:225], v172
	v_cvt_pk_f32_fp8_sdwa v[226:227], v172 src0_sel:WORD_1
	v_cvt_pk_f32_fp8_e32 v[228:229], v173
	v_cvt_pk_f32_fp8_sdwa v[230:231], v173 src0_sel:WORD_1
	v_pk_fma_f32 v[0:1], v[224:225], v[250:251], v[0:1] op_sel:[0,1,0] op_sel_hi:[1,1,1]
	v_pk_fma_f32 v[2:3], v[226:227], v[250:251], v[2:3] op_sel:[0,1,0] op_sel_hi:[1,1,1]
	v_pk_fma_f32 v[4:5], v[228:229], v[250:251], v[4:5] op_sel:[0,1,0] op_sel_hi:[1,1,1]
	v_pk_fma_f32 v[6:7], v[230:231], v[250:251], v[6:7] op_sel:[0,1,0] op_sel_hi:[1,1,1]
	v_cvt_pk_f32_fp8_e32 v[224:225], v174
	v_cvt_pk_f32_fp8_sdwa v[226:227], v174 src0_sel:WORD_1
	v_cvt_pk_f32_fp8_e32 v[228:229], v175
	v_cvt_pk_f32_fp8_sdwa v[230:231], v175 src0_sel:WORD_1
	v_pk_fma_f32 v[8:9], v[224:225], v[250:251], v[8:9] op_sel:[0,1,0] op_sel_hi:[1,1,1]
	v_pk_fma_f32 v[10:11], v[226:227], v[250:251], v[10:11] op_sel:[0,1,0] op_sel_hi:[1,1,1]
	v_pk_fma_f32 v[12:13], v[228:229], v[250:251], v[12:13] op_sel:[0,1,0] op_sel_hi:[1,1,1]
	v_pk_fma_f32 v[14:15], v[230:231], v[250:251], v[14:15] op_sel:[0,1,0] op_sel_hi:[1,1,1]
	s_sub_i32 s90, s90, 1
	s_cmp_eq_u32 s90, 0
	s_cbranch_scc1 .LV_sw3
; __device__ __forceinline__ void peer_tile(const Args& A, LAS unsigned char* lds, int tile) {
;     ...
;         for (int p = 0; p < 16; ++p) {
; #pragma unroll
;             for (int tk = 0; tk < 4; ++tk) {
;                 const int tl = tb + tk;
;                 const int beg = __builtin_amdgcn_readfirstlane(OFFS[tl * 17 + p]), end = __builtin_amdgcn_readfirstlane(OFFS[tl * 17 + p + 1]);
.LV_t0_s3:
	s_waitcnt lgkmcnt(0)
	v_add_u32_e32 v236, v232, v240
	v_add_u32_e32 v237, v233, v240
	v_add_u32_e32 v238, v234, v240
	v_add_u32_e32 v239, v235, v240
	global_load_dwordx4 v[160:163], v236, s[6:7]
	global_load_dwordx4 v[164:167], v237, s[6:7]
	global_load_dwordx4 v[168:171], v238, s[6:7]
	global_load_dwordx4 v[172:175], v239, s[6:7]
	ds_read_b128 v[232:235], v213 offset:112
	ds_read_b128 v[248:251], v213 offset:4928
	s_waitcnt vmcnt(12)
	v_cvt_pk_f32_fp8_e32 v[224:225], v176
	v_cvt_pk_f32_fp8_sdwa v[226:227], v176 src0_sel:WORD_1
	v_cvt_pk_f32_fp8_e32 v[228:229], v177
	v_cvt_pk_f32_fp8_sdwa v[230:231], v177 src0_sel:WORD_1
	v_pk_fma_f32 v[0:1], v[224:225], v[252:253], v[0:1] op_sel_hi:[1,0,1]
	v_pk_fma_f32 v[2:3], v[226:227], v[252:253], v[2:3] op_sel_hi:[1,0,1]
	v_pk_fma_f32 v[4:5], v[228:229], v[252:253], v[4:5] op_sel_hi:[1,0,1]
	v_pk_fma_f32 v[6:7], v[230:231], v[252:253], v[6:7] op_sel_hi:[1,0,1]
	v_cvt_pk_f32_fp8_e32 v[224:225], v178
	v_cvt_pk_f32_fp8_sdwa v[226:227], v178 src0_sel:WORD_1
	v_cvt_pk_f32_fp8_e32 v[228:229], v179
	v_cvt_pk_f32_fp8_sdwa v[230:231], v179 src0_sel:WORD_1
	v_pk_fma_f32 v[8:9], v[224:225], v[252:253], v[8:9] op_sel_hi:[1,0,1]
	v_pk_fma_f32 v[10:11], v[226:227], v[252:253], v[10:11] op_sel_hi:[1,0,1]
	v_pk_fma_f32 v[12:13], v[228:229], v[252:253], v[12:13] op_sel_hi:[1,0,1]
	v_pk_fma_f32 v[14:15], v[230:231], v[252:253], v[14:15] op_sel_hi:[1,0,1]
	v_cvt_pk_f32_fp8_e32 v[224:225], v180
	v_cvt_pk_f32_fp8_sdwa v[226:227], v180 src0_sel:WORD_1
	v_cvt_pk_f32_fp8_e32 v[228:229], v181
	v_cvt_pk_f32_fp8_sdwa v[230:231], v181 src0_sel:WORD_1
	v_pk_fma_f32 v[0:1], v[224:225], v[252:253], v[0:1] op_sel:[0,1,0] op_sel_hi:[1,1,1]
	v_pk_fma_f32 v[2:3], v[226:227], v[252:253], v[2:3] op_sel:[0,1,0] op_sel_hi:[1,1,1]
	v_pk_fma_f32 v[4:5], v[228:229], v[252:253], v[4:5] op_sel:[0,1,0] op_sel_hi:[1,1,1]
	v_pk_fma_f32 v[6:7], v[230:231], v[252:253], v[6:7] op_sel:[0,1,0] op_sel_hi:[1,1,1]
	v_cvt_pk_f32_fp8_e32 v[224:225], v182
	v_cvt_pk_f32_fp8_sdwa v[226:227], v182 src0_sel:WORD_1
	v_cvt_pk_f32_fp8_e32 v[228:229], v183
	v_cvt_pk_f32_fp8_sdwa v[230:231], v183 src0_sel:WORD_1
	v_pk_fma_f32 v[8:9], v[224:225], v[252:253], v[8:9] op_sel:[0,1,0] op_sel_hi:[1,1,1]
	v_pk_fma_f32 v[10:11], v[226:227], v[252:253], v[10:11] op_sel:[0,1,0] op_sel_hi:[1,1,1]
	v_pk_fma_f32 v[12:13], v[228:229], v[252:253], v[12:13] op_sel:[0,1,0] op_sel_hi:[1,1,1]
	v_pk_fma_f32 v[14:15], v[230:231], v[252:253], v[14:15] op_sel:[0,1,0] op_sel_hi:[1,1,1]
	v_cvt_pk_f32_fp8_e32 v[224:225], v184
	v_cvt_pk_f32_fp8_sdwa v[226:227], v184 src0_sel:WORD_1
	v_cvt_pk_f32_fp8_e32 v[228:229], v185
	v_cvt_pk_f32_fp8_sdwa v[230:231], v185 src0_sel:WORD_1
	v_pk_fma_f32 v[0:1], v[224:225], v[254:255], v[0:1] op_sel_hi:[1,0,1]
	v_pk_fma_f32 v[2:3], v[226:227], v[254:255], v[2:3] op_sel_hi:[1,0,1]
	v_pk_fma_f32 v[4:5], v[228:229], v[254:255], v[4:5] op_sel_hi:[1,0,1]
	v_pk_fma_f32 v[6:7], v[230:231], v[254:255], v[6:7] op_sel_hi:[1,0,1]
	v_cvt_pk_f32_fp8_e32 v[224:225], v186
	v_cvt_pk_f32_fp8_sdwa v[226:227], v186 src0_sel:WORD_1
	v_cvt_pk_f32_fp8_e32 v[228:229], v187
	v_cvt_pk_f32_fp8_sdwa v[230:231], v187 src0_sel:WORD_1
	v_pk_fma_f32 v[8:9], v[224:225], v[254:255], v[8:9] op_sel_hi:[1,0,1]
	v_pk_fma_f32 v[10:11], v[226:227], v[254:255], v[10:11] op_sel_hi:[1,0,1]
	v_pk_fma_f32 v[12:13], v[228:229], v[254:255], v[12:13] op_sel_hi:[1,0,1]
	v_pk_fma_f32 v[14:15], v[230:231], v[254:255], v[14:15] op_sel_hi:[1,0,1]
	v_cvt_pk_f32_fp8_e32 v[224:225], v188
	v_cvt_pk_f32_fp8_sdwa v[226:227], v188 src0_sel:WORD_1
	v_cvt_pk_f32_fp8_e32 v[228:229], v189
	v_cvt_pk_f32_fp8_sdwa v[230:231], v189 src0_sel:WORD_1
	v_pk_fma_f32 v[0:1], v[224:225], v[254:255], v[0:1] op_sel:[0,1,0] op_sel_hi:[1,1,1]
	v_pk_fma_f32 v[2:3], v[226:227], v[254:255], v[2:3] op_sel:[0,1,0] op_sel_hi:[1,1,1]
	v_pk_fma_f32 v[4:5], v[228:229], v[254:255], v[4:5] op_sel:[0,1,0] op_sel_hi:[1,1,1]
	v_pk_fma_f32 v[6:7], v[230:231], v[254:255], v[6:7] op_sel:[0,1,0] op_sel_hi:[1,1,1]
	v_cvt_pk_f32_fp8_e32 v[224:225], v190
	v_cvt_pk_f32_fp8_sdwa v[226:227], v190 src0_sel:WORD_1
	v_cvt_pk_f32_fp8_e32 v[228:229], v191
	v_cvt_pk_f32_fp8_sdwa v[230:231], v191 src0_sel:WORD_1
	v_pk_fma_f32 v[8:9], v[224:225], v[254:255], v[8:9] op_sel:[0,1,0] op_sel_hi:[1,1,1]
	v_pk_fma_f32 v[10:11], v[226:227], v[254:255], v[10:11] op_sel:[0,1,0] op_sel_hi:[1,1,1]
	v_pk_fma_f32 v[12:13], v[228:229], v[254:255], v[12:13] op_sel:[0,1,0] op_sel_hi:[1,1,1]
	v_pk_fma_f32 v[14:15], v[230:231], v[254:255], v[14:15] op_sel:[0,1,0] op_sel_hi:[1,1,1]
	v_add_u32_e32 v213, 64, v213
	s_add_i32 s21, s21, 4
	s_sub_i32 s90, s90, 1
	s_cmp_eq_u32 s90, 0
	s_cbranch_scc1 .LV_sw0
	s_branch .LV_t0_s0
.LV_t1_s0:
	s_cmp_ge_u32 s21, s20
	s_cbranch_scc1 .LV_done
	s_waitcnt lgkmcnt(0)
	v_add_u32_e32 v236, v232, v240
	v_add_u32_e32 v237, v233, v240
	v_add_u32_e32 v238, v234, v240
	v_add_u32_e32 v239, v235, v240
	global_load_dwordx4 v[176:179], v236, s[6:7]
	global_load_dwordx4 v[180:183], v237, s[6:7]
	global_load_dwordx4 v[184:187], v238, s[6:7]
	global_load_dwordx4 v[188:191], v239, s[6:7]
	ds_read_b128 v[232:235], v213 offset:64
	ds_read_b128 v[252:255], v213 offset:4880
	s_waitcnt vmcnt(12)
	v_cvt_pk_f32_fp8_e32 v[224:225], v128
	v_cvt_pk_f32_fp8_sdwa v[226:227], v128 src0_sel:WORD_1
	v_cvt_pk_f32_fp8_e32 v[228:229], v129
	v_cvt_pk_f32_fp8_sdwa v[230:231], v129 src0_sel:WORD_1
	v_pk_fma_f32 v[16:17], v[224:225], v[248:249], v[16:17] op_sel_hi:[1,0,1]
	v_pk_fma_f32 v[18:19], v[226:227], v[248:249], v[18:19] op_sel_hi:[1,0,1]
	v_pk_fma_f32 v[20:21], v[228:229], v[248:249], v[20:21] op_sel_hi:[1,0,1]
	v_pk_fma_f32 v[22:23], v[230:231], v[248:249], v[22:23] op_sel_hi:[1,0,1]
	v_cvt_pk_f32_fp8_e32 v[224:225], v130
	v_cvt_pk_f32_fp8_sdwa v[226:227], v130 src0_sel:WORD_1
	v_cvt_pk_f32_fp8_e32 v[228:229], v131
	v_cvt_pk_f32_fp8_sdwa v[230:231], v131 src0_sel:WORD_1
	v_pk_fma_f32 v[24:25], v[224:225], v[248:249], v[24:25] op_sel_hi:[1,0,1]
	v_pk_fma_f32 v[26:27], v[226:227], v[248:249], v[26:27] op_sel_hi:[1,0,1]
	v_pk_fma_f32 v[28:29], v[228:229], v[248:249], v[28:29] op_sel_hi:[1,0,1]
	v_pk_fma_f32 v[30:31], v[230:231], v[248:249], v[30:31] op_sel_hi:[1,0,1]
	v_cvt_pk_f32_fp8_e32 v[224:225], v132
	v_cvt_pk_f32_fp8_sdwa v[226:227], v132 src0_sel:WORD_1
	v_cvt_pk_f32_fp8_e32 v[228:229], v133
	v_cvt_pk_f32_fp8_sdwa v[230:231], v133 src0_sel:WORD_1
	v_pk_fma_f32 v[16:17], v[224:225], v[248:249], v[16:17] op_sel:[0,1,0] op_sel_hi:[1,1,1]
	v_pk_fma_f32 v[18:19], v[226:227], v[248:249], v[18:19] op_sel:[0,1,0] op_sel_hi:[1,1,1]
	v_pk_fma_f32 v[20:21], v[228:229], v[248:249], v[20:21] op_sel:[0,1,0] op_sel_hi:[1,1,1]
	v_pk_fma_f32 v[22:23], v[230:231], v[248:249], v[22:23] op_sel:[0,1,0] op_sel_hi:[1,1,1]
	v_cvt_pk_f32_fp8_e32 v[224:225], v134
	v_cvt_pk_f32_fp8_sdwa v[226:227], v134 src0_sel:WORD_1
	v_cvt_pk_f32_fp8_e32 v[228:229], v135
	v_cvt_pk_f32_fp8_sdwa v[230:231], v135 src0_sel:WORD_1
	v_pk_fma_f32 v[24:25], v[224:225], v[248:249], v[24:25] op_sel:[0,1,0] op_sel_hi:[1,1,1]
	v_pk_fma_f32 v[26:27], v[226:227], v[248:249], v[26:27] op_sel:[0,1,0] op_sel_hi:[1,1,1]
	v_pk_fma_f32 v[28:29], v[228:229], v[248:249], v[28:29] op_sel:[0,1,0] op_sel_hi:[1,1,1]
	v_pk_fma_f32 v[30:31], v[230:231], v[248:249], v[30:31] op_sel:[0,1,0] op_sel_hi:[1,1,1]
	v_cvt_pk_f32_fp8_e32 v[224:225], v136
	v_cvt_pk_f32_fp8_sdwa v[226:227], v136 src0_sel:WORD_1
	v_cvt_pk_f32_fp8_e32 v[228:229], v137
	v_cvt_pk_f32_fp8_sdwa v[230:231], v137 src0_sel:WORD_1
	v_pk_fma_f32 v[16:17], v[224:225], v[250:251], v[16:17] op_sel_hi:[1,0,1]
	v_pk_fma_f32 v[18:19], v[226:227], v[250:251], v[18:19] op_sel_hi:[1,0,1]
	v_pk_fma_f32 v[20:21], v[228:229], v[250:251], v[20:21] op_sel_hi:[1,0,1]
	v_pk_fma_f32 v[22:23], v[230:231], v[250:251], v[22:23] op_sel_hi:[1,0,1]
	v_cvt_pk_f32_fp8_e32 v[224:225], v138
	v_cvt_pk_f32_fp8_sdwa v[226:227], v138 src0_sel:WORD_1
	v_cvt_pk_f32_fp8_e32 v[228:229], v139
	v_cvt_pk_f32_fp8_sdwa v[230:231], v139 src0_sel:WORD_1
	v_pk_fma_f32 v[24:25], v[224:225], v[250:251], v[24:25] op_sel_hi:[1,0,1]
	v_pk_fma_f32 v[26:27], v[226:227], v[250:251], v[26:27] op_sel_hi:[1,0,1]
	v_pk_fma_f32 v[28:29], v[228:229], v[250:251], v[28:29] op_sel_hi:[1,0,1]
	v_pk_fma_f32 v[30:31], v[230:231], v[250:251], v[30:31] op_sel_hi:[1,0,1]
	v_cvt_pk_f32_fp8_e32 v[224:225], v140
	v_cvt_pk_f32_fp8_sdwa v[226:227], v140 src0_sel:WORD_1
	v_cvt_pk_f32_fp8_e32 v[228:229], v141
	v_cvt_pk_f32_fp8_sdwa v[230:231], v141 src0_sel:WORD_1
	v_pk_fma_f32 v[16:17], v[224:225], v[250:251], v[16:17] op_sel:[0,1,0] op_sel_hi:[1,1,1]
	v_pk_fma_f32 v[18:19], v[226:227], v[250:251], v[18:19] op_sel:[0,1,0] op_sel_hi:[1,1,1]
	v_pk_fma_f32 v[20:21], v[228:229], v[250:251], v[20:21] op_sel:[0,1,0] op_sel_hi:[1,1,1]
	v_pk_fma_f32 v[22:23], v[230:231], v[250:251], v[22:23] op_sel:[0,1,0] op_sel_hi:[1,1,1]
	v_cvt_pk_f32_fp8_e32 v[224:225], v142
	v_cvt_pk_f32_fp8_sdwa v[226:227], v142 src0_sel:WORD_1
	v_cvt_pk_f32_fp8_e32 v[228:229], v143
	v_cvt_pk_f32_fp8_sdwa v[230:231], v143 src0_sel:WORD_1
	v_pk_fma_f32 v[24:25], v[224:225], v[250:251], v[24:25] op_sel:[0,1,0] op_sel_hi:[1,1,1]
	v_pk_fma_f32 v[26:27], v[226:227], v[250:251], v[26:27] op_sel:[0,1,0] op_sel_hi:[1,1,1]
	v_pk_fma_f32 v[28:29], v[228:229], v[250:251], v[28:29] op_sel:[0,1,0] op_sel_hi:[1,1,1]
	v_pk_fma_f32 v[30:31], v[230:231], v[250:251], v[30:31] op_sel:[0,1,0] op_sel_hi:[1,1,1]
	s_sub_i32 s90, s90, 1
	s_cmp_eq_u32 s90, 0
	s_cbranch_scc1 .LV_sw1
.LV_t1_s1:
	s_waitcnt lgkmcnt(0)
	v_add_u32_e32 v236, v232, v240
	v_add_u32_e32 v237, v233, v240
	v_add_u32_e32 v238, v234, v240
	v_add_u32_e32 v239, v235, v240
	global_load_dwordx4 v[128:131], v236, s[6:7]
	global_load_dwordx4 v[132:135], v237, s[6:7]
	global_load_dwordx4 v[136:139], v238, s[6:7]
	global_load_dwordx4 v[140:143], v239, s[6:7]
	ds_read_b128 v[232:235], v213 offset:80
	ds_read_b128 v[248:251], v213 offset:4896
	s_waitcnt vmcnt(12)
	v_cvt_pk_f32_fp8_e32 v[224:225], v144
	v_cvt_pk_f32_fp8_sdwa v[226:227], v144 src0_sel:WORD_1
	v_cvt_pk_f32_fp8_e32 v[228:229], v145
	v_cvt_pk_f32_fp8_sdwa v[230:231], v145 src0_sel:WORD_1
	v_pk_fma_f32 v[16:17], v[224:225], v[252:253], v[16:17] op_sel_hi:[1,0,1]
	v_pk_fma_f32 v[18:19], v[226:227], v[252:253], v[18:19] op_sel_hi:[1,0,1]
	v_pk_fma_f32 v[20:21], v[228:229], v[252:253], v[20:21] op_sel_hi:[1,0,1]
	v_pk_fma_f32 v[22:23], v[230:231], v[252:253], v[22:23] op_sel_hi:[1,0,1]
	v_cvt_pk_f32_fp8_e32 v[224:225], v146
	v_cvt_pk_f32_fp8_sdwa v[226:227], v146 src0_sel:WORD_1
	v_cvt_pk_f32_fp8_e32 v[228:229], v147
	v_cvt_pk_f32_fp8_sdwa v[230:231], v147 src0_sel:WORD_1
	v_pk_fma_f32 v[24:25], v[224:225], v[252:253], v[24:25] op_sel_hi:[1,0,1]
	v_pk_fma_f32 v[26:27], v[226:227], v[252:253], v[26:27] op_sel_hi:[1,0,1]
	v_pk_fma_f32 v[28:29], v[228:229], v[252:253], v[28:29] op_sel_hi:[1,0,1]
	v_pk_fma_f32 v[30:31], v[230:231], v[252:253], v[30:31] op_sel_hi:[1,0,1]
	v_cvt_pk_f32_fp8_e32 v[224:225], v148
	v_cvt_pk_f32_fp8_sdwa v[226:227], v148 src0_sel:WORD_1
	v_cvt_pk_f32_fp8_e32 v[228:229], v149
	v_cvt_pk_f32_fp8_sdwa v[230:231], v149 src0_sel:WORD_1
	v_pk_fma_f32 v[16:17], v[224:225], v[252:253], v[16:17] op_sel:[0,1,0] op_sel_hi:[1,1,1]
	v_pk_fma_f32 v[18:19], v[226:227], v[252:253], v[18:19] op_sel:[0,1,0] op_sel_hi:[1,1,1]
	v_pk_fma_f32 v[20:21], v[228:229], v[252:253], v[20:21] op_sel:[0,1,0] op_sel_hi:[1,1,1]
	v_pk_fma_f32 v[22:23], v[230:231], v[252:253], v[22:23] op_sel:[0,1,0] op_sel_hi:[1,1,1]
	v_cvt_pk_f32_fp8_e32 v[224:225], v150
	v_cvt_pk_f32_fp8_sdwa v[226:227], v150 src0_sel:WORD_1
	v_cvt_pk_f32_fp8_e32 v[228:229], v151
	v_cvt_pk_f32_fp8_sdwa v[230:231], v151 src0_sel:WORD_1
	v_pk_fma_f32 v[24:25], v[224:225], v[252:253], v[24:25] op_sel:[0,1,0] op_sel_hi:[1,1,1]
	v_pk_fma_f32 v[26:27], v[226:227], v[252:253], v[26:27] op_sel:[0,1,0] op_sel_hi:[1,1,1]
	v_pk_fma_f32 v[28:29], v[228:229], v[252:253], v[28:29] op_sel:[0,1,0] op_sel_hi:[1,1,1]
	v_pk_fma_f32 v[30:31], v[230:231], v[252:253], v[30:31] op_sel:[0,1,0] op_sel_hi:[1,1,1]
	v_cvt_pk_f32_fp8_e32 v[224:225], v152
	v_cvt_pk_f32_fp8_sdwa v[226:227], v152 src0_sel:WORD_1
	v_cvt_pk_f32_fp8_e32 v[228:229], v153
	v_cvt_pk_f32_fp8_sdwa v[230:231], v153 src0_sel:WORD_1
	v_pk_fma_f32 v[16:17], v[224:225], v[254:255], v[16:17] op_sel_hi:[1,0,1]
	v_pk_fma_f32 v[18:19], v[226:227], v[254:255], v[18:19] op_sel_hi:[1,0,1]
	v_pk_fma_f32 v[20:21], v[228:229], v[254:255], v[20:21] op_sel_hi:[1,0,1]
	v_pk_fma_f32 v[22:23], v[230:231], v[254:255], v[22:23] op_sel_hi:[1,0,1]
	v_cvt_pk_f32_fp8_e32 v[224:225], v154
	v_cvt_pk_f32_fp8_sdwa v[226:227], v154 src0_sel:WORD_1
	v_cvt_pk_f32_fp8_e32 v[228:229], v155
	v_cvt_pk_f32_fp8_sdwa v[230:231], v155 src0_sel:WORD_1
	v_pk_fma_f32 v[24:25], v[224:225], v[254:255], v[24:25] op_sel_hi:[1,0,1]
	v_pk_fma_f32 v[26:27], v[226:227], v[254:255], v[26:27] op_sel_hi:[1,0,1]
	v_pk_fma_f32 v[28:29], v[228:229], v[254:255], v[28:29] op_sel_hi:[1,0,1]
	v_pk_fma_f32 v[30:31], v[230:231], v[254:255], v[30:31] op_sel_hi:[1,0,1]
	v_cvt_pk_f32_fp8_e32 v[224:225], v156
	v_cvt_pk_f32_fp8_sdwa v[226:227], v156 src0_sel:WORD_1
	v_cvt_pk_f32_fp8_e32 v[228:229], v157
	v_cvt_pk_f32_fp8_sdwa v[230:231], v157 src0_sel:WORD_1
	v_pk_fma_f32 v[16:17], v[224:225], v[254:255], v[16:17] op_sel:[0,1,0] op_sel_hi:[1,1,1]
	v_pk_fma_f32 v[18:19], v[226:227], v[254:255], v[18:19] op_sel:[0,1,0] op_sel_hi:[1,1,1]
	v_pk_fma_f32 v[20:21], v[228:229], v[254:255], v[20:21] op_sel:[0,1,0] op_sel_hi:[1,1,1]
	v_pk_fma_f32 v[22:23], v[230:231], v[254:255], v[22:23] op_sel:[0,1,0] op_sel_hi:[1,1,1]
	v_cvt_pk_f32_fp8_e32 v[224:225], v158
	v_cvt_pk_f32_fp8_sdwa v[226:227], v158 src0_sel:WORD_1
	v_cvt_pk_f32_fp8_e32 v[228:229], v159
	v_cvt_pk_f32_fp8_sdwa v[230:231], v159 src0_sel:WORD_1
	v_pk_fma_f32 v[24:25], v[224:225], v[254:255], v[24:25] op_sel:[0,1,0] op_sel_hi:[1,1,1]
	v_pk_fma_f32 v[26:27], v[226:227], v[254:255], v[26:27] op_sel:[0,1,0] op_sel_hi:[1,1,1]
	v_pk_fma_f32 v[28:29], v[228:229], v[254:255], v[28:29] op_sel:[0,1,0] op_sel_hi:[1,1,1]
	v_pk_fma_f32 v[30:31], v[230:231], v[254:255], v[30:31] op_sel:[0,1,0] op_sel_hi:[1,1,1]
	s_sub_i32 s90, s90, 1
	s_cmp_eq_u32 s90, 0
	s_cbranch_scc1 .LV_sw2
.LV_t1_s2:
	s_waitcnt lgkmcnt(0)
	v_add_u32_e32 v236, v232, v240
	v_add_u32_e32 v237, v233, v240
	v_add_u32_e32 v238, v234, v240
	v_add_u32_e32 v239, v235, v240
	global_load_dwordx4 v[144:147], v236, s[6:7]
	global_load_dwordx4 v[148:151], v237, s[6:7]
	global_load_dwordx4 v[152:155], v238, s[6:7]
	global_load_dwordx4 v[156:159], v239, s[6:7]
	ds_read_b128 v[232:235], v213 offset:96
	ds_read_b128 v[252:255], v213 offset:4912
	s_waitcnt vmcnt(12)
	v_cvt_pk_f32_fp8_e32 v[224:225], v160
	v_cvt_pk_f32_fp8_sdwa v[226:227], v160 src0_sel:WORD_1
	v_cvt_pk_f32_fp8_e32 v[228:229], v161
	v_cvt_pk_f32_fp8_sdwa v[230:231], v161 src0_sel:WORD_1
	v_pk_fma_f32 v[16:17], v[224:225], v[248:249], v[16:17] op_sel_hi:[1,0,1]
	v_pk_fma_f32 v[18:19], v[226:227], v[248:249], v[18:19] op_sel_hi:[1,0,1]
	v_pk_fma_f32 v[20:21], v[228:229], v[248:249], v[20:21] op_sel_hi:[1,0,1]
	v_pk_fma_f32 v[22:23], v[230:231], v[248:249], v[22:23] op_sel_hi:[1,0,1]
	v_cvt_pk_f32_fp8_e32 v[224:225], v162
	v_cvt_pk_f32_fp8_sdwa v[226:227], v162 src0_sel:WORD_1
	v_cvt_pk_f32_fp8_e32 v[228:229], v163
	v_cvt_pk_f32_fp8_sdwa v[230:231], v163 src0_sel:WORD_1
	v_pk_fma_f32 v[24:25], v[224:225], v[248:249], v[24:25] op_sel_hi:[1,0,1]
	v_pk_fma_f32 v[26:27], v[226:227], v[248:249], v[26:27] op_sel_hi:[1,0,1]
	v_pk_fma_f32 v[28:29], v[228:229], v[248:249], v[28:29] op_sel_hi:[1,0,1]
	v_pk_fma_f32 v[30:31], v[230:231], v[248:249], v[30:31] op_sel_hi:[1,0,1]
	v_cvt_pk_f32_fp8_e32 v[224:225], v164
	v_cvt_pk_f32_fp8_sdwa v[226:227], v164 src0_sel:WORD_1
	v_cvt_pk_f32_fp8_e32 v[228:229], v165
	v_cvt_pk_f32_fp8_sdwa v[230:231], v165 src0_sel:WORD_1
	v_pk_fma_f32 v[16:17], v[224:225], v[248:249], v[16:17] op_sel:[0,1,0] op_sel_hi:[1,1,1]
	v_pk_fma_f32 v[18:19], v[226:227], v[248:249], v[18:19] op_sel:[0,1,0] op_sel_hi:[1,1,1]
	v_pk_fma_f32 v[20:21], v[228:229], v[248:249], v[20:21] op_sel:[0,1,0] op_sel_hi:[1,1,1]
	v_pk_fma_f32 v[22:23], v[230:231], v[248:249], v[22:23] op_sel:[0,1,0] op_sel_hi:[1,1,1]
	v_cvt_pk_f32_fp8_e32 v[224:225], v166
	v_cvt_pk_f32_fp8_sdwa v[226:227], v166 src0_sel:WORD_1
	v_cvt_pk_f32_fp8_e32 v[228:229], v167
	v_cvt_pk_f32_fp8_sdwa v[230:231], v167 src0_sel:WORD_1
	v_pk_fma_f32 v[24:25], v[224:225], v[248:249], v[24:25] op_sel:[0,1,0] op_sel_hi:[1,1,1]
	v_pk_fma_f32 v[26:27], v[226:227], v[248:249], v[26:27] op_sel:[0,1,0] op_sel_hi:[1,1,1]
	v_pk_fma_f32 v[28:29], v[228:229], v[248:249], v[28:29] op_sel:[0,1,0] op_sel_hi:[1,1,1]
	v_pk_fma_f32 v[30:31], v[230:231], v[248:249], v[30:31] op_sel:[0,1,0] op_sel_hi:[1,1,1]
	v_cvt_pk_f32_fp8_e32 v[224:225], v168
	v_cvt_pk_f32_fp8_sdwa v[226:227], v168 src0_sel:WORD_1
	v_cvt_pk_f32_fp8_e32 v[228:229], v169
	v_cvt_pk_f32_fp8_sdwa v[230:231], v169 src0_sel:WORD_1
	v_pk_fma_f32 v[16:17], v[224:225], v[250:251], v[16:17] op_sel_hi:[1,0,1]
	v_pk_fma_f32 v[18:19], v[226:227], v[250:251], v[18:19] op_sel_hi:[1,0,1]
	v_pk_fma_f32 v[20:21], v[228:229], v[250:251], v[20:21] op_sel_hi:[1,0,1]
	v_pk_fma_f32 v[22:23], v[230:231], v[250:251], v[22:23] op_sel_hi:[1,0,1]
	v_cvt_pk_f32_fp8_e32 v[224:225], v170
	v_cvt_pk_f32_fp8_sdwa v[226:227], v170 src0_sel:WORD_1
	v_cvt_pk_f32_fp8_e32 v[228:229], v171
	v_cvt_pk_f32_fp8_sdwa v[230:231], v171 src0_sel:WORD_1
	v_pk_fma_f32 v[24:25], v[224:225], v[250:251], v[24:25] op_sel_hi:[1,0,1]
	v_pk_fma_f32 v[26:27], v[226:227], v[250:251], v[26:27] op_sel_hi:[1,0,1]
	v_pk_fma_f32 v[28:29], v[228:229], v[250:251], v[28:29] op_sel_hi:[1,0,1]
	v_pk_fma_f32 v[30:31], v[230:231], v[250:251], v[30:31] op_sel_hi:[1,0,1]
	v_cvt_pk_f32_fp8_e32 v[224:225], v172
	v_cvt_pk_f32_fp8_sdwa v[226:227], v172 src0_sel:WORD_1
	v_cvt_pk_f32_fp8_e32 v[228:229], v173
	v_cvt_pk_f32_fp8_sdwa v[230:231], v173 src0_sel:WORD_1
	v_pk_fma_f32 v[16:17], v[224:225], v[250:251], v[16:17] op_sel:[0,1,0] op_sel_hi:[1,1,1]
	v_pk_fma_f32 v[18:19], v[226:227], v[250:251], v[18:19] op_sel:[0,1,0] op_sel_hi:[1,1,1]
	v_pk_fma_f32 v[20:21], v[228:229], v[250:251], v[20:21] op_sel:[0,1,0] op_sel_hi:[1,1,1]
	v_pk_fma_f32 v[22:23], v[230:231], v[250:251], v[22:23] op_sel:[0,1,0] op_sel_hi:[1,1,1]
	v_cvt_pk_f32_fp8_e32 v[224:225], v174
	v_cvt_pk_f32_fp8_sdwa v[226:227], v174 src0_sel:WORD_1
	v_cvt_pk_f32_fp8_e32 v[228:229], v175
	v_cvt_pk_f32_fp8_sdwa v[230:231], v175 src0_sel:WORD_1
	v_pk_fma_f32 v[24:25], v[224:225], v[250:251], v[24:25] op_sel:[0,1,0] op_sel_hi:[1,1,1]
	v_pk_fma_f32 v[26:27], v[226:227], v[250:251], v[26:27] op_sel:[0,1,0] op_sel_hi:[1,1,1]
	v_pk_fma_f32 v[28:29], v[228:229], v[250:251], v[28:29] op_sel:[0,1,0] op_sel_hi:[1,1,1]
	v_pk_fma_f32 v[30:31], v[230:231], v[250:251], v[30:31] op_sel:[0,1,0] op_sel_hi:[1,1,1]
	s_sub_i32 s90, s90, 1
	s_cmp_eq_u32 s90, 0
	s_cbranch_scc1 .LV_sw3
; __device__ __forceinline__ void peer_tile(const Args& A, LAS unsigned char* lds, int tile) {
;     ...
;         for (int p = 0; p < 16; ++p) {
; #pragma unroll
;             for (int tk = 0; tk < 4; ++tk) {
;                 const int tl = tb + tk;
;                 const int beg = __builtin_amdgcn_readfirstlane(OFFS[tl * 17 + p]), end = __builtin_amdgcn_readfirstlane(OFFS[tl * 17 + p + 1]);
.LV_t1_s3:
	s_waitcnt lgkmcnt(0)
	v_add_u32_e32 v236, v232, v240
	v_add_u32_e32 v237, v233, v240
	v_add_u32_e32 v238, v234, v240
	v_add_u32_e32 v239, v235, v240
	global_load_dwordx4 v[160:163], v236, s[6:7]
	global_load_dwordx4 v[164:167], v237, s[6:7]
	global_load_dwordx4 v[168:171], v238, s[6:7]
	global_load_dwordx4 v[172:175], v239, s[6:7]
	ds_read_b128 v[232:235], v213 offset:112
	ds_read_b128 v[248:251], v213 offset:4928
	s_waitcnt vmcnt(12)
	v_cvt_pk_f32_fp8_e32 v[224:225], v176
	v_cvt_pk_f32_fp8_sdwa v[226:227], v176 src0_sel:WORD_1
	v_cvt_pk_f32_fp8_e32 v[228:229], v177
	v_cvt_pk_f32_fp8_sdwa v[230:231], v177 src0_sel:WORD_1
	v_pk_fma_f32 v[16:17], v[224:225], v[252:253], v[16:17] op_sel_hi:[1,0,1]
	v_pk_fma_f32 v[18:19], v[226:227], v[252:253], v[18:19] op_sel_hi:[1,0,1]
	v_pk_fma_f32 v[20:21], v[228:229], v[252:253], v[20:21] op_sel_hi:[1,0,1]
	v_pk_fma_f32 v[22:23], v[230:231], v[252:253], v[22:23] op_sel_hi:[1,0,1]
	v_cvt_pk_f32_fp8_e32 v[224:225], v178
	v_cvt_pk_f32_fp8_sdwa v[226:227], v178 src0_sel:WORD_1
	v_cvt_pk_f32_fp8_e32 v[228:229], v179
	v_cvt_pk_f32_fp8_sdwa v[230:231], v179 src0_sel:WORD_1
	v_pk_fma_f32 v[24:25], v[224:225], v[252:253], v[24:25] op_sel_hi:[1,0,1]
	v_pk_fma_f32 v[26:27], v[226:227], v[252:253], v[26:27] op_sel_hi:[1,0,1]
	v_pk_fma_f32 v[28:29], v[228:229], v[252:253], v[28:29] op_sel_hi:[1,0,1]
	v_pk_fma_f32 v[30:31], v[230:231], v[252:253], v[30:31] op_sel_hi:[1,0,1]
	v_cvt_pk_f32_fp8_e32 v[224:225], v180
	v_cvt_pk_f32_fp8_sdwa v[226:227], v180 src0_sel:WORD_1
	v_cvt_pk_f32_fp8_e32 v[228:229], v181
	v_cvt_pk_f32_fp8_sdwa v[230:231], v181 src0_sel:WORD_1
	v_pk_fma_f32 v[16:17], v[224:225], v[252:253], v[16:17] op_sel:[0,1,0] op_sel_hi:[1,1,1]
	v_pk_fma_f32 v[18:19], v[226:227], v[252:253], v[18:19] op_sel:[0,1,0] op_sel_hi:[1,1,1]
	v_pk_fma_f32 v[20:21], v[228:229], v[252:253], v[20:21] op_sel:[0,1,0] op_sel_hi:[1,1,1]
	v_pk_fma_f32 v[22:23], v[230:231], v[252:253], v[22:23] op_sel:[0,1,0] op_sel_hi:[1,1,1]
	v_cvt_pk_f32_fp8_e32 v[224:225], v182
	v_cvt_pk_f32_fp8_sdwa v[226:227], v182 src0_sel:WORD_1
	v_cvt_pk_f32_fp8_e32 v[228:229], v183
	v_cvt_pk_f32_fp8_sdwa v[230:231], v183 src0_sel:WORD_1
	v_pk_fma_f32 v[24:25], v[224:225], v[252:253], v[24:25] op_sel:[0,1,0] op_sel_hi:[1,1,1]
	v_pk_fma_f32 v[26:27], v[226:227], v[252:253], v[26:27] op_sel:[0,1,0] op_sel_hi:[1,1,1]
	v_pk_fma_f32 v[28:29], v[228:229], v[252:253], v[28:29] op_sel:[0,1,0] op_sel_hi:[1,1,1]
	v_pk_fma_f32 v[30:31], v[230:231], v[252:253], v[30:31] op_sel:[0,1,0] op_sel_hi:[1,1,1]
	v_cvt_pk_f32_fp8_e32 v[224:225], v184
	v_cvt_pk_f32_fp8_sdwa v[226:227], v184 src0_sel:WORD_1
	v_cvt_pk_f32_fp8_e32 v[228:229], v185
	v_cvt_pk_f32_fp8_sdwa v[230:231], v185 src0_sel:WORD_1
	v_pk_fma_f32 v[16:17], v[224:225], v[254:255], v[16:17] op_sel_hi:[1,0,1]
	v_pk_fma_f32 v[18:19], v[226:227], v[254:255], v[18:19] op_sel_hi:[1,0,1]
	v_pk_fma_f32 v[20:21], v[228:229], v[254:255], v[20:21] op_sel_hi:[1,0,1]
	v_pk_fma_f32 v[22:23], v[230:231], v[254:255], v[22:23] op_sel_hi:[1,0,1]
	v_cvt_pk_f32_fp8_e32 v[224:225], v186
	v_cvt_pk_f32_fp8_sdwa v[226:227], v186 src0_sel:WORD_1
	v_cvt_pk_f32_fp8_e32 v[228:229], v187
	v_cvt_pk_f32_fp8_sdwa v[230:231], v187 src0_sel:WORD_1
	v_pk_fma_f32 v[24:25], v[224:225], v[254:255], v[24:25] op_sel_hi:[1,0,1]
	v_pk_fma_f32 v[26:27], v[226:227], v[254:255], v[26:27] op_sel_hi:[1,0,1]
	v_pk_fma_f32 v[28:29], v[228:229], v[254:255], v[28:29] op_sel_hi:[1,0,1]
	v_pk_fma_f32 v[30:31], v[230:231], v[254:255], v[30:31] op_sel_hi:[1,0,1]
	v_cvt_pk_f32_fp8_e32 v[224:225], v188
	v_cvt_pk_f32_fp8_sdwa v[226:227], v188 src0_sel:WORD_1
	v_cvt_pk_f32_fp8_e32 v[228:229], v189
	v_cvt_pk_f32_fp8_sdwa v[230:231], v189 src0_sel:WORD_1
	v_pk_fma_f32 v[16:17], v[224:225], v[254:255], v[16:17] op_sel:[0,1,0] op_sel_hi:[1,1,1]
	v_pk_fma_f32 v[18:19], v[226:227], v[254:255], v[18:19] op_sel:[0,1,0] op_sel_hi:[1,1,1]
	v_pk_fma_f32 v[20:21], v[228:229], v[254:255], v[20:21] op_sel:[0,1,0] op_sel_hi:[1,1,1]
	v_pk_fma_f32 v[22:23], v[230:231], v[254:255], v[22:23] op_sel:[0,1,0] op_sel_hi:[1,1,1]
	v_cvt_pk_f32_fp8_e32 v[224:225], v190
	v_cvt_pk_f32_fp8_sdwa v[226:227], v190 src0_sel:WORD_1
	v_cvt_pk_f32_fp8_e32 v[228:229], v191
	v_cvt_pk_f32_fp8_sdwa v[230:231], v191 src0_sel:WORD_1
	v_pk_fma_f32 v[24:25], v[224:225], v[254:255], v[24:25] op_sel:[0,1,0] op_sel_hi:[1,1,1]
	v_pk_fma_f32 v[26:27], v[226:227], v[254:255], v[26:27] op_sel:[0,1,0] op_sel_hi:[1,1,1]
	v_pk_fma_f32 v[28:29], v[228:229], v[254:255], v[28:29] op_sel:[0,1,0] op_sel_hi:[1,1,1]
	v_pk_fma_f32 v[30:31], v[230:231], v[254:255], v[30:31] op_sel:[0,1,0] op_sel_hi:[1,1,1]
	v_add_u32_e32 v213, 64, v213
	s_add_i32 s21, s21, 4
	s_sub_i32 s90, s90, 1
	s_cmp_eq_u32 s90, 0
	s_cbranch_scc1 .LV_sw0
	s_branch .LV_t1_s0
.LV_t2_s0:
	s_cmp_ge_u32 s21, s20
	s_cbranch_scc1 .LV_done
	s_waitcnt lgkmcnt(0)
	v_add_u32_e32 v236, v232, v240
	v_add_u32_e32 v237, v233, v240
	v_add_u32_e32 v238, v234, v240
	v_add_u32_e32 v239, v235, v240
	global_load_dwordx4 v[176:179], v236, s[6:7]
	global_load_dwordx4 v[180:183], v237, s[6:7]
	global_load_dwordx4 v[184:187], v238, s[6:7]
	global_load_dwordx4 v[188:191], v239, s[6:7]
	ds_read_b128 v[232:235], v213 offset:64
	ds_read_b128 v[252:255], v213 offset:4880
	s_waitcnt vmcnt(12)
	v_cvt_pk_f32_fp8_e32 v[224:225], v128
	v_cvt_pk_f32_fp8_sdwa v[226:227], v128 src0_sel:WORD_1
	v_cvt_pk_f32_fp8_e32 v[228:229], v129
	v_cvt_pk_f32_fp8_sdwa v[230:231], v129 src0_sel:WORD_1
	v_pk_fma_f32 v[32:33], v[224:225], v[248:249], v[32:33] op_sel_hi:[1,0,1]
	v_pk_fma_f32 v[34:35], v[226:227], v[248:249], v[34:35] op_sel_hi:[1,0,1]
	v_pk_fma_f32 v[36:37], v[228:229], v[248:249], v[36:37] op_sel_hi:[1,0,1]
	v_pk_fma_f32 v[38:39], v[230:231], v[248:249], v[38:39] op_sel_hi:[1,0,1]
	v_cvt_pk_f32_fp8_e32 v[224:225], v130
	v_cvt_pk_f32_fp8_sdwa v[226:227], v130 src0_sel:WORD_1
	v_cvt_pk_f32_fp8_e32 v[228:229], v131
	v_cvt_pk_f32_fp8_sdwa v[230:231], v131 src0_sel:WORD_1
	v_pk_fma_f32 v[40:41], v[224:225], v[248:249], v[40:41] op_sel_hi:[1,0,1]
	v_pk_fma_f32 v[42:43], v[226:227], v[248:249], v[42:43] op_sel_hi:[1,0,1]
	v_pk_fma_f32 v[44:45], v[228:229], v[248:249], v[44:45] op_sel_hi:[1,0,1]
	v_pk_fma_f32 v[46:47], v[230:231], v[248:249], v[46:47] op_sel_hi:[1,0,1]
	v_cvt_pk_f32_fp8_e32 v[224:225], v132
	v_cvt_pk_f32_fp8_sdwa v[226:227], v132 src0_sel:WORD_1
	v_cvt_pk_f32_fp8_e32 v[228:229], v133
	v_cvt_pk_f32_fp8_sdwa v[230:231], v133 src0_sel:WORD_1
	v_pk_fma_f32 v[32:33], v[224:225], v[248:249], v[32:33] op_sel:[0,1,0] op_sel_hi:[1,1,1]
	v_pk_fma_f32 v[34:35], v[226:227], v[248:249], v[34:35] op_sel:[0,1,0] op_sel_hi:[1,1,1]
	v_pk_fma_f32 v[36:37], v[228:229], v[248:249], v[36:37] op_sel:[0,1,0] op_sel_hi:[1,1,1]
	v_pk_fma_f32 v[38:39], v[230:231], v[248:249], v[38:39] op_sel:[0,1,0] op_sel_hi:[1,1,1]
	v_cvt_pk_f32_fp8_e32 v[224:225], v134
	v_cvt_pk_f32_fp8_sdwa v[226:227], v134 src0_sel:WORD_1
	v_cvt_pk_f32_fp8_e32 v[228:229], v135
	v_cvt_pk_f32_fp8_sdwa v[230:231], v135 src0_sel:WORD_1
	v_pk_fma_f32 v[40:41], v[224:225], v[248:249], v[40:41] op_sel:[0,1,0] op_sel_hi:[1,1,1]
	v_pk_fma_f32 v[42:43], v[226:227], v[248:249], v[42:43] op_sel:[0,1,0] op_sel_hi:[1,1,1]
	v_pk_fma_f32 v[44:45], v[228:229], v[248:249], v[44:45] op_sel:[0,1,0] op_sel_hi:[1,1,1]
	v_pk_fma_f32 v[46:47], v[230:231], v[248:249], v[46:47] op_sel:[0,1,0] op_sel_hi:[1,1,1]
	v_cvt_pk_f32_fp8_e32 v[224:225], v136
	v_cvt_pk_f32_fp8_sdwa v[226:227], v136 src0_sel:WORD_1
	v_cvt_pk_f32_fp8_e32 v[228:229], v137
	v_cvt_pk_f32_fp8_sdwa v[230:231], v137 src0_sel:WORD_1
	v_pk_fma_f32 v[32:33], v[224:225], v[250:251], v[32:33] op_sel_hi:[1,0,1]
	v_pk_fma_f32 v[34:35], v[226:227], v[250:251], v[34:35] op_sel_hi:[1,0,1]
	v_pk_fma_f32 v[36:37], v[228:229], v[250:251], v[36:37] op_sel_hi:[1,0,1]
	v_pk_fma_f32 v[38:39], v[230:231], v[250:251], v[38:39] op_sel_hi:[1,0,1]
	v_cvt_pk_f32_fp8_e32 v[224:225], v138
	v_cvt_pk_f32_fp8_sdwa v[226:227], v138 src0_sel:WORD_1
	v_cvt_pk_f32_fp8_e32 v[228:229], v139
	v_cvt_pk_f32_fp8_sdwa v[230:231], v139 src0_sel:WORD_1
	v_pk_fma_f32 v[40:41], v[224:225], v[250:251], v[40:41] op_sel_hi:[1,0,1]
	v_pk_fma_f32 v[42:43], v[226:227], v[250:251], v[42:43] op_sel_hi:[1,0,1]
	v_pk_fma_f32 v[44:45], v[228:229], v[250:251], v[44:45] op_sel_hi:[1,0,1]
	v_pk_fma_f32 v[46:47], v[230:231], v[250:251], v[46:47] op_sel_hi:[1,0,1]
	v_cvt_pk_f32_fp8_e32 v[224:225], v140
	v_cvt_pk_f32_fp8_sdwa v[226:227], v140 src0_sel:WORD_1
	v_cvt_pk_f32_fp8_e32 v[228:229], v141
	v_cvt_pk_f32_fp8_sdwa v[230:231], v141 src0_sel:WORD_1
	v_pk_fma_f32 v[32:33], v[224:225], v[250:251], v[32:33] op_sel:[0,1,0] op_sel_hi:[1,1,1]
	v_pk_fma_f32 v[34:35], v[226:227], v[250:251], v[34:35] op_sel:[0,1,0] op_sel_hi:[1,1,1]
	v_pk_fma_f32 v[36:37], v[228:229], v[250:251], v[36:37] op_sel:[0,1,0] op_sel_hi:[1,1,1]
	v_pk_fma_f32 v[38:39], v[230:231], v[250:251], v[38:39] op_sel:[0,1,0] op_sel_hi:[1,1,1]
	v_cvt_pk_f32_fp8_e32 v[224:225], v142
	v_cvt_pk_f32_fp8_sdwa v[226:227], v142 src0_sel:WORD_1
	v_cvt_pk_f32_fp8_e32 v[228:229], v143
	v_cvt_pk_f32_fp8_sdwa v[230:231], v143 src0_sel:WORD_1
	v_pk_fma_f32 v[40:41], v[224:225], v[250:251], v[40:41] op_sel:[0,1,0] op_sel_hi:[1,1,1]
	v_pk_fma_f32 v[42:43], v[226:227], v[250:251], v[42:43] op_sel:[0,1,0] op_sel_hi:[1,1,1]
	v_pk_fma_f32 v[44:45], v[228:229], v[250:251], v[44:45] op_sel:[0,1,0] op_sel_hi:[1,1,1]
	v_pk_fma_f32 v[46:47], v[230:231], v[250:251], v[46:47] op_sel:[0,1,0] op_sel_hi:[1,1,1]
	s_sub_i32 s90, s90, 1
	s_cmp_eq_u32 s90, 0
	s_cbranch_scc1 .LV_sw1
.LV_t2_s1:
	s_waitcnt lgkmcnt(0)
	v_add_u32_e32 v236, v232, v240
	v_add_u32_e32 v237, v233, v240
	v_add_u32_e32 v238, v234, v240
	v_add_u32_e32 v239, v235, v240
	global_load_dwordx4 v[128:131], v236, s[6:7]
	global_load_dwordx4 v[132:135], v237, s[6:7]
	global_load_dwordx4 v[136:139], v238, s[6:7]
	global_load_dwordx4 v[140:143], v239, s[6:7]
	ds_read_b128 v[232:235], v213 offset:80
	ds_read_b128 v[248:251], v213 offset:4896
	s_waitcnt vmcnt(12)
	v_cvt_pk_f32_fp8_e32 v[224:225], v144
	v_cvt_pk_f32_fp8_sdwa v[226:227], v144 src0_sel:WORD_1
	v_cvt_pk_f32_fp8_e32 v[228:229], v145
	v_cvt_pk_f32_fp8_sdwa v[230:231], v145 src0_sel:WORD_1
	v_pk_fma_f32 v[32:33], v[224:225], v[252:253], v[32:33] op_sel_hi:[1,0,1]
	v_pk_fma_f32 v[34:35], v[226:227], v[252:253], v[34:35] op_sel_hi:[1,0,1]
	v_pk_fma_f32 v[36:37], v[228:229], v[252:253], v[36:37] op_sel_hi:[1,0,1]
	v_pk_fma_f32 v[38:39], v[230:231], v[252:253], v[38:39] op_sel_hi:[1,0,1]
	v_cvt_pk_f32_fp8_e32 v[224:225], v146
	v_cvt_pk_f32_fp8_sdwa v[226:227], v146 src0_sel:WORD_1
	v_cvt_pk_f32_fp8_e32 v[228:229], v147
	v_cvt_pk_f32_fp8_sdwa v[230:231], v147 src0_sel:WORD_1
	v_pk_fma_f32 v[40:41], v[224:225], v[252:253], v[40:41] op_sel_hi:[1,0,1]
	v_pk_fma_f32 v[42:43], v[226:227], v[252:253], v[42:43] op_sel_hi:[1,0,1]
	v_pk_fma_f32 v[44:45], v[228:229], v[252:253], v[44:45] op_sel_hi:[1,0,1]
	v_pk_fma_f32 v[46:47], v[230:231], v[252:253], v[46:47] op_sel_hi:[1,0,1]
	v_cvt_pk_f32_fp8_e32 v[224:225], v148
	v_cvt_pk_f32_fp8_sdwa v[226:227], v148 src0_sel:WORD_1
	v_cvt_pk_f32_fp8_e32 v[228:229], v149
	v_cvt_pk_f32_fp8_sdwa v[230:231], v149 src0_sel:WORD_1
	v_pk_fma_f32 v[32:33], v[224:225], v[252:253], v[32:33] op_sel:[0,1,0] op_sel_hi:[1,1,1]
	v_pk_fma_f32 v[34:35], v[226:227], v[252:253], v[34:35] op_sel:[0,1,0] op_sel_hi:[1,1,1]
	v_pk_fma_f32 v[36:37], v[228:229], v[252:253], v[36:37] op_sel:[0,1,0] op_sel_hi:[1,1,1]
	v_pk_fma_f32 v[38:39], v[230:231], v[252:253], v[38:39] op_sel:[0,1,0] op_sel_hi:[1,1,1]
	v_cvt_pk_f32_fp8_e32 v[224:225], v150
	v_cvt_pk_f32_fp8_sdwa v[226:227], v150 src0_sel:WORD_1
	v_cvt_pk_f32_fp8_e32 v[228:229], v151
	v_cvt_pk_f32_fp8_sdwa v[230:231], v151 src0_sel:WORD_1
	v_pk_fma_f32 v[40:41], v[224:225], v[252:253], v[40:41] op_sel:[0,1,0] op_sel_hi:[1,1,1]
	v_pk_fma_f32 v[42:43], v[226:227], v[252:253], v[42:43] op_sel:[0,1,0] op_sel_hi:[1,1,1]
	v_pk_fma_f32 v[44:45], v[228:229], v[252:253], v[44:45] op_sel:[0,1,0] op_sel_hi:[1,1,1]
	v_pk_fma_f32 v[46:47], v[230:231], v[252:253], v[46:47] op_sel:[0,1,0] op_sel_hi:[1,1,1]
	v_cvt_pk_f32_fp8_e32 v[224:225], v152
	v_cvt_pk_f32_fp8_sdwa v[226:227], v152 src0_sel:WORD_1
	v_cvt_pk_f32_fp8_e32 v[228:229], v153
	v_cvt_pk_f32_fp8_sdwa v[230:231], v153 src0_sel:WORD_1
	v_pk_fma_f32 v[32:33], v[224:225], v[254:255], v[32:33] op_sel_hi:[1,0,1]
	v_pk_fma_f32 v[34:35], v[226:227], v[254:255], v[34:35] op_sel_hi:[1,0,1]
	v_pk_fma_f32 v[36:37], v[228:229], v[254:255], v[36:37] op_sel_hi:[1,0,1]
	v_pk_fma_f32 v[38:39], v[230:231], v[254:255], v[38:39] op_sel_hi:[1,0,1]
	v_cvt_pk_f32_fp8_e32 v[224:225], v154
	v_cvt_pk_f32_fp8_sdwa v[226:227], v154 src0_sel:WORD_1
	v_cvt_pk_f32_fp8_e32 v[228:229], v155
	v_cvt_pk_f32_fp8_sdwa v[230:231], v155 src0_sel:WORD_1
	v_pk_fma_f32 v[40:41], v[224:225], v[254:255], v[40:41] op_sel_hi:[1,0,1]
	v_pk_fma_f32 v[42:43], v[226:227], v[254:255], v[42:43] op_sel_hi:[1,0,1]
	v_pk_fma_f32 v[44:45], v[228:229], v[254:255], v[44:45] op_sel_hi:[1,0,1]
	v_pk_fma_f32 v[46:47], v[230:231], v[254:255], v[46:47] op_sel_hi:[1,0,1]
	v_cvt_pk_f32_fp8_e32 v[224:225], v156
	v_cvt_pk_f32_fp8_sdwa v[226:227], v156 src0_sel:WORD_1
	v_cvt_pk_f32_fp8_e32 v[228:229], v157
	v_cvt_pk_f32_fp8_sdwa v[230:231], v157 src0_sel:WORD_1
	v_pk_fma_f32 v[32:33], v[224:225], v[254:255], v[32:33] op_sel:[0,1,0] op_sel_hi:[1,1,1]
	v_pk_fma_f32 v[34:35], v[226:227], v[254:255], v[34:35] op_sel:[0,1,0] op_sel_hi:[1,1,1]
	v_pk_fma_f32 v[36:37], v[228:229], v[254:255], v[36:37] op_sel:[0,1,0] op_sel_hi:[1,1,1]
	v_pk_fma_f32 v[38:39], v[230:231], v[254:255], v[38:39] op_sel:[0,1,0] op_sel_hi:[1,1,1]
	v_cvt_pk_f32_fp8_e32 v[224:225], v158
	v_cvt_pk_f32_fp8_sdwa v[226:227], v158 src0_sel:WORD_1
	v_cvt_pk_f32_fp8_e32 v[228:229], v159
	v_cvt_pk_f32_fp8_sdwa v[230:231], v159 src0_sel:WORD_1
	v_pk_fma_f32 v[40:41], v[224:225], v[254:255], v[40:41] op_sel:[0,1,0] op_sel_hi:[1,1,1]
	v_pk_fma_f32 v[42:43], v[226:227], v[254:255], v[42:43] op_sel:[0,1,0] op_sel_hi:[1,1,1]
	v_pk_fma_f32 v[44:45], v[228:229], v[254:255], v[44:45] op_sel:[0,1,0] op_sel_hi:[1,1,1]
	v_pk_fma_f32 v[46:47], v[230:231], v[254:255], v[46:47] op_sel:[0,1,0] op_sel_hi:[1,1,1]
	s_sub_i32 s90, s90, 1
	s_cmp_eq_u32 s90, 0
	s_cbranch_scc1 .LV_sw2
.LV_t2_s2:
	s_waitcnt lgkmcnt(0)
	v_add_u32_e32 v236, v232, v240
	v_add_u32_e32 v237, v233, v240
	v_add_u32_e32 v238, v234, v240
	v_add_u32_e32 v239, v235, v240
	global_load_dwordx4 v[144:147], v236, s[6:7]
	global_load_dwordx4 v[148:151], v237, s[6:7]
	global_load_dwordx4 v[152:155], v238, s[6:7]
	global_load_dwordx4 v[156:159], v239, s[6:7]
	ds_read_b128 v[232:235], v213 offset:96
	ds_read_b128 v[252:255], v213 offset:4912
	s_waitcnt vmcnt(12)
	v_cvt_pk_f32_fp8_e32 v[224:225], v160
	v_cvt_pk_f32_fp8_sdwa v[226:227], v160 src0_sel:WORD_1
	v_cvt_pk_f32_fp8_e32 v[228:229], v161
	v_cvt_pk_f32_fp8_sdwa v[230:231], v161 src0_sel:WORD_1
	v_pk_fma_f32 v[32:33], v[224:225], v[248:249], v[32:33] op_sel_hi:[1,0,1]
	v_pk_fma_f32 v[34:35], v[226:227], v[248:249], v[34:35] op_sel_hi:[1,0,1]
	v_pk_fma_f32 v[36:37], v[228:229], v[248:249], v[36:37] op_sel_hi:[1,0,1]
	v_pk_fma_f32 v[38:39], v[230:231], v[248:249], v[38:39] op_sel_hi:[1,0,1]
	v_cvt_pk_f32_fp8_e32 v[224:225], v162
	v_cvt_pk_f32_fp8_sdwa v[226:227], v162 src0_sel:WORD_1
	v_cvt_pk_f32_fp8_e32 v[228:229], v163
	v_cvt_pk_f32_fp8_sdwa v[230:231], v163 src0_sel:WORD_1
	v_pk_fma_f32 v[40:41], v[224:225], v[248:249], v[40:41] op_sel_hi:[1,0,1]
	v_pk_fma_f32 v[42:43], v[226:227], v[248:249], v[42:43] op_sel_hi:[1,0,1]
	v_pk_fma_f32 v[44:45], v[228:229], v[248:249], v[44:45] op_sel_hi:[1,0,1]
	v_pk_fma_f32 v[46:47], v[230:231], v[248:249], v[46:47] op_sel_hi:[1,0,1]
	v_cvt_pk_f32_fp8_e32 v[224:225], v164
	v_cvt_pk_f32_fp8_sdwa v[226:227], v164 src0_sel:WORD_1
	v_cvt_pk_f32_fp8_e32 v[228:229], v165
	v_cvt_pk_f32_fp8_sdwa v[230:231], v165 src0_sel:WORD_1
	v_pk_fma_f32 v[32:33], v[224:225], v[248:249], v[32:33] op_sel:[0,1,0] op_sel_hi:[1,1,1]
	v_pk_fma_f32 v[34:35], v[226:227], v[248:249], v[34:35] op_sel:[0,1,0] op_sel_hi:[1,1,1]
	v_pk_fma_f32 v[36:37], v[228:229], v[248:249], v[36:37] op_sel:[0,1,0] op_sel_hi:[1,1,1]
	v_pk_fma_f32 v[38:39], v[230:231], v[248:249], v[38:39] op_sel:[0,1,0] op_sel_hi:[1,1,1]
	v_cvt_pk_f32_fp8_e32 v[224:225], v166
	v_cvt_pk_f32_fp8_sdwa v[226:227], v166 src0_sel:WORD_1
	v_cvt_pk_f32_fp8_e32 v[228:229], v167
	v_cvt_pk_f32_fp8_sdwa v[230:231], v167 src0_sel:WORD_1
	v_pk_fma_f32 v[40:41], v[224:225], v[248:249], v[40:41] op_sel:[0,1,0] op_sel_hi:[1,1,1]
	v_pk_fma_f32 v[42:43], v[226:227], v[248:249], v[42:43] op_sel:[0,1,0] op_sel_hi:[1,1,1]
	v_pk_fma_f32 v[44:45], v[228:229], v[248:249], v[44:45] op_sel:[0,1,0] op_sel_hi:[1,1,1]
	v_pk_fma_f32 v[46:47], v[230:231], v[248:249], v[46:47] op_sel:[0,1,0] op_sel_hi:[1,1,1]
	v_cvt_pk_f32_fp8_e32 v[224:225], v168
	v_cvt_pk_f32_fp8_sdwa v[226:227], v168 src0_sel:WORD_1
	v_cvt_pk_f32_fp8_e32 v[228:229], v169
	v_cvt_pk_f32_fp8_sdwa v[230:231], v169 src0_sel:WORD_1
	v_pk_fma_f32 v[32:33], v[224:225], v[250:251], v[32:33] op_sel_hi:[1,0,1]
	v_pk_fma_f32 v[34:35], v[226:227], v[250:251], v[34:35] op_sel_hi:[1,0,1]
	v_pk_fma_f32 v[36:37], v[228:229], v[250:251], v[36:37] op_sel_hi:[1,0,1]
	v_pk_fma_f32 v[38:39], v[230:231], v[250:251], v[38:39] op_sel_hi:[1,0,1]
	v_cvt_pk_f32_fp8_e32 v[224:225], v170
	v_cvt_pk_f32_fp8_sdwa v[226:227], v170 src0_sel:WORD_1
	v_cvt_pk_f32_fp8_e32 v[228:229], v171
	v_cvt_pk_f32_fp8_sdwa v[230:231], v171 src0_sel:WORD_1
	v_pk_fma_f32 v[40:41], v[224:225], v[250:251], v[40:41] op_sel_hi:[1,0,1]
	v_pk_fma_f32 v[42:43], v[226:227], v[250:251], v[42:43] op_sel_hi:[1,0,1]
	v_pk_fma_f32 v[44:45], v[228:229], v[250:251], v[44:45] op_sel_hi:[1,0,1]
	v_pk_fma_f32 v[46:47], v[230:231], v[250:251], v[46:47] op_sel_hi:[1,0,1]
	v_cvt_pk_f32_fp8_e32 v[224:225], v172
	v_cvt_pk_f32_fp8_sdwa v[226:227], v172 src0_sel:WORD_1
	v_cvt_pk_f32_fp8_e32 v[228:229], v173
	v_cvt_pk_f32_fp8_sdwa v[230:231], v173 src0_sel:WORD_1
	v_pk_fma_f32 v[32:33], v[224:225], v[250:251], v[32:33] op_sel:[0,1,0] op_sel_hi:[1,1,1]
	v_pk_fma_f32 v[34:35], v[226:227], v[250:251], v[34:35] op_sel:[0,1,0] op_sel_hi:[1,1,1]
	v_pk_fma_f32 v[36:37], v[228:229], v[250:251], v[36:37] op_sel:[0,1,0] op_sel_hi:[1,1,1]
	v_pk_fma_f32 v[38:39], v[230:231], v[250:251], v[38:39] op_sel:[0,1,0] op_sel_hi:[1,1,1]
	v_cvt_pk_f32_fp8_e32 v[224:225], v174
	v_cvt_pk_f32_fp8_sdwa v[226:227], v174 src0_sel:WORD_1
	v_cvt_pk_f32_fp8_e32 v[228:229], v175
	v_cvt_pk_f32_fp8_sdwa v[230:231], v175 src0_sel:WORD_1
	v_pk_fma_f32 v[40:41], v[224:225], v[250:251], v[40:41] op_sel:[0,1,0] op_sel_hi:[1,1,1]
	v_pk_fma_f32 v[42:43], v[226:227], v[250:251], v[42:43] op_sel:[0,1,0] op_sel_hi:[1,1,1]
	v_pk_fma_f32 v[44:45], v[228:229], v[250:251], v[44:45] op_sel:[0,1,0] op_sel_hi:[1,1,1]
	v_pk_fma_f32 v[46:47], v[230:231], v[250:251], v[46:47] op_sel:[0,1,0] op_sel_hi:[1,1,1]
	s_sub_i32 s90, s90, 1
	s_cmp_eq_u32 s90, 0
	s_cbranch_scc1 .LV_sw3
; __device__ __forceinline__ void peer_tile(const Args& A, LAS unsigned char* lds, int tile) {
;     ...
;         for (int p = 0; p < 16; ++p) {
; #pragma unroll
;             for (int tk = 0; tk < 4; ++tk) {
;                 const int tl = tb + tk;
;                 const int beg = __builtin_amdgcn_readfirstlane(OFFS[tl * 17 + p]), end = __builtin_amdgcn_readfirstlane(OFFS[tl * 17 + p + 1]);
.LV_t2_s3:
	s_waitcnt lgkmcnt(0)
	v_add_u32_e32 v236, v232, v240
	v_add_u32_e32 v237, v233, v240
	v_add_u32_e32 v238, v234, v240
	v_add_u32_e32 v239, v235, v240
	global_load_dwordx4 v[160:163], v236, s[6:7]
	global_load_dwordx4 v[164:167], v237, s[6:7]
	global_load_dwordx4 v[168:171], v238, s[6:7]
	global_load_dwordx4 v[172:175], v239, s[6:7]
	ds_read_b128 v[232:235], v213 offset:112
	ds_read_b128 v[248:251], v213 offset:4928
	s_waitcnt vmcnt(12)
	v_cvt_pk_f32_fp8_e32 v[224:225], v176
	v_cvt_pk_f32_fp8_sdwa v[226:227], v176 src0_sel:WORD_1
	v_cvt_pk_f32_fp8_e32 v[228:229], v177
	v_cvt_pk_f32_fp8_sdwa v[230:231], v177 src0_sel:WORD_1
	v_pk_fma_f32 v[32:33], v[224:225], v[252:253], v[32:33] op_sel_hi:[1,0,1]
	v_pk_fma_f32 v[34:35], v[226:227], v[252:253], v[34:35] op_sel_hi:[1,0,1]
	v_pk_fma_f32 v[36:37], v[228:229], v[252:253], v[36:37] op_sel_hi:[1,0,1]
	v_pk_fma_f32 v[38:39], v[230:231], v[252:253], v[38:39] op_sel_hi:[1,0,1]
	v_cvt_pk_f32_fp8_e32 v[224:225], v178
	v_cvt_pk_f32_fp8_sdwa v[226:227], v178 src0_sel:WORD_1
	v_cvt_pk_f32_fp8_e32 v[228:229], v179
	v_cvt_pk_f32_fp8_sdwa v[230:231], v179 src0_sel:WORD_1
	v_pk_fma_f32 v[40:41], v[224:225], v[252:253], v[40:41] op_sel_hi:[1,0,1]
	v_pk_fma_f32 v[42:43], v[226:227], v[252:253], v[42:43] op_sel_hi:[1,0,1]
	v_pk_fma_f32 v[44:45], v[228:229], v[252:253], v[44:45] op_sel_hi:[1,0,1]
	v_pk_fma_f32 v[46:47], v[230:231], v[252:253], v[46:47] op_sel_hi:[1,0,1]
	v_cvt_pk_f32_fp8_e32 v[224:225], v180
	v_cvt_pk_f32_fp8_sdwa v[226:227], v180 src0_sel:WORD_1
	v_cvt_pk_f32_fp8_e32 v[228:229], v181
	v_cvt_pk_f32_fp8_sdwa v[230:231], v181 src0_sel:WORD_1
	v_pk_fma_f32 v[32:33], v[224:225], v[252:253], v[32:33] op_sel:[0,1,0] op_sel_hi:[1,1,1]
	v_pk_fma_f32 v[34:35], v[226:227], v[252:253], v[34:35] op_sel:[0,1,0] op_sel_hi:[1,1,1]
	v_pk_fma_f32 v[36:37], v[228:229], v[252:253], v[36:37] op_sel:[0,1,0] op_sel_hi:[1,1,1]
	v_pk_fma_f32 v[38:39], v[230:231], v[252:253], v[38:39] op_sel:[0,1,0] op_sel_hi:[1,1,1]
	v_cvt_pk_f32_fp8_e32 v[224:225], v182
	v_cvt_pk_f32_fp8_sdwa v[226:227], v182 src0_sel:WORD_1
	v_cvt_pk_f32_fp8_e32 v[228:229], v183
	v_cvt_pk_f32_fp8_sdwa v[230:231], v183 src0_sel:WORD_1
	v_pk_fma_f32 v[40:41], v[224:225], v[252:253], v[40:41] op_sel:[0,1,0] op_sel_hi:[1,1,1]
	v_pk_fma_f32 v[42:43], v[226:227], v[252:253], v[42:43] op_sel:[0,1,0] op_sel_hi:[1,1,1]
	v_pk_fma_f32 v[44:45], v[228:229], v[252:253], v[44:45] op_sel:[0,1,0] op_sel_hi:[1,1,1]
	v_pk_fma_f32 v[46:47], v[230:231], v[252:253], v[46:47] op_sel:[0,1,0] op_sel_hi:[1,1,1]
	v_cvt_pk_f32_fp8_e32 v[224:225], v184
	v_cvt_pk_f32_fp8_sdwa v[226:227], v184 src0_sel:WORD_1
	v_cvt_pk_f32_fp8_e32 v[228:229], v185
	v_cvt_pk_f32_fp8_sdwa v[230:231], v185 src0_sel:WORD_1
	v_pk_fma_f32 v[32:33], v[224:225], v[254:255], v[32:33] op_sel_hi:[1,0,1]
	v_pk_fma_f32 v[34:35], v[226:227], v[254:255], v[34:35] op_sel_hi:[1,0,1]
	v_pk_fma_f32 v[36:37], v[228:229], v[254:255], v[36:37] op_sel_hi:[1,0,1]
	v_pk_fma_f32 v[38:39], v[230:231], v[254:255], v[38:39] op_sel_hi:[1,0,1]
	v_cvt_pk_f32_fp8_e32 v[224:225], v186
	v_cvt_pk_f32_fp8_sdwa v[226:227], v186 src0_sel:WORD_1
	v_cvt_pk_f32_fp8_e32 v[228:229], v187
	v_cvt_pk_f32_fp8_sdwa v[230:231], v187 src0_sel:WORD_1
	v_pk_fma_f32 v[40:41], v[224:225], v[254:255], v[40:41] op_sel_hi:[1,0,1]
	v_pk_fma_f32 v[42:43], v[226:227], v[254:255], v[42:43] op_sel_hi:[1,0,1]
	v_pk_fma_f32 v[44:45], v[228:229], v[254:255], v[44:45] op_sel_hi:[1,0,1]
	v_pk_fma_f32 v[46:47], v[230:231], v[254:255], v[46:47] op_sel_hi:[1,0,1]
	v_cvt_pk_f32_fp8_e32 v[224:225], v188
	v_cvt_pk_f32_fp8_sdwa v[226:227], v188 src0_sel:WORD_1
	v_cvt_pk_f32_fp8_e32 v[228:229], v189
	v_cvt_pk_f32_fp8_sdwa v[230:231], v189 src0_sel:WORD_1
	v_pk_fma_f32 v[32:33], v[224:225], v[254:255], v[32:33] op_sel:[0,1,0] op_sel_hi:[1,1,1]
	v_pk_fma_f32 v[34:35], v[226:227], v[254:255], v[34:35] op_sel:[0,1,0] op_sel_hi:[1,1,1]
	v_pk_fma_f32 v[36:37], v[228:229], v[254:255], v[36:37] op_sel:[0,1,0] op_sel_hi:[1,1,1]
	v_pk_fma_f32 v[38:39], v[230:231], v[254:255], v[38:39] op_sel:[0,1,0] op_sel_hi:[1,1,1]
	v_cvt_pk_f32_fp8_e32 v[224:225], v190
	v_cvt_pk_f32_fp8_sdwa v[226:227], v190 src0_sel:WORD_1
	v_cvt_pk_f32_fp8_e32 v[228:229], v191
	v_cvt_pk_f32_fp8_sdwa v[230:231], v191 src0_sel:WORD_1
	v_pk_fma_f32 v[40:41], v[224:225], v[254:255], v[40:41] op_sel:[0,1,0] op_sel_hi:[1,1,1]
	v_pk_fma_f32 v[42:43], v[226:227], v[254:255], v[42:43] op_sel:[0,1,0] op_sel_hi:[1,1,1]
	v_pk_fma_f32 v[44:45], v[228:229], v[254:255], v[44:45] op_sel:[0,1,0] op_sel_hi:[1,1,1]
	v_pk_fma_f32 v[46:47], v[230:231], v[254:255], v[46:47] op_sel:[0,1,0] op_sel_hi:[1,1,1]
	v_add_u32_e32 v213, 64, v213
	s_add_i32 s21, s21, 4
	s_sub_i32 s90, s90, 1
	s_cmp_eq_u32 s90, 0
	s_cbranch_scc1 .LV_sw0
	s_branch .LV_t2_s0
.LV_t3_s0:
	s_cmp_ge_u32 s21, s20
	s_cbranch_scc1 .LV_done
	s_waitcnt lgkmcnt(0)
	v_add_u32_e32 v236, v232, v240
	v_add_u32_e32 v237, v233, v240
	v_add_u32_e32 v238, v234, v240
	v_add_u32_e32 v239, v235, v240
	global_load_dwordx4 v[176:179], v236, s[6:7]
	global_load_dwordx4 v[180:183], v237, s[6:7]
	global_load_dwordx4 v[184:187], v238, s[6:7]
	global_load_dwordx4 v[188:191], v239, s[6:7]
	ds_read_b128 v[232:235], v213 offset:64
	ds_read_b128 v[252:255], v213 offset:4880
	s_waitcnt vmcnt(12)
	v_cvt_pk_f32_fp8_e32 v[224:225], v128
	v_cvt_pk_f32_fp8_sdwa v[226:227], v128 src0_sel:WORD_1
	v_cvt_pk_f32_fp8_e32 v[228:229], v129
	v_cvt_pk_f32_fp8_sdwa v[230:231], v129 src0_sel:WORD_1
	v_pk_fma_f32 v[48:49], v[224:225], v[248:249], v[48:49] op_sel_hi:[1,0,1]
	v_pk_fma_f32 v[50:51], v[226:227], v[248:249], v[50:51] op_sel_hi:[1,0,1]
	v_pk_fma_f32 v[52:53], v[228:229], v[248:249], v[52:53] op_sel_hi:[1,0,1]
	v_pk_fma_f32 v[54:55], v[230:231], v[248:249], v[54:55] op_sel_hi:[1,0,1]
	v_cvt_pk_f32_fp8_e32 v[224:225], v130
	v_cvt_pk_f32_fp8_sdwa v[226:227], v130 src0_sel:WORD_1
	v_cvt_pk_f32_fp8_e32 v[228:229], v131
	v_cvt_pk_f32_fp8_sdwa v[230:231], v131 src0_sel:WORD_1
	v_pk_fma_f32 v[56:57], v[224:225], v[248:249], v[56:57] op_sel_hi:[1,0,1]
	v_pk_fma_f32 v[58:59], v[226:227], v[248:249], v[58:59] op_sel_hi:[1,0,1]
	v_pk_fma_f32 v[60:61], v[228:229], v[248:249], v[60:61] op_sel_hi:[1,0,1]
	v_pk_fma_f32 v[62:63], v[230:231], v[248:249], v[62:63] op_sel_hi:[1,0,1]
	v_cvt_pk_f32_fp8_e32 v[224:225], v132
	v_cvt_pk_f32_fp8_sdwa v[226:227], v132 src0_sel:WORD_1
	v_cvt_pk_f32_fp8_e32 v[228:229], v133
	v_cvt_pk_f32_fp8_sdwa v[230:231], v133 src0_sel:WORD_1
	v_pk_fma_f32 v[48:49], v[224:225], v[248:249], v[48:49] op_sel:[0,1,0] op_sel_hi:[1,1,1]
	v_pk_fma_f32 v[50:51], v[226:227], v[248:249], v[50:51] op_sel:[0,1,0] op_sel_hi:[1,1,1]
	v_pk_fma_f32 v[52:53], v[228:229], v[248:249], v[52:53] op_sel:[0,1,0] op_sel_hi:[1,1,1]
	v_pk_fma_f32 v[54:55], v[230:231], v[248:249], v[54:55] op_sel:[0,1,0] op_sel_hi:[1,1,1]
	v_cvt_pk_f32_fp8_e32 v[224:225], v134
	v_cvt_pk_f32_fp8_sdwa v[226:227], v134 src0_sel:WORD_1
	v_cvt_pk_f32_fp8_e32 v[228:229], v135
	v_cvt_pk_f32_fp8_sdwa v[230:231], v135 src0_sel:WORD_1
	v_pk_fma_f32 v[56:57], v[224:225], v[248:249], v[56:57] op_sel:[0,1,0] op_sel_hi:[1,1,1]
	v_pk_fma_f32 v[58:59], v[226:227], v[248:249], v[58:59] op_sel:[0,1,0] op_sel_hi:[1,1,1]
	v_pk_fma_f32 v[60:61], v[228:229], v[248:249], v[60:61] op_sel:[0,1,0] op_sel_hi:[1,1,1]
	v_pk_fma_f32 v[62:63], v[230:231], v[248:249], v[62:63] op_sel:[0,1,0] op_sel_hi:[1,1,1]
	v_cvt_pk_f32_fp8_e32 v[224:225], v136
	v_cvt_pk_f32_fp8_sdwa v[226:227], v136 src0_sel:WORD_1
	v_cvt_pk_f32_fp8_e32 v[228:229], v137
	v_cvt_pk_f32_fp8_sdwa v[230:231], v137 src0_sel:WORD_1
	v_pk_fma_f32 v[48:49], v[224:225], v[250:251], v[48:49] op_sel_hi:[1,0,1]
	v_pk_fma_f32 v[50:51], v[226:227], v[250:251], v[50:51] op_sel_hi:[1,0,1]
	v_pk_fma_f32 v[52:53], v[228:229], v[250:251], v[52:53] op_sel_hi:[1,0,1]
	v_pk_fma_f32 v[54:55], v[230:231], v[250:251], v[54:55] op_sel_hi:[1,0,1]
	v_cvt_pk_f32_fp8_e32 v[224:225], v138
	v_cvt_pk_f32_fp8_sdwa v[226:227], v138 src0_sel:WORD_1
	v_cvt_pk_f32_fp8_e32 v[228:229], v139
	v_cvt_pk_f32_fp8_sdwa v[230:231], v139 src0_sel:WORD_1
	v_pk_fma_f32 v[56:57], v[224:225], v[250:251], v[56:57] op_sel_hi:[1,0,1]
	v_pk_fma_f32 v[58:59], v[226:227], v[250:251], v[58:59] op_sel_hi:[1,0,1]
	v_pk_fma_f32 v[60:61], v[228:229], v[250:251], v[60:61] op_sel_hi:[1,0,1]
	v_pk_fma_f32 v[62:63], v[230:231], v[250:251], v[62:63] op_sel_hi:[1,0,1]
	v_cvt_pk_f32_fp8_e32 v[224:225], v140
	v_cvt_pk_f32_fp8_sdwa v[226:227], v140 src0_sel:WORD_1
	v_cvt_pk_f32_fp8_e32 v[228:229], v141
	v_cvt_pk_f32_fp8_sdwa v[230:231], v141 src0_sel:WORD_1
	v_pk_fma_f32 v[48:49], v[224:225], v[250:251], v[48:49] op_sel:[0,1,0] op_sel_hi:[1,1,1]
	v_pk_fma_f32 v[50:51], v[226:227], v[250:251], v[50:51] op_sel:[0,1,0] op_sel_hi:[1,1,1]
	v_pk_fma_f32 v[52:53], v[228:229], v[250:251], v[52:53] op_sel:[0,1,0] op_sel_hi:[1,1,1]
	v_pk_fma_f32 v[54:55], v[230:231], v[250:251], v[54:55] op_sel:[0,1,0] op_sel_hi:[1,1,1]
	v_cvt_pk_f32_fp8_e32 v[224:225], v142
	v_cvt_pk_f32_fp8_sdwa v[226:227], v142 src0_sel:WORD_1
	v_cvt_pk_f32_fp8_e32 v[228:229], v143
	v_cvt_pk_f32_fp8_sdwa v[230:231], v143 src0_sel:WORD_1
	v_pk_fma_f32 v[56:57], v[224:225], v[250:251], v[56:57] op_sel:[0,1,0] op_sel_hi:[1,1,1]
	v_pk_fma_f32 v[58:59], v[226:227], v[250:251], v[58:59] op_sel:[0,1,0] op_sel_hi:[1,1,1]
	v_pk_fma_f32 v[60:61], v[228:229], v[250:251], v[60:61] op_sel:[0,1,0] op_sel_hi:[1,1,1]
	v_pk_fma_f32 v[62:63], v[230:231], v[250:251], v[62:63] op_sel:[0,1,0] op_sel_hi:[1,1,1]
	s_sub_i32 s90, s90, 1
	s_cmp_eq_u32 s90, 0
	s_cbranch_scc1 .LV_sw1
.LV_t3_s1:
	s_waitcnt lgkmcnt(0)
	v_add_u32_e32 v236, v232, v240
	v_add_u32_e32 v237, v233, v240
	v_add_u32_e32 v238, v234, v240
	v_add_u32_e32 v239, v235, v240
	global_load_dwordx4 v[128:131], v236, s[6:7]
	global_load_dwordx4 v[132:135], v237, s[6:7]
	global_load_dwordx4 v[136:139], v238, s[6:7]
	global_load_dwordx4 v[140:143], v239, s[6:7]
	ds_read_b128 v[232:235], v213 offset:80
	ds_read_b128 v[248:251], v213 offset:4896
	s_waitcnt vmcnt(12)
	v_cvt_pk_f32_fp8_e32 v[224:225], v144
	v_cvt_pk_f32_fp8_sdwa v[226:227], v144 src0_sel:WORD_1
	v_cvt_pk_f32_fp8_e32 v[228:229], v145
	v_cvt_pk_f32_fp8_sdwa v[230:231], v145 src0_sel:WORD_1
	v_pk_fma_f32 v[48:49], v[224:225], v[252:253], v[48:49] op_sel_hi:[1,0,1]
	v_pk_fma_f32 v[50:51], v[226:227], v[252:253], v[50:51] op_sel_hi:[1,0,1]
	v_pk_fma_f32 v[52:53], v[228:229], v[252:253], v[52:53] op_sel_hi:[1,0,1]
	v_pk_fma_f32 v[54:55], v[230:231], v[252:253], v[54:55] op_sel_hi:[1,0,1]
	v_cvt_pk_f32_fp8_e32 v[224:225], v146
	v_cvt_pk_f32_fp8_sdwa v[226:227], v146 src0_sel:WORD_1
	v_cvt_pk_f32_fp8_e32 v[228:229], v147
	v_cvt_pk_f32_fp8_sdwa v[230:231], v147 src0_sel:WORD_1
	v_pk_fma_f32 v[56:57], v[224:225], v[252:253], v[56:57] op_sel_hi:[1,0,1]
	v_pk_fma_f32 v[58:59], v[226:227], v[252:253], v[58:59] op_sel_hi:[1,0,1]
	v_pk_fma_f32 v[60:61], v[228:229], v[252:253], v[60:61] op_sel_hi:[1,0,1]
	v_pk_fma_f32 v[62:63], v[230:231], v[252:253], v[62:63] op_sel_hi:[1,0,1]
	v_cvt_pk_f32_fp8_e32 v[224:225], v148
	v_cvt_pk_f32_fp8_sdwa v[226:227], v148 src0_sel:WORD_1
	v_cvt_pk_f32_fp8_e32 v[228:229], v149
	v_cvt_pk_f32_fp8_sdwa v[230:231], v149 src0_sel:WORD_1
	v_pk_fma_f32 v[48:49], v[224:225], v[252:253], v[48:49] op_sel:[0,1,0] op_sel_hi:[1,1,1]
	v_pk_fma_f32 v[50:51], v[226:227], v[252:253], v[50:51] op_sel:[0,1,0] op_sel_hi:[1,1,1]
	v_pk_fma_f32 v[52:53], v[228:229], v[252:253], v[52:53] op_sel:[0,1,0] op_sel_hi:[1,1,1]
	v_pk_fma_f32 v[54:55], v[230:231], v[252:253], v[54:55] op_sel:[0,1,0] op_sel_hi:[1,1,1]
	v_cvt_pk_f32_fp8_e32 v[224:225], v150
	v_cvt_pk_f32_fp8_sdwa v[226:227], v150 src0_sel:WORD_1
	v_cvt_pk_f32_fp8_e32 v[228:229], v151
	v_cvt_pk_f32_fp8_sdwa v[230:231], v151 src0_sel:WORD_1
	v_pk_fma_f32 v[56:57], v[224:225], v[252:253], v[56:57] op_sel:[0,1,0] op_sel_hi:[1,1,1]
	v_pk_fma_f32 v[58:59], v[226:227], v[252:253], v[58:59] op_sel:[0,1,0] op_sel_hi:[1,1,1]
	v_pk_fma_f32 v[60:61], v[228:229], v[252:253], v[60:61] op_sel:[0,1,0] op_sel_hi:[1,1,1]
	v_pk_fma_f32 v[62:63], v[230:231], v[252:253], v[62:63] op_sel:[0,1,0] op_sel_hi:[1,1,1]
	v_cvt_pk_f32_fp8_e32 v[224:225], v152
	v_cvt_pk_f32_fp8_sdwa v[226:227], v152 src0_sel:WORD_1
	v_cvt_pk_f32_fp8_e32 v[228:229], v153
	v_cvt_pk_f32_fp8_sdwa v[230:231], v153 src0_sel:WORD_1
	v_pk_fma_f32 v[48:49], v[224:225], v[254:255], v[48:49] op_sel_hi:[1,0,1]
	v_pk_fma_f32 v[50:51], v[226:227], v[254:255], v[50:51] op_sel_hi:[1,0,1]
	v_pk_fma_f32 v[52:53], v[228:229], v[254:255], v[52:53] op_sel_hi:[1,0,1]
	v_pk_fma_f32 v[54:55], v[230:231], v[254:255], v[54:55] op_sel_hi:[1,0,1]
	v_cvt_pk_f32_fp8_e32 v[224:225], v154
	v_cvt_pk_f32_fp8_sdwa v[226:227], v154 src0_sel:WORD_1
	v_cvt_pk_f32_fp8_e32 v[228:229], v155
	v_cvt_pk_f32_fp8_sdwa v[230:231], v155 src0_sel:WORD_1
	v_pk_fma_f32 v[56:57], v[224:225], v[254:255], v[56:57] op_sel_hi:[1,0,1]
	v_pk_fma_f32 v[58:59], v[226:227], v[254:255], v[58:59] op_sel_hi:[1,0,1]
	v_pk_fma_f32 v[60:61], v[228:229], v[254:255], v[60:61] op_sel_hi:[1,0,1]
	v_pk_fma_f32 v[62:63], v[230:231], v[254:255], v[62:63] op_sel_hi:[1,0,1]
	v_cvt_pk_f32_fp8_e32 v[224:225], v156
	v_cvt_pk_f32_fp8_sdwa v[226:227], v156 src0_sel:WORD_1
	v_cvt_pk_f32_fp8_e32 v[228:229], v157
	v_cvt_pk_f32_fp8_sdwa v[230:231], v157 src0_sel:WORD_1
	v_pk_fma_f32 v[48:49], v[224:225], v[254:255], v[48:49] op_sel:[0,1,0] op_sel_hi:[1,1,1]
	v_pk_fma_f32 v[50:51], v[226:227], v[254:255], v[50:51] op_sel:[0,1,0] op_sel_hi:[1,1,1]
	v_pk_fma_f32 v[52:53], v[228:229], v[254:255], v[52:53] op_sel:[0,1,0] op_sel_hi:[1,1,1]
	v_pk_fma_f32 v[54:55], v[230:231], v[254:255], v[54:55] op_sel:[0,1,0] op_sel_hi:[1,1,1]
	v_cvt_pk_f32_fp8_e32 v[224:225], v158
	v_cvt_pk_f32_fp8_sdwa v[226:227], v158 src0_sel:WORD_1
	v_cvt_pk_f32_fp8_e32 v[228:229], v159
	v_cvt_pk_f32_fp8_sdwa v[230:231], v159 src0_sel:WORD_1
	v_pk_fma_f32 v[56:57], v[224:225], v[254:255], v[56:57] op_sel:[0,1,0] op_sel_hi:[1,1,1]
	v_pk_fma_f32 v[58:59], v[226:227], v[254:255], v[58:59] op_sel:[0,1,0] op_sel_hi:[1,1,1]
	v_pk_fma_f32 v[60:61], v[228:229], v[254:255], v[60:61] op_sel:[0,1,0] op_sel_hi:[1,1,1]
	v_pk_fma_f32 v[62:63], v[230:231], v[254:255], v[62:63] op_sel:[0,1,0] op_sel_hi:[1,1,1]
	s_sub_i32 s90, s90, 1
	s_cmp_eq_u32 s90, 0
	s_cbranch_scc1 .LV_sw2
.LV_t3_s2:
	s_waitcnt lgkmcnt(0)
	v_add_u32_e32 v236, v232, v240
	v_add_u32_e32 v237, v233, v240
	v_add_u32_e32 v238, v234, v240
	v_add_u32_e32 v239, v235, v240
	global_load_dwordx4 v[144:147], v236, s[6:7]
	global_load_dwordx4 v[148:151], v237, s[6:7]
	global_load_dwordx4 v[152:155], v238, s[6:7]
	global_load_dwordx4 v[156:159], v239, s[6:7]
	ds_read_b128 v[232:235], v213 offset:96
	ds_read_b128 v[252:255], v213 offset:4912
	s_waitcnt vmcnt(12)
	v_cvt_pk_f32_fp8_e32 v[224:225], v160
	v_cvt_pk_f32_fp8_sdwa v[226:227], v160 src0_sel:WORD_1
	v_cvt_pk_f32_fp8_e32 v[228:229], v161
	v_cvt_pk_f32_fp8_sdwa v[230:231], v161 src0_sel:WORD_1
	v_pk_fma_f32 v[48:49], v[224:225], v[248:249], v[48:49] op_sel_hi:[1,0,1]
	v_pk_fma_f32 v[50:51], v[226:227], v[248:249], v[50:51] op_sel_hi:[1,0,1]
	v_pk_fma_f32 v[52:53], v[228:229], v[248:249], v[52:53] op_sel_hi:[1,0,1]
	v_pk_fma_f32 v[54:55], v[230:231], v[248:249], v[54:55] op_sel_hi:[1,0,1]
	v_cvt_pk_f32_fp8_e32 v[224:225], v162
	v_cvt_pk_f32_fp8_sdwa v[226:227], v162 src0_sel:WORD_1
	v_cvt_pk_f32_fp8_e32 v[228:229], v163
	v_cvt_pk_f32_fp8_sdwa v[230:231], v163 src0_sel:WORD_1
	v_pk_fma_f32 v[56:57], v[224:225], v[248:249], v[56:57] op_sel_hi:[1,0,1]
	v_pk_fma_f32 v[58:59], v[226:227], v[248:249], v[58:59] op_sel_hi:[1,0,1]
	v_pk_fma_f32 v[60:61], v[228:229], v[248:249], v[60:61] op_sel_hi:[1,0,1]
	v_pk_fma_f32 v[62:63], v[230:231], v[248:249], v[62:63] op_sel_hi:[1,0,1]
	v_cvt_pk_f32_fp8_e32 v[224:225], v164
	v_cvt_pk_f32_fp8_sdwa v[226:227], v164 src0_sel:WORD_1
	v_cvt_pk_f32_fp8_e32 v[228:229], v165
	v_cvt_pk_f32_fp8_sdwa v[230:231], v165 src0_sel:WORD_1
	v_pk_fma_f32 v[48:49], v[224:225], v[248:249], v[48:49] op_sel:[0,1,0] op_sel_hi:[1,1,1]
	v_pk_fma_f32 v[50:51], v[226:227], v[248:249], v[50:51] op_sel:[0,1,0] op_sel_hi:[1,1,1]
	v_pk_fma_f32 v[52:53], v[228:229], v[248:249], v[52:53] op_sel:[0,1,0] op_sel_hi:[1,1,1]
	v_pk_fma_f32 v[54:55], v[230:231], v[248:249], v[54:55] op_sel:[0,1,0] op_sel_hi:[1,1,1]
	v_cvt_pk_f32_fp8_e32 v[224:225], v166
	v_cvt_pk_f32_fp8_sdwa v[226:227], v166 src0_sel:WORD_1
	v_cvt_pk_f32_fp8_e32 v[228:229], v167
	v_cvt_pk_f32_fp8_sdwa v[230:231], v167 src0_sel:WORD_1
	v_pk_fma_f32 v[56:57], v[224:225], v[248:249], v[56:57] op_sel:[0,1,0] op_sel_hi:[1,1,1]
	v_pk_fma_f32 v[58:59], v[226:227], v[248:249], v[58:59] op_sel:[0,1,0] op_sel_hi:[1,1,1]
	v_pk_fma_f32 v[60:61], v[228:229], v[248:249], v[60:61] op_sel:[0,1,0] op_sel_hi:[1,1,1]
	v_pk_fma_f32 v[62:63], v[230:231], v[248:249], v[62:63] op_sel:[0,1,0] op_sel_hi:[1,1,1]
	v_cvt_pk_f32_fp8_e32 v[224:225], v168
	v_cvt_pk_f32_fp8_sdwa v[226:227], v168 src0_sel:WORD_1
	v_cvt_pk_f32_fp8_e32 v[228:229], v169
	v_cvt_pk_f32_fp8_sdwa v[230:231], v169 src0_sel:WORD_1
	v_pk_fma_f32 v[48:49], v[224:225], v[250:251], v[48:49] op_sel_hi:[1,0,1]
	v_pk_fma_f32 v[50:51], v[226:227], v[250:251], v[50:51] op_sel_hi:[1,0,1]
	v_pk_fma_f32 v[52:53], v[228:229], v[250:251], v[52:53] op_sel_hi:[1,0,1]
	v_pk_fma_f32 v[54:55], v[230:231], v[250:251], v[54:55] op_sel_hi:[1,0,1]
	v_cvt_pk_f32_fp8_e32 v[224:225], v170
	v_cvt_pk_f32_fp8_sdwa v[226:227], v170 src0_sel:WORD_1
	v_cvt_pk_f32_fp8_e32 v[228:229], v171
	v_cvt_pk_f32_fp8_sdwa v[230:231], v171 src0_sel:WORD_1
	v_pk_fma_f32 v[56:57], v[224:225], v[250:251], v[56:57] op_sel_hi:[1,0,1]
	v_pk_fma_f32 v[58:59], v[226:227], v[250:251], v[58:59] op_sel_hi:[1,0,1]
	v_pk_fma_f32 v[60:61], v[228:229], v[250:251], v[60:61] op_sel_hi:[1,0,1]
	v_pk_fma_f32 v[62:63], v[230:231], v[250:251], v[62:63] op_sel_hi:[1,0,1]
	v_cvt_pk_f32_fp8_e32 v[224:225], v172
	v_cvt_pk_f32_fp8_sdwa v[226:227], v172 src0_sel:WORD_1
	v_cvt_pk_f32_fp8_e32 v[228:229], v173
	v_cvt_pk_f32_fp8_sdwa v[230:231], v173 src0_sel:WORD_1
	v_pk_fma_f32 v[48:49], v[224:225], v[250:251], v[48:49] op_sel:[0,1,0] op_sel_hi:[1,1,1]
	v_pk_fma_f32 v[50:51], v[226:227], v[250:251], v[50:51] op_sel:[0,1,0] op_sel_hi:[1,1,1]
	v_pk_fma_f32 v[52:53], v[228:229], v[250:251], v[52:53] op_sel:[0,1,0] op_sel_hi:[1,1,1]
	v_pk_fma_f32 v[54:55], v[230:231], v[250:251], v[54:55] op_sel:[0,1,0] op_sel_hi:[1,1,1]
	v_cvt_pk_f32_fp8_e32 v[224:225], v174
	v_cvt_pk_f32_fp8_sdwa v[226:227], v174 src0_sel:WORD_1
	v_cvt_pk_f32_fp8_e32 v[228:229], v175
	v_cvt_pk_f32_fp8_sdwa v[230:231], v175 src0_sel:WORD_1
	v_pk_fma_f32 v[56:57], v[224:225], v[250:251], v[56:57] op_sel:[0,1,0] op_sel_hi:[1,1,1]
	v_pk_fma_f32 v[58:59], v[226:227], v[250:251], v[58:59] op_sel:[0,1,0] op_sel_hi:[1,1,1]
	v_pk_fma_f32 v[60:61], v[228:229], v[250:251], v[60:61] op_sel:[0,1,0] op_sel_hi:[1,1,1]
	v_pk_fma_f32 v[62:63], v[230:231], v[250:251], v[62:63] op_sel:[0,1,0] op_sel_hi:[1,1,1]
	s_sub_i32 s90, s90, 1
	s_cmp_eq_u32 s90, 0
	s_cbranch_scc1 .LV_sw3
; __device__ __forceinline__ void peer_tile(const Args& A, LAS unsigned char* lds, int tile) {
;     ...
;         for (int p = 0; p < 16; ++p) {
; #pragma unroll
;             for (int tk = 0; tk < 4; ++tk) {
;                 const int tl = tb + tk;
;                 const int beg = __builtin_amdgcn_readfirstlane(OFFS[tl * 17 + p]), end = __builtin_amdgcn_readfirstlane(OFFS[tl * 17 + p + 1]);
.LV_t3_s3:
	s_waitcnt lgkmcnt(0)
	v_add_u32_e32 v236, v232, v240
	v_add_u32_e32 v237, v233, v240
	v_add_u32_e32 v238, v234, v240
	v_add_u32_e32 v239, v235, v240
	global_load_dwordx4 v[160:163], v236, s[6:7]
	global_load_dwordx4 v[164:167], v237, s[6:7]
	global_load_dwordx4 v[168:171], v238, s[6:7]
	global_load_dwordx4 v[172:175], v239, s[6:7]
	ds_read_b128 v[232:235], v213 offset:112
	ds_read_b128 v[248:251], v213 offset:4928
	s_waitcnt vmcnt(12)
	v_cvt_pk_f32_fp8_e32 v[224:225], v176
	v_cvt_pk_f32_fp8_sdwa v[226:227], v176 src0_sel:WORD_1
	v_cvt_pk_f32_fp8_e32 v[228:229], v177
	v_cvt_pk_f32_fp8_sdwa v[230:231], v177 src0_sel:WORD_1
	v_pk_fma_f32 v[48:49], v[224:225], v[252:253], v[48:49] op_sel_hi:[1,0,1]
	v_pk_fma_f32 v[50:51], v[226:227], v[252:253], v[50:51] op_sel_hi:[1,0,1]
	v_pk_fma_f32 v[52:53], v[228:229], v[252:253], v[52:53] op_sel_hi:[1,0,1]
	v_pk_fma_f32 v[54:55], v[230:231], v[252:253], v[54:55] op_sel_hi:[1,0,1]
	v_cvt_pk_f32_fp8_e32 v[224:225], v178
	v_cvt_pk_f32_fp8_sdwa v[226:227], v178 src0_sel:WORD_1
	v_cvt_pk_f32_fp8_e32 v[228:229], v179
	v_cvt_pk_f32_fp8_sdwa v[230:231], v179 src0_sel:WORD_1
	v_pk_fma_f32 v[56:57], v[224:225], v[252:253], v[56:57] op_sel_hi:[1,0,1]
	v_pk_fma_f32 v[58:59], v[226:227], v[252:253], v[58:59] op_sel_hi:[1,0,1]
	v_pk_fma_f32 v[60:61], v[228:229], v[252:253], v[60:61] op_sel_hi:[1,0,1]
	v_pk_fma_f32 v[62:63], v[230:231], v[252:253], v[62:63] op_sel_hi:[1,0,1]
	v_cvt_pk_f32_fp8_e32 v[224:225], v180
	v_cvt_pk_f32_fp8_sdwa v[226:227], v180 src0_sel:WORD_1
	v_cvt_pk_f32_fp8_e32 v[228:229], v181
	v_cvt_pk_f32_fp8_sdwa v[230:231], v181 src0_sel:WORD_1
	v_pk_fma_f32 v[48:49], v[224:225], v[252:253], v[48:49] op_sel:[0,1,0] op_sel_hi:[1,1,1]
	v_pk_fma_f32 v[50:51], v[226:227], v[252:253], v[50:51] op_sel:[0,1,0] op_sel_hi:[1,1,1]
	v_pk_fma_f32 v[52:53], v[228:229], v[252:253], v[52:53] op_sel:[0,1,0] op_sel_hi:[1,1,1]
	v_pk_fma_f32 v[54:55], v[230:231], v[252:253], v[54:55] op_sel:[0,1,0] op_sel_hi:[1,1,1]
	v_cvt_pk_f32_fp8_e32 v[224:225], v182
	v_cvt_pk_f32_fp8_sdwa v[226:227], v182 src0_sel:WORD_1
	v_cvt_pk_f32_fp8_e32 v[228:229], v183
	v_cvt_pk_f32_fp8_sdwa v[230:231], v183 src0_sel:WORD_1
	v_pk_fma_f32 v[56:57], v[224:225], v[252:253], v[56:57] op_sel:[0,1,0] op_sel_hi:[1,1,1]
	v_pk_fma_f32 v[58:59], v[226:227], v[252:253], v[58:59] op_sel:[0,1,0] op_sel_hi:[1,1,1]
	v_pk_fma_f32 v[60:61], v[228:229], v[252:253], v[60:61] op_sel:[0,1,0] op_sel_hi:[1,1,1]
	v_pk_fma_f32 v[62:63], v[230:231], v[252:253], v[62:63] op_sel:[0,1,0] op_sel_hi:[1,1,1]
	v_cvt_pk_f32_fp8_e32 v[224:225], v184
	v_cvt_pk_f32_fp8_sdwa v[226:227], v184 src0_sel:WORD_1
	v_cvt_pk_f32_fp8_e32 v[228:229], v185
	v_cvt_pk_f32_fp8_sdwa v[230:231], v185 src0_sel:WORD_1
	v_pk_fma_f32 v[48:49], v[224:225], v[254:255], v[48:49] op_sel_hi:[1,0,1]
	v_pk_fma_f32 v[50:51], v[226:227], v[254:255], v[50:51] op_sel_hi:[1,0,1]
	v_pk_fma_f32 v[52:53], v[228:229], v[254:255], v[52:53] op_sel_hi:[1,0,1]
	v_pk_fma_f32 v[54:55], v[230:231], v[254:255], v[54:55] op_sel_hi:[1,0,1]
	v_cvt_pk_f32_fp8_e32 v[224:225], v186
	v_cvt_pk_f32_fp8_sdwa v[226:227], v186 src0_sel:WORD_1
	v_cvt_pk_f32_fp8_e32 v[228:229], v187
	v_cvt_pk_f32_fp8_sdwa v[230:231], v187 src0_sel:WORD_1
	v_pk_fma_f32 v[56:57], v[224:225], v[254:255], v[56:57] op_sel_hi:[1,0,1]
	v_pk_fma_f32 v[58:59], v[226:227], v[254:255], v[58:59] op_sel_hi:[1,0,1]
	v_pk_fma_f32 v[60:61], v[228:229], v[254:255], v[60:61] op_sel_hi:[1,0,1]
	v_pk_fma_f32 v[62:63], v[230:231], v[254:255], v[62:63] op_sel_hi:[1,0,1]
	v_cvt_pk_f32_fp8_e32 v[224:225], v188
	v_cvt_pk_f32_fp8_sdwa v[226:227], v188 src0_sel:WORD_1
	v_cvt_pk_f32_fp8_e32 v[228:229], v189
	v_cvt_pk_f32_fp8_sdwa v[230:231], v189 src0_sel:WORD_1
	v_pk_fma_f32 v[48:49], v[224:225], v[254:255], v[48:49] op_sel:[0,1,0] op_sel_hi:[1,1,1]
	v_pk_fma_f32 v[50:51], v[226:227], v[254:255], v[50:51] op_sel:[0,1,0] op_sel_hi:[1,1,1]
	v_pk_fma_f32 v[52:53], v[228:229], v[254:255], v[52:53] op_sel:[0,1,0] op_sel_hi:[1,1,1]
	v_pk_fma_f32 v[54:55], v[230:231], v[254:255], v[54:55] op_sel:[0,1,0] op_sel_hi:[1,1,1]
	v_cvt_pk_f32_fp8_e32 v[224:225], v190
	v_cvt_pk_f32_fp8_sdwa v[226:227], v190 src0_sel:WORD_1
	v_cvt_pk_f32_fp8_e32 v[228:229], v191
	v_cvt_pk_f32_fp8_sdwa v[230:231], v191 src0_sel:WORD_1
	v_pk_fma_f32 v[56:57], v[224:225], v[254:255], v[56:57] op_sel:[0,1,0] op_sel_hi:[1,1,1]
	v_pk_fma_f32 v[58:59], v[226:227], v[254:255], v[58:59] op_sel:[0,1,0] op_sel_hi:[1,1,1]
	v_pk_fma_f32 v[60:61], v[228:229], v[254:255], v[60:61] op_sel:[0,1,0] op_sel_hi:[1,1,1]
	v_pk_fma_f32 v[62:63], v[230:231], v[254:255], v[62:63] op_sel:[0,1,0] op_sel_hi:[1,1,1]
	v_add_u32_e32 v213, 64, v213
	s_add_i32 s21, s21, 4
	s_sub_i32 s90, s90, 1
	s_cmp_eq_u32 s90, 0
	s_cbranch_scc1 .LV_sw0
	s_branch .LV_t3_s0
.LV_t4_s0:
	s_cmp_ge_u32 s21, s20
	s_cbranch_scc1 .LV_done
	s_waitcnt lgkmcnt(0)
	v_add_u32_e32 v236, v232, v240
	v_add_u32_e32 v237, v233, v240
	v_add_u32_e32 v238, v234, v240
	v_add_u32_e32 v239, v235, v240
	global_load_dwordx4 v[176:179], v236, s[6:7]
	global_load_dwordx4 v[180:183], v237, s[6:7]
	global_load_dwordx4 v[184:187], v238, s[6:7]
	global_load_dwordx4 v[188:191], v239, s[6:7]
	ds_read_b128 v[232:235], v213 offset:64
	ds_read_b128 v[252:255], v213 offset:4880
	s_waitcnt vmcnt(12)
	v_cvt_pk_f32_fp8_e32 v[224:225], v128
	v_cvt_pk_f32_fp8_sdwa v[226:227], v128 src0_sel:WORD_1
	v_cvt_pk_f32_fp8_e32 v[228:229], v129
	v_cvt_pk_f32_fp8_sdwa v[230:231], v129 src0_sel:WORD_1
	v_pk_fma_f32 v[64:65], v[224:225], v[248:249], v[64:65] op_sel_hi:[1,0,1]
	v_pk_fma_f32 v[66:67], v[226:227], v[248:249], v[66:67] op_sel_hi:[1,0,1]
	v_pk_fma_f32 v[68:69], v[228:229], v[248:249], v[68:69] op_sel_hi:[1,0,1]
	v_pk_fma_f32 v[70:71], v[230:231], v[248:249], v[70:71] op_sel_hi:[1,0,1]
	v_cvt_pk_f32_fp8_e32 v[224:225], v130
	v_cvt_pk_f32_fp8_sdwa v[226:227], v130 src0_sel:WORD_1
	v_cvt_pk_f32_fp8_e32 v[228:229], v131
	v_cvt_pk_f32_fp8_sdwa v[230:231], v131 src0_sel:WORD_1
	v_pk_fma_f32 v[72:73], v[224:225], v[248:249], v[72:73] op_sel_hi:[1,0,1]
	v_pk_fma_f32 v[74:75], v[226:227], v[248:249], v[74:75] op_sel_hi:[1,0,1]
	v_pk_fma_f32 v[76:77], v[228:229], v[248:249], v[76:77] op_sel_hi:[1,0,1]
	v_pk_fma_f32 v[78:79], v[230:231], v[248:249], v[78:79] op_sel_hi:[1,0,1]
	v_cvt_pk_f32_fp8_e32 v[224:225], v132
	v_cvt_pk_f32_fp8_sdwa v[226:227], v132 src0_sel:WORD_1
	v_cvt_pk_f32_fp8_e32 v[228:229], v133
	v_cvt_pk_f32_fp8_sdwa v[230:231], v133 src0_sel:WORD_1
	v_pk_fma_f32 v[64:65], v[224:225], v[248:249], v[64:65] op_sel:[0,1,0] op_sel_hi:[1,1,1]
	v_pk_fma_f32 v[66:67], v[226:227], v[248:249], v[66:67] op_sel:[0,1,0] op_sel_hi:[1,1,1]
	v_pk_fma_f32 v[68:69], v[228:229], v[248:249], v[68:69] op_sel:[0,1,0] op_sel_hi:[1,1,1]
	v_pk_fma_f32 v[70:71], v[230:231], v[248:249], v[70:71] op_sel:[0,1,0] op_sel_hi:[1,1,1]
	v_cvt_pk_f32_fp8_e32 v[224:225], v134
	v_cvt_pk_f32_fp8_sdwa v[226:227], v134 src0_sel:WORD_1
	v_cvt_pk_f32_fp8_e32 v[228:229], v135
	v_cvt_pk_f32_fp8_sdwa v[230:231], v135 src0_sel:WORD_1
	v_pk_fma_f32 v[72:73], v[224:225], v[248:249], v[72:73] op_sel:[0,1,0] op_sel_hi:[1,1,1]
	v_pk_fma_f32 v[74:75], v[226:227], v[248:249], v[74:75] op_sel:[0,1,0] op_sel_hi:[1,1,1]
	v_pk_fma_f32 v[76:77], v[228:229], v[248:249], v[76:77] op_sel:[0,1,0] op_sel_hi:[1,1,1]
	v_pk_fma_f32 v[78:79], v[230:231], v[248:249], v[78:79] op_sel:[0,1,0] op_sel_hi:[1,1,1]
	v_cvt_pk_f32_fp8_e32 v[224:225], v136
	v_cvt_pk_f32_fp8_sdwa v[226:227], v136 src0_sel:WORD_1
	v_cvt_pk_f32_fp8_e32 v[228:229], v137
	v_cvt_pk_f32_fp8_sdwa v[230:231], v137 src0_sel:WORD_1
	v_pk_fma_f32 v[64:65], v[224:225], v[250:251], v[64:65] op_sel_hi:[1,0,1]
	v_pk_fma_f32 v[66:67], v[226:227], v[250:251], v[66:67] op_sel_hi:[1,0,1]
	v_pk_fma_f32 v[68:69], v[228:229], v[250:251], v[68:69] op_sel_hi:[1,0,1]
	v_pk_fma_f32 v[70:71], v[230:231], v[250:251], v[70:71] op_sel_hi:[1,0,1]
	v_cvt_pk_f32_fp8_e32 v[224:225], v138
	v_cvt_pk_f32_fp8_sdwa v[226:227], v138 src0_sel:WORD_1
	v_cvt_pk_f32_fp8_e32 v[228:229], v139
	v_cvt_pk_f32_fp8_sdwa v[230:231], v139 src0_sel:WORD_1
	v_pk_fma_f32 v[72:73], v[224:225], v[250:251], v[72:73] op_sel_hi:[1,0,1]
	v_pk_fma_f32 v[74:75], v[226:227], v[250:251], v[74:75] op_sel_hi:[1,0,1]
	v_pk_fma_f32 v[76:77], v[228:229], v[250:251], v[76:77] op_sel_hi:[1,0,1]
	v_pk_fma_f32 v[78:79], v[230:231], v[250:251], v[78:79] op_sel_hi:[1,0,1]
	v_cvt_pk_f32_fp8_e32 v[224:225], v140
	v_cvt_pk_f32_fp8_sdwa v[226:227], v140 src0_sel:WORD_1
	v_cvt_pk_f32_fp8_e32 v[228:229], v141
	v_cvt_pk_f32_fp8_sdwa v[230:231], v141 src0_sel:WORD_1
	v_pk_fma_f32 v[64:65], v[224:225], v[250:251], v[64:65] op_sel:[0,1,0] op_sel_hi:[1,1,1]
	v_pk_fma_f32 v[66:67], v[226:227], v[250:251], v[66:67] op_sel:[0,1,0] op_sel_hi:[1,1,1]
	v_pk_fma_f32 v[68:69], v[228:229], v[250:251], v[68:69] op_sel:[0,1,0] op_sel_hi:[1,1,1]
	v_pk_fma_f32 v[70:71], v[230:231], v[250:251], v[70:71] op_sel:[0,1,0] op_sel_hi:[1,1,1]
	v_cvt_pk_f32_fp8_e32 v[224:225], v142
	v_cvt_pk_f32_fp8_sdwa v[226:227], v142 src0_sel:WORD_1
	v_cvt_pk_f32_fp8_e32 v[228:229], v143
	v_cvt_pk_f32_fp8_sdwa v[230:231], v143 src0_sel:WORD_1
	v_pk_fma_f32 v[72:73], v[224:225], v[250:251], v[72:73] op_sel:[0,1,0] op_sel_hi:[1,1,1]
	v_pk_fma_f32 v[74:75], v[226:227], v[250:251], v[74:75] op_sel:[0,1,0] op_sel_hi:[1,1,1]
	v_pk_fma_f32 v[76:77], v[228:229], v[250:251], v[76:77] op_sel:[0,1,0] op_sel_hi:[1,1,1]
	v_pk_fma_f32 v[78:79], v[230:231], v[250:251], v[78:79] op_sel:[0,1,0] op_sel_hi:[1,1,1]
	s_sub_i32 s90, s90, 1
	s_cmp_eq_u32 s90, 0
	s_cbranch_scc1 .LV_sw1
.LV_t4_s1:
	s_waitcnt lgkmcnt(0)
	v_add_u32_e32 v236, v232, v240
	v_add_u32_e32 v237, v233, v240
	v_add_u32_e32 v238, v234, v240
	v_add_u32_e32 v239, v235, v240
	global_load_dwordx4 v[128:131], v236, s[6:7]
	global_load_dwordx4 v[132:135], v237, s[6:7]
	global_load_dwordx4 v[136:139], v238, s[6:7]
	global_load_dwordx4 v[140:143], v239, s[6:7]
	ds_read_b128 v[232:235], v213 offset:80
	ds_read_b128 v[248:251], v213 offset:4896
	s_waitcnt vmcnt(12)
	v_cvt_pk_f32_fp8_e32 v[224:225], v144
	v_cvt_pk_f32_fp8_sdwa v[226:227], v144 src0_sel:WORD_1
	v_cvt_pk_f32_fp8_e32 v[228:229], v145
	v_cvt_pk_f32_fp8_sdwa v[230:231], v145 src0_sel:WORD_1
	v_pk_fma_f32 v[64:65], v[224:225], v[252:253], v[64:65] op_sel_hi:[1,0,1]
	v_pk_fma_f32 v[66:67], v[226:227], v[252:253], v[66:67] op_sel_hi:[1,0,1]
	v_pk_fma_f32 v[68:69], v[228:229], v[252:253], v[68:69] op_sel_hi:[1,0,1]
	v_pk_fma_f32 v[70:71], v[230:231], v[252:253], v[70:71] op_sel_hi:[1,0,1]
	v_cvt_pk_f32_fp8_e32 v[224:225], v146
	v_cvt_pk_f32_fp8_sdwa v[226:227], v146 src0_sel:WORD_1
	v_cvt_pk_f32_fp8_e32 v[228:229], v147
	v_cvt_pk_f32_fp8_sdwa v[230:231], v147 src0_sel:WORD_1
	v_pk_fma_f32 v[72:73], v[224:225], v[252:253], v[72:73] op_sel_hi:[1,0,1]
	v_pk_fma_f32 v[74:75], v[226:227], v[252:253], v[74:75] op_sel_hi:[1,0,1]
	v_pk_fma_f32 v[76:77], v[228:229], v[252:253], v[76:77] op_sel_hi:[1,0,1]
	v_pk_fma_f32 v[78:79], v[230:231], v[252:253], v[78:79] op_sel_hi:[1,0,1]
	v_cvt_pk_f32_fp8_e32 v[224:225], v148
	v_cvt_pk_f32_fp8_sdwa v[226:227], v148 src0_sel:WORD_1
	v_cvt_pk_f32_fp8_e32 v[228:229], v149
	v_cvt_pk_f32_fp8_sdwa v[230:231], v149 src0_sel:WORD_1
	v_pk_fma_f32 v[64:65], v[224:225], v[252:253], v[64:65] op_sel:[0,1,0] op_sel_hi:[1,1,1]
	v_pk_fma_f32 v[66:67], v[226:227], v[252:253], v[66:67] op_sel:[0,1,0] op_sel_hi:[1,1,1]
	v_pk_fma_f32 v[68:69], v[228:229], v[252:253], v[68:69] op_sel:[0,1,0] op_sel_hi:[1,1,1]
	v_pk_fma_f32 v[70:71], v[230:231], v[252:253], v[70:71] op_sel:[0,1,0] op_sel_hi:[1,1,1]
	v_cvt_pk_f32_fp8_e32 v[224:225], v150
	v_cvt_pk_f32_fp8_sdwa v[226:227], v150 src0_sel:WORD_1
	v_cvt_pk_f32_fp8_e32 v[228:229], v151
	v_cvt_pk_f32_fp8_sdwa v[230:231], v151 src0_sel:WORD_1
	v_pk_fma_f32 v[72:73], v[224:225], v[252:253], v[72:73] op_sel:[0,1,0] op_sel_hi:[1,1,1]
	v_pk_fma_f32 v[74:75], v[226:227], v[252:253], v[74:75] op_sel:[0,1,0] op_sel_hi:[1,1,1]
	v_pk_fma_f32 v[76:77], v[228:229], v[252:253], v[76:77] op_sel:[0,1,0] op_sel_hi:[1,1,1]
	v_pk_fma_f32 v[78:79], v[230:231], v[252:253], v[78:79] op_sel:[0,1,0] op_sel_hi:[1,1,1]
	v_cvt_pk_f32_fp8_e32 v[224:225], v152
	v_cvt_pk_f32_fp8_sdwa v[226:227], v152 src0_sel:WORD_1
	v_cvt_pk_f32_fp8_e32 v[228:229], v153
	v_cvt_pk_f32_fp8_sdwa v[230:231], v153 src0_sel:WORD_1
	v_pk_fma_f32 v[64:65], v[224:225], v[254:255], v[64:65] op_sel_hi:[1,0,1]
	v_pk_fma_f32 v[66:67], v[226:227], v[254:255], v[66:67] op_sel_hi:[1,0,1]
	v_pk_fma_f32 v[68:69], v[228:229], v[254:255], v[68:69] op_sel_hi:[1,0,1]
	v_pk_fma_f32 v[70:71], v[230:231], v[254:255], v[70:71] op_sel_hi:[1,0,1]
	v_cvt_pk_f32_fp8_e32 v[224:225], v154
	v_cvt_pk_f32_fp8_sdwa v[226:227], v154 src0_sel:WORD_1
	v_cvt_pk_f32_fp8_e32 v[228:229], v155
	v_cvt_pk_f32_fp8_sdwa v[230:231], v155 src0_sel:WORD_1
	v_pk_fma_f32 v[72:73], v[224:225], v[254:255], v[72:73] op_sel_hi:[1,0,1]
	v_pk_fma_f32 v[74:75], v[226:227], v[254:255], v[74:75] op_sel_hi:[1,0,1]
	v_pk_fma_f32 v[76:77], v[228:229], v[254:255], v[76:77] op_sel_hi:[1,0,1]
	v_pk_fma_f32 v[78:79], v[230:231], v[254:255], v[78:79] op_sel_hi:[1,0,1]
	v_cvt_pk_f32_fp8_e32 v[224:225], v156
	v_cvt_pk_f32_fp8_sdwa v[226:227], v156 src0_sel:WORD_1
	v_cvt_pk_f32_fp8_e32 v[228:229], v157
	v_cvt_pk_f32_fp8_sdwa v[230:231], v157 src0_sel:WORD_1
	v_pk_fma_f32 v[64:65], v[224:225], v[254:255], v[64:65] op_sel:[0,1,0] op_sel_hi:[1,1,1]
	v_pk_fma_f32 v[66:67], v[226:227], v[254:255], v[66:67] op_sel:[0,1,0] op_sel_hi:[1,1,1]
	v_pk_fma_f32 v[68:69], v[228:229], v[254:255], v[68:69] op_sel:[0,1,0] op_sel_hi:[1,1,1]
	v_pk_fma_f32 v[70:71], v[230:231], v[254:255], v[70:71] op_sel:[0,1,0] op_sel_hi:[1,1,1]
	v_cvt_pk_f32_fp8_e32 v[224:225], v158
	v_cvt_pk_f32_fp8_sdwa v[226:227], v158 src0_sel:WORD_1
	v_cvt_pk_f32_fp8_e32 v[228:229], v159
	v_cvt_pk_f32_fp8_sdwa v[230:231], v159 src0_sel:WORD_1
	v_pk_fma_f32 v[72:73], v[224:225], v[254:255], v[72:73] op_sel:[0,1,0] op_sel_hi:[1,1,1]
	v_pk_fma_f32 v[74:75], v[226:227], v[254:255], v[74:75] op_sel:[0,1,0] op_sel_hi:[1,1,1]
	v_pk_fma_f32 v[76:77], v[228:229], v[254:255], v[76:77] op_sel:[0,1,0] op_sel_hi:[1,1,1]
	v_pk_fma_f32 v[78:79], v[230:231], v[254:255], v[78:79] op_sel:[0,1,0] op_sel_hi:[1,1,1]
	s_sub_i32 s90, s90, 1
	s_cmp_eq_u32 s90, 0
	s_cbranch_scc1 .LV_sw2
.LV_t4_s2:
	s_waitcnt lgkmcnt(0)
	v_add_u32_e32 v236, v232, v240
	v_add_u32_e32 v237, v233, v240
	v_add_u32_e32 v238, v234, v240
	v_add_u32_e32 v239, v235, v240
	global_load_dwordx4 v[144:147], v236, s[6:7]
	global_load_dwordx4 v[148:151], v237, s[6:7]
	global_load_dwordx4 v[152:155], v238, s[6:7]
	global_load_dwordx4 v[156:159], v239, s[6:7]
	ds_read_b128 v[232:235], v213 offset:96
	ds_read_b128 v[252:255], v213 offset:4912
	s_waitcnt vmcnt(12)
	v_cvt_pk_f32_fp8_e32 v[224:225], v160
	v_cvt_pk_f32_fp8_sdwa v[226:227], v160 src0_sel:WORD_1
	v_cvt_pk_f32_fp8_e32 v[228:229], v161
	v_cvt_pk_f32_fp8_sdwa v[230:231], v161 src0_sel:WORD_1
	v_pk_fma_f32 v[64:65], v[224:225], v[248:249], v[64:65] op_sel_hi:[1,0,1]
	v_pk_fma_f32 v[66:67], v[226:227], v[248:249], v[66:67] op_sel_hi:[1,0,1]
	v_pk_fma_f32 v[68:69], v[228:229], v[248:249], v[68:69] op_sel_hi:[1,0,1]
	v_pk_fma_f32 v[70:71], v[230:231], v[248:249], v[70:71] op_sel_hi:[1,0,1]
	v_cvt_pk_f32_fp8_e32 v[224:225], v162
	v_cvt_pk_f32_fp8_sdwa v[226:227], v162 src0_sel:WORD_1
	v_cvt_pk_f32_fp8_e32 v[228:229], v163
	v_cvt_pk_f32_fp8_sdwa v[230:231], v163 src0_sel:WORD_1
	v_pk_fma_f32 v[72:73], v[224:225], v[248:249], v[72:73] op_sel_hi:[1,0,1]
	v_pk_fma_f32 v[74:75], v[226:227], v[248:249], v[74:75] op_sel_hi:[1,0,1]
	v_pk_fma_f32 v[76:77], v[228:229], v[248:249], v[76:77] op_sel_hi:[1,0,1]
	v_pk_fma_f32 v[78:79], v[230:231], v[248:249], v[78:79] op_sel_hi:[1,0,1]
	v_cvt_pk_f32_fp8_e32 v[224:225], v164
	v_cvt_pk_f32_fp8_sdwa v[226:227], v164 src0_sel:WORD_1
	v_cvt_pk_f32_fp8_e32 v[228:229], v165
	v_cvt_pk_f32_fp8_sdwa v[230:231], v165 src0_sel:WORD_1
	v_pk_fma_f32 v[64:65], v[224:225], v[248:249], v[64:65] op_sel:[0,1,0] op_sel_hi:[1,1,1]
	v_pk_fma_f32 v[66:67], v[226:227], v[248:249], v[66:67] op_sel:[0,1,0] op_sel_hi:[1,1,1]
	v_pk_fma_f32 v[68:69], v[228:229], v[248:249], v[68:69] op_sel:[0,1,0] op_sel_hi:[1,1,1]
	v_pk_fma_f32 v[70:71], v[230:231], v[248:249], v[70:71] op_sel:[0,1,0] op_sel_hi:[1,1,1]
	v_cvt_pk_f32_fp8_e32 v[224:225], v166
	v_cvt_pk_f32_fp8_sdwa v[226:227], v166 src0_sel:WORD_1
	v_cvt_pk_f32_fp8_e32 v[228:229], v167
	v_cvt_pk_f32_fp8_sdwa v[230:231], v167 src0_sel:WORD_1
	v_pk_fma_f32 v[72:73], v[224:225], v[248:249], v[72:73] op_sel:[0,1,0] op_sel_hi:[1,1,1]
	v_pk_fma_f32 v[74:75], v[226:227], v[248:249], v[74:75] op_sel:[0,1,0] op_sel_hi:[1,1,1]
	v_pk_fma_f32 v[76:77], v[228:229], v[248:249], v[76:77] op_sel:[0,1,0] op_sel_hi:[1,1,1]
	v_pk_fma_f32 v[78:79], v[230:231], v[248:249], v[78:79] op_sel:[0,1,0] op_sel_hi:[1,1,1]
	v_cvt_pk_f32_fp8_e32 v[224:225], v168
	v_cvt_pk_f32_fp8_sdwa v[226:227], v168 src0_sel:WORD_1
	v_cvt_pk_f32_fp8_e32 v[228:229], v169
	v_cvt_pk_f32_fp8_sdwa v[230:231], v169 src0_sel:WORD_1
	v_pk_fma_f32 v[64:65], v[224:225], v[250:251], v[64:65] op_sel_hi:[1,0,1]
	v_pk_fma_f32 v[66:67], v[226:227], v[250:251], v[66:67] op_sel_hi:[1,0,1]
	v_pk_fma_f32 v[68:69], v[228:229], v[250:251], v[68:69] op_sel_hi:[1,0,1]
	v_pk_fma_f32 v[70:71], v[230:231], v[250:251], v[70:71] op_sel_hi:[1,0,1]
	v_cvt_pk_f32_fp8_e32 v[224:225], v170
	v_cvt_pk_f32_fp8_sdwa v[226:227], v170 src0_sel:WORD_1
	v_cvt_pk_f32_fp8_e32 v[228:229], v171
	v_cvt_pk_f32_fp8_sdwa v[230:231], v171 src0_sel:WORD_1
	v_pk_fma_f32 v[72:73], v[224:225], v[250:251], v[72:73] op_sel_hi:[1,0,1]
	v_pk_fma_f32 v[74:75], v[226:227], v[250:251], v[74:75] op_sel_hi:[1,0,1]
	v_pk_fma_f32 v[76:77], v[228:229], v[250:251], v[76:77] op_sel_hi:[1,0,1]
	v_pk_fma_f32 v[78:79], v[230:231], v[250:251], v[78:79] op_sel_hi:[1,0,1]
	v_cvt_pk_f32_fp8_e32 v[224:225], v172
	v_cvt_pk_f32_fp8_sdwa v[226:227], v172 src0_sel:WORD_1
	v_cvt_pk_f32_fp8_e32 v[228:229], v173
	v_cvt_pk_f32_fp8_sdwa v[230:231], v173 src0_sel:WORD_1
	v_pk_fma_f32 v[64:65], v[224:225], v[250:251], v[64:65] op_sel:[0,1,0] op_sel_hi:[1,1,1]
	v_pk_fma_f32 v[66:67], v[226:227], v[250:251], v[66:67] op_sel:[0,1,0] op_sel_hi:[1,1,1]
	v_pk_fma_f32 v[68:69], v[228:229], v[250:251], v[68:69] op_sel:[0,1,0] op_sel_hi:[1,1,1]
	v_pk_fma_f32 v[70:71], v[230:231], v[250:251], v[70:71] op_sel:[0,1,0] op_sel_hi:[1,1,1]
	v_cvt_pk_f32_fp8_e32 v[224:225], v174
	v_cvt_pk_f32_fp8_sdwa v[226:227], v174 src0_sel:WORD_1
	v_cvt_pk_f32_fp8_e32 v[228:229], v175
	v_cvt_pk_f32_fp8_sdwa v[230:231], v175 src0_sel:WORD_1
	v_pk_fma_f32 v[72:73], v[224:225], v[250:251], v[72:73] op_sel:[0,1,0] op_sel_hi:[1,1,1]
	v_pk_fma_f32 v[74:75], v[226:227], v[250:251], v[74:75] op_sel:[0,1,0] op_sel_hi:[1,1,1]
	v_pk_fma_f32 v[76:77], v[228:229], v[250:251], v[76:77] op_sel:[0,1,0] op_sel_hi:[1,1,1]
	v_pk_fma_f32 v[78:79], v[230:231], v[250:251], v[78:79] op_sel:[0,1,0] op_sel_hi:[1,1,1]
	s_sub_i32 s90, s90, 1
	s_cmp_eq_u32 s90, 0
	s_cbranch_scc1 .LV_sw3
.LV_t4_s3:
	s_waitcnt lgkmcnt(0)
	v_add_u32_e32 v236, v232, v240
	v_add_u32_e32 v237, v233, v240
	v_add_u32_e32 v238, v234, v240
	v_add_u32_e32 v239, v235, v240
	global_load_dwordx4 v[160:163], v236, s[6:7]
	global_load_dwordx4 v[164:167], v237, s[6:7]
	global_load_dwordx4 v[168:171], v238, s[6:7]
	global_load_dwordx4 v[172:175], v239, s[6:7]
	ds_read_b128 v[232:235], v213 offset:112
	ds_read_b128 v[248:251], v213 offset:4928
	s_waitcnt vmcnt(12)
	v_cvt_pk_f32_fp8_e32 v[224:225], v176
	v_cvt_pk_f32_fp8_sdwa v[226:227], v176 src0_sel:WORD_1
	v_cvt_pk_f32_fp8_e32 v[228:229], v177
	v_cvt_pk_f32_fp8_sdwa v[230:231], v177 src0_sel:WORD_1
	v_pk_fma_f32 v[64:65], v[224:225], v[252:253], v[64:65] op_sel_hi:[1,0,1]
	v_pk_fma_f32 v[66:67], v[226:227], v[252:253], v[66:67] op_sel_hi:[1,0,1]
	v_pk_fma_f32 v[68:69], v[228:229], v[252:253], v[68:69] op_sel_hi:[1,0,1]
	v_pk_fma_f32 v[70:71], v[230:231], v[252:253], v[70:71] op_sel_hi:[1,0,1]
	v_cvt_pk_f32_fp8_e32 v[224:225], v178
	v_cvt_pk_f32_fp8_sdwa v[226:227], v178 src0_sel:WORD_1
	v_cvt_pk_f32_fp8_e32 v[228:229], v179
	v_cvt_pk_f32_fp8_sdwa v[230:231], v179 src0_sel:WORD_1
	v_pk_fma_f32 v[72:73], v[224:225], v[252:253], v[72:73] op_sel_hi:[1,0,1]
	v_pk_fma_f32 v[74:75], v[226:227], v[252:253], v[74:75] op_sel_hi:[1,0,1]
	v_pk_fma_f32 v[76:77], v[228:229], v[252:253], v[76:77] op_sel_hi:[1,0,1]
	v_pk_fma_f32 v[78:79], v[230:231], v[252:253], v[78:79] op_sel_hi:[1,0,1]
	v_cvt_pk_f32_fp8_e32 v[224:225], v180
	v_cvt_pk_f32_fp8_sdwa v[226:227], v180 src0_sel:WORD_1
	v_cvt_pk_f32_fp8_e32 v[228:229], v181
	v_cvt_pk_f32_fp8_sdwa v[230:231], v181 src0_sel:WORD_1
	v_pk_fma_f32 v[64:65], v[224:225], v[252:253], v[64:65] op_sel:[0,1,0] op_sel_hi:[1,1,1]
	v_pk_fma_f32 v[66:67], v[226:227], v[252:253], v[66:67] op_sel:[0,1,0] op_sel_hi:[1,1,1]
	v_pk_fma_f32 v[68:69], v[228:229], v[252:253], v[68:69] op_sel:[0,1,0] op_sel_hi:[1,1,1]
	v_pk_fma_f32 v[70:71], v[230:231], v[252:253], v[70:71] op_sel:[0,1,0] op_sel_hi:[1,1,1]
	v_cvt_pk_f32_fp8_e32 v[224:225], v182
	v_cvt_pk_f32_fp8_sdwa v[226:227], v182 src0_sel:WORD_1
	v_cvt_pk_f32_fp8_e32 v[228:229], v183
	v_cvt_pk_f32_fp8_sdwa v[230:231], v183 src0_sel:WORD_1
	v_pk_fma_f32 v[72:73], v[224:225], v[252:253], v[72:73] op_sel:[0,1,0] op_sel_hi:[1,1,1]
	v_pk_fma_f32 v[74:75], v[226:227], v[252:253], v[74:75] op_sel:[0,1,0] op_sel_hi:[1,1,1]
	v_pk_fma_f32 v[76:77], v[228:229], v[252:253], v[76:77] op_sel:[0,1,0] op_sel_hi:[1,1,1]
	v_pk_fma_f32 v[78:79], v[230:231], v[252:253], v[78:79] op_sel:[0,1,0] op_sel_hi:[1,1,1]
	v_cvt_pk_f32_fp8_e32 v[224:225], v184
	v_cvt_pk_f32_fp8_sdwa v[226:227], v184 src0_sel:WORD_1
	v_cvt_pk_f32_fp8_e32 v[228:229], v185
	v_cvt_pk_f32_fp8_sdwa v[230:231], v185 src0_sel:WORD_1
	v_pk_fma_f32 v[64:65], v[224:225], v[254:255], v[64:65] op_sel_hi:[1,0,1]
	v_pk_fma_f32 v[66:67], v[226:227], v[254:255], v[66:67] op_sel_hi:[1,0,1]
	v_pk_fma_f32 v[68:69], v[228:229], v[254:255], v[68:69] op_sel_hi:[1,0,1]
	v_pk_fma_f32 v[70:71], v[230:231], v[254:255], v[70:71] op_sel_hi:[1,0,1]
	v_cvt_pk_f32_fp8_e32 v[224:225], v186
	v_cvt_pk_f32_fp8_sdwa v[226:227], v186 src0_sel:WORD_1
	v_cvt_pk_f32_fp8_e32 v[228:229], v187
	v_cvt_pk_f32_fp8_sdwa v[230:231], v187 src0_sel:WORD_1
	v_pk_fma_f32 v[72:73], v[224:225], v[254:255], v[72:73] op_sel_hi:[1,0,1]
	v_pk_fma_f32 v[74:75], v[226:227], v[254:255], v[74:75] op_sel_hi:[1,0,1]
	v_pk_fma_f32 v[76:77], v[228:229], v[254:255], v[76:77] op_sel_hi:[1,0,1]
	v_pk_fma_f32 v[78:79], v[230:231], v[254:255], v[78:79] op_sel_hi:[1,0,1]
	v_cvt_pk_f32_fp8_e32 v[224:225], v188
	v_cvt_pk_f32_fp8_sdwa v[226:227], v188 src0_sel:WORD_1
	v_cvt_pk_f32_fp8_e32 v[228:229], v189
	v_cvt_pk_f32_fp8_sdwa v[230:231], v189 src0_sel:WORD_1
	v_pk_fma_f32 v[64:65], v[224:225], v[254:255], v[64:65] op_sel:[0,1,0] op_sel_hi:[1,1,1]
	v_pk_fma_f32 v[66:67], v[226:227], v[254:255], v[66:67] op_sel:[0,1,0] op_sel_hi:[1,1,1]
	v_pk_fma_f32 v[68:69], v[228:229], v[254:255], v[68:69] op_sel:[0,1,0] op_sel_hi:[1,1,1]
	v_pk_fma_f32 v[70:71], v[230:231], v[254:255], v[70:71] op_sel:[0,1,0] op_sel_hi:[1,1,1]
	v_cvt_pk_f32_fp8_e32 v[224:225], v190
	v_cvt_pk_f32_fp8_sdwa v[226:227], v190 src0_sel:WORD_1
	v_cvt_pk_f32_fp8_e32 v[228:229], v191
	v_cvt_pk_f32_fp8_sdwa v[230:231], v191 src0_sel:WORD_1
	v_pk_fma_f32 v[72:73], v[224:225], v[254:255], v[72:73] op_sel:[0,1,0] op_sel_hi:[1,1,1]
	v_pk_fma_f32 v[74:75], v[226:227], v[254:255], v[74:75] op_sel:[0,1,0] op_sel_hi:[1,1,1]
	v_pk_fma_f32 v[76:77], v[228:229], v[254:255], v[76:77] op_sel:[0,1,0] op_sel_hi:[1,1,1]
	v_pk_fma_f32 v[78:79], v[230:231], v[254:255], v[78:79] op_sel:[0,1,0] op_sel_hi:[1,1,1]
	v_add_u32_e32 v213, 64, v213
	s_add_i32 s21, s21, 4
	s_sub_i32 s90, s90, 1
	s_cmp_eq_u32 s90, 0
	s_cbranch_scc1 .LV_sw0
	s_branch .LV_t4_s0
.LV_t5_s0:
	s_cmp_ge_u32 s21, s20
	s_cbranch_scc1 .LV_done
	s_waitcnt lgkmcnt(0)
	v_add_u32_e32 v236, v232, v240
	v_add_u32_e32 v237, v233, v240
	v_add_u32_e32 v238, v234, v240
	v_add_u32_e32 v239, v235, v240
	global_load_dwordx4 v[176:179], v236, s[6:7]
	global_load_dwordx4 v[180:183], v237, s[6:7]
	global_load_dwordx4 v[184:187], v238, s[6:7]
	global_load_dwordx4 v[188:191], v239, s[6:7]
	ds_read_b128 v[232:235], v213 offset:64
	ds_read_b128 v[252:255], v213 offset:4880
	s_waitcnt vmcnt(12)
	v_cvt_pk_f32_fp8_e32 v[224:225], v128
	v_cvt_pk_f32_fp8_sdwa v[226:227], v128 src0_sel:WORD_1
	v_cvt_pk_f32_fp8_e32 v[228:229], v129
	v_cvt_pk_f32_fp8_sdwa v[230:231], v129 src0_sel:WORD_1
	v_pk_fma_f32 v[80:81], v[224:225], v[248:249], v[80:81] op_sel_hi:[1,0,1]
	v_pk_fma_f32 v[82:83], v[226:227], v[248:249], v[82:83] op_sel_hi:[1,0,1]
	v_pk_fma_f32 v[84:85], v[228:229], v[248:249], v[84:85] op_sel_hi:[1,0,1]
	v_pk_fma_f32 v[86:87], v[230:231], v[248:249], v[86:87] op_sel_hi:[1,0,1]
	v_cvt_pk_f32_fp8_e32 v[224:225], v130
	v_cvt_pk_f32_fp8_sdwa v[226:227], v130 src0_sel:WORD_1
	v_cvt_pk_f32_fp8_e32 v[228:229], v131
	v_cvt_pk_f32_fp8_sdwa v[230:231], v131 src0_sel:WORD_1
	v_pk_fma_f32 v[88:89], v[224:225], v[248:249], v[88:89] op_sel_hi:[1,0,1]
	v_pk_fma_f32 v[90:91], v[226:227], v[248:249], v[90:91] op_sel_hi:[1,0,1]
	v_pk_fma_f32 v[92:93], v[228:229], v[248:249], v[92:93] op_sel_hi:[1,0,1]
	v_pk_fma_f32 v[94:95], v[230:231], v[248:249], v[94:95] op_sel_hi:[1,0,1]
	v_cvt_pk_f32_fp8_e32 v[224:225], v132
	v_cvt_pk_f32_fp8_sdwa v[226:227], v132 src0_sel:WORD_1
	v_cvt_pk_f32_fp8_e32 v[228:229], v133
	v_cvt_pk_f32_fp8_sdwa v[230:231], v133 src0_sel:WORD_1
	v_pk_fma_f32 v[80:81], v[224:225], v[248:249], v[80:81] op_sel:[0,1,0] op_sel_hi:[1,1,1]
	v_pk_fma_f32 v[82:83], v[226:227], v[248:249], v[82:83] op_sel:[0,1,0] op_sel_hi:[1,1,1]
	v_pk_fma_f32 v[84:85], v[228:229], v[248:249], v[84:85] op_sel:[0,1,0] op_sel_hi:[1,1,1]
	v_pk_fma_f32 v[86:87], v[230:231], v[248:249], v[86:87] op_sel:[0,1,0] op_sel_hi:[1,1,1]
	v_cvt_pk_f32_fp8_e32 v[224:225], v134
	v_cvt_pk_f32_fp8_sdwa v[226:227], v134 src0_sel:WORD_1
	v_cvt_pk_f32_fp8_e32 v[228:229], v135
	v_cvt_pk_f32_fp8_sdwa v[230:231], v135 src0_sel:WORD_1
	v_pk_fma_f32 v[88:89], v[224:225], v[248:249], v[88:89] op_sel:[0,1,0] op_sel_hi:[1,1,1]
	v_pk_fma_f32 v[90:91], v[226:227], v[248:249], v[90:91] op_sel:[0,1,0] op_sel_hi:[1,1,1]
	v_pk_fma_f32 v[92:93], v[228:229], v[248:249], v[92:93] op_sel:[0,1,0] op_sel_hi:[1,1,1]
	v_pk_fma_f32 v[94:95], v[230:231], v[248:249], v[94:95] op_sel:[0,1,0] op_sel_hi:[1,1,1]
	v_cvt_pk_f32_fp8_e32 v[224:225], v136
	v_cvt_pk_f32_fp8_sdwa v[226:227], v136 src0_sel:WORD_1
	v_cvt_pk_f32_fp8_e32 v[228:229], v137
	v_cvt_pk_f32_fp8_sdwa v[230:231], v137 src0_sel:WORD_1
	v_pk_fma_f32 v[80:81], v[224:225], v[250:251], v[80:81] op_sel_hi:[1,0,1]
	v_pk_fma_f32 v[82:83], v[226:227], v[250:251], v[82:83] op_sel_hi:[1,0,1]
	v_pk_fma_f32 v[84:85], v[228:229], v[250:251], v[84:85] op_sel_hi:[1,0,1]
	v_pk_fma_f32 v[86:87], v[230:231], v[250:251], v[86:87] op_sel_hi:[1,0,1]
	v_cvt_pk_f32_fp8_e32 v[224:225], v138
	v_cvt_pk_f32_fp8_sdwa v[226:227], v138 src0_sel:WORD_1
	v_cvt_pk_f32_fp8_e32 v[228:229], v139
	v_cvt_pk_f32_fp8_sdwa v[230:231], v139 src0_sel:WORD_1
	v_pk_fma_f32 v[88:89], v[224:225], v[250:251], v[88:89] op_sel_hi:[1,0,1]
	v_pk_fma_f32 v[90:91], v[226:227], v[250:251], v[90:91] op_sel_hi:[1,0,1]
	v_pk_fma_f32 v[92:93], v[228:229], v[250:251], v[92:93] op_sel_hi:[1,0,1]
	v_pk_fma_f32 v[94:95], v[230:231], v[250:251], v[94:95] op_sel_hi:[1,0,1]
	v_cvt_pk_f32_fp8_e32 v[224:225], v140
	v_cvt_pk_f32_fp8_sdwa v[226:227], v140 src0_sel:WORD_1
	v_cvt_pk_f32_fp8_e32 v[228:229], v141
	v_cvt_pk_f32_fp8_sdwa v[230:231], v141 src0_sel:WORD_1
	v_pk_fma_f32 v[80:81], v[224:225], v[250:251], v[80:81] op_sel:[0,1,0] op_sel_hi:[1,1,1]
	v_pk_fma_f32 v[82:83], v[226:227], v[250:251], v[82:83] op_sel:[0,1,0] op_sel_hi:[1,1,1]
	v_pk_fma_f32 v[84:85], v[228:229], v[250:251], v[84:85] op_sel:[0,1,0] op_sel_hi:[1,1,1]
	v_pk_fma_f32 v[86:87], v[230:231], v[250:251], v[86:87] op_sel:[0,1,0] op_sel_hi:[1,1,1]
	v_cvt_pk_f32_fp8_e32 v[224:225], v142
	v_cvt_pk_f32_fp8_sdwa v[226:227], v142 src0_sel:WORD_1
	v_cvt_pk_f32_fp8_e32 v[228:229], v143
	v_cvt_pk_f32_fp8_sdwa v[230:231], v143 src0_sel:WORD_1
	v_pk_fma_f32 v[88:89], v[224:225], v[250:251], v[88:89] op_sel:[0,1,0] op_sel_hi:[1,1,1]
	v_pk_fma_f32 v[90:91], v[226:227], v[250:251], v[90:91] op_sel:[0,1,0] op_sel_hi:[1,1,1]
	v_pk_fma_f32 v[92:93], v[228:229], v[250:251], v[92:93] op_sel:[0,1,0] op_sel_hi:[1,1,1]
	v_pk_fma_f32 v[94:95], v[230:231], v[250:251], v[94:95] op_sel:[0,1,0] op_sel_hi:[1,1,1]
	s_sub_i32 s90, s90, 1
	s_cmp_eq_u32 s90, 0
	s_cbranch_scc1 .LV_sw1
.LV_t5_s1:
	s_waitcnt lgkmcnt(0)
	v_add_u32_e32 v236, v232, v240
	v_add_u32_e32 v237, v233, v240
	v_add_u32_e32 v238, v234, v240
	v_add_u32_e32 v239, v235, v240
	global_load_dwordx4 v[128:131], v236, s[6:7]
	global_load_dwordx4 v[132:135], v237, s[6:7]
	global_load_dwordx4 v[136:139], v238, s[6:7]
	global_load_dwordx4 v[140:143], v239, s[6:7]
	ds_read_b128 v[232:235], v213 offset:80
	ds_read_b128 v[248:251], v213 offset:4896
	s_waitcnt vmcnt(12)
	v_cvt_pk_f32_fp8_e32 v[224:225], v144
	v_cvt_pk_f32_fp8_sdwa v[226:227], v144 src0_sel:WORD_1
	v_cvt_pk_f32_fp8_e32 v[228:229], v145
	v_cvt_pk_f32_fp8_sdwa v[230:231], v145 src0_sel:WORD_1
	v_pk_fma_f32 v[80:81], v[224:225], v[252:253], v[80:81] op_sel_hi:[1,0,1]
	v_pk_fma_f32 v[82:83], v[226:227], v[252:253], v[82:83] op_sel_hi:[1,0,1]
	v_pk_fma_f32 v[84:85], v[228:229], v[252:253], v[84:85] op_sel_hi:[1,0,1]
	v_pk_fma_f32 v[86:87], v[230:231], v[252:253], v[86:87] op_sel_hi:[1,0,1]
	v_cvt_pk_f32_fp8_e32 v[224:225], v146
	v_cvt_pk_f32_fp8_sdwa v[226:227], v146 src0_sel:WORD_1
	v_cvt_pk_f32_fp8_e32 v[228:229], v147
	v_cvt_pk_f32_fp8_sdwa v[230:231], v147 src0_sel:WORD_1
	v_pk_fma_f32 v[88:89], v[224:225], v[252:253], v[88:89] op_sel_hi:[1,0,1]
	v_pk_fma_f32 v[90:91], v[226:227], v[252:253], v[90:91] op_sel_hi:[1,0,1]
	v_pk_fma_f32 v[92:93], v[228:229], v[252:253], v[92:93] op_sel_hi:[1,0,1]
	v_pk_fma_f32 v[94:95], v[230:231], v[252:253], v[94:95] op_sel_hi:[1,0,1]
	v_cvt_pk_f32_fp8_e32 v[224:225], v148
	v_cvt_pk_f32_fp8_sdwa v[226:227], v148 src0_sel:WORD_1
	v_cvt_pk_f32_fp8_e32 v[228:229], v149
	v_cvt_pk_f32_fp8_sdwa v[230:231], v149 src0_sel:WORD_1
	v_pk_fma_f32 v[80:81], v[224:225], v[252:253], v[80:81] op_sel:[0,1,0] op_sel_hi:[1,1,1]
	v_pk_fma_f32 v[82:83], v[226:227], v[252:253], v[82:83] op_sel:[0,1,0] op_sel_hi:[1,1,1]
	v_pk_fma_f32 v[84:85], v[228:229], v[252:253], v[84:85] op_sel:[0,1,0] op_sel_hi:[1,1,1]
	v_pk_fma_f32 v[86:87], v[230:231], v[252:253], v[86:87] op_sel:[0,1,0] op_sel_hi:[1,1,1]
	v_cvt_pk_f32_fp8_e32 v[224:225], v150
	v_cvt_pk_f32_fp8_sdwa v[226:227], v150 src0_sel:WORD_1
	v_cvt_pk_f32_fp8_e32 v[228:229], v151
	v_cvt_pk_f32_fp8_sdwa v[230:231], v151 src0_sel:WORD_1
	v_pk_fma_f32 v[88:89], v[224:225], v[252:253], v[88:89] op_sel:[0,1,0] op_sel_hi:[1,1,1]
	v_pk_fma_f32 v[90:91], v[226:227], v[252:253], v[90:91] op_sel:[0,1,0] op_sel_hi:[1,1,1]
	v_pk_fma_f32 v[92:93], v[228:229], v[252:253], v[92:93] op_sel:[0,1,0] op_sel_hi:[1,1,1]
	v_pk_fma_f32 v[94:95], v[230:231], v[252:253], v[94:95] op_sel:[0,1,0] op_sel_hi:[1,1,1]
	v_cvt_pk_f32_fp8_e32 v[224:225], v152
	v_cvt_pk_f32_fp8_sdwa v[226:227], v152 src0_sel:WORD_1
	v_cvt_pk_f32_fp8_e32 v[228:229], v153
	v_cvt_pk_f32_fp8_sdwa v[230:231], v153 src0_sel:WORD_1
	v_pk_fma_f32 v[80:81], v[224:225], v[254:255], v[80:81] op_sel_hi:[1,0,1]
	v_pk_fma_f32 v[82:83], v[226:227], v[254:255], v[82:83] op_sel_hi:[1,0,1]
	v_pk_fma_f32 v[84:85], v[228:229], v[254:255], v[84:85] op_sel_hi:[1,0,1]
	v_pk_fma_f32 v[86:87], v[230:231], v[254:255], v[86:87] op_sel_hi:[1,0,1]
	v_cvt_pk_f32_fp8_e32 v[224:225], v154
	v_cvt_pk_f32_fp8_sdwa v[226:227], v154 src0_sel:WORD_1
	v_cvt_pk_f32_fp8_e32 v[228:229], v155
	v_cvt_pk_f32_fp8_sdwa v[230:231], v155 src0_sel:WORD_1
	v_pk_fma_f32 v[88:89], v[224:225], v[254:255], v[88:89] op_sel_hi:[1,0,1]
	v_pk_fma_f32 v[90:91], v[226:227], v[254:255], v[90:91] op_sel_hi:[1,0,1]
	v_pk_fma_f32 v[92:93], v[228:229], v[254:255], v[92:93] op_sel_hi:[1,0,1]
	v_pk_fma_f32 v[94:95], v[230:231], v[254:255], v[94:95] op_sel_hi:[1,0,1]
	v_cvt_pk_f32_fp8_e32 v[224:225], v156
	v_cvt_pk_f32_fp8_sdwa v[226:227], v156 src0_sel:WORD_1
	v_cvt_pk_f32_fp8_e32 v[228:229], v157
	v_cvt_pk_f32_fp8_sdwa v[230:231], v157 src0_sel:WORD_1
	v_pk_fma_f32 v[80:81], v[224:225], v[254:255], v[80:81] op_sel:[0,1,0] op_sel_hi:[1,1,1]
	v_pk_fma_f32 v[82:83], v[226:227], v[254:255], v[82:83] op_sel:[0,1,0] op_sel_hi:[1,1,1]
	v_pk_fma_f32 v[84:85], v[228:229], v[254:255], v[84:85] op_sel:[0,1,0] op_sel_hi:[1,1,1]
	v_pk_fma_f32 v[86:87], v[230:231], v[254:255], v[86:87] op_sel:[0,1,0] op_sel_hi:[1,1,1]
	v_cvt_pk_f32_fp8_e32 v[224:225], v158
	v_cvt_pk_f32_fp8_sdwa v[226:227], v158 src0_sel:WORD_1
	v_cvt_pk_f32_fp8_e32 v[228:229], v159
	v_cvt_pk_f32_fp8_sdwa v[230:231], v159 src0_sel:WORD_1
	v_pk_fma_f32 v[88:89], v[224:225], v[254:255], v[88:89] op_sel:[0,1,0] op_sel_hi:[1,1,1]
	v_pk_fma_f32 v[90:91], v[226:227], v[254:255], v[90:91] op_sel:[0,1,0] op_sel_hi:[1,1,1]
	v_pk_fma_f32 v[92:93], v[228:229], v[254:255], v[92:93] op_sel:[0,1,0] op_sel_hi:[1,1,1]
	v_pk_fma_f32 v[94:95], v[230:231], v[254:255], v[94:95] op_sel:[0,1,0] op_sel_hi:[1,1,1]
	s_sub_i32 s90, s90, 1
	s_cmp_eq_u32 s90, 0
	s_cbranch_scc1 .LV_sw2
.LV_t5_s2:
	s_waitcnt lgkmcnt(0)
	v_add_u32_e32 v236, v232, v240
	v_add_u32_e32 v237, v233, v240
	v_add_u32_e32 v238, v234, v240
	v_add_u32_e32 v239, v235, v240
	global_load_dwordx4 v[144:147], v236, s[6:7]
	global_load_dwordx4 v[148:151], v237, s[6:7]
	global_load_dwordx4 v[152:155], v238, s[6:7]
	global_load_dwordx4 v[156:159], v239, s[6:7]
	ds_read_b128 v[232:235], v213 offset:96
	ds_read_b128 v[252:255], v213 offset:4912
	s_waitcnt vmcnt(12)
	v_cvt_pk_f32_fp8_e32 v[224:225], v160
	v_cvt_pk_f32_fp8_sdwa v[226:227], v160 src0_sel:WORD_1
	v_cvt_pk_f32_fp8_e32 v[228:229], v161
	v_cvt_pk_f32_fp8_sdwa v[230:231], v161 src0_sel:WORD_1
	v_pk_fma_f32 v[80:81], v[224:225], v[248:249], v[80:81] op_sel_hi:[1,0,1]
	v_pk_fma_f32 v[82:83], v[226:227], v[248:249], v[82:83] op_sel_hi:[1,0,1]
	v_pk_fma_f32 v[84:85], v[228:229], v[248:249], v[84:85] op_sel_hi:[1,0,1]
	v_pk_fma_f32 v[86:87], v[230:231], v[248:249], v[86:87] op_sel_hi:[1,0,1]
	v_cvt_pk_f32_fp8_e32 v[224:225], v162
	v_cvt_pk_f32_fp8_sdwa v[226:227], v162 src0_sel:WORD_1
	v_cvt_pk_f32_fp8_e32 v[228:229], v163
	v_cvt_pk_f32_fp8_sdwa v[230:231], v163 src0_sel:WORD_1
	v_pk_fma_f32 v[88:89], v[224:225], v[248:249], v[88:89] op_sel_hi:[1,0,1]
	v_pk_fma_f32 v[90:91], v[226:227], v[248:249], v[90:91] op_sel_hi:[1,0,1]
	v_pk_fma_f32 v[92:93], v[228:229], v[248:249], v[92:93] op_sel_hi:[1,0,1]
	v_pk_fma_f32 v[94:95], v[230:231], v[248:249], v[94:95] op_sel_hi:[1,0,1]
	v_cvt_pk_f32_fp8_e32 v[224:225], v164
	v_cvt_pk_f32_fp8_sdwa v[226:227], v164 src0_sel:WORD_1
	v_cvt_pk_f32_fp8_e32 v[228:229], v165
	v_cvt_pk_f32_fp8_sdwa v[230:231], v165 src0_sel:WORD_1
	v_pk_fma_f32 v[80:81], v[224:225], v[248:249], v[80:81] op_sel:[0,1,0] op_sel_hi:[1,1,1]
	v_pk_fma_f32 v[82:83], v[226:227], v[248:249], v[82:83] op_sel:[0,1,0] op_sel_hi:[1,1,1]
	v_pk_fma_f32 v[84:85], v[228:229], v[248:249], v[84:85] op_sel:[0,1,0] op_sel_hi:[1,1,1]
	v_pk_fma_f32 v[86:87], v[230:231], v[248:249], v[86:87] op_sel:[0,1,0] op_sel_hi:[1,1,1]
	v_cvt_pk_f32_fp8_e32 v[224:225], v166
	v_cvt_pk_f32_fp8_sdwa v[226:227], v166 src0_sel:WORD_1
	v_cvt_pk_f32_fp8_e32 v[228:229], v167
	v_cvt_pk_f32_fp8_sdwa v[230:231], v167 src0_sel:WORD_1
	v_pk_fma_f32 v[88:89], v[224:225], v[248:249], v[88:89] op_sel:[0,1,0] op_sel_hi:[1,1,1]
	v_pk_fma_f32 v[90:91], v[226:227], v[248:249], v[90:91] op_sel:[0,1,0] op_sel_hi:[1,1,1]
	v_pk_fma_f32 v[92:93], v[228:229], v[248:249], v[92:93] op_sel:[0,1,0] op_sel_hi:[1,1,1]
	v_pk_fma_f32 v[94:95], v[230:231], v[248:249], v[94:95] op_sel:[0,1,0] op_sel_hi:[1,1,1]
	v_cvt_pk_f32_fp8_e32 v[224:225], v168
	v_cvt_pk_f32_fp8_sdwa v[226:227], v168 src0_sel:WORD_1
	v_cvt_pk_f32_fp8_e32 v[228:229], v169
	v_cvt_pk_f32_fp8_sdwa v[230:231], v169 src0_sel:WORD_1
	v_pk_fma_f32 v[80:81], v[224:225], v[250:251], v[80:81] op_sel_hi:[1,0,1]
	v_pk_fma_f32 v[82:83], v[226:227], v[250:251], v[82:83] op_sel_hi:[1,0,1]
	v_pk_fma_f32 v[84:85], v[228:229], v[250:251], v[84:85] op_sel_hi:[1,0,1]
	v_pk_fma_f32 v[86:87], v[230:231], v[250:251], v[86:87] op_sel_hi:[1,0,1]
	v_cvt_pk_f32_fp8_e32 v[224:225], v170
	v_cvt_pk_f32_fp8_sdwa v[226:227], v170 src0_sel:WORD_1
	v_cvt_pk_f32_fp8_e32 v[228:229], v171
	v_cvt_pk_f32_fp8_sdwa v[230:231], v171 src0_sel:WORD_1
	v_pk_fma_f32 v[88:89], v[224:225], v[250:251], v[88:89] op_sel_hi:[1,0,1]
	v_pk_fma_f32 v[90:91], v[226:227], v[250:251], v[90:91] op_sel_hi:[1,0,1]
	v_pk_fma_f32 v[92:93], v[228:229], v[250:251], v[92:93] op_sel_hi:[1,0,1]
	v_pk_fma_f32 v[94:95], v[230:231], v[250:251], v[94:95] op_sel_hi:[1,0,1]
	v_cvt_pk_f32_fp8_e32 v[224:225], v172
	v_cvt_pk_f32_fp8_sdwa v[226:227], v172 src0_sel:WORD_1
	v_cvt_pk_f32_fp8_e32 v[228:229], v173
	v_cvt_pk_f32_fp8_sdwa v[230:231], v173 src0_sel:WORD_1
	v_pk_fma_f32 v[80:81], v[224:225], v[250:251], v[80:81] op_sel:[0,1,0] op_sel_hi:[1,1,1]
	v_pk_fma_f32 v[82:83], v[226:227], v[250:251], v[82:83] op_sel:[0,1,0] op_sel_hi:[1,1,1]
	v_pk_fma_f32 v[84:85], v[228:229], v[250:251], v[84:85] op_sel:[0,1,0] op_sel_hi:[1,1,1]
	v_pk_fma_f32 v[86:87], v[230:231], v[250:251], v[86:87] op_sel:[0,1,0] op_sel_hi:[1,1,1]
	v_cvt_pk_f32_fp8_e32 v[224:225], v174
	v_cvt_pk_f32_fp8_sdwa v[226:227], v174 src0_sel:WORD_1
	v_cvt_pk_f32_fp8_e32 v[228:229], v175
	v_cvt_pk_f32_fp8_sdwa v[230:231], v175 src0_sel:WORD_1
	v_pk_fma_f32 v[88:89], v[224:225], v[250:251], v[88:89] op_sel:[0,1,0] op_sel_hi:[1,1,1]
	v_pk_fma_f32 v[90:91], v[226:227], v[250:251], v[90:91] op_sel:[0,1,0] op_sel_hi:[1,1,1]
	v_pk_fma_f32 v[92:93], v[228:229], v[250:251], v[92:93] op_sel:[0,1,0] op_sel_hi:[1,1,1]
	v_pk_fma_f32 v[94:95], v[230:231], v[250:251], v[94:95] op_sel:[0,1,0] op_sel_hi:[1,1,1]
	s_sub_i32 s90, s90, 1
	s_cmp_eq_u32 s90, 0
	s_cbranch_scc1 .LV_sw3
.LV_t5_s3:
	s_waitcnt lgkmcnt(0)
	v_add_u32_e32 v236, v232, v240
	v_add_u32_e32 v237, v233, v240
	v_add_u32_e32 v238, v234, v240
	v_add_u32_e32 v239, v235, v240
	global_load_dwordx4 v[160:163], v236, s[6:7]
	global_load_dwordx4 v[164:167], v237, s[6:7]
	global_load_dwordx4 v[168:171], v238, s[6:7]
	global_load_dwordx4 v[172:175], v239, s[6:7]
	ds_read_b128 v[232:235], v213 offset:112
	ds_read_b128 v[248:251], v213 offset:4928
	s_waitcnt vmcnt(12)
	v_cvt_pk_f32_fp8_e32 v[224:225], v176
	v_cvt_pk_f32_fp8_sdwa v[226:227], v176 src0_sel:WORD_1
	v_cvt_pk_f32_fp8_e32 v[228:229], v177
	v_cvt_pk_f32_fp8_sdwa v[230:231], v177 src0_sel:WORD_1
	v_pk_fma_f32 v[80:81], v[224:225], v[252:253], v[80:81] op_sel_hi:[1,0,1]
	v_pk_fma_f32 v[82:83], v[226:227], v[252:253], v[82:83] op_sel_hi:[1,0,1]
	v_pk_fma_f32 v[84:85], v[228:229], v[252:253], v[84:85] op_sel_hi:[1,0,1]
	v_pk_fma_f32 v[86:87], v[230:231], v[252:253], v[86:87] op_sel_hi:[1,0,1]
	v_cvt_pk_f32_fp8_e32 v[224:225], v178
	v_cvt_pk_f32_fp8_sdwa v[226:227], v178 src0_sel:WORD_1
	v_cvt_pk_f32_fp8_e32 v[228:229], v179
	v_cvt_pk_f32_fp8_sdwa v[230:231], v179 src0_sel:WORD_1
	v_pk_fma_f32 v[88:89], v[224:225], v[252:253], v[88:89] op_sel_hi:[1,0,1]
	v_pk_fma_f32 v[90:91], v[226:227], v[252:253], v[90:91] op_sel_hi:[1,0,1]
	v_pk_fma_f32 v[92:93], v[228:229], v[252:253], v[92:93] op_sel_hi:[1,0,1]
	v_pk_fma_f32 v[94:95], v[230:231], v[252:253], v[94:95] op_sel_hi:[1,0,1]
	v_cvt_pk_f32_fp8_e32 v[224:225], v180
	v_cvt_pk_f32_fp8_sdwa v[226:227], v180 src0_sel:WORD_1
	v_cvt_pk_f32_fp8_e32 v[228:229], v181
	v_cvt_pk_f32_fp8_sdwa v[230:231], v181 src0_sel:WORD_1
	v_pk_fma_f32 v[80:81], v[224:225], v[252:253], v[80:81] op_sel:[0,1,0] op_sel_hi:[1,1,1]
	v_pk_fma_f32 v[82:83], v[226:227], v[252:253], v[82:83] op_sel:[0,1,0] op_sel_hi:[1,1,1]
	v_pk_fma_f32 v[84:85], v[228:229], v[252:253], v[84:85] op_sel:[0,1,0] op_sel_hi:[1,1,1]
	v_pk_fma_f32 v[86:87], v[230:231], v[252:253], v[86:87] op_sel:[0,1,0] op_sel_hi:[1,1,1]
	v_cvt_pk_f32_fp8_e32 v[224:225], v182
	v_cvt_pk_f32_fp8_sdwa v[226:227], v182 src0_sel:WORD_1
	v_cvt_pk_f32_fp8_e32 v[228:229], v183
	v_cvt_pk_f32_fp8_sdwa v[230:231], v183 src0_sel:WORD_1
	v_pk_fma_f32 v[88:89], v[224:225], v[252:253], v[88:89] op_sel:[0,1,0] op_sel_hi:[1,1,1]
	v_pk_fma_f32 v[90:91], v[226:227], v[252:253], v[90:91] op_sel:[0,1,0] op_sel_hi:[1,1,1]
	v_pk_fma_f32 v[92:93], v[228:229], v[252:253], v[92:93] op_sel:[0,1,0] op_sel_hi:[1,1,1]
	v_pk_fma_f32 v[94:95], v[230:231], v[252:253], v[94:95] op_sel:[0,1,0] op_sel_hi:[1,1,1]
	v_cvt_pk_f32_fp8_e32 v[224:225], v184
	v_cvt_pk_f32_fp8_sdwa v[226:227], v184 src0_sel:WORD_1
	v_cvt_pk_f32_fp8_e32 v[228:229], v185
	v_cvt_pk_f32_fp8_sdwa v[230:231], v185 src0_sel:WORD_1
	v_pk_fma_f32 v[80:81], v[224:225], v[254:255], v[80:81] op_sel_hi:[1,0,1]
	v_pk_fma_f32 v[82:83], v[226:227], v[254:255], v[82:83] op_sel_hi:[1,0,1]
	v_pk_fma_f32 v[84:85], v[228:229], v[254:255], v[84:85] op_sel_hi:[1,0,1]
	v_pk_fma_f32 v[86:87], v[230:231], v[254:255], v[86:87] op_sel_hi:[1,0,1]
	v_cvt_pk_f32_fp8_e32 v[224:225], v186
	v_cvt_pk_f32_fp8_sdwa v[226:227], v186 src0_sel:WORD_1
	v_cvt_pk_f32_fp8_e32 v[228:229], v187
	v_cvt_pk_f32_fp8_sdwa v[230:231], v187 src0_sel:WORD_1
	v_pk_fma_f32 v[88:89], v[224:225], v[254:255], v[88:89] op_sel_hi:[1,0,1]
	v_pk_fma_f32 v[90:91], v[226:227], v[254:255], v[90:91] op_sel_hi:[1,0,1]
	v_pk_fma_f32 v[92:93], v[228:229], v[254:255], v[92:93] op_sel_hi:[1,0,1]
	v_pk_fma_f32 v[94:95], v[230:231], v[254:255], v[94:95] op_sel_hi:[1,0,1]
	v_cvt_pk_f32_fp8_e32 v[224:225], v188
	v_cvt_pk_f32_fp8_sdwa v[226:227], v188 src0_sel:WORD_1
	v_cvt_pk_f32_fp8_e32 v[228:229], v189
	v_cvt_pk_f32_fp8_sdwa v[230:231], v189 src0_sel:WORD_1
	v_pk_fma_f32 v[80:81], v[224:225], v[254:255], v[80:81] op_sel:[0,1,0] op_sel_hi:[1,1,1]
	v_pk_fma_f32 v[82:83], v[226:227], v[254:255], v[82:83] op_sel:[0,1,0] op_sel_hi:[1,1,1]
	v_pk_fma_f32 v[84:85], v[228:229], v[254:255], v[84:85] op_sel:[0,1,0] op_sel_hi:[1,1,1]
	v_pk_fma_f32 v[86:87], v[230:231], v[254:255], v[86:87] op_sel:[0,1,0] op_sel_hi:[1,1,1]
	v_cvt_pk_f32_fp8_e32 v[224:225], v190
	v_cvt_pk_f32_fp8_sdwa v[226:227], v190 src0_sel:WORD_1
	v_cvt_pk_f32_fp8_e32 v[228:229], v191
	v_cvt_pk_f32_fp8_sdwa v[230:231], v191 src0_sel:WORD_1
	v_pk_fma_f32 v[88:89], v[224:225], v[254:255], v[88:89] op_sel:[0,1,0] op_sel_hi:[1,1,1]
	v_pk_fma_f32 v[90:91], v[226:227], v[254:255], v[90:91] op_sel:[0,1,0] op_sel_hi:[1,1,1]
	v_pk_fma_f32 v[92:93], v[228:229], v[254:255], v[92:93] op_sel:[0,1,0] op_sel_hi:[1,1,1]
	v_pk_fma_f32 v[94:95], v[230:231], v[254:255], v[94:95] op_sel:[0,1,0] op_sel_hi:[1,1,1]
	v_add_u32_e32 v213, 64, v213
	s_add_i32 s21, s21, 4
	s_sub_i32 s90, s90, 1
	s_cmp_eq_u32 s90, 0
	s_cbranch_scc1 .LV_sw0
	s_branch .LV_t5_s0
.LV_t6_s0:
	s_cmp_ge_u32 s21, s20
	s_cbranch_scc1 .LV_done
	s_waitcnt lgkmcnt(0)
	v_add_u32_e32 v236, v232, v240
	v_add_u32_e32 v237, v233, v240
	v_add_u32_e32 v238, v234, v240
	v_add_u32_e32 v239, v235, v240
	global_load_dwordx4 v[176:179], v236, s[6:7]
	global_load_dwordx4 v[180:183], v237, s[6:7]
	global_load_dwordx4 v[184:187], v238, s[6:7]
	global_load_dwordx4 v[188:191], v239, s[6:7]
	ds_read_b128 v[232:235], v213 offset:64
	ds_read_b128 v[252:255], v213 offset:4880
	s_waitcnt vmcnt(12)
	v_cvt_pk_f32_fp8_e32 v[224:225], v128
	v_cvt_pk_f32_fp8_sdwa v[226:227], v128 src0_sel:WORD_1
	v_cvt_pk_f32_fp8_e32 v[228:229], v129
	v_cvt_pk_f32_fp8_sdwa v[230:231], v129 src0_sel:WORD_1
	v_pk_fma_f32 v[96:97], v[224:225], v[248:249], v[96:97] op_sel_hi:[1,0,1]
	v_pk_fma_f32 v[98:99], v[226:227], v[248:249], v[98:99] op_sel_hi:[1,0,1]
	v_pk_fma_f32 v[100:101], v[228:229], v[248:249], v[100:101] op_sel_hi:[1,0,1]
	v_pk_fma_f32 v[102:103], v[230:231], v[248:249], v[102:103] op_sel_hi:[1,0,1]
	v_cvt_pk_f32_fp8_e32 v[224:225], v130
	v_cvt_pk_f32_fp8_sdwa v[226:227], v130 src0_sel:WORD_1
	v_cvt_pk_f32_fp8_e32 v[228:229], v131
	v_cvt_pk_f32_fp8_sdwa v[230:231], v131 src0_sel:WORD_1
	v_pk_fma_f32 v[104:105], v[224:225], v[248:249], v[104:105] op_sel_hi:[1,0,1]
	v_pk_fma_f32 v[106:107], v[226:227], v[248:249], v[106:107] op_sel_hi:[1,0,1]
	v_pk_fma_f32 v[108:109], v[228:229], v[248:249], v[108:109] op_sel_hi:[1,0,1]
	v_pk_fma_f32 v[110:111], v[230:231], v[248:249], v[110:111] op_sel_hi:[1,0,1]
	v_cvt_pk_f32_fp8_e32 v[224:225], v132
	v_cvt_pk_f32_fp8_sdwa v[226:227], v132 src0_sel:WORD_1
	v_cvt_pk_f32_fp8_e32 v[228:229], v133
	v_cvt_pk_f32_fp8_sdwa v[230:231], v133 src0_sel:WORD_1
	v_pk_fma_f32 v[96:97], v[224:225], v[248:249], v[96:97] op_sel:[0,1,0] op_sel_hi:[1,1,1]
	v_pk_fma_f32 v[98:99], v[226:227], v[248:249], v[98:99] op_sel:[0,1,0] op_sel_hi:[1,1,1]
	v_pk_fma_f32 v[100:101], v[228:229], v[248:249], v[100:101] op_sel:[0,1,0] op_sel_hi:[1,1,1]
	v_pk_fma_f32 v[102:103], v[230:231], v[248:249], v[102:103] op_sel:[0,1,0] op_sel_hi:[1,1,1]
	v_cvt_pk_f32_fp8_e32 v[224:225], v134
	v_cvt_pk_f32_fp8_sdwa v[226:227], v134 src0_sel:WORD_1
	v_cvt_pk_f32_fp8_e32 v[228:229], v135
	v_cvt_pk_f32_fp8_sdwa v[230:231], v135 src0_sel:WORD_1
	v_pk_fma_f32 v[104:105], v[224:225], v[248:249], v[104:105] op_sel:[0,1,0] op_sel_hi:[1,1,1]
	v_pk_fma_f32 v[106:107], v[226:227], v[248:249], v[106:107] op_sel:[0,1,0] op_sel_hi:[1,1,1]
	v_pk_fma_f32 v[108:109], v[228:229], v[248:249], v[108:109] op_sel:[0,1,0] op_sel_hi:[1,1,1]
	v_pk_fma_f32 v[110:111], v[230:231], v[248:249], v[110:111] op_sel:[0,1,0] op_sel_hi:[1,1,1]
	v_cvt_pk_f32_fp8_e32 v[224:225], v136
	v_cvt_pk_f32_fp8_sdwa v[226:227], v136 src0_sel:WORD_1
	v_cvt_pk_f32_fp8_e32 v[228:229], v137
	v_cvt_pk_f32_fp8_sdwa v[230:231], v137 src0_sel:WORD_1
	v_pk_fma_f32 v[96:97], v[224:225], v[250:251], v[96:97] op_sel_hi:[1,0,1]
	v_pk_fma_f32 v[98:99], v[226:227], v[250:251], v[98:99] op_sel_hi:[1,0,1]
	v_pk_fma_f32 v[100:101], v[228:229], v[250:251], v[100:101] op_sel_hi:[1,0,1]
	v_pk_fma_f32 v[102:103], v[230:231], v[250:251], v[102:103] op_sel_hi:[1,0,1]
	v_cvt_pk_f32_fp8_e32 v[224:225], v138
	v_cvt_pk_f32_fp8_sdwa v[226:227], v138 src0_sel:WORD_1
	v_cvt_pk_f32_fp8_e32 v[228:229], v139
	v_cvt_pk_f32_fp8_sdwa v[230:231], v139 src0_sel:WORD_1
	v_pk_fma_f32 v[104:105], v[224:225], v[250:251], v[104:105] op_sel_hi:[1,0,1]
	v_pk_fma_f32 v[106:107], v[226:227], v[250:251], v[106:107] op_sel_hi:[1,0,1]
	v_pk_fma_f32 v[108:109], v[228:229], v[250:251], v[108:109] op_sel_hi:[1,0,1]
	v_pk_fma_f32 v[110:111], v[230:231], v[250:251], v[110:111] op_sel_hi:[1,0,1]
	v_cvt_pk_f32_fp8_e32 v[224:225], v140
	v_cvt_pk_f32_fp8_sdwa v[226:227], v140 src0_sel:WORD_1
	v_cvt_pk_f32_fp8_e32 v[228:229], v141
	v_cvt_pk_f32_fp8_sdwa v[230:231], v141 src0_sel:WORD_1
	v_pk_fma_f32 v[96:97], v[224:225], v[250:251], v[96:97] op_sel:[0,1,0] op_sel_hi:[1,1,1]
	v_pk_fma_f32 v[98:99], v[226:227], v[250:251], v[98:99] op_sel:[0,1,0] op_sel_hi:[1,1,1]
	v_pk_fma_f32 v[100:101], v[228:229], v[250:251], v[100:101] op_sel:[0,1,0] op_sel_hi:[1,1,1]
	v_pk_fma_f32 v[102:103], v[230:231], v[250:251], v[102:103] op_sel:[0,1,0] op_sel_hi:[1,1,1]
	v_cvt_pk_f32_fp8_e32 v[224:225], v142
	v_cvt_pk_f32_fp8_sdwa v[226:227], v142 src0_sel:WORD_1
	v_cvt_pk_f32_fp8_e32 v[228:229], v143
	v_cvt_pk_f32_fp8_sdwa v[230:231], v143 src0_sel:WORD_1
	v_pk_fma_f32 v[104:105], v[224:225], v[250:251], v[104:105] op_sel:[0,1,0] op_sel_hi:[1,1,1]
	v_pk_fma_f32 v[106:107], v[226:227], v[250:251], v[106:107] op_sel:[0,1,0] op_sel_hi:[1,1,1]
	v_pk_fma_f32 v[108:109], v[228:229], v[250:251], v[108:109] op_sel:[0,1,0] op_sel_hi:[1,1,1]
	v_pk_fma_f32 v[110:111], v[230:231], v[250:251], v[110:111] op_sel:[0,1,0] op_sel_hi:[1,1,1]
	s_sub_i32 s90, s90, 1
	s_cmp_eq_u32 s90, 0
	s_cbranch_scc1 .LV_sw1
.LV_t6_s1:
	s_waitcnt lgkmcnt(0)
	v_add_u32_e32 v236, v232, v240
	v_add_u32_e32 v237, v233, v240
	v_add_u32_e32 v238, v234, v240
	v_add_u32_e32 v239, v235, v240
	global_load_dwordx4 v[128:131], v236, s[6:7]
	global_load_dwordx4 v[132:135], v237, s[6:7]
	global_load_dwordx4 v[136:139], v238, s[6:7]
	global_load_dwordx4 v[140:143], v239, s[6:7]
	ds_read_b128 v[232:235], v213 offset:80
	ds_read_b128 v[248:251], v213 offset:4896
	s_waitcnt vmcnt(12)
	v_cvt_pk_f32_fp8_e32 v[224:225], v144
	v_cvt_pk_f32_fp8_sdwa v[226:227], v144 src0_sel:WORD_1
	v_cvt_pk_f32_fp8_e32 v[228:229], v145
	v_cvt_pk_f32_fp8_sdwa v[230:231], v145 src0_sel:WORD_1
	v_pk_fma_f32 v[96:97], v[224:225], v[252:253], v[96:97] op_sel_hi:[1,0,1]
	v_pk_fma_f32 v[98:99], v[226:227], v[252:253], v[98:99] op_sel_hi:[1,0,1]
	v_pk_fma_f32 v[100:101], v[228:229], v[252:253], v[100:101] op_sel_hi:[1,0,1]
	v_pk_fma_f32 v[102:103], v[230:231], v[252:253], v[102:103] op_sel_hi:[1,0,1]
	v_cvt_pk_f32_fp8_e32 v[224:225], v146
	v_cvt_pk_f32_fp8_sdwa v[226:227], v146 src0_sel:WORD_1
	v_cvt_pk_f32_fp8_e32 v[228:229], v147
	v_cvt_pk_f32_fp8_sdwa v[230:231], v147 src0_sel:WORD_1
	v_pk_fma_f32 v[104:105], v[224:225], v[252:253], v[104:105] op_sel_hi:[1,0,1]
	v_pk_fma_f32 v[106:107], v[226:227], v[252:253], v[106:107] op_sel_hi:[1,0,1]
	v_pk_fma_f32 v[108:109], v[228:229], v[252:253], v[108:109] op_sel_hi:[1,0,1]
	v_pk_fma_f32 v[110:111], v[230:231], v[252:253], v[110:111] op_sel_hi:[1,0,1]
	v_cvt_pk_f32_fp8_e32 v[224:225], v148
	v_cvt_pk_f32_fp8_sdwa v[226:227], v148 src0_sel:WORD_1
	v_cvt_pk_f32_fp8_e32 v[228:229], v149
	v_cvt_pk_f32_fp8_sdwa v[230:231], v149 src0_sel:WORD_1
	v_pk_fma_f32 v[96:97], v[224:225], v[252:253], v[96:97] op_sel:[0,1,0] op_sel_hi:[1,1,1]
	v_pk_fma_f32 v[98:99], v[226:227], v[252:253], v[98:99] op_sel:[0,1,0] op_sel_hi:[1,1,1]
	v_pk_fma_f32 v[100:101], v[228:229], v[252:253], v[100:101] op_sel:[0,1,0] op_sel_hi:[1,1,1]
	v_pk_fma_f32 v[102:103], v[230:231], v[252:253], v[102:103] op_sel:[0,1,0] op_sel_hi:[1,1,1]
	v_cvt_pk_f32_fp8_e32 v[224:225], v150
	v_cvt_pk_f32_fp8_sdwa v[226:227], v150 src0_sel:WORD_1
	v_cvt_pk_f32_fp8_e32 v[228:229], v151
	v_cvt_pk_f32_fp8_sdwa v[230:231], v151 src0_sel:WORD_1
	v_pk_fma_f32 v[104:105], v[224:225], v[252:253], v[104:105] op_sel:[0,1,0] op_sel_hi:[1,1,1]
	v_pk_fma_f32 v[106:107], v[226:227], v[252:253], v[106:107] op_sel:[0,1,0] op_sel_hi:[1,1,1]
	v_pk_fma_f32 v[108:109], v[228:229], v[252:253], v[108:109] op_sel:[0,1,0] op_sel_hi:[1,1,1]
	v_pk_fma_f32 v[110:111], v[230:231], v[252:253], v[110:111] op_sel:[0,1,0] op_sel_hi:[1,1,1]
	v_cvt_pk_f32_fp8_e32 v[224:225], v152
	v_cvt_pk_f32_fp8_sdwa v[226:227], v152 src0_sel:WORD_1
	v_cvt_pk_f32_fp8_e32 v[228:229], v153
	v_cvt_pk_f32_fp8_sdwa v[230:231], v153 src0_sel:WORD_1
	v_pk_fma_f32 v[96:97], v[224:225], v[254:255], v[96:97] op_sel_hi:[1,0,1]
	v_pk_fma_f32 v[98:99], v[226:227], v[254:255], v[98:99] op_sel_hi:[1,0,1]
	v_pk_fma_f32 v[100:101], v[228:229], v[254:255], v[100:101] op_sel_hi:[1,0,1]
	v_pk_fma_f32 v[102:103], v[230:231], v[254:255], v[102:103] op_sel_hi:[1,0,1]
	v_cvt_pk_f32_fp8_e32 v[224:225], v154
	v_cvt_pk_f32_fp8_sdwa v[226:227], v154 src0_sel:WORD_1
	v_cvt_pk_f32_fp8_e32 v[228:229], v155
	v_cvt_pk_f32_fp8_sdwa v[230:231], v155 src0_sel:WORD_1
	v_pk_fma_f32 v[104:105], v[224:225], v[254:255], v[104:105] op_sel_hi:[1,0,1]
	v_pk_fma_f32 v[106:107], v[226:227], v[254:255], v[106:107] op_sel_hi:[1,0,1]
	v_pk_fma_f32 v[108:109], v[228:229], v[254:255], v[108:109] op_sel_hi:[1,0,1]
	v_pk_fma_f32 v[110:111], v[230:231], v[254:255], v[110:111] op_sel_hi:[1,0,1]
	v_cvt_pk_f32_fp8_e32 v[224:225], v156
	v_cvt_pk_f32_fp8_sdwa v[226:227], v156 src0_sel:WORD_1
	v_cvt_pk_f32_fp8_e32 v[228:229], v157
	v_cvt_pk_f32_fp8_sdwa v[230:231], v157 src0_sel:WORD_1
	v_pk_fma_f32 v[96:97], v[224:225], v[254:255], v[96:97] op_sel:[0,1,0] op_sel_hi:[1,1,1]
	v_pk_fma_f32 v[98:99], v[226:227], v[254:255], v[98:99] op_sel:[0,1,0] op_sel_hi:[1,1,1]
	v_pk_fma_f32 v[100:101], v[228:229], v[254:255], v[100:101] op_sel:[0,1,0] op_sel_hi:[1,1,1]
	v_pk_fma_f32 v[102:103], v[230:231], v[254:255], v[102:103] op_sel:[0,1,0] op_sel_hi:[1,1,1]
	v_cvt_pk_f32_fp8_e32 v[224:225], v158
	v_cvt_pk_f32_fp8_sdwa v[226:227], v158 src0_sel:WORD_1
	v_cvt_pk_f32_fp8_e32 v[228:229], v159
	v_cvt_pk_f32_fp8_sdwa v[230:231], v159 src0_sel:WORD_1
	v_pk_fma_f32 v[104:105], v[224:225], v[254:255], v[104:105] op_sel:[0,1,0] op_sel_hi:[1,1,1]
	v_pk_fma_f32 v[106:107], v[226:227], v[254:255], v[106:107] op_sel:[0,1,0] op_sel_hi:[1,1,1]
	v_pk_fma_f32 v[108:109], v[228:229], v[254:255], v[108:109] op_sel:[0,1,0] op_sel_hi:[1,1,1]
	v_pk_fma_f32 v[110:111], v[230:231], v[254:255], v[110:111] op_sel:[0,1,0] op_sel_hi:[1,1,1]
	s_sub_i32 s90, s90, 1
	s_cmp_eq_u32 s90, 0
	s_cbranch_scc1 .LV_sw2
.LV_t6_s2:
	s_waitcnt lgkmcnt(0)
	v_add_u32_e32 v236, v232, v240
	v_add_u32_e32 v237, v233, v240
	v_add_u32_e32 v238, v234, v240
	v_add_u32_e32 v239, v235, v240
	global_load_dwordx4 v[144:147], v236, s[6:7]
	global_load_dwordx4 v[148:151], v237, s[6:7]
	global_load_dwordx4 v[152:155], v238, s[6:7]
	global_load_dwordx4 v[156:159], v239, s[6:7]
	ds_read_b128 v[232:235], v213 offset:96
	ds_read_b128 v[252:255], v213 offset:4912
	s_waitcnt vmcnt(12)
	v_cvt_pk_f32_fp8_e32 v[224:225], v160
	v_cvt_pk_f32_fp8_sdwa v[226:227], v160 src0_sel:WORD_1
	v_cvt_pk_f32_fp8_e32 v[228:229], v161
	v_cvt_pk_f32_fp8_sdwa v[230:231], v161 src0_sel:WORD_1
	v_pk_fma_f32 v[96:97], v[224:225], v[248:249], v[96:97] op_sel_hi:[1,0,1]
	v_pk_fma_f32 v[98:99], v[226:227], v[248:249], v[98:99] op_sel_hi:[1,0,1]
	v_pk_fma_f32 v[100:101], v[228:229], v[248:249], v[100:101] op_sel_hi:[1,0,1]
	v_pk_fma_f32 v[102:103], v[230:231], v[248:249], v[102:103] op_sel_hi:[1,0,1]
	v_cvt_pk_f32_fp8_e32 v[224:225], v162
	v_cvt_pk_f32_fp8_sdwa v[226:227], v162 src0_sel:WORD_1
	v_cvt_pk_f32_fp8_e32 v[228:229], v163
	v_cvt_pk_f32_fp8_sdwa v[230:231], v163 src0_sel:WORD_1
	v_pk_fma_f32 v[104:105], v[224:225], v[248:249], v[104:105] op_sel_hi:[1,0,1]
	v_pk_fma_f32 v[106:107], v[226:227], v[248:249], v[106:107] op_sel_hi:[1,0,1]
	v_pk_fma_f32 v[108:109], v[228:229], v[248:249], v[108:109] op_sel_hi:[1,0,1]
	v_pk_fma_f32 v[110:111], v[230:231], v[248:249], v[110:111] op_sel_hi:[1,0,1]
	v_cvt_pk_f32_fp8_e32 v[224:225], v164
	v_cvt_pk_f32_fp8_sdwa v[226:227], v164 src0_sel:WORD_1
	v_cvt_pk_f32_fp8_e32 v[228:229], v165
	v_cvt_pk_f32_fp8_sdwa v[230:231], v165 src0_sel:WORD_1
	v_pk_fma_f32 v[96:97], v[224:225], v[248:249], v[96:97] op_sel:[0,1,0] op_sel_hi:[1,1,1]
	v_pk_fma_f32 v[98:99], v[226:227], v[248:249], v[98:99] op_sel:[0,1,0] op_sel_hi:[1,1,1]
	v_pk_fma_f32 v[100:101], v[228:229], v[248:249], v[100:101] op_sel:[0,1,0] op_sel_hi:[1,1,1]
	v_pk_fma_f32 v[102:103], v[230:231], v[248:249], v[102:103] op_sel:[0,1,0] op_sel_hi:[1,1,1]
	v_cvt_pk_f32_fp8_e32 v[224:225], v166
	v_cvt_pk_f32_fp8_sdwa v[226:227], v166 src0_sel:WORD_1
	v_cvt_pk_f32_fp8_e32 v[228:229], v167
	v_cvt_pk_f32_fp8_sdwa v[230:231], v167 src0_sel:WORD_1
	v_pk_fma_f32 v[104:105], v[224:225], v[248:249], v[104:105] op_sel:[0,1,0] op_sel_hi:[1,1,1]
	v_pk_fma_f32 v[106:107], v[226:227], v[248:249], v[106:107] op_sel:[0,1,0] op_sel_hi:[1,1,1]
	v_pk_fma_f32 v[108:109], v[228:229], v[248:249], v[108:109] op_sel:[0,1,0] op_sel_hi:[1,1,1]
	v_pk_fma_f32 v[110:111], v[230:231], v[248:249], v[110:111] op_sel:[0,1,0] op_sel_hi:[1,1,1]
	v_cvt_pk_f32_fp8_e32 v[224:225], v168
	v_cvt_pk_f32_fp8_sdwa v[226:227], v168 src0_sel:WORD_1
	v_cvt_pk_f32_fp8_e32 v[228:229], v169
	v_cvt_pk_f32_fp8_sdwa v[230:231], v169 src0_sel:WORD_1
	v_pk_fma_f32 v[96:97], v[224:225], v[250:251], v[96:97] op_sel_hi:[1,0,1]
	v_pk_fma_f32 v[98:99], v[226:227], v[250:251], v[98:99] op_sel_hi:[1,0,1]
	v_pk_fma_f32 v[100:101], v[228:229], v[250:251], v[100:101] op_sel_hi:[1,0,1]
	v_pk_fma_f32 v[102:103], v[230:231], v[250:251], v[102:103] op_sel_hi:[1,0,1]
	v_cvt_pk_f32_fp8_e32 v[224:225], v170
	v_cvt_pk_f32_fp8_sdwa v[226:227], v170 src0_sel:WORD_1
	v_cvt_pk_f32_fp8_e32 v[228:229], v171
	v_cvt_pk_f32_fp8_sdwa v[230:231], v171 src0_sel:WORD_1
	v_pk_fma_f32 v[104:105], v[224:225], v[250:251], v[104:105] op_sel_hi:[1,0,1]
	v_pk_fma_f32 v[106:107], v[226:227], v[250:251], v[106:107] op_sel_hi:[1,0,1]
	v_pk_fma_f32 v[108:109], v[228:229], v[250:251], v[108:109] op_sel_hi:[1,0,1]
	v_pk_fma_f32 v[110:111], v[230:231], v[250:251], v[110:111] op_sel_hi:[1,0,1]
	v_cvt_pk_f32_fp8_e32 v[224:225], v172
	v_cvt_pk_f32_fp8_sdwa v[226:227], v172 src0_sel:WORD_1
	v_cvt_pk_f32_fp8_e32 v[228:229], v173
	v_cvt_pk_f32_fp8_sdwa v[230:231], v173 src0_sel:WORD_1
	v_pk_fma_f32 v[96:97], v[224:225], v[250:251], v[96:97] op_sel:[0,1,0] op_sel_hi:[1,1,1]
	v_pk_fma_f32 v[98:99], v[226:227], v[250:251], v[98:99] op_sel:[0,1,0] op_sel_hi:[1,1,1]
	v_pk_fma_f32 v[100:101], v[228:229], v[250:251], v[100:101] op_sel:[0,1,0] op_sel_hi:[1,1,1]
	v_pk_fma_f32 v[102:103], v[230:231], v[250:251], v[102:103] op_sel:[0,1,0] op_sel_hi:[1,1,1]
	v_cvt_pk_f32_fp8_e32 v[224:225], v174
	v_cvt_pk_f32_fp8_sdwa v[226:227], v174 src0_sel:WORD_1
	v_cvt_pk_f32_fp8_e32 v[228:229], v175
	v_cvt_pk_f32_fp8_sdwa v[230:231], v175 src0_sel:WORD_1
	v_pk_fma_f32 v[104:105], v[224:225], v[250:251], v[104:105] op_sel:[0,1,0] op_sel_hi:[1,1,1]
	v_pk_fma_f32 v[106:107], v[226:227], v[250:251], v[106:107] op_sel:[0,1,0] op_sel_hi:[1,1,1]
	v_pk_fma_f32 v[108:109], v[228:229], v[250:251], v[108:109] op_sel:[0,1,0] op_sel_hi:[1,1,1]
	v_pk_fma_f32 v[110:111], v[230:231], v[250:251], v[110:111] op_sel:[0,1,0] op_sel_hi:[1,1,1]
	s_sub_i32 s90, s90, 1
	s_cmp_eq_u32 s90, 0
	s_cbranch_scc1 .LV_sw3
.LV_t6_s3:
	s_waitcnt lgkmcnt(0)
	v_add_u32_e32 v236, v232, v240
	v_add_u32_e32 v237, v233, v240
	v_add_u32_e32 v238, v234, v240
	v_add_u32_e32 v239, v235, v240
	global_load_dwordx4 v[160:163], v236, s[6:7]
	global_load_dwordx4 v[164:167], v237, s[6:7]
	global_load_dwordx4 v[168:171], v238, s[6:7]
	global_load_dwordx4 v[172:175], v239, s[6:7]
	ds_read_b128 v[232:235], v213 offset:112
	ds_read_b128 v[248:251], v213 offset:4928
	s_waitcnt vmcnt(12)
	v_cvt_pk_f32_fp8_e32 v[224:225], v176
	v_cvt_pk_f32_fp8_sdwa v[226:227], v176 src0_sel:WORD_1
	v_cvt_pk_f32_fp8_e32 v[228:229], v177
	v_cvt_pk_f32_fp8_sdwa v[230:231], v177 src0_sel:WORD_1
	v_pk_fma_f32 v[96:97], v[224:225], v[252:253], v[96:97] op_sel_hi:[1,0,1]
	v_pk_fma_f32 v[98:99], v[226:227], v[252:253], v[98:99] op_sel_hi:[1,0,1]
	v_pk_fma_f32 v[100:101], v[228:229], v[252:253], v[100:101] op_sel_hi:[1,0,1]
	v_pk_fma_f32 v[102:103], v[230:231], v[252:253], v[102:103] op_sel_hi:[1,0,1]
	v_cvt_pk_f32_fp8_e32 v[224:225], v178
	v_cvt_pk_f32_fp8_sdwa v[226:227], v178 src0_sel:WORD_1
	v_cvt_pk_f32_fp8_e32 v[228:229], v179
	v_cvt_pk_f32_fp8_sdwa v[230:231], v179 src0_sel:WORD_1
	v_pk_fma_f32 v[104:105], v[224:225], v[252:253], v[104:105] op_sel_hi:[1,0,1]
	v_pk_fma_f32 v[106:107], v[226:227], v[252:253], v[106:107] op_sel_hi:[1,0,1]
	v_pk_fma_f32 v[108:109], v[228:229], v[252:253], v[108:109] op_sel_hi:[1,0,1]
	v_pk_fma_f32 v[110:111], v[230:231], v[252:253], v[110:111] op_sel_hi:[1,0,1]
	v_cvt_pk_f32_fp8_e32 v[224:225], v180
	v_cvt_pk_f32_fp8_sdwa v[226:227], v180 src0_sel:WORD_1
	v_cvt_pk_f32_fp8_e32 v[228:229], v181
	v_cvt_pk_f32_fp8_sdwa v[230:231], v181 src0_sel:WORD_1
	v_pk_fma_f32 v[96:97], v[224:225], v[252:253], v[96:97] op_sel:[0,1,0] op_sel_hi:[1,1,1]
	v_pk_fma_f32 v[98:99], v[226:227], v[252:253], v[98:99] op_sel:[0,1,0] op_sel_hi:[1,1,1]
	v_pk_fma_f32 v[100:101], v[228:229], v[252:253], v[100:101] op_sel:[0,1,0] op_sel_hi:[1,1,1]
	v_pk_fma_f32 v[102:103], v[230:231], v[252:253], v[102:103] op_sel:[0,1,0] op_sel_hi:[1,1,1]
	v_cvt_pk_f32_fp8_e32 v[224:225], v182
	v_cvt_pk_f32_fp8_sdwa v[226:227], v182 src0_sel:WORD_1
	v_cvt_pk_f32_fp8_e32 v[228:229], v183
	v_cvt_pk_f32_fp8_sdwa v[230:231], v183 src0_sel:WORD_1
	v_pk_fma_f32 v[104:105], v[224:225], v[252:253], v[104:105] op_sel:[0,1,0] op_sel_hi:[1,1,1]
	v_pk_fma_f32 v[106:107], v[226:227], v[252:253], v[106:107] op_sel:[0,1,0] op_sel_hi:[1,1,1]
	v_pk_fma_f32 v[108:109], v[228:229], v[252:253], v[108:109] op_sel:[0,1,0] op_sel_hi:[1,1,1]
	v_pk_fma_f32 v[110:111], v[230:231], v[252:253], v[110:111] op_sel:[0,1,0] op_sel_hi:[1,1,1]
	v_cvt_pk_f32_fp8_e32 v[224:225], v184
	v_cvt_pk_f32_fp8_sdwa v[226:227], v184 src0_sel:WORD_1
	v_cvt_pk_f32_fp8_e32 v[228:229], v185
	v_cvt_pk_f32_fp8_sdwa v[230:231], v185 src0_sel:WORD_1
	v_pk_fma_f32 v[96:97], v[224:225], v[254:255], v[96:97] op_sel_hi:[1,0,1]
	v_pk_fma_f32 v[98:99], v[226:227], v[254:255], v[98:99] op_sel_hi:[1,0,1]
	v_pk_fma_f32 v[100:101], v[228:229], v[254:255], v[100:101] op_sel_hi:[1,0,1]
	v_pk_fma_f32 v[102:103], v[230:231], v[254:255], v[102:103] op_sel_hi:[1,0,1]
	v_cvt_pk_f32_fp8_e32 v[224:225], v186
	v_cvt_pk_f32_fp8_sdwa v[226:227], v186 src0_sel:WORD_1
	v_cvt_pk_f32_fp8_e32 v[228:229], v187
	v_cvt_pk_f32_fp8_sdwa v[230:231], v187 src0_sel:WORD_1
	v_pk_fma_f32 v[104:105], v[224:225], v[254:255], v[104:105] op_sel_hi:[1,0,1]
	v_pk_fma_f32 v[106:107], v[226:227], v[254:255], v[106:107] op_sel_hi:[1,0,1]
	v_pk_fma_f32 v[108:109], v[228:229], v[254:255], v[108:109] op_sel_hi:[1,0,1]
	v_pk_fma_f32 v[110:111], v[230:231], v[254:255], v[110:111] op_sel_hi:[1,0,1]
	v_cvt_pk_f32_fp8_e32 v[224:225], v188
	v_cvt_pk_f32_fp8_sdwa v[226:227], v188 src0_sel:WORD_1
	v_cvt_pk_f32_fp8_e32 v[228:229], v189
	v_cvt_pk_f32_fp8_sdwa v[230:231], v189 src0_sel:WORD_1
	v_pk_fma_f32 v[96:97], v[224:225], v[254:255], v[96:97] op_sel:[0,1,0] op_sel_hi:[1,1,1]
	v_pk_fma_f32 v[98:99], v[226:227], v[254:255], v[98:99] op_sel:[0,1,0] op_sel_hi:[1,1,1]
	v_pk_fma_f32 v[100:101], v[228:229], v[254:255], v[100:101] op_sel:[0,1,0] op_sel_hi:[1,1,1]
	v_pk_fma_f32 v[102:103], v[230:231], v[254:255], v[102:103] op_sel:[0,1,0] op_sel_hi:[1,1,1]
	v_cvt_pk_f32_fp8_e32 v[224:225], v190
	v_cvt_pk_f32_fp8_sdwa v[226:227], v190 src0_sel:WORD_1
	v_cvt_pk_f32_fp8_e32 v[228:229], v191
	v_cvt_pk_f32_fp8_sdwa v[230:231], v191 src0_sel:WORD_1
	v_pk_fma_f32 v[104:105], v[224:225], v[254:255], v[104:105] op_sel:[0,1,0] op_sel_hi:[1,1,1]
	v_pk_fma_f32 v[106:107], v[226:227], v[254:255], v[106:107] op_sel:[0,1,0] op_sel_hi:[1,1,1]
	v_pk_fma_f32 v[108:109], v[228:229], v[254:255], v[108:109] op_sel:[0,1,0] op_sel_hi:[1,1,1]
	v_pk_fma_f32 v[110:111], v[230:231], v[254:255], v[110:111] op_sel:[0,1,0] op_sel_hi:[1,1,1]
	v_add_u32_e32 v213, 64, v213
	s_add_i32 s21, s21, 4
	s_sub_i32 s90, s90, 1
	s_cmp_eq_u32 s90, 0
	s_cbranch_scc1 .LV_sw0
	s_branch .LV_t6_s0
.LV_t7_s0:
	s_cmp_ge_u32 s21, s20
	s_cbranch_scc1 .LV_done
	s_waitcnt lgkmcnt(0)
	v_add_u32_e32 v236, v232, v240
	v_add_u32_e32 v237, v233, v240
	v_add_u32_e32 v238, v234, v240
	v_add_u32_e32 v239, v235, v240
	global_load_dwordx4 v[176:179], v236, s[6:7]
	global_load_dwordx4 v[180:183], v237, s[6:7]
	global_load_dwordx4 v[184:187], v238, s[6:7]
	global_load_dwordx4 v[188:191], v239, s[6:7]
	ds_read_b128 v[232:235], v213 offset:64
	ds_read_b128 v[252:255], v213 offset:4880
	s_waitcnt vmcnt(12)
	v_cvt_pk_f32_fp8_e32 v[224:225], v128
	v_cvt_pk_f32_fp8_sdwa v[226:227], v128 src0_sel:WORD_1
	v_cvt_pk_f32_fp8_e32 v[228:229], v129
	v_cvt_pk_f32_fp8_sdwa v[230:231], v129 src0_sel:WORD_1
	v_pk_fma_f32 v[112:113], v[224:225], v[248:249], v[112:113] op_sel_hi:[1,0,1]
	v_pk_fma_f32 v[114:115], v[226:227], v[248:249], v[114:115] op_sel_hi:[1,0,1]
	v_pk_fma_f32 v[116:117], v[228:229], v[248:249], v[116:117] op_sel_hi:[1,0,1]
	v_pk_fma_f32 v[118:119], v[230:231], v[248:249], v[118:119] op_sel_hi:[1,0,1]
	v_cvt_pk_f32_fp8_e32 v[224:225], v130
	v_cvt_pk_f32_fp8_sdwa v[226:227], v130 src0_sel:WORD_1
	v_cvt_pk_f32_fp8_e32 v[228:229], v131
	v_cvt_pk_f32_fp8_sdwa v[230:231], v131 src0_sel:WORD_1
	v_pk_fma_f32 v[120:121], v[224:225], v[248:249], v[120:121] op_sel_hi:[1,0,1]
	v_pk_fma_f32 v[122:123], v[226:227], v[248:249], v[122:123] op_sel_hi:[1,0,1]
	v_pk_fma_f32 v[124:125], v[228:229], v[248:249], v[124:125] op_sel_hi:[1,0,1]
	v_pk_fma_f32 v[126:127], v[230:231], v[248:249], v[126:127] op_sel_hi:[1,0,1]
	v_cvt_pk_f32_fp8_e32 v[224:225], v132
	v_cvt_pk_f32_fp8_sdwa v[226:227], v132 src0_sel:WORD_1
	v_cvt_pk_f32_fp8_e32 v[228:229], v133
	v_cvt_pk_f32_fp8_sdwa v[230:231], v133 src0_sel:WORD_1
	v_pk_fma_f32 v[112:113], v[224:225], v[248:249], v[112:113] op_sel:[0,1,0] op_sel_hi:[1,1,1]
	v_pk_fma_f32 v[114:115], v[226:227], v[248:249], v[114:115] op_sel:[0,1,0] op_sel_hi:[1,1,1]
	v_pk_fma_f32 v[116:117], v[228:229], v[248:249], v[116:117] op_sel:[0,1,0] op_sel_hi:[1,1,1]
	v_pk_fma_f32 v[118:119], v[230:231], v[248:249], v[118:119] op_sel:[0,1,0] op_sel_hi:[1,1,1]
	v_cvt_pk_f32_fp8_e32 v[224:225], v134
	v_cvt_pk_f32_fp8_sdwa v[226:227], v134 src0_sel:WORD_1
	v_cvt_pk_f32_fp8_e32 v[228:229], v135
	v_cvt_pk_f32_fp8_sdwa v[230:231], v135 src0_sel:WORD_1
	v_pk_fma_f32 v[120:121], v[224:225], v[248:249], v[120:121] op_sel:[0,1,0] op_sel_hi:[1,1,1]
	v_pk_fma_f32 v[122:123], v[226:227], v[248:249], v[122:123] op_sel:[0,1,0] op_sel_hi:[1,1,1]
	v_pk_fma_f32 v[124:125], v[228:229], v[248:249], v[124:125] op_sel:[0,1,0] op_sel_hi:[1,1,1]
	v_pk_fma_f32 v[126:127], v[230:231], v[248:249], v[126:127] op_sel:[0,1,0] op_sel_hi:[1,1,1]
	v_cvt_pk_f32_fp8_e32 v[224:225], v136
	v_cvt_pk_f32_fp8_sdwa v[226:227], v136 src0_sel:WORD_1
	v_cvt_pk_f32_fp8_e32 v[228:229], v137
	v_cvt_pk_f32_fp8_sdwa v[230:231], v137 src0_sel:WORD_1
	v_pk_fma_f32 v[112:113], v[224:225], v[250:251], v[112:113] op_sel_hi:[1,0,1]
	v_pk_fma_f32 v[114:115], v[226:227], v[250:251], v[114:115] op_sel_hi:[1,0,1]
	v_pk_fma_f32 v[116:117], v[228:229], v[250:251], v[116:117] op_sel_hi:[1,0,1]
	v_pk_fma_f32 v[118:119], v[230:231], v[250:251], v[118:119] op_sel_hi:[1,0,1]
	v_cvt_pk_f32_fp8_e32 v[224:225], v138
	v_cvt_pk_f32_fp8_sdwa v[226:227], v138 src0_sel:WORD_1
	v_cvt_pk_f32_fp8_e32 v[228:229], v139
	v_cvt_pk_f32_fp8_sdwa v[230:231], v139 src0_sel:WORD_1
	v_pk_fma_f32 v[120:121], v[224:225], v[250:251], v[120:121] op_sel_hi:[1,0,1]
	v_pk_fma_f32 v[122:123], v[226:227], v[250:251], v[122:123] op_sel_hi:[1,0,1]
	v_pk_fma_f32 v[124:125], v[228:229], v[250:251], v[124:125] op_sel_hi:[1,0,1]
	v_pk_fma_f32 v[126:127], v[230:231], v[250:251], v[126:127] op_sel_hi:[1,0,1]
	v_cvt_pk_f32_fp8_e32 v[224:225], v140
	v_cvt_pk_f32_fp8_sdwa v[226:227], v140 src0_sel:WORD_1
	v_cvt_pk_f32_fp8_e32 v[228:229], v141
	v_cvt_pk_f32_fp8_sdwa v[230:231], v141 src0_sel:WORD_1
	v_pk_fma_f32 v[112:113], v[224:225], v[250:251], v[112:113] op_sel:[0,1,0] op_sel_hi:[1,1,1]
	v_pk_fma_f32 v[114:115], v[226:227], v[250:251], v[114:115] op_sel:[0,1,0] op_sel_hi:[1,1,1]
	v_pk_fma_f32 v[116:117], v[228:229], v[250:251], v[116:117] op_sel:[0,1,0] op_sel_hi:[1,1,1]
	v_pk_fma_f32 v[118:119], v[230:231], v[250:251], v[118:119] op_sel:[0,1,0] op_sel_hi:[1,1,1]
	v_cvt_pk_f32_fp8_e32 v[224:225], v142
	v_cvt_pk_f32_fp8_sdwa v[226:227], v142 src0_sel:WORD_1
	v_cvt_pk_f32_fp8_e32 v[228:229], v143
	v_cvt_pk_f32_fp8_sdwa v[230:231], v143 src0_sel:WORD_1
	v_pk_fma_f32 v[120:121], v[224:225], v[250:251], v[120:121] op_sel:[0,1,0] op_sel_hi:[1,1,1]
	v_pk_fma_f32 v[122:123], v[226:227], v[250:251], v[122:123] op_sel:[0,1,0] op_sel_hi:[1,1,1]
	v_pk_fma_f32 v[124:125], v[228:229], v[250:251], v[124:125] op_sel:[0,1,0] op_sel_hi:[1,1,1]
	v_pk_fma_f32 v[126:127], v[230:231], v[250:251], v[126:127] op_sel:[0,1,0] op_sel_hi:[1,1,1]
	s_sub_i32 s90, s90, 1
	s_cmp_eq_u32 s90, 0
	s_cbranch_scc1 .LV_sw1
.LV_t7_s1:
	s_waitcnt lgkmcnt(0)
	v_add_u32_e32 v236, v232, v240
	v_add_u32_e32 v237, v233, v240
	v_add_u32_e32 v238, v234, v240
	v_add_u32_e32 v239, v235, v240
	global_load_dwordx4 v[128:131], v236, s[6:7]
	global_load_dwordx4 v[132:135], v237, s[6:7]
	global_load_dwordx4 v[136:139], v238, s[6:7]
	global_load_dwordx4 v[140:143], v239, s[6:7]
	ds_read_b128 v[232:235], v213 offset:80
	ds_read_b128 v[248:251], v213 offset:4896
	s_waitcnt vmcnt(12)
	v_cvt_pk_f32_fp8_e32 v[224:225], v144
	v_cvt_pk_f32_fp8_sdwa v[226:227], v144 src0_sel:WORD_1
	v_cvt_pk_f32_fp8_e32 v[228:229], v145
	v_cvt_pk_f32_fp8_sdwa v[230:231], v145 src0_sel:WORD_1
	v_pk_fma_f32 v[112:113], v[224:225], v[252:253], v[112:113] op_sel_hi:[1,0,1]
	v_pk_fma_f32 v[114:115], v[226:227], v[252:253], v[114:115] op_sel_hi:[1,0,1]
	v_pk_fma_f32 v[116:117], v[228:229], v[252:253], v[116:117] op_sel_hi:[1,0,1]
	v_pk_fma_f32 v[118:119], v[230:231], v[252:253], v[118:119] op_sel_hi:[1,0,1]
	v_cvt_pk_f32_fp8_e32 v[224:225], v146
	v_cvt_pk_f32_fp8_sdwa v[226:227], v146 src0_sel:WORD_1
	v_cvt_pk_f32_fp8_e32 v[228:229], v147
	v_cvt_pk_f32_fp8_sdwa v[230:231], v147 src0_sel:WORD_1
	v_pk_fma_f32 v[120:121], v[224:225], v[252:253], v[120:121] op_sel_hi:[1,0,1]
	v_pk_fma_f32 v[122:123], v[226:227], v[252:253], v[122:123] op_sel_hi:[1,0,1]
	v_pk_fma_f32 v[124:125], v[228:229], v[252:253], v[124:125] op_sel_hi:[1,0,1]
	v_pk_fma_f32 v[126:127], v[230:231], v[252:253], v[126:127] op_sel_hi:[1,0,1]
	v_cvt_pk_f32_fp8_e32 v[224:225], v148
	v_cvt_pk_f32_fp8_sdwa v[226:227], v148 src0_sel:WORD_1
	v_cvt_pk_f32_fp8_e32 v[228:229], v149
	v_cvt_pk_f32_fp8_sdwa v[230:231], v149 src0_sel:WORD_1
	v_pk_fma_f32 v[112:113], v[224:225], v[252:253], v[112:113] op_sel:[0,1,0] op_sel_hi:[1,1,1]
	v_pk_fma_f32 v[114:115], v[226:227], v[252:253], v[114:115] op_sel:[0,1,0] op_sel_hi:[1,1,1]
	v_pk_fma_f32 v[116:117], v[228:229], v[252:253], v[116:117] op_sel:[0,1,0] op_sel_hi:[1,1,1]
	v_pk_fma_f32 v[118:119], v[230:231], v[252:253], v[118:119] op_sel:[0,1,0] op_sel_hi:[1,1,1]
	v_cvt_pk_f32_fp8_e32 v[224:225], v150
	v_cvt_pk_f32_fp8_sdwa v[226:227], v150 src0_sel:WORD_1
	v_cvt_pk_f32_fp8_e32 v[228:229], v151
	v_cvt_pk_f32_fp8_sdwa v[230:231], v151 src0_sel:WORD_1
	v_pk_fma_f32 v[120:121], v[224:225], v[252:253], v[120:121] op_sel:[0,1,0] op_sel_hi:[1,1,1]
	v_pk_fma_f32 v[122:123], v[226:227], v[252:253], v[122:123] op_sel:[0,1,0] op_sel_hi:[1,1,1]
	v_pk_fma_f32 v[124:125], v[228:229], v[252:253], v[124:125] op_sel:[0,1,0] op_sel_hi:[1,1,1]
	v_pk_fma_f32 v[126:127], v[230:231], v[252:253], v[126:127] op_sel:[0,1,0] op_sel_hi:[1,1,1]
	v_cvt_pk_f32_fp8_e32 v[224:225], v152
	v_cvt_pk_f32_fp8_sdwa v[226:227], v152 src0_sel:WORD_1
	v_cvt_pk_f32_fp8_e32 v[228:229], v153
	v_cvt_pk_f32_fp8_sdwa v[230:231], v153 src0_sel:WORD_1
	v_pk_fma_f32 v[112:113], v[224:225], v[254:255], v[112:113] op_sel_hi:[1,0,1]
	v_pk_fma_f32 v[114:115], v[226:227], v[254:255], v[114:115] op_sel_hi:[1,0,1]
	v_pk_fma_f32 v[116:117], v[228:229], v[254:255], v[116:117] op_sel_hi:[1,0,1]
	v_pk_fma_f32 v[118:119], v[230:231], v[254:255], v[118:119] op_sel_hi:[1,0,1]
	v_cvt_pk_f32_fp8_e32 v[224:225], v154
	v_cvt_pk_f32_fp8_sdwa v[226:227], v154 src0_sel:WORD_1
	v_cvt_pk_f32_fp8_e32 v[228:229], v155
	v_cvt_pk_f32_fp8_sdwa v[230:231], v155 src0_sel:WORD_1
	v_pk_fma_f32 v[120:121], v[224:225], v[254:255], v[120:121] op_sel_hi:[1,0,1]
	v_pk_fma_f32 v[122:123], v[226:227], v[254:255], v[122:123] op_sel_hi:[1,0,1]
	v_pk_fma_f32 v[124:125], v[228:229], v[254:255], v[124:125] op_sel_hi:[1,0,1]
	v_pk_fma_f32 v[126:127], v[230:231], v[254:255], v[126:127] op_sel_hi:[1,0,1]
	v_cvt_pk_f32_fp8_e32 v[224:225], v156
	v_cvt_pk_f32_fp8_sdwa v[226:227], v156 src0_sel:WORD_1
	v_cvt_pk_f32_fp8_e32 v[228:229], v157
	v_cvt_pk_f32_fp8_sdwa v[230:231], v157 src0_sel:WORD_1
	v_pk_fma_f32 v[112:113], v[224:225], v[254:255], v[112:113] op_sel:[0,1,0] op_sel_hi:[1,1,1]
	v_pk_fma_f32 v[114:115], v[226:227], v[254:255], v[114:115] op_sel:[0,1,0] op_sel_hi:[1,1,1]
	v_pk_fma_f32 v[116:117], v[228:229], v[254:255], v[116:117] op_sel:[0,1,0] op_sel_hi:[1,1,1]
	v_pk_fma_f32 v[118:119], v[230:231], v[254:255], v[118:119] op_sel:[0,1,0] op_sel_hi:[1,1,1]
	v_cvt_pk_f32_fp8_e32 v[224:225], v158
	v_cvt_pk_f32_fp8_sdwa v[226:227], v158 src0_sel:WORD_1
	v_cvt_pk_f32_fp8_e32 v[228:229], v159
	v_cvt_pk_f32_fp8_sdwa v[230:231], v159 src0_sel:WORD_1
	v_pk_fma_f32 v[120:121], v[224:225], v[254:255], v[120:121] op_sel:[0,1,0] op_sel_hi:[1,1,1]
	v_pk_fma_f32 v[122:123], v[226:227], v[254:255], v[122:123] op_sel:[0,1,0] op_sel_hi:[1,1,1]
	v_pk_fma_f32 v[124:125], v[228:229], v[254:255], v[124:125] op_sel:[0,1,0] op_sel_hi:[1,1,1]
	v_pk_fma_f32 v[126:127], v[230:231], v[254:255], v[126:127] op_sel:[0,1,0] op_sel_hi:[1,1,1]
	s_sub_i32 s90, s90, 1
	s_cmp_eq_u32 s90, 0
	s_cbranch_scc1 .LV_sw2
.LV_t7_s2:
	s_waitcnt lgkmcnt(0)
	v_add_u32_e32 v236, v232, v240
	v_add_u32_e32 v237, v233, v240
	v_add_u32_e32 v238, v234, v240
	v_add_u32_e32 v239, v235, v240
	global_load_dwordx4 v[144:147], v236, s[6:7]
	global_load_dwordx4 v[148:151], v237, s[6:7]
	global_load_dwordx4 v[152:155], v238, s[6:7]
	global_load_dwordx4 v[156:159], v239, s[6:7]
	ds_read_b128 v[232:235], v213 offset:96
	ds_read_b128 v[252:255], v213 offset:4912
	s_waitcnt vmcnt(12)
	v_cvt_pk_f32_fp8_e32 v[224:225], v160
	v_cvt_pk_f32_fp8_sdwa v[226:227], v160 src0_sel:WORD_1
	v_cvt_pk_f32_fp8_e32 v[228:229], v161
	v_cvt_pk_f32_fp8_sdwa v[230:231], v161 src0_sel:WORD_1
	v_pk_fma_f32 v[112:113], v[224:225], v[248:249], v[112:113] op_sel_hi:[1,0,1]
	v_pk_fma_f32 v[114:115], v[226:227], v[248:249], v[114:115] op_sel_hi:[1,0,1]
	v_pk_fma_f32 v[116:117], v[228:229], v[248:249], v[116:117] op_sel_hi:[1,0,1]
	v_pk_fma_f32 v[118:119], v[230:231], v[248:249], v[118:119] op_sel_hi:[1,0,1]
	v_cvt_pk_f32_fp8_e32 v[224:225], v162
	v_cvt_pk_f32_fp8_sdwa v[226:227], v162 src0_sel:WORD_1
	v_cvt_pk_f32_fp8_e32 v[228:229], v163
	v_cvt_pk_f32_fp8_sdwa v[230:231], v163 src0_sel:WORD_1
	v_pk_fma_f32 v[120:121], v[224:225], v[248:249], v[120:121] op_sel_hi:[1,0,1]
	v_pk_fma_f32 v[122:123], v[226:227], v[248:249], v[122:123] op_sel_hi:[1,0,1]
	v_pk_fma_f32 v[124:125], v[228:229], v[248:249], v[124:125] op_sel_hi:[1,0,1]
	v_pk_fma_f32 v[126:127], v[230:231], v[248:249], v[126:127] op_sel_hi:[1,0,1]
	v_cvt_pk_f32_fp8_e32 v[224:225], v164
	v_cvt_pk_f32_fp8_sdwa v[226:227], v164 src0_sel:WORD_1
	v_cvt_pk_f32_fp8_e32 v[228:229], v165
	v_cvt_pk_f32_fp8_sdwa v[230:231], v165 src0_sel:WORD_1
	v_pk_fma_f32 v[112:113], v[224:225], v[248:249], v[112:113] op_sel:[0,1,0] op_sel_hi:[1,1,1]
	v_pk_fma_f32 v[114:115], v[226:227], v[248:249], v[114:115] op_sel:[0,1,0] op_sel_hi:[1,1,1]
	v_pk_fma_f32 v[116:117], v[228:229], v[248:249], v[116:117] op_sel:[0,1,0] op_sel_hi:[1,1,1]
	v_pk_fma_f32 v[118:119], v[230:231], v[248:249], v[118:119] op_sel:[0,1,0] op_sel_hi:[1,1,1]
	v_cvt_pk_f32_fp8_e32 v[224:225], v166
	v_cvt_pk_f32_fp8_sdwa v[226:227], v166 src0_sel:WORD_1
	v_cvt_pk_f32_fp8_e32 v[228:229], v167
	v_cvt_pk_f32_fp8_sdwa v[230:231], v167 src0_sel:WORD_1
	v_pk_fma_f32 v[120:121], v[224:225], v[248:249], v[120:121] op_sel:[0,1,0] op_sel_hi:[1,1,1]
	v_pk_fma_f32 v[122:123], v[226:227], v[248:249], v[122:123] op_sel:[0,1,0] op_sel_hi:[1,1,1]
	v_pk_fma_f32 v[124:125], v[228:229], v[248:249], v[124:125] op_sel:[0,1,0] op_sel_hi:[1,1,1]
	v_pk_fma_f32 v[126:127], v[230:231], v[248:249], v[126:127] op_sel:[0,1,0] op_sel_hi:[1,1,1]
	v_cvt_pk_f32_fp8_e32 v[224:225], v168
	v_cvt_pk_f32_fp8_sdwa v[226:227], v168 src0_sel:WORD_1
	v_cvt_pk_f32_fp8_e32 v[228:229], v169
	v_cvt_pk_f32_fp8_sdwa v[230:231], v169 src0_sel:WORD_1
	v_pk_fma_f32 v[112:113], v[224:225], v[250:251], v[112:113] op_sel_hi:[1,0,1]
	v_pk_fma_f32 v[114:115], v[226:227], v[250:251], v[114:115] op_sel_hi:[1,0,1]
	v_pk_fma_f32 v[116:117], v[228:229], v[250:251], v[116:117] op_sel_hi:[1,0,1]
	v_pk_fma_f32 v[118:119], v[230:231], v[250:251], v[118:119] op_sel_hi:[1,0,1]
	v_cvt_pk_f32_fp8_e32 v[224:225], v170
	v_cvt_pk_f32_fp8_sdwa v[226:227], v170 src0_sel:WORD_1
	v_cvt_pk_f32_fp8_e32 v[228:229], v171
	v_cvt_pk_f32_fp8_sdwa v[230:231], v171 src0_sel:WORD_1
	v_pk_fma_f32 v[120:121], v[224:225], v[250:251], v[120:121] op_sel_hi:[1,0,1]
	v_pk_fma_f32 v[122:123], v[226:227], v[250:251], v[122:123] op_sel_hi:[1,0,1]
	v_pk_fma_f32 v[124:125], v[228:229], v[250:251], v[124:125] op_sel_hi:[1,0,1]
	v_pk_fma_f32 v[126:127], v[230:231], v[250:251], v[126:127] op_sel_hi:[1,0,1]
	v_cvt_pk_f32_fp8_e32 v[224:225], v172
	v_cvt_pk_f32_fp8_sdwa v[226:227], v172 src0_sel:WORD_1
	v_cvt_pk_f32_fp8_e32 v[228:229], v173
	v_cvt_pk_f32_fp8_sdwa v[230:231], v173 src0_sel:WORD_1
	v_pk_fma_f32 v[112:113], v[224:225], v[250:251], v[112:113] op_sel:[0,1,0] op_sel_hi:[1,1,1]
	v_pk_fma_f32 v[114:115], v[226:227], v[250:251], v[114:115] op_sel:[0,1,0] op_sel_hi:[1,1,1]
	v_pk_fma_f32 v[116:117], v[228:229], v[250:251], v[116:117] op_sel:[0,1,0] op_sel_hi:[1,1,1]
	v_pk_fma_f32 v[118:119], v[230:231], v[250:251], v[118:119] op_sel:[0,1,0] op_sel_hi:[1,1,1]
	v_cvt_pk_f32_fp8_e32 v[224:225], v174
	v_cvt_pk_f32_fp8_sdwa v[226:227], v174 src0_sel:WORD_1
	v_cvt_pk_f32_fp8_e32 v[228:229], v175
	v_cvt_pk_f32_fp8_sdwa v[230:231], v175 src0_sel:WORD_1
	v_pk_fma_f32 v[120:121], v[224:225], v[250:251], v[120:121] op_sel:[0,1,0] op_sel_hi:[1,1,1]
	v_pk_fma_f32 v[122:123], v[226:227], v[250:251], v[122:123] op_sel:[0,1,0] op_sel_hi:[1,1,1]
	v_pk_fma_f32 v[124:125], v[228:229], v[250:251], v[124:125] op_sel:[0,1,0] op_sel_hi:[1,1,1]
	v_pk_fma_f32 v[126:127], v[230:231], v[250:251], v[126:127] op_sel:[0,1,0] op_sel_hi:[1,1,1]
	s_sub_i32 s90, s90, 1
	s_cmp_eq_u32 s90, 0
	s_cbranch_scc1 .LV_sw3
.LV_t7_s3:
	s_waitcnt lgkmcnt(0)
	v_add_u32_e32 v236, v232, v240
	v_add_u32_e32 v237, v233, v240
	v_add_u32_e32 v238, v234, v240
	v_add_u32_e32 v239, v235, v240
	global_load_dwordx4 v[160:163], v236, s[6:7]
	global_load_dwordx4 v[164:167], v237, s[6:7]
	global_load_dwordx4 v[168:171], v238, s[6:7]
	global_load_dwordx4 v[172:175], v239, s[6:7]
	ds_read_b128 v[232:235], v213 offset:112
	ds_read_b128 v[248:251], v213 offset:4928
	s_waitcnt vmcnt(12)
	v_cvt_pk_f32_fp8_e32 v[224:225], v176
	v_cvt_pk_f32_fp8_sdwa v[226:227], v176 src0_sel:WORD_1
	v_cvt_pk_f32_fp8_e32 v[228:229], v177
	v_cvt_pk_f32_fp8_sdwa v[230:231], v177 src0_sel:WORD_1
	v_pk_fma_f32 v[112:113], v[224:225], v[252:253], v[112:113] op_sel_hi:[1,0,1]
	v_pk_fma_f32 v[114:115], v[226:227], v[252:253], v[114:115] op_sel_hi:[1,0,1]
	v_pk_fma_f32 v[116:117], v[228:229], v[252:253], v[116:117] op_sel_hi:[1,0,1]
	v_pk_fma_f32 v[118:119], v[230:231], v[252:253], v[118:119] op_sel_hi:[1,0,1]
	v_cvt_pk_f32_fp8_e32 v[224:225], v178
	v_cvt_pk_f32_fp8_sdwa v[226:227], v178 src0_sel:WORD_1
	v_cvt_pk_f32_fp8_e32 v[228:229], v179
	v_cvt_pk_f32_fp8_sdwa v[230:231], v179 src0_sel:WORD_1
	v_pk_fma_f32 v[120:121], v[224:225], v[252:253], v[120:121] op_sel_hi:[1,0,1]
	v_pk_fma_f32 v[122:123], v[226:227], v[252:253], v[122:123] op_sel_hi:[1,0,1]
	v_pk_fma_f32 v[124:125], v[228:229], v[252:253], v[124:125] op_sel_hi:[1,0,1]
	v_pk_fma_f32 v[126:127], v[230:231], v[252:253], v[126:127] op_sel_hi:[1,0,1]
	v_cvt_pk_f32_fp8_e32 v[224:225], v180
	v_cvt_pk_f32_fp8_sdwa v[226:227], v180 src0_sel:WORD_1
	v_cvt_pk_f32_fp8_e32 v[228:229], v181
	v_cvt_pk_f32_fp8_sdwa v[230:231], v181 src0_sel:WORD_1
	v_pk_fma_f32 v[112:113], v[224:225], v[252:253], v[112:113] op_sel:[0,1,0] op_sel_hi:[1,1,1]
	v_pk_fma_f32 v[114:115], v[226:227], v[252:253], v[114:115] op_sel:[0,1,0] op_sel_hi:[1,1,1]
	v_pk_fma_f32 v[116:117], v[228:229], v[252:253], v[116:117] op_sel:[0,1,0] op_sel_hi:[1,1,1]
	v_pk_fma_f32 v[118:119], v[230:231], v[252:253], v[118:119] op_sel:[0,1,0] op_sel_hi:[1,1,1]
	v_cvt_pk_f32_fp8_e32 v[224:225], v182
	v_cvt_pk_f32_fp8_sdwa v[226:227], v182 src0_sel:WORD_1
	v_cvt_pk_f32_fp8_e32 v[228:229], v183
	v_cvt_pk_f32_fp8_sdwa v[230:231], v183 src0_sel:WORD_1
	v_pk_fma_f32 v[120:121], v[224:225], v[252:253], v[120:121] op_sel:[0,1,0] op_sel_hi:[1,1,1]
	v_pk_fma_f32 v[122:123], v[226:227], v[252:253], v[122:123] op_sel:[0,1,0] op_sel_hi:[1,1,1]
	v_pk_fma_f32 v[124:125], v[228:229], v[252:253], v[124:125] op_sel:[0,1,0] op_sel_hi:[1,1,1]
	v_pk_fma_f32 v[126:127], v[230:231], v[252:253], v[126:127] op_sel:[0,1,0] op_sel_hi:[1,1,1]
	v_cvt_pk_f32_fp8_e32 v[224:225], v184
	v_cvt_pk_f32_fp8_sdwa v[226:227], v184 src0_sel:WORD_1
	v_cvt_pk_f32_fp8_e32 v[228:229], v185
	v_cvt_pk_f32_fp8_sdwa v[230:231], v185 src0_sel:WORD_1
	v_pk_fma_f32 v[112:113], v[224:225], v[254:255], v[112:113] op_sel_hi:[1,0,1]
	v_pk_fma_f32 v[114:115], v[226:227], v[254:255], v[114:115] op_sel_hi:[1,0,1]
	v_pk_fma_f32 v[116:117], v[228:229], v[254:255], v[116:117] op_sel_hi:[1,0,1]
	v_pk_fma_f32 v[118:119], v[230:231], v[254:255], v[118:119] op_sel_hi:[1,0,1]
	v_cvt_pk_f32_fp8_e32 v[224:225], v186
	v_cvt_pk_f32_fp8_sdwa v[226:227], v186 src0_sel:WORD_1
	v_cvt_pk_f32_fp8_e32 v[228:229], v187
	v_cvt_pk_f32_fp8_sdwa v[230:231], v187 src0_sel:WORD_1
	v_pk_fma_f32 v[120:121], v[224:225], v[254:255], v[120:121] op_sel_hi:[1,0,1]
	v_pk_fma_f32 v[122:123], v[226:227], v[254:255], v[122:123] op_sel_hi:[1,0,1]
	v_pk_fma_f32 v[124:125], v[228:229], v[254:255], v[124:125] op_sel_hi:[1,0,1]
	v_pk_fma_f32 v[126:127], v[230:231], v[254:255], v[126:127] op_sel_hi:[1,0,1]
	v_cvt_pk_f32_fp8_e32 v[224:225], v188
	v_cvt_pk_f32_fp8_sdwa v[226:227], v188 src0_sel:WORD_1
	v_cvt_pk_f32_fp8_e32 v[228:229], v189
	v_cvt_pk_f32_fp8_sdwa v[230:231], v189 src0_sel:WORD_1
	v_pk_fma_f32 v[112:113], v[224:225], v[254:255], v[112:113] op_sel:[0,1,0] op_sel_hi:[1,1,1]
	v_pk_fma_f32 v[114:115], v[226:227], v[254:255], v[114:115] op_sel:[0,1,0] op_sel_hi:[1,1,1]
	v_pk_fma_f32 v[116:117], v[228:229], v[254:255], v[116:117] op_sel:[0,1,0] op_sel_hi:[1,1,1]
	v_pk_fma_f32 v[118:119], v[230:231], v[254:255], v[118:119] op_sel:[0,1,0] op_sel_hi:[1,1,1]
	v_cvt_pk_f32_fp8_e32 v[224:225], v190
	v_cvt_pk_f32_fp8_sdwa v[226:227], v190 src0_sel:WORD_1
	v_cvt_pk_f32_fp8_e32 v[228:229], v191
	v_cvt_pk_f32_fp8_sdwa v[230:231], v191 src0_sel:WORD_1
	v_pk_fma_f32 v[120:121], v[224:225], v[254:255], v[120:121] op_sel:[0,1,0] op_sel_hi:[1,1,1]
	v_pk_fma_f32 v[122:123], v[226:227], v[254:255], v[122:123] op_sel:[0,1,0] op_sel_hi:[1,1,1]
	v_pk_fma_f32 v[124:125], v[228:229], v[254:255], v[124:125] op_sel:[0,1,0] op_sel_hi:[1,1,1]
	v_pk_fma_f32 v[126:127], v[230:231], v[254:255], v[126:127] op_sel:[0,1,0] op_sel_hi:[1,1,1]
	v_add_u32_e32 v213, 64, v213
	s_add_i32 s21, s21, 4
	s_sub_i32 s90, s90, 1
	s_cmp_eq_u32 s90, 0
	s_cbranch_scc1 .LV_sw0
	s_branch .LV_t7_s0
